# v25 plus xor-16/32 row-sum shuffles in every GEMM epilogue done with v_permlane16/32_swap instead of ds_bpermute
# speedup vs baseline: 1.0109x; 1.0109x over previous
; __device__ __forceinline__ float row_part(const float* ss, int row, int fq) { const f32x4 a = ((const f32x4*)(ss + (size_t)row * 16))[fq]; return (a[0] + a[1]) + (a[2] + a[3]); }
; __device__ __forceinline__ float row_finish(float t) { t += shx(t, 16); t += shx(t, 32); return __builtin_amdgcn_rsqf(t * (1.0f / 1024.0f) + RMS_EPS); }
; __device__ __forceinline__ float shx(float v, int o) {
;     int l = (int)__builtin_amdgcn_mbcnt_hi(~0u, __builtin_amdgcn_mbcnt_lo(~0u, 0u)); asm volatile("" : "+v"(l));
;     return __builtin_bit_cast(float, __builtin_amdgcn_ds_bpermute((l ^ o) << 2, __builtin_bit_cast(int, v)));
;     __device__ __forceinline__ void operator()(const f32x4 (&acc)[2][2][4][2], const Unit& u, int wr, int wc, int fr, int fq) const {
;         const int g = u.pn * 4 + wc;
;         int mode = 0; const float* w = mqw; float sc = 1.f, nsc = 1.f;
;         if (g >= 36) { mode = 2; w = mqw; nsc = qscale; }
;         else if (diff) { if (g < 12) { mode = 2; w = qw; nsc = qscale; } else if (g < 24) { mode = 2; w = kw; } }
;         else { if (g >= 6 && g < 12) sc = 0.125f; else if (g >= 24) mode = 1; }
;         f32x4 wv[2][2];
; #pragma unroll
;         for (int bj = 0; bj < 2; ++bj)
; #pragma unroll
;             for (int n = 0; n < 2; ++n) wv[bj][n] = *(const f32x4*)(w + 32 * bj + 8 * fq + 4 * n) * nsc;
;         const int lcol = u.pn * 256 + 64 * wc + 8 * fq;
;         float rs[2][4];
; #pragma unroll
;         for (int ai = 0; ai < 2; ++ai)
; #pragma unroll
;             for (int m = 0; m < 4; ++m) rs[ai][m] = row_part(ss, u.pm * BM + ai * HALF + wr * 64 + m * 16 + fr, fq);
; #pragma unroll
;         for (int ai = 0; ai < 2; ++ai)
; #pragma unroll
;             for (int m = 0; m < 4; ++m) rs[ai][m] = row_finish(rs[ai][m]);
.LBB0_123:
	s_lshl_b32 s9, s36, 2
	s_or_b32 s11, s9, s47
	s_cmp_gt_i32 s11, 35
	s_cselect_b64 s[34:35], -1, 0
	s_cmp_lt_i32 s11, 36
	s_cselect_b64 s[42:43], -1, 0
	s_add_i32 s11, s11, -12
	s_cmp_lt_u32 s11, -6
	s_cselect_b64 s[40:41], -1, 0
	s_sub_i32 s9, s9, 24
	s_cmp_gt_u32 s9, 11
	s_cselect_b64 s[26:27], -1, 0
	s_lshl_b32 s9, s38, 8
	v_add_u32_e32 v176, s9, v192
	v_ashrrev_i32_e32 v177, 31, v176
	v_or_b32_e32 v158, 16, v176
	v_lshlrev_b64 v[148:149], 6, v[176:177]
	v_ashrrev_i32_e32 v159, 31, v158
	v_lshl_add_u64 v[148:149], v[136:137], 0, v[148:149]
	v_lshlrev_b64 v[158:159], 6, v[158:159]
	global_load_dwordx4 v[150:153], v[138:139], off offset:16
	global_load_dwordx4 v[154:157], v[138:139], off
	global_load_dwordx4 v[168:171], v[138:139], off offset:144
	global_load_dwordx4 v[178:181], v[138:139], off offset:128
	v_lshl_add_u64 v[158:159], v[136:137], 0, v[158:159]
	ds_read_b128 v[182:185], v239
	ds_read_b128 v[186:189], v239 offset:1024
	v_or_b32_e32 v148, 32, v176
	v_ashrrev_i32_e32 v149, 31, v148
	v_or_b32_e32 v158, 48, v176
	v_lshlrev_b64 v[148:149], 6, v[148:149]
	v_ashrrev_i32_e32 v159, 31, v158
	v_lshl_add_u64 v[148:149], v[136:137], 0, v[148:149]
	v_lshlrev_b64 v[158:159], 6, v[158:159]
	v_lshl_add_u64 v[158:159], v[136:137], 0, v[158:159]
	ds_read_b128 v[206:209], v239 offset:2048
	ds_read_b128 v[210:213], v239 offset:3072
	v_add_u32_e32 v174, 0x80, v176
	v_ashrrev_i32_e32 v175, 31, v174
	v_add_u32_e32 v172, 0x90, v176
	v_lshlrev_b64 v[148:149], 6, v[174:175]
	v_ashrrev_i32_e32 v173, 31, v172
	v_lshl_add_u64 v[148:149], v[136:137], 0, v[148:149]
	v_lshlrev_b64 v[158:159], 6, v[172:173]
	v_lshl_add_u64 v[158:159], v[136:137], 0, v[158:159]
	ds_read_b128 v[214:217], v239 offset:8192
	ds_read_b128 v[218:221], v239 offset:9216
	v_add_u32_e32 v166, 0xa0, v176
	v_ashrrev_i32_e32 v167, 31, v166
	v_lshlrev_b64 v[148:149], 6, v[166:167]
	v_lshl_add_u64 v[148:149], v[136:137], 0, v[148:149]
	ds_read_b128 v[222:225], v239 offset:10240
	v_add_u32_e32 v148, 0xb0, v176
	v_ashrrev_i32_e32 v149, 31, v148
	v_lshlrev_b64 v[158:159], 6, v[148:149]
	v_lshl_add_u64 v[158:159], v[136:137], 0, v[158:159]
	ds_read_b128 v[226:229], v239 offset:11264
	v_mov_b32_e32 v149, v201
	v_mov_b32_e32 v158, v201
	v_cndmask_b32_e64 v190, v203, 1.0, s[42:43]
	v_lshlrev_b32_e32 v158, 2, v158
	v_xor_b32_e32 v173, 0x80, v158
	v_lshlrev_b32_e32 v149, 2, v149
	v_xor_b32_e32 v149, 64, v149
	v_mov_b32_e32 v167, v201
	s_mov_b64 s[38:39], -1
	v_lshlrev_b32_e32 v167, 2, v167
	v_xor_b32_e32 v167, 64, v167
	s_and_b64 vcc, exec, s[42:43]
	s_waitcnt vmcnt(0) lgkmcnt(0)
	v_pk_mul_f32 v[158:159], v[190:191], v[152:153] op_sel_hi:[0,1]
	v_pk_mul_f32 v[160:161], v[190:191], v[150:151] op_sel_hi:[0,1]
	v_pk_mul_f32 v[152:153], v[190:191], v[168:169] op_sel_hi:[0,1]
	v_pk_mul_f32 v[150:151], v[190:191], v[170:171] op_sel_hi:[0,1]
	v_mov_b32_e32 v168, v183
	v_mov_b32_e32 v169, v184
	v_mov_b32_e32 v183, v185
	v_pk_add_f32 v[168:169], v[168:169], v[182:183]
	v_add_f32_e32 v170, v186, v187
	v_add_f32_e32 v168, v168, v169
	v_mov_b32_e32 v149, v168
	s_nop 1
	v_permlane16_swap_b32_e32 v149, v168
	v_add_f32_e32 v171, v188, v189
	v_add_f32_e32 v169, v170, v171
	v_mov_b32_e32 v167, v169
	s_nop 1
	v_permlane16_swap_b32_e32 v167, v169
	v_pk_mul_f32 v[162:163], v[190:191], v[156:157] op_sel_hi:[0,1]
	s_waitcnt lgkmcnt(0)
	v_add_f32_e32 v149, v168, v149
	v_mov_b32_e32 v168, v149
	s_nop 1
	v_permlane32_swap_b32_e32 v168, v149
	v_pk_mul_f32 v[156:157], v[190:191], v[178:179] op_sel_hi:[0,1]
	v_add_f32_e32 v179, v212, v213
	s_waitcnt lgkmcnt(0)
	v_add_f32_e32 v212, v169, v167
	v_add_f32_e32 v175, v206, v207
	s_waitcnt lgkmcnt(0)
	v_add_f32_e32 v149, v149, v168
	v_fmamk_f32 v149, v149, 0x3a800000, v202
	v_rsq_f32_e32 v168, v149
	v_mov_b32_e32 v149, v201
	v_add_f32_e32 v177, v208, v209
	v_lshlrev_b32_e32 v149, 2, v149
	v_xor_b32_e32 v149, 0x80, v149
	v_mov_b32_e32 v213, v212
	s_nop 1
	v_permlane32_swap_b32_e32 v213, v212
	v_mov_b32_e32 v149, v201
	v_add_f32_e32 v170, v175, v177
	v_lshlrev_b32_e32 v149, 2, v149
	v_xor_b32_e32 v149, 64, v149
	v_mov_b32_e32 v149, v170
	s_nop 1
	v_permlane16_swap_b32_e32 v149, v170
	v_mov_b32_e32 v167, v201
	v_mov_b32_e32 v169, v201
	v_add_f32_e32 v178, v210, v211
	v_lshlrev_b32_e32 v169, 2, v169
	v_add_f32_e32 v171, v178, v179
	v_xor_b32_e32 v169, 64, v169
	v_mov_b32_e32 v169, v171
	s_nop 1
	v_permlane16_swap_b32_e32 v169, v171
	s_waitcnt lgkmcnt(0)
	v_add_f32_e32 v210, v170, v149
	v_lshlrev_b32_e32 v149, 2, v167
	v_xor_b32_e32 v149, 0x80, v149
	v_mov_b32_e32 v211, v210
	s_nop 1
	v_permlane32_swap_b32_e32 v211, v210
	v_mov_b32_e32 v149, v201
	s_waitcnt lgkmcnt(0)
; __device__ __forceinline__ float row_finish(float t) { t += shx(t, 16); t += shx(t, 32); return __builtin_amdgcn_rsqf(t * (1.0f / 1024.0f) + RMS_EPS); }
; __device__ __forceinline__ float sq4(f32x4 v) { return (v[0] * v[0] + v[1] * v[1]) + (v[2] * v[2] + v[3] * v[3]); }
;     __device__ __forceinline__ void operator()(const f32x4 (&acc)[2][2][4][2], const Unit& u, int wr, int wc, int fr, int fq) const {
;     ...
;             for (int m = 0; m < 4; ++m) rs[ai][m] = row_finish(rs[ai][m]);
; #pragma unroll
;         for (int ai = 0; ai < 2; ++ai)
; #pragma unroll
;             for (int m = 0; m < 4; ++m) {
;                 const int row = u.pm * BM + ai * HALF + wr * 64 + m * 16 + fr;
;                 const float rstd = rs[ai][m];
;                 f32x4 v[2][2];
; #pragma unroll
;                 for (int bj = 0; bj < 2; ++bj)
; #pragma unroll
;                     for (int n = 0; n < 2; ++n) v[bj][n] = acc[ai][bj][m][n] * rstd;
;                 if (mode == 2) {
;                     float q = (sq4(v[0][0]) + sq4(v[0][1])) + (sq4(v[1][0]) + sq4(v[1][1]));
;                     q += shx(q, 16); q += shx(q, 32);
;                     const float r2 = __builtin_amdgcn_rsqf(q * (1.0f / 64.0f) + RMS_EPS);
; #pragma unroll
;                     for (int bj = 0; bj < 2; ++bj)
; #pragma unroll
;                         for (int n = 0; n < 2; ++n) v[bj][n] = v[bj][n] * r2 * wv[bj][n];
	v_add_f32_e32 v208, v171, v169
	v_lshlrev_b32_e32 v149, 2, v149
	v_xor_b32_e32 v149, 0x80, v149
	v_mov_b32_e32 v209, v208
	s_nop 1
	v_permlane32_swap_b32_e32 v209, v208
	v_mov_b32_e32 v149, v201
	v_pk_mul_f32 v[164:165], v[190:191], v[154:155] op_sel_hi:[0,1]
	v_pk_mul_f32 v[154:155], v[190:191], v[180:181] op_sel_hi:[0,1]
	v_add_f32_e32 v180, v214, v215
	v_add_f32_e32 v181, v216, v217
	v_lshlrev_b32_e32 v149, 2, v149
	v_add_f32_e32 v175, v180, v181
	v_xor_b32_e32 v149, 64, v149
	v_mov_b32_e32 v149, v175
	s_nop 1
	v_permlane16_swap_b32_e32 v149, v175
	v_mov_b32_e32 v167, v201
	v_mov_b32_e32 v169, v201
	v_add_f32_e32 v182, v218, v219
	v_add_f32_e32 v183, v220, v221
	v_lshlrev_b32_e32 v169, 2, v169
	v_add_f32_e32 v177, v182, v183
	v_xor_b32_e32 v169, 64, v169
	v_mov_b32_e32 v169, v177
	s_nop 1
	v_permlane16_swap_b32_e32 v169, v177
	s_waitcnt lgkmcnt(0)
	v_add_f32_e32 v206, v175, v149
	v_lshlrev_b32_e32 v149, 2, v167
	v_xor_b32_e32 v149, 0x80, v149
	v_mov_b32_e32 v207, v206
	s_nop 1
	v_permlane32_swap_b32_e32 v207, v206
	v_mov_b32_e32 v149, v201
	s_waitcnt lgkmcnt(0)
	v_add_f32_e32 v177, v177, v169
	v_lshlrev_b32_e32 v149, 2, v149
	v_xor_b32_e32 v149, 0x80, v149
	v_mov_b32_e32 v205, v177
	s_nop 1
	v_permlane32_swap_b32_e32 v205, v177
	v_mov_b32_e32 v149, v201
	v_add_f32_e32 v184, v222, v223
	v_add_f32_e32 v185, v224, v225
	v_lshlrev_b32_e32 v149, 2, v149
	v_add_f32_e32 v178, v184, v185
	v_xor_b32_e32 v149, 64, v149
	v_mov_b32_e32 v167, v201
	v_mov_b32_e32 v169, v201
	v_mov_b32_e32 v149, v178
	s_nop 1
	v_permlane16_swap_b32_e32 v149, v178
	v_add_f32_e32 v186, v226, v227
	v_add_f32_e32 v187, v228, v229
	v_lshlrev_b32_e32 v169, 2, v169
	v_add_f32_e32 v179, v186, v187
	v_xor_b32_e32 v169, 64, v169
	v_mov_b32_e32 v169, v179
	s_nop 1
	v_permlane16_swap_b32_e32 v169, v179
	s_waitcnt lgkmcnt(0)
	v_add_f32_e32 v173, v178, v149
	v_lshlrev_b32_e32 v149, 2, v167
	v_mov_b32_e32 v167, v201
	v_xor_b32_e32 v149, 0x80, v149
	v_lshlrev_b32_e32 v167, 2, v167
	v_mov_b32_e32 v175, v173
	s_nop 1
	v_permlane32_swap_b32_e32 v175, v173
	s_waitcnt lgkmcnt(0)
	v_add_f32_e32 v149, v179, v169
	v_xor_b32_e32 v167, 0x80, v167
	v_mov_b32_e32 v167, v149
	s_nop 1
	v_permlane32_swap_b32_e32 v167, v149
	v_pk_mul_f32 v[190:191], v[126:127], v[168:169] op_sel_hi:[1,0]
	v_pk_mul_f32 v[184:185], v[124:125], v[168:169] op_sel_hi:[1,0]
	v_pk_mul_f32 v[186:187], v[122:123], v[168:169] op_sel_hi:[1,0]
	v_pk_mul_f32 v[188:189], v[120:121], v[168:169] op_sel_hi:[1,0]
	v_pk_mul_f32 v[180:181], v[118:119], v[168:169] op_sel_hi:[1,0]
	v_pk_mul_f32 v[182:183], v[116:117], v[168:169] op_sel_hi:[1,0]
	v_pk_mul_f32 v[178:179], v[114:115], v[168:169] op_sel_hi:[1,0]
	v_pk_mul_f32 v[170:171], v[112:113], v[168:169] op_sel_hi:[1,0]
	s_cbranch_vccnz .LBB0_125
	v_mov_b32_e32 v114, v185
	v_mov_b32_e32 v115, v183
	v_mov_b32_e32 v112, v184
	v_mov_b32_e32 v113, v182
	v_pk_mul_f32 v[114:115], v[114:115], v[114:115]
	v_mov_b32_e32 v116, v191
	v_mov_b32_e32 v117, v181
	v_pk_fma_f32 v[112:113], v[112:113], v[112:113], v[114:115]
	v_mov_b32_e32 v114, v190
	v_mov_b32_e32 v115, v180
	v_pk_mul_f32 v[116:117], v[116:117], v[116:117]
	v_mov_b32_e32 v118, v187
	v_pk_fma_f32 v[114:115], v[114:115], v[114:115], v[116:117]
	v_mov_b32_e32 v116, v189
	v_mov_b32_e32 v117, v171
	v_pk_add_f32 v[112:113], v[112:113], v[114:115]
	v_mov_b32_e32 v114, v188
	v_mov_b32_e32 v115, v170
	v_pk_mul_f32 v[116:117], v[116:117], v[116:117]
	v_mov_b32_e32 v119, v179
	v_pk_fma_f32 v[114:115], v[114:115], v[114:115], v[116:117]
	v_mov_b32_e32 v116, v186
	v_mov_b32_e32 v117, v178
	v_pk_mul_f32 v[118:119], v[118:119], v[118:119]
	s_mov_b64 s[38:39], 0
	v_pk_fma_f32 v[116:117], v[116:117], v[116:117], v[118:119]
	s_nop 0
	v_pk_add_f32 v[114:115], v[114:115], v[116:117]
	s_nop 0
	v_pk_add_f32 v[112:113], v[112:113], v[114:115]
	s_nop 0
	v_add_f32_e32 v112, v112, v113
	v_mov_b32_e32 v113, v201
	s_nop 0
	v_lshlrev_b32_e32 v113, 2, v113
	v_xor_b32_e32 v113, 64, v113
	v_mov_b32_e32 v113, v112
	s_nop 1
	v_permlane16_swap_b32_e32 v113, v112
	s_waitcnt lgkmcnt(0)
	v_add_f32_e32 v112, v112, v113
	v_mov_b32_e32 v113, v201
	s_nop 0
	v_lshlrev_b32_e32 v113, 2, v113
	v_xor_b32_e32 v113, 0x80, v113
	v_mov_b32_e32 v113, v112
	s_nop 1
	v_permlane32_swap_b32_e32 v113, v112
	s_waitcnt lgkmcnt(0)
	v_add_f32_e32 v112, v112, v113
	v_fmamk_f32 v112, v112, 0x3c800000, v202
	v_rsq_f32_e32 v124, v112
	s_nop 0
	v_pk_mul_f32 v[112:113], v[184:185], v[124:125] op_sel_hi:[1,0]
	v_pk_mul_f32 v[114:115], v[190:191], v[124:125] op_sel_hi:[1,0]
	v_pk_mul_f32 v[116:117], v[188:189], v[124:125] op_sel_hi:[1,0]
	v_pk_mul_f32 v[118:119], v[186:187], v[124:125] op_sel_hi:[1,0]
	v_pk_mul_f32 v[120:121], v[182:183], v[124:125] op_sel_hi:[1,0]
	v_pk_mul_f32 v[122:123], v[180:181], v[124:125] op_sel_hi:[1,0]
	v_pk_mul_f32 v[168:169], v[170:171], v[124:125] op_sel_hi:[1,0]
	v_pk_mul_f32 v[124:125], v[178:179], v[124:125] op_sel_hi:[1,0]
	v_pk_mul_f32 v[114:115], v[162:163], v[114:115]
	v_pk_mul_f32 v[112:113], v[164:165], v[112:113]
	v_pk_mul_f32 v[118:119], v[158:159], v[118:119]
	v_pk_mul_f32 v[116:117], v[160:161], v[116:117]
	v_pk_mul_f32 v[122:123], v[154:155], v[122:123]
	v_pk_mul_f32 v[120:121], v[156:157], v[120:121]
	v_pk_mul_f32 v[126:127], v[150:151], v[124:125]
	v_pk_mul_f32 v[124:125], v[152:153], v[168:169]

; __device__ __forceinline__ f32x4 silu4(f32x4 v) { return (f32x4){silu_f(v[0]), silu_f(v[1]), silu_f(v[2]), silu_f(v[3])}; }
; __device__ __forceinline__ float sq4(f32x4 v) { return (v[0] * v[0] + v[1] * v[1]) + (v[2] * v[2] + v[3] * v[3]); }
; __device__ __forceinline__ u32x4 pack8(f32x4 a, f32x4 b) { u32x4 w; w.x = cvt_pk_bf16(a[0], a[1]); w.y = cvt_pk_bf16(a[2], a[3]); w.z = cvt_pk_bf16(b[0], b[1]); w.w = cvt_pk_bf16(b[2], b[3]); return w; }
;     __device__ __forceinline__ void operator()(const f32x4 (&acc)[2][2][4][2], const Unit& u, int wr, int wc, int fr, int fq) const {
;     ...
;             for (int m = 0; m < 4; ++m) {
;                 const int row = u.pm * BM + ai * HALF + wr * 64 + m * 16 + fr;
;                 const float rstd = rs[ai][m];
;                 f32x4 v[2][2];
; #pragma unroll
;                 for (int bj = 0; bj < 2; ++bj)
; #pragma unroll
;                     for (int n = 0; n < 2; ++n) v[bj][n] = acc[ai][bj][m][n] * rstd;
;                 if (mode == 2) {
;                     float q = (sq4(v[0][0]) + sq4(v[0][1])) + (sq4(v[1][0]) + sq4(v[1][1]));
;                     q += shx(q, 16); q += shx(q, 32);
;                     const float r2 = __builtin_amdgcn_rsqf(q * (1.0f / 64.0f) + RMS_EPS);
; #pragma unroll
;                     for (int bj = 0; bj < 2; ++bj)
; #pragma unroll
;                         for (int n = 0; n < 2; ++n) v[bj][n] = v[bj][n] * r2 * wv[bj][n];
;                 } else if (mode == 1) {
; #pragma unroll
;                     for (int bj = 0; bj < 2; ++bj)
; #pragma unroll
;                         for (int n = 0; n < 2; ++n) v[bj][n] = silu4(v[bj][n]);
;                 } else {
; #pragma unroll
;                     for (int bj = 0; bj < 2; ++bj)
; #pragma unroll
;                         for (int n = 0; n < 2; ++n) v[bj][n] = v[bj][n] * sc;
;                 }
;                 bf16_t* rowp = U + (size_t)row * 2560 + lcol;
; #pragma unroll
;                 for (int bj = 0; bj < 2; ++bj) *(u32x4*)(rowp + 32 * bj) = pack8(v[bj][0], v[bj][1]);
.LBB0_130:
	v_add_f32_e32 v170, v212, v213
	v_fmamk_f32 v170, v170, 0x3a800000, v202
	v_rsq_f32_e32 v178, v170
	v_lshl_or_b32 v170, s36, 8, v197
	v_mov_b64_e32 v[180:181], s[14:15]
	v_ashrrev_i32_e32 v171, 31, v170
	v_mad_i64_i32 v[180:181], s[36:37], v176, s56, v[180:181]
	v_lshl_add_u64 v[180:181], v[170:171], 1, v[180:181]
	v_cvt_pk_bf16_f32 v112, v112, v113
	v_cvt_pk_bf16_f32 v113, v114, v115
	v_cvt_pk_bf16_f32 v114, v116, v117
	v_cvt_pk_bf16_f32 v115, v118, v119
	global_store_dwordx4 v[180:181], v[112:115], off
	v_pk_mul_f32 v[116:117], v[102:103], v[178:179] op_sel_hi:[1,0]
	v_pk_mul_f32 v[118:119], v[100:101], v[178:179] op_sel_hi:[1,0]
	v_cvt_pk_bf16_f32 v112, v120, v121
	v_cvt_pk_bf16_f32 v113, v122, v123
	v_cvt_pk_bf16_f32 v114, v124, v125
	v_cvt_pk_bf16_f32 v115, v126, v127
	global_store_dwordx4 v[180:181], v[112:115], off offset:64
	v_pk_mul_f32 v[126:127], v[110:111], v[178:179] op_sel_hi:[1,0]
	v_pk_mul_f32 v[120:121], v[108:109], v[178:179] op_sel_hi:[1,0]
	v_pk_mul_f32 v[122:123], v[106:107], v[178:179] op_sel_hi:[1,0]
	v_pk_mul_f32 v[124:125], v[104:105], v[178:179] op_sel_hi:[1,0]
	v_pk_mul_f32 v[114:115], v[98:99], v[178:179] op_sel_hi:[1,0]
	v_pk_mul_f32 v[112:113], v[96:97], v[178:179] op_sel_hi:[1,0]
	s_mov_b64 s[36:37], -1
	s_and_b64 vcc, exec, s[34:35]
	s_cbranch_vccz .LBB0_132
	v_mov_b32_e32 v98, v121
	v_mov_b32_e32 v99, v119
	v_mov_b32_e32 v96, v120
	v_mov_b32_e32 v97, v118
	v_pk_mul_f32 v[98:99], v[98:99], v[98:99]
	v_mov_b32_e32 v100, v127
	v_mov_b32_e32 v101, v117
	v_pk_fma_f32 v[96:97], v[96:97], v[96:97], v[98:99]
	v_mov_b32_e32 v98, v126
	v_mov_b32_e32 v99, v116
	v_pk_mul_f32 v[100:101], v[100:101], v[100:101]
	v_mov_b32_e32 v102, v123
	v_pk_fma_f32 v[98:99], v[98:99], v[98:99], v[100:101]
	v_mov_b32_e32 v100, v125
	v_mov_b32_e32 v101, v113
	v_pk_add_f32 v[96:97], v[96:97], v[98:99]
	v_mov_b32_e32 v98, v124
	v_mov_b32_e32 v99, v112
	v_pk_mul_f32 v[100:101], v[100:101], v[100:101]
	v_mov_b32_e32 v103, v115
	v_pk_fma_f32 v[98:99], v[98:99], v[98:99], v[100:101]
	v_mov_b32_e32 v100, v122
	v_mov_b32_e32 v101, v114
	v_pk_mul_f32 v[102:103], v[102:103], v[102:103]
	s_mov_b64 s[36:37], 0
	v_pk_fma_f32 v[100:101], v[100:101], v[100:101], v[102:103]
	s_nop 0
	v_pk_add_f32 v[98:99], v[98:99], v[100:101]
	s_nop 0
	v_pk_add_f32 v[96:97], v[96:97], v[98:99]
	s_nop 0
	v_add_f32_e32 v96, v96, v97
	v_mov_b32_e32 v97, v201
	s_nop 0
	v_lshlrev_b32_e32 v97, 2, v97
	v_xor_b32_e32 v97, 64, v97
	v_mov_b32_e32 v97, v96
	s_nop 1
	v_permlane16_swap_b32_e32 v97, v96
	s_waitcnt lgkmcnt(0)
	v_add_f32_e32 v96, v96, v97
	v_mov_b32_e32 v97, v201
	s_nop 0
	v_lshlrev_b32_e32 v97, 2, v97
	v_xor_b32_e32 v97, 0x80, v97
	v_mov_b32_e32 v97, v96
	s_nop 1
	v_permlane32_swap_b32_e32 v97, v96
	s_waitcnt lgkmcnt(0)
	v_add_f32_e32 v96, v96, v97
	v_fmamk_f32 v96, v96, 0x3c800000, v202
	v_rsq_f32_e32 v108, v96
	s_nop 0
	v_pk_mul_f32 v[96:97], v[120:121], v[108:109] op_sel_hi:[1,0]
	v_pk_mul_f32 v[98:99], v[126:127], v[108:109] op_sel_hi:[1,0]
	v_pk_mul_f32 v[100:101], v[124:125], v[108:109] op_sel_hi:[1,0]
	v_pk_mul_f32 v[102:103], v[122:123], v[108:109] op_sel_hi:[1,0]
	v_pk_mul_f32 v[104:105], v[118:119], v[108:109] op_sel_hi:[1,0]
	v_pk_mul_f32 v[106:107], v[116:117], v[108:109] op_sel_hi:[1,0]
	v_pk_mul_f32 v[178:179], v[112:113], v[108:109] op_sel_hi:[1,0]
	v_pk_mul_f32 v[108:109], v[114:115], v[108:109] op_sel_hi:[1,0]
	v_pk_mul_f32 v[98:99], v[162:163], v[98:99]
	v_pk_mul_f32 v[96:97], v[164:165], v[96:97]
	v_pk_mul_f32 v[102:103], v[158:159], v[102:103]
	v_pk_mul_f32 v[100:101], v[160:161], v[100:101]
	v_pk_mul_f32 v[106:107], v[154:155], v[106:107]
	v_pk_mul_f32 v[104:105], v[156:157], v[104:105]
	v_pk_mul_f32 v[110:111], v[150:151], v[108:109]
	v_pk_mul_f32 v[108:109], v[152:153], v[178:179]

; __device__ __forceinline__ f32x4 silu4(f32x4 v) { return (f32x4){silu_f(v[0]), silu_f(v[1]), silu_f(v[2]), silu_f(v[3])}; }
; __device__ __forceinline__ float sq4(f32x4 v) { return (v[0] * v[0] + v[1] * v[1]) + (v[2] * v[2] + v[3] * v[3]); }
; __device__ __forceinline__ u32x4 pack8(f32x4 a, f32x4 b) { u32x4 w; w.x = cvt_pk_bf16(a[0], a[1]); w.y = cvt_pk_bf16(a[2], a[3]); w.z = cvt_pk_bf16(b[0], b[1]); w.w = cvt_pk_bf16(b[2], b[3]); return w; }
;     __device__ __forceinline__ void operator()(const f32x4 (&acc)[2][2][4][2], const Unit& u, int wr, int wc, int fr, int fq) const {
;     ...
;             for (int m = 0; m < 4; ++m) {
;                 const int row = u.pm * BM + ai * HALF + wr * 64 + m * 16 + fr;
;                 const float rstd = rs[ai][m];
;                 f32x4 v[2][2];
; #pragma unroll
;                 for (int bj = 0; bj < 2; ++bj)
; #pragma unroll
;                     for (int n = 0; n < 2; ++n) v[bj][n] = acc[ai][bj][m][n] * rstd;
;                 if (mode == 2) {
;                     float q = (sq4(v[0][0]) + sq4(v[0][1])) + (sq4(v[1][0]) + sq4(v[1][1]));
;                     q += shx(q, 16); q += shx(q, 32);
;                     const float r2 = __builtin_amdgcn_rsqf(q * (1.0f / 64.0f) + RMS_EPS);
; #pragma unroll
;                     for (int bj = 0; bj < 2; ++bj)
; #pragma unroll
;                         for (int n = 0; n < 2; ++n) v[bj][n] = v[bj][n] * r2 * wv[bj][n];
;                 } else if (mode == 1) {
; #pragma unroll
;                     for (int bj = 0; bj < 2; ++bj)
; #pragma unroll
;                         for (int n = 0; n < 2; ++n) v[bj][n] = silu4(v[bj][n]);
;                 } else {
; #pragma unroll
;                     for (int bj = 0; bj < 2; ++bj)
; #pragma unroll
;                         for (int n = 0; n < 2; ++n) v[bj][n] = v[bj][n] * sc;
;                 }
;                 bf16_t* rowp = U + (size_t)row * 2560 + lcol;
; #pragma unroll
;                 for (int bj = 0; bj < 2; ++bj) *(u32x4*)(rowp + 32 * bj) = pack8(v[bj][0], v[bj][1]);
.LBB0_137:
	v_add_f32_e32 v112, v210, v211
	v_fmamk_f32 v112, v112, 0x3a800000, v202
	v_add_u32_e32 v113, s9, v194
	v_rsq_f32_e32 v112, v112
	v_mov_b64_e32 v[114:115], s[14:15]
	v_mad_i64_i32 v[114:115], s[36:37], v113, s56, v[114:115]
	v_lshl_add_u64 v[114:115], v[170:171], 1, v[114:115]
	v_cvt_pk_bf16_f32 v96, v96, v97
	v_cvt_pk_bf16_f32 v97, v98, v99
	v_cvt_pk_bf16_f32 v98, v100, v101
	v_cvt_pk_bf16_f32 v99, v102, v103
	global_store_dwordx4 v[114:115], v[96:99], off
	v_pk_mul_f32 v[100:101], v[86:87], v[112:113] op_sel_hi:[1,0]
	v_pk_mul_f32 v[102:103], v[84:85], v[112:113] op_sel_hi:[1,0]
	v_cvt_pk_bf16_f32 v96, v104, v105
	v_cvt_pk_bf16_f32 v97, v106, v107
	v_cvt_pk_bf16_f32 v98, v108, v109
	v_cvt_pk_bf16_f32 v99, v110, v111
	global_store_dwordx4 v[114:115], v[96:99], off offset:64
	v_pk_mul_f32 v[110:111], v[94:95], v[112:113] op_sel_hi:[1,0]
	v_pk_mul_f32 v[104:105], v[92:93], v[112:113] op_sel_hi:[1,0]
	v_pk_mul_f32 v[106:107], v[90:91], v[112:113] op_sel_hi:[1,0]
	v_pk_mul_f32 v[108:109], v[88:89], v[112:113] op_sel_hi:[1,0]
	v_pk_mul_f32 v[98:99], v[82:83], v[112:113] op_sel_hi:[1,0]
	v_pk_mul_f32 v[96:97], v[80:81], v[112:113] op_sel_hi:[1,0]
	s_mov_b64 s[36:37], -1
	s_and_b64 vcc, exec, s[34:35]
	s_cbranch_vccz .LBB0_139
	v_mov_b32_e32 v82, v105
	v_mov_b32_e32 v83, v103
	v_mov_b32_e32 v80, v104
	v_mov_b32_e32 v81, v102
	v_pk_mul_f32 v[82:83], v[82:83], v[82:83]
	v_mov_b32_e32 v84, v111
	v_mov_b32_e32 v85, v101
	v_pk_fma_f32 v[80:81], v[80:81], v[80:81], v[82:83]
	v_mov_b32_e32 v82, v110
	v_mov_b32_e32 v83, v100
	v_pk_mul_f32 v[84:85], v[84:85], v[84:85]
	v_mov_b32_e32 v86, v107
	v_pk_fma_f32 v[82:83], v[82:83], v[82:83], v[84:85]
	v_mov_b32_e32 v84, v109
	v_mov_b32_e32 v85, v97
	v_pk_add_f32 v[80:81], v[80:81], v[82:83]
	v_mov_b32_e32 v82, v108
	v_mov_b32_e32 v83, v96
	v_pk_mul_f32 v[84:85], v[84:85], v[84:85]
	v_mov_b32_e32 v87, v99
	v_pk_fma_f32 v[82:83], v[82:83], v[82:83], v[84:85]
	v_mov_b32_e32 v84, v106
	v_mov_b32_e32 v85, v98
	v_pk_mul_f32 v[86:87], v[86:87], v[86:87]
	s_mov_b64 s[36:37], 0
	v_pk_fma_f32 v[84:85], v[84:85], v[84:85], v[86:87]
	s_nop 0
	v_pk_add_f32 v[82:83], v[82:83], v[84:85]
	s_nop 0
	v_pk_add_f32 v[80:81], v[80:81], v[82:83]
	s_nop 0
	v_add_f32_e32 v80, v80, v81
	v_mov_b32_e32 v81, v201
	s_nop 0
	v_lshlrev_b32_e32 v81, 2, v81
	v_xor_b32_e32 v81, 64, v81
	v_mov_b32_e32 v81, v80
	s_nop 1
	v_permlane16_swap_b32_e32 v81, v80
	s_waitcnt lgkmcnt(0)
	v_add_f32_e32 v80, v80, v81
	v_mov_b32_e32 v81, v201
	s_nop 0
	v_lshlrev_b32_e32 v81, 2, v81
	v_xor_b32_e32 v81, 0x80, v81
	v_mov_b32_e32 v81, v80
	s_nop 1
	v_permlane32_swap_b32_e32 v81, v80
	s_waitcnt lgkmcnt(0)
	v_add_f32_e32 v80, v80, v81
	v_fmamk_f32 v80, v80, 0x3c800000, v202
	v_rsq_f32_e32 v92, v80
	s_nop 0
	v_pk_mul_f32 v[80:81], v[104:105], v[92:93] op_sel_hi:[1,0]
	v_pk_mul_f32 v[82:83], v[110:111], v[92:93] op_sel_hi:[1,0]
	v_pk_mul_f32 v[84:85], v[108:109], v[92:93] op_sel_hi:[1,0]
	v_pk_mul_f32 v[86:87], v[106:107], v[92:93] op_sel_hi:[1,0]
	v_pk_mul_f32 v[88:89], v[102:103], v[92:93] op_sel_hi:[1,0]
	v_pk_mul_f32 v[90:91], v[100:101], v[92:93] op_sel_hi:[1,0]
	v_pk_mul_f32 v[112:113], v[96:97], v[92:93] op_sel_hi:[1,0]
	v_pk_mul_f32 v[92:93], v[98:99], v[92:93] op_sel_hi:[1,0]
	v_pk_mul_f32 v[82:83], v[162:163], v[82:83]
	v_pk_mul_f32 v[80:81], v[164:165], v[80:81]
	v_pk_mul_f32 v[86:87], v[158:159], v[86:87]
	v_pk_mul_f32 v[84:85], v[160:161], v[84:85]
	v_pk_mul_f32 v[90:91], v[154:155], v[90:91]
	v_pk_mul_f32 v[88:89], v[156:157], v[88:89]
	v_pk_mul_f32 v[94:95], v[150:151], v[92:93]
	v_pk_mul_f32 v[92:93], v[152:153], v[112:113]

; __device__ __forceinline__ f32x4 silu4(f32x4 v) { return (f32x4){silu_f(v[0]), silu_f(v[1]), silu_f(v[2]), silu_f(v[3])}; }
; __device__ __forceinline__ float sq4(f32x4 v) { return (v[0] * v[0] + v[1] * v[1]) + (v[2] * v[2] + v[3] * v[3]); }
; __device__ __forceinline__ u32x4 pack8(f32x4 a, f32x4 b) { u32x4 w; w.x = cvt_pk_bf16(a[0], a[1]); w.y = cvt_pk_bf16(a[2], a[3]); w.z = cvt_pk_bf16(b[0], b[1]); w.w = cvt_pk_bf16(b[2], b[3]); return w; }
;     __device__ __forceinline__ void operator()(const f32x4 (&acc)[2][2][4][2], const Unit& u, int wr, int wc, int fr, int fq) const {
;     ...
;             for (int m = 0; m < 4; ++m) {
;                 const int row = u.pm * BM + ai * HALF + wr * 64 + m * 16 + fr;
;                 const float rstd = rs[ai][m];
;                 f32x4 v[2][2];
; #pragma unroll
;                 for (int bj = 0; bj < 2; ++bj)
; #pragma unroll
;                     for (int n = 0; n < 2; ++n) v[bj][n] = acc[ai][bj][m][n] * rstd;
;                 if (mode == 2) {
;                     float q = (sq4(v[0][0]) + sq4(v[0][1])) + (sq4(v[1][0]) + sq4(v[1][1]));
;                     q += shx(q, 16); q += shx(q, 32);
;                     const float r2 = __builtin_amdgcn_rsqf(q * (1.0f / 64.0f) + RMS_EPS);
; #pragma unroll
;                     for (int bj = 0; bj < 2; ++bj)
; #pragma unroll
;                         for (int n = 0; n < 2; ++n) v[bj][n] = v[bj][n] * r2 * wv[bj][n];
;                 } else if (mode == 1) {
; #pragma unroll
;                     for (int bj = 0; bj < 2; ++bj)
; #pragma unroll
;                         for (int n = 0; n < 2; ++n) v[bj][n] = silu4(v[bj][n]);
;                 } else {
; #pragma unroll
;                     for (int bj = 0; bj < 2; ++bj)
; #pragma unroll
;                         for (int n = 0; n < 2; ++n) v[bj][n] = v[bj][n] * sc;
;                 }
;                 bf16_t* rowp = U + (size_t)row * 2560 + lcol;
; #pragma unroll
;                 for (int bj = 0; bj < 2; ++bj) *(u32x4*)(rowp + 32 * bj) = pack8(v[bj][0], v[bj][1]);
.LBB0_144:
	v_add_f32_e32 v96, v208, v209
	v_fmamk_f32 v96, v96, 0x3a800000, v202
	v_add_u32_e32 v97, s9, v195
	v_rsq_f32_e32 v96, v96
	v_mov_b64_e32 v[98:99], s[14:15]
	v_mad_i64_i32 v[98:99], s[36:37], v97, s56, v[98:99]
	v_lshl_add_u64 v[98:99], v[170:171], 1, v[98:99]
	v_cvt_pk_bf16_f32 v80, v80, v81
	v_cvt_pk_bf16_f32 v81, v82, v83
	v_cvt_pk_bf16_f32 v82, v84, v85
	v_cvt_pk_bf16_f32 v83, v86, v87
	global_store_dwordx4 v[98:99], v[80:83], off
	v_pk_mul_f32 v[84:85], v[70:71], v[96:97] op_sel_hi:[1,0]
	v_pk_mul_f32 v[86:87], v[68:69], v[96:97] op_sel_hi:[1,0]
	v_cvt_pk_bf16_f32 v80, v88, v89
	v_cvt_pk_bf16_f32 v81, v90, v91
	v_cvt_pk_bf16_f32 v82, v92, v93
	v_cvt_pk_bf16_f32 v83, v94, v95
	global_store_dwordx4 v[98:99], v[80:83], off offset:64
	v_pk_mul_f32 v[94:95], v[78:79], v[96:97] op_sel_hi:[1,0]
	v_pk_mul_f32 v[88:89], v[76:77], v[96:97] op_sel_hi:[1,0]
	v_pk_mul_f32 v[90:91], v[74:75], v[96:97] op_sel_hi:[1,0]
	v_pk_mul_f32 v[92:93], v[72:73], v[96:97] op_sel_hi:[1,0]
	v_pk_mul_f32 v[82:83], v[66:67], v[96:97] op_sel_hi:[1,0]
	v_pk_mul_f32 v[80:81], v[64:65], v[96:97] op_sel_hi:[1,0]
	s_mov_b64 s[36:37], -1
	s_and_b64 vcc, exec, s[34:35]
	s_cbranch_vccz .LBB0_146
	v_mov_b32_e32 v66, v89
	v_mov_b32_e32 v67, v87
	v_mov_b32_e32 v64, v88
	v_mov_b32_e32 v65, v86
	v_pk_mul_f32 v[66:67], v[66:67], v[66:67]
	v_mov_b32_e32 v68, v95
	v_mov_b32_e32 v69, v85
	v_pk_fma_f32 v[64:65], v[64:65], v[64:65], v[66:67]
	v_mov_b32_e32 v66, v94
	v_mov_b32_e32 v67, v84
	v_pk_mul_f32 v[68:69], v[68:69], v[68:69]
	v_mov_b32_e32 v70, v91
	v_pk_fma_f32 v[66:67], v[66:67], v[66:67], v[68:69]
	v_mov_b32_e32 v68, v93
	v_mov_b32_e32 v69, v81
	v_pk_add_f32 v[64:65], v[64:65], v[66:67]
	v_mov_b32_e32 v66, v92
	v_mov_b32_e32 v67, v80
	v_pk_mul_f32 v[68:69], v[68:69], v[68:69]
	v_mov_b32_e32 v71, v83
	v_pk_fma_f32 v[66:67], v[66:67], v[66:67], v[68:69]
	v_mov_b32_e32 v68, v90
	v_mov_b32_e32 v69, v82
	v_pk_mul_f32 v[70:71], v[70:71], v[70:71]
	s_mov_b64 s[36:37], 0
	v_pk_fma_f32 v[68:69], v[68:69], v[68:69], v[70:71]
	s_nop 0
	v_pk_add_f32 v[66:67], v[66:67], v[68:69]
	s_nop 0
	v_pk_add_f32 v[64:65], v[64:65], v[66:67]
	s_nop 0
	v_add_f32_e32 v64, v64, v65
	v_mov_b32_e32 v65, v201
	s_nop 0
	v_lshlrev_b32_e32 v65, 2, v65
	v_xor_b32_e32 v65, 64, v65
	v_mov_b32_e32 v65, v64
	s_nop 1
	v_permlane16_swap_b32_e32 v65, v64
	s_waitcnt lgkmcnt(0)
	v_add_f32_e32 v64, v64, v65
	v_mov_b32_e32 v65, v201
	s_nop 0
	v_lshlrev_b32_e32 v65, 2, v65
	v_xor_b32_e32 v65, 0x80, v65
	v_mov_b32_e32 v65, v64
	s_nop 1
	v_permlane32_swap_b32_e32 v65, v64
	s_waitcnt lgkmcnt(0)
	v_add_f32_e32 v64, v64, v65
	v_fmamk_f32 v64, v64, 0x3c800000, v202
	v_rsq_f32_e32 v76, v64
	s_nop 0
	v_pk_mul_f32 v[64:65], v[88:89], v[76:77] op_sel_hi:[1,0]
	v_pk_mul_f32 v[66:67], v[94:95], v[76:77] op_sel_hi:[1,0]
	v_pk_mul_f32 v[68:69], v[92:93], v[76:77] op_sel_hi:[1,0]
	v_pk_mul_f32 v[70:71], v[90:91], v[76:77] op_sel_hi:[1,0]
	v_pk_mul_f32 v[72:73], v[86:87], v[76:77] op_sel_hi:[1,0]
	v_pk_mul_f32 v[74:75], v[84:85], v[76:77] op_sel_hi:[1,0]
	v_pk_mul_f32 v[96:97], v[80:81], v[76:77] op_sel_hi:[1,0]
	v_pk_mul_f32 v[76:77], v[82:83], v[76:77] op_sel_hi:[1,0]
	v_pk_mul_f32 v[66:67], v[162:163], v[66:67]
	v_pk_mul_f32 v[64:65], v[164:165], v[64:65]
	v_pk_mul_f32 v[70:71], v[158:159], v[70:71]
	v_pk_mul_f32 v[68:69], v[160:161], v[68:69]
	v_pk_mul_f32 v[74:75], v[154:155], v[74:75]
	v_pk_mul_f32 v[72:73], v[156:157], v[72:73]
	v_pk_mul_f32 v[78:79], v[150:151], v[76:77]
	v_pk_mul_f32 v[76:77], v[152:153], v[96:97]

; __device__ __forceinline__ f32x4 silu4(f32x4 v) { return (f32x4){silu_f(v[0]), silu_f(v[1]), silu_f(v[2]), silu_f(v[3])}; }
; __device__ __forceinline__ float sq4(f32x4 v) { return (v[0] * v[0] + v[1] * v[1]) + (v[2] * v[2] + v[3] * v[3]); }
; __device__ __forceinline__ u32x4 pack8(f32x4 a, f32x4 b) { u32x4 w; w.x = cvt_pk_bf16(a[0], a[1]); w.y = cvt_pk_bf16(a[2], a[3]); w.z = cvt_pk_bf16(b[0], b[1]); w.w = cvt_pk_bf16(b[2], b[3]); return w; }
;     __device__ __forceinline__ void operator()(const f32x4 (&acc)[2][2][4][2], const Unit& u, int wr, int wc, int fr, int fq) const {
;     ...
;             for (int m = 0; m < 4; ++m) {
;                 const int row = u.pm * BM + ai * HALF + wr * 64 + m * 16 + fr;
;                 const float rstd = rs[ai][m];
;                 f32x4 v[2][2];
; #pragma unroll
;                 for (int bj = 0; bj < 2; ++bj)
; #pragma unroll
;                     for (int n = 0; n < 2; ++n) v[bj][n] = acc[ai][bj][m][n] * rstd;
;                 if (mode == 2) {
;                     float q = (sq4(v[0][0]) + sq4(v[0][1])) + (sq4(v[1][0]) + sq4(v[1][1]));
;                     q += shx(q, 16); q += shx(q, 32);
;                     const float r2 = __builtin_amdgcn_rsqf(q * (1.0f / 64.0f) + RMS_EPS);
; #pragma unroll
;                     for (int bj = 0; bj < 2; ++bj)
; #pragma unroll
;                         for (int n = 0; n < 2; ++n) v[bj][n] = v[bj][n] * r2 * wv[bj][n];
;                 } else if (mode == 1) {
; #pragma unroll
;                     for (int bj = 0; bj < 2; ++bj)
; #pragma unroll
;                         for (int n = 0; n < 2; ++n) v[bj][n] = silu4(v[bj][n]);
;                 } else {
; #pragma unroll
;                     for (int bj = 0; bj < 2; ++bj)
; #pragma unroll
;                         for (int n = 0; n < 2; ++n) v[bj][n] = v[bj][n] * sc;
;                 }
;                 bf16_t* rowp = U + (size_t)row * 2560 + lcol;
; #pragma unroll
;                 for (int bj = 0; bj < 2; ++bj) *(u32x4*)(rowp + 32 * bj) = pack8(v[bj][0], v[bj][1]);
.LBB0_151:
	v_add_f32_e32 v80, v206, v207
	v_fmamk_f32 v80, v80, 0x3a800000, v202
	v_add_u32_e32 v81, s9, v196
	v_rsq_f32_e32 v80, v80
	v_mov_b64_e32 v[82:83], s[14:15]
	v_mad_i64_i32 v[82:83], s[36:37], v81, s56, v[82:83]
	v_lshl_add_u64 v[82:83], v[170:171], 1, v[82:83]
	v_cvt_pk_bf16_f32 v64, v64, v65
	v_cvt_pk_bf16_f32 v65, v66, v67
	v_cvt_pk_bf16_f32 v66, v68, v69
	v_cvt_pk_bf16_f32 v67, v70, v71
	global_store_dwordx4 v[82:83], v[64:67], off
	v_pk_mul_f32 v[68:69], v[54:55], v[80:81] op_sel_hi:[1,0]
	v_pk_mul_f32 v[70:71], v[52:53], v[80:81] op_sel_hi:[1,0]
	v_cvt_pk_bf16_f32 v64, v72, v73
	v_cvt_pk_bf16_f32 v65, v74, v75
	v_cvt_pk_bf16_f32 v66, v76, v77
	v_cvt_pk_bf16_f32 v67, v78, v79
	global_store_dwordx4 v[82:83], v[64:67], off offset:64
	v_pk_mul_f32 v[78:79], v[62:63], v[80:81] op_sel_hi:[1,0]
	v_pk_mul_f32 v[72:73], v[60:61], v[80:81] op_sel_hi:[1,0]
	v_pk_mul_f32 v[74:75], v[58:59], v[80:81] op_sel_hi:[1,0]
	v_pk_mul_f32 v[76:77], v[56:57], v[80:81] op_sel_hi:[1,0]
	v_pk_mul_f32 v[66:67], v[50:51], v[80:81] op_sel_hi:[1,0]
	v_pk_mul_f32 v[64:65], v[48:49], v[80:81] op_sel_hi:[1,0]
	s_mov_b64 s[36:37], -1
	s_and_b64 vcc, exec, s[34:35]
	s_cbranch_vccz .LBB0_153
	v_mov_b32_e32 v50, v73
	v_mov_b32_e32 v51, v71
	v_mov_b32_e32 v48, v72
	v_mov_b32_e32 v49, v70
	v_pk_mul_f32 v[50:51], v[50:51], v[50:51]
	v_mov_b32_e32 v52, v79
	v_mov_b32_e32 v53, v69
	v_pk_fma_f32 v[48:49], v[48:49], v[48:49], v[50:51]
	v_mov_b32_e32 v50, v78
	v_mov_b32_e32 v51, v68
	v_pk_mul_f32 v[52:53], v[52:53], v[52:53]
	v_mov_b32_e32 v54, v75
	v_pk_fma_f32 v[50:51], v[50:51], v[50:51], v[52:53]
	v_mov_b32_e32 v52, v77
	v_mov_b32_e32 v53, v65
	v_pk_add_f32 v[48:49], v[48:49], v[50:51]
	v_mov_b32_e32 v50, v76
	v_mov_b32_e32 v51, v64
	v_pk_mul_f32 v[52:53], v[52:53], v[52:53]
	v_mov_b32_e32 v55, v67
	v_pk_fma_f32 v[50:51], v[50:51], v[50:51], v[52:53]
	v_mov_b32_e32 v52, v74
	v_mov_b32_e32 v53, v66
	v_pk_mul_f32 v[54:55], v[54:55], v[54:55]
	s_mov_b64 s[36:37], 0
	v_pk_fma_f32 v[52:53], v[52:53], v[52:53], v[54:55]
	s_nop 0
	v_pk_add_f32 v[50:51], v[50:51], v[52:53]
	s_nop 0
	v_pk_add_f32 v[48:49], v[48:49], v[50:51]
	s_nop 0
	v_add_f32_e32 v48, v48, v49
	v_mov_b32_e32 v49, v201
	s_nop 0
	v_lshlrev_b32_e32 v49, 2, v49
	v_xor_b32_e32 v49, 64, v49
	v_mov_b32_e32 v49, v48
	s_nop 1
	v_permlane16_swap_b32_e32 v49, v48
	s_waitcnt lgkmcnt(0)
	v_add_f32_e32 v48, v48, v49
	v_mov_b32_e32 v49, v201
	s_nop 0
	v_lshlrev_b32_e32 v49, 2, v49
	v_xor_b32_e32 v49, 0x80, v49
	v_mov_b32_e32 v49, v48
	s_nop 1
	v_permlane32_swap_b32_e32 v49, v48
	s_waitcnt lgkmcnt(0)
	v_add_f32_e32 v48, v48, v49
	v_fmamk_f32 v48, v48, 0x3c800000, v202
	v_rsq_f32_e32 v60, v48
	s_nop 0
	v_pk_mul_f32 v[48:49], v[72:73], v[60:61] op_sel_hi:[1,0]
	v_pk_mul_f32 v[50:51], v[78:79], v[60:61] op_sel_hi:[1,0]
	v_pk_mul_f32 v[52:53], v[76:77], v[60:61] op_sel_hi:[1,0]
	v_pk_mul_f32 v[54:55], v[74:75], v[60:61] op_sel_hi:[1,0]
	v_pk_mul_f32 v[56:57], v[70:71], v[60:61] op_sel_hi:[1,0]
	v_pk_mul_f32 v[58:59], v[68:69], v[60:61] op_sel_hi:[1,0]
	v_pk_mul_f32 v[80:81], v[64:65], v[60:61] op_sel_hi:[1,0]
	v_pk_mul_f32 v[60:61], v[66:67], v[60:61] op_sel_hi:[1,0]
	v_pk_mul_f32 v[50:51], v[162:163], v[50:51]
	v_pk_mul_f32 v[48:49], v[164:165], v[48:49]
	v_pk_mul_f32 v[54:55], v[158:159], v[54:55]
	v_pk_mul_f32 v[52:53], v[160:161], v[52:53]
	v_pk_mul_f32 v[58:59], v[154:155], v[58:59]
	v_pk_mul_f32 v[56:57], v[156:157], v[56:57]
	v_pk_mul_f32 v[62:63], v[150:151], v[60:61]
	v_pk_mul_f32 v[60:61], v[152:153], v[80:81]

; __device__ __forceinline__ f32x4 silu4(f32x4 v) { return (f32x4){silu_f(v[0]), silu_f(v[1]), silu_f(v[2]), silu_f(v[3])}; }
; __device__ __forceinline__ float sq4(f32x4 v) { return (v[0] * v[0] + v[1] * v[1]) + (v[2] * v[2] + v[3] * v[3]); }
; __device__ __forceinline__ u32x4 pack8(f32x4 a, f32x4 b) { u32x4 w; w.x = cvt_pk_bf16(a[0], a[1]); w.y = cvt_pk_bf16(a[2], a[3]); w.z = cvt_pk_bf16(b[0], b[1]); w.w = cvt_pk_bf16(b[2], b[3]); return w; }
;     __device__ __forceinline__ void operator()(const f32x4 (&acc)[2][2][4][2], const Unit& u, int wr, int wc, int fr, int fq) const {
;     ...
;             for (int m = 0; m < 4; ++m) {
;                 const int row = u.pm * BM + ai * HALF + wr * 64 + m * 16 + fr;
;                 const float rstd = rs[ai][m];
;                 f32x4 v[2][2];
; #pragma unroll
;                 for (int bj = 0; bj < 2; ++bj)
; #pragma unroll
;                     for (int n = 0; n < 2; ++n) v[bj][n] = acc[ai][bj][m][n] * rstd;
;                 if (mode == 2) {
;                     float q = (sq4(v[0][0]) + sq4(v[0][1])) + (sq4(v[1][0]) + sq4(v[1][1]));
;                     q += shx(q, 16); q += shx(q, 32);
;                     const float r2 = __builtin_amdgcn_rsqf(q * (1.0f / 64.0f) + RMS_EPS);
; #pragma unroll
;                     for (int bj = 0; bj < 2; ++bj)
; #pragma unroll
;                         for (int n = 0; n < 2; ++n) v[bj][n] = v[bj][n] * r2 * wv[bj][n];
;                 } else if (mode == 1) {
; #pragma unroll
;                     for (int bj = 0; bj < 2; ++bj)
; #pragma unroll
;                         for (int n = 0; n < 2; ++n) v[bj][n] = silu4(v[bj][n]);
;                 } else {
; #pragma unroll
;                     for (int bj = 0; bj < 2; ++bj)
; #pragma unroll
;                         for (int n = 0; n < 2; ++n) v[bj][n] = v[bj][n] * sc;
;                 }
;                 bf16_t* rowp = U + (size_t)row * 2560 + lcol;
; #pragma unroll
;                 for (int bj = 0; bj < 2; ++bj) *(u32x4*)(rowp + 32 * bj) = pack8(v[bj][0], v[bj][1]);
.LBB0_158:
	v_add_f32_e32 v64, v177, v205
	v_fmamk_f32 v64, v64, 0x3a800000, v202
	v_rsq_f32_e32 v64, v64
	v_mov_b64_e32 v[66:67], s[14:15]
	v_mad_i64_i32 v[66:67], s[36:37], v174, s56, v[66:67]
	v_lshl_add_u64 v[66:67], v[170:171], 1, v[66:67]
	v_cvt_pk_bf16_f32 v48, v48, v49
	v_cvt_pk_bf16_f32 v49, v50, v51
	v_cvt_pk_bf16_f32 v50, v52, v53
	v_cvt_pk_bf16_f32 v51, v54, v55
	global_store_dwordx4 v[66:67], v[48:51], off
	v_pk_mul_f32 v[52:53], v[38:39], v[64:65] op_sel_hi:[1,0]
	v_pk_mul_f32 v[54:55], v[36:37], v[64:65] op_sel_hi:[1,0]
	v_cvt_pk_bf16_f32 v48, v56, v57
	v_cvt_pk_bf16_f32 v49, v58, v59
	v_cvt_pk_bf16_f32 v50, v60, v61
	v_cvt_pk_bf16_f32 v51, v62, v63
	global_store_dwordx4 v[66:67], v[48:51], off offset:64
	v_pk_mul_f32 v[62:63], v[46:47], v[64:65] op_sel_hi:[1,0]
	v_pk_mul_f32 v[56:57], v[44:45], v[64:65] op_sel_hi:[1,0]
	v_pk_mul_f32 v[58:59], v[42:43], v[64:65] op_sel_hi:[1,0]
	v_pk_mul_f32 v[60:61], v[40:41], v[64:65] op_sel_hi:[1,0]
	v_pk_mul_f32 v[50:51], v[34:35], v[64:65] op_sel_hi:[1,0]
	v_pk_mul_f32 v[48:49], v[32:33], v[64:65] op_sel_hi:[1,0]
	s_mov_b64 s[36:37], -1
	s_and_b64 vcc, exec, s[34:35]
	s_cbranch_vccz .LBB0_160
	v_mov_b32_e32 v34, v57
	v_mov_b32_e32 v35, v55
	v_mov_b32_e32 v32, v56
	v_mov_b32_e32 v33, v54
	v_pk_mul_f32 v[34:35], v[34:35], v[34:35]
	v_mov_b32_e32 v36, v63
	v_mov_b32_e32 v37, v53
	v_pk_fma_f32 v[32:33], v[32:33], v[32:33], v[34:35]
	v_mov_b32_e32 v34, v62
	v_mov_b32_e32 v35, v52
	v_pk_mul_f32 v[36:37], v[36:37], v[36:37]
	v_mov_b32_e32 v38, v59
	v_pk_fma_f32 v[34:35], v[34:35], v[34:35], v[36:37]
	v_mov_b32_e32 v36, v61
	v_mov_b32_e32 v37, v49
	v_pk_add_f32 v[32:33], v[32:33], v[34:35]
	v_mov_b32_e32 v34, v60
	v_mov_b32_e32 v35, v48
	v_pk_mul_f32 v[36:37], v[36:37], v[36:37]
	v_mov_b32_e32 v39, v51
	v_pk_fma_f32 v[34:35], v[34:35], v[34:35], v[36:37]
	v_mov_b32_e32 v36, v58
	v_mov_b32_e32 v37, v50
	v_pk_mul_f32 v[38:39], v[38:39], v[38:39]
	s_mov_b64 s[36:37], 0
	v_pk_fma_f32 v[36:37], v[36:37], v[36:37], v[38:39]
	s_nop 0
	v_pk_add_f32 v[34:35], v[34:35], v[36:37]
	s_nop 0
	v_pk_add_f32 v[32:33], v[32:33], v[34:35]
	s_nop 0
	v_add_f32_e32 v32, v32, v33
	v_mov_b32_e32 v33, v201
	s_nop 0
	v_lshlrev_b32_e32 v33, 2, v33
	v_xor_b32_e32 v33, 64, v33
	v_mov_b32_e32 v33, v32
	s_nop 1
	v_permlane16_swap_b32_e32 v33, v32
	s_waitcnt lgkmcnt(0)
	v_add_f32_e32 v32, v32, v33
	v_mov_b32_e32 v33, v201
	s_nop 0
	v_lshlrev_b32_e32 v33, 2, v33
	v_xor_b32_e32 v33, 0x80, v33
	v_mov_b32_e32 v33, v32
	s_nop 1
	v_permlane32_swap_b32_e32 v33, v32
	s_waitcnt lgkmcnt(0)
	v_add_f32_e32 v32, v32, v33
	v_fmamk_f32 v32, v32, 0x3c800000, v202
	v_rsq_f32_e32 v44, v32
	s_nop 0
	v_pk_mul_f32 v[32:33], v[56:57], v[44:45] op_sel_hi:[1,0]
	v_pk_mul_f32 v[34:35], v[62:63], v[44:45] op_sel_hi:[1,0]
	v_pk_mul_f32 v[36:37], v[60:61], v[44:45] op_sel_hi:[1,0]
	v_pk_mul_f32 v[38:39], v[58:59], v[44:45] op_sel_hi:[1,0]
	v_pk_mul_f32 v[40:41], v[54:55], v[44:45] op_sel_hi:[1,0]
	v_pk_mul_f32 v[42:43], v[52:53], v[44:45] op_sel_hi:[1,0]
	v_pk_mul_f32 v[64:65], v[48:49], v[44:45] op_sel_hi:[1,0]
	v_pk_mul_f32 v[44:45], v[50:51], v[44:45] op_sel_hi:[1,0]
	v_pk_mul_f32 v[34:35], v[162:163], v[34:35]
	v_pk_mul_f32 v[32:33], v[164:165], v[32:33]
	v_pk_mul_f32 v[38:39], v[158:159], v[38:39]
	v_pk_mul_f32 v[36:37], v[160:161], v[36:37]
	v_pk_mul_f32 v[42:43], v[154:155], v[42:43]
	v_pk_mul_f32 v[40:41], v[156:157], v[40:41]
	v_pk_mul_f32 v[46:47], v[150:151], v[44:45]
	v_pk_mul_f32 v[44:45], v[152:153], v[64:65]

; __device__ __forceinline__ f32x4 silu4(f32x4 v) { return (f32x4){silu_f(v[0]), silu_f(v[1]), silu_f(v[2]), silu_f(v[3])}; }
; __device__ __forceinline__ float sq4(f32x4 v) { return (v[0] * v[0] + v[1] * v[1]) + (v[2] * v[2] + v[3] * v[3]); }
; __device__ __forceinline__ u32x4 pack8(f32x4 a, f32x4 b) { u32x4 w; w.x = cvt_pk_bf16(a[0], a[1]); w.y = cvt_pk_bf16(a[2], a[3]); w.z = cvt_pk_bf16(b[0], b[1]); w.w = cvt_pk_bf16(b[2], b[3]); return w; }
;     __device__ __forceinline__ void operator()(const f32x4 (&acc)[2][2][4][2], const Unit& u, int wr, int wc, int fr, int fq) const {
;     ...
;             for (int m = 0; m < 4; ++m) {
;                 const int row = u.pm * BM + ai * HALF + wr * 64 + m * 16 + fr;
;                 const float rstd = rs[ai][m];
;                 f32x4 v[2][2];
; #pragma unroll
;                 for (int bj = 0; bj < 2; ++bj)
; #pragma unroll
;                     for (int n = 0; n < 2; ++n) v[bj][n] = acc[ai][bj][m][n] * rstd;
;                 if (mode == 2) {
;                     float q = (sq4(v[0][0]) + sq4(v[0][1])) + (sq4(v[1][0]) + sq4(v[1][1]));
;                     q += shx(q, 16); q += shx(q, 32);
;                     const float r2 = __builtin_amdgcn_rsqf(q * (1.0f / 64.0f) + RMS_EPS);
; #pragma unroll
;                     for (int bj = 0; bj < 2; ++bj)
; #pragma unroll
;                         for (int n = 0; n < 2; ++n) v[bj][n] = v[bj][n] * r2 * wv[bj][n];
;                 } else if (mode == 1) {
; #pragma unroll
;                     for (int bj = 0; bj < 2; ++bj)
; #pragma unroll
;                         for (int n = 0; n < 2; ++n) v[bj][n] = silu4(v[bj][n]);
;                 } else {
; #pragma unroll
;                     for (int bj = 0; bj < 2; ++bj)
; #pragma unroll
;                         for (int n = 0; n < 2; ++n) v[bj][n] = v[bj][n] * sc;
;                 }
;                 bf16_t* rowp = U + (size_t)row * 2560 + lcol;
; #pragma unroll
;                 for (int bj = 0; bj < 2; ++bj) *(u32x4*)(rowp + 32 * bj) = pack8(v[bj][0], v[bj][1]);
.LBB0_165:
	s_waitcnt lgkmcnt(0)
	v_add_f32_e32 v48, v173, v175
	v_fmamk_f32 v48, v48, 0x3a800000, v202
	v_rsq_f32_e32 v48, v48
	v_mov_b64_e32 v[50:51], s[14:15]
	v_mad_i64_i32 v[50:51], s[36:37], v172, s56, v[50:51]
	v_lshl_add_u64 v[50:51], v[170:171], 1, v[50:51]
	v_cvt_pk_bf16_f32 v32, v32, v33
	v_cvt_pk_bf16_f32 v33, v34, v35
	v_cvt_pk_bf16_f32 v34, v36, v37
	v_cvt_pk_bf16_f32 v35, v38, v39
	global_store_dwordx4 v[50:51], v[32:35], off
	v_pk_mul_f32 v[36:37], v[22:23], v[48:49] op_sel_hi:[1,0]
	v_pk_mul_f32 v[38:39], v[20:21], v[48:49] op_sel_hi:[1,0]
	v_cvt_pk_bf16_f32 v32, v40, v41
	v_cvt_pk_bf16_f32 v33, v42, v43
	v_cvt_pk_bf16_f32 v34, v44, v45
	v_cvt_pk_bf16_f32 v35, v46, v47
	global_store_dwordx4 v[50:51], v[32:35], off offset:64
	v_pk_mul_f32 v[46:47], v[30:31], v[48:49] op_sel_hi:[1,0]
	v_pk_mul_f32 v[40:41], v[28:29], v[48:49] op_sel_hi:[1,0]
	v_pk_mul_f32 v[42:43], v[26:27], v[48:49] op_sel_hi:[1,0]
	v_pk_mul_f32 v[44:45], v[24:25], v[48:49] op_sel_hi:[1,0]
	v_pk_mul_f32 v[34:35], v[18:19], v[48:49] op_sel_hi:[1,0]
	v_pk_mul_f32 v[32:33], v[16:17], v[48:49] op_sel_hi:[1,0]
	s_mov_b64 s[36:37], -1
	s_and_b64 vcc, exec, s[34:35]
	s_cbranch_vccz .LBB0_167
	v_mov_b32_e32 v18, v41
	v_mov_b32_e32 v19, v39
	v_mov_b32_e32 v16, v40
	v_mov_b32_e32 v17, v38
	v_pk_mul_f32 v[18:19], v[18:19], v[18:19]
	v_mov_b32_e32 v20, v47
	v_mov_b32_e32 v21, v37
	v_pk_fma_f32 v[16:17], v[16:17], v[16:17], v[18:19]
	v_mov_b32_e32 v18, v46
	v_mov_b32_e32 v19, v36
	v_pk_mul_f32 v[20:21], v[20:21], v[20:21]
	v_mov_b32_e32 v22, v43
	v_pk_fma_f32 v[18:19], v[18:19], v[18:19], v[20:21]
	v_mov_b32_e32 v20, v45
	v_mov_b32_e32 v21, v33
	v_pk_add_f32 v[16:17], v[16:17], v[18:19]
	v_mov_b32_e32 v18, v44
	v_mov_b32_e32 v19, v32
	v_pk_mul_f32 v[20:21], v[20:21], v[20:21]
	v_mov_b32_e32 v23, v35
	v_pk_fma_f32 v[18:19], v[18:19], v[18:19], v[20:21]
	v_mov_b32_e32 v20, v42
	v_mov_b32_e32 v21, v34
	v_pk_mul_f32 v[22:23], v[22:23], v[22:23]
	s_mov_b64 s[36:37], 0
	v_pk_fma_f32 v[20:21], v[20:21], v[20:21], v[22:23]
	s_nop 0
	v_pk_add_f32 v[18:19], v[18:19], v[20:21]
	s_nop 0
	v_pk_add_f32 v[16:17], v[16:17], v[18:19]
	s_nop 0
	v_add_f32_e32 v16, v16, v17
	v_mov_b32_e32 v17, v201
	s_nop 0
	v_lshlrev_b32_e32 v17, 2, v17
	v_xor_b32_e32 v17, 64, v17
	v_mov_b32_e32 v17, v16
	s_nop 1
	v_permlane16_swap_b32_e32 v17, v16
	s_waitcnt lgkmcnt(0)
	v_add_f32_e32 v16, v16, v17
	v_mov_b32_e32 v17, v201
	s_nop 0
	v_lshlrev_b32_e32 v17, 2, v17
	v_xor_b32_e32 v17, 0x80, v17
	v_mov_b32_e32 v17, v16
	s_nop 1
	v_permlane32_swap_b32_e32 v17, v16
	s_waitcnt lgkmcnt(0)
	v_add_f32_e32 v16, v16, v17
	v_fmamk_f32 v16, v16, 0x3c800000, v202
	v_rsq_f32_e32 v28, v16
	s_nop 0
	v_pk_mul_f32 v[16:17], v[40:41], v[28:29] op_sel_hi:[1,0]
	v_pk_mul_f32 v[18:19], v[46:47], v[28:29] op_sel_hi:[1,0]
	v_pk_mul_f32 v[20:21], v[44:45], v[28:29] op_sel_hi:[1,0]
	v_pk_mul_f32 v[22:23], v[42:43], v[28:29] op_sel_hi:[1,0]
	v_pk_mul_f32 v[24:25], v[38:39], v[28:29] op_sel_hi:[1,0]
	v_pk_mul_f32 v[26:27], v[36:37], v[28:29] op_sel_hi:[1,0]
	v_pk_mul_f32 v[48:49], v[32:33], v[28:29] op_sel_hi:[1,0]
	v_pk_mul_f32 v[28:29], v[34:35], v[28:29] op_sel_hi:[1,0]
	v_pk_mul_f32 v[18:19], v[162:163], v[18:19]
	v_pk_mul_f32 v[16:17], v[164:165], v[16:17]
	v_pk_mul_f32 v[22:23], v[158:159], v[22:23]
	v_pk_mul_f32 v[20:21], v[160:161], v[20:21]
	v_pk_mul_f32 v[26:27], v[154:155], v[26:27]
	v_pk_mul_f32 v[24:25], v[156:157], v[24:25]
	v_pk_mul_f32 v[30:31], v[150:151], v[28:29]
	v_pk_mul_f32 v[28:29], v[152:153], v[48:49]

; __device__ __forceinline__ f32x4 silu4(f32x4 v) { return (f32x4){silu_f(v[0]), silu_f(v[1]), silu_f(v[2]), silu_f(v[3])}; }
; __device__ __forceinline__ float sq4(f32x4 v) { return (v[0] * v[0] + v[1] * v[1]) + (v[2] * v[2] + v[3] * v[3]); }
; __device__ __forceinline__ u32x4 pack8(f32x4 a, f32x4 b) { u32x4 w; w.x = cvt_pk_bf16(a[0], a[1]); w.y = cvt_pk_bf16(a[2], a[3]); w.z = cvt_pk_bf16(b[0], b[1]); w.w = cvt_pk_bf16(b[2], b[3]); return w; }
;     __device__ __forceinline__ void operator()(const f32x4 (&acc)[2][2][4][2], const Unit& u, int wr, int wc, int fr, int fq) const {
;     ...
;             for (int m = 0; m < 4; ++m) {
;                 const int row = u.pm * BM + ai * HALF + wr * 64 + m * 16 + fr;
;                 const float rstd = rs[ai][m];
;                 f32x4 v[2][2];
; #pragma unroll
;                 for (int bj = 0; bj < 2; ++bj)
; #pragma unroll
;                     for (int n = 0; n < 2; ++n) v[bj][n] = acc[ai][bj][m][n] * rstd;
;                 if (mode == 2) {
;                     float q = (sq4(v[0][0]) + sq4(v[0][1])) + (sq4(v[1][0]) + sq4(v[1][1]));
;                     q += shx(q, 16); q += shx(q, 32);
;                     const float r2 = __builtin_amdgcn_rsqf(q * (1.0f / 64.0f) + RMS_EPS);
; #pragma unroll
;                     for (int bj = 0; bj < 2; ++bj)
; #pragma unroll
;                         for (int n = 0; n < 2; ++n) v[bj][n] = v[bj][n] * r2 * wv[bj][n];
;                 } else if (mode == 1) {
; #pragma unroll
;                     for (int bj = 0; bj < 2; ++bj)
; #pragma unroll
;                         for (int n = 0; n < 2; ++n) v[bj][n] = silu4(v[bj][n]);
;                 } else {
; #pragma unroll
;                     for (int bj = 0; bj < 2; ++bj)
; #pragma unroll
;                         for (int n = 0; n < 2; ++n) v[bj][n] = v[bj][n] * sc;
;                 }
;                 bf16_t* rowp = U + (size_t)row * 2560 + lcol;
; #pragma unroll
;                 for (int bj = 0; bj < 2; ++bj) *(u32x4*)(rowp + 32 * bj) = pack8(v[bj][0], v[bj][1]);
.LBB0_172:
	s_waitcnt lgkmcnt(0)
	v_add_f32_e32 v32, v149, v167
	v_fmamk_f32 v32, v32, 0x3a800000, v202
	v_rsq_f32_e32 v32, v32
	v_mov_b64_e32 v[34:35], s[14:15]
	v_mad_i64_i32 v[34:35], s[36:37], v166, s56, v[34:35]
	v_lshl_add_u64 v[34:35], v[170:171], 1, v[34:35]
	v_cvt_pk_bf16_f32 v16, v16, v17
	v_cvt_pk_bf16_f32 v17, v18, v19
	v_cvt_pk_bf16_f32 v18, v20, v21
	v_cvt_pk_bf16_f32 v19, v22, v23
	global_store_dwordx4 v[34:35], v[16:19], off
	v_pk_mul_f32 v[20:21], v[6:7], v[32:33] op_sel_hi:[1,0]
	v_pk_mul_f32 v[22:23], v[4:5], v[32:33] op_sel_hi:[1,0]
	v_cvt_pk_bf16_f32 v16, v24, v25
	v_cvt_pk_bf16_f32 v17, v26, v27
	v_cvt_pk_bf16_f32 v18, v28, v29
	v_cvt_pk_bf16_f32 v19, v30, v31
	global_store_dwordx4 v[34:35], v[16:19], off offset:64
	v_pk_mul_f32 v[30:31], v[14:15], v[32:33] op_sel_hi:[1,0]
	v_pk_mul_f32 v[24:25], v[12:13], v[32:33] op_sel_hi:[1,0]
	v_pk_mul_f32 v[26:27], v[10:11], v[32:33] op_sel_hi:[1,0]
	v_pk_mul_f32 v[28:29], v[8:9], v[32:33] op_sel_hi:[1,0]
	v_pk_mul_f32 v[18:19], v[2:3], v[32:33] op_sel_hi:[1,0]
	v_pk_mul_f32 v[16:17], v[0:1], v[32:33] op_sel_hi:[1,0]
	s_mov_b64 s[36:37], -1
	s_and_b64 vcc, exec, s[34:35]
	s_cbranch_vccz .LBB0_174
	v_mov_b32_e32 v2, v25
	v_mov_b32_e32 v3, v23
	v_mov_b32_e32 v0, v24
	v_mov_b32_e32 v1, v22
	v_pk_mul_f32 v[2:3], v[2:3], v[2:3]
	v_mov_b32_e32 v4, v31
	v_mov_b32_e32 v5, v21
	v_pk_fma_f32 v[0:1], v[0:1], v[0:1], v[2:3]
	v_mov_b32_e32 v2, v30
	v_mov_b32_e32 v3, v20
	v_pk_mul_f32 v[4:5], v[4:5], v[4:5]
	v_mov_b32_e32 v6, v27
	v_pk_fma_f32 v[2:3], v[2:3], v[2:3], v[4:5]
	v_mov_b32_e32 v4, v29
	v_mov_b32_e32 v5, v17
	v_pk_add_f32 v[0:1], v[0:1], v[2:3]
	v_mov_b32_e32 v2, v28
	v_mov_b32_e32 v3, v16
	v_pk_mul_f32 v[4:5], v[4:5], v[4:5]
	v_mov_b32_e32 v7, v19
	v_pk_fma_f32 v[2:3], v[2:3], v[2:3], v[4:5]
	v_mov_b32_e32 v4, v26
	v_mov_b32_e32 v5, v18
	v_pk_mul_f32 v[6:7], v[6:7], v[6:7]
	s_mov_b64 s[36:37], 0
	v_pk_fma_f32 v[4:5], v[4:5], v[4:5], v[6:7]
	s_nop 0
	v_pk_add_f32 v[2:3], v[2:3], v[4:5]
	s_nop 0
	v_pk_add_f32 v[0:1], v[0:1], v[2:3]
	s_nop 0
	v_add_f32_e32 v0, v0, v1
	v_mov_b32_e32 v1, v201
	s_nop 0
	v_lshlrev_b32_e32 v1, 2, v1
	v_xor_b32_e32 v1, 64, v1
	v_mov_b32_e32 v1, v0
	s_nop 1
	v_permlane16_swap_b32_e32 v1, v0
	s_waitcnt lgkmcnt(0)
	v_add_f32_e32 v0, v0, v1
	v_mov_b32_e32 v1, v201
	s_nop 0
	v_lshlrev_b32_e32 v1, 2, v1
	v_xor_b32_e32 v1, 0x80, v1
	v_mov_b32_e32 v1, v0
	s_nop 1
	v_permlane32_swap_b32_e32 v1, v0
	s_waitcnt lgkmcnt(0)
	v_add_f32_e32 v0, v0, v1
	v_fmamk_f32 v0, v0, 0x3c800000, v202
	v_rsq_f32_e32 v12, v0
	s_nop 0
	v_pk_mul_f32 v[0:1], v[24:25], v[12:13] op_sel_hi:[1,0]
	v_pk_mul_f32 v[2:3], v[30:31], v[12:13] op_sel_hi:[1,0]
	v_pk_mul_f32 v[4:5], v[28:29], v[12:13] op_sel_hi:[1,0]
	v_pk_mul_f32 v[6:7], v[26:27], v[12:13] op_sel_hi:[1,0]
	v_pk_mul_f32 v[8:9], v[22:23], v[12:13] op_sel_hi:[1,0]
	v_pk_mul_f32 v[10:11], v[20:21], v[12:13] op_sel_hi:[1,0]
	v_pk_mul_f32 v[32:33], v[16:17], v[12:13] op_sel_hi:[1,0]
	v_pk_mul_f32 v[12:13], v[18:19], v[12:13] op_sel_hi:[1,0]
	v_pk_mul_f32 v[2:3], v[162:163], v[2:3]
	v_pk_mul_f32 v[0:1], v[164:165], v[0:1]
	v_pk_mul_f32 v[6:7], v[158:159], v[6:7]
	v_pk_mul_f32 v[4:5], v[160:161], v[4:5]
	v_pk_mul_f32 v[10:11], v[154:155], v[10:11]
	v_pk_mul_f32 v[8:9], v[156:157], v[8:9]
	v_pk_mul_f32 v[14:15], v[150:151], v[12:13]
	v_pk_mul_f32 v[12:13], v[152:153], v[32:33]

; __device__ __forceinline__ float sq4(f32x4 v) { return (v[0] * v[0] + v[1] * v[1]) + (v[2] * v[2] + v[3] * v[3]); }
; __device__ __forceinline__ u32x4 pack8(f32x4 a, f32x4 b) { u32x4 w; w.x = cvt_pk_bf16(a[0], a[1]); w.y = cvt_pk_bf16(a[2], a[3]); w.z = cvt_pk_bf16(b[0], b[1]); w.w = cvt_pk_bf16(b[2], b[3]); return w; }
;     __device__ __forceinline__ void operator()(const f32x4 (&acc)[2][2][4][2], const Unit& u, int wr, int wc, int fr, int fq) const {
;     ...
;             for (int m = 0; m < 4; ++m)
; #pragma unroll
;                 for (int bj = 0; bj < 2; ++bj) bs[m][bj] = *(const u32x4*)(xb + (size_t)(u.pm * BM + ai * HALF + wr * 64 + m * 16 + fr) * 1024 + col0 + 128 * bj);
; #pragma unroll
;             for (int m = 0; m < 4; ++m) {
;                 const int row = u.pm * BM + ai * HALF + wr * 64 + m * 16 + fr;
;                 float q = 0.f;
; #pragma unroll
;                 for (int bj = 0; bj < 2; ++bj) {
;                     const size_t off = (size_t)row * 1024 + col0 + 128 * bj; const u32x4 w = bs[m][bj];
;                     const f32x4 b0 = (f32x4){__builtin_bit_cast(float, w.x << 16), __builtin_bit_cast(float, w.x & 0xffff0000u), __builtin_bit_cast(float, w.y << 16), __builtin_bit_cast(float, w.y & 0xffff0000u)};
;                     const f32x4 b1 = (f32x4){__builtin_bit_cast(float, w.z << 16), __builtin_bit_cast(float, w.z & 0xffff0000u), __builtin_bit_cast(float, w.w << 16), __builtin_bit_cast(float, w.w & 0xffff0000u)};
;                     const f32x4 v0 = acc[ai][bj][m][0] + b0, v1 = acc[ai][bj][m][1] + b1;
;                     if (last) { __builtin_nontemporal_store(v0, (f32x4*)(out + off)); __builtin_nontemporal_store(v1, (f32x4*)(out + off + 4)); }
;                     else { q += sq4(v0) + sq4(v1); *(u32x4*)(xb + off) = pack8(v0, v1); }
;                 }
;                 if (!last) { q += shx(q, 16); q += shx(q, 32); if (fq == 0) ss[(size_t)row * 16 + u.pn * 4 + wc] = q; }
.LBB0_439:
	v_lshl_or_b32 v168, s14, 8, v188
	v_lshl_add_u32 v172, s42, 8, v186
	v_ashrrev_i32_e32 v169, 31, v168
	v_lshlrev_b64 v[202:203], 1, v[168:169]
	v_ashrrev_i32_e32 v173, 31, v172
	v_lshl_add_u64 v[170:171], s[18:19], 0, v[202:203]
	v_lshlrev_b64 v[204:205], 11, v[172:173]
	v_lshl_add_u64 v[128:129], v[170:171], 0, v[204:205]
	global_load_dwordx4 v[192:195], v[128:129], off
	global_load_dwordx4 v[196:199], v[128:129], off offset:256
	v_or_b32_e32 v182, 16, v172
	v_or_b32_e32 v178, 32, v172
	v_or_b32_e32 v174, 48, v172
	v_ashrrev_i32_e32 v183, 31, v182
	v_ashrrev_i32_e32 v179, 31, v178
	v_ashrrev_i32_e32 v175, 31, v174
	v_lshlrev_b64 v[184:185], 11, v[182:183]
	v_lshlrev_b64 v[180:181], 11, v[178:179]
	v_lshlrev_b64 v[176:177], 11, v[174:175]
	v_lshl_add_u64 v[128:129], v[170:171], 0, v[184:185]
	v_lshl_add_u64 v[130:131], v[170:171], 0, v[180:181]
	v_lshl_add_u64 v[206:207], v[170:171], 0, v[176:177]
	global_load_dwordx4 v[148:151], v[128:129], off
	global_load_dwordx4 v[144:147], v[128:129], off offset:256
	global_load_dwordx4 v[140:143], v[130:131], off
	global_load_dwordx4 v[136:139], v[130:131], off offset:256
	global_load_dwordx4 v[132:135], v[206:207], off
	s_nop 0
	global_load_dwordx4 v[128:131], v[206:207], off offset:256
	v_lshl_add_u64 v[204:205], s[18:19], 0, v[204:205]
	v_lshl_add_u64 v[202:203], v[204:205], 0, v[202:203]
	v_mov_b32_e32 v200, v201
	s_lshl_b32 s42, s14, 2
	s_ashr_i32 s43, s42, 31
	s_waitcnt vmcnt(0)
	v_lshlrev_b32_e32 v204, 16, v192
	v_and_b32_e32 v205, 0xffff0000, v192
	v_lshlrev_b32_e32 v192, 16, v193
	v_and_b32_e32 v193, 0xffff0000, v193
	v_lshlrev_b32_e32 v206, 16, v194
	v_and_b32_e32 v207, 0xffff0000, v194
	v_lshlrev_b32_e32 v194, 16, v195
	v_and_b32_e32 v195, 0xffff0000, v195
	v_lshlrev_b32_e32 v208, 16, v196
	v_and_b32_e32 v209, 0xffff0000, v196
	v_lshlrev_b32_e32 v196, 16, v197
	v_and_b32_e32 v197, 0xffff0000, v197
	v_lshlrev_b32_e32 v210, 16, v198
	v_and_b32_e32 v211, 0xffff0000, v198
	v_lshlrev_b32_e32 v198, 16, v199
	v_and_b32_e32 v199, 0xffff0000, v199
	v_pk_add_f32 v[126:127], v[126:127], v[192:193]
	v_pk_add_f32 v[124:125], v[124:125], v[204:205]
	v_pk_add_f32 v[122:123], v[122:123], v[194:195]
	v_pk_add_f32 v[120:121], v[120:121], v[206:207]
	v_pk_add_f32 v[118:119], v[118:119], v[196:197]
	v_pk_add_f32 v[116:117], v[116:117], v[208:209]
	v_pk_add_f32 v[192:193], v[114:115], v[198:199]
	v_pk_add_f32 v[194:195], v[112:113], v[210:211]
	v_mul_f32_e32 v196, v125, v125
	v_mul_f32_e32 v197, v127, v127
	v_mul_f32_e32 v198, v121, v121
	v_mul_f32_e32 v199, v123, v123
	v_cvt_pk_bf16_f32 v112, v124, v125
	v_cvt_pk_bf16_f32 v113, v126, v127
	v_cvt_pk_bf16_f32 v114, v120, v121
	v_cvt_pk_bf16_f32 v115, v122, v123
	v_mul_f32_e32 v121, v117, v117
	v_mul_f32_e32 v123, v119, v119
	v_mul_f32_e32 v125, v195, v195
	v_mul_f32_e32 v127, v193, v193
	v_fmac_f32_e32 v196, v124, v124
	v_fmac_f32_e32 v197, v126, v126
	v_fmac_f32_e32 v198, v120, v120
	v_fmac_f32_e32 v199, v122, v122
	v_fmac_f32_e32 v121, v116, v116
	v_fmac_f32_e32 v123, v118, v118
	v_fmac_f32_e32 v125, v194, v194
	v_fmac_f32_e32 v127, v192, v192
	global_store_dwordx4 v[202:203], v[112:115], off
	s_nop 1
	v_cvt_pk_bf16_f32 v112, v116, v117
	v_cvt_pk_bf16_f32 v113, v118, v119
	v_cvt_pk_bf16_f32 v114, v194, v195
	v_add_f32_e32 v116, v196, v197
	v_add_f32_e32 v117, v198, v199
	v_add_f32_e32 v118, v121, v123
	v_add_f32_e32 v119, v125, v127
	v_cvt_pk_bf16_f32 v115, v192, v193
	global_store_dwordx4 v[202:203], v[112:115], off offset:256
	s_nop 1
	v_add_f32_e32 v112, v116, v117
	v_add_f32_e32 v113, v118, v119
	v_lshlrev_b32_e32 v114, 2, v200
	v_add_f32_e32 v112, v112, v113
	v_xor_b32_e32 v113, 64, v114
	v_mov_b32_e32 v113, v112
	s_nop 1
	v_permlane16_swap_b32_e32 v113, v112
	v_mov_b32_e32 v114, v201
	s_waitcnt lgkmcnt(0)
	v_add_f32_e32 v112, v112, v113
	v_lshlrev_b32_e32 v114, 2, v114
	v_xor_b32_e32 v113, 0x80, v114
	v_mov_b32_e32 v113, v112
	s_nop 1
	v_permlane32_swap_b32_e32 v113, v112
	s_and_saveexec_b64 s[44:45], s[10:11]
	s_cbranch_execz .LBB0_441
	s_waitcnt lgkmcnt(0)
	v_add_f32_e32 v114, v112, v113
	v_lshlrev_b64 v[112:113], 6, v[172:173]
	v_lshl_add_u64 v[112:113], s[22:23], 0, v[112:113]
	v_lshl_add_u64 v[112:113], s[42:43], 2, v[112:113]
	s_lshl_b32 s14, s52, 2
	v_lshl_add_u64 v[112:113], v[112:113], 0, s[14:15]
	global_store_dword v[112:113], v114, off
; __device__ __forceinline__ float sq4(f32x4 v) { return (v[0] * v[0] + v[1] * v[1]) + (v[2] * v[2] + v[3] * v[3]); }
; __device__ __forceinline__ u32x4 pack8(f32x4 a, f32x4 b) { u32x4 w; w.x = cvt_pk_bf16(a[0], a[1]); w.y = cvt_pk_bf16(a[2], a[3]); w.z = cvt_pk_bf16(b[0], b[1]); w.w = cvt_pk_bf16(b[2], b[3]); return w; }
;     __device__ __forceinline__ void operator()(const f32x4 (&acc)[2][2][4][2], const Unit& u, int wr, int wc, int fr, int fq) const {
;     ...
;             for (int m = 0; m < 4; ++m) {
;                 const int row = u.pm * BM + ai * HALF + wr * 64 + m * 16 + fr;
;                 float q = 0.f;
; #pragma unroll
;                 for (int bj = 0; bj < 2; ++bj) {
;                     const size_t off = (size_t)row * 1024 + col0 + 128 * bj; const u32x4 w = bs[m][bj];
;                     const f32x4 b0 = (f32x4){__builtin_bit_cast(float, w.x << 16), __builtin_bit_cast(float, w.x & 0xffff0000u), __builtin_bit_cast(float, w.y << 16), __builtin_bit_cast(float, w.y & 0xffff0000u)};
;                     const f32x4 b1 = (f32x4){__builtin_bit_cast(float, w.z << 16), __builtin_bit_cast(float, w.z & 0xffff0000u), __builtin_bit_cast(float, w.w << 16), __builtin_bit_cast(float, w.w & 0xffff0000u)};
;                     const f32x4 v0 = acc[ai][bj][m][0] + b0, v1 = acc[ai][bj][m][1] + b1;
;                     if (last) { __builtin_nontemporal_store(v0, (f32x4*)(out + off)); __builtin_nontemporal_store(v1, (f32x4*)(out + off + 4)); }
;                     else { q += sq4(v0) + sq4(v1); *(u32x4*)(xb + off) = pack8(v0, v1); }
;                 }
;                 if (!last) { q += shx(q, 16); q += shx(q, 32); if (fq == 0) ss[(size_t)row * 16 + u.pn * 4 + wc] = q; }
.LBB0_441:
	s_or_b64 exec, exec, s[44:45]
	v_lshlrev_b32_e32 v112, 16, v148
	s_waitcnt lgkmcnt(0)
	v_and_b32_e32 v113, 0xffff0000, v148
	v_lshlrev_b32_e32 v114, 16, v149
	v_and_b32_e32 v115, 0xffff0000, v149
	v_lshlrev_b32_e32 v116, 16, v150
	v_and_b32_e32 v117, 0xffff0000, v150
	v_lshlrev_b32_e32 v118, 16, v151
	v_and_b32_e32 v119, 0xffff0000, v151
	v_pk_add_f32 v[110:111], v[110:111], v[114:115]
	v_pk_add_f32 v[108:109], v[108:109], v[112:113]
	v_pk_add_f32 v[112:113], v[106:107], v[118:119]
	v_pk_add_f32 v[106:107], v[104:105], v[116:117]
	v_mul_f32_e32 v104, v109, v109
	v_mul_f32_e32 v105, v111, v111
	v_fmac_f32_e32 v104, v108, v108
	v_fmac_f32_e32 v105, v110, v110
	v_add_f32_e32 v104, v104, v105
	v_mul_f32_e32 v105, v107, v107
	v_mul_f32_e32 v114, v113, v113
	v_fmac_f32_e32 v105, v106, v106
	v_fmac_f32_e32 v114, v112, v112
	v_add_f32_e32 v105, v105, v114
	v_add_f32_e32 v114, v104, v105
	v_cvt_pk_bf16_f32 v104, v108, v109
	v_lshl_add_u64 v[108:109], s[18:19], 0, v[184:185]
	v_cvt_pk_bf16_f32 v105, v110, v111
	v_cvt_pk_bf16_f32 v106, v106, v107
	v_cvt_pk_bf16_f32 v107, v112, v113
	v_lshl_add_u64 v[108:109], v[168:169], 1, v[108:109]
	global_store_dwordx4 v[108:109], v[104:107], off
	v_lshlrev_b32_e32 v110, 16, v146
	v_and_b32_e32 v111, 0xffff0000, v146
	v_lshlrev_b32_e32 v104, 16, v144
	v_and_b32_e32 v105, 0xffff0000, v144
	v_lshlrev_b32_e32 v106, 16, v145
	v_and_b32_e32 v107, 0xffff0000, v145
	v_lshlrev_b32_e32 v112, 16, v147
	v_and_b32_e32 v113, 0xffff0000, v147
	v_pk_add_f32 v[102:103], v[102:103], v[106:107]
	v_pk_add_f32 v[100:101], v[100:101], v[104:105]
	v_pk_add_f32 v[104:105], v[98:99], v[112:113]
	v_pk_add_f32 v[98:99], v[96:97], v[110:111]
	v_mul_f32_e32 v96, v101, v101
	v_mul_f32_e32 v97, v103, v103
	v_fmac_f32_e32 v96, v100, v100
	v_fmac_f32_e32 v97, v102, v102
	v_add_f32_e32 v96, v96, v97
	v_mul_f32_e32 v97, v99, v99
	v_mul_f32_e32 v106, v105, v105
	v_fmac_f32_e32 v97, v98, v98
	v_fmac_f32_e32 v106, v104, v104
	v_add_f32_e32 v97, v97, v106
	v_add_f32_e32 v96, v96, v97
	v_add_f32_e32 v106, v114, v96
	v_cvt_pk_bf16_f32 v96, v100, v101
	v_cvt_pk_bf16_f32 v97, v102, v103
	v_cvt_pk_bf16_f32 v98, v98, v99
	v_cvt_pk_bf16_f32 v99, v104, v105
	global_store_dwordx4 v[108:109], v[96:99], off offset:256
	s_nop 1
	v_mov_b32_e32 v96, v201
	v_mov_b32_e32 v97, v201
	v_lshlrev_b32_e32 v96, 2, v96
	v_xor_b32_e32 v96, 64, v96
	v_mov_b32_e32 v96, v106
	s_nop 1
	v_permlane16_swap_b32_e32 v96, v106
	s_waitcnt lgkmcnt(0)
	v_add_f32_e32 v96, v106, v96
	v_lshlrev_b32_e32 v97, 2, v97
	v_xor_b32_e32 v97, 0x80, v97
	v_mov_b32_e32 v97, v96
	s_nop 1
	v_permlane32_swap_b32_e32 v97, v96
	s_and_saveexec_b64 s[44:45], s[10:11]
	s_cbranch_execz .LBB0_443
	s_waitcnt lgkmcnt(0)
	v_add_f32_e32 v98, v96, v97
	v_lshlrev_b64 v[96:97], 6, v[182:183]
	v_lshl_add_u64 v[96:97], s[22:23], 0, v[96:97]
	v_lshl_add_u64 v[96:97], s[42:43], 2, v[96:97]
	s_lshl_b32 s14, s52, 2
	v_lshl_add_u64 v[96:97], v[96:97], 0, s[14:15]
	global_store_dword v[96:97], v98, off
.LBB0_443:
	s_or_b64 exec, exec, s[44:45]
	v_lshlrev_b32_e32 v96, 16, v140
	s_waitcnt lgkmcnt(0)
	v_and_b32_e32 v97, 0xffff0000, v140
	v_lshlrev_b32_e32 v98, 16, v141
	v_and_b32_e32 v99, 0xffff0000, v141
	v_lshlrev_b32_e32 v100, 16, v142
	v_and_b32_e32 v101, 0xffff0000, v142
	v_lshlrev_b32_e32 v102, 16, v143
	v_and_b32_e32 v103, 0xffff0000, v143
	v_pk_add_f32 v[94:95], v[94:95], v[98:99]
	v_pk_add_f32 v[92:93], v[92:93], v[96:97]
	v_pk_add_f32 v[96:97], v[90:91], v[102:103]
	v_pk_add_f32 v[90:91], v[88:89], v[100:101]
	v_mul_f32_e32 v88, v93, v93
	v_mul_f32_e32 v89, v95, v95
	v_fmac_f32_e32 v88, v92, v92
	v_fmac_f32_e32 v89, v94, v94
	v_add_f32_e32 v88, v88, v89
	v_mul_f32_e32 v89, v91, v91
	v_mul_f32_e32 v98, v97, v97
	v_fmac_f32_e32 v89, v90, v90
	v_fmac_f32_e32 v98, v96, v96
	v_add_f32_e32 v89, v89, v98
	v_add_f32_e32 v98, v88, v89
	v_cvt_pk_bf16_f32 v88, v92, v93
	v_lshl_add_u64 v[92:93], s[18:19], 0, v[180:181]
	v_cvt_pk_bf16_f32 v89, v94, v95
	v_cvt_pk_bf16_f32 v90, v90, v91
	v_cvt_pk_bf16_f32 v91, v96, v97
	v_lshl_add_u64 v[92:93], v[168:169], 1, v[92:93]
	global_store_dwordx4 v[92:93], v[88:91], off
	v_lshlrev_b32_e32 v94, 16, v138
	v_and_b32_e32 v95, 0xffff0000, v138
	v_lshlrev_b32_e32 v88, 16, v136
	v_and_b32_e32 v89, 0xffff0000, v136
	v_lshlrev_b32_e32 v90, 16, v137
	v_and_b32_e32 v91, 0xffff0000, v137
	v_lshlrev_b32_e32 v96, 16, v139
	v_and_b32_e32 v97, 0xffff0000, v139
	v_pk_add_f32 v[86:87], v[86:87], v[90:91]
	v_pk_add_f32 v[84:85], v[84:85], v[88:89]
	v_pk_add_f32 v[88:89], v[82:83], v[96:97]
	v_pk_add_f32 v[82:83], v[80:81], v[94:95]
	v_mul_f32_e32 v80, v85, v85
	v_mul_f32_e32 v81, v87, v87
	v_fmac_f32_e32 v80, v84, v84
	v_fmac_f32_e32 v81, v86, v86
	v_add_f32_e32 v80, v80, v81
	v_mul_f32_e32 v81, v83, v83
	v_mul_f32_e32 v90, v89, v89
	v_fmac_f32_e32 v81, v82, v82
	v_fmac_f32_e32 v90, v88, v88
	v_add_f32_e32 v81, v81, v90
	v_add_f32_e32 v80, v80, v81
	v_add_f32_e32 v90, v98, v80
	v_cvt_pk_bf16_f32 v80, v84, v85
	v_cvt_pk_bf16_f32 v81, v86, v87
	v_cvt_pk_bf16_f32 v82, v82, v83
	v_cvt_pk_bf16_f32 v83, v88, v89
	global_store_dwordx4 v[92:93], v[80:83], off offset:256
	s_nop 1
	v_mov_b32_e32 v80, v201
	v_mov_b32_e32 v81, v201
	v_lshlrev_b32_e32 v80, 2, v80
	v_xor_b32_e32 v80, 64, v80
	v_mov_b32_e32 v80, v90
	s_nop 1
	v_permlane16_swap_b32_e32 v80, v90
	s_waitcnt lgkmcnt(0)
	v_add_f32_e32 v80, v90, v80
	v_lshlrev_b32_e32 v81, 2, v81
	v_xor_b32_e32 v81, 0x80, v81
	v_mov_b32_e32 v81, v80
	s_nop 1
	v_permlane32_swap_b32_e32 v81, v80
	s_and_saveexec_b64 s[44:45], s[10:11]
	s_cbranch_execz .LBB0_445
	s_waitcnt lgkmcnt(0)
	v_add_f32_e32 v82, v80, v81
	v_lshlrev_b64 v[80:81], 6, v[178:179]
	v_lshl_add_u64 v[80:81], s[22:23], 0, v[80:81]
	v_lshl_add_u64 v[80:81], s[42:43], 2, v[80:81]
	s_lshl_b32 s14, s52, 2
	v_lshl_add_u64 v[80:81], v[80:81], 0, s[14:15]
	global_store_dword v[80:81], v82, off
; __device__ __forceinline__ float sq4(f32x4 v) { return (v[0] * v[0] + v[1] * v[1]) + (v[2] * v[2] + v[3] * v[3]); }
; __device__ __forceinline__ u32x4 pack8(f32x4 a, f32x4 b) { u32x4 w; w.x = cvt_pk_bf16(a[0], a[1]); w.y = cvt_pk_bf16(a[2], a[3]); w.z = cvt_pk_bf16(b[0], b[1]); w.w = cvt_pk_bf16(b[2], b[3]); return w; }
;     __device__ __forceinline__ void operator()(const f32x4 (&acc)[2][2][4][2], const Unit& u, int wr, int wc, int fr, int fq) const {
;     ...
;             u32x4 bs[4][2];
; #pragma unroll
;             for (int m = 0; m < 4; ++m)
; #pragma unroll
;                 for (int bj = 0; bj < 2; ++bj) bs[m][bj] = *(const u32x4*)(xb + (size_t)(u.pm * BM + ai * HALF + wr * 64 + m * 16 + fr) * 1024 + col0 + 128 * bj);
; #pragma unroll
;             for (int m = 0; m < 4; ++m) {
;                 const int row = u.pm * BM + ai * HALF + wr * 64 + m * 16 + fr;
;                 float q = 0.f;
; #pragma unroll
;                 for (int bj = 0; bj < 2; ++bj) {
;                     const size_t off = (size_t)row * 1024 + col0 + 128 * bj; const u32x4 w = bs[m][bj];
;                     const f32x4 b0 = (f32x4){__builtin_bit_cast(float, w.x << 16), __builtin_bit_cast(float, w.x & 0xffff0000u), __builtin_bit_cast(float, w.y << 16), __builtin_bit_cast(float, w.y & 0xffff0000u)};
;                     const f32x4 b1 = (f32x4){__builtin_bit_cast(float, w.z << 16), __builtin_bit_cast(float, w.z & 0xffff0000u), __builtin_bit_cast(float, w.w << 16), __builtin_bit_cast(float, w.w & 0xffff0000u)};
;                     const f32x4 v0 = acc[ai][bj][m][0] + b0, v1 = acc[ai][bj][m][1] + b1;
;                     if (last) { __builtin_nontemporal_store(v0, (f32x4*)(out + off)); __builtin_nontemporal_store(v1, (f32x4*)(out + off + 4)); }
;                     else { q += sq4(v0) + sq4(v1); *(u32x4*)(xb + off) = pack8(v0, v1); }
;                 }
;                 if (!last) { q += shx(q, 16); q += shx(q, 32); if (fq == 0) ss[(size_t)row * 16 + u.pn * 4 + wc] = q; }
.LBB0_445:
	s_or_b64 exec, exec, s[44:45]
	v_lshlrev_b32_e32 v80, 16, v132
	s_waitcnt lgkmcnt(0)
	v_and_b32_e32 v81, 0xffff0000, v132
	v_lshlrev_b32_e32 v82, 16, v133
	v_and_b32_e32 v83, 0xffff0000, v133
	v_lshlrev_b32_e32 v84, 16, v134
	v_and_b32_e32 v85, 0xffff0000, v134
	v_lshlrev_b32_e32 v86, 16, v135
	v_and_b32_e32 v87, 0xffff0000, v135
	v_pk_add_f32 v[78:79], v[78:79], v[82:83]
	v_pk_add_f32 v[76:77], v[76:77], v[80:81]
	v_pk_add_f32 v[80:81], v[74:75], v[86:87]
	v_pk_add_f32 v[74:75], v[72:73], v[84:85]
	v_mul_f32_e32 v72, v77, v77
	v_mul_f32_e32 v73, v79, v79
	v_fmac_f32_e32 v72, v76, v76
	v_fmac_f32_e32 v73, v78, v78
	v_add_f32_e32 v72, v72, v73
	v_mul_f32_e32 v73, v75, v75
	v_mul_f32_e32 v82, v81, v81
	v_fmac_f32_e32 v73, v74, v74
	v_fmac_f32_e32 v82, v80, v80
	v_add_f32_e32 v73, v73, v82
	v_add_f32_e32 v82, v72, v73
	v_cvt_pk_bf16_f32 v72, v76, v77
	v_lshl_add_u64 v[76:77], s[18:19], 0, v[176:177]
	v_cvt_pk_bf16_f32 v73, v78, v79
	v_cvt_pk_bf16_f32 v74, v74, v75
	v_cvt_pk_bf16_f32 v75, v80, v81
	v_lshl_add_u64 v[76:77], v[168:169], 1, v[76:77]
	global_store_dwordx4 v[76:77], v[72:75], off
	v_lshlrev_b32_e32 v78, 16, v130
	v_and_b32_e32 v79, 0xffff0000, v130
	v_lshlrev_b32_e32 v72, 16, v128
	v_and_b32_e32 v73, 0xffff0000, v128
	v_lshlrev_b32_e32 v74, 16, v129
	v_and_b32_e32 v75, 0xffff0000, v129
	v_lshlrev_b32_e32 v80, 16, v131
	v_and_b32_e32 v81, 0xffff0000, v131
	v_pk_add_f32 v[70:71], v[70:71], v[74:75]
	v_pk_add_f32 v[68:69], v[68:69], v[72:73]
	v_pk_add_f32 v[72:73], v[66:67], v[80:81]
	v_pk_add_f32 v[66:67], v[64:65], v[78:79]
	v_mul_f32_e32 v64, v69, v69
	v_mul_f32_e32 v65, v71, v71
	v_fmac_f32_e32 v64, v68, v68
	v_fmac_f32_e32 v65, v70, v70
	v_add_f32_e32 v64, v64, v65
	v_mul_f32_e32 v65, v67, v67
	v_mul_f32_e32 v74, v73, v73
	v_fmac_f32_e32 v65, v66, v66
	v_fmac_f32_e32 v74, v72, v72
	v_add_f32_e32 v65, v65, v74
	v_add_f32_e32 v64, v64, v65
	v_add_f32_e32 v74, v82, v64
	v_cvt_pk_bf16_f32 v64, v68, v69
	v_cvt_pk_bf16_f32 v65, v70, v71
	v_cvt_pk_bf16_f32 v66, v66, v67
	v_cvt_pk_bf16_f32 v67, v72, v73
	global_store_dwordx4 v[76:77], v[64:67], off offset:256
	s_nop 1
	v_mov_b32_e32 v64, v201
	v_mov_b32_e32 v65, v201
	v_lshlrev_b32_e32 v64, 2, v64
	v_xor_b32_e32 v64, 64, v64
	v_mov_b32_e32 v64, v74
	s_nop 1
	v_permlane16_swap_b32_e32 v64, v74
	s_waitcnt lgkmcnt(0)
	v_add_f32_e32 v64, v74, v64
	v_lshlrev_b32_e32 v65, 2, v65
	v_xor_b32_e32 v65, 0x80, v65
	v_mov_b32_e32 v65, v64
	s_nop 1
	v_permlane32_swap_b32_e32 v65, v64
	s_and_saveexec_b64 s[44:45], s[10:11]
	s_cbranch_execz .LBB0_447
	s_waitcnt lgkmcnt(0)
	v_add_f32_e32 v66, v64, v65
	v_lshlrev_b64 v[64:65], 6, v[174:175]
	v_lshl_add_u64 v[64:65], s[22:23], 0, v[64:65]
	v_lshl_add_u64 v[64:65], s[42:43], 2, v[64:65]
	s_lshl_b32 s14, s52, 2
	v_lshl_add_u64 v[64:65], v[64:65], 0, s[14:15]
	global_store_dword v[64:65], v66, off
.LBB0_447:
	s_or_b64 exec, exec, s[44:45]
	v_add_u32_e32 v100, 0x80, v172
	v_ashrrev_i32_e32 v101, 31, v100
	v_lshlrev_b64 v[110:111], 11, v[100:101]
	s_waitcnt lgkmcnt(0)
	v_lshl_add_u64 v[64:65], v[170:171], 0, v[110:111]
	global_load_dwordx4 v[102:105], v[64:65], off
	global_load_dwordx4 v[106:109], v[64:65], off offset:256
	v_add_u32_e32 v96, 0x90, v172
	v_add_u32_e32 v92, 0xa0, v172
	v_add_u32_e32 v88, 0xb0, v172
	v_ashrrev_i32_e32 v97, 31, v96
	v_ashrrev_i32_e32 v93, 31, v92
	v_ashrrev_i32_e32 v89, 31, v88
	v_lshlrev_b64 v[98:99], 11, v[96:97]
	v_lshlrev_b64 v[94:95], 11, v[92:93]
	v_lshlrev_b64 v[90:91], 11, v[88:89]
	v_lshl_add_u64 v[64:65], v[170:171], 0, v[98:99]
	v_lshl_add_u64 v[66:67], v[170:171], 0, v[94:95]
	v_lshl_add_u64 v[112:113], v[170:171], 0, v[90:91]
	global_load_dwordx4 v[84:87], v[64:65], off
	global_load_dwordx4 v[80:83], v[64:65], off offset:256
	global_load_dwordx4 v[76:79], v[66:67], off
	global_load_dwordx4 v[72:75], v[66:67], off offset:256
	global_load_dwordx4 v[68:71], v[112:113], off
	s_nop 0
	global_load_dwordx4 v[64:67], v[112:113], off offset:256
	v_lshl_add_u64 v[110:111], s[18:19], 0, v[110:111]
	v_lshl_add_u64 v[110:111], v[168:169], 1, v[110:111]
	v_mov_b32_e32 v120, v201
	s_waitcnt vmcnt(7)
	v_lshlrev_b32_e32 v112, 16, v102
	v_and_b32_e32 v113, 0xffff0000, v102
	v_lshlrev_b32_e32 v102, 16, v103
	v_and_b32_e32 v103, 0xffff0000, v103
	v_lshlrev_b32_e32 v114, 16, v104
	v_and_b32_e32 v115, 0xffff0000, v104
	v_lshlrev_b32_e32 v104, 16, v105
	v_and_b32_e32 v105, 0xffff0000, v105
	s_waitcnt vmcnt(6)
	v_lshlrev_b32_e32 v116, 16, v106
	v_and_b32_e32 v117, 0xffff0000, v106
	v_lshlrev_b32_e32 v106, 16, v107
	v_and_b32_e32 v107, 0xffff0000, v107
	v_lshlrev_b32_e32 v118, 16, v108
	v_and_b32_e32 v119, 0xffff0000, v108
	v_lshlrev_b32_e32 v108, 16, v109
	v_and_b32_e32 v109, 0xffff0000, v109
	v_pk_add_f32 v[62:63], v[62:63], v[102:103]
	v_pk_add_f32 v[60:61], v[60:61], v[112:113]
	v_pk_add_f32 v[58:59], v[58:59], v[104:105]
	v_pk_add_f32 v[56:57], v[56:57], v[114:115]
	v_pk_add_f32 v[54:55], v[54:55], v[106:107]
	v_pk_add_f32 v[52:53], v[52:53], v[116:117]
	v_pk_add_f32 v[102:103], v[50:51], v[108:109]
	v_pk_add_f32 v[104:105], v[48:49], v[118:119]
	v_mul_f32_e32 v106, v61, v61
	v_mul_f32_e32 v107, v63, v63
	v_mul_f32_e32 v108, v57, v57
	v_mul_f32_e32 v109, v59, v59
	v_cvt_pk_bf16_f32 v48, v60, v61
	v_cvt_pk_bf16_f32 v49, v62, v63
	v_cvt_pk_bf16_f32 v50, v56, v57
	v_cvt_pk_bf16_f32 v51, v58, v59
	v_mul_f32_e32 v57, v53, v53
	v_mul_f32_e32 v59, v55, v55
	v_mul_f32_e32 v61, v105, v105
	v_mul_f32_e32 v63, v103, v103
	v_fmac_f32_e32 v106, v60, v60
	v_fmac_f32_e32 v107, v62, v62
	v_fmac_f32_e32 v108, v56, v56
	v_fmac_f32_e32 v109, v58, v58
	v_fmac_f32_e32 v57, v52, v52
	v_fmac_f32_e32 v59, v54, v54
	v_fmac_f32_e32 v61, v104, v104
	v_fmac_f32_e32 v63, v102, v102
	global_store_dwordx4 v[110:111], v[48:51], off
	s_nop 1
	v_cvt_pk_bf16_f32 v48, v52, v53
	v_cvt_pk_bf16_f32 v49, v54, v55
	v_cvt_pk_bf16_f32 v50, v104, v105
	v_add_f32_e32 v52, v106, v107
	v_add_f32_e32 v53, v108, v109
	v_add_f32_e32 v54, v57, v59
	v_add_f32_e32 v55, v61, v63
	v_cvt_pk_bf16_f32 v51, v102, v103
	global_store_dwordx4 v[110:111], v[48:51], off offset:256
	s_nop 1
	v_add_f32_e32 v48, v52, v53
	v_add_f32_e32 v49, v54, v55
	v_lshlrev_b32_e32 v50, 2, v120
	v_add_f32_e32 v48, v48, v49
	v_xor_b32_e32 v49, 64, v50
	v_mov_b32_e32 v49, v48
	s_nop 1
	v_permlane16_swap_b32_e32 v49, v48
	v_mov_b32_e32 v50, v201
	s_waitcnt lgkmcnt(0)
	v_add_f32_e32 v48, v48, v49
	v_lshlrev_b32_e32 v50, 2, v50
	v_xor_b32_e32 v49, 0x80, v50
	v_mov_b32_e32 v49, v48
	s_nop 1
	v_permlane32_swap_b32_e32 v49, v48
	s_and_saveexec_b64 s[44:45], s[10:11]
	s_cbranch_execz .LBB0_449
	s_waitcnt lgkmcnt(0)
	v_add_f32_e32 v50, v48, v49
	v_lshlrev_b64 v[48:49], 6, v[100:101]
	v_lshl_add_u64 v[48:49], s[22:23], 0, v[48:49]
	v_lshl_add_u64 v[48:49], s[42:43], 2, v[48:49]
	s_lshl_b32 s14, s52, 2
	v_lshl_add_u64 v[48:49], v[48:49], 0, s[14:15]
	global_store_dword v[48:49], v50, off
; __device__ __forceinline__ float sq4(f32x4 v) { return (v[0] * v[0] + v[1] * v[1]) + (v[2] * v[2] + v[3] * v[3]); }
; __device__ __forceinline__ u32x4 pack8(f32x4 a, f32x4 b) { u32x4 w; w.x = cvt_pk_bf16(a[0], a[1]); w.y = cvt_pk_bf16(a[2], a[3]); w.z = cvt_pk_bf16(b[0], b[1]); w.w = cvt_pk_bf16(b[2], b[3]); return w; }
;     __device__ __forceinline__ void operator()(const f32x4 (&acc)[2][2][4][2], const Unit& u, int wr, int wc, int fr, int fq) const {
;     ...
;             for (int m = 0; m < 4; ++m) {
;                 const int row = u.pm * BM + ai * HALF + wr * 64 + m * 16 + fr;
;                 float q = 0.f;
; #pragma unroll
;                 for (int bj = 0; bj < 2; ++bj) {
;                     const size_t off = (size_t)row * 1024 + col0 + 128 * bj; const u32x4 w = bs[m][bj];
;                     const f32x4 b0 = (f32x4){__builtin_bit_cast(float, w.x << 16), __builtin_bit_cast(float, w.x & 0xffff0000u), __builtin_bit_cast(float, w.y << 16), __builtin_bit_cast(float, w.y & 0xffff0000u)};
;                     const f32x4 b1 = (f32x4){__builtin_bit_cast(float, w.z << 16), __builtin_bit_cast(float, w.z & 0xffff0000u), __builtin_bit_cast(float, w.w << 16), __builtin_bit_cast(float, w.w & 0xffff0000u)};
;                     const f32x4 v0 = acc[ai][bj][m][0] + b0, v1 = acc[ai][bj][m][1] + b1;
;                     if (last) { __builtin_nontemporal_store(v0, (f32x4*)(out + off)); __builtin_nontemporal_store(v1, (f32x4*)(out + off + 4)); }
;                     else { q += sq4(v0) + sq4(v1); *(u32x4*)(xb + off) = pack8(v0, v1); }
;                 }
;                 if (!last) { q += shx(q, 16); q += shx(q, 32); if (fq == 0) ss[(size_t)row * 16 + u.pn * 4 + wc] = q; }
.LBB0_449:
	s_or_b64 exec, exec, s[44:45]
	s_waitcnt vmcnt(7)
	v_lshlrev_b32_e32 v48, 16, v84
	s_waitcnt lgkmcnt(0)
	v_and_b32_e32 v49, 0xffff0000, v84
	v_lshlrev_b32_e32 v50, 16, v85
	v_and_b32_e32 v51, 0xffff0000, v85
	v_lshlrev_b32_e32 v52, 16, v86
	v_and_b32_e32 v53, 0xffff0000, v86
	v_lshlrev_b32_e32 v54, 16, v87
	v_and_b32_e32 v55, 0xffff0000, v87
	v_pk_add_f32 v[46:47], v[46:47], v[50:51]
	v_pk_add_f32 v[44:45], v[44:45], v[48:49]
	v_pk_add_f32 v[48:49], v[42:43], v[54:55]
	v_pk_add_f32 v[42:43], v[40:41], v[52:53]
	v_mul_f32_e32 v40, v45, v45
	v_mul_f32_e32 v41, v47, v47
	v_fmac_f32_e32 v40, v44, v44
	v_fmac_f32_e32 v41, v46, v46
	v_add_f32_e32 v40, v40, v41
	v_mul_f32_e32 v41, v43, v43
	v_mul_f32_e32 v50, v49, v49
	v_fmac_f32_e32 v41, v42, v42
	v_fmac_f32_e32 v50, v48, v48
	v_add_f32_e32 v41, v41, v50
	v_add_f32_e32 v50, v40, v41
	v_cvt_pk_bf16_f32 v40, v44, v45
	v_lshl_add_u64 v[44:45], s[18:19], 0, v[98:99]
	v_cvt_pk_bf16_f32 v41, v46, v47
	v_cvt_pk_bf16_f32 v42, v42, v43
	v_cvt_pk_bf16_f32 v43, v48, v49
	v_lshl_add_u64 v[44:45], v[168:169], 1, v[44:45]
	global_store_dwordx4 v[44:45], v[40:43], off
	s_waitcnt vmcnt(7)
	v_lshlrev_b32_e32 v46, 16, v82
	v_and_b32_e32 v47, 0xffff0000, v82
	v_lshlrev_b32_e32 v40, 16, v80
	v_and_b32_e32 v41, 0xffff0000, v80
	v_lshlrev_b32_e32 v42, 16, v81
	v_and_b32_e32 v43, 0xffff0000, v81
	v_lshlrev_b32_e32 v48, 16, v83
	v_and_b32_e32 v49, 0xffff0000, v83
	v_pk_add_f32 v[38:39], v[38:39], v[42:43]
	v_pk_add_f32 v[36:37], v[36:37], v[40:41]
	v_pk_add_f32 v[40:41], v[34:35], v[48:49]
	v_pk_add_f32 v[34:35], v[32:33], v[46:47]
	v_mul_f32_e32 v32, v37, v37
	v_mul_f32_e32 v33, v39, v39
	v_fmac_f32_e32 v32, v36, v36
	v_fmac_f32_e32 v33, v38, v38
	v_add_f32_e32 v32, v32, v33
	v_mul_f32_e32 v33, v35, v35
	v_mul_f32_e32 v42, v41, v41
	v_fmac_f32_e32 v33, v34, v34
	v_fmac_f32_e32 v42, v40, v40
	v_add_f32_e32 v33, v33, v42
	v_add_f32_e32 v32, v32, v33
	v_add_f32_e32 v42, v50, v32
	v_cvt_pk_bf16_f32 v32, v36, v37
	v_cvt_pk_bf16_f32 v33, v38, v39
	v_cvt_pk_bf16_f32 v34, v34, v35
	v_cvt_pk_bf16_f32 v35, v40, v41
	global_store_dwordx4 v[44:45], v[32:35], off offset:256
	s_nop 1
	v_mov_b32_e32 v32, v201
	v_mov_b32_e32 v33, v201
	v_lshlrev_b32_e32 v32, 2, v32
	v_xor_b32_e32 v32, 64, v32
	v_mov_b32_e32 v32, v42
	s_nop 1
	v_permlane16_swap_b32_e32 v32, v42
	s_waitcnt lgkmcnt(0)
	v_add_f32_e32 v32, v42, v32
	v_lshlrev_b32_e32 v33, 2, v33
	v_xor_b32_e32 v33, 0x80, v33
	v_mov_b32_e32 v33, v32
	s_nop 1
	v_permlane32_swap_b32_e32 v33, v32
	s_and_saveexec_b64 s[44:45], s[10:11]
	s_cbranch_execz .LBB0_451
	s_waitcnt lgkmcnt(0)
	v_add_f32_e32 v34, v32, v33
	v_lshlrev_b64 v[32:33], 6, v[96:97]
	v_lshl_add_u64 v[32:33], s[22:23], 0, v[32:33]
	v_lshl_add_u64 v[32:33], s[42:43], 2, v[32:33]
	s_lshl_b32 s14, s52, 2
	v_lshl_add_u64 v[32:33], v[32:33], 0, s[14:15]
	global_store_dword v[32:33], v34, off
; __device__ __forceinline__ float sq4(f32x4 v) { return (v[0] * v[0] + v[1] * v[1]) + (v[2] * v[2] + v[3] * v[3]); }
; __device__ __forceinline__ u32x4 pack8(f32x4 a, f32x4 b) { u32x4 w; w.x = cvt_pk_bf16(a[0], a[1]); w.y = cvt_pk_bf16(a[2], a[3]); w.z = cvt_pk_bf16(b[0], b[1]); w.w = cvt_pk_bf16(b[2], b[3]); return w; }
;     __device__ __forceinline__ void operator()(const f32x4 (&acc)[2][2][4][2], const Unit& u, int wr, int wc, int fr, int fq) const {
;     ...
;             for (int m = 0; m < 4; ++m) {
;                 const int row = u.pm * BM + ai * HALF + wr * 64 + m * 16 + fr;
;                 float q = 0.f;
; #pragma unroll
;                 for (int bj = 0; bj < 2; ++bj) {
;                     const size_t off = (size_t)row * 1024 + col0 + 128 * bj; const u32x4 w = bs[m][bj];
;                     const f32x4 b0 = (f32x4){__builtin_bit_cast(float, w.x << 16), __builtin_bit_cast(float, w.x & 0xffff0000u), __builtin_bit_cast(float, w.y << 16), __builtin_bit_cast(float, w.y & 0xffff0000u)};
;                     const f32x4 b1 = (f32x4){__builtin_bit_cast(float, w.z << 16), __builtin_bit_cast(float, w.z & 0xffff0000u), __builtin_bit_cast(float, w.w << 16), __builtin_bit_cast(float, w.w & 0xffff0000u)};
;                     const f32x4 v0 = acc[ai][bj][m][0] + b0, v1 = acc[ai][bj][m][1] + b1;
;                     if (last) { __builtin_nontemporal_store(v0, (f32x4*)(out + off)); __builtin_nontemporal_store(v1, (f32x4*)(out + off + 4)); }
;                     else { q += sq4(v0) + sq4(v1); *(u32x4*)(xb + off) = pack8(v0, v1); }
;                 }
;                 if (!last) { q += shx(q, 16); q += shx(q, 32); if (fq == 0) ss[(size_t)row * 16 + u.pn * 4 + wc] = q; }
.LBB0_451:
	s_or_b64 exec, exec, s[44:45]
	s_waitcnt vmcnt(7)
	v_lshlrev_b32_e32 v32, 16, v76
	s_waitcnt lgkmcnt(0)
	v_and_b32_e32 v33, 0xffff0000, v76
	v_lshlrev_b32_e32 v34, 16, v77
	v_and_b32_e32 v35, 0xffff0000, v77
	v_lshlrev_b32_e32 v36, 16, v78
	v_and_b32_e32 v37, 0xffff0000, v78
	v_lshlrev_b32_e32 v38, 16, v79
	v_and_b32_e32 v39, 0xffff0000, v79
	v_pk_add_f32 v[30:31], v[30:31], v[34:35]
	v_pk_add_f32 v[28:29], v[28:29], v[32:33]
	v_pk_add_f32 v[32:33], v[26:27], v[38:39]
	v_pk_add_f32 v[26:27], v[24:25], v[36:37]
	v_mul_f32_e32 v24, v29, v29
	v_mul_f32_e32 v25, v31, v31
	v_fmac_f32_e32 v24, v28, v28
	v_fmac_f32_e32 v25, v30, v30
	v_add_f32_e32 v24, v24, v25
	v_mul_f32_e32 v25, v27, v27
	v_mul_f32_e32 v34, v33, v33
	v_fmac_f32_e32 v25, v26, v26
	v_fmac_f32_e32 v34, v32, v32
	v_add_f32_e32 v25, v25, v34
	v_add_f32_e32 v34, v24, v25
	v_cvt_pk_bf16_f32 v24, v28, v29
	v_lshl_add_u64 v[28:29], s[18:19], 0, v[94:95]
	v_cvt_pk_bf16_f32 v25, v30, v31
	v_cvt_pk_bf16_f32 v26, v26, v27
	v_cvt_pk_bf16_f32 v27, v32, v33
	v_lshl_add_u64 v[28:29], v[168:169], 1, v[28:29]
	global_store_dwordx4 v[28:29], v[24:27], off
	s_waitcnt vmcnt(7)
	v_lshlrev_b32_e32 v30, 16, v74
	v_and_b32_e32 v31, 0xffff0000, v74
	v_lshlrev_b32_e32 v24, 16, v72
	v_and_b32_e32 v25, 0xffff0000, v72
	v_lshlrev_b32_e32 v26, 16, v73
	v_and_b32_e32 v27, 0xffff0000, v73
	v_lshlrev_b32_e32 v32, 16, v75
	v_and_b32_e32 v33, 0xffff0000, v75
	v_pk_add_f32 v[22:23], v[22:23], v[26:27]
	v_pk_add_f32 v[20:21], v[20:21], v[24:25]
	v_pk_add_f32 v[24:25], v[18:19], v[32:33]
	v_pk_add_f32 v[18:19], v[16:17], v[30:31]
	v_mul_f32_e32 v16, v21, v21
	v_mul_f32_e32 v17, v23, v23
	v_fmac_f32_e32 v16, v20, v20
	v_fmac_f32_e32 v17, v22, v22
	v_add_f32_e32 v16, v16, v17
	v_mul_f32_e32 v17, v19, v19
	v_mul_f32_e32 v26, v25, v25
	v_fmac_f32_e32 v17, v18, v18
	v_fmac_f32_e32 v26, v24, v24
	v_add_f32_e32 v17, v17, v26
	v_add_f32_e32 v16, v16, v17
	v_add_f32_e32 v26, v34, v16
	v_cvt_pk_bf16_f32 v16, v20, v21
	v_cvt_pk_bf16_f32 v17, v22, v23
	v_cvt_pk_bf16_f32 v18, v18, v19
	v_cvt_pk_bf16_f32 v19, v24, v25
	global_store_dwordx4 v[28:29], v[16:19], off offset:256
	s_nop 1
	v_mov_b32_e32 v16, v201
	v_mov_b32_e32 v17, v201
	v_lshlrev_b32_e32 v16, 2, v16
	v_xor_b32_e32 v16, 64, v16
	v_mov_b32_e32 v16, v26
	s_nop 1
	v_permlane16_swap_b32_e32 v16, v26
	s_waitcnt lgkmcnt(0)
	v_add_f32_e32 v16, v26, v16
	v_lshlrev_b32_e32 v17, 2, v17
	v_xor_b32_e32 v17, 0x80, v17
	v_mov_b32_e32 v17, v16
	s_nop 1
	v_permlane32_swap_b32_e32 v17, v16
	s_and_saveexec_b64 s[44:45], s[10:11]
	s_cbranch_execz .LBB0_453
	s_waitcnt lgkmcnt(0)
	v_add_f32_e32 v18, v16, v17
	v_lshlrev_b64 v[16:17], 6, v[92:93]
	v_lshl_add_u64 v[16:17], s[22:23], 0, v[16:17]
	v_lshl_add_u64 v[16:17], s[42:43], 2, v[16:17]
	s_lshl_b32 s14, s52, 2
	v_lshl_add_u64 v[16:17], v[16:17], 0, s[14:15]
	global_store_dword v[16:17], v18, off
.LBB0_453:
	s_or_b64 exec, exec, s[44:45]
	s_waitcnt vmcnt(7)
	v_lshlrev_b32_e32 v16, 16, v68
	s_waitcnt lgkmcnt(0)
	v_and_b32_e32 v17, 0xffff0000, v68
	v_lshlrev_b32_e32 v18, 16, v69
	v_and_b32_e32 v19, 0xffff0000, v69
	v_lshlrev_b32_e32 v20, 16, v70
	v_and_b32_e32 v21, 0xffff0000, v70
	v_lshlrev_b32_e32 v22, 16, v71
	v_and_b32_e32 v23, 0xffff0000, v71
	v_pk_add_f32 v[14:15], v[14:15], v[18:19]
	v_pk_add_f32 v[12:13], v[12:13], v[16:17]
	v_pk_add_f32 v[16:17], v[10:11], v[22:23]
	v_pk_add_f32 v[10:11], v[8:9], v[20:21]
	v_mul_f32_e32 v8, v13, v13
	v_mul_f32_e32 v9, v15, v15
	v_fmac_f32_e32 v8, v12, v12
	v_fmac_f32_e32 v9, v14, v14
	v_add_f32_e32 v8, v8, v9
	v_mul_f32_e32 v9, v11, v11
	v_mul_f32_e32 v18, v17, v17
	v_fmac_f32_e32 v9, v10, v10
	v_fmac_f32_e32 v18, v16, v16
	v_add_f32_e32 v9, v9, v18
	v_add_f32_e32 v18, v8, v9
	v_cvt_pk_bf16_f32 v8, v12, v13
	v_lshl_add_u64 v[12:13], s[18:19], 0, v[90:91]
	v_cvt_pk_bf16_f32 v9, v14, v15
	v_cvt_pk_bf16_f32 v10, v10, v11
	v_cvt_pk_bf16_f32 v11, v16, v17
	v_lshl_add_u64 v[12:13], v[168:169], 1, v[12:13]
	global_store_dwordx4 v[12:13], v[8:11], off
	s_waitcnt vmcnt(7)
	v_lshlrev_b32_e32 v14, 16, v66
	v_and_b32_e32 v15, 0xffff0000, v66
	v_lshlrev_b32_e32 v8, 16, v64
	v_and_b32_e32 v9, 0xffff0000, v64
	v_lshlrev_b32_e32 v10, 16, v65
	v_and_b32_e32 v11, 0xffff0000, v65
	v_lshlrev_b32_e32 v16, 16, v67
	v_and_b32_e32 v17, 0xffff0000, v67
	v_pk_add_f32 v[6:7], v[6:7], v[10:11]
	v_pk_add_f32 v[4:5], v[4:5], v[8:9]
	v_pk_add_f32 v[8:9], v[2:3], v[16:17]
	v_pk_add_f32 v[2:3], v[0:1], v[14:15]
	v_mul_f32_e32 v0, v5, v5
	v_mul_f32_e32 v1, v7, v7
	v_fmac_f32_e32 v0, v4, v4
	v_fmac_f32_e32 v1, v6, v6
	v_add_f32_e32 v0, v0, v1
	v_mul_f32_e32 v1, v3, v3
	v_mul_f32_e32 v10, v9, v9
	v_fmac_f32_e32 v1, v2, v2
	v_fmac_f32_e32 v10, v8, v8
	v_add_f32_e32 v1, v1, v10
	v_add_f32_e32 v0, v0, v1
	v_add_f32_e32 v10, v18, v0
	v_cvt_pk_bf16_f32 v0, v4, v5
	v_cvt_pk_bf16_f32 v1, v6, v7
	v_cvt_pk_bf16_f32 v2, v2, v3
	v_cvt_pk_bf16_f32 v3, v8, v9
	global_store_dwordx4 v[12:13], v[0:3], off offset:256
	s_nop 1
	v_mov_b32_e32 v0, v201
	v_mov_b32_e32 v1, v201
	v_lshlrev_b32_e32 v0, 2, v0
	v_xor_b32_e32 v0, 64, v0
	v_mov_b32_e32 v0, v10
	s_nop 1
	v_permlane16_swap_b32_e32 v0, v10
	s_waitcnt lgkmcnt(0)
	v_add_f32_e32 v0, v10, v0
	v_lshlrev_b32_e32 v1, 2, v1
	v_xor_b32_e32 v1, 0x80, v1
	v_mov_b32_e32 v1, v0
	s_nop 1
	v_permlane32_swap_b32_e32 v1, v0
	s_and_saveexec_b64 s[44:45], s[10:11]
	s_cbranch_execz .LBB0_455
	s_waitcnt lgkmcnt(0)
	v_add_f32_e32 v2, v0, v1
	v_lshlrev_b64 v[0:1], 6, v[88:89]
	v_lshl_add_u64 v[0:1], s[22:23], 0, v[0:1]
	v_lshl_add_u64 v[0:1], s[42:43], 2, v[0:1]
	s_lshl_b32 s14, s52, 2
	v_lshl_add_u64 v[0:1], v[0:1], 0, s[14:15]
	global_store_dword v[0:1], v2, off

; __device__ __forceinline__ float row_part(const float* ss, int row, int fq) { const f32x4 a = ((const f32x4*)(ss + (size_t)row * 16))[fq]; return (a[0] + a[1]) + (a[2] + a[3]); }
; __device__ __forceinline__ float row_finish(float t) { t += shx(t, 16); t += shx(t, 32); return __builtin_amdgcn_rsqf(t * (1.0f / 1024.0f) + RMS_EPS); }
;     __device__ __forceinline__ void operator()(const f32x4 (&acc)[2][2][4][2], const Unit& u, int wr, int wc, int fr, int fq) const {
;     ...
;         float rs[2][4];
; #pragma unroll
;         for (int ai = 0; ai < 2; ++ai)
; #pragma unroll
;             for (int m = 0; m < 4; ++m) rs[ai][m] = row_part(ss, u.pm * BM + ai * HALF + wr * 64 + m * 16 + fr, fq);
; #pragma unroll
;         for (int ai = 0; ai < 2; ++ai)
; #pragma unroll
;             for (int m = 0; m < 4; ++m) rs[ai][m] = row_finish(rs[ai][m]);
.LBB0_523:
	v_lshl_add_u32 v170, s36, 8, v153
	v_ashrrev_i32_e32 v171, 31, v170
	v_or_b32_e32 v166, 16, v170
	v_lshlrev_b64 v[146:147], 6, v[170:171]
	v_ashrrev_i32_e32 v167, 31, v166
	v_lshl_add_u64 v[146:147], v[136:137], 0, v[146:147]
	v_lshlrev_b64 v[148:149], 6, v[166:167]
	v_lshl_add_u64 v[148:149], v[136:137], 0, v[148:149]
	ds_read_b128 v[176:179], v239
	ds_read_b128 v[180:183], v239 offset:1024
	v_or_b32_e32 v162, 32, v170
	v_ashrrev_i32_e32 v163, 31, v162
	v_or_b32_e32 v158, 48, v170
	v_lshlrev_b64 v[146:147], 6, v[162:163]
	v_ashrrev_i32_e32 v159, 31, v158
	v_lshl_add_u64 v[146:147], v[136:137], 0, v[146:147]
	v_lshlrev_b64 v[148:149], 6, v[158:159]
	v_lshl_add_u64 v[148:149], v[136:137], 0, v[148:149]
	ds_read_b128 v[184:187], v239 offset:2048
	ds_read_b128 v[188:191], v239 offset:3072
	v_add_u32_e32 v154, 0x80, v170
	v_ashrrev_i32_e32 v155, 31, v154
	v_add_u32_e32 v150, 0x90, v170
	v_lshlrev_b64 v[146:147], 6, v[154:155]
	v_ashrrev_i32_e32 v151, 31, v150
	v_lshl_add_u64 v[146:147], v[136:137], 0, v[146:147]
	v_lshlrev_b64 v[148:149], 6, v[150:151]
	v_lshl_add_u64 v[148:149], v[136:137], 0, v[148:149]
	ds_read_b128 v[192:195], v239 offset:8192
	ds_read_b128 v[196:199], v239 offset:9216
	v_add_u32_e32 v148, 0xa0, v170
	v_ashrrev_i32_e32 v149, 31, v148
	v_lshlrev_b64 v[146:147], 6, v[148:149]
	v_lshl_add_u64 v[146:147], v[136:137], 0, v[146:147]
	ds_read_b128 v[202:205], v239 offset:10240
	v_add_u32_e32 v146, 0xb0, v170
	v_ashrrev_i32_e32 v147, 31, v146
	v_lshlrev_b64 v[206:207], 6, v[146:147]
	v_lshl_add_u64 v[206:207], v[136:137], 0, v[206:207]
	ds_read_b128 v[206:209], v239 offset:11264
	v_mov_b32_e32 v147, v201
	v_mov_b32_e32 v149, v201
	v_lshlrev_b32_e32 v147, 2, v147
	v_mov_b32_e32 v151, v201
	v_xor_b32_e32 v147, 64, v147
	s_andn2_b64 vcc, exec, s[10:11]
	v_lshlrev_b32_e32 v151, 2, v151
	v_xor_b32_e32 v151, 64, v151
	v_lshlrev_b32_e32 v149, 2, v149
	v_xor_b32_e32 v149, 0x80, v149
	s_mov_b64 s[10:11], -1
	s_waitcnt lgkmcnt(0)
	v_mov_b32_e32 v210, v177
	v_mov_b32_e32 v211, v178
	v_mov_b32_e32 v177, v179
	v_pk_add_f32 v[176:177], v[210:211], v[176:177]
	v_mov_b32_e32 v178, v181
	v_add_f32_e32 v152, v176, v177
	v_mov_b32_e32 v179, v182
	v_mov_b32_e32 v181, v183
	v_mov_b32_e32 v147, v152
	s_nop 1
	v_permlane16_swap_b32_e32 v147, v152
	v_pk_add_f32 v[176:177], v[178:179], v[180:181]
	v_mov_b32_e32 v182, v185
	v_add_f32_e32 v155, v176, v177
	v_mov_b32_e32 v151, v155
	s_nop 1
	v_permlane16_swap_b32_e32 v151, v155
	s_waitcnt lgkmcnt(0)
	v_add_f32_e32 v147, v152, v147
	v_mov_b32_e32 v152, v201
	v_mov_b32_e32 v149, v147
	s_nop 1
	v_permlane32_swap_b32_e32 v149, v147
	s_waitcnt lgkmcnt(0)
	v_add_f32_e32 v151, v155, v151
	v_lshlrev_b32_e32 v152, 2, v152
	v_xor_b32_e32 v152, 0x80, v152
	v_mov_b32_e32 v152, v151
	s_nop 1
	v_permlane32_swap_b32_e32 v152, v151
	s_waitcnt lgkmcnt(0)
	v_add_f32_e32 v147, v147, v149
	v_mov_b32_e32 v149, v201
	v_mov_b32_e32 v183, v186
	v_mov_b32_e32 v185, v187
	v_pk_add_f32 v[178:179], v[182:183], v[184:185]
	v_fmamk_f32 v147, v147, 0x3a800000, v175
	v_lshlrev_b32_e32 v149, 2, v149
	v_add_f32_e32 v156, v178, v179
	v_rsq_f32_e32 v176, v147
	s_waitcnt lgkmcnt(0)
	v_add_f32_e32 v147, v151, v152
	v_xor_b32_e32 v149, 64, v149
	v_mov_b32_e32 v151, v201
	v_mov_b32_e32 v152, v201
	v_mov_b32_e32 v186, v189
	v_mov_b32_e32 v187, v190
	v_mov_b32_e32 v189, v191
	v_mov_b32_e32 v149, v156
	s_nop 1
	v_permlane16_swap_b32_e32 v149, v156
	v_pk_add_f32 v[180:181], v[186:187], v[188:189]
	v_lshlrev_b32_e32 v152, 2, v152
	v_add_f32_e32 v159, v180, v181
	v_xor_b32_e32 v152, 64, v152
	v_mov_b32_e32 v152, v159
	s_nop 1
	v_permlane16_swap_b32_e32 v152, v159
	s_waitcnt lgkmcnt(0)
	v_add_f32_e32 v149, v156, v149
	v_lshlrev_b32_e32 v151, 2, v151
	v_mov_b32_e32 v156, v201
	v_xor_b32_e32 v151, 0x80, v151
	v_mov_b32_e32 v151, v149
	s_nop 1
	v_permlane32_swap_b32_e32 v151, v149
	v_lshlrev_b32_e32 v156, 2, v156
	s_waitcnt lgkmcnt(0)
	v_add_f32_e32 v152, v159, v152
	v_xor_b32_e32 v156, 0x80, v156
	v_mov_b32_e32 v156, v152
	s_nop 1
	v_permlane32_swap_b32_e32 v156, v152
	v_fmamk_f32 v147, v147, 0x3a800000, v175
	v_rsq_f32_e32 v174, v147
	s_waitcnt lgkmcnt(0)
	v_add_f32_e32 v147, v149, v151
	v_mov_b32_e32 v149, v201
	v_mov_b32_e32 v190, v193
	v_mov_b32_e32 v191, v194
	v_mov_b32_e32 v193, v195
	v_fmamk_f32 v147, v147, 0x3a800000, v175
	v_pk_add_f32 v[182:183], v[190:191], v[192:193]
	v_rsq_f32_e32 v172, v147
	s_waitcnt lgkmcnt(0)
	v_add_f32_e32 v147, v152, v156
	v_lshlrev_b32_e32 v149, 2, v149
	v_mov_b32_e32 v151, v201
	v_mov_b32_e32 v152, v201
	v_mov_b32_e32 v194, v197
	v_mov_b32_e32 v195, v198
	v_mov_b32_e32 v197, v199
	v_add_f32_e32 v160, v182, v183
	v_xor_b32_e32 v149, 64, v149
	v_pk_add_f32 v[184:185], v[194:195], v[196:197]
	v_mov_b32_e32 v149, v160
	s_nop 1
	v_permlane16_swap_b32_e32 v149, v160
	v_lshlrev_b32_e32 v152, 2, v152
	v_add_f32_e32 v163, v184, v185
	v_xor_b32_e32 v152, 64, v152
	v_mov_b32_e32 v152, v163
	s_nop 1
	v_permlane16_swap_b32_e32 v152, v163
	v_lshlrev_b32_e32 v151, 2, v151
	v_mov_b32_e32 v156, v201
	s_waitcnt lgkmcnt(0)
	v_add_f32_e32 v149, v160, v149
	v_xor_b32_e32 v151, 0x80, v151
	v_mov_b32_e32 v151, v149
	s_nop 1
	v_permlane32_swap_b32_e32 v151, v149
	v_lshlrev_b32_e32 v156, 2, v156
	s_waitcnt lgkmcnt(0)
	v_add_f32_e32 v152, v163, v152
	v_xor_b32_e32 v156, 0x80, v156
	v_mov_b32_e32 v156, v152
	s_nop 1
	v_permlane32_swap_b32_e32 v156, v152
	v_fmamk_f32 v147, v147, 0x3a800000, v175
	v_rsq_f32_e32 v168, v147
	s_waitcnt lgkmcnt(0)
	v_add_f32_e32 v147, v149, v151
	v_fmamk_f32 v147, v147, 0x3a800000, v175
	v_rsq_f32_e32 v164, v147
	s_waitcnt lgkmcnt(0)
; __device__ __forceinline__ float row_finish(float t) { t += shx(t, 16); t += shx(t, 32); return __builtin_amdgcn_rsqf(t * (1.0f / 1024.0f) + RMS_EPS); }
; __device__ __forceinline__ f32x4 silu4(f32x4 v) { return (f32x4){silu_f(v[0]), silu_f(v[1]), silu_f(v[2]), silu_f(v[3])}; }
; __device__ __forceinline__ u32x4 pack8(f32x4 a, f32x4 b) { u32x4 w; w.x = cvt_pk_bf16(a[0], a[1]); w.y = cvt_pk_bf16(a[2], a[3]); w.z = cvt_pk_bf16(b[0], b[1]); w.w = cvt_pk_bf16(b[2], b[3]); return w; }
;     __device__ __forceinline__ void operator()(const f32x4 (&acc)[2][2][4][2], const Unit& u, int wr, int wc, int fr, int fq) const {
;     ...
;             for (int m = 0; m < 4; ++m) rs[ai][m] = row_finish(rs[ai][m]);
; #pragma unroll
;         for (int ai = 0; ai < 2; ++ai)
; #pragma unroll
;             for (int m = 0; m < 4; ++m) {
;                 const int row = u.pm * BM + ai * HALF + wr * 64 + m * 16 + fr;
;                 const float rstd = rs[ai][m];
;                 const f32x4 a0 = silu4(acc[ai][0][m][0] * rstd) * (acc[ai][1][m][0] * rstd);
;                 const f32x4 a1 = silu4(acc[ai][0][m][1] * rstd) * (acc[ai][1][m][1] * rstd);
;                 *(u32x4*)(ACT + (size_t)row * 2816 + col0) = pack8(a0, a1);
	v_add_f32_e32 v147, v152, v156
	v_mov_b32_e32 v149, v201
	v_mov_b32_e32 v151, v201
	v_mov_b32_e32 v152, v201
	v_mov_b32_e32 v198, v203
	v_mov_b32_e32 v199, v204
	v_mov_b32_e32 v203, v205
	v_mov_b32_e32 v204, v207
	v_mov_b32_e32 v205, v208
	v_mov_b32_e32 v207, v209
	v_pk_add_f32 v[188:189], v[204:205], v[206:207]
	v_lshlrev_b32_e32 v152, 2, v152
	v_pk_add_f32 v[186:187], v[198:199], v[202:203]
	v_add_f32_e32 v155, v188, v189
	v_lshlrev_b32_e32 v149, 2, v149
	v_xor_b32_e32 v152, 64, v152
	v_add_f32_e32 v167, v186, v187
	v_xor_b32_e32 v149, 64, v149
	v_mov_b32_e32 v152, v155
	s_nop 1
	v_permlane16_swap_b32_e32 v152, v155
	v_mov_b32_e32 v149, v167
	s_nop 1
	v_permlane16_swap_b32_e32 v149, v167
	v_lshlrev_b32_e32 v151, 2, v151
	v_xor_b32_e32 v151, 0x80, v151
	v_fmamk_f32 v147, v147, 0x3a800000, v175
	s_waitcnt lgkmcnt(0)
	v_add_f32_e32 v152, v155, v152
	v_mov_b32_e32 v155, v201
	s_waitcnt lgkmcnt(0)
	v_add_f32_e32 v149, v167, v149
	v_mov_b32_e32 v151, v149
	s_nop 1
	v_permlane32_swap_b32_e32 v151, v149
	v_lshlrev_b32_e32 v155, 2, v155
	v_xor_b32_e32 v155, 0x80, v155
	v_mov_b32_e32 v155, v152
	s_nop 1
	v_permlane32_swap_b32_e32 v155, v152
	v_rsq_f32_e32 v160, v147
	s_waitcnt lgkmcnt(0)
	v_add_f32_e32 v147, v149, v151
	v_fmamk_f32 v147, v147, 0x3a800000, v175
	v_rsq_f32_e32 v156, v147
	s_waitcnt lgkmcnt(0)
	v_add_f32_e32 v147, v152, v155
	v_fmamk_f32 v147, v147, 0x3a800000, v175
	v_pk_mul_f32 v[124:125], v[124:125], v[176:177] op_sel_hi:[1,0]
	v_rsq_f32_e32 v152, v147
	v_mul_f32_e32 v147, 0xbfb8aa3b, v124
	v_exp_f32_e32 v147, v147
	v_mul_f32_e32 v149, 0xbfb8aa3b, v125
	v_exp_f32_e32 v149, v149
	v_pk_mul_f32 v[126:127], v[126:127], v[176:177] op_sel_hi:[1,0]
	v_add_f32_e32 v147, 1.0, v147
	v_rcp_f32_e32 v178, v147
	v_add_f32_e32 v147, 1.0, v149
	v_mul_f32_e32 v149, 0xbfb8aa3b, v126
	v_exp_f32_e32 v149, v149
	v_mul_f32_e32 v151, 0xbfb8aa3b, v127
	v_exp_f32_e32 v151, v151
	v_rcp_f32_e32 v179, v147
	v_add_f32_e32 v147, 1.0, v149
	v_rcp_f32_e32 v180, v147
	v_add_f32_e32 v147, 1.0, v151
	v_pk_mul_f32 v[120:121], v[120:121], v[176:177] op_sel_hi:[1,0]
	v_rcp_f32_e32 v181, v147
	v_mul_f32_e32 v147, 0xbfb8aa3b, v120
	v_exp_f32_e32 v147, v147
	v_mul_f32_e32 v149, 0xbfb8aa3b, v121
	v_exp_f32_e32 v149, v149
	v_pk_mul_f32 v[122:123], v[122:123], v[176:177] op_sel_hi:[1,0]
	v_add_f32_e32 v147, 1.0, v147
	v_pk_mul_f32 v[124:125], v[124:125], v[178:179]
	v_rcp_f32_e32 v178, v147
	v_add_f32_e32 v147, 1.0, v149
	v_mul_f32_e32 v149, 0xbfb8aa3b, v122
	v_exp_f32_e32 v149, v149
	v_mul_f32_e32 v151, 0xbfb8aa3b, v123
	v_exp_f32_e32 v151, v151
	v_rcp_f32_e32 v179, v147
	v_add_f32_e32 v147, 1.0, v149
	v_pk_mul_f32 v[126:127], v[126:127], v[180:181]
	v_rcp_f32_e32 v180, v147
	v_add_f32_e32 v147, 1.0, v151
	v_rcp_f32_e32 v181, v147
	v_pk_mul_f32 v[116:117], v[116:117], v[176:177] op_sel_hi:[1,0]
	v_pk_mul_f32 v[118:119], v[118:119], v[176:177] op_sel_hi:[1,0]
	v_pk_mul_f32 v[120:121], v[120:121], v[178:179]
	v_pk_mul_f32 v[112:113], v[112:113], v[176:177] op_sel_hi:[1,0]
	v_lshl_or_b32 v182, s57, 7, v161
	v_pk_mul_f32 v[118:119], v[118:119], v[126:127]
	v_pk_mul_f32 v[116:117], v[116:117], v[124:125]
	v_pk_mul_f32 v[122:123], v[122:123], v[180:181]
	v_pk_mul_f32 v[114:115], v[114:115], v[176:177] op_sel_hi:[1,0]
	v_pk_mul_f32 v[112:113], v[112:113], v[120:121]
	v_ashrrev_i32_e32 v183, 31, v182
	v_pk_mul_f32 v[114:115], v[114:115], v[122:123]
	v_cvt_pk_bf16_f32 v116, v116, v117
	v_cvt_pk_bf16_f32 v117, v118, v119
	v_cvt_pk_bf16_f32 v118, v112, v113
	v_mov_b64_e32 v[112:113], s[14:15]
	v_cvt_pk_bf16_f32 v119, v114, v115
	v_mad_i64_i32 v[120:121], s[38:39], v170, s56, v[112:113]
	v_lshlrev_b64 v[114:115], 1, v[182:183]
	v_pk_mul_f32 v[108:109], v[108:109], v[174:175] op_sel_hi:[1,0]
	v_pk_mul_f32 v[110:111], v[110:111], v[174:175] op_sel_hi:[1,0]
	v_mul_f32_e32 v122, 0xbfb8aa3b, v108
	v_mul_f32_e32 v123, 0xbfb8aa3b, v109
	v_lshl_add_u64 v[120:121], v[120:121], 0, v[114:115]
	v_pk_mul_f32 v[104:105], v[104:105], v[174:175] op_sel_hi:[1,0]
	v_pk_mul_f32 v[106:107], v[106:107], v[174:175] op_sel_hi:[1,0]
	v_exp_f32_e32 v122, v122
	v_exp_f32_e32 v123, v123
	v_mul_f32_e32 v124, 0xbfb8aa3b, v110
	v_mul_f32_e32 v125, 0xbfb8aa3b, v111
	global_store_dwordx4 v[120:121], v[116:119], off
	v_exp_f32_e32 v124, v124
	v_exp_f32_e32 v125, v125
	v_mul_f32_e32 v116, 0xbfb8aa3b, v104
	v_mul_f32_e32 v117, 0xbfb8aa3b, v105
	v_mul_f32_e32 v118, 0xbfb8aa3b, v106
	v_mul_f32_e32 v119, 0xbfb8aa3b, v107
	v_exp_f32_e32 v116, v116
	v_exp_f32_e32 v117, v117
	v_exp_f32_e32 v118, v118
	v_exp_f32_e32 v119, v119
	v_add_f32_e32 v122, 1.0, v122
	v_add_f32_e32 v123, 1.0, v123
	v_rcp_f32_e32 v122, v122
	v_rcp_f32_e32 v123, v123
	v_add_f32_e32 v124, 1.0, v124
	v_add_f32_e32 v125, 1.0, v125
	v_add_f32_e32 v116, 1.0, v116
	v_add_f32_e32 v117, 1.0, v117
	v_add_f32_e32 v118, 1.0, v118
	v_add_f32_e32 v119, 1.0, v119
	v_rcp_f32_e32 v124, v124
	v_rcp_f32_e32 v125, v125
	v_rcp_f32_e32 v116, v116
	v_rcp_f32_e32 v117, v117
	v_rcp_f32_e32 v118, v118
	v_rcp_f32_e32 v119, v119
	v_pk_mul_f32 v[108:109], v[108:109], v[122:123]
	v_pk_mul_f32 v[100:101], v[100:101], v[174:175] op_sel_hi:[1,0]
	v_pk_mul_f32 v[110:111], v[110:111], v[124:125]
	v_pk_mul_f32 v[102:103], v[102:103], v[174:175] op_sel_hi:[1,0]
	v_pk_mul_f32 v[100:101], v[100:101], v[108:109]
	v_pk_mul_f32 v[104:105], v[104:105], v[116:117]
	v_pk_mul_f32 v[106:107], v[106:107], v[118:119]
	v_pk_mul_f32 v[96:97], v[96:97], v[174:175] op_sel_hi:[1,0]
	v_pk_mul_f32 v[98:99], v[98:99], v[174:175] op_sel_hi:[1,0]
	v_pk_mul_f32 v[102:103], v[102:103], v[110:111]
	v_pk_mul_f32 v[106:107], v[98:99], v[106:107]
	v_pk_mul_f32 v[98:99], v[96:97], v[104:105]
	v_cvt_pk_bf16_f32 v96, v100, v101
; __device__ __forceinline__ f32x4 silu4(f32x4 v) { return (f32x4){silu_f(v[0]), silu_f(v[1]), silu_f(v[2]), silu_f(v[3])}; }
; __device__ __forceinline__ u32x4 pack8(f32x4 a, f32x4 b) { u32x4 w; w.x = cvt_pk_bf16(a[0], a[1]); w.y = cvt_pk_bf16(a[2], a[3]); w.z = cvt_pk_bf16(b[0], b[1]); w.w = cvt_pk_bf16(b[2], b[3]); return w; }
;     __device__ __forceinline__ void operator()(const f32x4 (&acc)[2][2][4][2], const Unit& u, int wr, int wc, int fr, int fq) const {
;     ...
;         for (int ai = 0; ai < 2; ++ai)
; #pragma unroll
;             for (int m = 0; m < 4; ++m) {
;                 const int row = u.pm * BM + ai * HALF + wr * 64 + m * 16 + fr;
;                 const float rstd = rs[ai][m];
;                 const f32x4 a0 = silu4(acc[ai][0][m][0] * rstd) * (acc[ai][1][m][0] * rstd);
;                 const f32x4 a1 = silu4(acc[ai][0][m][1] * rstd) * (acc[ai][1][m][1] * rstd);
;                 *(u32x4*)(ACT + (size_t)row * 2816 + col0) = pack8(a0, a1);
;             }
	v_mad_i64_i32 v[100:101], s[38:39], v166, s56, v[112:113]
	v_pk_mul_f32 v[92:93], v[92:93], v[172:173] op_sel_hi:[1,0]
	v_cvt_pk_bf16_f32 v97, v102, v103
	v_cvt_pk_bf16_f32 v98, v98, v99
	v_cvt_pk_bf16_f32 v99, v106, v107
	v_pk_mul_f32 v[94:95], v[94:95], v[172:173] op_sel_hi:[1,0]
	v_mul_f32_e32 v102, 0xbfb8aa3b, v92
	v_mul_f32_e32 v103, 0xbfb8aa3b, v93
	v_lshl_add_u64 v[100:101], v[100:101], 0, v[114:115]
	v_pk_mul_f32 v[88:89], v[88:89], v[172:173] op_sel_hi:[1,0]
	v_pk_mul_f32 v[90:91], v[90:91], v[172:173] op_sel_hi:[1,0]
	v_exp_f32_e32 v102, v102
	v_exp_f32_e32 v103, v103
	v_mul_f32_e32 v104, 0xbfb8aa3b, v94
	v_mul_f32_e32 v105, 0xbfb8aa3b, v95
	global_store_dwordx4 v[100:101], v[96:99], off
	v_exp_f32_e32 v104, v104
	v_exp_f32_e32 v105, v105
	v_mul_f32_e32 v96, 0xbfb8aa3b, v88
	v_mul_f32_e32 v97, 0xbfb8aa3b, v89
	v_mul_f32_e32 v98, 0xbfb8aa3b, v90
	v_mul_f32_e32 v99, 0xbfb8aa3b, v91
	v_exp_f32_e32 v96, v96
	v_exp_f32_e32 v97, v97
	v_exp_f32_e32 v98, v98
	v_exp_f32_e32 v99, v99
	v_add_f32_e32 v102, 1.0, v102
	v_add_f32_e32 v103, 1.0, v103
	v_rcp_f32_e32 v102, v102
	v_rcp_f32_e32 v103, v103
	v_add_f32_e32 v104, 1.0, v104
	v_add_f32_e32 v105, 1.0, v105
	v_add_f32_e32 v96, 1.0, v96
	v_add_f32_e32 v97, 1.0, v97
	v_add_f32_e32 v98, 1.0, v98
	v_add_f32_e32 v99, 1.0, v99
	v_rcp_f32_e32 v104, v104
	v_rcp_f32_e32 v105, v105
	v_rcp_f32_e32 v96, v96
	v_rcp_f32_e32 v97, v97
	v_rcp_f32_e32 v98, v98
	v_rcp_f32_e32 v99, v99
	v_pk_mul_f32 v[92:93], v[92:93], v[102:103]
	v_pk_mul_f32 v[84:85], v[84:85], v[172:173] op_sel_hi:[1,0]
	v_pk_mul_f32 v[94:95], v[94:95], v[104:105]
	v_pk_mul_f32 v[86:87], v[86:87], v[172:173] op_sel_hi:[1,0]
	v_pk_mul_f32 v[84:85], v[84:85], v[92:93]
	v_pk_mul_f32 v[88:89], v[88:89], v[96:97]
	v_pk_mul_f32 v[90:91], v[90:91], v[98:99]
	v_pk_mul_f32 v[80:81], v[80:81], v[172:173] op_sel_hi:[1,0]
	v_pk_mul_f32 v[82:83], v[82:83], v[172:173] op_sel_hi:[1,0]
	v_pk_mul_f32 v[86:87], v[86:87], v[94:95]
	v_pk_mul_f32 v[90:91], v[82:83], v[90:91]
	v_pk_mul_f32 v[82:83], v[80:81], v[88:89]
	v_cvt_pk_bf16_f32 v80, v84, v85
	v_mad_i64_i32 v[84:85], s[38:39], v162, s56, v[112:113]
	v_pk_mul_f32 v[76:77], v[76:77], v[168:169] op_sel_hi:[1,0]
	v_cvt_pk_bf16_f32 v81, v86, v87
	v_cvt_pk_bf16_f32 v82, v82, v83
	v_cvt_pk_bf16_f32 v83, v90, v91
	v_pk_mul_f32 v[78:79], v[78:79], v[168:169] op_sel_hi:[1,0]
	v_mul_f32_e32 v86, 0xbfb8aa3b, v76
	v_mul_f32_e32 v87, 0xbfb8aa3b, v77
	v_lshl_add_u64 v[84:85], v[84:85], 0, v[114:115]
	v_pk_mul_f32 v[72:73], v[72:73], v[168:169] op_sel_hi:[1,0]
	v_pk_mul_f32 v[74:75], v[74:75], v[168:169] op_sel_hi:[1,0]
	v_exp_f32_e32 v86, v86
	v_exp_f32_e32 v87, v87
	v_mul_f32_e32 v88, 0xbfb8aa3b, v78
	v_mul_f32_e32 v89, 0xbfb8aa3b, v79
	global_store_dwordx4 v[84:85], v[80:83], off
	v_exp_f32_e32 v88, v88
	v_exp_f32_e32 v89, v89
	v_mul_f32_e32 v80, 0xbfb8aa3b, v72
	v_mul_f32_e32 v81, 0xbfb8aa3b, v73
	v_mul_f32_e32 v82, 0xbfb8aa3b, v74
	v_mul_f32_e32 v83, 0xbfb8aa3b, v75
	v_exp_f32_e32 v80, v80
	v_exp_f32_e32 v81, v81
	v_exp_f32_e32 v82, v82
	v_exp_f32_e32 v83, v83
	v_add_f32_e32 v86, 1.0, v86
	v_add_f32_e32 v87, 1.0, v87
	v_rcp_f32_e32 v86, v86
	v_rcp_f32_e32 v87, v87
	v_add_f32_e32 v88, 1.0, v88
	v_add_f32_e32 v89, 1.0, v89
	v_add_f32_e32 v80, 1.0, v80
	v_add_f32_e32 v81, 1.0, v81
	v_add_f32_e32 v82, 1.0, v82
	v_add_f32_e32 v83, 1.0, v83
	v_rcp_f32_e32 v88, v88
	v_rcp_f32_e32 v89, v89
	v_rcp_f32_e32 v80, v80
	v_rcp_f32_e32 v81, v81
	v_rcp_f32_e32 v82, v82
	v_rcp_f32_e32 v83, v83
	v_pk_mul_f32 v[76:77], v[76:77], v[86:87]
	v_pk_mul_f32 v[68:69], v[68:69], v[168:169] op_sel_hi:[1,0]
	v_pk_mul_f32 v[78:79], v[78:79], v[88:89]
	v_pk_mul_f32 v[70:71], v[70:71], v[168:169] op_sel_hi:[1,0]
	v_pk_mul_f32 v[68:69], v[68:69], v[76:77]
	v_pk_mul_f32 v[72:73], v[72:73], v[80:81]
	v_pk_mul_f32 v[74:75], v[74:75], v[82:83]
	v_pk_mul_f32 v[64:65], v[64:65], v[168:169] op_sel_hi:[1,0]
	v_pk_mul_f32 v[66:67], v[66:67], v[168:169] op_sel_hi:[1,0]
	v_pk_mul_f32 v[70:71], v[70:71], v[78:79]
	v_pk_mul_f32 v[74:75], v[66:67], v[74:75]
	v_pk_mul_f32 v[66:67], v[64:65], v[72:73]
	v_cvt_pk_bf16_f32 v64, v68, v69
	v_mad_i64_i32 v[68:69], s[38:39], v158, s56, v[112:113]
	v_pk_mul_f32 v[60:61], v[60:61], v[164:165] op_sel_hi:[1,0]
	v_cvt_pk_bf16_f32 v65, v70, v71
	v_cvt_pk_bf16_f32 v66, v66, v67
	v_cvt_pk_bf16_f32 v67, v74, v75
	v_pk_mul_f32 v[62:63], v[62:63], v[164:165] op_sel_hi:[1,0]
	v_mul_f32_e32 v70, 0xbfb8aa3b, v60
	v_mul_f32_e32 v71, 0xbfb8aa3b, v61
	v_lshl_add_u64 v[68:69], v[68:69], 0, v[114:115]
	v_pk_mul_f32 v[56:57], v[56:57], v[164:165] op_sel_hi:[1,0]
	v_pk_mul_f32 v[58:59], v[58:59], v[164:165] op_sel_hi:[1,0]
	v_exp_f32_e32 v70, v70
	v_exp_f32_e32 v71, v71
	v_mul_f32_e32 v72, 0xbfb8aa3b, v62
	v_mul_f32_e32 v73, 0xbfb8aa3b, v63
	global_store_dwordx4 v[68:69], v[64:67], off
	v_exp_f32_e32 v72, v72
	v_exp_f32_e32 v73, v73
	v_mul_f32_e32 v64, 0xbfb8aa3b, v56
	v_mul_f32_e32 v65, 0xbfb8aa3b, v57
	v_mul_f32_e32 v66, 0xbfb8aa3b, v58
	v_mul_f32_e32 v67, 0xbfb8aa3b, v59
	v_exp_f32_e32 v64, v64
	v_exp_f32_e32 v65, v65
	v_exp_f32_e32 v66, v66
	v_exp_f32_e32 v67, v67
	v_add_f32_e32 v70, 1.0, v70
	v_add_f32_e32 v71, 1.0, v71
	v_rcp_f32_e32 v70, v70
	v_rcp_f32_e32 v71, v71
	v_add_f32_e32 v72, 1.0, v72
	v_add_f32_e32 v73, 1.0, v73
	v_add_f32_e32 v64, 1.0, v64
	v_add_f32_e32 v65, 1.0, v65
	v_add_f32_e32 v66, 1.0, v66
	v_add_f32_e32 v67, 1.0, v67
	v_rcp_f32_e32 v72, v72
	v_rcp_f32_e32 v73, v73
	v_rcp_f32_e32 v64, v64
	v_rcp_f32_e32 v65, v65
	v_rcp_f32_e32 v66, v66
	v_rcp_f32_e32 v67, v67
	v_pk_mul_f32 v[60:61], v[60:61], v[70:71]
	v_pk_mul_f32 v[52:53], v[52:53], v[164:165] op_sel_hi:[1,0]
	v_pk_mul_f32 v[62:63], v[62:63], v[72:73]
; __device__ __forceinline__ f32x4 silu4(f32x4 v) { return (f32x4){silu_f(v[0]), silu_f(v[1]), silu_f(v[2]), silu_f(v[3])}; }
; __device__ __forceinline__ u32x4 pack8(f32x4 a, f32x4 b) { u32x4 w; w.x = cvt_pk_bf16(a[0], a[1]); w.y = cvt_pk_bf16(a[2], a[3]); w.z = cvt_pk_bf16(b[0], b[1]); w.w = cvt_pk_bf16(b[2], b[3]); return w; }
; #define PG8_BAR __builtin_amdgcn_s_barrier()
;     __device__ __forceinline__ void operator()(const f32x4 (&acc)[2][2][4][2], const Unit& u, int wr, int wc, int fr, int fq) const {
;     ...
; #pragma unroll
;             for (int m = 0; m < 4; ++m) {
;                 const int row = u.pm * BM + ai * HALF + wr * 64 + m * 16 + fr;
;                 const float rstd = rs[ai][m];
;                 const f32x4 a0 = silu4(acc[ai][0][m][0] * rstd) * (acc[ai][1][m][0] * rstd);
;                 const f32x4 a1 = silu4(acc[ai][0][m][1] * rstd) * (acc[ai][1][m][1] * rstd);
;                 *(u32x4*)(ACT + (size_t)row * 2816 + col0) = pack8(a0, a1);
;             }
; template <class Epi, class Sched, bool ALIGN_EPI = false, bool SP2 = false>
; __device__ __forceinline__ void gemm_phase(PG8_LAS unsigned char* lds, const Gemm g, const Sched& S, const Epi& E, int tid_in) {
;     ...
;         if (!has_next) break;
; #pragma unroll
;         for (int a = 0; a < 2; ++a)
; #pragma unroll
;             for (int b = 0; b < 2; ++b)
; #pragma unroll
;                 for (int m = 0; m < 4; ++m)
; #pragma unroll
;                     for (int n = 0; n < 2; ++n) acc[a][b][m][n] = (f32x4){0.f, 0.f, 0.f, 0.f};
;         cur = nxt; cA = nA; cB = nB; ++ui;
;         if constexpr (ALIGN_EPI) { if (wr == 1) PG8_BAR; }
	v_pk_mul_f32 v[54:55], v[54:55], v[164:165] op_sel_hi:[1,0]
	v_pk_mul_f32 v[52:53], v[52:53], v[60:61]
	v_pk_mul_f32 v[56:57], v[56:57], v[64:65]
	v_pk_mul_f32 v[58:59], v[58:59], v[66:67]
	v_pk_mul_f32 v[48:49], v[48:49], v[164:165] op_sel_hi:[1,0]
	v_pk_mul_f32 v[50:51], v[50:51], v[164:165] op_sel_hi:[1,0]
	v_pk_mul_f32 v[54:55], v[54:55], v[62:63]
	v_pk_mul_f32 v[58:59], v[50:51], v[58:59]
	v_pk_mul_f32 v[50:51], v[48:49], v[56:57]
	v_cvt_pk_bf16_f32 v48, v52, v53
	v_mad_i64_i32 v[52:53], s[38:39], v154, s56, v[112:113]
	v_pk_mul_f32 v[44:45], v[44:45], v[160:161] op_sel_hi:[1,0]
	v_cvt_pk_bf16_f32 v49, v54, v55
	v_cvt_pk_bf16_f32 v50, v50, v51
	v_cvt_pk_bf16_f32 v51, v58, v59
	v_pk_mul_f32 v[46:47], v[46:47], v[160:161] op_sel_hi:[1,0]
	v_mul_f32_e32 v54, 0xbfb8aa3b, v44
	v_mul_f32_e32 v55, 0xbfb8aa3b, v45
	v_lshl_add_u64 v[52:53], v[52:53], 0, v[114:115]
	v_pk_mul_f32 v[40:41], v[40:41], v[160:161] op_sel_hi:[1,0]
	v_pk_mul_f32 v[42:43], v[42:43], v[160:161] op_sel_hi:[1,0]
	v_exp_f32_e32 v54, v54
	v_exp_f32_e32 v55, v55
	v_mul_f32_e32 v56, 0xbfb8aa3b, v46
	v_mul_f32_e32 v57, 0xbfb8aa3b, v47
	global_store_dwordx4 v[52:53], v[48:51], off
	v_exp_f32_e32 v56, v56
	v_exp_f32_e32 v57, v57
	v_mul_f32_e32 v48, 0xbfb8aa3b, v40
	v_mul_f32_e32 v49, 0xbfb8aa3b, v41
	v_mul_f32_e32 v50, 0xbfb8aa3b, v42
	v_mul_f32_e32 v51, 0xbfb8aa3b, v43
	v_exp_f32_e32 v48, v48
	v_exp_f32_e32 v49, v49
	v_exp_f32_e32 v50, v50
	v_exp_f32_e32 v51, v51
	v_add_f32_e32 v54, 1.0, v54
	v_add_f32_e32 v55, 1.0, v55
	v_rcp_f32_e32 v54, v54
	v_rcp_f32_e32 v55, v55
	v_add_f32_e32 v56, 1.0, v56
	v_add_f32_e32 v57, 1.0, v57
	v_add_f32_e32 v48, 1.0, v48
	v_add_f32_e32 v49, 1.0, v49
	v_add_f32_e32 v50, 1.0, v50
	v_add_f32_e32 v51, 1.0, v51
	v_rcp_f32_e32 v56, v56
	v_rcp_f32_e32 v57, v57
	v_rcp_f32_e32 v48, v48
	v_rcp_f32_e32 v49, v49
	v_rcp_f32_e32 v50, v50
	v_rcp_f32_e32 v51, v51
	v_pk_mul_f32 v[44:45], v[44:45], v[54:55]
	v_pk_mul_f32 v[36:37], v[36:37], v[160:161] op_sel_hi:[1,0]
	v_pk_mul_f32 v[46:47], v[46:47], v[56:57]
	v_pk_mul_f32 v[38:39], v[38:39], v[160:161] op_sel_hi:[1,0]
	v_pk_mul_f32 v[36:37], v[36:37], v[44:45]
	v_pk_mul_f32 v[40:41], v[40:41], v[48:49]
	v_pk_mul_f32 v[42:43], v[42:43], v[50:51]
	v_pk_mul_f32 v[32:33], v[32:33], v[160:161] op_sel_hi:[1,0]
	v_pk_mul_f32 v[34:35], v[34:35], v[160:161] op_sel_hi:[1,0]
	v_pk_mul_f32 v[38:39], v[38:39], v[46:47]
	v_pk_mul_f32 v[42:43], v[34:35], v[42:43]
	v_pk_mul_f32 v[34:35], v[32:33], v[40:41]
	v_cvt_pk_bf16_f32 v32, v36, v37
	v_mad_i64_i32 v[36:37], s[38:39], v150, s56, v[112:113]
	v_pk_mul_f32 v[28:29], v[28:29], v[156:157] op_sel_hi:[1,0]
	v_cvt_pk_bf16_f32 v33, v38, v39
	v_cvt_pk_bf16_f32 v34, v34, v35
	v_cvt_pk_bf16_f32 v35, v42, v43
	v_pk_mul_f32 v[30:31], v[30:31], v[156:157] op_sel_hi:[1,0]
	v_mul_f32_e32 v38, 0xbfb8aa3b, v28
	v_mul_f32_e32 v39, 0xbfb8aa3b, v29
	v_lshl_add_u64 v[36:37], v[36:37], 0, v[114:115]
	v_pk_mul_f32 v[24:25], v[24:25], v[156:157] op_sel_hi:[1,0]
	v_pk_mul_f32 v[26:27], v[26:27], v[156:157] op_sel_hi:[1,0]
	v_exp_f32_e32 v38, v38
	v_exp_f32_e32 v39, v39
	v_mul_f32_e32 v40, 0xbfb8aa3b, v30
	v_mul_f32_e32 v41, 0xbfb8aa3b, v31
	global_store_dwordx4 v[36:37], v[32:35], off
	v_exp_f32_e32 v40, v40
	v_exp_f32_e32 v41, v41
	v_mul_f32_e32 v32, 0xbfb8aa3b, v24
	v_mul_f32_e32 v33, 0xbfb8aa3b, v25
	v_mul_f32_e32 v34, 0xbfb8aa3b, v26
	v_mul_f32_e32 v35, 0xbfb8aa3b, v27
	v_exp_f32_e32 v32, v32
	v_exp_f32_e32 v33, v33
	v_exp_f32_e32 v34, v34
	v_exp_f32_e32 v35, v35
	v_add_f32_e32 v38, 1.0, v38
	v_add_f32_e32 v39, 1.0, v39
	v_rcp_f32_e32 v38, v38
	v_rcp_f32_e32 v39, v39
	v_add_f32_e32 v40, 1.0, v40
	v_add_f32_e32 v41, 1.0, v41
	v_add_f32_e32 v32, 1.0, v32
	v_add_f32_e32 v33, 1.0, v33
	v_add_f32_e32 v34, 1.0, v34
	v_add_f32_e32 v35, 1.0, v35
	v_rcp_f32_e32 v40, v40
	v_rcp_f32_e32 v41, v41
	v_rcp_f32_e32 v32, v32
	v_rcp_f32_e32 v33, v33
	v_rcp_f32_e32 v34, v34
	v_rcp_f32_e32 v35, v35
	v_pk_mul_f32 v[28:29], v[28:29], v[38:39]
	v_pk_mul_f32 v[20:21], v[20:21], v[156:157] op_sel_hi:[1,0]
	v_pk_mul_f32 v[30:31], v[30:31], v[40:41]
	v_pk_mul_f32 v[22:23], v[22:23], v[156:157] op_sel_hi:[1,0]
	v_pk_mul_f32 v[20:21], v[20:21], v[28:29]
	v_pk_mul_f32 v[24:25], v[24:25], v[32:33]
	v_pk_mul_f32 v[26:27], v[26:27], v[34:35]
	v_pk_mul_f32 v[16:17], v[16:17], v[156:157] op_sel_hi:[1,0]
	v_pk_mul_f32 v[18:19], v[18:19], v[156:157] op_sel_hi:[1,0]
	v_pk_mul_f32 v[22:23], v[22:23], v[30:31]
	v_pk_mul_f32 v[26:27], v[18:19], v[26:27]
	v_pk_mul_f32 v[18:19], v[16:17], v[24:25]
	v_cvt_pk_bf16_f32 v16, v20, v21
	v_mad_i64_i32 v[20:21], s[38:39], v148, s56, v[112:113]
	v_pk_mul_f32 v[12:13], v[12:13], v[152:153] op_sel_hi:[1,0]
	v_cvt_pk_bf16_f32 v17, v22, v23
	v_cvt_pk_bf16_f32 v18, v18, v19
	v_cvt_pk_bf16_f32 v19, v26, v27
	v_lshl_add_u64 v[20:21], v[20:21], 0, v[114:115]
	v_mul_f32_e32 v22, 0xbfb8aa3b, v12
	v_mul_f32_e32 v23, 0xbfb8aa3b, v13
	v_pk_mul_f32 v[8:9], v[8:9], v[152:153] op_sel_hi:[1,0]
	v_pk_mul_f32 v[10:11], v[10:11], v[152:153] op_sel_hi:[1,0]
	v_exp_f32_e32 v22, v22
	v_exp_f32_e32 v23, v23
	global_store_dwordx4 v[20:21], v[16:19], off
	v_pk_mul_f32 v[14:15], v[14:15], v[152:153] op_sel_hi:[1,0]
	v_add_f32_e32 v22, 1.0, v22
	v_mul_f32_e32 v16, 0xbfb8aa3b, v8
	v_mul_f32_e32 v17, 0xbfb8aa3b, v9
	v_mul_f32_e32 v18, 0xbfb8aa3b, v10
	v_mul_f32_e32 v19, 0xbfb8aa3b, v11
	v_exp_f32_e32 v16, v16
	v_exp_f32_e32 v17, v17
	v_exp_f32_e32 v18, v18
	v_exp_f32_e32 v19, v19
	v_mul_f32_e32 v24, 0xbfb8aa3b, v14
	v_mul_f32_e32 v25, 0xbfb8aa3b, v15
	v_exp_f32_e32 v24, v24
	v_exp_f32_e32 v25, v25
	v_add_f32_e32 v23, 1.0, v23
	v_rcp_f32_e32 v22, v22
	v_rcp_f32_e32 v23, v23
	v_add_f32_e32 v16, 1.0, v16
	v_add_f32_e32 v17, 1.0, v17
	v_add_f32_e32 v18, 1.0, v18
	v_add_f32_e32 v19, 1.0, v19
	v_rcp_f32_e32 v16, v16
	v_rcp_f32_e32 v17, v17
	v_rcp_f32_e32 v18, v18
	v_rcp_f32_e32 v19, v19
	v_add_f32_e32 v24, 1.0, v24
	v_add_f32_e32 v25, 1.0, v25
	v_rcp_f32_e32 v24, v24
	v_rcp_f32_e32 v25, v25
	v_pk_mul_f32 v[12:13], v[12:13], v[22:23]
	v_pk_mul_f32 v[4:5], v[4:5], v[152:153] op_sel_hi:[1,0]
	v_pk_mul_f32 v[8:9], v[8:9], v[16:17]
	v_pk_mul_f32 v[4:5], v[4:5], v[12:13]
	v_pk_mul_f32 v[10:11], v[10:11], v[18:19]
	v_pk_mul_f32 v[0:1], v[0:1], v[152:153] op_sel_hi:[1,0]
	v_pk_mul_f32 v[2:3], v[2:3], v[152:153] op_sel_hi:[1,0]
	v_pk_mul_f32 v[14:15], v[14:15], v[24:25]
	v_pk_mul_f32 v[10:11], v[2:3], v[10:11]
	v_pk_mul_f32 v[2:3], v[0:1], v[8:9]
	v_cvt_pk_bf16_f32 v0, v4, v5
	v_mad_i64_i32 v[4:5], s[38:39], v146, s56, v[112:113]
	v_pk_mul_f32 v[6:7], v[6:7], v[152:153] op_sel_hi:[1,0]
	v_lshl_add_u64 v[4:5], v[4:5], 0, v[114:115]
	v_pk_mul_f32 v[6:7], v[6:7], v[14:15]
	s_nop 0
	v_cvt_pk_bf16_f32 v1, v6, v7
	v_cvt_pk_bf16_f32 v2, v2, v3
	v_cvt_pk_bf16_f32 v3, v10, v11
	global_store_dwordx4 v[4:5], v[0:3], off
	s_cbranch_vccnz .LBB0_516
	s_andn2_b64 vcc, exec, s[12:13]
	s_cbranch_vccnz .LBB0_515
	s_barrier
	s_branch .LBB0_515

; __device__ __forceinline__ float sq4(f32x4 v) { return (v[0] * v[0] + v[1] * v[1]) + (v[2] * v[2] + v[3] * v[3]); }
; __device__ __forceinline__ u32x4 pack8(f32x4 a, f32x4 b) { u32x4 w; w.x = cvt_pk_bf16(a[0], a[1]); w.y = cvt_pk_bf16(a[2], a[3]); w.z = cvt_pk_bf16(b[0], b[1]); w.w = cvt_pk_bf16(b[2], b[3]); return w; }
;     __device__ __forceinline__ void operator()(const f32x4 (&acc)[2][2][4][2], const Unit& u, int wr, int wc, int fr, int fq) const {
;     ...
;             for (int m = 0; m < 4; ++m)
; #pragma unroll
;                 for (int bj = 0; bj < 2; ++bj) bs[m][bj] = *(const u32x4*)(xb + (size_t)(u.pm * BM + ai * HALF + wr * 64 + m * 16 + fr) * 1024 + col0 + 128 * bj);
; #pragma unroll
;             for (int m = 0; m < 4; ++m) {
;                 const int row = u.pm * BM + ai * HALF + wr * 64 + m * 16 + fr;
;                 float q = 0.f;
; #pragma unroll
;                 for (int bj = 0; bj < 2; ++bj) {
;                     const size_t off = (size_t)row * 1024 + col0 + 128 * bj; const u32x4 w = bs[m][bj];
;                     const f32x4 b0 = (f32x4){__builtin_bit_cast(float, w.x << 16), __builtin_bit_cast(float, w.x & 0xffff0000u), __builtin_bit_cast(float, w.y << 16), __builtin_bit_cast(float, w.y & 0xffff0000u)};
;                     const f32x4 b1 = (f32x4){__builtin_bit_cast(float, w.z << 16), __builtin_bit_cast(float, w.z & 0xffff0000u), __builtin_bit_cast(float, w.w << 16), __builtin_bit_cast(float, w.w & 0xffff0000u)};
;                     const f32x4 v0 = acc[ai][bj][m][0] + b0, v1 = acc[ai][bj][m][1] + b1;
;                     if (last) { __builtin_nontemporal_store(v0, (f32x4*)(out + off)); __builtin_nontemporal_store(v1, (f32x4*)(out + off + 4)); }
;                     else { q += sq4(v0) + sq4(v1); *(u32x4*)(xb + off) = pack8(v0, v1); }
;                 }
;                 if (!last) { q += shx(q, 16); q += shx(q, 32); if (fq == 0) ss[(size_t)row * 16 + u.pn * 4 + wc] = q; }
.LBB0_605:
	v_lshl_or_b32 v168, s16, 8, v188
	v_lshl_add_u32 v172, s61, 8, v186
	v_ashrrev_i32_e32 v169, 31, v168
	v_lshlrev_b64 v[202:203], 1, v[168:169]
	v_ashrrev_i32_e32 v173, 31, v172
	v_lshl_add_u64 v[170:171], s[22:23], 0, v[202:203]
	v_lshlrev_b64 v[204:205], 11, v[172:173]
	v_lshl_add_u64 v[128:129], v[170:171], 0, v[204:205]
	global_load_dwordx4 v[192:195], v[128:129], off
	global_load_dwordx4 v[196:199], v[128:129], off offset:256
	v_or_b32_e32 v182, 16, v172
	v_or_b32_e32 v178, 32, v172
	v_or_b32_e32 v174, 48, v172
	v_ashrrev_i32_e32 v183, 31, v182
	v_ashrrev_i32_e32 v179, 31, v178
	v_ashrrev_i32_e32 v175, 31, v174
	v_lshlrev_b64 v[184:185], 11, v[182:183]
	v_lshlrev_b64 v[180:181], 11, v[178:179]
	v_lshlrev_b64 v[176:177], 11, v[174:175]
	v_lshl_add_u64 v[128:129], v[170:171], 0, v[184:185]
	v_lshl_add_u64 v[130:131], v[170:171], 0, v[180:181]
	v_lshl_add_u64 v[206:207], v[170:171], 0, v[176:177]
	global_load_dwordx4 v[148:151], v[128:129], off
	global_load_dwordx4 v[144:147], v[128:129], off offset:256
	global_load_dwordx4 v[140:143], v[130:131], off
	global_load_dwordx4 v[136:139], v[130:131], off offset:256
	global_load_dwordx4 v[132:135], v[206:207], off
	s_nop 0
	global_load_dwordx4 v[128:131], v[206:207], off offset:256
	v_lshl_add_u64 v[204:205], s[22:23], 0, v[204:205]
	v_lshl_add_u64 v[202:203], v[204:205], 0, v[202:203]
	v_mov_b32_e32 v200, v201
	s_lshl_b32 s38, s16, 2
	s_ashr_i32 s39, s38, 31
	s_waitcnt vmcnt(0)
	v_lshlrev_b32_e32 v204, 16, v192
	v_and_b32_e32 v205, 0xffff0000, v192
	v_lshlrev_b32_e32 v192, 16, v193
	v_and_b32_e32 v193, 0xffff0000, v193
	v_lshlrev_b32_e32 v206, 16, v194
	v_and_b32_e32 v207, 0xffff0000, v194
	v_lshlrev_b32_e32 v194, 16, v195
	v_and_b32_e32 v195, 0xffff0000, v195
	v_lshlrev_b32_e32 v208, 16, v196
	v_and_b32_e32 v209, 0xffff0000, v196
	v_lshlrev_b32_e32 v196, 16, v197
	v_and_b32_e32 v197, 0xffff0000, v197
	v_lshlrev_b32_e32 v210, 16, v198
	v_and_b32_e32 v211, 0xffff0000, v198
	v_lshlrev_b32_e32 v198, 16, v199
	v_and_b32_e32 v199, 0xffff0000, v199
	v_pk_add_f32 v[126:127], v[126:127], v[192:193]
	v_pk_add_f32 v[124:125], v[124:125], v[204:205]
	v_pk_add_f32 v[122:123], v[122:123], v[194:195]
	v_pk_add_f32 v[120:121], v[120:121], v[206:207]
	v_pk_add_f32 v[118:119], v[118:119], v[196:197]
	v_pk_add_f32 v[116:117], v[116:117], v[208:209]
	v_pk_add_f32 v[192:193], v[114:115], v[198:199]
	v_pk_add_f32 v[194:195], v[112:113], v[210:211]
	v_mul_f32_e32 v196, v125, v125
	v_mul_f32_e32 v197, v127, v127
	v_mul_f32_e32 v198, v121, v121
	v_mul_f32_e32 v199, v123, v123
	v_cvt_pk_bf16_f32 v112, v124, v125
	v_cvt_pk_bf16_f32 v113, v126, v127
	v_cvt_pk_bf16_f32 v114, v120, v121
	v_cvt_pk_bf16_f32 v115, v122, v123
	v_mul_f32_e32 v121, v117, v117
	v_mul_f32_e32 v123, v119, v119
	v_mul_f32_e32 v125, v195, v195
	v_mul_f32_e32 v127, v193, v193
	v_fmac_f32_e32 v196, v124, v124
	v_fmac_f32_e32 v197, v126, v126
	v_fmac_f32_e32 v198, v120, v120
	v_fmac_f32_e32 v199, v122, v122
	v_fmac_f32_e32 v121, v116, v116
	v_fmac_f32_e32 v123, v118, v118
	v_fmac_f32_e32 v125, v194, v194
	v_fmac_f32_e32 v127, v192, v192
	global_store_dwordx4 v[202:203], v[112:115], off
	s_nop 1
	v_cvt_pk_bf16_f32 v112, v116, v117
	v_cvt_pk_bf16_f32 v113, v118, v119
	v_cvt_pk_bf16_f32 v114, v194, v195
	v_add_f32_e32 v116, v196, v197
	v_add_f32_e32 v117, v198, v199
	v_add_f32_e32 v118, v121, v123
	v_add_f32_e32 v119, v125, v127
	v_cvt_pk_bf16_f32 v115, v192, v193
	global_store_dwordx4 v[202:203], v[112:115], off offset:256
	s_nop 1
	v_add_f32_e32 v112, v116, v117
	v_add_f32_e32 v113, v118, v119
	v_lshlrev_b32_e32 v114, 2, v200
	v_add_f32_e32 v112, v112, v113
	v_xor_b32_e32 v113, 64, v114
	v_mov_b32_e32 v113, v112
	s_nop 1
	v_permlane16_swap_b32_e32 v113, v112
	v_mov_b32_e32 v114, v201
	s_waitcnt lgkmcnt(0)
	v_add_f32_e32 v112, v112, v113
	v_lshlrev_b32_e32 v114, 2, v114
	v_xor_b32_e32 v113, 0x80, v114
	v_mov_b32_e32 v113, v112
	s_nop 1
	v_permlane32_swap_b32_e32 v113, v112
	s_and_saveexec_b64 s[40:41], s[10:11]
	s_cbranch_execz .LBB0_607
	s_waitcnt lgkmcnt(0)
	v_add_f32_e32 v114, v112, v113
	v_lshlrev_b64 v[112:113], 6, v[172:173]
	v_lshl_add_u64 v[112:113], s[24:25], 0, v[112:113]
	v_lshl_add_u64 v[112:113], s[38:39], 2, v[112:113]
	s_lshl_b32 s16, s50, 2
	v_lshl_add_u64 v[112:113], v[112:113], 0, s[16:17]
	global_store_dword v[112:113], v114, off
; __device__ __forceinline__ float sq4(f32x4 v) { return (v[0] * v[0] + v[1] * v[1]) + (v[2] * v[2] + v[3] * v[3]); }
; __device__ __forceinline__ u32x4 pack8(f32x4 a, f32x4 b) { u32x4 w; w.x = cvt_pk_bf16(a[0], a[1]); w.y = cvt_pk_bf16(a[2], a[3]); w.z = cvt_pk_bf16(b[0], b[1]); w.w = cvt_pk_bf16(b[2], b[3]); return w; }
;     __device__ __forceinline__ void operator()(const f32x4 (&acc)[2][2][4][2], const Unit& u, int wr, int wc, int fr, int fq) const {
;     ...
;             for (int m = 0; m < 4; ++m) {
;                 const int row = u.pm * BM + ai * HALF + wr * 64 + m * 16 + fr;
;                 float q = 0.f;
; #pragma unroll
;                 for (int bj = 0; bj < 2; ++bj) {
;                     const size_t off = (size_t)row * 1024 + col0 + 128 * bj; const u32x4 w = bs[m][bj];
;                     const f32x4 b0 = (f32x4){__builtin_bit_cast(float, w.x << 16), __builtin_bit_cast(float, w.x & 0xffff0000u), __builtin_bit_cast(float, w.y << 16), __builtin_bit_cast(float, w.y & 0xffff0000u)};
;                     const f32x4 b1 = (f32x4){__builtin_bit_cast(float, w.z << 16), __builtin_bit_cast(float, w.z & 0xffff0000u), __builtin_bit_cast(float, w.w << 16), __builtin_bit_cast(float, w.w & 0xffff0000u)};
;                     const f32x4 v0 = acc[ai][bj][m][0] + b0, v1 = acc[ai][bj][m][1] + b1;
;                     if (last) { __builtin_nontemporal_store(v0, (f32x4*)(out + off)); __builtin_nontemporal_store(v1, (f32x4*)(out + off + 4)); }
;                     else { q += sq4(v0) + sq4(v1); *(u32x4*)(xb + off) = pack8(v0, v1); }
;                 }
;                 if (!last) { q += shx(q, 16); q += shx(q, 32); if (fq == 0) ss[(size_t)row * 16 + u.pn * 4 + wc] = q; }
.LBB0_607:
	s_or_b64 exec, exec, s[40:41]
	v_lshlrev_b32_e32 v112, 16, v148
	s_waitcnt lgkmcnt(0)
	v_and_b32_e32 v113, 0xffff0000, v148
	v_lshlrev_b32_e32 v114, 16, v149
	v_and_b32_e32 v115, 0xffff0000, v149
	v_lshlrev_b32_e32 v116, 16, v150
	v_and_b32_e32 v117, 0xffff0000, v150
	v_lshlrev_b32_e32 v118, 16, v151
	v_and_b32_e32 v119, 0xffff0000, v151
	v_pk_add_f32 v[110:111], v[110:111], v[114:115]
	v_pk_add_f32 v[108:109], v[108:109], v[112:113]
	v_pk_add_f32 v[112:113], v[106:107], v[118:119]
	v_pk_add_f32 v[106:107], v[104:105], v[116:117]
	v_mul_f32_e32 v104, v109, v109
	v_mul_f32_e32 v105, v111, v111
	v_fmac_f32_e32 v104, v108, v108
	v_fmac_f32_e32 v105, v110, v110
	v_add_f32_e32 v104, v104, v105
	v_mul_f32_e32 v105, v107, v107
	v_mul_f32_e32 v114, v113, v113
	v_fmac_f32_e32 v105, v106, v106
	v_fmac_f32_e32 v114, v112, v112
	v_add_f32_e32 v105, v105, v114
	v_add_f32_e32 v114, v104, v105
	v_cvt_pk_bf16_f32 v104, v108, v109
	v_lshl_add_u64 v[108:109], s[22:23], 0, v[184:185]
	v_cvt_pk_bf16_f32 v105, v110, v111
	v_cvt_pk_bf16_f32 v106, v106, v107
	v_cvt_pk_bf16_f32 v107, v112, v113
	v_lshl_add_u64 v[108:109], v[168:169], 1, v[108:109]
	global_store_dwordx4 v[108:109], v[104:107], off
	v_lshlrev_b32_e32 v110, 16, v146
	v_and_b32_e32 v111, 0xffff0000, v146
	v_lshlrev_b32_e32 v104, 16, v144
	v_and_b32_e32 v105, 0xffff0000, v144
	v_lshlrev_b32_e32 v106, 16, v145
	v_and_b32_e32 v107, 0xffff0000, v145
	v_lshlrev_b32_e32 v112, 16, v147
	v_and_b32_e32 v113, 0xffff0000, v147
	v_pk_add_f32 v[102:103], v[102:103], v[106:107]
	v_pk_add_f32 v[100:101], v[100:101], v[104:105]
	v_pk_add_f32 v[104:105], v[98:99], v[112:113]
	v_pk_add_f32 v[98:99], v[96:97], v[110:111]
	v_mul_f32_e32 v96, v101, v101
	v_mul_f32_e32 v97, v103, v103
	v_fmac_f32_e32 v96, v100, v100
	v_fmac_f32_e32 v97, v102, v102
	v_add_f32_e32 v96, v96, v97
	v_mul_f32_e32 v97, v99, v99
	v_mul_f32_e32 v106, v105, v105
	v_fmac_f32_e32 v97, v98, v98
	v_fmac_f32_e32 v106, v104, v104
	v_add_f32_e32 v97, v97, v106
	v_add_f32_e32 v96, v96, v97
	v_add_f32_e32 v106, v114, v96
	v_cvt_pk_bf16_f32 v96, v100, v101
	v_cvt_pk_bf16_f32 v97, v102, v103
	v_cvt_pk_bf16_f32 v98, v98, v99
	v_cvt_pk_bf16_f32 v99, v104, v105
	global_store_dwordx4 v[108:109], v[96:99], off offset:256
	s_nop 1
	v_mov_b32_e32 v96, v201
	v_mov_b32_e32 v97, v201
	v_lshlrev_b32_e32 v96, 2, v96
	v_xor_b32_e32 v96, 64, v96
	v_mov_b32_e32 v96, v106
	s_nop 1
	v_permlane16_swap_b32_e32 v96, v106
	s_waitcnt lgkmcnt(0)
	v_add_f32_e32 v96, v106, v96
	v_lshlrev_b32_e32 v97, 2, v97
	v_xor_b32_e32 v97, 0x80, v97
	v_mov_b32_e32 v97, v96
	s_nop 1
	v_permlane32_swap_b32_e32 v97, v96
	s_and_saveexec_b64 s[40:41], s[10:11]
	s_cbranch_execz .LBB0_609
	s_waitcnt lgkmcnt(0)
	v_add_f32_e32 v98, v96, v97
	v_lshlrev_b64 v[96:97], 6, v[182:183]
	v_lshl_add_u64 v[96:97], s[24:25], 0, v[96:97]
	v_lshl_add_u64 v[96:97], s[38:39], 2, v[96:97]
	s_lshl_b32 s16, s50, 2
	v_lshl_add_u64 v[96:97], v[96:97], 0, s[16:17]
	global_store_dword v[96:97], v98, off
.LBB0_609:
	s_or_b64 exec, exec, s[40:41]
	v_lshlrev_b32_e32 v96, 16, v140
	s_waitcnt lgkmcnt(0)
	v_and_b32_e32 v97, 0xffff0000, v140
	v_lshlrev_b32_e32 v98, 16, v141
	v_and_b32_e32 v99, 0xffff0000, v141
	v_lshlrev_b32_e32 v100, 16, v142
	v_and_b32_e32 v101, 0xffff0000, v142
	v_lshlrev_b32_e32 v102, 16, v143
	v_and_b32_e32 v103, 0xffff0000, v143
	v_pk_add_f32 v[94:95], v[94:95], v[98:99]
	v_pk_add_f32 v[92:93], v[92:93], v[96:97]
	v_pk_add_f32 v[96:97], v[90:91], v[102:103]
	v_pk_add_f32 v[90:91], v[88:89], v[100:101]
	v_mul_f32_e32 v88, v93, v93
	v_mul_f32_e32 v89, v95, v95
	v_fmac_f32_e32 v88, v92, v92
	v_fmac_f32_e32 v89, v94, v94
	v_add_f32_e32 v88, v88, v89
	v_mul_f32_e32 v89, v91, v91
	v_mul_f32_e32 v98, v97, v97
	v_fmac_f32_e32 v89, v90, v90
	v_fmac_f32_e32 v98, v96, v96
	v_add_f32_e32 v89, v89, v98
	v_add_f32_e32 v98, v88, v89
	v_cvt_pk_bf16_f32 v88, v92, v93
	v_lshl_add_u64 v[92:93], s[22:23], 0, v[180:181]
	v_cvt_pk_bf16_f32 v89, v94, v95
	v_cvt_pk_bf16_f32 v90, v90, v91
	v_cvt_pk_bf16_f32 v91, v96, v97
	v_lshl_add_u64 v[92:93], v[168:169], 1, v[92:93]
	global_store_dwordx4 v[92:93], v[88:91], off
	v_lshlrev_b32_e32 v94, 16, v138
	v_and_b32_e32 v95, 0xffff0000, v138
	v_lshlrev_b32_e32 v88, 16, v136
	v_and_b32_e32 v89, 0xffff0000, v136
	v_lshlrev_b32_e32 v90, 16, v137
	v_and_b32_e32 v91, 0xffff0000, v137
	v_lshlrev_b32_e32 v96, 16, v139
	v_and_b32_e32 v97, 0xffff0000, v139
	v_pk_add_f32 v[86:87], v[86:87], v[90:91]
	v_pk_add_f32 v[84:85], v[84:85], v[88:89]
	v_pk_add_f32 v[88:89], v[82:83], v[96:97]
	v_pk_add_f32 v[82:83], v[80:81], v[94:95]
	v_mul_f32_e32 v80, v85, v85
	v_mul_f32_e32 v81, v87, v87
	v_fmac_f32_e32 v80, v84, v84
	v_fmac_f32_e32 v81, v86, v86
	v_add_f32_e32 v80, v80, v81
	v_mul_f32_e32 v81, v83, v83
	v_mul_f32_e32 v90, v89, v89
	v_fmac_f32_e32 v81, v82, v82
	v_fmac_f32_e32 v90, v88, v88
	v_add_f32_e32 v81, v81, v90
	v_add_f32_e32 v80, v80, v81
	v_add_f32_e32 v90, v98, v80
	v_cvt_pk_bf16_f32 v80, v84, v85
	v_cvt_pk_bf16_f32 v81, v86, v87
	v_cvt_pk_bf16_f32 v82, v82, v83
	v_cvt_pk_bf16_f32 v83, v88, v89
	global_store_dwordx4 v[92:93], v[80:83], off offset:256
	s_nop 1
	v_mov_b32_e32 v80, v201
	v_mov_b32_e32 v81, v201
	v_lshlrev_b32_e32 v80, 2, v80
	v_xor_b32_e32 v80, 64, v80
	v_mov_b32_e32 v80, v90
	s_nop 1
	v_permlane16_swap_b32_e32 v80, v90
	s_waitcnt lgkmcnt(0)
	v_add_f32_e32 v80, v90, v80
	v_lshlrev_b32_e32 v81, 2, v81
	v_xor_b32_e32 v81, 0x80, v81
	v_mov_b32_e32 v81, v80
	s_nop 1
	v_permlane32_swap_b32_e32 v81, v80
	s_and_saveexec_b64 s[40:41], s[10:11]
	s_cbranch_execz .LBB0_611
	s_waitcnt lgkmcnt(0)
	v_add_f32_e32 v82, v80, v81
	v_lshlrev_b64 v[80:81], 6, v[178:179]
	v_lshl_add_u64 v[80:81], s[24:25], 0, v[80:81]
	v_lshl_add_u64 v[80:81], s[38:39], 2, v[80:81]
	s_lshl_b32 s16, s50, 2
	v_lshl_add_u64 v[80:81], v[80:81], 0, s[16:17]
	global_store_dword v[80:81], v82, off
; __device__ __forceinline__ float sq4(f32x4 v) { return (v[0] * v[0] + v[1] * v[1]) + (v[2] * v[2] + v[3] * v[3]); }
; __device__ __forceinline__ u32x4 pack8(f32x4 a, f32x4 b) { u32x4 w; w.x = cvt_pk_bf16(a[0], a[1]); w.y = cvt_pk_bf16(a[2], a[3]); w.z = cvt_pk_bf16(b[0], b[1]); w.w = cvt_pk_bf16(b[2], b[3]); return w; }
;     __device__ __forceinline__ void operator()(const f32x4 (&acc)[2][2][4][2], const Unit& u, int wr, int wc, int fr, int fq) const {
;     ...
;             u32x4 bs[4][2];
; #pragma unroll
;             for (int m = 0; m < 4; ++m)
; #pragma unroll
;                 for (int bj = 0; bj < 2; ++bj) bs[m][bj] = *(const u32x4*)(xb + (size_t)(u.pm * BM + ai * HALF + wr * 64 + m * 16 + fr) * 1024 + col0 + 128 * bj);
; #pragma unroll
;             for (int m = 0; m < 4; ++m) {
;                 const int row = u.pm * BM + ai * HALF + wr * 64 + m * 16 + fr;
;                 float q = 0.f;
; #pragma unroll
;                 for (int bj = 0; bj < 2; ++bj) {
;                     const size_t off = (size_t)row * 1024 + col0 + 128 * bj; const u32x4 w = bs[m][bj];
;                     const f32x4 b0 = (f32x4){__builtin_bit_cast(float, w.x << 16), __builtin_bit_cast(float, w.x & 0xffff0000u), __builtin_bit_cast(float, w.y << 16), __builtin_bit_cast(float, w.y & 0xffff0000u)};
;                     const f32x4 b1 = (f32x4){__builtin_bit_cast(float, w.z << 16), __builtin_bit_cast(float, w.z & 0xffff0000u), __builtin_bit_cast(float, w.w << 16), __builtin_bit_cast(float, w.w & 0xffff0000u)};
;                     const f32x4 v0 = acc[ai][bj][m][0] + b0, v1 = acc[ai][bj][m][1] + b1;
;                     if (last) { __builtin_nontemporal_store(v0, (f32x4*)(out + off)); __builtin_nontemporal_store(v1, (f32x4*)(out + off + 4)); }
;                     else { q += sq4(v0) + sq4(v1); *(u32x4*)(xb + off) = pack8(v0, v1); }
;                 }
;                 if (!last) { q += shx(q, 16); q += shx(q, 32); if (fq == 0) ss[(size_t)row * 16 + u.pn * 4 + wc] = q; }
.LBB0_611:
	s_or_b64 exec, exec, s[40:41]
	v_lshlrev_b32_e32 v80, 16, v132
	s_waitcnt lgkmcnt(0)
	v_and_b32_e32 v81, 0xffff0000, v132
	v_lshlrev_b32_e32 v82, 16, v133
	v_and_b32_e32 v83, 0xffff0000, v133
	v_lshlrev_b32_e32 v84, 16, v134
	v_and_b32_e32 v85, 0xffff0000, v134
	v_lshlrev_b32_e32 v86, 16, v135
	v_and_b32_e32 v87, 0xffff0000, v135
	v_pk_add_f32 v[78:79], v[78:79], v[82:83]
	v_pk_add_f32 v[76:77], v[76:77], v[80:81]
	v_pk_add_f32 v[80:81], v[74:75], v[86:87]
	v_pk_add_f32 v[74:75], v[72:73], v[84:85]
	v_mul_f32_e32 v72, v77, v77
	v_mul_f32_e32 v73, v79, v79
	v_fmac_f32_e32 v72, v76, v76
	v_fmac_f32_e32 v73, v78, v78
	v_add_f32_e32 v72, v72, v73
	v_mul_f32_e32 v73, v75, v75
	v_mul_f32_e32 v82, v81, v81
	v_fmac_f32_e32 v73, v74, v74
	v_fmac_f32_e32 v82, v80, v80
	v_add_f32_e32 v73, v73, v82
	v_add_f32_e32 v82, v72, v73
	v_cvt_pk_bf16_f32 v72, v76, v77
	v_lshl_add_u64 v[76:77], s[22:23], 0, v[176:177]
	v_cvt_pk_bf16_f32 v73, v78, v79
	v_cvt_pk_bf16_f32 v74, v74, v75
	v_cvt_pk_bf16_f32 v75, v80, v81
	v_lshl_add_u64 v[76:77], v[168:169], 1, v[76:77]
	global_store_dwordx4 v[76:77], v[72:75], off
	v_lshlrev_b32_e32 v78, 16, v130
	v_and_b32_e32 v79, 0xffff0000, v130
	v_lshlrev_b32_e32 v72, 16, v128
	v_and_b32_e32 v73, 0xffff0000, v128
	v_lshlrev_b32_e32 v74, 16, v129
	v_and_b32_e32 v75, 0xffff0000, v129
	v_lshlrev_b32_e32 v80, 16, v131
	v_and_b32_e32 v81, 0xffff0000, v131
	v_pk_add_f32 v[70:71], v[70:71], v[74:75]
	v_pk_add_f32 v[68:69], v[68:69], v[72:73]
	v_pk_add_f32 v[72:73], v[66:67], v[80:81]
	v_pk_add_f32 v[66:67], v[64:65], v[78:79]
	v_mul_f32_e32 v64, v69, v69
	v_mul_f32_e32 v65, v71, v71
	v_fmac_f32_e32 v64, v68, v68
	v_fmac_f32_e32 v65, v70, v70
	v_add_f32_e32 v64, v64, v65
	v_mul_f32_e32 v65, v67, v67
	v_mul_f32_e32 v74, v73, v73
	v_fmac_f32_e32 v65, v66, v66
	v_fmac_f32_e32 v74, v72, v72
	v_add_f32_e32 v65, v65, v74
	v_add_f32_e32 v64, v64, v65
	v_add_f32_e32 v74, v82, v64
	v_cvt_pk_bf16_f32 v64, v68, v69
	v_cvt_pk_bf16_f32 v65, v70, v71
	v_cvt_pk_bf16_f32 v66, v66, v67
	v_cvt_pk_bf16_f32 v67, v72, v73
	global_store_dwordx4 v[76:77], v[64:67], off offset:256
	s_nop 1
	v_mov_b32_e32 v64, v201
	v_mov_b32_e32 v65, v201
	v_lshlrev_b32_e32 v64, 2, v64
	v_xor_b32_e32 v64, 64, v64
	v_mov_b32_e32 v64, v74
	s_nop 1
	v_permlane16_swap_b32_e32 v64, v74
	s_waitcnt lgkmcnt(0)
	v_add_f32_e32 v64, v74, v64
	v_lshlrev_b32_e32 v65, 2, v65
	v_xor_b32_e32 v65, 0x80, v65
	v_mov_b32_e32 v65, v64
	s_nop 1
	v_permlane32_swap_b32_e32 v65, v64
	s_and_saveexec_b64 s[40:41], s[10:11]
	s_cbranch_execz .LBB0_613
	s_waitcnt lgkmcnt(0)
	v_add_f32_e32 v66, v64, v65
	v_lshlrev_b64 v[64:65], 6, v[174:175]
	v_lshl_add_u64 v[64:65], s[24:25], 0, v[64:65]
	v_lshl_add_u64 v[64:65], s[38:39], 2, v[64:65]
	s_lshl_b32 s16, s50, 2
	v_lshl_add_u64 v[64:65], v[64:65], 0, s[16:17]
	global_store_dword v[64:65], v66, off
.LBB0_613:
	s_or_b64 exec, exec, s[40:41]
	v_add_u32_e32 v100, 0x80, v172
	v_ashrrev_i32_e32 v101, 31, v100
	v_lshlrev_b64 v[110:111], 11, v[100:101]
	s_waitcnt lgkmcnt(0)
	v_lshl_add_u64 v[64:65], v[170:171], 0, v[110:111]
	global_load_dwordx4 v[102:105], v[64:65], off
	global_load_dwordx4 v[106:109], v[64:65], off offset:256
	v_add_u32_e32 v96, 0x90, v172
	v_add_u32_e32 v92, 0xa0, v172
	v_add_u32_e32 v88, 0xb0, v172
	v_ashrrev_i32_e32 v97, 31, v96
	v_ashrrev_i32_e32 v93, 31, v92
	v_ashrrev_i32_e32 v89, 31, v88
	v_lshlrev_b64 v[98:99], 11, v[96:97]
	v_lshlrev_b64 v[94:95], 11, v[92:93]
	v_lshlrev_b64 v[90:91], 11, v[88:89]
	v_lshl_add_u64 v[64:65], v[170:171], 0, v[98:99]
	v_lshl_add_u64 v[66:67], v[170:171], 0, v[94:95]
	v_lshl_add_u64 v[112:113], v[170:171], 0, v[90:91]
	global_load_dwordx4 v[84:87], v[64:65], off
	global_load_dwordx4 v[80:83], v[64:65], off offset:256
	global_load_dwordx4 v[76:79], v[66:67], off
	global_load_dwordx4 v[72:75], v[66:67], off offset:256
	global_load_dwordx4 v[68:71], v[112:113], off
	s_nop 0
	global_load_dwordx4 v[64:67], v[112:113], off offset:256
	v_lshl_add_u64 v[110:111], s[22:23], 0, v[110:111]
	v_lshl_add_u64 v[110:111], v[168:169], 1, v[110:111]
	v_mov_b32_e32 v120, v201
	s_waitcnt vmcnt(7)
	v_lshlrev_b32_e32 v112, 16, v102
	v_and_b32_e32 v113, 0xffff0000, v102
	v_lshlrev_b32_e32 v102, 16, v103
	v_and_b32_e32 v103, 0xffff0000, v103
	v_lshlrev_b32_e32 v114, 16, v104
	v_and_b32_e32 v115, 0xffff0000, v104
	v_lshlrev_b32_e32 v104, 16, v105
	v_and_b32_e32 v105, 0xffff0000, v105
	s_waitcnt vmcnt(6)
	v_lshlrev_b32_e32 v116, 16, v106
	v_and_b32_e32 v117, 0xffff0000, v106
	v_lshlrev_b32_e32 v106, 16, v107
	v_and_b32_e32 v107, 0xffff0000, v107
	v_lshlrev_b32_e32 v118, 16, v108
	v_and_b32_e32 v119, 0xffff0000, v108
	v_lshlrev_b32_e32 v108, 16, v109
	v_and_b32_e32 v109, 0xffff0000, v109
	v_pk_add_f32 v[62:63], v[62:63], v[102:103]
	v_pk_add_f32 v[60:61], v[60:61], v[112:113]
	v_pk_add_f32 v[58:59], v[58:59], v[104:105]
	v_pk_add_f32 v[56:57], v[56:57], v[114:115]
	v_pk_add_f32 v[54:55], v[54:55], v[106:107]
	v_pk_add_f32 v[52:53], v[52:53], v[116:117]
	v_pk_add_f32 v[102:103], v[50:51], v[108:109]
	v_pk_add_f32 v[104:105], v[48:49], v[118:119]
	v_mul_f32_e32 v106, v61, v61
	v_mul_f32_e32 v107, v63, v63
	v_mul_f32_e32 v108, v57, v57
	v_mul_f32_e32 v109, v59, v59
	v_cvt_pk_bf16_f32 v48, v60, v61
	v_cvt_pk_bf16_f32 v49, v62, v63
	v_cvt_pk_bf16_f32 v50, v56, v57
	v_cvt_pk_bf16_f32 v51, v58, v59
	v_mul_f32_e32 v57, v53, v53
	v_mul_f32_e32 v59, v55, v55
	v_mul_f32_e32 v61, v105, v105
	v_mul_f32_e32 v63, v103, v103
	v_fmac_f32_e32 v106, v60, v60
	v_fmac_f32_e32 v107, v62, v62
	v_fmac_f32_e32 v108, v56, v56
	v_fmac_f32_e32 v109, v58, v58
	v_fmac_f32_e32 v57, v52, v52
	v_fmac_f32_e32 v59, v54, v54
	v_fmac_f32_e32 v61, v104, v104
	v_fmac_f32_e32 v63, v102, v102
	global_store_dwordx4 v[110:111], v[48:51], off
	s_nop 1
	v_cvt_pk_bf16_f32 v48, v52, v53
	v_cvt_pk_bf16_f32 v49, v54, v55
	v_cvt_pk_bf16_f32 v50, v104, v105
	v_add_f32_e32 v52, v106, v107
	v_add_f32_e32 v53, v108, v109
	v_add_f32_e32 v54, v57, v59
	v_add_f32_e32 v55, v61, v63
	v_cvt_pk_bf16_f32 v51, v102, v103
	global_store_dwordx4 v[110:111], v[48:51], off offset:256
	s_nop 1
	v_add_f32_e32 v48, v52, v53
	v_add_f32_e32 v49, v54, v55
	v_lshlrev_b32_e32 v50, 2, v120
	v_add_f32_e32 v48, v48, v49
	v_xor_b32_e32 v49, 64, v50
	v_mov_b32_e32 v49, v48
	s_nop 1
	v_permlane16_swap_b32_e32 v49, v48
	v_mov_b32_e32 v50, v201
	s_waitcnt lgkmcnt(0)
	v_add_f32_e32 v48, v48, v49
	v_lshlrev_b32_e32 v50, 2, v50
	v_xor_b32_e32 v49, 0x80, v50
	v_mov_b32_e32 v49, v48
	s_nop 1
	v_permlane32_swap_b32_e32 v49, v48
	s_and_saveexec_b64 s[40:41], s[10:11]
	s_cbranch_execz .LBB0_615
	s_waitcnt lgkmcnt(0)
	v_add_f32_e32 v50, v48, v49
	v_lshlrev_b64 v[48:49], 6, v[100:101]
	v_lshl_add_u64 v[48:49], s[24:25], 0, v[48:49]
	v_lshl_add_u64 v[48:49], s[38:39], 2, v[48:49]
	s_lshl_b32 s16, s50, 2
	v_lshl_add_u64 v[48:49], v[48:49], 0, s[16:17]
	global_store_dword v[48:49], v50, off
; __device__ __forceinline__ float sq4(f32x4 v) { return (v[0] * v[0] + v[1] * v[1]) + (v[2] * v[2] + v[3] * v[3]); }
; __device__ __forceinline__ u32x4 pack8(f32x4 a, f32x4 b) { u32x4 w; w.x = cvt_pk_bf16(a[0], a[1]); w.y = cvt_pk_bf16(a[2], a[3]); w.z = cvt_pk_bf16(b[0], b[1]); w.w = cvt_pk_bf16(b[2], b[3]); return w; }
;     __device__ __forceinline__ void operator()(const f32x4 (&acc)[2][2][4][2], const Unit& u, int wr, int wc, int fr, int fq) const {
;     ...
;             for (int m = 0; m < 4; ++m) {
;                 const int row = u.pm * BM + ai * HALF + wr * 64 + m * 16 + fr;
;                 float q = 0.f;
; #pragma unroll
;                 for (int bj = 0; bj < 2; ++bj) {
;                     const size_t off = (size_t)row * 1024 + col0 + 128 * bj; const u32x4 w = bs[m][bj];
;                     const f32x4 b0 = (f32x4){__builtin_bit_cast(float, w.x << 16), __builtin_bit_cast(float, w.x & 0xffff0000u), __builtin_bit_cast(float, w.y << 16), __builtin_bit_cast(float, w.y & 0xffff0000u)};
;                     const f32x4 b1 = (f32x4){__builtin_bit_cast(float, w.z << 16), __builtin_bit_cast(float, w.z & 0xffff0000u), __builtin_bit_cast(float, w.w << 16), __builtin_bit_cast(float, w.w & 0xffff0000u)};
;                     const f32x4 v0 = acc[ai][bj][m][0] + b0, v1 = acc[ai][bj][m][1] + b1;
;                     if (last) { __builtin_nontemporal_store(v0, (f32x4*)(out + off)); __builtin_nontemporal_store(v1, (f32x4*)(out + off + 4)); }
;                     else { q += sq4(v0) + sq4(v1); *(u32x4*)(xb + off) = pack8(v0, v1); }
;                 }
;                 if (!last) { q += shx(q, 16); q += shx(q, 32); if (fq == 0) ss[(size_t)row * 16 + u.pn * 4 + wc] = q; }
.LBB0_615:
	s_or_b64 exec, exec, s[40:41]
	s_waitcnt vmcnt(7)
	v_lshlrev_b32_e32 v48, 16, v84
	s_waitcnt lgkmcnt(0)
	v_and_b32_e32 v49, 0xffff0000, v84
	v_lshlrev_b32_e32 v50, 16, v85
	v_and_b32_e32 v51, 0xffff0000, v85
	v_lshlrev_b32_e32 v52, 16, v86
	v_and_b32_e32 v53, 0xffff0000, v86
	v_lshlrev_b32_e32 v54, 16, v87
	v_and_b32_e32 v55, 0xffff0000, v87
	v_pk_add_f32 v[46:47], v[46:47], v[50:51]
	v_pk_add_f32 v[44:45], v[44:45], v[48:49]
	v_pk_add_f32 v[48:49], v[42:43], v[54:55]
	v_pk_add_f32 v[42:43], v[40:41], v[52:53]
	v_mul_f32_e32 v40, v45, v45
	v_mul_f32_e32 v41, v47, v47
	v_fmac_f32_e32 v40, v44, v44
	v_fmac_f32_e32 v41, v46, v46
	v_add_f32_e32 v40, v40, v41
	v_mul_f32_e32 v41, v43, v43
	v_mul_f32_e32 v50, v49, v49
	v_fmac_f32_e32 v41, v42, v42
	v_fmac_f32_e32 v50, v48, v48
	v_add_f32_e32 v41, v41, v50
	v_add_f32_e32 v50, v40, v41
	v_cvt_pk_bf16_f32 v40, v44, v45
	v_lshl_add_u64 v[44:45], s[22:23], 0, v[98:99]
	v_cvt_pk_bf16_f32 v41, v46, v47
	v_cvt_pk_bf16_f32 v42, v42, v43
	v_cvt_pk_bf16_f32 v43, v48, v49
	v_lshl_add_u64 v[44:45], v[168:169], 1, v[44:45]
	global_store_dwordx4 v[44:45], v[40:43], off
	s_waitcnt vmcnt(7)
	v_lshlrev_b32_e32 v46, 16, v82
	v_and_b32_e32 v47, 0xffff0000, v82
	v_lshlrev_b32_e32 v40, 16, v80
	v_and_b32_e32 v41, 0xffff0000, v80
	v_lshlrev_b32_e32 v42, 16, v81
	v_and_b32_e32 v43, 0xffff0000, v81
	v_lshlrev_b32_e32 v48, 16, v83
	v_and_b32_e32 v49, 0xffff0000, v83
	v_pk_add_f32 v[38:39], v[38:39], v[42:43]
	v_pk_add_f32 v[36:37], v[36:37], v[40:41]
	v_pk_add_f32 v[40:41], v[34:35], v[48:49]
	v_pk_add_f32 v[34:35], v[32:33], v[46:47]
	v_mul_f32_e32 v32, v37, v37
	v_mul_f32_e32 v33, v39, v39
	v_fmac_f32_e32 v32, v36, v36
	v_fmac_f32_e32 v33, v38, v38
	v_add_f32_e32 v32, v32, v33
	v_mul_f32_e32 v33, v35, v35
	v_mul_f32_e32 v42, v41, v41
	v_fmac_f32_e32 v33, v34, v34
	v_fmac_f32_e32 v42, v40, v40
	v_add_f32_e32 v33, v33, v42
	v_add_f32_e32 v32, v32, v33
	v_add_f32_e32 v42, v50, v32
	v_cvt_pk_bf16_f32 v32, v36, v37
	v_cvt_pk_bf16_f32 v33, v38, v39
	v_cvt_pk_bf16_f32 v34, v34, v35
	v_cvt_pk_bf16_f32 v35, v40, v41
	global_store_dwordx4 v[44:45], v[32:35], off offset:256
	s_nop 1
	v_mov_b32_e32 v32, v201
	v_mov_b32_e32 v33, v201
	v_lshlrev_b32_e32 v32, 2, v32
	v_xor_b32_e32 v32, 64, v32
	v_mov_b32_e32 v32, v42
	s_nop 1
	v_permlane16_swap_b32_e32 v32, v42
	s_waitcnt lgkmcnt(0)
	v_add_f32_e32 v32, v42, v32
	v_lshlrev_b32_e32 v33, 2, v33
	v_xor_b32_e32 v33, 0x80, v33
	v_mov_b32_e32 v33, v32
	s_nop 1
	v_permlane32_swap_b32_e32 v33, v32
	s_and_saveexec_b64 s[40:41], s[10:11]
	s_cbranch_execz .LBB0_617
	s_waitcnt lgkmcnt(0)
	v_add_f32_e32 v34, v32, v33
	v_lshlrev_b64 v[32:33], 6, v[96:97]
	v_lshl_add_u64 v[32:33], s[24:25], 0, v[32:33]
	v_lshl_add_u64 v[32:33], s[38:39], 2, v[32:33]
	s_lshl_b32 s16, s50, 2
	v_lshl_add_u64 v[32:33], v[32:33], 0, s[16:17]
	global_store_dword v[32:33], v34, off
; __device__ __forceinline__ float sq4(f32x4 v) { return (v[0] * v[0] + v[1] * v[1]) + (v[2] * v[2] + v[3] * v[3]); }
; __device__ __forceinline__ u32x4 pack8(f32x4 a, f32x4 b) { u32x4 w; w.x = cvt_pk_bf16(a[0], a[1]); w.y = cvt_pk_bf16(a[2], a[3]); w.z = cvt_pk_bf16(b[0], b[1]); w.w = cvt_pk_bf16(b[2], b[3]); return w; }
;     __device__ __forceinline__ void operator()(const f32x4 (&acc)[2][2][4][2], const Unit& u, int wr, int wc, int fr, int fq) const {
;     ...
;             for (int m = 0; m < 4; ++m) {
;                 const int row = u.pm * BM + ai * HALF + wr * 64 + m * 16 + fr;
;                 float q = 0.f;
; #pragma unroll
;                 for (int bj = 0; bj < 2; ++bj) {
;                     const size_t off = (size_t)row * 1024 + col0 + 128 * bj; const u32x4 w = bs[m][bj];
;                     const f32x4 b0 = (f32x4){__builtin_bit_cast(float, w.x << 16), __builtin_bit_cast(float, w.x & 0xffff0000u), __builtin_bit_cast(float, w.y << 16), __builtin_bit_cast(float, w.y & 0xffff0000u)};
;                     const f32x4 b1 = (f32x4){__builtin_bit_cast(float, w.z << 16), __builtin_bit_cast(float, w.z & 0xffff0000u), __builtin_bit_cast(float, w.w << 16), __builtin_bit_cast(float, w.w & 0xffff0000u)};
;                     const f32x4 v0 = acc[ai][bj][m][0] + b0, v1 = acc[ai][bj][m][1] + b1;
;                     if (last) { __builtin_nontemporal_store(v0, (f32x4*)(out + off)); __builtin_nontemporal_store(v1, (f32x4*)(out + off + 4)); }
;                     else { q += sq4(v0) + sq4(v1); *(u32x4*)(xb + off) = pack8(v0, v1); }
;                 }
;                 if (!last) { q += shx(q, 16); q += shx(q, 32); if (fq == 0) ss[(size_t)row * 16 + u.pn * 4 + wc] = q; }
.LBB0_617:
	s_or_b64 exec, exec, s[40:41]
	s_waitcnt vmcnt(7)
	v_lshlrev_b32_e32 v32, 16, v76
	s_waitcnt lgkmcnt(0)
	v_and_b32_e32 v33, 0xffff0000, v76
	v_lshlrev_b32_e32 v34, 16, v77
	v_and_b32_e32 v35, 0xffff0000, v77
	v_lshlrev_b32_e32 v36, 16, v78
	v_and_b32_e32 v37, 0xffff0000, v78
	v_lshlrev_b32_e32 v38, 16, v79
	v_and_b32_e32 v39, 0xffff0000, v79
	v_pk_add_f32 v[30:31], v[30:31], v[34:35]
	v_pk_add_f32 v[28:29], v[28:29], v[32:33]
	v_pk_add_f32 v[32:33], v[26:27], v[38:39]
	v_pk_add_f32 v[26:27], v[24:25], v[36:37]
	v_mul_f32_e32 v24, v29, v29
	v_mul_f32_e32 v25, v31, v31
	v_fmac_f32_e32 v24, v28, v28
	v_fmac_f32_e32 v25, v30, v30
	v_add_f32_e32 v24, v24, v25
	v_mul_f32_e32 v25, v27, v27
	v_mul_f32_e32 v34, v33, v33
	v_fmac_f32_e32 v25, v26, v26
	v_fmac_f32_e32 v34, v32, v32
	v_add_f32_e32 v25, v25, v34
	v_add_f32_e32 v34, v24, v25
	v_cvt_pk_bf16_f32 v24, v28, v29
	v_lshl_add_u64 v[28:29], s[22:23], 0, v[94:95]
	v_cvt_pk_bf16_f32 v25, v30, v31
	v_cvt_pk_bf16_f32 v26, v26, v27
	v_cvt_pk_bf16_f32 v27, v32, v33
	v_lshl_add_u64 v[28:29], v[168:169], 1, v[28:29]
	global_store_dwordx4 v[28:29], v[24:27], off
	s_waitcnt vmcnt(7)
	v_lshlrev_b32_e32 v30, 16, v74
	v_and_b32_e32 v31, 0xffff0000, v74
	v_lshlrev_b32_e32 v24, 16, v72
	v_and_b32_e32 v25, 0xffff0000, v72
	v_lshlrev_b32_e32 v26, 16, v73
	v_and_b32_e32 v27, 0xffff0000, v73
	v_lshlrev_b32_e32 v32, 16, v75
	v_and_b32_e32 v33, 0xffff0000, v75
	v_pk_add_f32 v[22:23], v[22:23], v[26:27]
	v_pk_add_f32 v[20:21], v[20:21], v[24:25]
	v_pk_add_f32 v[24:25], v[18:19], v[32:33]
	v_pk_add_f32 v[18:19], v[16:17], v[30:31]
	v_mul_f32_e32 v16, v21, v21
	v_mul_f32_e32 v17, v23, v23
	v_fmac_f32_e32 v16, v20, v20
	v_fmac_f32_e32 v17, v22, v22
	v_add_f32_e32 v16, v16, v17
	v_mul_f32_e32 v17, v19, v19
	v_mul_f32_e32 v26, v25, v25
	v_fmac_f32_e32 v17, v18, v18
	v_fmac_f32_e32 v26, v24, v24
	v_add_f32_e32 v17, v17, v26
	v_add_f32_e32 v16, v16, v17
	v_add_f32_e32 v26, v34, v16
	v_cvt_pk_bf16_f32 v16, v20, v21
	v_cvt_pk_bf16_f32 v17, v22, v23
	v_cvt_pk_bf16_f32 v18, v18, v19
	v_cvt_pk_bf16_f32 v19, v24, v25
	global_store_dwordx4 v[28:29], v[16:19], off offset:256
	s_nop 1
	v_mov_b32_e32 v16, v201
	v_mov_b32_e32 v17, v201
	v_lshlrev_b32_e32 v16, 2, v16
	v_xor_b32_e32 v16, 64, v16
	v_mov_b32_e32 v16, v26
	s_nop 1
	v_permlane16_swap_b32_e32 v16, v26
	s_waitcnt lgkmcnt(0)
	v_add_f32_e32 v16, v26, v16
	v_lshlrev_b32_e32 v17, 2, v17
	v_xor_b32_e32 v17, 0x80, v17
	v_mov_b32_e32 v17, v16
	s_nop 1
	v_permlane32_swap_b32_e32 v17, v16
	s_and_saveexec_b64 s[40:41], s[10:11]
	s_cbranch_execz .LBB0_619
	s_waitcnt lgkmcnt(0)
	v_add_f32_e32 v18, v16, v17
	v_lshlrev_b64 v[16:17], 6, v[92:93]
	v_lshl_add_u64 v[16:17], s[24:25], 0, v[16:17]
	v_lshl_add_u64 v[16:17], s[38:39], 2, v[16:17]
	s_lshl_b32 s16, s50, 2
	v_lshl_add_u64 v[16:17], v[16:17], 0, s[16:17]
	global_store_dword v[16:17], v18, off
.LBB0_619:
	s_or_b64 exec, exec, s[40:41]
	s_waitcnt vmcnt(7)
	v_lshlrev_b32_e32 v16, 16, v68
	s_waitcnt lgkmcnt(0)
	v_and_b32_e32 v17, 0xffff0000, v68
	v_lshlrev_b32_e32 v18, 16, v69
	v_and_b32_e32 v19, 0xffff0000, v69
	v_lshlrev_b32_e32 v20, 16, v70
	v_and_b32_e32 v21, 0xffff0000, v70
	v_lshlrev_b32_e32 v22, 16, v71
	v_and_b32_e32 v23, 0xffff0000, v71
	v_pk_add_f32 v[14:15], v[14:15], v[18:19]
	v_pk_add_f32 v[12:13], v[12:13], v[16:17]
	v_pk_add_f32 v[16:17], v[10:11], v[22:23]
	v_pk_add_f32 v[10:11], v[8:9], v[20:21]
	v_mul_f32_e32 v8, v13, v13
	v_mul_f32_e32 v9, v15, v15
	v_fmac_f32_e32 v8, v12, v12
	v_fmac_f32_e32 v9, v14, v14
	v_add_f32_e32 v8, v8, v9
	v_mul_f32_e32 v9, v11, v11
	v_mul_f32_e32 v18, v17, v17
	v_fmac_f32_e32 v9, v10, v10
	v_fmac_f32_e32 v18, v16, v16
	v_add_f32_e32 v9, v9, v18
	v_add_f32_e32 v18, v8, v9
	v_cvt_pk_bf16_f32 v8, v12, v13
	v_lshl_add_u64 v[12:13], s[22:23], 0, v[90:91]
	v_cvt_pk_bf16_f32 v9, v14, v15
	v_cvt_pk_bf16_f32 v10, v10, v11
	v_cvt_pk_bf16_f32 v11, v16, v17
	v_lshl_add_u64 v[12:13], v[168:169], 1, v[12:13]
	global_store_dwordx4 v[12:13], v[8:11], off
	s_waitcnt vmcnt(7)
	v_lshlrev_b32_e32 v14, 16, v66
	v_and_b32_e32 v15, 0xffff0000, v66
	v_lshlrev_b32_e32 v8, 16, v64
	v_and_b32_e32 v9, 0xffff0000, v64
	v_lshlrev_b32_e32 v10, 16, v65
	v_and_b32_e32 v11, 0xffff0000, v65
	v_lshlrev_b32_e32 v16, 16, v67
	v_and_b32_e32 v17, 0xffff0000, v67
	v_pk_add_f32 v[6:7], v[6:7], v[10:11]
	v_pk_add_f32 v[4:5], v[4:5], v[8:9]
	v_pk_add_f32 v[8:9], v[2:3], v[16:17]
	v_pk_add_f32 v[2:3], v[0:1], v[14:15]
	v_mul_f32_e32 v0, v5, v5
	v_mul_f32_e32 v1, v7, v7
	v_fmac_f32_e32 v0, v4, v4
	v_fmac_f32_e32 v1, v6, v6
	v_add_f32_e32 v0, v0, v1
	v_mul_f32_e32 v1, v3, v3
	v_mul_f32_e32 v10, v9, v9
	v_fmac_f32_e32 v1, v2, v2
	v_fmac_f32_e32 v10, v8, v8
	v_add_f32_e32 v1, v1, v10
	v_add_f32_e32 v0, v0, v1
	v_add_f32_e32 v10, v18, v0
	v_cvt_pk_bf16_f32 v0, v4, v5
	v_cvt_pk_bf16_f32 v1, v6, v7
	v_cvt_pk_bf16_f32 v2, v2, v3
	v_cvt_pk_bf16_f32 v3, v8, v9
	global_store_dwordx4 v[12:13], v[0:3], off offset:256
	s_nop 1
	v_mov_b32_e32 v0, v201
	v_mov_b32_e32 v1, v201
	v_lshlrev_b32_e32 v0, 2, v0
	v_xor_b32_e32 v0, 64, v0
	v_mov_b32_e32 v0, v10
	s_nop 1
	v_permlane16_swap_b32_e32 v0, v10
	s_waitcnt lgkmcnt(0)
	v_add_f32_e32 v0, v10, v0
	v_lshlrev_b32_e32 v1, 2, v1
	v_xor_b32_e32 v1, 0x80, v1
	v_mov_b32_e32 v1, v0
	s_nop 1
	v_permlane32_swap_b32_e32 v1, v0
	s_and_saveexec_b64 s[40:41], s[10:11]
	s_cbranch_execz .LBB0_621
	s_waitcnt lgkmcnt(0)
	v_add_f32_e32 v2, v0, v1
	v_lshlrev_b64 v[0:1], 6, v[88:89]
	v_lshl_add_u64 v[0:1], s[24:25], 0, v[0:1]
	v_lshl_add_u64 v[0:1], s[38:39], 2, v[0:1]
	s_lshl_b32 s16, s50, 2
	v_lshl_add_u64 v[0:1], v[0:1], 0, s[16:17]
	global_store_dword v[0:1], v2, off

; __device__ __forceinline__ float row_part(const float* ss, int row, int fq) { const f32x4 a = ((const f32x4*)(ss + (size_t)row * 16))[fq]; return (a[0] + a[1]) + (a[2] + a[3]); }
; __device__ __forceinline__ float row_finish(float t) { t += shx(t, 16); t += shx(t, 32); return __builtin_amdgcn_rsqf(t * (1.0f / 1024.0f) + RMS_EPS); }
;     __device__ __forceinline__ void operator()(const f32x4 (&acc)[2][2][4][2], const Unit& u, int wr, int wc, int fr, int fq) const {
;         const int g = u.pn * 4 + wc;
;         int mode = 0; const float* w = mqw; float sc = 1.f, nsc = 1.f;
;         if (g >= 36) { mode = 2; w = mqw; nsc = qscale; }
;         else if (diff) { if (g < 12) { mode = 2; w = qw; nsc = qscale; } else if (g < 24) { mode = 2; w = kw; } }
;         else { if (g >= 6 && g < 12) sc = 0.125f; else if (g >= 24) mode = 1; }
;         f32x4 wv[2][2];
; #pragma unroll
;         for (int bj = 0; bj < 2; ++bj)
; #pragma unroll
;             for (int n = 0; n < 2; ++n) wv[bj][n] = *(const f32x4*)(w + 32 * bj + 8 * fq + 4 * n) * nsc;
;         const int lcol = u.pn * 256 + 64 * wc + 8 * fq;
;         float rs[2][4];
; #pragma unroll
;         for (int ai = 0; ai < 2; ++ai)
; #pragma unroll
;             for (int m = 0; m < 4; ++m) rs[ai][m] = row_part(ss, u.pm * BM + ai * HALF + wr * 64 + m * 16 + fr, fq);
; #pragma unroll
;         for (int ai = 0; ai < 2; ++ai)
; #pragma unroll
;             for (int m = 0; m < 4; ++m) rs[ai][m] = row_finish(rs[ai][m]);
.LBB0_715:
	s_lshl_b32 s12, s44, 2
	s_or_b32 s13, s12, s53
	s_cmp_lt_u32 s12, 24
	s_cselect_b32 s14, s19, s55
	s_cselect_b32 s15, s18, s54
	s_cmp_lt_i32 s13, 12
	s_cselect_b32 s15, s16, s15
	s_cselect_b32 s14, s17, s14
	s_sub_i32 s37, s12, 36
	s_cmp_lt_u32 s37, 0xffffffe8
	s_cselect_b64 vcc, -1, 0
	s_cmp_gt_i32 s13, 35
	s_cselect_b32 s13, s55, s14
	s_cselect_b32 s12, s54, s15
	s_cmp_lt_u32 s37, -12
	s_cselect_b64 s[48:49], -1, 0
	s_lshl_b32 s35, s46, 8
	v_add_u32_e32 v170, s35, v174
	v_ashrrev_i32_e32 v171, 31, v170
	v_or_b32_e32 v156, 16, v170
	v_lshlrev_b64 v[146:147], 6, v[170:171]
	v_ashrrev_i32_e32 v157, 31, v156
	global_load_dwordx4 v[148:151], v183, s[12:13] offset:16
	global_load_dwordx4 v[152:155], v183, s[12:13]
	global_load_dwordx4 v[186:189], v183, s[12:13] offset:144
	global_load_dwordx4 v[190:193], v183, s[12:13] offset:128
	v_lshl_add_u64 v[146:147], v[136:137], 0, v[146:147]
	v_lshlrev_b64 v[156:157], 6, v[156:157]
	v_lshl_add_u64 v[156:157], v[136:137], 0, v[156:157]
	ds_read_b128 v[194:197], v239
	ds_read_b128 v[202:205], v239 offset:1024
	v_or_b32_e32 v146, 32, v170
	v_ashrrev_i32_e32 v147, 31, v146
	v_or_b32_e32 v156, 48, v170
	v_lshlrev_b64 v[146:147], 6, v[146:147]
	v_ashrrev_i32_e32 v157, 31, v156
	v_lshl_add_u64 v[146:147], v[136:137], 0, v[146:147]
	v_lshlrev_b64 v[156:157], 6, v[156:157]
	v_lshl_add_u64 v[156:157], v[136:137], 0, v[156:157]
	ds_read_b128 v[206:209], v239 offset:2048
	ds_read_b128 v[210:213], v239 offset:3072
	v_add_u32_e32 v168, 0x80, v170
	v_ashrrev_i32_e32 v169, 31, v168
	v_add_u32_e32 v166, 0x90, v170
	v_lshlrev_b64 v[146:147], 6, v[168:169]
	v_ashrrev_i32_e32 v167, 31, v166
	v_add_u32_e32 v164, 0xa0, v170
	v_lshl_add_u64 v[146:147], v[136:137], 0, v[146:147]
	v_lshlrev_b64 v[156:157], 6, v[166:167]
	v_ashrrev_i32_e32 v165, 31, v164
	v_lshl_add_u64 v[156:157], v[136:137], 0, v[156:157]
	ds_read_b128 v[214:217], v239 offset:8192
	ds_read_b128 v[218:221], v239 offset:9216
	v_lshlrev_b64 v[146:147], 6, v[164:165]
	v_lshl_add_u64 v[146:147], v[136:137], 0, v[146:147]
	ds_read_b128 v[222:225], v239 offset:10240
	v_add_u32_e32 v146, 0xb0, v170
	v_ashrrev_i32_e32 v147, 31, v146
	v_lshlrev_b64 v[156:157], 6, v[146:147]
	v_lshl_add_u64 v[156:157], v[136:137], 0, v[156:157]
	ds_read_b128 v[226:229], v239 offset:11264
	v_mov_b32_e32 v147, v201
	v_cndmask_b32_e32 v172, 1.0, v185, vcc
	s_cmp_gt_u32 s37, -13
	v_lshlrev_b32_e32 v147, 2, v147
	v_xor_b32_e32 v147, 64, v147
	s_waitcnt vmcnt(0) lgkmcnt(0)
	v_pk_mul_f32 v[156:157], v[172:173], v[150:151] op_sel_hi:[0,1]
	v_pk_mul_f32 v[160:161], v[172:173], v[154:155] op_sel_hi:[0,1]
	v_pk_mul_f32 v[162:163], v[172:173], v[152:153] op_sel_hi:[0,1]
	v_pk_mul_f32 v[158:159], v[172:173], v[148:149] op_sel_hi:[0,1]
	v_pk_mul_f32 v[152:153], v[172:173], v[192:193] op_sel_hi:[0,1]
	v_pk_mul_f32 v[154:155], v[172:173], v[190:191] op_sel_hi:[0,1]
	v_pk_mul_f32 v[148:149], v[172:173], v[188:189] op_sel_hi:[0,1]
	v_pk_mul_f32 v[150:151], v[172:173], v[186:187] op_sel_hi:[0,1]
	v_mov_b32_e32 v172, v195
	v_mov_b32_e32 v173, v196
	v_mov_b32_e32 v195, v197
	v_pk_add_f32 v[172:173], v[172:173], v[194:195]
	v_add_f32_e32 v165, v202, v203
	v_add_f32_e32 v172, v172, v173
	v_mov_b32_e32 v147, v172
	s_nop 1
	v_permlane16_swap_b32_e32 v147, v172
	v_add_f32_e32 v167, v204, v205
	v_add_f32_e32 v169, v206, v207
	v_add_f32_e32 v171, v208, v209
	v_add_f32_e32 v186, v210, v211
	s_waitcnt lgkmcnt(0)
	v_add_f32_e32 v147, v172, v147
	v_mov_b32_e32 v172, v201
	v_add_f32_e32 v187, v212, v213
	v_lshlrev_b32_e32 v172, 2, v172
	v_xor_b32_e32 v172, 0x80, v172
	v_mov_b32_e32 v172, v147
	s_nop 1
	v_permlane32_swap_b32_e32 v172, v147
	v_add_f32_e32 v165, v165, v167
	v_add_f32_e32 v167, v169, v171
	v_add_f32_e32 v169, v186, v187
	v_mov_b32_e32 v186, v201
	s_waitcnt lgkmcnt(0)
	v_add_f32_e32 v147, v147, v172
	v_lshlrev_b32_e32 v186, 2, v186
	v_xor_b32_e32 v186, 64, v186
	v_mov_b32_e32 v186, v165
	s_nop 1
	v_permlane16_swap_b32_e32 v186, v165
	v_fmamk_f32 v147, v147, 0x3a800000, v184
	v_rsq_f32_e32 v196, v147
	v_mov_b32_e32 v147, v201
	v_add_f32_e32 v192, v222, v223
	v_add_f32_e32 v193, v224, v225
	v_lshlrev_b32_e32 v147, 2, v147
	v_add_f32_e32 v194, v226, v227
	v_add_f32_e32 v195, v228, v229
	v_add_f32_e32 v197, v192, v193
	s_waitcnt lgkmcnt(0)
	v_add_f32_e32 v193, v165, v186
	v_xor_b32_e32 v147, 0x80, v147
	v_add_f32_e32 v195, v194, v195
	v_mov_b32_e32 v194, v193
	s_nop 1
	v_permlane32_swap_b32_e32 v194, v193
	v_mov_b32_e32 v147, v201
	v_mov_b32_e32 v165, v201
	v_lshlrev_b32_e32 v147, 2, v147
	v_xor_b32_e32 v147, 64, v147
	v_mov_b32_e32 v147, v167
	s_nop 1
	v_permlane16_swap_b32_e32 v147, v167
	v_mov_b32_e32 v172, v201
	v_add_f32_e32 v190, v218, v219
	v_lshlrev_b32_e32 v172, 2, v172
	v_add_f32_e32 v191, v220, v221
	v_xor_b32_e32 v172, 64, v172
	v_add_f32_e32 v173, v190, v191
	v_mov_b32_e32 v172, v169
	s_nop 1
	v_permlane16_swap_b32_e32 v172, v169
	s_waitcnt lgkmcnt(0)
	v_add_f32_e32 v191, v167, v147
	v_lshlrev_b32_e32 v147, 2, v165
	v_xor_b32_e32 v147, 0x80, v147
	v_mov_b32_e32 v192, v191
	s_nop 1
	v_permlane32_swap_b32_e32 v192, v191
	v_mov_b32_e32 v147, v201
	v_add_f32_e32 v188, v214, v215
	v_add_f32_e32 v189, v216, v217
	v_lshlrev_b32_e32 v147, 2, v147
	v_add_f32_e32 v171, v188, v189
	s_waitcnt lgkmcnt(0)
	v_add_f32_e32 v189, v169, v172
	v_xor_b32_e32 v147, 0x80, v147
	v_mov_b32_e32 v190, v189
	s_nop 1
	v_permlane32_swap_b32_e32 v190, v189
	v_mov_b32_e32 v147, v201
	v_mov_b32_e32 v165, v201
	v_lshlrev_b32_e32 v147, 2, v147
	v_xor_b32_e32 v147, 64, v147
	v_mov_b32_e32 v147, v171
	s_nop 1
	v_permlane16_swap_b32_e32 v147, v171
	v_mov_b32_e32 v167, v201
	v_pk_mul_f32 v[126:127], v[126:127], v[196:197] op_sel_hi:[1,0]
	v_lshlrev_b32_e32 v167, 2, v167
	v_xor_b32_e32 v167, 64, v167
	v_mov_b32_e32 v167, v173
	s_nop 1
	v_permlane16_swap_b32_e32 v167, v173
	s_waitcnt lgkmcnt(0)
; __device__ __forceinline__ float row_finish(float t) { t += shx(t, 16); t += shx(t, 32); return __builtin_amdgcn_rsqf(t * (1.0f / 1024.0f) + RMS_EPS); }
; __device__ __forceinline__ f32x4 silu4(f32x4 v) { return (f32x4){silu_f(v[0]), silu_f(v[1]), silu_f(v[2]), silu_f(v[3])}; }
; __device__ __forceinline__ float sq4(f32x4 v) { return (v[0] * v[0] + v[1] * v[1]) + (v[2] * v[2] + v[3] * v[3]); }
; __device__ __forceinline__ u32x4 pack8(f32x4 a, f32x4 b) { u32x4 w; w.x = cvt_pk_bf16(a[0], a[1]); w.y = cvt_pk_bf16(a[2], a[3]); w.z = cvt_pk_bf16(b[0], b[1]); w.w = cvt_pk_bf16(b[2], b[3]); return w; }
;     __device__ __forceinline__ void operator()(const f32x4 (&acc)[2][2][4][2], const Unit& u, int wr, int wc, int fr, int fq) const {
;     ...
;             for (int m = 0; m < 4; ++m) rs[ai][m] = row_finish(rs[ai][m]);
; #pragma unroll
;         for (int ai = 0; ai < 2; ++ai)
; #pragma unroll
;             for (int m = 0; m < 4; ++m) {
;                 const int row = u.pm * BM + ai * HALF + wr * 64 + m * 16 + fr;
;                 const float rstd = rs[ai][m];
;                 f32x4 v[2][2];
; #pragma unroll
;                 for (int bj = 0; bj < 2; ++bj)
; #pragma unroll
;                     for (int n = 0; n < 2; ++n) v[bj][n] = acc[ai][bj][m][n] * rstd;
;                 if (mode == 2) {
;                     float q = (sq4(v[0][0]) + sq4(v[0][1])) + (sq4(v[1][0]) + sq4(v[1][1]));
;                     q += shx(q, 16); q += shx(q, 32);
;                     const float r2 = __builtin_amdgcn_rsqf(q * (1.0f / 64.0f) + RMS_EPS);
; #pragma unroll
;                     for (int bj = 0; bj < 2; ++bj)
; #pragma unroll
;                         for (int n = 0; n < 2; ++n) v[bj][n] = v[bj][n] * r2 * wv[bj][n];
;                 } else if (mode == 1) {
; #pragma unroll
;                     for (int bj = 0; bj < 2; ++bj)
; #pragma unroll
;                         for (int n = 0; n < 2; ++n) v[bj][n] = silu4(v[bj][n]);
;                 } else {
; #pragma unroll
;                     for (int bj = 0; bj < 2; ++bj)
; #pragma unroll
;                         for (int n = 0; n < 2; ++n) v[bj][n] = v[bj][n] * sc;
;                 }
;                 bf16_t* rowp = U + (size_t)row * 2560 + lcol;
; #pragma unroll
;                 for (int bj = 0; bj < 2; ++bj) *(u32x4*)(rowp + 32 * bj) = pack8(v[bj][0], v[bj][1]);
	v_add_f32_e32 v187, v171, v147
	v_lshlrev_b32_e32 v147, 2, v165
	v_xor_b32_e32 v147, 0x80, v147
	v_mov_b32_e32 v188, v187
	s_nop 1
	v_permlane32_swap_b32_e32 v188, v187
	v_mov_b32_e32 v147, v201
	s_waitcnt lgkmcnt(0)
	v_add_f32_e32 v171, v173, v167
	v_lshlrev_b32_e32 v147, 2, v147
	v_xor_b32_e32 v147, 0x80, v147
	v_mov_b32_e32 v186, v171
	s_nop 1
	v_permlane32_swap_b32_e32 v186, v171
	v_mov_b32_e32 v147, v201
	v_mov_b32_e32 v165, v201
	v_lshlrev_b32_e32 v147, 2, v147
	v_xor_b32_e32 v147, 64, v147
	v_mov_b32_e32 v167, v201
	v_mov_b32_e32 v147, v197
	s_nop 1
	v_permlane16_swap_b32_e32 v147, v197
	v_pk_mul_f32 v[124:125], v[124:125], v[196:197] op_sel_hi:[1,0]
	v_lshlrev_b32_e32 v167, 2, v167
	v_xor_b32_e32 v167, 64, v167
	v_mov_b32_e32 v172, v195
	s_nop 1
	v_permlane16_swap_b32_e32 v172, v195
	s_waitcnt lgkmcnt(0)
	v_add_f32_e32 v167, v197, v147
	v_lshlrev_b32_e32 v147, 2, v165
	v_mov_b32_e32 v165, v201
	v_xor_b32_e32 v147, 0x80, v147
	v_lshlrev_b32_e32 v165, 2, v165
	v_mov_b32_e32 v169, v167
	s_nop 1
	v_permlane32_swap_b32_e32 v169, v167
	s_waitcnt lgkmcnt(0)
	v_add_f32_e32 v147, v195, v172
	v_xor_b32_e32 v165, 0x80, v165
	v_mov_b32_e32 v165, v147
	s_nop 1
	v_permlane32_swap_b32_e32 v165, v147
	v_pk_mul_f32 v[122:123], v[122:123], v[196:197] op_sel_hi:[1,0]
	v_pk_mul_f32 v[172:173], v[120:121], v[196:197] op_sel_hi:[1,0]
	v_pk_mul_f32 v[118:119], v[118:119], v[196:197] op_sel_hi:[1,0]
	v_pk_mul_f32 v[116:117], v[116:117], v[196:197] op_sel_hi:[1,0]
	v_pk_mul_f32 v[114:115], v[114:115], v[196:197] op_sel_hi:[1,0]
	v_pk_mul_f32 v[120:121], v[112:113], v[196:197] op_sel_hi:[1,0]
	s_cbranch_scc1 .LBB0_717
	v_mov_b32_e32 v196, v125
	v_mov_b32_e32 v197, v117
	v_mov_b32_e32 v112, v124
	v_mov_b32_e32 v113, v116
	v_pk_mul_f32 v[196:197], v[196:197], v[196:197]
	v_mov_b32_e32 v198, v127
	v_mov_b32_e32 v199, v119
	v_pk_fma_f32 v[112:113], v[112:113], v[112:113], v[196:197]
	v_mov_b32_e32 v196, v126
	v_mov_b32_e32 v197, v118
	v_pk_mul_f32 v[198:199], v[198:199], v[198:199]
	v_mov_b32_e32 v202, v123
	v_pk_fma_f32 v[196:197], v[196:197], v[196:197], v[198:199]
	v_mov_b32_e32 v198, v173
	v_mov_b32_e32 v199, v121
	v_pk_add_f32 v[112:113], v[112:113], v[196:197]
	v_mov_b32_e32 v196, v172
	v_mov_b32_e32 v197, v120
	v_pk_mul_f32 v[198:199], v[198:199], v[198:199]
	v_mov_b32_e32 v203, v115
	v_pk_fma_f32 v[196:197], v[196:197], v[196:197], v[198:199]
	v_mov_b32_e32 v198, v122
	v_mov_b32_e32 v199, v114
	v_pk_mul_f32 v[202:203], v[202:203], v[202:203]
	s_nop 0
	v_pk_fma_f32 v[198:199], v[198:199], v[198:199], v[202:203]
	s_nop 0
	v_pk_add_f32 v[196:197], v[196:197], v[198:199]
	s_nop 0
	v_pk_add_f32 v[112:113], v[112:113], v[196:197]
	s_nop 0
	v_add_f32_e32 v112, v112, v113
	v_mov_b32_e32 v113, v201
	s_nop 0
	v_lshlrev_b32_e32 v113, 2, v113
	v_xor_b32_e32 v113, 64, v113
	v_mov_b32_e32 v113, v112
	s_nop 1
	v_permlane16_swap_b32_e32 v113, v112
	s_waitcnt lgkmcnt(0)
	v_add_f32_e32 v112, v112, v113
	v_mov_b32_e32 v113, v201
	s_nop 0
	v_lshlrev_b32_e32 v113, 2, v113
	v_xor_b32_e32 v113, 0x80, v113
	v_mov_b32_e32 v113, v112
	s_nop 1
	v_permlane32_swap_b32_e32 v113, v112
	s_waitcnt lgkmcnt(0)
	v_add_f32_e32 v112, v112, v113
	v_fmamk_f32 v112, v112, 0x3c800000, v184
	v_rsq_f32_e32 v112, v112
	s_nop 0
	v_pk_mul_f32 v[124:125], v[124:125], v[112:113] op_sel_hi:[1,0]
	v_pk_mul_f32 v[126:127], v[126:127], v[112:113] op_sel_hi:[1,0]
	v_pk_mul_f32 v[172:173], v[172:173], v[112:113] op_sel_hi:[1,0]
	v_pk_mul_f32 v[122:123], v[122:123], v[112:113] op_sel_hi:[1,0]
	v_pk_mul_f32 v[116:117], v[116:117], v[112:113] op_sel_hi:[1,0]
	v_pk_mul_f32 v[118:119], v[118:119], v[112:113] op_sel_hi:[1,0]
	v_pk_mul_f32 v[120:121], v[120:121], v[112:113] op_sel_hi:[1,0]
	v_pk_mul_f32 v[112:113], v[114:115], v[112:113] op_sel_hi:[1,0]
	v_pk_mul_f32 v[126:127], v[160:161], v[126:127]
	v_pk_mul_f32 v[124:125], v[162:163], v[124:125]
	v_pk_mul_f32 v[122:123], v[156:157], v[122:123]
	v_pk_mul_f32 v[172:173], v[158:159], v[172:173]
	v_pk_mul_f32 v[118:119], v[152:153], v[118:119]
	v_pk_mul_f32 v[116:117], v[154:155], v[116:117]
	v_pk_mul_f32 v[114:115], v[148:149], v[112:113]
	v_pk_mul_f32 v[120:121], v[150:151], v[120:121]
.LBB0_717:
	v_add_f32_e32 v112, v193, v194
	v_fmamk_f32 v112, v112, 0x3a800000, v184
	v_rsq_f32_e32 v194, v112
	v_lshl_or_b32 v112, s44, 8, v179
	v_mov_b64_e32 v[196:197], s[22:23]
	v_ashrrev_i32_e32 v113, 31, v112
	v_mad_i64_i32 v[196:197], s[12:13], v170, s64, v[196:197]
	v_lshl_add_u64 v[196:197], v[112:113], 1, v[196:197]
	v_cvt_pk_bf16_f32 v124, v124, v125
	v_cvt_pk_bf16_f32 v125, v126, v127
	v_cvt_pk_bf16_f32 v126, v172, v173
	v_cvt_pk_bf16_f32 v127, v122, v123
	global_store_dwordx4 v[196:197], v[124:127], off
	v_cvt_pk_bf16_f32 v116, v116, v117
	v_cvt_pk_bf16_f32 v117, v118, v119
	v_cvt_pk_bf16_f32 v118, v120, v121
	v_cvt_pk_bf16_f32 v119, v114, v115
	v_cndmask_b32_e64 v114, 0, 1, s[48:49]
	v_pk_mul_f32 v[110:111], v[110:111], v[194:195] op_sel_hi:[1,0]
	v_pk_mul_f32 v[108:109], v[108:109], v[194:195] op_sel_hi:[1,0]
	v_pk_mul_f32 v[106:107], v[106:107], v[194:195] op_sel_hi:[1,0]
	v_pk_mul_f32 v[104:105], v[104:105], v[194:195] op_sel_hi:[1,0]
	v_pk_mul_f32 v[102:103], v[102:103], v[194:195] op_sel_hi:[1,0]
	v_pk_mul_f32 v[100:101], v[100:101], v[194:195] op_sel_hi:[1,0]
	v_pk_mul_f32 v[98:99], v[98:99], v[194:195] op_sel_hi:[1,0]
	v_cmp_ne_u32_e64 s[12:13], 1, v114
	s_andn2_b64 vcc, exec, s[48:49]
	v_pk_mul_f32 v[96:97], v[96:97], v[194:195] op_sel_hi:[1,0]
	global_store_dwordx4 v[196:197], v[116:119], off offset:64
	s_cbranch_vccnz .LBB0_719
; __device__ __forceinline__ f32x4 silu4(f32x4 v) { return (f32x4){silu_f(v[0]), silu_f(v[1]), silu_f(v[2]), silu_f(v[3])}; }
; __device__ __forceinline__ float sq4(f32x4 v) { return (v[0] * v[0] + v[1] * v[1]) + (v[2] * v[2] + v[3] * v[3]); }
; __device__ __forceinline__ u32x4 pack8(f32x4 a, f32x4 b) { u32x4 w; w.x = cvt_pk_bf16(a[0], a[1]); w.y = cvt_pk_bf16(a[2], a[3]); w.z = cvt_pk_bf16(b[0], b[1]); w.w = cvt_pk_bf16(b[2], b[3]); return w; }
; __device__ __forceinline__ float row_finish(float t) { t += shx(t, 16); t += shx(t, 32); return __builtin_amdgcn_rsqf(t * (1.0f / 1024.0f) + RMS_EPS); }
;     __device__ __forceinline__ void operator()(const f32x4 (&acc)[2][2][4][2], const Unit& u, int wr, int wc, int fr, int fq) const {
;     ...
;                     for (int n = 0; n < 2; ++n) v[bj][n] = acc[ai][bj][m][n] * rstd;
;                 if (mode == 2) {
;                     float q = (sq4(v[0][0]) + sq4(v[0][1])) + (sq4(v[1][0]) + sq4(v[1][1]));
;                     q += shx(q, 16); q += shx(q, 32);
;                     const float r2 = __builtin_amdgcn_rsqf(q * (1.0f / 64.0f) + RMS_EPS);
; #pragma unroll
;                     for (int bj = 0; bj < 2; ++bj)
; #pragma unroll
;                         for (int n = 0; n < 2; ++n) v[bj][n] = v[bj][n] * r2 * wv[bj][n];
;                 } else if (mode == 1) {
; #pragma unroll
;                     for (int bj = 0; bj < 2; ++bj)
; #pragma unroll
;                         for (int n = 0; n < 2; ++n) v[bj][n] = silu4(v[bj][n]);
;                 } else {
; #pragma unroll
;                     for (int bj = 0; bj < 2; ++bj)
; #pragma unroll
;                         for (int n = 0; n < 2; ++n) v[bj][n] = v[bj][n] * sc;
;                 }
;                 bf16_t* rowp = U + (size_t)row * 2560 + lcol;
; #pragma unroll
;                 for (int bj = 0; bj < 2; ++bj) *(u32x4*)(rowp + 32 * bj) = pack8(v[bj][0], v[bj][1]);
	s_nop 0
	v_mov_b32_e32 v116, v109
	v_mov_b32_e32 v117, v101
	v_mov_b32_e32 v114, v108
	v_mov_b32_e32 v115, v100
	v_pk_mul_f32 v[116:117], v[116:117], v[116:117]
	v_mov_b32_e32 v118, v111
	v_mov_b32_e32 v119, v103
	v_pk_fma_f32 v[114:115], v[114:115], v[114:115], v[116:117]
	v_mov_b32_e32 v116, v110
	v_mov_b32_e32 v117, v102
	v_pk_mul_f32 v[118:119], v[118:119], v[118:119]
	v_mov_b32_e32 v120, v107
	v_pk_fma_f32 v[116:117], v[116:117], v[116:117], v[118:119]
	v_mov_b32_e32 v118, v105
	v_mov_b32_e32 v119, v97
	v_pk_add_f32 v[114:115], v[114:115], v[116:117]
	v_mov_b32_e32 v116, v104
	v_mov_b32_e32 v117, v96
	v_pk_mul_f32 v[118:119], v[118:119], v[118:119]
	v_mov_b32_e32 v121, v99
	v_pk_fma_f32 v[116:117], v[116:117], v[116:117], v[118:119]
	v_mov_b32_e32 v118, v106
	v_mov_b32_e32 v119, v98
	v_pk_mul_f32 v[120:121], v[120:121], v[120:121]
	s_nop 0
	v_pk_fma_f32 v[118:119], v[118:119], v[118:119], v[120:121]
	s_nop 0
	v_pk_add_f32 v[116:117], v[116:117], v[118:119]
	s_nop 0
	v_pk_add_f32 v[114:115], v[114:115], v[116:117]
	s_nop 0
	v_add_f32_e32 v114, v114, v115
	v_mov_b32_e32 v115, v201
	s_nop 0
	v_lshlrev_b32_e32 v115, 2, v115
	v_xor_b32_e32 v115, 64, v115
	v_mov_b32_e32 v115, v114
	s_nop 1
	v_permlane16_swap_b32_e32 v115, v114
	s_waitcnt lgkmcnt(0)
	v_add_f32_e32 v114, v114, v115
	v_mov_b32_e32 v115, v201
	s_nop 0
	v_lshlrev_b32_e32 v115, 2, v115
	v_xor_b32_e32 v115, 0x80, v115
	v_mov_b32_e32 v115, v114
	s_nop 1
	v_permlane32_swap_b32_e32 v115, v114
	s_waitcnt lgkmcnt(0)
	v_add_f32_e32 v114, v114, v115
	v_fmamk_f32 v114, v114, 0x3c800000, v184
	v_rsq_f32_e32 v114, v114
	s_nop 0
	v_pk_mul_f32 v[108:109], v[108:109], v[114:115] op_sel_hi:[1,0]
	v_pk_mul_f32 v[110:111], v[110:111], v[114:115] op_sel_hi:[1,0]
	v_pk_mul_f32 v[104:105], v[104:105], v[114:115] op_sel_hi:[1,0]
	v_pk_mul_f32 v[106:107], v[106:107], v[114:115] op_sel_hi:[1,0]
	v_pk_mul_f32 v[100:101], v[100:101], v[114:115] op_sel_hi:[1,0]
	v_pk_mul_f32 v[102:103], v[102:103], v[114:115] op_sel_hi:[1,0]
	v_pk_mul_f32 v[96:97], v[96:97], v[114:115] op_sel_hi:[1,0]
	v_pk_mul_f32 v[98:99], v[98:99], v[114:115] op_sel_hi:[1,0]
	v_pk_mul_f32 v[110:111], v[160:161], v[110:111]
	v_pk_mul_f32 v[108:109], v[162:163], v[108:109]
	v_pk_mul_f32 v[106:107], v[156:157], v[106:107]
	v_pk_mul_f32 v[104:105], v[158:159], v[104:105]
	v_pk_mul_f32 v[102:103], v[152:153], v[102:103]
	v_pk_mul_f32 v[100:101], v[154:155], v[100:101]
	v_pk_mul_f32 v[98:99], v[148:149], v[98:99]
	v_pk_mul_f32 v[96:97], v[150:151], v[96:97]
.LBB0_719:
	v_add_f32_e32 v114, v191, v192
	v_fmamk_f32 v114, v114, 0x3a800000, v184
	v_rsq_f32_e32 v114, v114
	v_add_u32_e32 v115, s35, v176
	v_mov_b64_e32 v[116:117], s[22:23]
	v_mad_i64_i32 v[116:117], s[48:49], v115, s64, v[116:117]
	v_lshl_add_u64 v[116:117], v[112:113], 1, v[116:117]
	v_pk_mul_f32 v[94:95], v[94:95], v[114:115] op_sel_hi:[1,0]
	v_pk_mul_f32 v[92:93], v[92:93], v[114:115] op_sel_hi:[1,0]
	v_pk_mul_f32 v[90:91], v[90:91], v[114:115] op_sel_hi:[1,0]
	v_pk_mul_f32 v[88:89], v[88:89], v[114:115] op_sel_hi:[1,0]
	v_pk_mul_f32 v[86:87], v[86:87], v[114:115] op_sel_hi:[1,0]
	v_pk_mul_f32 v[84:85], v[84:85], v[114:115] op_sel_hi:[1,0]
	v_pk_mul_f32 v[82:83], v[82:83], v[114:115] op_sel_hi:[1,0]
	s_and_b64 vcc, exec, s[12:13]
	v_pk_mul_f32 v[80:81], v[80:81], v[114:115] op_sel_hi:[1,0]
	v_cvt_pk_bf16_f32 v108, v108, v109
	v_cvt_pk_bf16_f32 v109, v110, v111
	v_cvt_pk_bf16_f32 v110, v104, v105
	v_cvt_pk_bf16_f32 v111, v106, v107
	global_store_dwordx4 v[116:117], v[108:111], off
	v_cvt_pk_bf16_f32 v100, v100, v101
	v_cvt_pk_bf16_f32 v101, v102, v103
	v_cvt_pk_bf16_f32 v102, v96, v97
	v_cvt_pk_bf16_f32 v103, v98, v99
	global_store_dwordx4 v[116:117], v[100:103], off offset:64
	s_cbranch_vccnz .LBB0_721
	v_mov_b32_e32 v98, v93
	v_mov_b32_e32 v99, v85
	v_mov_b32_e32 v96, v92
	v_mov_b32_e32 v97, v84
	v_pk_mul_f32 v[98:99], v[98:99], v[98:99]
	v_mov_b32_e32 v100, v95
	v_mov_b32_e32 v101, v87
	v_pk_fma_f32 v[96:97], v[96:97], v[96:97], v[98:99]
	v_mov_b32_e32 v98, v94
	v_mov_b32_e32 v99, v86
	v_pk_mul_f32 v[100:101], v[100:101], v[100:101]
	v_mov_b32_e32 v102, v91
	v_pk_fma_f32 v[98:99], v[98:99], v[98:99], v[100:101]
	v_mov_b32_e32 v100, v89
	v_mov_b32_e32 v101, v81
	v_pk_add_f32 v[96:97], v[96:97], v[98:99]
	v_mov_b32_e32 v98, v88
	v_mov_b32_e32 v99, v80
	v_pk_mul_f32 v[100:101], v[100:101], v[100:101]
	v_mov_b32_e32 v103, v83
	v_pk_fma_f32 v[98:99], v[98:99], v[98:99], v[100:101]
	v_mov_b32_e32 v100, v90
	v_mov_b32_e32 v101, v82
	v_pk_mul_f32 v[102:103], v[102:103], v[102:103]
	s_nop 0
	v_pk_fma_f32 v[100:101], v[100:101], v[100:101], v[102:103]
	s_nop 0
	v_pk_add_f32 v[98:99], v[98:99], v[100:101]
	s_nop 0
	v_pk_add_f32 v[96:97], v[96:97], v[98:99]
	s_nop 0
	v_add_f32_e32 v96, v96, v97
	v_mov_b32_e32 v97, v201
	s_nop 0
	v_lshlrev_b32_e32 v97, 2, v97
	v_xor_b32_e32 v97, 64, v97
	v_mov_b32_e32 v97, v96
	s_nop 1
	v_permlane16_swap_b32_e32 v97, v96
	s_waitcnt lgkmcnt(0)
	v_add_f32_e32 v96, v96, v97
	v_mov_b32_e32 v97, v201
	s_nop 0
	v_lshlrev_b32_e32 v97, 2, v97
	v_xor_b32_e32 v97, 0x80, v97
	v_mov_b32_e32 v97, v96
	s_nop 1
	v_permlane32_swap_b32_e32 v97, v96
	s_waitcnt lgkmcnt(0)
	v_add_f32_e32 v96, v96, v97
	v_fmamk_f32 v96, v96, 0x3c800000, v184
	v_rsq_f32_e32 v96, v96
	s_nop 0
	v_pk_mul_f32 v[92:93], v[92:93], v[96:97] op_sel_hi:[1,0]
	v_pk_mul_f32 v[94:95], v[94:95], v[96:97] op_sel_hi:[1,0]
	v_pk_mul_f32 v[88:89], v[88:89], v[96:97] op_sel_hi:[1,0]
	v_pk_mul_f32 v[90:91], v[90:91], v[96:97] op_sel_hi:[1,0]
	v_pk_mul_f32 v[84:85], v[84:85], v[96:97] op_sel_hi:[1,0]
	v_pk_mul_f32 v[86:87], v[86:87], v[96:97] op_sel_hi:[1,0]
	v_pk_mul_f32 v[80:81], v[80:81], v[96:97] op_sel_hi:[1,0]
	v_pk_mul_f32 v[82:83], v[82:83], v[96:97] op_sel_hi:[1,0]
	v_pk_mul_f32 v[94:95], v[160:161], v[94:95]
	v_pk_mul_f32 v[92:93], v[162:163], v[92:93]
	v_pk_mul_f32 v[90:91], v[156:157], v[90:91]
	v_pk_mul_f32 v[88:89], v[158:159], v[88:89]
	v_pk_mul_f32 v[86:87], v[152:153], v[86:87]
	v_pk_mul_f32 v[84:85], v[154:155], v[84:85]
	v_pk_mul_f32 v[82:83], v[148:149], v[82:83]
	v_pk_mul_f32 v[80:81], v[150:151], v[80:81]
; __device__ __forceinline__ f32x4 silu4(f32x4 v) { return (f32x4){silu_f(v[0]), silu_f(v[1]), silu_f(v[2]), silu_f(v[3])}; }
; __device__ __forceinline__ float sq4(f32x4 v) { return (v[0] * v[0] + v[1] * v[1]) + (v[2] * v[2] + v[3] * v[3]); }
; __device__ __forceinline__ u32x4 pack8(f32x4 a, f32x4 b) { u32x4 w; w.x = cvt_pk_bf16(a[0], a[1]); w.y = cvt_pk_bf16(a[2], a[3]); w.z = cvt_pk_bf16(b[0], b[1]); w.w = cvt_pk_bf16(b[2], b[3]); return w; }
; __device__ __forceinline__ float row_finish(float t) { t += shx(t, 16); t += shx(t, 32); return __builtin_amdgcn_rsqf(t * (1.0f / 1024.0f) + RMS_EPS); }
;     __device__ __forceinline__ void operator()(const f32x4 (&acc)[2][2][4][2], const Unit& u, int wr, int wc, int fr, int fq) const {
;     ...
;                     for (int n = 0; n < 2; ++n) v[bj][n] = acc[ai][bj][m][n] * rstd;
;                 if (mode == 2) {
;                     float q = (sq4(v[0][0]) + sq4(v[0][1])) + (sq4(v[1][0]) + sq4(v[1][1]));
;                     q += shx(q, 16); q += shx(q, 32);
;                     const float r2 = __builtin_amdgcn_rsqf(q * (1.0f / 64.0f) + RMS_EPS);
; #pragma unroll
;                     for (int bj = 0; bj < 2; ++bj)
; #pragma unroll
;                         for (int n = 0; n < 2; ++n) v[bj][n] = v[bj][n] * r2 * wv[bj][n];
;                 } else if (mode == 1) {
; #pragma unroll
;                     for (int bj = 0; bj < 2; ++bj)
; #pragma unroll
;                         for (int n = 0; n < 2; ++n) v[bj][n] = silu4(v[bj][n]);
;                 } else {
; #pragma unroll
;                     for (int bj = 0; bj < 2; ++bj)
; #pragma unroll
;                         for (int n = 0; n < 2; ++n) v[bj][n] = v[bj][n] * sc;
;                 }
;                 bf16_t* rowp = U + (size_t)row * 2560 + lcol;
; #pragma unroll
;                 for (int bj = 0; bj < 2; ++bj) *(u32x4*)(rowp + 32 * bj) = pack8(v[bj][0], v[bj][1]);
.LBB0_721:
	v_add_f32_e32 v96, v189, v190
	v_fmamk_f32 v96, v96, 0x3a800000, v184
	v_rsq_f32_e32 v96, v96
	v_add_u32_e32 v97, s35, v177
	v_mov_b64_e32 v[98:99], s[22:23]
	v_mad_i64_i32 v[98:99], s[48:49], v97, s64, v[98:99]
	v_lshl_add_u64 v[98:99], v[112:113], 1, v[98:99]
	v_pk_mul_f32 v[78:79], v[78:79], v[96:97] op_sel_hi:[1,0]
	v_pk_mul_f32 v[76:77], v[76:77], v[96:97] op_sel_hi:[1,0]
	v_pk_mul_f32 v[74:75], v[74:75], v[96:97] op_sel_hi:[1,0]
	v_pk_mul_f32 v[72:73], v[72:73], v[96:97] op_sel_hi:[1,0]
	v_pk_mul_f32 v[70:71], v[70:71], v[96:97] op_sel_hi:[1,0]
	v_pk_mul_f32 v[68:69], v[68:69], v[96:97] op_sel_hi:[1,0]
	v_pk_mul_f32 v[66:67], v[66:67], v[96:97] op_sel_hi:[1,0]
	s_and_b64 vcc, exec, s[12:13]
	v_pk_mul_f32 v[64:65], v[64:65], v[96:97] op_sel_hi:[1,0]
	v_cvt_pk_bf16_f32 v92, v92, v93
	v_cvt_pk_bf16_f32 v93, v94, v95
	v_cvt_pk_bf16_f32 v94, v88, v89
	v_cvt_pk_bf16_f32 v95, v90, v91
	global_store_dwordx4 v[98:99], v[92:95], off
	v_cvt_pk_bf16_f32 v84, v84, v85
	v_cvt_pk_bf16_f32 v85, v86, v87
	v_cvt_pk_bf16_f32 v86, v80, v81
	v_cvt_pk_bf16_f32 v87, v82, v83
	global_store_dwordx4 v[98:99], v[84:87], off offset:64
	s_cbranch_vccnz .LBB0_723
	v_mov_b32_e32 v82, v77
	v_mov_b32_e32 v83, v69
	v_mov_b32_e32 v80, v76
	v_mov_b32_e32 v81, v68
	v_pk_mul_f32 v[82:83], v[82:83], v[82:83]
	v_mov_b32_e32 v84, v79
	v_mov_b32_e32 v85, v71
	v_pk_fma_f32 v[80:81], v[80:81], v[80:81], v[82:83]
	v_mov_b32_e32 v82, v78
	v_mov_b32_e32 v83, v70
	v_pk_mul_f32 v[84:85], v[84:85], v[84:85]
	v_mov_b32_e32 v86, v75
	v_pk_fma_f32 v[82:83], v[82:83], v[82:83], v[84:85]
	v_mov_b32_e32 v84, v73
	v_mov_b32_e32 v85, v65
	v_pk_add_f32 v[80:81], v[80:81], v[82:83]
	v_mov_b32_e32 v82, v72
	v_mov_b32_e32 v83, v64
	v_pk_mul_f32 v[84:85], v[84:85], v[84:85]
	v_mov_b32_e32 v87, v67
	v_pk_fma_f32 v[82:83], v[82:83], v[82:83], v[84:85]
	v_mov_b32_e32 v84, v74
	v_mov_b32_e32 v85, v66
	v_pk_mul_f32 v[86:87], v[86:87], v[86:87]
	s_nop 0
	v_pk_fma_f32 v[84:85], v[84:85], v[84:85], v[86:87]
	s_nop 0
	v_pk_add_f32 v[82:83], v[82:83], v[84:85]
	s_nop 0
	v_pk_add_f32 v[80:81], v[80:81], v[82:83]
	s_nop 0
	v_add_f32_e32 v80, v80, v81
	v_mov_b32_e32 v81, v201
	s_nop 0
	v_lshlrev_b32_e32 v81, 2, v81
	v_xor_b32_e32 v81, 64, v81
	v_mov_b32_e32 v81, v80
	s_nop 1
	v_permlane16_swap_b32_e32 v81, v80
	s_waitcnt lgkmcnt(0)
	v_add_f32_e32 v80, v80, v81
	v_mov_b32_e32 v81, v201
	s_nop 0
	v_lshlrev_b32_e32 v81, 2, v81
	v_xor_b32_e32 v81, 0x80, v81
	v_mov_b32_e32 v81, v80
	s_nop 1
	v_permlane32_swap_b32_e32 v81, v80
	s_waitcnt lgkmcnt(0)
	v_add_f32_e32 v80, v80, v81
	v_fmamk_f32 v80, v80, 0x3c800000, v184
	v_rsq_f32_e32 v80, v80
	s_nop 0
	v_pk_mul_f32 v[76:77], v[76:77], v[80:81] op_sel_hi:[1,0]
	v_pk_mul_f32 v[78:79], v[78:79], v[80:81] op_sel_hi:[1,0]
	v_pk_mul_f32 v[72:73], v[72:73], v[80:81] op_sel_hi:[1,0]
	v_pk_mul_f32 v[74:75], v[74:75], v[80:81] op_sel_hi:[1,0]
	v_pk_mul_f32 v[68:69], v[68:69], v[80:81] op_sel_hi:[1,0]
	v_pk_mul_f32 v[70:71], v[70:71], v[80:81] op_sel_hi:[1,0]
	v_pk_mul_f32 v[64:65], v[64:65], v[80:81] op_sel_hi:[1,0]
	v_pk_mul_f32 v[66:67], v[66:67], v[80:81] op_sel_hi:[1,0]
	v_pk_mul_f32 v[78:79], v[160:161], v[78:79]
	v_pk_mul_f32 v[76:77], v[162:163], v[76:77]
	v_pk_mul_f32 v[74:75], v[156:157], v[74:75]
	v_pk_mul_f32 v[72:73], v[158:159], v[72:73]
	v_pk_mul_f32 v[70:71], v[152:153], v[70:71]
	v_pk_mul_f32 v[68:69], v[154:155], v[68:69]
	v_pk_mul_f32 v[66:67], v[148:149], v[66:67]
	v_pk_mul_f32 v[64:65], v[150:151], v[64:65]
.LBB0_723:
	v_add_f32_e32 v80, v187, v188
	v_fmamk_f32 v80, v80, 0x3a800000, v184
	v_rsq_f32_e32 v80, v80
	v_add_u32_e32 v81, s35, v178
	v_mov_b64_e32 v[82:83], s[22:23]
	v_mad_i64_i32 v[82:83], s[48:49], v81, s64, v[82:83]
	v_lshl_add_u64 v[82:83], v[112:113], 1, v[82:83]
	v_pk_mul_f32 v[62:63], v[62:63], v[80:81] op_sel_hi:[1,0]
	v_pk_mul_f32 v[60:61], v[60:61], v[80:81] op_sel_hi:[1,0]
	v_pk_mul_f32 v[58:59], v[58:59], v[80:81] op_sel_hi:[1,0]
	v_pk_mul_f32 v[56:57], v[56:57], v[80:81] op_sel_hi:[1,0]
	v_pk_mul_f32 v[54:55], v[54:55], v[80:81] op_sel_hi:[1,0]
	v_pk_mul_f32 v[52:53], v[52:53], v[80:81] op_sel_hi:[1,0]
	v_pk_mul_f32 v[50:51], v[50:51], v[80:81] op_sel_hi:[1,0]
	s_and_b64 vcc, exec, s[12:13]
	v_pk_mul_f32 v[48:49], v[48:49], v[80:81] op_sel_hi:[1,0]
	v_cvt_pk_bf16_f32 v76, v76, v77
	v_cvt_pk_bf16_f32 v77, v78, v79
	v_cvt_pk_bf16_f32 v78, v72, v73
	v_cvt_pk_bf16_f32 v79, v74, v75
	global_store_dwordx4 v[82:83], v[76:79], off
	v_cvt_pk_bf16_f32 v68, v68, v69
	v_cvt_pk_bf16_f32 v69, v70, v71
	v_cvt_pk_bf16_f32 v70, v64, v65
	v_cvt_pk_bf16_f32 v71, v66, v67
	global_store_dwordx4 v[82:83], v[68:71], off offset:64
	s_cbranch_vccnz .LBB0_725
	v_mov_b32_e32 v66, v61
	v_mov_b32_e32 v67, v53
	v_mov_b32_e32 v64, v60
	v_mov_b32_e32 v65, v52
	v_pk_mul_f32 v[66:67], v[66:67], v[66:67]
	v_mov_b32_e32 v68, v63
	v_mov_b32_e32 v69, v55
	v_pk_fma_f32 v[64:65], v[64:65], v[64:65], v[66:67]
	v_mov_b32_e32 v66, v62
	v_mov_b32_e32 v67, v54
	v_pk_mul_f32 v[68:69], v[68:69], v[68:69]
	v_mov_b32_e32 v70, v59
	v_pk_fma_f32 v[66:67], v[66:67], v[66:67], v[68:69]
	v_mov_b32_e32 v68, v57
	v_mov_b32_e32 v69, v49
	v_pk_add_f32 v[64:65], v[64:65], v[66:67]
	v_mov_b32_e32 v66, v56
	v_mov_b32_e32 v67, v48
	v_pk_mul_f32 v[68:69], v[68:69], v[68:69]
	v_mov_b32_e32 v71, v51
	v_pk_fma_f32 v[66:67], v[66:67], v[66:67], v[68:69]
	v_mov_b32_e32 v68, v58
	v_mov_b32_e32 v69, v50
	v_pk_mul_f32 v[70:71], v[70:71], v[70:71]
	s_nop 0
	v_pk_fma_f32 v[68:69], v[68:69], v[68:69], v[70:71]
	s_nop 0
	v_pk_add_f32 v[66:67], v[66:67], v[68:69]
	s_nop 0
	v_pk_add_f32 v[64:65], v[64:65], v[66:67]
	s_nop 0
	v_add_f32_e32 v64, v64, v65
	v_mov_b32_e32 v65, v201
	s_nop 0
	v_lshlrev_b32_e32 v65, 2, v65
	v_xor_b32_e32 v65, 64, v65
	v_mov_b32_e32 v65, v64
	s_nop 1
	v_permlane16_swap_b32_e32 v65, v64
	s_waitcnt lgkmcnt(0)
	v_add_f32_e32 v64, v64, v65
	v_mov_b32_e32 v65, v201
	s_nop 0
	v_lshlrev_b32_e32 v65, 2, v65
	v_xor_b32_e32 v65, 0x80, v65
	v_mov_b32_e32 v65, v64
	s_nop 1
	v_permlane32_swap_b32_e32 v65, v64
	s_waitcnt lgkmcnt(0)
	v_add_f32_e32 v64, v64, v65
	v_fmamk_f32 v64, v64, 0x3c800000, v184
	v_rsq_f32_e32 v64, v64
	s_nop 0
	v_pk_mul_f32 v[60:61], v[60:61], v[64:65] op_sel_hi:[1,0]
	v_pk_mul_f32 v[62:63], v[62:63], v[64:65] op_sel_hi:[1,0]
	v_pk_mul_f32 v[56:57], v[56:57], v[64:65] op_sel_hi:[1,0]
	v_pk_mul_f32 v[58:59], v[58:59], v[64:65] op_sel_hi:[1,0]
	v_pk_mul_f32 v[52:53], v[52:53], v[64:65] op_sel_hi:[1,0]
	v_pk_mul_f32 v[54:55], v[54:55], v[64:65] op_sel_hi:[1,0]
	v_pk_mul_f32 v[48:49], v[48:49], v[64:65] op_sel_hi:[1,0]
	v_pk_mul_f32 v[50:51], v[50:51], v[64:65] op_sel_hi:[1,0]
	v_pk_mul_f32 v[62:63], v[160:161], v[62:63]
	v_pk_mul_f32 v[60:61], v[162:163], v[60:61]
	v_pk_mul_f32 v[58:59], v[156:157], v[58:59]
	v_pk_mul_f32 v[56:57], v[158:159], v[56:57]
	v_pk_mul_f32 v[54:55], v[152:153], v[54:55]
	v_pk_mul_f32 v[52:53], v[154:155], v[52:53]
	v_pk_mul_f32 v[50:51], v[148:149], v[50:51]
	v_pk_mul_f32 v[48:49], v[150:151], v[48:49]
; __device__ __forceinline__ f32x4 silu4(f32x4 v) { return (f32x4){silu_f(v[0]), silu_f(v[1]), silu_f(v[2]), silu_f(v[3])}; }
; __device__ __forceinline__ float sq4(f32x4 v) { return (v[0] * v[0] + v[1] * v[1]) + (v[2] * v[2] + v[3] * v[3]); }
; __device__ __forceinline__ u32x4 pack8(f32x4 a, f32x4 b) { u32x4 w; w.x = cvt_pk_bf16(a[0], a[1]); w.y = cvt_pk_bf16(a[2], a[3]); w.z = cvt_pk_bf16(b[0], b[1]); w.w = cvt_pk_bf16(b[2], b[3]); return w; }
; __device__ __forceinline__ float row_finish(float t) { t += shx(t, 16); t += shx(t, 32); return __builtin_amdgcn_rsqf(t * (1.0f / 1024.0f) + RMS_EPS); }
;     __device__ __forceinline__ void operator()(const f32x4 (&acc)[2][2][4][2], const Unit& u, int wr, int wc, int fr, int fq) const {
;     ...
;                     for (int n = 0; n < 2; ++n) v[bj][n] = acc[ai][bj][m][n] * rstd;
;                 if (mode == 2) {
;                     float q = (sq4(v[0][0]) + sq4(v[0][1])) + (sq4(v[1][0]) + sq4(v[1][1]));
;                     q += shx(q, 16); q += shx(q, 32);
;                     const float r2 = __builtin_amdgcn_rsqf(q * (1.0f / 64.0f) + RMS_EPS);
; #pragma unroll
;                     for (int bj = 0; bj < 2; ++bj)
; #pragma unroll
;                         for (int n = 0; n < 2; ++n) v[bj][n] = v[bj][n] * r2 * wv[bj][n];
;                 } else if (mode == 1) {
; #pragma unroll
;                     for (int bj = 0; bj < 2; ++bj)
; #pragma unroll
;                         for (int n = 0; n < 2; ++n) v[bj][n] = silu4(v[bj][n]);
;                 } else {
; #pragma unroll
;                     for (int bj = 0; bj < 2; ++bj)
; #pragma unroll
;                         for (int n = 0; n < 2; ++n) v[bj][n] = v[bj][n] * sc;
;                 }
;                 bf16_t* rowp = U + (size_t)row * 2560 + lcol;
; #pragma unroll
;                 for (int bj = 0; bj < 2; ++bj) *(u32x4*)(rowp + 32 * bj) = pack8(v[bj][0], v[bj][1]);
.LBB0_725:
	v_add_f32_e32 v64, v171, v186
	v_fmamk_f32 v64, v64, 0x3a800000, v184
	v_rsq_f32_e32 v64, v64
	v_mov_b64_e32 v[66:67], s[22:23]
	v_mad_i64_i32 v[66:67], s[48:49], v168, s64, v[66:67]
	v_lshl_add_u64 v[66:67], v[112:113], 1, v[66:67]
	v_pk_mul_f32 v[46:47], v[46:47], v[64:65] op_sel_hi:[1,0]
	v_pk_mul_f32 v[44:45], v[44:45], v[64:65] op_sel_hi:[1,0]
	v_pk_mul_f32 v[42:43], v[42:43], v[64:65] op_sel_hi:[1,0]
	v_pk_mul_f32 v[40:41], v[40:41], v[64:65] op_sel_hi:[1,0]
	v_pk_mul_f32 v[38:39], v[38:39], v[64:65] op_sel_hi:[1,0]
	v_pk_mul_f32 v[36:37], v[36:37], v[64:65] op_sel_hi:[1,0]
	v_pk_mul_f32 v[34:35], v[34:35], v[64:65] op_sel_hi:[1,0]
	s_and_b64 vcc, exec, s[12:13]
	v_pk_mul_f32 v[32:33], v[32:33], v[64:65] op_sel_hi:[1,0]
	v_cvt_pk_bf16_f32 v60, v60, v61
	v_cvt_pk_bf16_f32 v61, v62, v63
	v_cvt_pk_bf16_f32 v62, v56, v57
	v_cvt_pk_bf16_f32 v63, v58, v59
	global_store_dwordx4 v[66:67], v[60:63], off
	v_cvt_pk_bf16_f32 v52, v52, v53
	v_cvt_pk_bf16_f32 v53, v54, v55
	v_cvt_pk_bf16_f32 v54, v48, v49
	v_cvt_pk_bf16_f32 v55, v50, v51
	global_store_dwordx4 v[66:67], v[52:55], off offset:64
	s_cbranch_vccnz .LBB0_727
	v_mov_b32_e32 v50, v45
	v_mov_b32_e32 v51, v37
	v_mov_b32_e32 v48, v44
	v_mov_b32_e32 v49, v36
	v_pk_mul_f32 v[50:51], v[50:51], v[50:51]
	v_mov_b32_e32 v52, v47
	v_mov_b32_e32 v53, v39
	v_pk_fma_f32 v[48:49], v[48:49], v[48:49], v[50:51]
	v_mov_b32_e32 v50, v46
	v_mov_b32_e32 v51, v38
	v_pk_mul_f32 v[52:53], v[52:53], v[52:53]
	v_mov_b32_e32 v54, v43
	v_pk_fma_f32 v[50:51], v[50:51], v[50:51], v[52:53]
	v_mov_b32_e32 v52, v41
	v_mov_b32_e32 v53, v33
	v_pk_add_f32 v[48:49], v[48:49], v[50:51]
	v_mov_b32_e32 v50, v40
	v_mov_b32_e32 v51, v32
	v_pk_mul_f32 v[52:53], v[52:53], v[52:53]
	v_mov_b32_e32 v55, v35
	v_pk_fma_f32 v[50:51], v[50:51], v[50:51], v[52:53]
	v_mov_b32_e32 v52, v42
	v_mov_b32_e32 v53, v34
	v_pk_mul_f32 v[54:55], v[54:55], v[54:55]
	s_nop 0
	v_pk_fma_f32 v[52:53], v[52:53], v[52:53], v[54:55]
	s_nop 0
	v_pk_add_f32 v[50:51], v[50:51], v[52:53]
	s_nop 0
	v_pk_add_f32 v[48:49], v[48:49], v[50:51]
	s_nop 0
	v_add_f32_e32 v48, v48, v49
	v_mov_b32_e32 v49, v201
	s_nop 0
	v_lshlrev_b32_e32 v49, 2, v49
	v_xor_b32_e32 v49, 64, v49
	v_mov_b32_e32 v49, v48
	s_nop 1
	v_permlane16_swap_b32_e32 v49, v48
	s_waitcnt lgkmcnt(0)
	v_add_f32_e32 v48, v48, v49
	v_mov_b32_e32 v49, v201
	s_nop 0
	v_lshlrev_b32_e32 v49, 2, v49
	v_xor_b32_e32 v49, 0x80, v49
	v_mov_b32_e32 v49, v48
	s_nop 1
	v_permlane32_swap_b32_e32 v49, v48
	s_waitcnt lgkmcnt(0)
	v_add_f32_e32 v48, v48, v49
	v_fmamk_f32 v48, v48, 0x3c800000, v184
	v_rsq_f32_e32 v48, v48
	s_nop 0
	v_pk_mul_f32 v[44:45], v[44:45], v[48:49] op_sel_hi:[1,0]
	v_pk_mul_f32 v[46:47], v[46:47], v[48:49] op_sel_hi:[1,0]
	v_pk_mul_f32 v[40:41], v[40:41], v[48:49] op_sel_hi:[1,0]
	v_pk_mul_f32 v[42:43], v[42:43], v[48:49] op_sel_hi:[1,0]
	v_pk_mul_f32 v[36:37], v[36:37], v[48:49] op_sel_hi:[1,0]
	v_pk_mul_f32 v[38:39], v[38:39], v[48:49] op_sel_hi:[1,0]
	v_pk_mul_f32 v[32:33], v[32:33], v[48:49] op_sel_hi:[1,0]
	v_pk_mul_f32 v[34:35], v[34:35], v[48:49] op_sel_hi:[1,0]
	v_pk_mul_f32 v[46:47], v[160:161], v[46:47]
	v_pk_mul_f32 v[44:45], v[162:163], v[44:45]
	v_pk_mul_f32 v[42:43], v[156:157], v[42:43]
	v_pk_mul_f32 v[40:41], v[158:159], v[40:41]
	v_pk_mul_f32 v[38:39], v[152:153], v[38:39]
	v_pk_mul_f32 v[36:37], v[154:155], v[36:37]
	v_pk_mul_f32 v[34:35], v[148:149], v[34:35]
	v_pk_mul_f32 v[32:33], v[150:151], v[32:33]
; __device__ __forceinline__ f32x4 silu4(f32x4 v) { return (f32x4){silu_f(v[0]), silu_f(v[1]), silu_f(v[2]), silu_f(v[3])}; }
; __device__ __forceinline__ float sq4(f32x4 v) { return (v[0] * v[0] + v[1] * v[1]) + (v[2] * v[2] + v[3] * v[3]); }
; __device__ __forceinline__ u32x4 pack8(f32x4 a, f32x4 b) { u32x4 w; w.x = cvt_pk_bf16(a[0], a[1]); w.y = cvt_pk_bf16(a[2], a[3]); w.z = cvt_pk_bf16(b[0], b[1]); w.w = cvt_pk_bf16(b[2], b[3]); return w; }
; __device__ __forceinline__ float row_finish(float t) { t += shx(t, 16); t += shx(t, 32); return __builtin_amdgcn_rsqf(t * (1.0f / 1024.0f) + RMS_EPS); }
;     __device__ __forceinline__ void operator()(const f32x4 (&acc)[2][2][4][2], const Unit& u, int wr, int wc, int fr, int fq) const {
;     ...
;                     for (int n = 0; n < 2; ++n) v[bj][n] = acc[ai][bj][m][n] * rstd;
;                 if (mode == 2) {
;                     float q = (sq4(v[0][0]) + sq4(v[0][1])) + (sq4(v[1][0]) + sq4(v[1][1]));
;                     q += shx(q, 16); q += shx(q, 32);
;                     const float r2 = __builtin_amdgcn_rsqf(q * (1.0f / 64.0f) + RMS_EPS);
; #pragma unroll
;                     for (int bj = 0; bj < 2; ++bj)
; #pragma unroll
;                         for (int n = 0; n < 2; ++n) v[bj][n] = v[bj][n] * r2 * wv[bj][n];
;                 } else if (mode == 1) {
; #pragma unroll
;                     for (int bj = 0; bj < 2; ++bj)
; #pragma unroll
;                         for (int n = 0; n < 2; ++n) v[bj][n] = silu4(v[bj][n]);
;                 } else {
; #pragma unroll
;                     for (int bj = 0; bj < 2; ++bj)
; #pragma unroll
;                         for (int n = 0; n < 2; ++n) v[bj][n] = v[bj][n] * sc;
;                 }
;                 bf16_t* rowp = U + (size_t)row * 2560 + lcol;
; #pragma unroll
;                 for (int bj = 0; bj < 2; ++bj) *(u32x4*)(rowp + 32 * bj) = pack8(v[bj][0], v[bj][1]);
.LBB0_727:
	s_waitcnt lgkmcnt(0)
	v_add_f32_e32 v48, v167, v169
	v_fmamk_f32 v48, v48, 0x3a800000, v184
	v_rsq_f32_e32 v48, v48
	v_mov_b64_e32 v[50:51], s[22:23]
	v_mad_i64_i32 v[50:51], s[48:49], v166, s64, v[50:51]
	v_lshl_add_u64 v[50:51], v[112:113], 1, v[50:51]
	v_pk_mul_f32 v[30:31], v[30:31], v[48:49] op_sel_hi:[1,0]
	v_pk_mul_f32 v[28:29], v[28:29], v[48:49] op_sel_hi:[1,0]
	v_pk_mul_f32 v[26:27], v[26:27], v[48:49] op_sel_hi:[1,0]
	v_pk_mul_f32 v[24:25], v[24:25], v[48:49] op_sel_hi:[1,0]
	v_pk_mul_f32 v[22:23], v[22:23], v[48:49] op_sel_hi:[1,0]
	v_pk_mul_f32 v[20:21], v[20:21], v[48:49] op_sel_hi:[1,0]
	v_pk_mul_f32 v[18:19], v[18:19], v[48:49] op_sel_hi:[1,0]
	s_and_b64 vcc, exec, s[12:13]
	v_pk_mul_f32 v[16:17], v[16:17], v[48:49] op_sel_hi:[1,0]
	v_cvt_pk_bf16_f32 v44, v44, v45
	v_cvt_pk_bf16_f32 v45, v46, v47
	v_cvt_pk_bf16_f32 v46, v40, v41
	v_cvt_pk_bf16_f32 v47, v42, v43
	global_store_dwordx4 v[50:51], v[44:47], off
	v_cvt_pk_bf16_f32 v36, v36, v37
	v_cvt_pk_bf16_f32 v37, v38, v39
	v_cvt_pk_bf16_f32 v38, v32, v33
	v_cvt_pk_bf16_f32 v39, v34, v35
	global_store_dwordx4 v[50:51], v[36:39], off offset:64
	s_cbranch_vccnz .LBB0_729
	v_mov_b32_e32 v34, v29
	v_mov_b32_e32 v35, v21
	v_mov_b32_e32 v32, v28
	v_mov_b32_e32 v33, v20
	v_pk_mul_f32 v[34:35], v[34:35], v[34:35]
	v_mov_b32_e32 v36, v31
	v_mov_b32_e32 v37, v23
	v_pk_fma_f32 v[32:33], v[32:33], v[32:33], v[34:35]
	v_mov_b32_e32 v34, v30
	v_mov_b32_e32 v35, v22
	v_pk_mul_f32 v[36:37], v[36:37], v[36:37]
	v_mov_b32_e32 v38, v27
	v_pk_fma_f32 v[34:35], v[34:35], v[34:35], v[36:37]
	v_mov_b32_e32 v36, v25
	v_mov_b32_e32 v37, v17
	v_pk_add_f32 v[32:33], v[32:33], v[34:35]
	v_mov_b32_e32 v34, v24
	v_mov_b32_e32 v35, v16
	v_pk_mul_f32 v[36:37], v[36:37], v[36:37]
	v_mov_b32_e32 v39, v19
	v_pk_fma_f32 v[34:35], v[34:35], v[34:35], v[36:37]
	v_mov_b32_e32 v36, v26
	v_mov_b32_e32 v37, v18
	v_pk_mul_f32 v[38:39], v[38:39], v[38:39]
	s_nop 0
	v_pk_fma_f32 v[36:37], v[36:37], v[36:37], v[38:39]
	s_nop 0
	v_pk_add_f32 v[34:35], v[34:35], v[36:37]
	s_nop 0
	v_pk_add_f32 v[32:33], v[32:33], v[34:35]
	s_nop 0
	v_add_f32_e32 v32, v32, v33
	v_mov_b32_e32 v33, v201
	s_nop 0
	v_lshlrev_b32_e32 v33, 2, v33
	v_xor_b32_e32 v33, 64, v33
	v_mov_b32_e32 v33, v32
	s_nop 1
	v_permlane16_swap_b32_e32 v33, v32
	s_waitcnt lgkmcnt(0)
	v_add_f32_e32 v32, v32, v33
	v_mov_b32_e32 v33, v201
	s_nop 0
	v_lshlrev_b32_e32 v33, 2, v33
	v_xor_b32_e32 v33, 0x80, v33
	v_mov_b32_e32 v33, v32
	s_nop 1
	v_permlane32_swap_b32_e32 v33, v32
	s_waitcnt lgkmcnt(0)
	v_add_f32_e32 v32, v32, v33
	v_fmamk_f32 v32, v32, 0x3c800000, v184
	v_rsq_f32_e32 v32, v32
	s_nop 0
	v_pk_mul_f32 v[28:29], v[28:29], v[32:33] op_sel_hi:[1,0]
	v_pk_mul_f32 v[30:31], v[30:31], v[32:33] op_sel_hi:[1,0]
	v_pk_mul_f32 v[24:25], v[24:25], v[32:33] op_sel_hi:[1,0]
	v_pk_mul_f32 v[26:27], v[26:27], v[32:33] op_sel_hi:[1,0]
	v_pk_mul_f32 v[20:21], v[20:21], v[32:33] op_sel_hi:[1,0]
	v_pk_mul_f32 v[22:23], v[22:23], v[32:33] op_sel_hi:[1,0]
	v_pk_mul_f32 v[16:17], v[16:17], v[32:33] op_sel_hi:[1,0]
	v_pk_mul_f32 v[18:19], v[18:19], v[32:33] op_sel_hi:[1,0]
	v_pk_mul_f32 v[30:31], v[160:161], v[30:31]
	v_pk_mul_f32 v[28:29], v[162:163], v[28:29]
	v_pk_mul_f32 v[26:27], v[156:157], v[26:27]
	v_pk_mul_f32 v[24:25], v[158:159], v[24:25]
	v_pk_mul_f32 v[22:23], v[152:153], v[22:23]
	v_pk_mul_f32 v[20:21], v[154:155], v[20:21]
	v_pk_mul_f32 v[18:19], v[148:149], v[18:19]
	v_pk_mul_f32 v[16:17], v[150:151], v[16:17]
.LBB0_729:
	s_waitcnt lgkmcnt(0)
	v_add_f32_e32 v32, v147, v165
	v_fmamk_f32 v32, v32, 0x3a800000, v184
	v_rsq_f32_e32 v32, v32
	v_mov_b64_e32 v[34:35], s[22:23]
	v_mad_i64_i32 v[34:35], s[48:49], v164, s64, v[34:35]
	v_lshl_add_u64 v[34:35], v[112:113], 1, v[34:35]
	v_pk_mul_f32 v[14:15], v[14:15], v[32:33] op_sel_hi:[1,0]
	v_pk_mul_f32 v[12:13], v[12:13], v[32:33] op_sel_hi:[1,0]
	v_pk_mul_f32 v[10:11], v[10:11], v[32:33] op_sel_hi:[1,0]
	v_pk_mul_f32 v[8:9], v[8:9], v[32:33] op_sel_hi:[1,0]
	v_pk_mul_f32 v[6:7], v[6:7], v[32:33] op_sel_hi:[1,0]
	v_pk_mul_f32 v[4:5], v[4:5], v[32:33] op_sel_hi:[1,0]
	v_pk_mul_f32 v[2:3], v[2:3], v[32:33] op_sel_hi:[1,0]
	s_and_b64 vcc, exec, s[12:13]
	v_pk_mul_f32 v[0:1], v[0:1], v[32:33] op_sel_hi:[1,0]
	v_cvt_pk_bf16_f32 v28, v28, v29
	v_cvt_pk_bf16_f32 v29, v30, v31
	v_cvt_pk_bf16_f32 v30, v24, v25
	v_cvt_pk_bf16_f32 v31, v26, v27
	global_store_dwordx4 v[34:35], v[28:31], off
	v_cvt_pk_bf16_f32 v20, v20, v21
	v_cvt_pk_bf16_f32 v21, v22, v23
	v_cvt_pk_bf16_f32 v22, v16, v17
	v_cvt_pk_bf16_f32 v23, v18, v19
	global_store_dwordx4 v[34:35], v[20:23], off offset:64
	s_cbranch_vccnz .LBB0_731
	v_mov_b32_e32 v18, v13
	v_mov_b32_e32 v19, v5
	v_mov_b32_e32 v16, v12
	v_mov_b32_e32 v17, v4
	v_pk_mul_f32 v[18:19], v[18:19], v[18:19]
	v_mov_b32_e32 v20, v15
	v_mov_b32_e32 v21, v7
	v_pk_fma_f32 v[16:17], v[16:17], v[16:17], v[18:19]
	v_mov_b32_e32 v18, v14
	v_mov_b32_e32 v19, v6
	v_pk_mul_f32 v[20:21], v[20:21], v[20:21]
	v_mov_b32_e32 v22, v11
	v_pk_fma_f32 v[18:19], v[18:19], v[18:19], v[20:21]
	v_mov_b32_e32 v20, v9
	v_mov_b32_e32 v21, v1
	v_pk_add_f32 v[16:17], v[16:17], v[18:19]
	v_mov_b32_e32 v18, v8
	v_mov_b32_e32 v19, v0
	v_pk_mul_f32 v[20:21], v[20:21], v[20:21]
	v_mov_b32_e32 v23, v3
	v_pk_fma_f32 v[18:19], v[18:19], v[18:19], v[20:21]
	v_mov_b32_e32 v20, v10
	v_mov_b32_e32 v21, v2
	v_pk_mul_f32 v[22:23], v[22:23], v[22:23]
	s_nop 0
	v_pk_fma_f32 v[20:21], v[20:21], v[20:21], v[22:23]
	s_nop 0
	v_pk_add_f32 v[18:19], v[18:19], v[20:21]
	s_nop 0
	v_pk_add_f32 v[16:17], v[16:17], v[18:19]
	s_nop 0
	v_add_f32_e32 v16, v16, v17
	v_mov_b32_e32 v17, v201
	s_nop 0
	v_lshlrev_b32_e32 v17, 2, v17
	v_xor_b32_e32 v17, 64, v17
	v_mov_b32_e32 v17, v16
	s_nop 1
	v_permlane16_swap_b32_e32 v17, v16
	s_waitcnt lgkmcnt(0)
	v_add_f32_e32 v16, v16, v17
	v_mov_b32_e32 v17, v201
	s_nop 0
	v_lshlrev_b32_e32 v17, 2, v17
	v_xor_b32_e32 v17, 0x80, v17
	v_mov_b32_e32 v17, v16
	s_nop 1
	v_permlane32_swap_b32_e32 v17, v16
	s_waitcnt lgkmcnt(0)
	v_add_f32_e32 v16, v16, v17
	v_fmamk_f32 v16, v16, 0x3c800000, v184
	v_rsq_f32_e32 v16, v16
	s_nop 0
	v_pk_mul_f32 v[12:13], v[12:13], v[16:17] op_sel_hi:[1,0]
	v_pk_mul_f32 v[14:15], v[14:15], v[16:17] op_sel_hi:[1,0]
	v_pk_mul_f32 v[8:9], v[8:9], v[16:17] op_sel_hi:[1,0]
	v_pk_mul_f32 v[10:11], v[10:11], v[16:17] op_sel_hi:[1,0]
	v_pk_mul_f32 v[4:5], v[4:5], v[16:17] op_sel_hi:[1,0]
	v_pk_mul_f32 v[6:7], v[6:7], v[16:17] op_sel_hi:[1,0]
	v_pk_mul_f32 v[0:1], v[0:1], v[16:17] op_sel_hi:[1,0]
	v_pk_mul_f32 v[2:3], v[2:3], v[16:17] op_sel_hi:[1,0]
	v_pk_mul_f32 v[14:15], v[160:161], v[14:15]
	v_pk_mul_f32 v[12:13], v[162:163], v[12:13]
	v_pk_mul_f32 v[10:11], v[156:157], v[10:11]
	v_pk_mul_f32 v[8:9], v[158:159], v[8:9]
	v_pk_mul_f32 v[6:7], v[152:153], v[6:7]
	v_pk_mul_f32 v[4:5], v[154:155], v[4:5]
	v_pk_mul_f32 v[2:3], v[148:149], v[2:3]
	v_pk_mul_f32 v[0:1], v[150:151], v[0:1]

; __device__ __forceinline__ float sq4(f32x4 v) { return (v[0] * v[0] + v[1] * v[1]) + (v[2] * v[2] + v[3] * v[3]); }
; __device__ __forceinline__ u32x4 pack8(f32x4 a, f32x4 b) { u32x4 w; w.x = cvt_pk_bf16(a[0], a[1]); w.y = cvt_pk_bf16(a[2], a[3]); w.z = cvt_pk_bf16(b[0], b[1]); w.w = cvt_pk_bf16(b[2], b[3]); return w; }
;     __device__ __forceinline__ void operator()(const f32x4 (&acc)[2][2][4][2], const Unit& u, int wr, int wc, int fr, int fq) const {
;         const int col0 = u.pn * 256 + 32 * wc + 8 * fq;
; #pragma unroll
;         for (int ai = 0; ai < 2; ++ai) {
;             u32x4 bs[4][2];
; #pragma unroll
;             for (int m = 0; m < 4; ++m)
; #pragma unroll
;                 for (int bj = 0; bj < 2; ++bj) bs[m][bj] = *(const u32x4*)(xb + (size_t)(u.pm * BM + ai * HALF + wr * 64 + m * 16 + fr) * 1024 + col0 + 128 * bj);
; #pragma unroll
;             for (int m = 0; m < 4; ++m) {
;                 const int row = u.pm * BM + ai * HALF + wr * 64 + m * 16 + fr;
;                 float q = 0.f;
; #pragma unroll
;                 for (int bj = 0; bj < 2; ++bj) {
;                     const size_t off = (size_t)row * 1024 + col0 + 128 * bj; const u32x4 w = bs[m][bj];
;                     const f32x4 b0 = (f32x4){__builtin_bit_cast(float, w.x << 16), __builtin_bit_cast(float, w.x & 0xffff0000u), __builtin_bit_cast(float, w.y << 16), __builtin_bit_cast(float, w.y & 0xffff0000u)};
;                     const f32x4 b1 = (f32x4){__builtin_bit_cast(float, w.z << 16), __builtin_bit_cast(float, w.z & 0xffff0000u), __builtin_bit_cast(float, w.w << 16), __builtin_bit_cast(float, w.w & 0xffff0000u)};
;                     const f32x4 v0 = acc[ai][bj][m][0] + b0, v1 = acc[ai][bj][m][1] + b1;
;                     if (last) { __builtin_nontemporal_store(v0, (f32x4*)(out + off)); __builtin_nontemporal_store(v1, (f32x4*)(out + off + 4)); }
;                     else { q += sq4(v0) + sq4(v1); *(u32x4*)(xb + off) = pack8(v0, v1); }
;                 }
;                 if (!last) { q += shx(q, 16); q += shx(q, 32); if (fq == 0) ss[(size_t)row * 16 + u.pn * 4 + wc] = q; }
.LBB0_915:
	v_lshl_or_b32 v168, s18, 8, v188
	v_lshl_add_u32 v172, s54, 8, v186
	v_ashrrev_i32_e32 v169, 31, v168
	v_lshlrev_b64 v[202:203], 1, v[168:169]
	v_ashrrev_i32_e32 v173, 31, v172
	v_lshl_add_u64 v[170:171], s[22:23], 0, v[202:203]
	v_lshlrev_b64 v[204:205], 11, v[172:173]
	v_lshl_add_u64 v[120:121], v[170:171], 0, v[204:205]
	global_load_dwordx4 v[192:195], v[120:121], off
	global_load_dwordx4 v[196:199], v[120:121], off offset:256
	v_or_b32_e32 v182, 16, v172
	v_ashrrev_i32_e32 v183, 31, v182
	v_or_b32_e32 v178, 32, v172
	v_lshlrev_b64 v[184:185], 11, v[182:183]
	v_ashrrev_i32_e32 v179, 31, v178
	v_or_b32_e32 v174, 48, v172
	v_lshl_add_u64 v[120:121], v[170:171], 0, v[184:185]
	v_lshlrev_b64 v[180:181], 11, v[178:179]
	v_ashrrev_i32_e32 v175, 31, v174
	global_load_dwordx4 v[148:151], v[120:121], off
	global_load_dwordx4 v[144:147], v[120:121], off offset:256
	v_lshl_add_u64 v[120:121], v[170:171], 0, v[180:181]
	v_lshlrev_b64 v[176:177], 11, v[174:175]
	global_load_dwordx4 v[140:143], v[120:121], off
	global_load_dwordx4 v[136:139], v[120:121], off offset:256
	v_lshl_add_u64 v[120:121], v[170:171], 0, v[176:177]
	global_load_dwordx4 v[132:135], v[120:121], off
	s_nop 0
	global_load_dwordx4 v[120:123], v[120:121], off offset:256
	s_lshl_b32 s54, s18, 2
	s_ashr_i32 s55, s54, 31
	s_waitcnt vmcnt(0)
	v_lshlrev_b32_e32 v206, 16, v192
	v_and_b32_e32 v207, 0xffff0000, v192
	v_lshlrev_b32_e32 v192, 16, v193
	v_and_b32_e32 v193, 0xffff0000, v193
	v_lshlrev_b32_e32 v208, 16, v194
	v_and_b32_e32 v209, 0xffff0000, v194
	v_lshlrev_b32_e32 v194, 16, v195
	v_and_b32_e32 v195, 0xffff0000, v195
	v_pk_add_f32 v[130:131], v[130:131], v[192:193]
	v_pk_add_f32 v[128:129], v[128:129], v[206:207]
	v_pk_add_f32 v[192:193], v[126:127], v[194:195]
	v_pk_add_f32 v[126:127], v[124:125], v[208:209]
	v_mul_f32_e32 v124, v129, v129
	v_mul_f32_e32 v125, v131, v131
	v_fmac_f32_e32 v124, v128, v128
	v_fmac_f32_e32 v125, v130, v130
	v_add_f32_e32 v124, v124, v125
	v_mul_f32_e32 v125, v127, v127
	v_mul_f32_e32 v194, v193, v193
	v_fmac_f32_e32 v125, v126, v126
	v_fmac_f32_e32 v194, v192, v192
	v_add_f32_e32 v125, v125, v194
	v_add_f32_e32 v194, v124, v125
	v_cvt_pk_bf16_f32 v124, v128, v129
	v_lshl_add_u64 v[128:129], s[22:23], 0, v[204:205]
	v_cvt_pk_bf16_f32 v125, v130, v131
	v_cvt_pk_bf16_f32 v126, v126, v127
	v_cvt_pk_bf16_f32 v127, v192, v193
	v_lshl_add_u64 v[128:129], v[128:129], 0, v[202:203]
	global_store_dwordx4 v[128:129], v[124:127], off
	v_lshlrev_b32_e32 v130, 16, v198
	v_and_b32_e32 v131, 0xffff0000, v198
	v_lshlrev_b32_e32 v124, 16, v196
	v_and_b32_e32 v125, 0xffff0000, v196
	v_lshlrev_b32_e32 v126, 16, v197
	v_and_b32_e32 v127, 0xffff0000, v197
	v_lshlrev_b32_e32 v192, 16, v199
	v_and_b32_e32 v193, 0xffff0000, v199
	v_pk_add_f32 v[118:119], v[118:119], v[126:127]
	v_pk_add_f32 v[116:117], v[116:117], v[124:125]
	v_pk_add_f32 v[124:125], v[114:115], v[192:193]
	v_pk_add_f32 v[114:115], v[112:113], v[130:131]
	v_mul_f32_e32 v112, v117, v117
	v_mul_f32_e32 v113, v119, v119
	v_fmac_f32_e32 v112, v116, v116
	v_fmac_f32_e32 v113, v118, v118
	v_add_f32_e32 v112, v112, v113
	v_mul_f32_e32 v113, v115, v115
	v_mul_f32_e32 v126, v125, v125
	v_fmac_f32_e32 v113, v114, v114
	v_fmac_f32_e32 v126, v124, v124
	v_add_f32_e32 v113, v113, v126
	v_add_f32_e32 v112, v112, v113
	v_add_f32_e32 v126, v194, v112
	v_cvt_pk_bf16_f32 v112, v116, v117
	v_cvt_pk_bf16_f32 v113, v118, v119
	v_cvt_pk_bf16_f32 v114, v114, v115
	v_cvt_pk_bf16_f32 v115, v124, v125
	global_store_dwordx4 v[128:129], v[112:115], off offset:256
	s_nop 1
	v_mov_b32_e32 v112, v201
	v_mov_b32_e32 v113, v201
	v_lshlrev_b32_e32 v112, 2, v112
	v_xor_b32_e32 v112, 64, v112
	v_mov_b32_e32 v112, v126
	s_nop 1
	v_permlane16_swap_b32_e32 v112, v126
	s_waitcnt lgkmcnt(0)
	v_add_f32_e32 v112, v126, v112
	v_lshlrev_b32_e32 v113, 2, v113
	v_xor_b32_e32 v113, 0x80, v113
	v_mov_b32_e32 v113, v112
	s_nop 1
	v_permlane32_swap_b32_e32 v113, v112
	s_and_saveexec_b64 s[56:57], s[12:13]
	s_cbranch_execz .LBB0_917
	s_waitcnt lgkmcnt(0)
	v_add_f32_e32 v114, v112, v113
	v_lshlrev_b64 v[112:113], 6, v[172:173]
	v_lshl_add_u64 v[112:113], s[24:25], 0, v[112:113]
	v_lshl_add_u64 v[112:113], s[54:55], 2, v[112:113]
	s_lshl_b32 s18, s67, 2
	v_lshl_add_u64 v[112:113], v[112:113], 0, s[18:19]
	global_store_dword v[112:113], v114, off
; __device__ __forceinline__ float sq4(f32x4 v) { return (v[0] * v[0] + v[1] * v[1]) + (v[2] * v[2] + v[3] * v[3]); }
; __device__ __forceinline__ u32x4 pack8(f32x4 a, f32x4 b) { u32x4 w; w.x = cvt_pk_bf16(a[0], a[1]); w.y = cvt_pk_bf16(a[2], a[3]); w.z = cvt_pk_bf16(b[0], b[1]); w.w = cvt_pk_bf16(b[2], b[3]); return w; }
;     __device__ __forceinline__ void operator()(const f32x4 (&acc)[2][2][4][2], const Unit& u, int wr, int wc, int fr, int fq) const {
;     ...
;             for (int m = 0; m < 4; ++m) {
;                 const int row = u.pm * BM + ai * HALF + wr * 64 + m * 16 + fr;
;                 float q = 0.f;
; #pragma unroll
;                 for (int bj = 0; bj < 2; ++bj) {
;                     const size_t off = (size_t)row * 1024 + col0 + 128 * bj; const u32x4 w = bs[m][bj];
;                     const f32x4 b0 = (f32x4){__builtin_bit_cast(float, w.x << 16), __builtin_bit_cast(float, w.x & 0xffff0000u), __builtin_bit_cast(float, w.y << 16), __builtin_bit_cast(float, w.y & 0xffff0000u)};
;                     const f32x4 b1 = (f32x4){__builtin_bit_cast(float, w.z << 16), __builtin_bit_cast(float, w.z & 0xffff0000u), __builtin_bit_cast(float, w.w << 16), __builtin_bit_cast(float, w.w & 0xffff0000u)};
;                     const f32x4 v0 = acc[ai][bj][m][0] + b0, v1 = acc[ai][bj][m][1] + b1;
;                     if (last) { __builtin_nontemporal_store(v0, (f32x4*)(out + off)); __builtin_nontemporal_store(v1, (f32x4*)(out + off + 4)); }
;                     else { q += sq4(v0) + sq4(v1); *(u32x4*)(xb + off) = pack8(v0, v1); }
;                 }
;                 if (!last) { q += shx(q, 16); q += shx(q, 32); if (fq == 0) ss[(size_t)row * 16 + u.pn * 4 + wc] = q; }
.LBB0_917:
	s_or_b64 exec, exec, s[56:57]
	v_lshlrev_b32_e32 v112, 16, v148
	s_waitcnt lgkmcnt(0)
	v_and_b32_e32 v113, 0xffff0000, v148
	v_lshlrev_b32_e32 v114, 16, v149
	v_and_b32_e32 v115, 0xffff0000, v149
	v_lshlrev_b32_e32 v116, 16, v150
	v_and_b32_e32 v117, 0xffff0000, v150
	v_lshlrev_b32_e32 v118, 16, v151
	v_and_b32_e32 v119, 0xffff0000, v151
	v_pk_add_f32 v[110:111], v[110:111], v[114:115]
	v_pk_add_f32 v[108:109], v[108:109], v[112:113]
	v_pk_add_f32 v[112:113], v[106:107], v[118:119]
	v_pk_add_f32 v[106:107], v[104:105], v[116:117]
	v_mul_f32_e32 v104, v109, v109
	v_mul_f32_e32 v105, v111, v111
	v_fmac_f32_e32 v104, v108, v108
	v_fmac_f32_e32 v105, v110, v110
	v_add_f32_e32 v104, v104, v105
	v_mul_f32_e32 v105, v107, v107
	v_mul_f32_e32 v114, v113, v113
	v_fmac_f32_e32 v105, v106, v106
	v_fmac_f32_e32 v114, v112, v112
	v_add_f32_e32 v105, v105, v114
	v_add_f32_e32 v114, v104, v105
	v_cvt_pk_bf16_f32 v104, v108, v109
	v_lshl_add_u64 v[108:109], s[22:23], 0, v[184:185]
	v_cvt_pk_bf16_f32 v105, v110, v111
	v_cvt_pk_bf16_f32 v106, v106, v107
	v_cvt_pk_bf16_f32 v107, v112, v113
	v_lshl_add_u64 v[108:109], v[168:169], 1, v[108:109]
	global_store_dwordx4 v[108:109], v[104:107], off
	v_lshlrev_b32_e32 v110, 16, v146
	v_and_b32_e32 v111, 0xffff0000, v146
	v_lshlrev_b32_e32 v104, 16, v144
	v_and_b32_e32 v105, 0xffff0000, v144
	v_lshlrev_b32_e32 v106, 16, v145
	v_and_b32_e32 v107, 0xffff0000, v145
	v_lshlrev_b32_e32 v112, 16, v147
	v_and_b32_e32 v113, 0xffff0000, v147
	v_pk_add_f32 v[102:103], v[102:103], v[106:107]
	v_pk_add_f32 v[100:101], v[100:101], v[104:105]
	v_pk_add_f32 v[104:105], v[98:99], v[112:113]
	v_pk_add_f32 v[98:99], v[96:97], v[110:111]
	v_mul_f32_e32 v96, v101, v101
	v_mul_f32_e32 v97, v103, v103
	v_fmac_f32_e32 v96, v100, v100
	v_fmac_f32_e32 v97, v102, v102
	v_add_f32_e32 v96, v96, v97
	v_mul_f32_e32 v97, v99, v99
	v_mul_f32_e32 v106, v105, v105
	v_fmac_f32_e32 v97, v98, v98
	v_fmac_f32_e32 v106, v104, v104
	v_add_f32_e32 v97, v97, v106
	v_add_f32_e32 v96, v96, v97
	v_add_f32_e32 v106, v114, v96
	v_cvt_pk_bf16_f32 v96, v100, v101
	v_cvt_pk_bf16_f32 v97, v102, v103
	v_cvt_pk_bf16_f32 v98, v98, v99
	v_cvt_pk_bf16_f32 v99, v104, v105
	global_store_dwordx4 v[108:109], v[96:99], off offset:256
	s_nop 1
	v_mov_b32_e32 v96, v201
	v_mov_b32_e32 v97, v201
	v_lshlrev_b32_e32 v96, 2, v96
	v_xor_b32_e32 v96, 64, v96
	v_mov_b32_e32 v96, v106
	s_nop 1
	v_permlane16_swap_b32_e32 v96, v106
	s_waitcnt lgkmcnt(0)
	v_add_f32_e32 v96, v106, v96
	v_lshlrev_b32_e32 v97, 2, v97
	v_xor_b32_e32 v97, 0x80, v97
	v_mov_b32_e32 v97, v96
	s_nop 1
	v_permlane32_swap_b32_e32 v97, v96
	s_and_saveexec_b64 s[56:57], s[12:13]
	s_cbranch_execz .LBB0_919
	s_waitcnt lgkmcnt(0)
	v_add_f32_e32 v98, v96, v97
	v_lshlrev_b64 v[96:97], 6, v[182:183]
	v_lshl_add_u64 v[96:97], s[24:25], 0, v[96:97]
	v_lshl_add_u64 v[96:97], s[54:55], 2, v[96:97]
	s_lshl_b32 s18, s67, 2
	v_lshl_add_u64 v[96:97], v[96:97], 0, s[18:19]
	global_store_dword v[96:97], v98, off
.LBB0_919:
	s_or_b64 exec, exec, s[56:57]
	v_lshlrev_b32_e32 v96, 16, v140
	s_waitcnt lgkmcnt(0)
	v_and_b32_e32 v97, 0xffff0000, v140
	v_lshlrev_b32_e32 v98, 16, v141
	v_and_b32_e32 v99, 0xffff0000, v141
	v_lshlrev_b32_e32 v100, 16, v142
	v_and_b32_e32 v101, 0xffff0000, v142
	v_lshlrev_b32_e32 v102, 16, v143
	v_and_b32_e32 v103, 0xffff0000, v143
	v_pk_add_f32 v[94:95], v[94:95], v[98:99]
	v_pk_add_f32 v[92:93], v[92:93], v[96:97]
	v_pk_add_f32 v[96:97], v[90:91], v[102:103]
	v_pk_add_f32 v[90:91], v[88:89], v[100:101]
	v_mul_f32_e32 v88, v93, v93
	v_mul_f32_e32 v89, v95, v95
	v_fmac_f32_e32 v88, v92, v92
	v_fmac_f32_e32 v89, v94, v94
	v_add_f32_e32 v88, v88, v89
	v_mul_f32_e32 v89, v91, v91
	v_mul_f32_e32 v98, v97, v97
	v_fmac_f32_e32 v89, v90, v90
	v_fmac_f32_e32 v98, v96, v96
	v_add_f32_e32 v89, v89, v98
	v_add_f32_e32 v98, v88, v89
	v_cvt_pk_bf16_f32 v88, v92, v93
	v_lshl_add_u64 v[92:93], s[22:23], 0, v[180:181]
	v_cvt_pk_bf16_f32 v89, v94, v95
	v_cvt_pk_bf16_f32 v90, v90, v91
	v_cvt_pk_bf16_f32 v91, v96, v97
	v_lshl_add_u64 v[92:93], v[168:169], 1, v[92:93]
	global_store_dwordx4 v[92:93], v[88:91], off
	v_lshlrev_b32_e32 v94, 16, v138
	v_and_b32_e32 v95, 0xffff0000, v138
	v_lshlrev_b32_e32 v88, 16, v136
	v_and_b32_e32 v89, 0xffff0000, v136
	v_lshlrev_b32_e32 v90, 16, v137
	v_and_b32_e32 v91, 0xffff0000, v137
	v_lshlrev_b32_e32 v96, 16, v139
	v_and_b32_e32 v97, 0xffff0000, v139
	v_pk_add_f32 v[86:87], v[86:87], v[90:91]
	v_pk_add_f32 v[84:85], v[84:85], v[88:89]
	v_pk_add_f32 v[88:89], v[82:83], v[96:97]
	v_pk_add_f32 v[82:83], v[80:81], v[94:95]
	v_mul_f32_e32 v80, v85, v85
	v_mul_f32_e32 v81, v87, v87
	v_fmac_f32_e32 v80, v84, v84
	v_fmac_f32_e32 v81, v86, v86
	v_add_f32_e32 v80, v80, v81
	v_mul_f32_e32 v81, v83, v83
	v_mul_f32_e32 v90, v89, v89
	v_fmac_f32_e32 v81, v82, v82
	v_fmac_f32_e32 v90, v88, v88
	v_add_f32_e32 v81, v81, v90
	v_add_f32_e32 v80, v80, v81
	v_add_f32_e32 v90, v98, v80
	v_cvt_pk_bf16_f32 v80, v84, v85
	v_cvt_pk_bf16_f32 v81, v86, v87
	v_cvt_pk_bf16_f32 v82, v82, v83
	v_cvt_pk_bf16_f32 v83, v88, v89
	global_store_dwordx4 v[92:93], v[80:83], off offset:256
	s_nop 1
	v_mov_b32_e32 v80, v201
	v_mov_b32_e32 v81, v201
	v_lshlrev_b32_e32 v80, 2, v80
	v_xor_b32_e32 v80, 64, v80
	v_mov_b32_e32 v80, v90
	s_nop 1
	v_permlane16_swap_b32_e32 v80, v90
	s_waitcnt lgkmcnt(0)
	v_add_f32_e32 v80, v90, v80
	v_lshlrev_b32_e32 v81, 2, v81
	v_xor_b32_e32 v81, 0x80, v81
	v_mov_b32_e32 v81, v80
	s_nop 1
	v_permlane32_swap_b32_e32 v81, v80
	s_and_saveexec_b64 s[56:57], s[12:13]
	s_cbranch_execz .LBB0_921
	s_waitcnt lgkmcnt(0)
	v_add_f32_e32 v82, v80, v81
	v_lshlrev_b64 v[80:81], 6, v[178:179]
	v_lshl_add_u64 v[80:81], s[24:25], 0, v[80:81]
	v_lshl_add_u64 v[80:81], s[54:55], 2, v[80:81]
	s_lshl_b32 s18, s67, 2
	v_lshl_add_u64 v[80:81], v[80:81], 0, s[18:19]
	global_store_dword v[80:81], v82, off
; __device__ __forceinline__ float sq4(f32x4 v) { return (v[0] * v[0] + v[1] * v[1]) + (v[2] * v[2] + v[3] * v[3]); }
; __device__ __forceinline__ u32x4 pack8(f32x4 a, f32x4 b) { u32x4 w; w.x = cvt_pk_bf16(a[0], a[1]); w.y = cvt_pk_bf16(a[2], a[3]); w.z = cvt_pk_bf16(b[0], b[1]); w.w = cvt_pk_bf16(b[2], b[3]); return w; }
;     __device__ __forceinline__ void operator()(const f32x4 (&acc)[2][2][4][2], const Unit& u, int wr, int wc, int fr, int fq) const {
;     ...
;         for (int ai = 0; ai < 2; ++ai) {
;             u32x4 bs[4][2];
; #pragma unroll
;             for (int m = 0; m < 4; ++m)
; #pragma unroll
;                 for (int bj = 0; bj < 2; ++bj) bs[m][bj] = *(const u32x4*)(xb + (size_t)(u.pm * BM + ai * HALF + wr * 64 + m * 16 + fr) * 1024 + col0 + 128 * bj);
; #pragma unroll
;             for (int m = 0; m < 4; ++m) {
;                 const int row = u.pm * BM + ai * HALF + wr * 64 + m * 16 + fr;
;                 float q = 0.f;
; #pragma unroll
;                 for (int bj = 0; bj < 2; ++bj) {
;                     const size_t off = (size_t)row * 1024 + col0 + 128 * bj; const u32x4 w = bs[m][bj];
;                     const f32x4 b0 = (f32x4){__builtin_bit_cast(float, w.x << 16), __builtin_bit_cast(float, w.x & 0xffff0000u), __builtin_bit_cast(float, w.y << 16), __builtin_bit_cast(float, w.y & 0xffff0000u)};
;                     const f32x4 b1 = (f32x4){__builtin_bit_cast(float, w.z << 16), __builtin_bit_cast(float, w.z & 0xffff0000u), __builtin_bit_cast(float, w.w << 16), __builtin_bit_cast(float, w.w & 0xffff0000u)};
;                     const f32x4 v0 = acc[ai][bj][m][0] + b0, v1 = acc[ai][bj][m][1] + b1;
;                     if (last) { __builtin_nontemporal_store(v0, (f32x4*)(out + off)); __builtin_nontemporal_store(v1, (f32x4*)(out + off + 4)); }
;                     else { q += sq4(v0) + sq4(v1); *(u32x4*)(xb + off) = pack8(v0, v1); }
;                 }
;                 if (!last) { q += shx(q, 16); q += shx(q, 32); if (fq == 0) ss[(size_t)row * 16 + u.pn * 4 + wc] = q; }
.LBB0_921:
	s_or_b64 exec, exec, s[56:57]
	v_lshlrev_b32_e32 v80, 16, v132
	s_waitcnt lgkmcnt(0)
	v_and_b32_e32 v81, 0xffff0000, v132
	v_lshlrev_b32_e32 v82, 16, v133
	v_and_b32_e32 v83, 0xffff0000, v133
	v_lshlrev_b32_e32 v84, 16, v134
	v_and_b32_e32 v85, 0xffff0000, v134
	v_lshlrev_b32_e32 v86, 16, v135
	v_and_b32_e32 v87, 0xffff0000, v135
	v_pk_add_f32 v[78:79], v[78:79], v[82:83]
	v_pk_add_f32 v[76:77], v[76:77], v[80:81]
	v_pk_add_f32 v[80:81], v[74:75], v[86:87]
	v_pk_add_f32 v[74:75], v[72:73], v[84:85]
	v_mul_f32_e32 v72, v77, v77
	v_mul_f32_e32 v73, v79, v79
	v_fmac_f32_e32 v72, v76, v76
	v_fmac_f32_e32 v73, v78, v78
	v_add_f32_e32 v72, v72, v73
	v_mul_f32_e32 v73, v75, v75
	v_mul_f32_e32 v82, v81, v81
	v_fmac_f32_e32 v73, v74, v74
	v_fmac_f32_e32 v82, v80, v80
	v_add_f32_e32 v73, v73, v82
	v_add_f32_e32 v82, v72, v73
	v_cvt_pk_bf16_f32 v72, v76, v77
	v_lshl_add_u64 v[76:77], s[22:23], 0, v[176:177]
	v_cvt_pk_bf16_f32 v73, v78, v79
	v_cvt_pk_bf16_f32 v74, v74, v75
	v_cvt_pk_bf16_f32 v75, v80, v81
	v_lshl_add_u64 v[76:77], v[168:169], 1, v[76:77]
	global_store_dwordx4 v[76:77], v[72:75], off
	v_lshlrev_b32_e32 v78, 16, v122
	v_and_b32_e32 v79, 0xffff0000, v122
	v_lshlrev_b32_e32 v72, 16, v120
	v_and_b32_e32 v73, 0xffff0000, v120
	v_lshlrev_b32_e32 v74, 16, v121
	v_and_b32_e32 v75, 0xffff0000, v121
	v_lshlrev_b32_e32 v80, 16, v123
	v_and_b32_e32 v81, 0xffff0000, v123
	v_pk_add_f32 v[70:71], v[70:71], v[74:75]
	v_pk_add_f32 v[68:69], v[68:69], v[72:73]
	v_pk_add_f32 v[72:73], v[66:67], v[80:81]
	v_pk_add_f32 v[66:67], v[64:65], v[78:79]
	v_mul_f32_e32 v64, v69, v69
	v_mul_f32_e32 v65, v71, v71
	v_fmac_f32_e32 v64, v68, v68
	v_fmac_f32_e32 v65, v70, v70
	v_add_f32_e32 v64, v64, v65
	v_mul_f32_e32 v65, v67, v67
	v_mul_f32_e32 v74, v73, v73
	v_fmac_f32_e32 v65, v66, v66
	v_fmac_f32_e32 v74, v72, v72
	v_add_f32_e32 v65, v65, v74
	v_add_f32_e32 v64, v64, v65
	v_add_f32_e32 v74, v82, v64
	v_cvt_pk_bf16_f32 v64, v68, v69
	v_cvt_pk_bf16_f32 v65, v70, v71
	v_cvt_pk_bf16_f32 v66, v66, v67
	v_cvt_pk_bf16_f32 v67, v72, v73
	global_store_dwordx4 v[76:77], v[64:67], off offset:256
	s_nop 1
	v_mov_b32_e32 v64, v201
	v_mov_b32_e32 v65, v201
	v_lshlrev_b32_e32 v64, 2, v64
	v_xor_b32_e32 v64, 64, v64
	v_mov_b32_e32 v64, v74
	s_nop 1
	v_permlane16_swap_b32_e32 v64, v74
	s_waitcnt lgkmcnt(0)
	v_add_f32_e32 v64, v74, v64
	v_lshlrev_b32_e32 v65, 2, v65
	v_xor_b32_e32 v65, 0x80, v65
	v_mov_b32_e32 v65, v64
	s_nop 1
	v_permlane32_swap_b32_e32 v65, v64
	s_and_saveexec_b64 s[56:57], s[12:13]
	s_cbranch_execz .LBB0_923
	s_waitcnt lgkmcnt(0)
	v_add_f32_e32 v66, v64, v65
	v_lshlrev_b64 v[64:65], 6, v[174:175]
	v_lshl_add_u64 v[64:65], s[24:25], 0, v[64:65]
	v_lshl_add_u64 v[64:65], s[54:55], 2, v[64:65]
	s_lshl_b32 s18, s67, 2
	v_lshl_add_u64 v[64:65], v[64:65], 0, s[18:19]
	global_store_dword v[64:65], v66, off
.LBB0_923:
	s_or_b64 exec, exec, s[56:57]
	v_add_u32_e32 v100, 0x80, v172
	v_ashrrev_i32_e32 v101, 31, v100
	v_lshlrev_b64 v[110:111], 11, v[100:101]
	s_waitcnt lgkmcnt(0)
	v_lshl_add_u64 v[64:65], v[170:171], 0, v[110:111]
	global_load_dwordx4 v[102:105], v[64:65], off
	global_load_dwordx4 v[106:109], v[64:65], off offset:256
	v_add_u32_e32 v96, 0x90, v172
	v_ashrrev_i32_e32 v97, 31, v96
	v_add_u32_e32 v92, 0xa0, v172
	v_lshlrev_b64 v[98:99], 11, v[96:97]
	v_ashrrev_i32_e32 v93, 31, v92
	v_add_u32_e32 v88, 0xb0, v172
	v_lshl_add_u64 v[64:65], v[170:171], 0, v[98:99]
	v_lshlrev_b64 v[94:95], 11, v[92:93]
	v_ashrrev_i32_e32 v89, 31, v88
	global_load_dwordx4 v[84:87], v[64:65], off
	global_load_dwordx4 v[80:83], v[64:65], off offset:256
	v_lshl_add_u64 v[64:65], v[170:171], 0, v[94:95]
	v_lshlrev_b64 v[90:91], 11, v[88:89]
	global_load_dwordx4 v[76:79], v[64:65], off
	global_load_dwordx4 v[72:75], v[64:65], off offset:256
	v_lshl_add_u64 v[64:65], v[170:171], 0, v[90:91]
	global_load_dwordx4 v[68:71], v[64:65], off
	s_nop 0
	global_load_dwordx4 v[64:67], v[64:65], off offset:256
	s_waitcnt vmcnt(7)
	v_lshlrev_b32_e32 v112, 16, v102
	v_and_b32_e32 v113, 0xffff0000, v102
	v_lshlrev_b32_e32 v102, 16, v103
	v_and_b32_e32 v103, 0xffff0000, v103
	v_lshlrev_b32_e32 v114, 16, v104
	v_and_b32_e32 v115, 0xffff0000, v104
	v_lshlrev_b32_e32 v104, 16, v105
	v_and_b32_e32 v105, 0xffff0000, v105
	v_pk_add_f32 v[62:63], v[62:63], v[102:103]
	v_pk_add_f32 v[60:61], v[60:61], v[112:113]
	v_pk_add_f32 v[102:103], v[58:59], v[104:105]
	v_pk_add_f32 v[58:59], v[56:57], v[114:115]
	v_mul_f32_e32 v56, v61, v61
	v_mul_f32_e32 v57, v63, v63
	v_fmac_f32_e32 v56, v60, v60
	v_fmac_f32_e32 v57, v62, v62
	v_add_f32_e32 v56, v56, v57
	v_mul_f32_e32 v57, v59, v59
	v_mul_f32_e32 v104, v103, v103
	v_fmac_f32_e32 v57, v58, v58
	v_fmac_f32_e32 v104, v102, v102
	v_add_f32_e32 v57, v57, v104
	v_add_f32_e32 v104, v56, v57
	v_cvt_pk_bf16_f32 v56, v60, v61
	v_lshl_add_u64 v[60:61], s[22:23], 0, v[110:111]
	v_cvt_pk_bf16_f32 v57, v62, v63
	v_cvt_pk_bf16_f32 v58, v58, v59
	v_cvt_pk_bf16_f32 v59, v102, v103
	v_lshl_add_u64 v[60:61], v[168:169], 1, v[60:61]
	global_store_dwordx4 v[60:61], v[56:59], off
	s_waitcnt vmcnt(7)
	v_lshlrev_b32_e32 v62, 16, v108
	v_and_b32_e32 v63, 0xffff0000, v108
	v_lshlrev_b32_e32 v56, 16, v106
	v_and_b32_e32 v57, 0xffff0000, v106
	v_lshlrev_b32_e32 v58, 16, v107
	v_and_b32_e32 v59, 0xffff0000, v107
	v_lshlrev_b32_e32 v102, 16, v109
	v_and_b32_e32 v103, 0xffff0000, v109
	v_pk_add_f32 v[54:55], v[54:55], v[58:59]
	v_pk_add_f32 v[52:53], v[52:53], v[56:57]
	v_pk_add_f32 v[56:57], v[50:51], v[102:103]
	v_pk_add_f32 v[50:51], v[48:49], v[62:63]
	v_mul_f32_e32 v48, v53, v53
	v_mul_f32_e32 v49, v55, v55
	v_fmac_f32_e32 v48, v52, v52
	v_fmac_f32_e32 v49, v54, v54
	v_add_f32_e32 v48, v48, v49
	v_mul_f32_e32 v49, v51, v51
	v_mul_f32_e32 v58, v57, v57
	v_fmac_f32_e32 v49, v50, v50
	v_fmac_f32_e32 v58, v56, v56
	v_add_f32_e32 v49, v49, v58
	v_add_f32_e32 v48, v48, v49
	v_add_f32_e32 v58, v104, v48
	v_cvt_pk_bf16_f32 v48, v52, v53
	v_cvt_pk_bf16_f32 v49, v54, v55
	v_cvt_pk_bf16_f32 v50, v50, v51
	v_cvt_pk_bf16_f32 v51, v56, v57
	global_store_dwordx4 v[60:61], v[48:51], off offset:256
	s_nop 1
	v_mov_b32_e32 v48, v201
	v_mov_b32_e32 v49, v201
	v_lshlrev_b32_e32 v48, 2, v48
	v_xor_b32_e32 v48, 64, v48
	v_mov_b32_e32 v48, v58
	s_nop 1
	v_permlane16_swap_b32_e32 v48, v58
	s_waitcnt lgkmcnt(0)
	v_add_f32_e32 v48, v58, v48
	v_lshlrev_b32_e32 v49, 2, v49
	v_xor_b32_e32 v49, 0x80, v49
	v_mov_b32_e32 v49, v48
	s_nop 1
	v_permlane32_swap_b32_e32 v49, v48
	s_and_saveexec_b64 s[56:57], s[12:13]
	s_cbranch_execz .LBB0_925
	s_waitcnt lgkmcnt(0)
	v_add_f32_e32 v50, v48, v49
	v_lshlrev_b64 v[48:49], 6, v[100:101]
	v_lshl_add_u64 v[48:49], s[24:25], 0, v[48:49]
	v_lshl_add_u64 v[48:49], s[54:55], 2, v[48:49]
	s_lshl_b32 s18, s67, 2
	v_lshl_add_u64 v[48:49], v[48:49], 0, s[18:19]
	global_store_dword v[48:49], v50, off
; __device__ __forceinline__ float sq4(f32x4 v) { return (v[0] * v[0] + v[1] * v[1]) + (v[2] * v[2] + v[3] * v[3]); }
; __device__ __forceinline__ u32x4 pack8(f32x4 a, f32x4 b) { u32x4 w; w.x = cvt_pk_bf16(a[0], a[1]); w.y = cvt_pk_bf16(a[2], a[3]); w.z = cvt_pk_bf16(b[0], b[1]); w.w = cvt_pk_bf16(b[2], b[3]); return w; }
;     __device__ __forceinline__ void operator()(const f32x4 (&acc)[2][2][4][2], const Unit& u, int wr, int wc, int fr, int fq) const {
;     ...
;             for (int m = 0; m < 4; ++m) {
;                 const int row = u.pm * BM + ai * HALF + wr * 64 + m * 16 + fr;
;                 float q = 0.f;
; #pragma unroll
;                 for (int bj = 0; bj < 2; ++bj) {
;                     const size_t off = (size_t)row * 1024 + col0 + 128 * bj; const u32x4 w = bs[m][bj];
;                     const f32x4 b0 = (f32x4){__builtin_bit_cast(float, w.x << 16), __builtin_bit_cast(float, w.x & 0xffff0000u), __builtin_bit_cast(float, w.y << 16), __builtin_bit_cast(float, w.y & 0xffff0000u)};
;                     const f32x4 b1 = (f32x4){__builtin_bit_cast(float, w.z << 16), __builtin_bit_cast(float, w.z & 0xffff0000u), __builtin_bit_cast(float, w.w << 16), __builtin_bit_cast(float, w.w & 0xffff0000u)};
;                     const f32x4 v0 = acc[ai][bj][m][0] + b0, v1 = acc[ai][bj][m][1] + b1;
;                     if (last) { __builtin_nontemporal_store(v0, (f32x4*)(out + off)); __builtin_nontemporal_store(v1, (f32x4*)(out + off + 4)); }
;                     else { q += sq4(v0) + sq4(v1); *(u32x4*)(xb + off) = pack8(v0, v1); }
;                 }
;                 if (!last) { q += shx(q, 16); q += shx(q, 32); if (fq == 0) ss[(size_t)row * 16 + u.pn * 4 + wc] = q; }
.LBB0_925:
	s_or_b64 exec, exec, s[56:57]
	s_waitcnt vmcnt(7)
	v_lshlrev_b32_e32 v48, 16, v84
	s_waitcnt lgkmcnt(0)
	v_and_b32_e32 v49, 0xffff0000, v84
	v_lshlrev_b32_e32 v50, 16, v85
	v_and_b32_e32 v51, 0xffff0000, v85
	v_lshlrev_b32_e32 v52, 16, v86
	v_and_b32_e32 v53, 0xffff0000, v86
	v_lshlrev_b32_e32 v54, 16, v87
	v_and_b32_e32 v55, 0xffff0000, v87
	v_pk_add_f32 v[46:47], v[46:47], v[50:51]
	v_pk_add_f32 v[44:45], v[44:45], v[48:49]
	v_pk_add_f32 v[48:49], v[42:43], v[54:55]
	v_pk_add_f32 v[42:43], v[40:41], v[52:53]
	v_mul_f32_e32 v40, v45, v45
	v_mul_f32_e32 v41, v47, v47
	v_fmac_f32_e32 v40, v44, v44
	v_fmac_f32_e32 v41, v46, v46
	v_add_f32_e32 v40, v40, v41
	v_mul_f32_e32 v41, v43, v43
	v_mul_f32_e32 v50, v49, v49
	v_fmac_f32_e32 v41, v42, v42
	v_fmac_f32_e32 v50, v48, v48
	v_add_f32_e32 v41, v41, v50
	v_add_f32_e32 v50, v40, v41
	v_cvt_pk_bf16_f32 v40, v44, v45
	v_lshl_add_u64 v[44:45], s[22:23], 0, v[98:99]
	v_cvt_pk_bf16_f32 v41, v46, v47
	v_cvt_pk_bf16_f32 v42, v42, v43
	v_cvt_pk_bf16_f32 v43, v48, v49
	v_lshl_add_u64 v[44:45], v[168:169], 1, v[44:45]
	global_store_dwordx4 v[44:45], v[40:43], off
	s_waitcnt vmcnt(7)
	v_lshlrev_b32_e32 v46, 16, v82
	v_and_b32_e32 v47, 0xffff0000, v82
	v_lshlrev_b32_e32 v40, 16, v80
	v_and_b32_e32 v41, 0xffff0000, v80
	v_lshlrev_b32_e32 v42, 16, v81
	v_and_b32_e32 v43, 0xffff0000, v81
	v_lshlrev_b32_e32 v48, 16, v83
	v_and_b32_e32 v49, 0xffff0000, v83
	v_pk_add_f32 v[38:39], v[38:39], v[42:43]
	v_pk_add_f32 v[36:37], v[36:37], v[40:41]
	v_pk_add_f32 v[40:41], v[34:35], v[48:49]
	v_pk_add_f32 v[34:35], v[32:33], v[46:47]
	v_mul_f32_e32 v32, v37, v37
	v_mul_f32_e32 v33, v39, v39
	v_fmac_f32_e32 v32, v36, v36
	v_fmac_f32_e32 v33, v38, v38
	v_add_f32_e32 v32, v32, v33
	v_mul_f32_e32 v33, v35, v35
	v_mul_f32_e32 v42, v41, v41
	v_fmac_f32_e32 v33, v34, v34
	v_fmac_f32_e32 v42, v40, v40
	v_add_f32_e32 v33, v33, v42
	v_add_f32_e32 v32, v32, v33
	v_add_f32_e32 v42, v50, v32
	v_cvt_pk_bf16_f32 v32, v36, v37
	v_cvt_pk_bf16_f32 v33, v38, v39
	v_cvt_pk_bf16_f32 v34, v34, v35
	v_cvt_pk_bf16_f32 v35, v40, v41
	global_store_dwordx4 v[44:45], v[32:35], off offset:256
	s_nop 1
	v_mov_b32_e32 v32, v201
	v_mov_b32_e32 v33, v201
	v_lshlrev_b32_e32 v32, 2, v32
	v_xor_b32_e32 v32, 64, v32
	v_mov_b32_e32 v32, v42
	s_nop 1
	v_permlane16_swap_b32_e32 v32, v42
	s_waitcnt lgkmcnt(0)
	v_add_f32_e32 v32, v42, v32
	v_lshlrev_b32_e32 v33, 2, v33
	v_xor_b32_e32 v33, 0x80, v33
	v_mov_b32_e32 v33, v32
	s_nop 1
	v_permlane32_swap_b32_e32 v33, v32
	s_and_saveexec_b64 s[56:57], s[12:13]
	s_cbranch_execz .LBB0_927
	s_waitcnt lgkmcnt(0)
	v_add_f32_e32 v34, v32, v33
	v_lshlrev_b64 v[32:33], 6, v[96:97]
	v_lshl_add_u64 v[32:33], s[24:25], 0, v[32:33]
	v_lshl_add_u64 v[32:33], s[54:55], 2, v[32:33]
	s_lshl_b32 s18, s67, 2
	v_lshl_add_u64 v[32:33], v[32:33], 0, s[18:19]
	global_store_dword v[32:33], v34, off
; __device__ __forceinline__ float sq4(f32x4 v) { return (v[0] * v[0] + v[1] * v[1]) + (v[2] * v[2] + v[3] * v[3]); }
; __device__ __forceinline__ u32x4 pack8(f32x4 a, f32x4 b) { u32x4 w; w.x = cvt_pk_bf16(a[0], a[1]); w.y = cvt_pk_bf16(a[2], a[3]); w.z = cvt_pk_bf16(b[0], b[1]); w.w = cvt_pk_bf16(b[2], b[3]); return w; }
;     __device__ __forceinline__ void operator()(const f32x4 (&acc)[2][2][4][2], const Unit& u, int wr, int wc, int fr, int fq) const {
;     ...
;             for (int m = 0; m < 4; ++m) {
;                 const int row = u.pm * BM + ai * HALF + wr * 64 + m * 16 + fr;
;                 float q = 0.f;
; #pragma unroll
;                 for (int bj = 0; bj < 2; ++bj) {
;                     const size_t off = (size_t)row * 1024 + col0 + 128 * bj; const u32x4 w = bs[m][bj];
;                     const f32x4 b0 = (f32x4){__builtin_bit_cast(float, w.x << 16), __builtin_bit_cast(float, w.x & 0xffff0000u), __builtin_bit_cast(float, w.y << 16), __builtin_bit_cast(float, w.y & 0xffff0000u)};
;                     const f32x4 b1 = (f32x4){__builtin_bit_cast(float, w.z << 16), __builtin_bit_cast(float, w.z & 0xffff0000u), __builtin_bit_cast(float, w.w << 16), __builtin_bit_cast(float, w.w & 0xffff0000u)};
;                     const f32x4 v0 = acc[ai][bj][m][0] + b0, v1 = acc[ai][bj][m][1] + b1;
;                     if (last) { __builtin_nontemporal_store(v0, (f32x4*)(out + off)); __builtin_nontemporal_store(v1, (f32x4*)(out + off + 4)); }
;                     else { q += sq4(v0) + sq4(v1); *(u32x4*)(xb + off) = pack8(v0, v1); }
;                 }
;                 if (!last) { q += shx(q, 16); q += shx(q, 32); if (fq == 0) ss[(size_t)row * 16 + u.pn * 4 + wc] = q; }
.LBB0_927:
	s_or_b64 exec, exec, s[56:57]
	s_waitcnt vmcnt(7)
	v_lshlrev_b32_e32 v32, 16, v76
	s_waitcnt lgkmcnt(0)
	v_and_b32_e32 v33, 0xffff0000, v76
	v_lshlrev_b32_e32 v34, 16, v77
	v_and_b32_e32 v35, 0xffff0000, v77
	v_lshlrev_b32_e32 v36, 16, v78
	v_and_b32_e32 v37, 0xffff0000, v78
	v_lshlrev_b32_e32 v38, 16, v79
	v_and_b32_e32 v39, 0xffff0000, v79
	v_pk_add_f32 v[30:31], v[30:31], v[34:35]
	v_pk_add_f32 v[28:29], v[28:29], v[32:33]
	v_pk_add_f32 v[32:33], v[26:27], v[38:39]
	v_pk_add_f32 v[26:27], v[24:25], v[36:37]
	v_mul_f32_e32 v24, v29, v29
	v_mul_f32_e32 v25, v31, v31
	v_fmac_f32_e32 v24, v28, v28
	v_fmac_f32_e32 v25, v30, v30
	v_add_f32_e32 v24, v24, v25
	v_mul_f32_e32 v25, v27, v27
	v_mul_f32_e32 v34, v33, v33
	v_fmac_f32_e32 v25, v26, v26
	v_fmac_f32_e32 v34, v32, v32
	v_add_f32_e32 v25, v25, v34
	v_add_f32_e32 v34, v24, v25
	v_cvt_pk_bf16_f32 v24, v28, v29
	v_lshl_add_u64 v[28:29], s[22:23], 0, v[94:95]
	v_cvt_pk_bf16_f32 v25, v30, v31
	v_cvt_pk_bf16_f32 v26, v26, v27
	v_cvt_pk_bf16_f32 v27, v32, v33
	v_lshl_add_u64 v[28:29], v[168:169], 1, v[28:29]
	global_store_dwordx4 v[28:29], v[24:27], off
	s_waitcnt vmcnt(7)
	v_lshlrev_b32_e32 v30, 16, v74
	v_and_b32_e32 v31, 0xffff0000, v74
	v_lshlrev_b32_e32 v24, 16, v72
	v_and_b32_e32 v25, 0xffff0000, v72
	v_lshlrev_b32_e32 v26, 16, v73
	v_and_b32_e32 v27, 0xffff0000, v73
	v_lshlrev_b32_e32 v32, 16, v75
	v_and_b32_e32 v33, 0xffff0000, v75
	v_pk_add_f32 v[22:23], v[22:23], v[26:27]
	v_pk_add_f32 v[20:21], v[20:21], v[24:25]
	v_pk_add_f32 v[24:25], v[18:19], v[32:33]
	v_pk_add_f32 v[18:19], v[16:17], v[30:31]
	v_mul_f32_e32 v16, v21, v21
	v_mul_f32_e32 v17, v23, v23
	v_fmac_f32_e32 v16, v20, v20
	v_fmac_f32_e32 v17, v22, v22
	v_add_f32_e32 v16, v16, v17
	v_mul_f32_e32 v17, v19, v19
	v_mul_f32_e32 v26, v25, v25
	v_fmac_f32_e32 v17, v18, v18
	v_fmac_f32_e32 v26, v24, v24
	v_add_f32_e32 v17, v17, v26
	v_add_f32_e32 v16, v16, v17
	v_add_f32_e32 v26, v34, v16
	v_cvt_pk_bf16_f32 v16, v20, v21
	v_cvt_pk_bf16_f32 v17, v22, v23
	v_cvt_pk_bf16_f32 v18, v18, v19
	v_cvt_pk_bf16_f32 v19, v24, v25
	global_store_dwordx4 v[28:29], v[16:19], off offset:256
	s_nop 1
	v_mov_b32_e32 v16, v201
	v_mov_b32_e32 v17, v201
	v_lshlrev_b32_e32 v16, 2, v16
	v_xor_b32_e32 v16, 64, v16
	v_mov_b32_e32 v16, v26
	s_nop 1
	v_permlane16_swap_b32_e32 v16, v26
	s_waitcnt lgkmcnt(0)
	v_add_f32_e32 v16, v26, v16
	v_lshlrev_b32_e32 v17, 2, v17
	v_xor_b32_e32 v17, 0x80, v17
	v_mov_b32_e32 v17, v16
	s_nop 1
	v_permlane32_swap_b32_e32 v17, v16
	s_and_saveexec_b64 s[56:57], s[12:13]
	s_cbranch_execz .LBB0_929
	s_waitcnt lgkmcnt(0)
	v_add_f32_e32 v18, v16, v17
	v_lshlrev_b64 v[16:17], 6, v[92:93]
	v_lshl_add_u64 v[16:17], s[24:25], 0, v[16:17]
	v_lshl_add_u64 v[16:17], s[54:55], 2, v[16:17]
	s_lshl_b32 s18, s67, 2
	v_lshl_add_u64 v[16:17], v[16:17], 0, s[18:19]
	global_store_dword v[16:17], v18, off
.LBB0_929:
	s_or_b64 exec, exec, s[56:57]
	s_waitcnt vmcnt(7)
	v_lshlrev_b32_e32 v16, 16, v68
	s_waitcnt lgkmcnt(0)
	v_and_b32_e32 v17, 0xffff0000, v68
	v_lshlrev_b32_e32 v18, 16, v69
	v_and_b32_e32 v19, 0xffff0000, v69
	v_lshlrev_b32_e32 v20, 16, v70
	v_and_b32_e32 v21, 0xffff0000, v70
	v_lshlrev_b32_e32 v22, 16, v71
	v_and_b32_e32 v23, 0xffff0000, v71
	v_pk_add_f32 v[14:15], v[14:15], v[18:19]
	v_pk_add_f32 v[12:13], v[12:13], v[16:17]
	v_pk_add_f32 v[16:17], v[10:11], v[22:23]
	v_pk_add_f32 v[10:11], v[8:9], v[20:21]
	v_mul_f32_e32 v8, v13, v13
	v_mul_f32_e32 v9, v15, v15
	v_fmac_f32_e32 v8, v12, v12
	v_fmac_f32_e32 v9, v14, v14
	v_add_f32_e32 v8, v8, v9
	v_mul_f32_e32 v9, v11, v11
	v_mul_f32_e32 v18, v17, v17
	v_fmac_f32_e32 v9, v10, v10
	v_fmac_f32_e32 v18, v16, v16
	v_add_f32_e32 v9, v9, v18
	v_add_f32_e32 v18, v8, v9
	v_cvt_pk_bf16_f32 v8, v12, v13
	v_lshl_add_u64 v[12:13], s[22:23], 0, v[90:91]
	v_cvt_pk_bf16_f32 v9, v14, v15
	v_cvt_pk_bf16_f32 v10, v10, v11
	v_cvt_pk_bf16_f32 v11, v16, v17
	v_lshl_add_u64 v[12:13], v[168:169], 1, v[12:13]
	global_store_dwordx4 v[12:13], v[8:11], off
	s_waitcnt vmcnt(7)
	v_lshlrev_b32_e32 v14, 16, v66
	v_and_b32_e32 v15, 0xffff0000, v66
	v_lshlrev_b32_e32 v8, 16, v64
	v_and_b32_e32 v9, 0xffff0000, v64
	v_lshlrev_b32_e32 v10, 16, v65
	v_and_b32_e32 v11, 0xffff0000, v65
	v_lshlrev_b32_e32 v16, 16, v67
	v_and_b32_e32 v17, 0xffff0000, v67
	v_pk_add_f32 v[6:7], v[6:7], v[10:11]
	v_pk_add_f32 v[4:5], v[4:5], v[8:9]
	v_pk_add_f32 v[8:9], v[2:3], v[16:17]
	v_pk_add_f32 v[2:3], v[0:1], v[14:15]
	v_mul_f32_e32 v0, v5, v5
	v_mul_f32_e32 v1, v7, v7
	v_fmac_f32_e32 v0, v4, v4
	v_fmac_f32_e32 v1, v6, v6
	v_add_f32_e32 v0, v0, v1
	v_mul_f32_e32 v1, v3, v3
	v_mul_f32_e32 v10, v9, v9
	v_fmac_f32_e32 v1, v2, v2
	v_fmac_f32_e32 v10, v8, v8
	v_add_f32_e32 v1, v1, v10
	v_add_f32_e32 v0, v0, v1
	v_add_f32_e32 v10, v18, v0
	v_cvt_pk_bf16_f32 v0, v4, v5
	v_cvt_pk_bf16_f32 v1, v6, v7
	v_cvt_pk_bf16_f32 v2, v2, v3
	v_cvt_pk_bf16_f32 v3, v8, v9
	global_store_dwordx4 v[12:13], v[0:3], off offset:256
	s_nop 1
	v_mov_b32_e32 v0, v201
	v_mov_b32_e32 v1, v201
	v_lshlrev_b32_e32 v0, 2, v0
	v_xor_b32_e32 v0, 64, v0
	v_mov_b32_e32 v0, v10
	s_nop 1
	v_permlane16_swap_b32_e32 v0, v10
	s_waitcnt lgkmcnt(0)
	v_add_f32_e32 v0, v10, v0
	v_lshlrev_b32_e32 v1, 2, v1
	v_xor_b32_e32 v1, 0x80, v1
	v_mov_b32_e32 v1, v0
	s_nop 1
	v_permlane32_swap_b32_e32 v1, v0
	s_and_saveexec_b64 s[56:57], s[12:13]
	s_cbranch_execz .LBB0_931
	s_waitcnt lgkmcnt(0)
	v_add_f32_e32 v2, v0, v1
	v_lshlrev_b64 v[0:1], 6, v[88:89]
	v_lshl_add_u64 v[0:1], s[24:25], 0, v[0:1]
	v_lshl_add_u64 v[0:1], s[54:55], 2, v[0:1]
	s_lshl_b32 s18, s67, 2
	v_lshl_add_u64 v[0:1], v[0:1], 0, s[18:19]
	global_store_dword v[0:1], v2, off

; __device__ __forceinline__ float row_part(const float* ss, int row, int fq) { const f32x4 a = ((const f32x4*)(ss + (size_t)row * 16))[fq]; return (a[0] + a[1]) + (a[2] + a[3]); }
; __device__ __forceinline__ float row_finish(float t) { t += shx(t, 16); t += shx(t, 32); return __builtin_amdgcn_rsqf(t * (1.0f / 1024.0f) + RMS_EPS); }
;     __device__ __forceinline__ void operator()(const f32x4 (&acc)[2][2][4][2], const Unit& u, int wr, int wc, int fr, int fq) const {
;     ...
;         float rs[2][4];
; #pragma unroll
;         for (int ai = 0; ai < 2; ++ai)
; #pragma unroll
;             for (int m = 0; m < 4; ++m) rs[ai][m] = row_part(ss, u.pm * BM + ai * HALF + wr * 64 + m * 16 + fr, fq);
; #pragma unroll
;         for (int ai = 0; ai < 2; ++ai)
; #pragma unroll
;             for (int m = 0; m < 4; ++m) rs[ai][m] = row_finish(rs[ai][m]);
.LBB0_999:
	v_lshl_add_u32 v168, s48, 8, v155
	v_ashrrev_i32_e32 v169, 31, v168
	v_lshlrev_b64 v[146:147], 6, v[168:169]
	v_lshl_add_u64 v[146:147], v[136:137], 0, v[146:147]
	ds_read_b128 v[146:149], v239
	v_or_b32_e32 v164, 16, v168
	v_ashrrev_i32_e32 v165, 31, v164
	v_or_b32_e32 v160, 32, v168
	v_ashrrev_i32_e32 v161, 31, v160
	v_or_b32_e32 v156, 48, v168
	v_ashrrev_i32_e32 v157, 31, v156
	v_add_u32_e32 v152, 0x80, v168
	v_ashrrev_i32_e32 v153, 31, v152
	v_mov_b32_e32 v162, v201
	s_andn2_b64 vcc, exec, s[16:17]
	s_waitcnt lgkmcnt(0)
	v_mov_b32_e32 v150, v147
	v_mov_b32_e32 v151, v148
	v_mov_b32_e32 v147, v149
	v_pk_add_f32 v[146:147], v[150:151], v[146:147]
	s_nop 0
	v_add_f32_e32 v154, v146, v147
	v_lshlrev_b64 v[146:147], 6, v[164:165]
	v_lshl_add_u64 v[146:147], v[136:137], 0, v[146:147]
	ds_read_b128 v[146:149], v239 offset:1024
	s_waitcnt lgkmcnt(0)
	v_mov_b32_e32 v150, v147
	v_mov_b32_e32 v151, v148
	v_mov_b32_e32 v147, v149
	v_pk_add_f32 v[146:147], v[150:151], v[146:147]
	s_nop 0
	v_add_f32_e32 v158, v146, v147
	v_lshlrev_b64 v[146:147], 6, v[160:161]
	v_lshl_add_u64 v[146:147], v[136:137], 0, v[146:147]
	ds_read_b128 v[146:149], v239 offset:2048
	s_waitcnt lgkmcnt(0)
	v_mov_b32_e32 v150, v147
	v_mov_b32_e32 v151, v148
	v_mov_b32_e32 v147, v149
	v_pk_add_f32 v[146:147], v[150:151], v[146:147]
	s_nop 0
	v_add_f32_e32 v161, v146, v147
	v_lshlrev_b64 v[146:147], 6, v[156:157]
	v_lshl_add_u64 v[146:147], v[136:137], 0, v[146:147]
	ds_read_b128 v[146:149], v239 offset:3072
	s_waitcnt lgkmcnt(0)
	v_mov_b32_e32 v150, v147
	v_mov_b32_e32 v151, v148
	v_mov_b32_e32 v147, v149
	v_pk_add_f32 v[146:147], v[150:151], v[146:147]
	s_nop 0
	v_add_f32_e32 v157, v146, v147
	v_lshlrev_b64 v[146:147], 6, v[152:153]
	v_lshl_add_u64 v[146:147], v[136:137], 0, v[146:147]
	ds_read_b128 v[146:149], v239 offset:8192
	s_waitcnt lgkmcnt(0)
	v_mov_b32_e32 v150, v147
	v_mov_b32_e32 v151, v148
	v_mov_b32_e32 v147, v149
	v_pk_add_f32 v[146:147], v[150:151], v[146:147]
	v_add_u32_e32 v150, 0x90, v168
	v_ashrrev_i32_e32 v151, 31, v150
	v_add_f32_e32 v153, v146, v147
	v_lshlrev_b64 v[146:147], 6, v[150:151]
	v_lshl_add_u64 v[146:147], v[136:137], 0, v[146:147]
	ds_read_b128 v[146:149], v239 offset:9216
	s_waitcnt lgkmcnt(0)
	v_mov_b32_e32 v176, v147
	v_mov_b32_e32 v177, v148
	v_mov_b32_e32 v147, v149
	v_add_u32_e32 v148, 0xa0, v168
	v_pk_add_f32 v[146:147], v[176:177], v[146:147]
	v_ashrrev_i32_e32 v149, 31, v148
	v_add_f32_e32 v151, v146, v147
	v_lshlrev_b64 v[146:147], 6, v[148:149]
	v_lshl_add_u64 v[146:147], v[136:137], 0, v[146:147]
	ds_read_b128 v[176:179], v239 offset:10240
	s_waitcnt lgkmcnt(0)
	v_mov_b32_e32 v146, v177
	v_mov_b32_e32 v147, v178
	v_mov_b32_e32 v177, v179
	v_pk_add_f32 v[146:147], v[146:147], v[176:177]
	s_nop 0
	v_add_f32_e32 v149, v146, v147
	v_add_u32_e32 v146, 0xb0, v168
	v_ashrrev_i32_e32 v147, 31, v146
	v_lshlrev_b64 v[176:177], 6, v[146:147]
	v_lshl_add_u64 v[176:177], v[136:137], 0, v[176:177]
	ds_read_b128 v[176:179], v239 offset:11264
	s_waitcnt lgkmcnt(0)
	v_mov_b32_e32 v180, v177
	v_lshlrev_b32_e32 v162, 2, v162
	v_xor_b32_e32 v162, 64, v162
	v_mov_b32_e32 v162, v154
	s_nop 1
	v_permlane16_swap_b32_e32 v162, v154
	v_mov_b32_e32 v181, v178
	v_mov_b32_e32 v177, v179
	v_pk_add_f32 v[176:177], v[180:181], v[176:177]
	v_lshl_or_b32 v178, s49, 7, v163
	s_waitcnt lgkmcnt(0)
	v_add_f32_e32 v154, v154, v162
	v_mov_b32_e32 v162, v201
	v_add_f32_e32 v147, v176, v177
	v_lshlrev_b32_e32 v162, 2, v162
	v_xor_b32_e32 v162, 0x80, v162
	v_mov_b32_e32 v162, v154
	s_nop 1
	v_permlane32_swap_b32_e32 v162, v154
	v_ashrrev_i32_e32 v179, 31, v178
	s_mov_b64 s[48:49], -1
	s_waitcnt lgkmcnt(0)
	v_add_f32_e32 v154, v154, v162
	v_fmamk_f32 v154, v154, 0x3a800000, v175
	v_rsq_f32_e32 v174, v154
	v_mov_b32_e32 v154, v201
	v_pk_mul_f32 v[124:125], v[124:125], v[174:175] op_sel_hi:[1,0]
	v_lshlrev_b32_e32 v154, 2, v154
	v_xor_b32_e32 v154, 64, v154
	v_mov_b32_e32 v154, v158
	s_nop 1
	v_permlane16_swap_b32_e32 v154, v158
	v_pk_mul_f32 v[126:127], v[126:127], v[174:175] op_sel_hi:[1,0]
	v_pk_mul_f32 v[116:117], v[116:117], v[174:175] op_sel_hi:[1,0]
	v_pk_mul_f32 v[120:121], v[120:121], v[174:175] op_sel_hi:[1,0]
	v_pk_mul_f32 v[118:119], v[118:119], v[174:175] op_sel_hi:[1,0]
	s_waitcnt lgkmcnt(0)
	v_add_f32_e32 v154, v158, v154
	v_mov_b32_e32 v158, v201
	v_pk_mul_f32 v[122:123], v[122:123], v[174:175] op_sel_hi:[1,0]
	v_lshlrev_b32_e32 v158, 2, v158
	v_xor_b32_e32 v158, 0x80, v158
	v_mov_b32_e32 v158, v154
	s_nop 1
	v_permlane32_swap_b32_e32 v158, v154
	v_pk_mul_f32 v[112:113], v[112:113], v[174:175] op_sel_hi:[1,0]
	v_pk_mul_f32 v[114:115], v[114:115], v[174:175] op_sel_hi:[1,0]
	s_waitcnt lgkmcnt(0)
	v_add_f32_e32 v154, v154, v158
	v_fmamk_f32 v154, v154, 0x3a800000, v175
	v_rsq_f32_e32 v176, v154
	v_mov_b32_e32 v154, v201
	v_mov_b32_e32 v158, v201
	v_lshlrev_b32_e32 v154, 2, v154
	v_xor_b32_e32 v154, 64, v154
	v_mov_b32_e32 v154, v161
	s_nop 1
	v_permlane16_swap_b32_e32 v154, v161
	v_pk_mul_f32 v[110:111], v[110:111], v[176:177] op_sel_hi:[1,0]
	v_lshlrev_b32_e32 v158, 2, v158
	v_xor_b32_e32 v158, 0x80, v158
	s_waitcnt lgkmcnt(0)
	v_add_f32_e32 v154, v161, v154
	v_mov_b32_e32 v158, v154
	s_nop 1
	v_permlane32_swap_b32_e32 v158, v154
	v_pk_mul_f32 v[108:109], v[108:109], v[176:177] op_sel_hi:[1,0]
	v_pk_mul_f32 v[100:101], v[100:101], v[176:177] op_sel_hi:[1,0]
	v_pk_mul_f32 v[102:103], v[102:103], v[176:177] op_sel_hi:[1,0]
	v_pk_mul_f32 v[106:107], v[106:107], v[176:177] op_sel_hi:[1,0]
	s_waitcnt lgkmcnt(0)
; __device__ __forceinline__ f32x4 silu4(f32x4 v) { return (f32x4){silu_f(v[0]), silu_f(v[1]), silu_f(v[2]), silu_f(v[3])}; }
; __device__ __forceinline__ float row_finish(float t) { t += shx(t, 16); t += shx(t, 32); return __builtin_amdgcn_rsqf(t * (1.0f / 1024.0f) + RMS_EPS); }
;     __device__ __forceinline__ void operator()(const f32x4 (&acc)[2][2][4][2], const Unit& u, int wr, int wc, int fr, int fq) const {
;     ...
;         for (int ai = 0; ai < 2; ++ai)
; #pragma unroll
;             for (int m = 0; m < 4; ++m) rs[ai][m] = row_finish(rs[ai][m]);
; #pragma unroll
;         for (int ai = 0; ai < 2; ++ai)
; #pragma unroll
;             for (int m = 0; m < 4; ++m) {
;                 const int row = u.pm * BM + ai * HALF + wr * 64 + m * 16 + fr;
;                 const float rstd = rs[ai][m];
;                 const f32x4 a0 = silu4(acc[ai][0][m][0] * rstd) * (acc[ai][1][m][0] * rstd);
;                 const f32x4 a1 = silu4(acc[ai][0][m][1] * rstd) * (acc[ai][1][m][1] * rstd);
	v_add_f32_e32 v154, v154, v158
	v_fmamk_f32 v154, v154, 0x3a800000, v175
	v_rsq_f32_e32 v172, v154
	v_mov_b32_e32 v154, v201
	v_pk_mul_f32 v[104:105], v[104:105], v[176:177] op_sel_hi:[1,0]
	v_lshlrev_b32_e32 v154, 2, v154
	v_xor_b32_e32 v154, 64, v154
	v_mov_b32_e32 v154, v157
	s_nop 1
	v_permlane16_swap_b32_e32 v154, v157
	v_pk_mul_f32 v[96:97], v[96:97], v[176:177] op_sel_hi:[1,0]
	v_pk_mul_f32 v[98:99], v[98:99], v[176:177] op_sel_hi:[1,0]
	v_pk_mul_f32 v[94:95], v[94:95], v[172:173] op_sel_hi:[1,0]
	v_pk_mul_f32 v[92:93], v[92:93], v[172:173] op_sel_hi:[1,0]
	s_waitcnt lgkmcnt(0)
	v_add_f32_e32 v154, v157, v154
	v_mov_b32_e32 v157, v201
	v_pk_mul_f32 v[84:85], v[84:85], v[172:173] op_sel_hi:[1,0]
	v_lshlrev_b32_e32 v157, 2, v157
	v_xor_b32_e32 v157, 0x80, v157
	v_mov_b32_e32 v157, v154
	s_nop 1
	v_permlane32_swap_b32_e32 v157, v154
	v_pk_mul_f32 v[86:87], v[86:87], v[172:173] op_sel_hi:[1,0]
	v_pk_mul_f32 v[90:91], v[90:91], v[172:173] op_sel_hi:[1,0]
	v_pk_mul_f32 v[88:89], v[88:89], v[172:173] op_sel_hi:[1,0]
	v_pk_mul_f32 v[80:81], v[80:81], v[172:173] op_sel_hi:[1,0]
	s_waitcnt lgkmcnt(0)
	v_add_f32_e32 v154, v154, v157
	v_fmamk_f32 v154, v154, 0x3a800000, v175
	v_rsq_f32_e32 v170, v154
	v_mov_b32_e32 v154, v201
	v_pk_mul_f32 v[82:83], v[82:83], v[172:173] op_sel_hi:[1,0]
	v_lshlrev_b32_e32 v154, 2, v154
	v_xor_b32_e32 v154, 64, v154
	v_mov_b32_e32 v154, v153
	s_nop 1
	v_permlane16_swap_b32_e32 v154, v153
	v_pk_mul_f32 v[78:79], v[78:79], v[170:171] op_sel_hi:[1,0]
	v_pk_mul_f32 v[76:77], v[76:77], v[170:171] op_sel_hi:[1,0]
	v_pk_mul_f32 v[68:69], v[68:69], v[170:171] op_sel_hi:[1,0]
	v_pk_mul_f32 v[70:71], v[70:71], v[170:171] op_sel_hi:[1,0]
	s_waitcnt lgkmcnt(0)
	v_add_f32_e32 v153, v153, v154
	v_mov_b32_e32 v154, v201
	v_pk_mul_f32 v[74:75], v[74:75], v[170:171] op_sel_hi:[1,0]
	v_lshlrev_b32_e32 v154, 2, v154
	v_xor_b32_e32 v154, 0x80, v154
	v_mov_b32_e32 v154, v153
	s_nop 1
	v_permlane32_swap_b32_e32 v154, v153
	v_pk_mul_f32 v[72:73], v[72:73], v[170:171] op_sel_hi:[1,0]
	v_pk_mul_f32 v[64:65], v[64:65], v[170:171] op_sel_hi:[1,0]
	v_pk_mul_f32 v[66:67], v[66:67], v[170:171] op_sel_hi:[1,0]
	s_waitcnt lgkmcnt(0)
	v_add_f32_e32 v153, v153, v154
	v_fmamk_f32 v153, v153, 0x3a800000, v175
	v_rsq_f32_e32 v166, v153
	v_mov_b32_e32 v153, v201
	v_pk_mul_f32 v[62:63], v[62:63], v[166:167] op_sel_hi:[1,0]
	v_lshlrev_b32_e32 v153, 2, v153
	v_xor_b32_e32 v153, 64, v153
	v_mov_b32_e32 v153, v151
	s_nop 1
	v_permlane16_swap_b32_e32 v153, v151
	v_pk_mul_f32 v[60:61], v[60:61], v[166:167] op_sel_hi:[1,0]
	v_pk_mul_f32 v[52:53], v[52:53], v[166:167] op_sel_hi:[1,0]
	v_pk_mul_f32 v[54:55], v[54:55], v[166:167] op_sel_hi:[1,0]
	v_pk_mul_f32 v[58:59], v[58:59], v[166:167] op_sel_hi:[1,0]
	s_waitcnt lgkmcnt(0)
	v_add_f32_e32 v151, v151, v153
	v_mov_b32_e32 v153, v201
	v_pk_mul_f32 v[56:57], v[56:57], v[166:167] op_sel_hi:[1,0]
	v_lshlrev_b32_e32 v153, 2, v153
	v_xor_b32_e32 v153, 0x80, v153
	v_mov_b32_e32 v153, v151
	s_nop 1
	v_permlane32_swap_b32_e32 v153, v151
	v_pk_mul_f32 v[48:49], v[48:49], v[166:167] op_sel_hi:[1,0]
	v_pk_mul_f32 v[50:51], v[50:51], v[166:167] op_sel_hi:[1,0]
	s_waitcnt lgkmcnt(0)
	v_add_f32_e32 v151, v151, v153
	v_fmamk_f32 v151, v151, 0x3a800000, v175
	v_rsq_f32_e32 v162, v151
	v_mov_b32_e32 v151, v201
	v_pk_mul_f32 v[46:47], v[46:47], v[162:163] op_sel_hi:[1,0]
	v_lshlrev_b32_e32 v151, 2, v151
	v_xor_b32_e32 v151, 64, v151
	v_mov_b32_e32 v151, v149
	s_nop 1
	v_permlane16_swap_b32_e32 v151, v149
	v_pk_mul_f32 v[44:45], v[44:45], v[162:163] op_sel_hi:[1,0]
	v_pk_mul_f32 v[36:37], v[36:37], v[162:163] op_sel_hi:[1,0]
	v_pk_mul_f32 v[38:39], v[38:39], v[162:163] op_sel_hi:[1,0]
	v_pk_mul_f32 v[42:43], v[42:43], v[162:163] op_sel_hi:[1,0]
	s_waitcnt lgkmcnt(0)
	v_add_f32_e32 v149, v149, v151
	v_mov_b32_e32 v151, v201
	v_pk_mul_f32 v[40:41], v[40:41], v[162:163] op_sel_hi:[1,0]
	v_lshlrev_b32_e32 v151, 2, v151
	v_xor_b32_e32 v151, 0x80, v151
	v_mov_b32_e32 v151, v149
	s_nop 1
	v_permlane32_swap_b32_e32 v151, v149
	v_pk_mul_f32 v[32:33], v[32:33], v[162:163] op_sel_hi:[1,0]
	v_pk_mul_f32 v[34:35], v[34:35], v[162:163] op_sel_hi:[1,0]
	s_waitcnt lgkmcnt(0)
	v_add_f32_e32 v149, v149, v151
	v_fmamk_f32 v149, v149, 0x3a800000, v175
	v_rsq_f32_e32 v158, v149
	v_mov_b32_e32 v149, v201
	v_pk_mul_f32 v[30:31], v[30:31], v[158:159] op_sel_hi:[1,0]
	v_lshlrev_b32_e32 v149, 2, v149
	v_xor_b32_e32 v149, 64, v149
	v_mov_b32_e32 v149, v147
	s_nop 1
	v_permlane16_swap_b32_e32 v149, v147
	v_pk_mul_f32 v[28:29], v[28:29], v[158:159] op_sel_hi:[1,0]
	v_pk_mul_f32 v[20:21], v[20:21], v[158:159] op_sel_hi:[1,0]
	v_pk_mul_f32 v[22:23], v[22:23], v[158:159] op_sel_hi:[1,0]
	v_pk_mul_f32 v[26:27], v[26:27], v[158:159] op_sel_hi:[1,0]
	s_waitcnt lgkmcnt(0)
	v_add_f32_e32 v147, v147, v149
	v_mov_b32_e32 v149, v201
	v_pk_mul_f32 v[24:25], v[24:25], v[158:159] op_sel_hi:[1,0]
	v_lshlrev_b32_e32 v149, 2, v149
	v_xor_b32_e32 v149, 0x80, v149
	v_mov_b32_e32 v149, v147
	s_nop 1
	v_permlane32_swap_b32_e32 v149, v147
	v_pk_mul_f32 v[16:17], v[16:17], v[158:159] op_sel_hi:[1,0]
	v_pk_mul_f32 v[18:19], v[18:19], v[158:159] op_sel_hi:[1,0]
	s_waitcnt lgkmcnt(0)
; __device__ __forceinline__ u32x4 pack8(f32x4 a, f32x4 b) { u32x4 w; w.x = cvt_pk_bf16(a[0], a[1]); w.y = cvt_pk_bf16(a[2], a[3]); w.z = cvt_pk_bf16(b[0], b[1]); w.w = cvt_pk_bf16(b[2], b[3]); return w; }
; __device__ __forceinline__ float silu_f(float v) { return v * __builtin_amdgcn_rcpf(1.0f + __builtin_amdgcn_exp2f(v * -1.4426950408889634f)); }
; __device__ __forceinline__ f32x4 silu4(f32x4 v) { return (f32x4){silu_f(v[0]), silu_f(v[1]), silu_f(v[2]), silu_f(v[3])}; }
;     __device__ __forceinline__ void operator()(const f32x4 (&acc)[2][2][4][2], const Unit& u, int wr, int wc, int fr, int fq) const {
;     ...
;         for (int ai = 0; ai < 2; ++ai)
; #pragma unroll
;             for (int m = 0; m < 4; ++m) {
;                 const int row = u.pm * BM + ai * HALF + wr * 64 + m * 16 + fr;
;                 const float rstd = rs[ai][m];
;                 const f32x4 a0 = silu4(acc[ai][0][m][0] * rstd) * (acc[ai][1][m][0] * rstd);
;                 const f32x4 a1 = silu4(acc[ai][0][m][1] * rstd) * (acc[ai][1][m][1] * rstd);
;                 *(u32x4*)(ACT + (size_t)row * 2816 + col0) = pack8(a0, a1);
	v_add_f32_e32 v147, v147, v149
	v_fmamk_f32 v147, v147, 0x3a800000, v175
	v_rsq_f32_e32 v154, v147
	v_mul_f32_e32 v147, 0xbfb8aa3b, v124
	v_exp_f32_e32 v147, v147
	v_pk_mul_f32 v[14:15], v[14:15], v[154:155] op_sel_hi:[1,0]
	v_pk_mul_f32 v[12:13], v[12:13], v[154:155] op_sel_hi:[1,0]
	v_add_f32_e32 v147, 1.0, v147
	v_rcp_f32_e32 v180, v147
	v_mul_f32_e32 v147, 0xbfb8aa3b, v125
	v_exp_f32_e32 v147, v147
	v_pk_mul_f32 v[4:5], v[4:5], v[154:155] op_sel_hi:[1,0]
	v_pk_mul_f32 v[6:7], v[6:7], v[154:155] op_sel_hi:[1,0]
	v_pk_mul_f32 v[10:11], v[10:11], v[154:155] op_sel_hi:[1,0]
	v_add_f32_e32 v147, 1.0, v147
	v_rcp_f32_e32 v181, v147
	v_mul_f32_e32 v147, 0xbfb8aa3b, v126
	v_exp_f32_e32 v147, v147
	v_pk_mul_f32 v[8:9], v[8:9], v[154:155] op_sel_hi:[1,0]
	v_pk_mul_f32 v[124:125], v[124:125], v[180:181]
	v_pk_mul_f32 v[0:1], v[0:1], v[154:155] op_sel_hi:[1,0]
	v_add_f32_e32 v147, 1.0, v147
	v_rcp_f32_e32 v182, v147
	v_mul_f32_e32 v147, 0xbfb8aa3b, v127
	v_exp_f32_e32 v147, v147
	v_pk_mul_f32 v[116:117], v[116:117], v[124:125]
	v_mul_f32_e32 v124, 0xbfb8aa3b, v120
	v_mul_f32_e32 v125, 0xbfb8aa3b, v121
	v_add_f32_e32 v147, 1.0, v147
	v_rcp_f32_e32 v183, v147
	v_exp_f32_e32 v124, v124
	v_exp_f32_e32 v125, v125
	v_cvt_pk_bf16_f32 v116, v116, v117
	v_pk_mul_f32 v[126:127], v[126:127], v[182:183]
	v_add_f32_e32 v124, 1.0, v124
	v_pk_mul_f32 v[118:119], v[118:119], v[126:127]
	v_mul_f32_e32 v126, 0xbfb8aa3b, v122
	v_mul_f32_e32 v127, 0xbfb8aa3b, v123
	v_exp_f32_e32 v126, v126
	v_exp_f32_e32 v127, v127
	v_add_f32_e32 v125, 1.0, v125
	v_rcp_f32_e32 v124, v124
	v_rcp_f32_e32 v125, v125
	v_add_f32_e32 v126, 1.0, v126
	v_add_f32_e32 v127, 1.0, v127
	v_rcp_f32_e32 v126, v126
	v_rcp_f32_e32 v127, v127
	v_pk_mul_f32 v[120:121], v[120:121], v[124:125]
	v_cvt_pk_bf16_f32 v117, v118, v119
	v_pk_mul_f32 v[2:3], v[2:3], v[154:155] op_sel_hi:[1,0]
	v_pk_mul_f32 v[122:123], v[122:123], v[126:127]
	v_pk_mul_f32 v[112:113], v[112:113], v[120:121]
	v_pk_mul_f32 v[114:115], v[114:115], v[122:123]
	v_cvt_pk_bf16_f32 v118, v112, v113
	v_mov_b64_e32 v[112:113], s[20:21]
	v_cvt_pk_bf16_f32 v119, v114, v115
	v_mad_i64_i32 v[120:121], s[14:15], v168, s68, v[112:113]
	v_lshlrev_b64 v[114:115], 1, v[178:179]
	v_lshl_add_u64 v[120:121], v[120:121], 0, v[114:115]
	global_store_dwordx4 v[120:121], v[116:119], off
	s_nop 1
	v_mul_f32_e32 v116, 0xbfb8aa3b, v108
	v_mul_f32_e32 v117, 0xbfb8aa3b, v109
	v_mul_f32_e32 v118, 0xbfb8aa3b, v110
	v_mul_f32_e32 v119, 0xbfb8aa3b, v111
	v_exp_f32_e32 v116, v116
	v_exp_f32_e32 v117, v117
	v_exp_f32_e32 v118, v118
	v_exp_f32_e32 v119, v119
	v_add_f32_e32 v116, 1.0, v116
	v_add_f32_e32 v117, 1.0, v117
	v_add_f32_e32 v118, 1.0, v118
	v_add_f32_e32 v119, 1.0, v119
	v_rcp_f32_e32 v116, v116
	v_rcp_f32_e32 v117, v117
	v_rcp_f32_e32 v118, v118
	v_rcp_f32_e32 v119, v119
	v_pk_mul_f32 v[108:109], v[108:109], v[116:117]
	s_nop 0
	v_pk_mul_f32 v[100:101], v[100:101], v[108:109]
	v_pk_mul_f32 v[110:111], v[110:111], v[118:119]
	v_mul_f32_e32 v108, 0xbfb8aa3b, v104
	v_pk_mul_f32 v[102:103], v[102:103], v[110:111]
	v_mul_f32_e32 v109, 0xbfb8aa3b, v105
	v_mul_f32_e32 v110, 0xbfb8aa3b, v106
	v_mul_f32_e32 v111, 0xbfb8aa3b, v107
	v_exp_f32_e32 v108, v108
	v_exp_f32_e32 v109, v109
	v_exp_f32_e32 v110, v110
	v_exp_f32_e32 v111, v111
	v_add_f32_e32 v108, 1.0, v108
	v_add_f32_e32 v109, 1.0, v109
	v_add_f32_e32 v110, 1.0, v110
	v_add_f32_e32 v111, 1.0, v111
	v_rcp_f32_e32 v108, v108
	v_rcp_f32_e32 v109, v109
	v_rcp_f32_e32 v110, v110
	v_rcp_f32_e32 v111, v111
	v_pk_mul_f32 v[104:105], v[104:105], v[108:109]
	v_pk_mul_f32 v[106:107], v[106:107], v[110:111]
	s_nop 0
	v_pk_mul_f32 v[106:107], v[98:99], v[106:107]
	v_pk_mul_f32 v[98:99], v[96:97], v[104:105]
	v_cvt_pk_bf16_f32 v96, v100, v101
	v_mad_i64_i32 v[100:101], s[14:15], v164, s68, v[112:113]
	v_cvt_pk_bf16_f32 v97, v102, v103
	v_cvt_pk_bf16_f32 v98, v98, v99
	v_cvt_pk_bf16_f32 v99, v106, v107
	v_lshl_add_u64 v[100:101], v[100:101], 0, v[114:115]
	global_store_dwordx4 v[100:101], v[96:99], off
	s_nop 1
	v_mul_f32_e32 v96, 0xbfb8aa3b, v92
	v_mul_f32_e32 v97, 0xbfb8aa3b, v93
	v_mul_f32_e32 v98, 0xbfb8aa3b, v94
	v_mul_f32_e32 v99, 0xbfb8aa3b, v95
	v_exp_f32_e32 v96, v96
	v_exp_f32_e32 v97, v97
	v_exp_f32_e32 v98, v98
	v_exp_f32_e32 v99, v99
	v_add_f32_e32 v96, 1.0, v96
	v_add_f32_e32 v97, 1.0, v97
	v_add_f32_e32 v98, 1.0, v98
	v_add_f32_e32 v99, 1.0, v99
	v_rcp_f32_e32 v96, v96
	v_rcp_f32_e32 v97, v97
	v_rcp_f32_e32 v98, v98
	v_rcp_f32_e32 v99, v99
	v_pk_mul_f32 v[92:93], v[92:93], v[96:97]
	s_nop 0
	v_pk_mul_f32 v[84:85], v[84:85], v[92:93]
	v_pk_mul_f32 v[94:95], v[94:95], v[98:99]
	v_mul_f32_e32 v92, 0xbfb8aa3b, v88
	v_pk_mul_f32 v[86:87], v[86:87], v[94:95]
	v_mul_f32_e32 v93, 0xbfb8aa3b, v89
	v_mul_f32_e32 v94, 0xbfb8aa3b, v90
	v_mul_f32_e32 v95, 0xbfb8aa3b, v91
	v_exp_f32_e32 v92, v92
	v_exp_f32_e32 v93, v93
	v_exp_f32_e32 v94, v94
	v_exp_f32_e32 v95, v95
	v_add_f32_e32 v92, 1.0, v92
	v_add_f32_e32 v93, 1.0, v93
	v_add_f32_e32 v94, 1.0, v94
	v_add_f32_e32 v95, 1.0, v95
	v_rcp_f32_e32 v92, v92
	v_rcp_f32_e32 v93, v93
	v_rcp_f32_e32 v94, v94
	v_rcp_f32_e32 v95, v95
	v_pk_mul_f32 v[88:89], v[88:89], v[92:93]
	v_pk_mul_f32 v[90:91], v[90:91], v[94:95]
	s_nop 0
	v_pk_mul_f32 v[90:91], v[82:83], v[90:91]
	v_pk_mul_f32 v[82:83], v[80:81], v[88:89]
	v_cvt_pk_bf16_f32 v80, v84, v85
	v_mad_i64_i32 v[84:85], s[14:15], v160, s68, v[112:113]
	v_cvt_pk_bf16_f32 v81, v86, v87
	v_cvt_pk_bf16_f32 v82, v82, v83
	v_cvt_pk_bf16_f32 v83, v90, v91
	v_lshl_add_u64 v[84:85], v[84:85], 0, v[114:115]
	global_store_dwordx4 v[84:85], v[80:83], off
	s_nop 1
	v_mul_f32_e32 v80, 0xbfb8aa3b, v76
	v_mul_f32_e32 v81, 0xbfb8aa3b, v77
; __device__ __forceinline__ u32x4 pack8(f32x4 a, f32x4 b) { u32x4 w; w.x = cvt_pk_bf16(a[0], a[1]); w.y = cvt_pk_bf16(a[2], a[3]); w.z = cvt_pk_bf16(b[0], b[1]); w.w = cvt_pk_bf16(b[2], b[3]); return w; }
; __device__ __forceinline__ float silu_f(float v) { return v * __builtin_amdgcn_rcpf(1.0f + __builtin_amdgcn_exp2f(v * -1.4426950408889634f)); }
; __device__ __forceinline__ f32x4 silu4(f32x4 v) { return (f32x4){silu_f(v[0]), silu_f(v[1]), silu_f(v[2]), silu_f(v[3])}; }
;     __device__ __forceinline__ void operator()(const f32x4 (&acc)[2][2][4][2], const Unit& u, int wr, int wc, int fr, int fq) const {
;     ...
;                 const int row = u.pm * BM + ai * HALF + wr * 64 + m * 16 + fr;
;                 const float rstd = rs[ai][m];
;                 const f32x4 a0 = silu4(acc[ai][0][m][0] * rstd) * (acc[ai][1][m][0] * rstd);
;                 const f32x4 a1 = silu4(acc[ai][0][m][1] * rstd) * (acc[ai][1][m][1] * rstd);
;                 *(u32x4*)(ACT + (size_t)row * 2816 + col0) = pack8(a0, a1);
	v_mul_f32_e32 v82, 0xbfb8aa3b, v78
	v_mul_f32_e32 v83, 0xbfb8aa3b, v79
	v_exp_f32_e32 v80, v80
	v_exp_f32_e32 v81, v81
	v_exp_f32_e32 v82, v82
	v_exp_f32_e32 v83, v83
	v_add_f32_e32 v80, 1.0, v80
	v_add_f32_e32 v81, 1.0, v81
	v_add_f32_e32 v82, 1.0, v82
	v_add_f32_e32 v83, 1.0, v83
	v_rcp_f32_e32 v80, v80
	v_rcp_f32_e32 v81, v81
	v_rcp_f32_e32 v82, v82
	v_rcp_f32_e32 v83, v83
	v_pk_mul_f32 v[76:77], v[76:77], v[80:81]
	s_nop 0
	v_pk_mul_f32 v[68:69], v[68:69], v[76:77]
	v_pk_mul_f32 v[78:79], v[78:79], v[82:83]
	v_mul_f32_e32 v76, 0xbfb8aa3b, v72
	v_pk_mul_f32 v[70:71], v[70:71], v[78:79]
	v_mul_f32_e32 v77, 0xbfb8aa3b, v73
	v_mul_f32_e32 v78, 0xbfb8aa3b, v74
	v_mul_f32_e32 v79, 0xbfb8aa3b, v75
	v_exp_f32_e32 v76, v76
	v_exp_f32_e32 v77, v77
	v_exp_f32_e32 v78, v78
	v_exp_f32_e32 v79, v79
	v_add_f32_e32 v76, 1.0, v76
	v_add_f32_e32 v77, 1.0, v77
	v_add_f32_e32 v78, 1.0, v78
	v_add_f32_e32 v79, 1.0, v79
	v_rcp_f32_e32 v76, v76
	v_rcp_f32_e32 v77, v77
	v_rcp_f32_e32 v78, v78
	v_rcp_f32_e32 v79, v79
	v_pk_mul_f32 v[72:73], v[72:73], v[76:77]
	v_pk_mul_f32 v[74:75], v[74:75], v[78:79]
	s_nop 0
	v_pk_mul_f32 v[74:75], v[66:67], v[74:75]
	v_pk_mul_f32 v[66:67], v[64:65], v[72:73]
	v_cvt_pk_bf16_f32 v64, v68, v69
	v_mad_i64_i32 v[68:69], s[14:15], v156, s68, v[112:113]
	v_cvt_pk_bf16_f32 v65, v70, v71
	v_cvt_pk_bf16_f32 v66, v66, v67
	v_cvt_pk_bf16_f32 v67, v74, v75
	v_lshl_add_u64 v[68:69], v[68:69], 0, v[114:115]
	global_store_dwordx4 v[68:69], v[64:67], off
	s_nop 1
	v_mul_f32_e32 v64, 0xbfb8aa3b, v60
	v_mul_f32_e32 v65, 0xbfb8aa3b, v61
	v_mul_f32_e32 v66, 0xbfb8aa3b, v62
	v_mul_f32_e32 v67, 0xbfb8aa3b, v63
	v_exp_f32_e32 v64, v64
	v_exp_f32_e32 v65, v65
	v_exp_f32_e32 v66, v66
	v_exp_f32_e32 v67, v67
	v_add_f32_e32 v64, 1.0, v64
	v_add_f32_e32 v65, 1.0, v65
	v_add_f32_e32 v66, 1.0, v66
	v_add_f32_e32 v67, 1.0, v67
	v_rcp_f32_e32 v64, v64
	v_rcp_f32_e32 v65, v65
	v_rcp_f32_e32 v66, v66
	v_rcp_f32_e32 v67, v67
	v_pk_mul_f32 v[60:61], v[60:61], v[64:65]
	s_nop 0
	v_pk_mul_f32 v[52:53], v[52:53], v[60:61]
	v_pk_mul_f32 v[62:63], v[62:63], v[66:67]
	v_mul_f32_e32 v60, 0xbfb8aa3b, v56
	v_pk_mul_f32 v[54:55], v[54:55], v[62:63]
	v_mul_f32_e32 v61, 0xbfb8aa3b, v57
	v_mul_f32_e32 v62, 0xbfb8aa3b, v58
	v_mul_f32_e32 v63, 0xbfb8aa3b, v59
	v_exp_f32_e32 v60, v60
	v_exp_f32_e32 v61, v61
	v_exp_f32_e32 v62, v62
	v_exp_f32_e32 v63, v63
	v_add_f32_e32 v60, 1.0, v60
	v_add_f32_e32 v61, 1.0, v61
	v_add_f32_e32 v62, 1.0, v62
	v_add_f32_e32 v63, 1.0, v63
	v_rcp_f32_e32 v60, v60
	v_rcp_f32_e32 v61, v61
	v_rcp_f32_e32 v62, v62
	v_rcp_f32_e32 v63, v63
	v_pk_mul_f32 v[56:57], v[56:57], v[60:61]
	v_pk_mul_f32 v[58:59], v[58:59], v[62:63]
	s_nop 0
	v_pk_mul_f32 v[58:59], v[50:51], v[58:59]
	v_pk_mul_f32 v[50:51], v[48:49], v[56:57]
	v_cvt_pk_bf16_f32 v48, v52, v53
	v_mad_i64_i32 v[52:53], s[14:15], v152, s68, v[112:113]
	v_cvt_pk_bf16_f32 v49, v54, v55
	v_cvt_pk_bf16_f32 v50, v50, v51
	v_cvt_pk_bf16_f32 v51, v58, v59
	v_lshl_add_u64 v[52:53], v[52:53], 0, v[114:115]
	global_store_dwordx4 v[52:53], v[48:51], off
	s_nop 1
	v_mul_f32_e32 v48, 0xbfb8aa3b, v44
	v_mul_f32_e32 v49, 0xbfb8aa3b, v45
	v_mul_f32_e32 v50, 0xbfb8aa3b, v46
	v_mul_f32_e32 v51, 0xbfb8aa3b, v47
	v_exp_f32_e32 v48, v48
	v_exp_f32_e32 v49, v49
	v_exp_f32_e32 v50, v50
	v_exp_f32_e32 v51, v51
	v_add_f32_e32 v48, 1.0, v48
	v_add_f32_e32 v49, 1.0, v49
	v_add_f32_e32 v50, 1.0, v50
	v_add_f32_e32 v51, 1.0, v51
	v_rcp_f32_e32 v48, v48
	v_rcp_f32_e32 v49, v49
	v_rcp_f32_e32 v50, v50
	v_rcp_f32_e32 v51, v51
	v_pk_mul_f32 v[44:45], v[44:45], v[48:49]
	s_nop 0
	v_pk_mul_f32 v[36:37], v[36:37], v[44:45]
	v_pk_mul_f32 v[46:47], v[46:47], v[50:51]
	v_mul_f32_e32 v44, 0xbfb8aa3b, v40
	v_pk_mul_f32 v[38:39], v[38:39], v[46:47]
	v_mul_f32_e32 v45, 0xbfb8aa3b, v41
	v_mul_f32_e32 v46, 0xbfb8aa3b, v42
	v_mul_f32_e32 v47, 0xbfb8aa3b, v43
	v_exp_f32_e32 v44, v44
	v_exp_f32_e32 v45, v45
	v_exp_f32_e32 v46, v46
; __device__ __forceinline__ u32x4 pack8(f32x4 a, f32x4 b) { u32x4 w; w.x = cvt_pk_bf16(a[0], a[1]); w.y = cvt_pk_bf16(a[2], a[3]); w.z = cvt_pk_bf16(b[0], b[1]); w.w = cvt_pk_bf16(b[2], b[3]); return w; }
; __device__ __forceinline__ float silu_f(float v) { return v * __builtin_amdgcn_rcpf(1.0f + __builtin_amdgcn_exp2f(v * -1.4426950408889634f)); }
; __device__ __forceinline__ f32x4 silu4(f32x4 v) { return (f32x4){silu_f(v[0]), silu_f(v[1]), silu_f(v[2]), silu_f(v[3])}; }
;     __device__ __forceinline__ void operator()(const f32x4 (&acc)[2][2][4][2], const Unit& u, int wr, int wc, int fr, int fq) const {
;     ...
;                 const int row = u.pm * BM + ai * HALF + wr * 64 + m * 16 + fr;
;                 const float rstd = rs[ai][m];
;                 const f32x4 a0 = silu4(acc[ai][0][m][0] * rstd) * (acc[ai][1][m][0] * rstd);
;                 const f32x4 a1 = silu4(acc[ai][0][m][1] * rstd) * (acc[ai][1][m][1] * rstd);
;                 *(u32x4*)(ACT + (size_t)row * 2816 + col0) = pack8(a0, a1);
	v_exp_f32_e32 v47, v47
	v_add_f32_e32 v44, 1.0, v44
	v_add_f32_e32 v45, 1.0, v45
	v_add_f32_e32 v46, 1.0, v46
	v_add_f32_e32 v47, 1.0, v47
	v_rcp_f32_e32 v44, v44
	v_rcp_f32_e32 v45, v45
	v_rcp_f32_e32 v46, v46
	v_rcp_f32_e32 v47, v47
	v_pk_mul_f32 v[40:41], v[40:41], v[44:45]
	v_pk_mul_f32 v[42:43], v[42:43], v[46:47]
	s_nop 0
	v_pk_mul_f32 v[42:43], v[34:35], v[42:43]
	v_pk_mul_f32 v[34:35], v[32:33], v[40:41]
	v_cvt_pk_bf16_f32 v32, v36, v37
	v_mad_i64_i32 v[36:37], s[14:15], v150, s68, v[112:113]
	v_cvt_pk_bf16_f32 v33, v38, v39
	v_cvt_pk_bf16_f32 v34, v34, v35
	v_cvt_pk_bf16_f32 v35, v42, v43
	v_lshl_add_u64 v[36:37], v[36:37], 0, v[114:115]
	global_store_dwordx4 v[36:37], v[32:35], off
	s_nop 1
	v_mul_f32_e32 v32, 0xbfb8aa3b, v28
	v_mul_f32_e32 v33, 0xbfb8aa3b, v29
	v_mul_f32_e32 v34, 0xbfb8aa3b, v30
	v_mul_f32_e32 v35, 0xbfb8aa3b, v31
	v_exp_f32_e32 v32, v32
	v_exp_f32_e32 v33, v33
	v_exp_f32_e32 v34, v34
	v_exp_f32_e32 v35, v35
	v_add_f32_e32 v32, 1.0, v32
	v_add_f32_e32 v33, 1.0, v33
	v_add_f32_e32 v34, 1.0, v34
	v_add_f32_e32 v35, 1.0, v35
	v_rcp_f32_e32 v32, v32
	v_rcp_f32_e32 v33, v33
	v_rcp_f32_e32 v34, v34
	v_rcp_f32_e32 v35, v35
	v_pk_mul_f32 v[28:29], v[28:29], v[32:33]
	s_nop 0
	v_pk_mul_f32 v[20:21], v[20:21], v[28:29]
	v_pk_mul_f32 v[30:31], v[30:31], v[34:35]
	v_mul_f32_e32 v28, 0xbfb8aa3b, v24
	v_pk_mul_f32 v[22:23], v[22:23], v[30:31]
	v_mul_f32_e32 v29, 0xbfb8aa3b, v25
	v_mul_f32_e32 v30, 0xbfb8aa3b, v26
	v_mul_f32_e32 v31, 0xbfb8aa3b, v27
	v_exp_f32_e32 v28, v28
	v_exp_f32_e32 v29, v29
	v_exp_f32_e32 v30, v30
	v_exp_f32_e32 v31, v31
	v_add_f32_e32 v28, 1.0, v28
	v_add_f32_e32 v29, 1.0, v29
	v_add_f32_e32 v30, 1.0, v30
	v_add_f32_e32 v31, 1.0, v31
	v_rcp_f32_e32 v28, v28
	v_rcp_f32_e32 v29, v29
	v_rcp_f32_e32 v30, v30
	v_rcp_f32_e32 v31, v31
	v_pk_mul_f32 v[24:25], v[24:25], v[28:29]
	v_pk_mul_f32 v[26:27], v[26:27], v[30:31]
	s_nop 0
	v_pk_mul_f32 v[26:27], v[18:19], v[26:27]
	v_pk_mul_f32 v[18:19], v[16:17], v[24:25]
	v_cvt_pk_bf16_f32 v16, v20, v21
	v_mad_i64_i32 v[20:21], s[14:15], v148, s68, v[112:113]
	v_cvt_pk_bf16_f32 v17, v22, v23
	v_cvt_pk_bf16_f32 v18, v18, v19
	v_cvt_pk_bf16_f32 v19, v26, v27
	v_lshl_add_u64 v[20:21], v[20:21], 0, v[114:115]
	global_store_dwordx4 v[20:21], v[16:19], off
	s_nop 1
	v_mul_f32_e32 v16, 0xbfb8aa3b, v12
	v_mul_f32_e32 v17, 0xbfb8aa3b, v13
	v_mul_f32_e32 v18, 0xbfb8aa3b, v14
	v_mul_f32_e32 v19, 0xbfb8aa3b, v15
	v_exp_f32_e32 v16, v16
	v_exp_f32_e32 v17, v17
	v_exp_f32_e32 v18, v18
	v_exp_f32_e32 v19, v19
	v_add_f32_e32 v16, 1.0, v16
	v_add_f32_e32 v17, 1.0, v17
	v_add_f32_e32 v18, 1.0, v18
	v_add_f32_e32 v19, 1.0, v19
	v_rcp_f32_e32 v16, v16
	v_rcp_f32_e32 v17, v17
	v_rcp_f32_e32 v18, v18
	v_rcp_f32_e32 v19, v19
	v_pk_mul_f32 v[12:13], v[12:13], v[16:17]
	s_nop 0
	v_pk_mul_f32 v[4:5], v[4:5], v[12:13]
	v_pk_mul_f32 v[14:15], v[14:15], v[18:19]
	v_mul_f32_e32 v12, 0xbfb8aa3b, v8
	v_pk_mul_f32 v[6:7], v[6:7], v[14:15]
	v_mul_f32_e32 v13, 0xbfb8aa3b, v9
	v_mul_f32_e32 v14, 0xbfb8aa3b, v10
	v_mul_f32_e32 v15, 0xbfb8aa3b, v11
	v_exp_f32_e32 v12, v12
	v_exp_f32_e32 v13, v13
	v_exp_f32_e32 v14, v14
	v_exp_f32_e32 v15, v15
	v_add_f32_e32 v12, 1.0, v12
	v_add_f32_e32 v13, 1.0, v13
	v_add_f32_e32 v14, 1.0, v14
	v_add_f32_e32 v15, 1.0, v15
	v_rcp_f32_e32 v12, v12
	v_rcp_f32_e32 v13, v13
	v_rcp_f32_e32 v14, v14
	v_rcp_f32_e32 v15, v15
	v_pk_mul_f32 v[8:9], v[8:9], v[12:13]
	v_pk_mul_f32 v[10:11], v[10:11], v[14:15]
	s_nop 0
	v_pk_mul_f32 v[10:11], v[2:3], v[10:11]
	v_pk_mul_f32 v[2:3], v[0:1], v[8:9]
	v_cvt_pk_bf16_f32 v0, v4, v5
	v_mad_i64_i32 v[4:5], s[14:15], v146, s68, v[112:113]
	v_lshl_add_u64 v[4:5], v[4:5], 0, v[114:115]
	v_cvt_pk_bf16_f32 v1, v6, v7
	v_cvt_pk_bf16_f32 v2, v2, v3
	v_cvt_pk_bf16_f32 v3, v10, v11
	global_store_dwordx4 v[4:5], v[0:3], off
	s_cbranch_vccnz .LBB0_992
	s_andn2_b64 vcc, exec, s[18:19]
	s_cbranch_vccnz .LBB0_991
	s_barrier
	s_branch .LBB0_991

; __device__ __forceinline__ float sq4(f32x4 v) { return (v[0] * v[0] + v[1] * v[1]) + (v[2] * v[2] + v[3] * v[3]); }
; __device__ __forceinline__ u32x4 pack8(f32x4 a, f32x4 b) { u32x4 w; w.x = cvt_pk_bf16(a[0], a[1]); w.y = cvt_pk_bf16(a[2], a[3]); w.z = cvt_pk_bf16(b[0], b[1]); w.w = cvt_pk_bf16(b[2], b[3]); return w; }
;     __device__ __forceinline__ void operator()(const f32x4 (&acc)[2][2][4][2], const Unit& u, int wr, int wc, int fr, int fq) const {
;         const int col0 = u.pn * 256 + 32 * wc + 8 * fq;
; #pragma unroll
;         for (int ai = 0; ai < 2; ++ai) {
;             u32x4 bs[4][2];
; #pragma unroll
;             for (int m = 0; m < 4; ++m)
; #pragma unroll
;                 for (int bj = 0; bj < 2; ++bj) bs[m][bj] = *(const u32x4*)(xb + (size_t)(u.pm * BM + ai * HALF + wr * 64 + m * 16 + fr) * 1024 + col0 + 128 * bj);
; #pragma unroll
;             for (int m = 0; m < 4; ++m) {
;                 const int row = u.pm * BM + ai * HALF + wr * 64 + m * 16 + fr;
;                 float q = 0.f;
; #pragma unroll
;                 for (int bj = 0; bj < 2; ++bj) {
;                     const size_t off = (size_t)row * 1024 + col0 + 128 * bj; const u32x4 w = bs[m][bj];
;                     const f32x4 b0 = (f32x4){__builtin_bit_cast(float, w.x << 16), __builtin_bit_cast(float, w.x & 0xffff0000u), __builtin_bit_cast(float, w.y << 16), __builtin_bit_cast(float, w.y & 0xffff0000u)};
;                     const f32x4 b1 = (f32x4){__builtin_bit_cast(float, w.z << 16), __builtin_bit_cast(float, w.z & 0xffff0000u), __builtin_bit_cast(float, w.w << 16), __builtin_bit_cast(float, w.w & 0xffff0000u)};
;                     const f32x4 v0 = acc[ai][bj][m][0] + b0, v1 = acc[ai][bj][m][1] + b1;
;                     if (last) { __builtin_nontemporal_store(v0, (f32x4*)(out + off)); __builtin_nontemporal_store(v1, (f32x4*)(out + off + 4)); }
;                     else { q += sq4(v0) + sq4(v1); *(u32x4*)(xb + off) = pack8(v0, v1); }
;                 }
;                 if (!last) { q += shx(q, 16); q += shx(q, 32); if (fq == 0) ss[(size_t)row * 16 + u.pn * 4 + wc] = q; }
.LBB0_1081:
	v_lshl_or_b32 v168, s22, 8, v188
	v_lshl_add_u32 v172, s72, 8, v186
	v_ashrrev_i32_e32 v169, 31, v168
	v_lshlrev_b64 v[202:203], 1, v[168:169]
	v_ashrrev_i32_e32 v173, 31, v172
	v_lshl_add_u64 v[170:171], s[26:27], 0, v[202:203]
	v_lshlrev_b64 v[204:205], 11, v[172:173]
	v_lshl_add_u64 v[120:121], v[170:171], 0, v[204:205]
	global_load_dwordx4 v[192:195], v[120:121], off
	global_load_dwordx4 v[196:199], v[120:121], off offset:256
	v_or_b32_e32 v182, 16, v172
	v_ashrrev_i32_e32 v183, 31, v182
	v_or_b32_e32 v178, 32, v172
	v_lshlrev_b64 v[184:185], 11, v[182:183]
	v_ashrrev_i32_e32 v179, 31, v178
	v_or_b32_e32 v174, 48, v172
	v_lshl_add_u64 v[120:121], v[170:171], 0, v[184:185]
	v_lshlrev_b64 v[180:181], 11, v[178:179]
	v_ashrrev_i32_e32 v175, 31, v174
	global_load_dwordx4 v[148:151], v[120:121], off
	global_load_dwordx4 v[144:147], v[120:121], off offset:256
	v_lshl_add_u64 v[120:121], v[170:171], 0, v[180:181]
	v_lshlrev_b64 v[176:177], 11, v[174:175]
	global_load_dwordx4 v[140:143], v[120:121], off
	global_load_dwordx4 v[136:139], v[120:121], off offset:256
	v_lshl_add_u64 v[120:121], v[170:171], 0, v[176:177]
	global_load_dwordx4 v[132:135], v[120:121], off
	s_nop 0
	global_load_dwordx4 v[120:123], v[120:121], off offset:256
	s_lshl_b32 s50, s22, 2
	s_ashr_i32 s51, s50, 31
	s_waitcnt vmcnt(0)
	v_lshlrev_b32_e32 v206, 16, v192
	v_and_b32_e32 v207, 0xffff0000, v192
	v_lshlrev_b32_e32 v192, 16, v193
	v_and_b32_e32 v193, 0xffff0000, v193
	v_lshlrev_b32_e32 v208, 16, v194
	v_and_b32_e32 v209, 0xffff0000, v194
	v_lshlrev_b32_e32 v194, 16, v195
	v_and_b32_e32 v195, 0xffff0000, v195
	v_pk_add_f32 v[130:131], v[130:131], v[192:193]
	v_pk_add_f32 v[128:129], v[128:129], v[206:207]
	v_pk_add_f32 v[192:193], v[126:127], v[194:195]
	v_pk_add_f32 v[126:127], v[124:125], v[208:209]
	v_mul_f32_e32 v124, v129, v129
	v_mul_f32_e32 v125, v131, v131
	v_fmac_f32_e32 v124, v128, v128
	v_fmac_f32_e32 v125, v130, v130
	v_add_f32_e32 v124, v124, v125
	v_mul_f32_e32 v125, v127, v127
	v_mul_f32_e32 v194, v193, v193
	v_fmac_f32_e32 v125, v126, v126
	v_fmac_f32_e32 v194, v192, v192
	v_add_f32_e32 v125, v125, v194
	v_add_f32_e32 v194, v124, v125
	v_cvt_pk_bf16_f32 v124, v128, v129
	v_lshl_add_u64 v[128:129], s[26:27], 0, v[204:205]
	v_cvt_pk_bf16_f32 v125, v130, v131
	v_cvt_pk_bf16_f32 v126, v126, v127
	v_cvt_pk_bf16_f32 v127, v192, v193
	v_lshl_add_u64 v[128:129], v[128:129], 0, v[202:203]
	global_store_dwordx4 v[128:129], v[124:127], off
	v_lshlrev_b32_e32 v130, 16, v198
	v_and_b32_e32 v131, 0xffff0000, v198
	v_lshlrev_b32_e32 v124, 16, v196
	v_and_b32_e32 v125, 0xffff0000, v196
	v_lshlrev_b32_e32 v126, 16, v197
	v_and_b32_e32 v127, 0xffff0000, v197
	v_lshlrev_b32_e32 v192, 16, v199
	v_and_b32_e32 v193, 0xffff0000, v199
	v_pk_add_f32 v[118:119], v[118:119], v[126:127]
	v_pk_add_f32 v[116:117], v[116:117], v[124:125]
	v_pk_add_f32 v[124:125], v[114:115], v[192:193]
	v_pk_add_f32 v[114:115], v[112:113], v[130:131]
	v_mul_f32_e32 v112, v117, v117
	v_mul_f32_e32 v113, v119, v119
	v_fmac_f32_e32 v112, v116, v116
	v_fmac_f32_e32 v113, v118, v118
	v_add_f32_e32 v112, v112, v113
	v_mul_f32_e32 v113, v115, v115
	v_mul_f32_e32 v126, v125, v125
	v_fmac_f32_e32 v113, v114, v114
	v_fmac_f32_e32 v126, v124, v124
	v_add_f32_e32 v113, v113, v126
	v_add_f32_e32 v112, v112, v113
	v_add_f32_e32 v126, v194, v112
	v_cvt_pk_bf16_f32 v112, v116, v117
	v_cvt_pk_bf16_f32 v113, v118, v119
	v_cvt_pk_bf16_f32 v114, v114, v115
	v_cvt_pk_bf16_f32 v115, v124, v125
	global_store_dwordx4 v[128:129], v[112:115], off offset:256
	s_nop 1
	v_mov_b32_e32 v112, v201
	v_mov_b32_e32 v113, v201
	v_lshlrev_b32_e32 v112, 2, v112
	v_xor_b32_e32 v112, 64, v112
	v_mov_b32_e32 v112, v126
	s_nop 1
	v_permlane16_swap_b32_e32 v112, v126
	s_waitcnt lgkmcnt(0)
	v_add_f32_e32 v112, v126, v112
	v_lshlrev_b32_e32 v113, 2, v113
	v_xor_b32_e32 v113, 0x80, v113
	v_mov_b32_e32 v113, v112
	s_nop 1
	v_permlane32_swap_b32_e32 v113, v112
	s_and_saveexec_b64 s[52:53], s[16:17]
	s_cbranch_execz .LBB0_1083
	s_waitcnt lgkmcnt(0)
	v_add_f32_e32 v114, v112, v113
	v_lshlrev_b64 v[112:113], 6, v[172:173]
	v_lshl_add_u64 v[112:113], s[42:43], 0, v[112:113]
	v_lshl_add_u64 v[112:113], s[50:51], 2, v[112:113]
	s_lshl_b32 s22, s61, 2
	v_lshl_add_u64 v[112:113], v[112:113], 0, s[22:23]
	global_store_dword v[112:113], v114, off
; __device__ __forceinline__ float sq4(f32x4 v) { return (v[0] * v[0] + v[1] * v[1]) + (v[2] * v[2] + v[3] * v[3]); }
; __device__ __forceinline__ u32x4 pack8(f32x4 a, f32x4 b) { u32x4 w; w.x = cvt_pk_bf16(a[0], a[1]); w.y = cvt_pk_bf16(a[2], a[3]); w.z = cvt_pk_bf16(b[0], b[1]); w.w = cvt_pk_bf16(b[2], b[3]); return w; }
;     __device__ __forceinline__ void operator()(const f32x4 (&acc)[2][2][4][2], const Unit& u, int wr, int wc, int fr, int fq) const {
;     ...
;             for (int m = 0; m < 4; ++m) {
;                 const int row = u.pm * BM + ai * HALF + wr * 64 + m * 16 + fr;
;                 float q = 0.f;
; #pragma unroll
;                 for (int bj = 0; bj < 2; ++bj) {
;                     const size_t off = (size_t)row * 1024 + col0 + 128 * bj; const u32x4 w = bs[m][bj];
;                     const f32x4 b0 = (f32x4){__builtin_bit_cast(float, w.x << 16), __builtin_bit_cast(float, w.x & 0xffff0000u), __builtin_bit_cast(float, w.y << 16), __builtin_bit_cast(float, w.y & 0xffff0000u)};
;                     const f32x4 b1 = (f32x4){__builtin_bit_cast(float, w.z << 16), __builtin_bit_cast(float, w.z & 0xffff0000u), __builtin_bit_cast(float, w.w << 16), __builtin_bit_cast(float, w.w & 0xffff0000u)};
;                     const f32x4 v0 = acc[ai][bj][m][0] + b0, v1 = acc[ai][bj][m][1] + b1;
;                     if (last) { __builtin_nontemporal_store(v0, (f32x4*)(out + off)); __builtin_nontemporal_store(v1, (f32x4*)(out + off + 4)); }
;                     else { q += sq4(v0) + sq4(v1); *(u32x4*)(xb + off) = pack8(v0, v1); }
;                 }
;                 if (!last) { q += shx(q, 16); q += shx(q, 32); if (fq == 0) ss[(size_t)row * 16 + u.pn * 4 + wc] = q; }
.LBB0_1083:
	s_or_b64 exec, exec, s[52:53]
	v_lshlrev_b32_e32 v112, 16, v148
	s_waitcnt lgkmcnt(0)
	v_and_b32_e32 v113, 0xffff0000, v148
	v_lshlrev_b32_e32 v114, 16, v149
	v_and_b32_e32 v115, 0xffff0000, v149
	v_lshlrev_b32_e32 v116, 16, v150
	v_and_b32_e32 v117, 0xffff0000, v150
	v_lshlrev_b32_e32 v118, 16, v151
	v_and_b32_e32 v119, 0xffff0000, v151
	v_pk_add_f32 v[110:111], v[110:111], v[114:115]
	v_pk_add_f32 v[108:109], v[108:109], v[112:113]
	v_pk_add_f32 v[112:113], v[106:107], v[118:119]
	v_pk_add_f32 v[106:107], v[104:105], v[116:117]
	v_mul_f32_e32 v104, v109, v109
	v_mul_f32_e32 v105, v111, v111
	v_fmac_f32_e32 v104, v108, v108
	v_fmac_f32_e32 v105, v110, v110
	v_add_f32_e32 v104, v104, v105
	v_mul_f32_e32 v105, v107, v107
	v_mul_f32_e32 v114, v113, v113
	v_fmac_f32_e32 v105, v106, v106
	v_fmac_f32_e32 v114, v112, v112
	v_add_f32_e32 v105, v105, v114
	v_add_f32_e32 v114, v104, v105
	v_cvt_pk_bf16_f32 v104, v108, v109
	v_lshl_add_u64 v[108:109], s[26:27], 0, v[184:185]
	v_cvt_pk_bf16_f32 v105, v110, v111
	v_cvt_pk_bf16_f32 v106, v106, v107
	v_cvt_pk_bf16_f32 v107, v112, v113
	v_lshl_add_u64 v[108:109], v[168:169], 1, v[108:109]
	global_store_dwordx4 v[108:109], v[104:107], off
	v_lshlrev_b32_e32 v110, 16, v146
	v_and_b32_e32 v111, 0xffff0000, v146
	v_lshlrev_b32_e32 v104, 16, v144
	v_and_b32_e32 v105, 0xffff0000, v144
	v_lshlrev_b32_e32 v106, 16, v145
	v_and_b32_e32 v107, 0xffff0000, v145
	v_lshlrev_b32_e32 v112, 16, v147
	v_and_b32_e32 v113, 0xffff0000, v147
	v_pk_add_f32 v[102:103], v[102:103], v[106:107]
	v_pk_add_f32 v[100:101], v[100:101], v[104:105]
	v_pk_add_f32 v[104:105], v[98:99], v[112:113]
	v_pk_add_f32 v[98:99], v[96:97], v[110:111]
	v_mul_f32_e32 v96, v101, v101
	v_mul_f32_e32 v97, v103, v103
	v_fmac_f32_e32 v96, v100, v100
	v_fmac_f32_e32 v97, v102, v102
	v_add_f32_e32 v96, v96, v97
	v_mul_f32_e32 v97, v99, v99
	v_mul_f32_e32 v106, v105, v105
	v_fmac_f32_e32 v97, v98, v98
	v_fmac_f32_e32 v106, v104, v104
	v_add_f32_e32 v97, v97, v106
	v_add_f32_e32 v96, v96, v97
	v_add_f32_e32 v106, v114, v96
	v_cvt_pk_bf16_f32 v96, v100, v101
	v_cvt_pk_bf16_f32 v97, v102, v103
	v_cvt_pk_bf16_f32 v98, v98, v99
	v_cvt_pk_bf16_f32 v99, v104, v105
	global_store_dwordx4 v[108:109], v[96:99], off offset:256
	s_nop 1
	v_mov_b32_e32 v96, v201
	v_mov_b32_e32 v97, v201
	v_lshlrev_b32_e32 v96, 2, v96
	v_xor_b32_e32 v96, 64, v96
	v_mov_b32_e32 v96, v106
	s_nop 1
	v_permlane16_swap_b32_e32 v96, v106
	s_waitcnt lgkmcnt(0)
	v_add_f32_e32 v96, v106, v96
	v_lshlrev_b32_e32 v97, 2, v97
	v_xor_b32_e32 v97, 0x80, v97
	v_mov_b32_e32 v97, v96
	s_nop 1
	v_permlane32_swap_b32_e32 v97, v96
	s_and_saveexec_b64 s[52:53], s[16:17]
	s_cbranch_execz .LBB0_1085
	s_waitcnt lgkmcnt(0)
	v_add_f32_e32 v98, v96, v97
	v_lshlrev_b64 v[96:97], 6, v[182:183]
	v_lshl_add_u64 v[96:97], s[42:43], 0, v[96:97]
	v_lshl_add_u64 v[96:97], s[50:51], 2, v[96:97]
	s_lshl_b32 s22, s61, 2
	v_lshl_add_u64 v[96:97], v[96:97], 0, s[22:23]
	global_store_dword v[96:97], v98, off
.LBB0_1085:
	s_or_b64 exec, exec, s[52:53]
	v_lshlrev_b32_e32 v96, 16, v140
	s_waitcnt lgkmcnt(0)
	v_and_b32_e32 v97, 0xffff0000, v140
	v_lshlrev_b32_e32 v98, 16, v141
	v_and_b32_e32 v99, 0xffff0000, v141
	v_lshlrev_b32_e32 v100, 16, v142
	v_and_b32_e32 v101, 0xffff0000, v142
	v_lshlrev_b32_e32 v102, 16, v143
	v_and_b32_e32 v103, 0xffff0000, v143
	v_pk_add_f32 v[94:95], v[94:95], v[98:99]
	v_pk_add_f32 v[92:93], v[92:93], v[96:97]
	v_pk_add_f32 v[96:97], v[90:91], v[102:103]
	v_pk_add_f32 v[90:91], v[88:89], v[100:101]
	v_mul_f32_e32 v88, v93, v93
	v_mul_f32_e32 v89, v95, v95
	v_fmac_f32_e32 v88, v92, v92
	v_fmac_f32_e32 v89, v94, v94
	v_add_f32_e32 v88, v88, v89
	v_mul_f32_e32 v89, v91, v91
	v_mul_f32_e32 v98, v97, v97
	v_fmac_f32_e32 v89, v90, v90
	v_fmac_f32_e32 v98, v96, v96
	v_add_f32_e32 v89, v89, v98
	v_add_f32_e32 v98, v88, v89
	v_cvt_pk_bf16_f32 v88, v92, v93
	v_lshl_add_u64 v[92:93], s[26:27], 0, v[180:181]
	v_cvt_pk_bf16_f32 v89, v94, v95
	v_cvt_pk_bf16_f32 v90, v90, v91
	v_cvt_pk_bf16_f32 v91, v96, v97
	v_lshl_add_u64 v[92:93], v[168:169], 1, v[92:93]
	global_store_dwordx4 v[92:93], v[88:91], off
	v_lshlrev_b32_e32 v94, 16, v138
	v_and_b32_e32 v95, 0xffff0000, v138
	v_lshlrev_b32_e32 v88, 16, v136
	v_and_b32_e32 v89, 0xffff0000, v136
	v_lshlrev_b32_e32 v90, 16, v137
	v_and_b32_e32 v91, 0xffff0000, v137
	v_lshlrev_b32_e32 v96, 16, v139
	v_and_b32_e32 v97, 0xffff0000, v139
	v_pk_add_f32 v[86:87], v[86:87], v[90:91]
	v_pk_add_f32 v[84:85], v[84:85], v[88:89]
	v_pk_add_f32 v[88:89], v[82:83], v[96:97]
	v_pk_add_f32 v[82:83], v[80:81], v[94:95]
	v_mul_f32_e32 v80, v85, v85
	v_mul_f32_e32 v81, v87, v87
	v_fmac_f32_e32 v80, v84, v84
	v_fmac_f32_e32 v81, v86, v86
	v_add_f32_e32 v80, v80, v81
	v_mul_f32_e32 v81, v83, v83
	v_mul_f32_e32 v90, v89, v89
	v_fmac_f32_e32 v81, v82, v82
	v_fmac_f32_e32 v90, v88, v88
	v_add_f32_e32 v81, v81, v90
	v_add_f32_e32 v80, v80, v81
	v_add_f32_e32 v90, v98, v80
	v_cvt_pk_bf16_f32 v80, v84, v85
	v_cvt_pk_bf16_f32 v81, v86, v87
	v_cvt_pk_bf16_f32 v82, v82, v83
	v_cvt_pk_bf16_f32 v83, v88, v89
	global_store_dwordx4 v[92:93], v[80:83], off offset:256
	s_nop 1
	v_mov_b32_e32 v80, v201
	v_mov_b32_e32 v81, v201
	v_lshlrev_b32_e32 v80, 2, v80
	v_xor_b32_e32 v80, 64, v80
	v_mov_b32_e32 v80, v90
	s_nop 1
	v_permlane16_swap_b32_e32 v80, v90
	s_waitcnt lgkmcnt(0)
	v_add_f32_e32 v80, v90, v80
	v_lshlrev_b32_e32 v81, 2, v81
	v_xor_b32_e32 v81, 0x80, v81
	v_mov_b32_e32 v81, v80
	s_nop 1
	v_permlane32_swap_b32_e32 v81, v80
	s_and_saveexec_b64 s[52:53], s[16:17]
	s_cbranch_execz .LBB0_1087
	s_waitcnt lgkmcnt(0)
	v_add_f32_e32 v82, v80, v81
	v_lshlrev_b64 v[80:81], 6, v[178:179]
	v_lshl_add_u64 v[80:81], s[42:43], 0, v[80:81]
	v_lshl_add_u64 v[80:81], s[50:51], 2, v[80:81]
	s_lshl_b32 s22, s61, 2
	v_lshl_add_u64 v[80:81], v[80:81], 0, s[22:23]
	global_store_dword v[80:81], v82, off
; __device__ __forceinline__ float sq4(f32x4 v) { return (v[0] * v[0] + v[1] * v[1]) + (v[2] * v[2] + v[3] * v[3]); }
; __device__ __forceinline__ u32x4 pack8(f32x4 a, f32x4 b) { u32x4 w; w.x = cvt_pk_bf16(a[0], a[1]); w.y = cvt_pk_bf16(a[2], a[3]); w.z = cvt_pk_bf16(b[0], b[1]); w.w = cvt_pk_bf16(b[2], b[3]); return w; }
;     __device__ __forceinline__ void operator()(const f32x4 (&acc)[2][2][4][2], const Unit& u, int wr, int wc, int fr, int fq) const {
;     ...
;         for (int ai = 0; ai < 2; ++ai) {
;             u32x4 bs[4][2];
; #pragma unroll
;             for (int m = 0; m < 4; ++m)
; #pragma unroll
;                 for (int bj = 0; bj < 2; ++bj) bs[m][bj] = *(const u32x4*)(xb + (size_t)(u.pm * BM + ai * HALF + wr * 64 + m * 16 + fr) * 1024 + col0 + 128 * bj);
; #pragma unroll
;             for (int m = 0; m < 4; ++m) {
;                 const int row = u.pm * BM + ai * HALF + wr * 64 + m * 16 + fr;
;                 float q = 0.f;
; #pragma unroll
;                 for (int bj = 0; bj < 2; ++bj) {
;                     const size_t off = (size_t)row * 1024 + col0 + 128 * bj; const u32x4 w = bs[m][bj];
;                     const f32x4 b0 = (f32x4){__builtin_bit_cast(float, w.x << 16), __builtin_bit_cast(float, w.x & 0xffff0000u), __builtin_bit_cast(float, w.y << 16), __builtin_bit_cast(float, w.y & 0xffff0000u)};
;                     const f32x4 b1 = (f32x4){__builtin_bit_cast(float, w.z << 16), __builtin_bit_cast(float, w.z & 0xffff0000u), __builtin_bit_cast(float, w.w << 16), __builtin_bit_cast(float, w.w & 0xffff0000u)};
;                     const f32x4 v0 = acc[ai][bj][m][0] + b0, v1 = acc[ai][bj][m][1] + b1;
;                     if (last) { __builtin_nontemporal_store(v0, (f32x4*)(out + off)); __builtin_nontemporal_store(v1, (f32x4*)(out + off + 4)); }
;                     else { q += sq4(v0) + sq4(v1); *(u32x4*)(xb + off) = pack8(v0, v1); }
;                 }
;                 if (!last) { q += shx(q, 16); q += shx(q, 32); if (fq == 0) ss[(size_t)row * 16 + u.pn * 4 + wc] = q; }
.LBB0_1087:
	s_or_b64 exec, exec, s[52:53]
	v_lshlrev_b32_e32 v80, 16, v132
	s_waitcnt lgkmcnt(0)
	v_and_b32_e32 v81, 0xffff0000, v132
	v_lshlrev_b32_e32 v82, 16, v133
	v_and_b32_e32 v83, 0xffff0000, v133
	v_lshlrev_b32_e32 v84, 16, v134
	v_and_b32_e32 v85, 0xffff0000, v134
	v_lshlrev_b32_e32 v86, 16, v135
	v_and_b32_e32 v87, 0xffff0000, v135
	v_pk_add_f32 v[78:79], v[78:79], v[82:83]
	v_pk_add_f32 v[76:77], v[76:77], v[80:81]
	v_pk_add_f32 v[80:81], v[74:75], v[86:87]
	v_pk_add_f32 v[74:75], v[72:73], v[84:85]
	v_mul_f32_e32 v72, v77, v77
	v_mul_f32_e32 v73, v79, v79
	v_fmac_f32_e32 v72, v76, v76
	v_fmac_f32_e32 v73, v78, v78
	v_add_f32_e32 v72, v72, v73
	v_mul_f32_e32 v73, v75, v75
	v_mul_f32_e32 v82, v81, v81
	v_fmac_f32_e32 v73, v74, v74
	v_fmac_f32_e32 v82, v80, v80
	v_add_f32_e32 v73, v73, v82
	v_add_f32_e32 v82, v72, v73
	v_cvt_pk_bf16_f32 v72, v76, v77
	v_lshl_add_u64 v[76:77], s[26:27], 0, v[176:177]
	v_cvt_pk_bf16_f32 v73, v78, v79
	v_cvt_pk_bf16_f32 v74, v74, v75
	v_cvt_pk_bf16_f32 v75, v80, v81
	v_lshl_add_u64 v[76:77], v[168:169], 1, v[76:77]
	global_store_dwordx4 v[76:77], v[72:75], off
	v_lshlrev_b32_e32 v78, 16, v122
	v_and_b32_e32 v79, 0xffff0000, v122
	v_lshlrev_b32_e32 v72, 16, v120
	v_and_b32_e32 v73, 0xffff0000, v120
	v_lshlrev_b32_e32 v74, 16, v121
	v_and_b32_e32 v75, 0xffff0000, v121
	v_lshlrev_b32_e32 v80, 16, v123
	v_and_b32_e32 v81, 0xffff0000, v123
	v_pk_add_f32 v[70:71], v[70:71], v[74:75]
	v_pk_add_f32 v[68:69], v[68:69], v[72:73]
	v_pk_add_f32 v[72:73], v[66:67], v[80:81]
	v_pk_add_f32 v[66:67], v[64:65], v[78:79]
	v_mul_f32_e32 v64, v69, v69
	v_mul_f32_e32 v65, v71, v71
	v_fmac_f32_e32 v64, v68, v68
	v_fmac_f32_e32 v65, v70, v70
	v_add_f32_e32 v64, v64, v65
	v_mul_f32_e32 v65, v67, v67
	v_mul_f32_e32 v74, v73, v73
	v_fmac_f32_e32 v65, v66, v66
	v_fmac_f32_e32 v74, v72, v72
	v_add_f32_e32 v65, v65, v74
	v_add_f32_e32 v64, v64, v65
	v_add_f32_e32 v74, v82, v64
	v_cvt_pk_bf16_f32 v64, v68, v69
	v_cvt_pk_bf16_f32 v65, v70, v71
	v_cvt_pk_bf16_f32 v66, v66, v67
	v_cvt_pk_bf16_f32 v67, v72, v73
	global_store_dwordx4 v[76:77], v[64:67], off offset:256
	s_nop 1
	v_mov_b32_e32 v64, v201
	v_mov_b32_e32 v65, v201
	v_lshlrev_b32_e32 v64, 2, v64
	v_xor_b32_e32 v64, 64, v64
	v_mov_b32_e32 v64, v74
	s_nop 1
	v_permlane16_swap_b32_e32 v64, v74
	s_waitcnt lgkmcnt(0)
	v_add_f32_e32 v64, v74, v64
	v_lshlrev_b32_e32 v65, 2, v65
	v_xor_b32_e32 v65, 0x80, v65
	v_mov_b32_e32 v65, v64
	s_nop 1
	v_permlane32_swap_b32_e32 v65, v64
	s_and_saveexec_b64 s[52:53], s[16:17]
	s_cbranch_execz .LBB0_1089
	s_waitcnt lgkmcnt(0)
	v_add_f32_e32 v66, v64, v65
	v_lshlrev_b64 v[64:65], 6, v[174:175]
	v_lshl_add_u64 v[64:65], s[42:43], 0, v[64:65]
	v_lshl_add_u64 v[64:65], s[50:51], 2, v[64:65]
	s_lshl_b32 s22, s61, 2
	v_lshl_add_u64 v[64:65], v[64:65], 0, s[22:23]
	global_store_dword v[64:65], v66, off
.LBB0_1089:
	s_or_b64 exec, exec, s[52:53]
	v_add_u32_e32 v100, 0x80, v172
	v_ashrrev_i32_e32 v101, 31, v100
	v_lshlrev_b64 v[110:111], 11, v[100:101]
	s_waitcnt lgkmcnt(0)
	v_lshl_add_u64 v[64:65], v[170:171], 0, v[110:111]
	global_load_dwordx4 v[102:105], v[64:65], off
	global_load_dwordx4 v[106:109], v[64:65], off offset:256
	v_add_u32_e32 v96, 0x90, v172
	v_ashrrev_i32_e32 v97, 31, v96
	v_add_u32_e32 v92, 0xa0, v172
	v_lshlrev_b64 v[98:99], 11, v[96:97]
	v_ashrrev_i32_e32 v93, 31, v92
	v_add_u32_e32 v88, 0xb0, v172
	v_lshl_add_u64 v[64:65], v[170:171], 0, v[98:99]
	v_lshlrev_b64 v[94:95], 11, v[92:93]
	v_ashrrev_i32_e32 v89, 31, v88
	global_load_dwordx4 v[84:87], v[64:65], off
	global_load_dwordx4 v[80:83], v[64:65], off offset:256
	v_lshl_add_u64 v[64:65], v[170:171], 0, v[94:95]
	v_lshlrev_b64 v[90:91], 11, v[88:89]
	global_load_dwordx4 v[76:79], v[64:65], off
	global_load_dwordx4 v[72:75], v[64:65], off offset:256
	v_lshl_add_u64 v[64:65], v[170:171], 0, v[90:91]
	global_load_dwordx4 v[68:71], v[64:65], off
	s_nop 0
	global_load_dwordx4 v[64:67], v[64:65], off offset:256
	s_waitcnt vmcnt(7)
	v_lshlrev_b32_e32 v112, 16, v102
	v_and_b32_e32 v113, 0xffff0000, v102
	v_lshlrev_b32_e32 v102, 16, v103
	v_and_b32_e32 v103, 0xffff0000, v103
	v_lshlrev_b32_e32 v114, 16, v104
	v_and_b32_e32 v115, 0xffff0000, v104
	v_lshlrev_b32_e32 v104, 16, v105
	v_and_b32_e32 v105, 0xffff0000, v105
	v_pk_add_f32 v[62:63], v[62:63], v[102:103]
	v_pk_add_f32 v[60:61], v[60:61], v[112:113]
	v_pk_add_f32 v[102:103], v[58:59], v[104:105]
	v_pk_add_f32 v[58:59], v[56:57], v[114:115]
	v_mul_f32_e32 v56, v61, v61
	v_mul_f32_e32 v57, v63, v63
	v_fmac_f32_e32 v56, v60, v60
	v_fmac_f32_e32 v57, v62, v62
	v_add_f32_e32 v56, v56, v57
	v_mul_f32_e32 v57, v59, v59
	v_mul_f32_e32 v104, v103, v103
	v_fmac_f32_e32 v57, v58, v58
	v_fmac_f32_e32 v104, v102, v102
	v_add_f32_e32 v57, v57, v104
	v_add_f32_e32 v104, v56, v57
	v_cvt_pk_bf16_f32 v56, v60, v61
	v_lshl_add_u64 v[60:61], s[26:27], 0, v[110:111]
	v_cvt_pk_bf16_f32 v57, v62, v63
	v_cvt_pk_bf16_f32 v58, v58, v59
	v_cvt_pk_bf16_f32 v59, v102, v103
	v_lshl_add_u64 v[60:61], v[168:169], 1, v[60:61]
	global_store_dwordx4 v[60:61], v[56:59], off
	s_waitcnt vmcnt(7)
	v_lshlrev_b32_e32 v62, 16, v108
	v_and_b32_e32 v63, 0xffff0000, v108
	v_lshlrev_b32_e32 v56, 16, v106
	v_and_b32_e32 v57, 0xffff0000, v106
	v_lshlrev_b32_e32 v58, 16, v107
	v_and_b32_e32 v59, 0xffff0000, v107
	v_lshlrev_b32_e32 v102, 16, v109
	v_and_b32_e32 v103, 0xffff0000, v109
	v_pk_add_f32 v[54:55], v[54:55], v[58:59]
	v_pk_add_f32 v[52:53], v[52:53], v[56:57]
	v_pk_add_f32 v[56:57], v[50:51], v[102:103]
	v_pk_add_f32 v[50:51], v[48:49], v[62:63]
	v_mul_f32_e32 v48, v53, v53
	v_mul_f32_e32 v49, v55, v55
	v_fmac_f32_e32 v48, v52, v52
	v_fmac_f32_e32 v49, v54, v54
	v_add_f32_e32 v48, v48, v49
	v_mul_f32_e32 v49, v51, v51
	v_mul_f32_e32 v58, v57, v57
	v_fmac_f32_e32 v49, v50, v50
	v_fmac_f32_e32 v58, v56, v56
	v_add_f32_e32 v49, v49, v58
	v_add_f32_e32 v48, v48, v49
	v_add_f32_e32 v58, v104, v48
	v_cvt_pk_bf16_f32 v48, v52, v53
	v_cvt_pk_bf16_f32 v49, v54, v55
	v_cvt_pk_bf16_f32 v50, v50, v51
	v_cvt_pk_bf16_f32 v51, v56, v57
	global_store_dwordx4 v[60:61], v[48:51], off offset:256
	s_nop 1
	v_mov_b32_e32 v48, v201
	v_mov_b32_e32 v49, v201
	v_lshlrev_b32_e32 v48, 2, v48
	v_xor_b32_e32 v48, 64, v48
	v_mov_b32_e32 v48, v58
	s_nop 1
	v_permlane16_swap_b32_e32 v48, v58
	s_waitcnt lgkmcnt(0)
	v_add_f32_e32 v48, v58, v48
	v_lshlrev_b32_e32 v49, 2, v49
	v_xor_b32_e32 v49, 0x80, v49
	v_mov_b32_e32 v49, v48
	s_nop 1
	v_permlane32_swap_b32_e32 v49, v48
	s_and_saveexec_b64 s[52:53], s[16:17]
	s_cbranch_execz .LBB0_1091
	s_waitcnt lgkmcnt(0)
	v_add_f32_e32 v50, v48, v49
	v_lshlrev_b64 v[48:49], 6, v[100:101]
	v_lshl_add_u64 v[48:49], s[42:43], 0, v[48:49]
	v_lshl_add_u64 v[48:49], s[50:51], 2, v[48:49]
	s_lshl_b32 s22, s61, 2
	v_lshl_add_u64 v[48:49], v[48:49], 0, s[22:23]
	global_store_dword v[48:49], v50, off
; __device__ __forceinline__ float sq4(f32x4 v) { return (v[0] * v[0] + v[1] * v[1]) + (v[2] * v[2] + v[3] * v[3]); }
; __device__ __forceinline__ u32x4 pack8(f32x4 a, f32x4 b) { u32x4 w; w.x = cvt_pk_bf16(a[0], a[1]); w.y = cvt_pk_bf16(a[2], a[3]); w.z = cvt_pk_bf16(b[0], b[1]); w.w = cvt_pk_bf16(b[2], b[3]); return w; }
;     __device__ __forceinline__ void operator()(const f32x4 (&acc)[2][2][4][2], const Unit& u, int wr, int wc, int fr, int fq) const {
;     ...
;             for (int m = 0; m < 4; ++m) {
;                 const int row = u.pm * BM + ai * HALF + wr * 64 + m * 16 + fr;
;                 float q = 0.f;
; #pragma unroll
;                 for (int bj = 0; bj < 2; ++bj) {
;                     const size_t off = (size_t)row * 1024 + col0 + 128 * bj; const u32x4 w = bs[m][bj];
;                     const f32x4 b0 = (f32x4){__builtin_bit_cast(float, w.x << 16), __builtin_bit_cast(float, w.x & 0xffff0000u), __builtin_bit_cast(float, w.y << 16), __builtin_bit_cast(float, w.y & 0xffff0000u)};
;                     const f32x4 b1 = (f32x4){__builtin_bit_cast(float, w.z << 16), __builtin_bit_cast(float, w.z & 0xffff0000u), __builtin_bit_cast(float, w.w << 16), __builtin_bit_cast(float, w.w & 0xffff0000u)};
;                     const f32x4 v0 = acc[ai][bj][m][0] + b0, v1 = acc[ai][bj][m][1] + b1;
;                     if (last) { __builtin_nontemporal_store(v0, (f32x4*)(out + off)); __builtin_nontemporal_store(v1, (f32x4*)(out + off + 4)); }
;                     else { q += sq4(v0) + sq4(v1); *(u32x4*)(xb + off) = pack8(v0, v1); }
;                 }
;                 if (!last) { q += shx(q, 16); q += shx(q, 32); if (fq == 0) ss[(size_t)row * 16 + u.pn * 4 + wc] = q; }
.LBB0_1091:
	s_or_b64 exec, exec, s[52:53]
	s_waitcnt vmcnt(7)
	v_lshlrev_b32_e32 v48, 16, v84
	s_waitcnt lgkmcnt(0)
	v_and_b32_e32 v49, 0xffff0000, v84
	v_lshlrev_b32_e32 v50, 16, v85
	v_and_b32_e32 v51, 0xffff0000, v85
	v_lshlrev_b32_e32 v52, 16, v86
	v_and_b32_e32 v53, 0xffff0000, v86
	v_lshlrev_b32_e32 v54, 16, v87
	v_and_b32_e32 v55, 0xffff0000, v87
	v_pk_add_f32 v[46:47], v[46:47], v[50:51]
	v_pk_add_f32 v[44:45], v[44:45], v[48:49]
	v_pk_add_f32 v[48:49], v[42:43], v[54:55]
	v_pk_add_f32 v[42:43], v[40:41], v[52:53]
	v_mul_f32_e32 v40, v45, v45
	v_mul_f32_e32 v41, v47, v47
	v_fmac_f32_e32 v40, v44, v44
	v_fmac_f32_e32 v41, v46, v46
	v_add_f32_e32 v40, v40, v41
	v_mul_f32_e32 v41, v43, v43
	v_mul_f32_e32 v50, v49, v49
	v_fmac_f32_e32 v41, v42, v42
	v_fmac_f32_e32 v50, v48, v48
	v_add_f32_e32 v41, v41, v50
	v_add_f32_e32 v50, v40, v41
	v_cvt_pk_bf16_f32 v40, v44, v45
	v_lshl_add_u64 v[44:45], s[26:27], 0, v[98:99]
	v_cvt_pk_bf16_f32 v41, v46, v47
	v_cvt_pk_bf16_f32 v42, v42, v43
	v_cvt_pk_bf16_f32 v43, v48, v49
	v_lshl_add_u64 v[44:45], v[168:169], 1, v[44:45]
	global_store_dwordx4 v[44:45], v[40:43], off
	s_waitcnt vmcnt(7)
	v_lshlrev_b32_e32 v46, 16, v82
	v_and_b32_e32 v47, 0xffff0000, v82
	v_lshlrev_b32_e32 v40, 16, v80
	v_and_b32_e32 v41, 0xffff0000, v80
	v_lshlrev_b32_e32 v42, 16, v81
	v_and_b32_e32 v43, 0xffff0000, v81
	v_lshlrev_b32_e32 v48, 16, v83
	v_and_b32_e32 v49, 0xffff0000, v83
	v_pk_add_f32 v[38:39], v[38:39], v[42:43]
	v_pk_add_f32 v[36:37], v[36:37], v[40:41]
	v_pk_add_f32 v[40:41], v[34:35], v[48:49]
	v_pk_add_f32 v[34:35], v[32:33], v[46:47]
	v_mul_f32_e32 v32, v37, v37
	v_mul_f32_e32 v33, v39, v39
	v_fmac_f32_e32 v32, v36, v36
	v_fmac_f32_e32 v33, v38, v38
	v_add_f32_e32 v32, v32, v33
	v_mul_f32_e32 v33, v35, v35
	v_mul_f32_e32 v42, v41, v41
	v_fmac_f32_e32 v33, v34, v34
	v_fmac_f32_e32 v42, v40, v40
	v_add_f32_e32 v33, v33, v42
	v_add_f32_e32 v32, v32, v33
	v_add_f32_e32 v42, v50, v32
	v_cvt_pk_bf16_f32 v32, v36, v37
	v_cvt_pk_bf16_f32 v33, v38, v39
	v_cvt_pk_bf16_f32 v34, v34, v35
	v_cvt_pk_bf16_f32 v35, v40, v41
	global_store_dwordx4 v[44:45], v[32:35], off offset:256
	s_nop 1
	v_mov_b32_e32 v32, v201
	v_mov_b32_e32 v33, v201
	v_lshlrev_b32_e32 v32, 2, v32
	v_xor_b32_e32 v32, 64, v32
	v_mov_b32_e32 v32, v42
	s_nop 1
	v_permlane16_swap_b32_e32 v32, v42
	s_waitcnt lgkmcnt(0)
	v_add_f32_e32 v32, v42, v32
	v_lshlrev_b32_e32 v33, 2, v33
	v_xor_b32_e32 v33, 0x80, v33
	v_mov_b32_e32 v33, v32
	s_nop 1
	v_permlane32_swap_b32_e32 v33, v32
	s_and_saveexec_b64 s[52:53], s[16:17]
	s_cbranch_execz .LBB0_1093
	s_waitcnt lgkmcnt(0)
	v_add_f32_e32 v34, v32, v33
	v_lshlrev_b64 v[32:33], 6, v[96:97]
	v_lshl_add_u64 v[32:33], s[42:43], 0, v[32:33]
	v_lshl_add_u64 v[32:33], s[50:51], 2, v[32:33]
	s_lshl_b32 s22, s61, 2
	v_lshl_add_u64 v[32:33], v[32:33], 0, s[22:23]
	global_store_dword v[32:33], v34, off
; __device__ __forceinline__ float sq4(f32x4 v) { return (v[0] * v[0] + v[1] * v[1]) + (v[2] * v[2] + v[3] * v[3]); }
; __device__ __forceinline__ u32x4 pack8(f32x4 a, f32x4 b) { u32x4 w; w.x = cvt_pk_bf16(a[0], a[1]); w.y = cvt_pk_bf16(a[2], a[3]); w.z = cvt_pk_bf16(b[0], b[1]); w.w = cvt_pk_bf16(b[2], b[3]); return w; }
;     __device__ __forceinline__ void operator()(const f32x4 (&acc)[2][2][4][2], const Unit& u, int wr, int wc, int fr, int fq) const {
;     ...
;             for (int m = 0; m < 4; ++m) {
;                 const int row = u.pm * BM + ai * HALF + wr * 64 + m * 16 + fr;
;                 float q = 0.f;
; #pragma unroll
;                 for (int bj = 0; bj < 2; ++bj) {
;                     const size_t off = (size_t)row * 1024 + col0 + 128 * bj; const u32x4 w = bs[m][bj];
;                     const f32x4 b0 = (f32x4){__builtin_bit_cast(float, w.x << 16), __builtin_bit_cast(float, w.x & 0xffff0000u), __builtin_bit_cast(float, w.y << 16), __builtin_bit_cast(float, w.y & 0xffff0000u)};
;                     const f32x4 b1 = (f32x4){__builtin_bit_cast(float, w.z << 16), __builtin_bit_cast(float, w.z & 0xffff0000u), __builtin_bit_cast(float, w.w << 16), __builtin_bit_cast(float, w.w & 0xffff0000u)};
;                     const f32x4 v0 = acc[ai][bj][m][0] + b0, v1 = acc[ai][bj][m][1] + b1;
;                     if (last) { __builtin_nontemporal_store(v0, (f32x4*)(out + off)); __builtin_nontemporal_store(v1, (f32x4*)(out + off + 4)); }
;                     else { q += sq4(v0) + sq4(v1); *(u32x4*)(xb + off) = pack8(v0, v1); }
;                 }
;                 if (!last) { q += shx(q, 16); q += shx(q, 32); if (fq == 0) ss[(size_t)row * 16 + u.pn * 4 + wc] = q; }
.LBB0_1093:
	s_or_b64 exec, exec, s[52:53]
	s_waitcnt vmcnt(7)
	v_lshlrev_b32_e32 v32, 16, v76
	s_waitcnt lgkmcnt(0)
	v_and_b32_e32 v33, 0xffff0000, v76
	v_lshlrev_b32_e32 v34, 16, v77
	v_and_b32_e32 v35, 0xffff0000, v77
	v_lshlrev_b32_e32 v36, 16, v78
	v_and_b32_e32 v37, 0xffff0000, v78
	v_lshlrev_b32_e32 v38, 16, v79
	v_and_b32_e32 v39, 0xffff0000, v79
	v_pk_add_f32 v[30:31], v[30:31], v[34:35]
	v_pk_add_f32 v[28:29], v[28:29], v[32:33]
	v_pk_add_f32 v[32:33], v[26:27], v[38:39]
	v_pk_add_f32 v[26:27], v[24:25], v[36:37]
	v_mul_f32_e32 v24, v29, v29
	v_mul_f32_e32 v25, v31, v31
	v_fmac_f32_e32 v24, v28, v28
	v_fmac_f32_e32 v25, v30, v30
	v_add_f32_e32 v24, v24, v25
	v_mul_f32_e32 v25, v27, v27
	v_mul_f32_e32 v34, v33, v33
	v_fmac_f32_e32 v25, v26, v26
	v_fmac_f32_e32 v34, v32, v32
	v_add_f32_e32 v25, v25, v34
	v_add_f32_e32 v34, v24, v25
	v_cvt_pk_bf16_f32 v24, v28, v29
	v_lshl_add_u64 v[28:29], s[26:27], 0, v[94:95]
	v_cvt_pk_bf16_f32 v25, v30, v31
	v_cvt_pk_bf16_f32 v26, v26, v27
	v_cvt_pk_bf16_f32 v27, v32, v33
	v_lshl_add_u64 v[28:29], v[168:169], 1, v[28:29]
	global_store_dwordx4 v[28:29], v[24:27], off
	s_waitcnt vmcnt(7)
	v_lshlrev_b32_e32 v30, 16, v74
	v_and_b32_e32 v31, 0xffff0000, v74
	v_lshlrev_b32_e32 v24, 16, v72
	v_and_b32_e32 v25, 0xffff0000, v72
	v_lshlrev_b32_e32 v26, 16, v73
	v_and_b32_e32 v27, 0xffff0000, v73
	v_lshlrev_b32_e32 v32, 16, v75
	v_and_b32_e32 v33, 0xffff0000, v75
	v_pk_add_f32 v[22:23], v[22:23], v[26:27]
	v_pk_add_f32 v[20:21], v[20:21], v[24:25]
	v_pk_add_f32 v[24:25], v[18:19], v[32:33]
	v_pk_add_f32 v[18:19], v[16:17], v[30:31]
	v_mul_f32_e32 v16, v21, v21
	v_mul_f32_e32 v17, v23, v23
	v_fmac_f32_e32 v16, v20, v20
	v_fmac_f32_e32 v17, v22, v22
	v_add_f32_e32 v16, v16, v17
	v_mul_f32_e32 v17, v19, v19
	v_mul_f32_e32 v26, v25, v25
	v_fmac_f32_e32 v17, v18, v18
	v_fmac_f32_e32 v26, v24, v24
	v_add_f32_e32 v17, v17, v26
	v_add_f32_e32 v16, v16, v17
	v_add_f32_e32 v26, v34, v16
	v_cvt_pk_bf16_f32 v16, v20, v21
	v_cvt_pk_bf16_f32 v17, v22, v23
	v_cvt_pk_bf16_f32 v18, v18, v19
	v_cvt_pk_bf16_f32 v19, v24, v25
	global_store_dwordx4 v[28:29], v[16:19], off offset:256
	s_nop 1
	v_mov_b32_e32 v16, v201
	v_mov_b32_e32 v17, v201
	v_lshlrev_b32_e32 v16, 2, v16
	v_xor_b32_e32 v16, 64, v16
	v_mov_b32_e32 v16, v26
	s_nop 1
	v_permlane16_swap_b32_e32 v16, v26
	s_waitcnt lgkmcnt(0)
	v_add_f32_e32 v16, v26, v16
	v_lshlrev_b32_e32 v17, 2, v17
	v_xor_b32_e32 v17, 0x80, v17
	v_mov_b32_e32 v17, v16
	s_nop 1
	v_permlane32_swap_b32_e32 v17, v16
	s_and_saveexec_b64 s[52:53], s[16:17]
	s_cbranch_execz .LBB0_1095
	s_waitcnt lgkmcnt(0)
	v_add_f32_e32 v18, v16, v17
	v_lshlrev_b64 v[16:17], 6, v[92:93]
	v_lshl_add_u64 v[16:17], s[42:43], 0, v[16:17]
	v_lshl_add_u64 v[16:17], s[50:51], 2, v[16:17]
	s_lshl_b32 s22, s61, 2
	v_lshl_add_u64 v[16:17], v[16:17], 0, s[22:23]
	global_store_dword v[16:17], v18, off
.LBB0_1095:
	s_or_b64 exec, exec, s[52:53]
	s_waitcnt vmcnt(7)
	v_lshlrev_b32_e32 v16, 16, v68
	s_waitcnt lgkmcnt(0)
	v_and_b32_e32 v17, 0xffff0000, v68
	v_lshlrev_b32_e32 v18, 16, v69
	v_and_b32_e32 v19, 0xffff0000, v69
	v_lshlrev_b32_e32 v20, 16, v70
	v_and_b32_e32 v21, 0xffff0000, v70
	v_lshlrev_b32_e32 v22, 16, v71
	v_and_b32_e32 v23, 0xffff0000, v71
	v_pk_add_f32 v[14:15], v[14:15], v[18:19]
	v_pk_add_f32 v[12:13], v[12:13], v[16:17]
	v_pk_add_f32 v[16:17], v[10:11], v[22:23]
	v_pk_add_f32 v[10:11], v[8:9], v[20:21]
	v_mul_f32_e32 v8, v13, v13
	v_mul_f32_e32 v9, v15, v15
	v_fmac_f32_e32 v8, v12, v12
	v_fmac_f32_e32 v9, v14, v14
	v_add_f32_e32 v8, v8, v9
	v_mul_f32_e32 v9, v11, v11
	v_mul_f32_e32 v18, v17, v17
	v_fmac_f32_e32 v9, v10, v10
	v_fmac_f32_e32 v18, v16, v16
	v_add_f32_e32 v9, v9, v18
	v_add_f32_e32 v18, v8, v9
	v_cvt_pk_bf16_f32 v8, v12, v13
	v_lshl_add_u64 v[12:13], s[26:27], 0, v[90:91]
	v_cvt_pk_bf16_f32 v9, v14, v15
	v_cvt_pk_bf16_f32 v10, v10, v11
	v_cvt_pk_bf16_f32 v11, v16, v17
	v_lshl_add_u64 v[12:13], v[168:169], 1, v[12:13]
	global_store_dwordx4 v[12:13], v[8:11], off
	s_waitcnt vmcnt(7)
	v_lshlrev_b32_e32 v14, 16, v66
	v_and_b32_e32 v15, 0xffff0000, v66
	v_lshlrev_b32_e32 v8, 16, v64
	v_and_b32_e32 v9, 0xffff0000, v64
	v_lshlrev_b32_e32 v10, 16, v65
	v_and_b32_e32 v11, 0xffff0000, v65
	v_lshlrev_b32_e32 v16, 16, v67
	v_and_b32_e32 v17, 0xffff0000, v67
	v_pk_add_f32 v[6:7], v[6:7], v[10:11]
	v_pk_add_f32 v[4:5], v[4:5], v[8:9]
	v_pk_add_f32 v[8:9], v[2:3], v[16:17]
	v_pk_add_f32 v[2:3], v[0:1], v[14:15]
	v_mul_f32_e32 v0, v5, v5
	v_mul_f32_e32 v1, v7, v7
	v_fmac_f32_e32 v0, v4, v4
	v_fmac_f32_e32 v1, v6, v6
	v_add_f32_e32 v0, v0, v1
	v_mul_f32_e32 v1, v3, v3
	v_mul_f32_e32 v10, v9, v9
	v_fmac_f32_e32 v1, v2, v2
	v_fmac_f32_e32 v10, v8, v8
	v_add_f32_e32 v1, v1, v10
	v_add_f32_e32 v0, v0, v1
	v_add_f32_e32 v10, v18, v0
	v_cvt_pk_bf16_f32 v0, v4, v5
	v_cvt_pk_bf16_f32 v1, v6, v7
	v_cvt_pk_bf16_f32 v2, v2, v3
	v_cvt_pk_bf16_f32 v3, v8, v9
	global_store_dwordx4 v[12:13], v[0:3], off offset:256
	s_nop 1
	v_mov_b32_e32 v0, v201
	v_mov_b32_e32 v1, v201
	v_lshlrev_b32_e32 v0, 2, v0
	v_xor_b32_e32 v0, 64, v0
	v_mov_b32_e32 v0, v10
	s_nop 1
	v_permlane16_swap_b32_e32 v0, v10
	s_waitcnt lgkmcnt(0)
	v_add_f32_e32 v0, v10, v0
	v_lshlrev_b32_e32 v1, 2, v1
	v_xor_b32_e32 v1, 0x80, v1
	v_mov_b32_e32 v1, v0
	s_nop 1
	v_permlane32_swap_b32_e32 v1, v0
	s_and_saveexec_b64 s[52:53], s[16:17]
	s_cbranch_execz .LBB0_1097
	s_waitcnt lgkmcnt(0)
	v_add_f32_e32 v2, v0, v1
	v_lshlrev_b64 v[0:1], 6, v[88:89]
	v_lshl_add_u64 v[0:1], s[42:43], 0, v[0:1]
	v_lshl_add_u64 v[0:1], s[50:51], 2, v[0:1]
	s_lshl_b32 s22, s61, 2
	v_lshl_add_u64 v[0:1], v[0:1], 0, s[22:23]
	global_store_dword v[0:1], v2, off

; __device__ __forceinline__ float row_part(const float* ss, int row, int fq) { const f32x4 a = ((const f32x4*)(ss + (size_t)row * 16))[fq]; return (a[0] + a[1]) + (a[2] + a[3]); }
; __device__ __forceinline__ float row_finish(float t) { t += shx(t, 16); t += shx(t, 32); return __builtin_amdgcn_rsqf(t * (1.0f / 1024.0f) + RMS_EPS); }
;     __device__ __forceinline__ void operator()(const f32x4 (&acc)[2][2][4][2], const Unit& u, int wr, int wc, int fr, int fq) const {
;         const int g = u.pn * 4 + wc;
;         int mode = 0; const float* w = mqw; float sc = 1.f, nsc = 1.f;
;         if (g >= 36) { mode = 2; w = mqw; nsc = qscale; }
;         else if (diff) { if (g < 12) { mode = 2; w = qw; nsc = qscale; } else if (g < 24) { mode = 2; w = kw; } }
;         else { if (g >= 6 && g < 12) sc = 0.125f; else if (g >= 24) mode = 1; }
;         f32x4 wv[2][2];
; #pragma unroll
;         for (int bj = 0; bj < 2; ++bj)
; #pragma unroll
;             for (int n = 0; n < 2; ++n) wv[bj][n] = *(const f32x4*)(w + 32 * bj + 8 * fq + 4 * n) * nsc;
;         const int lcol = u.pn * 256 + 64 * wc + 8 * fq;
;         float rs[2][4];
; #pragma unroll
;         for (int ai = 0; ai < 2; ++ai)
; #pragma unroll
;             for (int m = 0; m < 4; ++m) rs[ai][m] = row_part(ss, u.pm * BM + ai * HALF + wr * 64 + m * 16 + fr, fq);
.LBB0_1191:
	global_load_dwordx4 v[148:151], v[138:139], off offset:528
	global_load_dwordx4 v[152:155], v[138:139], off offset:512
	global_load_dwordx4 v[166:169], v[138:139], off offset:656
	global_load_dwordx4 v[170:173], v[138:139], off offset:640
	s_lshl_b32 s0, s50, 2
	s_or_b32 s4, s0, s67
	s_cmp_gt_i32 s4, 35
	s_cselect_b64 s[48:49], -1, 0
	s_cmp_lt_i32 s4, 36
	s_cselect_b64 s[56:57], -1, 0
	s_add_i32 s4, s4, -12
	s_cmp_lt_u32 s4, -6
	s_cselect_b64 s[54:55], -1, 0
	s_sub_i32 s0, s0, 24
	s_cmp_gt_u32 s0, 11
	s_cselect_b64 s[46:47], -1, 0
	s_lshl_b32 s0, s52, 8
	v_add_u32_e32 v176, s0, v192
	v_cndmask_b32_e64 v158, v203, 1.0, s[56:57]
	v_ashrrev_i32_e32 v177, 31, v176
	v_add_u32_e32 v174, 0x80, v176
	v_ashrrev_i32_e32 v175, 31, v174
	s_mov_b64 s[52:53], -1
	s_and_b64 vcc, exec, s[56:57]
	s_waitcnt vmcnt(0)
	v_pk_mul_f32 v[150:151], v[158:159], v[150:151] op_sel_hi:[0,1]
	v_pk_mul_f32 v[160:161], v[158:159], v[152:153] op_sel_hi:[0,1]
	v_pk_mul_f32 v[152:153], v[158:159], v[148:149] op_sel_hi:[0,1]
	v_lshlrev_b64 v[148:149], 6, v[176:177]
	v_lshl_add_u64 v[148:149], v[136:137], 0, v[148:149]
	v_pk_mul_f32 v[156:157], v[158:159], v[154:155] op_sel_hi:[0,1]
	v_pk_mul_f32 v[162:163], v[158:159], v[172:173] op_sel_hi:[0,1]
	v_pk_mul_f32 v[164:165], v[158:159], v[170:171] op_sel_hi:[0,1]
	v_pk_mul_f32 v[154:155], v[158:159], v[168:169] op_sel_hi:[0,1]
	v_pk_mul_f32 v[158:159], v[158:159], v[166:167] op_sel_hi:[0,1]
	ds_read_b128 v[166:169], v239
	v_add_u32_e32 v172, 0x90, v176
	v_ashrrev_i32_e32 v173, 31, v172
	s_waitcnt lgkmcnt(0)
	v_mov_b32_e32 v148, v167
	v_mov_b32_e32 v149, v168
	v_mov_b32_e32 v167, v169
	v_pk_add_f32 v[148:149], v[148:149], v[166:167]
	s_nop 0
	v_add_f32_e32 v177, v148, v149
	v_or_b32_e32 v148, 16, v176
	v_ashrrev_i32_e32 v149, 31, v148
	v_lshlrev_b64 v[148:149], 6, v[148:149]
	v_lshl_add_u64 v[148:149], v[136:137], 0, v[148:149]
	ds_read_b128 v[166:169], v239 offset:1024
	s_waitcnt lgkmcnt(0)
	v_add_f32_e32 v148, v166, v167
	v_add_f32_e32 v149, v168, v169
	v_add_f32_e32 v178, v148, v149
	v_or_b32_e32 v148, 32, v176
	v_ashrrev_i32_e32 v149, 31, v148
	v_lshlrev_b64 v[148:149], 6, v[148:149]
	v_lshl_add_u64 v[148:149], v[136:137], 0, v[148:149]
	ds_read_b128 v[166:169], v239 offset:2048
	s_waitcnt lgkmcnt(0)
	v_add_f32_e32 v148, v166, v167
	v_add_f32_e32 v149, v168, v169
	v_add_f32_e32 v179, v148, v149
	v_or_b32_e32 v148, 48, v176
	v_ashrrev_i32_e32 v149, 31, v148
	v_lshlrev_b64 v[148:149], 6, v[148:149]
	v_lshl_add_u64 v[148:149], v[136:137], 0, v[148:149]
	ds_read_b128 v[166:169], v239 offset:3072
	s_waitcnt lgkmcnt(0)
	v_add_f32_e32 v148, v166, v167
	v_add_f32_e32 v149, v168, v169
	v_add_f32_e32 v180, v148, v149
	v_lshlrev_b64 v[148:149], 6, v[174:175]
	v_lshl_add_u64 v[148:149], v[136:137], 0, v[148:149]
	ds_read_b128 v[166:169], v239 offset:8192
	s_waitcnt lgkmcnt(0)
	v_add_f32_e32 v148, v166, v167
	v_add_f32_e32 v149, v168, v169
	v_add_f32_e32 v175, v148, v149
	v_lshlrev_b64 v[148:149], 6, v[172:173]
	v_lshl_add_u64 v[148:149], v[136:137], 0, v[148:149]
	ds_read_b128 v[166:169], v239 offset:9216
	s_waitcnt lgkmcnt(0)
	v_add_f32_e32 v148, v166, v167
	v_add_u32_e32 v166, 0xa0, v176
	v_add_f32_e32 v149, v168, v169
	v_ashrrev_i32_e32 v167, 31, v166
	v_add_f32_e32 v173, v148, v149
	v_lshlrev_b64 v[148:149], 6, v[166:167]
	v_lshl_add_u64 v[148:149], v[136:137], 0, v[148:149]
	ds_read_b128 v[168:171], v239 offset:10240
	s_waitcnt lgkmcnt(0)
	v_add_f32_e32 v148, v168, v169
	v_add_f32_e32 v149, v170, v171
	v_add_f32_e32 v167, v148, v149
	v_add_u32_e32 v148, 0xb0, v176
	v_ashrrev_i32_e32 v149, 31, v148
	v_lshlrev_b64 v[168:169], 6, v[148:149]
	v_lshl_add_u64 v[168:169], v[136:137], 0, v[168:169]
	ds_read_b128 v[168:171], v239 offset:11264
	s_waitcnt lgkmcnt(0)
	v_add_f32_e32 v149, v168, v169
	v_add_f32_e32 v168, v170, v171
	v_add_f32_e32 v149, v149, v168
	v_mov_b32_e32 v168, v201
	v_mov_b32_e32 v169, v201
	v_lshlrev_b32_e32 v168, 2, v168
	v_xor_b32_e32 v168, 64, v168
	v_mov_b32_e32 v168, v177
	s_nop 1
	v_permlane16_swap_b32_e32 v168, v177
	s_waitcnt lgkmcnt(0)
	v_add_f32_e32 v168, v177, v168
	v_lshlrev_b32_e32 v169, 2, v169
	v_xor_b32_e32 v169, 0x80, v169
	v_mov_b32_e32 v169, v168
	s_nop 1
	v_permlane32_swap_b32_e32 v169, v168
	s_waitcnt lgkmcnt(0)
	v_add_f32_e32 v168, v168, v169
	v_mov_b32_e32 v169, v201
	v_fmamk_f32 v168, v168, 0x3a800000, v202
	v_lshlrev_b32_e32 v169, 2, v169
	v_xor_b32_e32 v169, 64, v169
	v_mov_b32_e32 v169, v178
	s_nop 1
	v_permlane16_swap_b32_e32 v169, v178
	v_rsq_f32_e32 v168, v168
	s_waitcnt lgkmcnt(0)
	v_add_f32_e32 v212, v178, v169
	v_mov_b32_e32 v169, v201
	s_nop 0
	v_lshlrev_b32_e32 v169, 2, v169
	v_xor_b32_e32 v169, 0x80, v169
	v_mov_b32_e32 v213, v212
	s_nop 1
	v_permlane32_swap_b32_e32 v213, v212
	v_mov_b32_e32 v169, v201
	s_nop 0
	v_lshlrev_b32_e32 v169, 2, v169
	v_xor_b32_e32 v169, 64, v169
	v_mov_b32_e32 v169, v179
	s_nop 1
	v_permlane16_swap_b32_e32 v169, v179
	s_waitcnt lgkmcnt(0)
; __device__ __forceinline__ float sq4(f32x4 v) { return (v[0] * v[0] + v[1] * v[1]) + (v[2] * v[2] + v[3] * v[3]); }
; __device__ __forceinline__ float row_finish(float t) { t += shx(t, 16); t += shx(t, 32); return __builtin_amdgcn_rsqf(t * (1.0f / 1024.0f) + RMS_EPS); }
;     __device__ __forceinline__ void operator()(const f32x4 (&acc)[2][2][4][2], const Unit& u, int wr, int wc, int fr, int fq) const {
;     ...
;             for (int m = 0; m < 4; ++m) rs[ai][m] = row_finish(rs[ai][m]);
; #pragma unroll
;         for (int ai = 0; ai < 2; ++ai)
; #pragma unroll
;             for (int m = 0; m < 4; ++m) {
;                 const int row = u.pm * BM + ai * HALF + wr * 64 + m * 16 + fr;
;                 const float rstd = rs[ai][m];
;                 f32x4 v[2][2];
; #pragma unroll
;                 for (int bj = 0; bj < 2; ++bj)
; #pragma unroll
;                     for (int n = 0; n < 2; ++n) v[bj][n] = acc[ai][bj][m][n] * rstd;
;                 if (mode == 2) {
;                     float q = (sq4(v[0][0]) + sq4(v[0][1])) + (sq4(v[1][0]) + sq4(v[1][1]));
;                     q += shx(q, 16); q += shx(q, 32);
;                     const float r2 = __builtin_amdgcn_rsqf(q * (1.0f / 64.0f) + RMS_EPS);
; #pragma unroll
;                     for (int bj = 0; bj < 2; ++bj)
; #pragma unroll
;                         for (int n = 0; n < 2; ++n) v[bj][n] = v[bj][n] * r2 * wv[bj][n];
	v_add_f32_e32 v210, v179, v169
	v_mov_b32_e32 v169, v201
	s_nop 0
	v_lshlrev_b32_e32 v169, 2, v169
	v_xor_b32_e32 v169, 0x80, v169
	v_mov_b32_e32 v211, v210
	s_nop 1
	v_permlane32_swap_b32_e32 v211, v210
	v_mov_b32_e32 v169, v201
	s_nop 0
	v_lshlrev_b32_e32 v169, 2, v169
	v_xor_b32_e32 v169, 64, v169
	v_mov_b32_e32 v169, v180
	s_nop 1
	v_permlane16_swap_b32_e32 v169, v180
	s_waitcnt lgkmcnt(0)
	v_add_f32_e32 v208, v180, v169
	v_mov_b32_e32 v169, v201
	s_nop 0
	v_lshlrev_b32_e32 v169, 2, v169
	v_xor_b32_e32 v169, 0x80, v169
	v_mov_b32_e32 v209, v208
	s_nop 1
	v_permlane32_swap_b32_e32 v209, v208
	v_mov_b32_e32 v169, v201
	s_nop 0
	v_lshlrev_b32_e32 v169, 2, v169
	v_xor_b32_e32 v169, 64, v169
	v_mov_b32_e32 v169, v175
	s_nop 1
	v_permlane16_swap_b32_e32 v169, v175
	s_waitcnt lgkmcnt(0)
	v_add_f32_e32 v206, v175, v169
	v_mov_b32_e32 v169, v201
	s_nop 0
	v_lshlrev_b32_e32 v169, 2, v169
	v_xor_b32_e32 v169, 0x80, v169
	v_mov_b32_e32 v207, v206
	s_nop 1
	v_permlane32_swap_b32_e32 v207, v206
	v_mov_b32_e32 v169, v201
	s_nop 0
	v_lshlrev_b32_e32 v169, 2, v169
	v_xor_b32_e32 v169, 64, v169
	v_mov_b32_e32 v169, v173
	s_nop 1
	v_permlane16_swap_b32_e32 v169, v173
	s_waitcnt lgkmcnt(0)
	v_add_f32_e32 v177, v173, v169
	v_mov_b32_e32 v169, v201
	s_nop 0
	v_lshlrev_b32_e32 v169, 2, v169
	v_xor_b32_e32 v169, 0x80, v169
	v_mov_b32_e32 v205, v177
	s_nop 1
	v_permlane32_swap_b32_e32 v205, v177
	v_mov_b32_e32 v169, v201
	s_nop 0
	v_lshlrev_b32_e32 v169, 2, v169
	v_xor_b32_e32 v169, 64, v169
	v_mov_b32_e32 v169, v167
	s_nop 1
	v_permlane16_swap_b32_e32 v169, v167
	s_waitcnt lgkmcnt(0)
	v_add_f32_e32 v173, v167, v169
	v_mov_b32_e32 v167, v201
	v_pk_mul_f32 v[188:189], v[126:127], v[168:169] op_sel_hi:[1,0]
	v_lshlrev_b32_e32 v167, 2, v167
	v_xor_b32_e32 v167, 0x80, v167
	v_mov_b32_e32 v175, v173
	s_nop 1
	v_permlane32_swap_b32_e32 v175, v173
	v_mov_b32_e32 v167, v201
	v_pk_mul_f32 v[190:191], v[124:125], v[168:169] op_sel_hi:[1,0]
	v_lshlrev_b32_e32 v167, 2, v167
	v_xor_b32_e32 v167, 64, v167
	v_mov_b32_e32 v167, v149
	s_nop 1
	v_permlane16_swap_b32_e32 v167, v149
	v_pk_mul_f32 v[184:185], v[122:123], v[168:169] op_sel_hi:[1,0]
	v_pk_mul_f32 v[186:187], v[120:121], v[168:169] op_sel_hi:[1,0]
	v_pk_mul_f32 v[180:181], v[118:119], v[168:169] op_sel_hi:[1,0]
	v_pk_mul_f32 v[182:183], v[116:117], v[168:169] op_sel_hi:[1,0]
	s_waitcnt lgkmcnt(0)
	v_add_f32_e32 v149, v149, v167
	v_mov_b32_e32 v167, v201
	v_pk_mul_f32 v[178:179], v[114:115], v[168:169] op_sel_hi:[1,0]
	v_lshlrev_b32_e32 v167, 2, v167
	v_xor_b32_e32 v167, 0x80, v167
	v_mov_b32_e32 v167, v149
	s_nop 1
	v_permlane32_swap_b32_e32 v167, v149
	v_pk_mul_f32 v[170:171], v[112:113], v[168:169] op_sel_hi:[1,0]
	s_cbranch_vccnz .LBB0_1193
	v_mov_b32_e32 v114, v191
	v_mov_b32_e32 v115, v183
	v_mov_b32_e32 v112, v190
	v_mov_b32_e32 v113, v182
	v_pk_mul_f32 v[114:115], v[114:115], v[114:115]
	v_mov_b32_e32 v116, v189
	v_mov_b32_e32 v117, v181
	v_pk_fma_f32 v[112:113], v[112:113], v[112:113], v[114:115]
	v_mov_b32_e32 v114, v188
	v_mov_b32_e32 v115, v180
	v_pk_mul_f32 v[116:117], v[116:117], v[116:117]
	v_mov_b32_e32 v118, v185
	v_pk_fma_f32 v[114:115], v[114:115], v[114:115], v[116:117]
	v_mov_b32_e32 v116, v187
	v_mov_b32_e32 v117, v171
	v_pk_add_f32 v[112:113], v[112:113], v[114:115]
	v_mov_b32_e32 v114, v186
	v_mov_b32_e32 v115, v170
	v_pk_mul_f32 v[116:117], v[116:117], v[116:117]
	v_mov_b32_e32 v119, v179
	v_pk_fma_f32 v[114:115], v[114:115], v[114:115], v[116:117]
	v_mov_b32_e32 v116, v184
	v_mov_b32_e32 v117, v178
	v_pk_mul_f32 v[118:119], v[118:119], v[118:119]
	s_mov_b64 s[52:53], 0
	v_pk_fma_f32 v[116:117], v[116:117], v[116:117], v[118:119]
	s_nop 0
	v_pk_add_f32 v[114:115], v[114:115], v[116:117]
	s_nop 0
	v_pk_add_f32 v[112:113], v[112:113], v[114:115]
	s_nop 0
	v_add_f32_e32 v112, v112, v113
	v_mov_b32_e32 v113, v201
	s_nop 0
	v_lshlrev_b32_e32 v113, 2, v113
	v_xor_b32_e32 v113, 64, v113
	v_mov_b32_e32 v113, v112
	s_nop 1
	v_permlane16_swap_b32_e32 v113, v112
	s_waitcnt lgkmcnt(0)
	v_add_f32_e32 v112, v112, v113
	v_mov_b32_e32 v113, v201
	s_nop 0
	v_lshlrev_b32_e32 v113, 2, v113
	v_xor_b32_e32 v113, 0x80, v113
	v_mov_b32_e32 v113, v112
	s_nop 1
	v_permlane32_swap_b32_e32 v113, v112
	s_waitcnt lgkmcnt(0)
	v_add_f32_e32 v112, v112, v113
	v_fmamk_f32 v112, v112, 0x3c800000, v202
	v_rsq_f32_e32 v124, v112
	s_nop 0
	v_pk_mul_f32 v[112:113], v[190:191], v[124:125] op_sel_hi:[1,0]
	v_pk_mul_f32 v[114:115], v[188:189], v[124:125] op_sel_hi:[1,0]
	v_pk_mul_f32 v[116:117], v[186:187], v[124:125] op_sel_hi:[1,0]
	v_pk_mul_f32 v[118:119], v[184:185], v[124:125] op_sel_hi:[1,0]
	v_pk_mul_f32 v[120:121], v[182:183], v[124:125] op_sel_hi:[1,0]
	v_pk_mul_f32 v[122:123], v[180:181], v[124:125] op_sel_hi:[1,0]
	v_pk_mul_f32 v[168:169], v[170:171], v[124:125] op_sel_hi:[1,0]
	v_pk_mul_f32 v[124:125], v[178:179], v[124:125] op_sel_hi:[1,0]
	v_pk_mul_f32 v[114:115], v[156:157], v[114:115]
	v_pk_mul_f32 v[112:113], v[160:161], v[112:113]
	v_pk_mul_f32 v[118:119], v[150:151], v[118:119]
	v_pk_mul_f32 v[116:117], v[152:153], v[116:117]
	v_pk_mul_f32 v[122:123], v[162:163], v[122:123]
	v_pk_mul_f32 v[120:121], v[164:165], v[120:121]
	v_pk_mul_f32 v[126:127], v[154:155], v[124:125]
	v_pk_mul_f32 v[124:125], v[158:159], v[168:169]

; __device__ __forceinline__ f32x4 silu4(f32x4 v) { return (f32x4){silu_f(v[0]), silu_f(v[1]), silu_f(v[2]), silu_f(v[3])}; }
; __device__ __forceinline__ float sq4(f32x4 v) { return (v[0] * v[0] + v[1] * v[1]) + (v[2] * v[2] + v[3] * v[3]); }
; __device__ __forceinline__ u32x4 pack8(f32x4 a, f32x4 b) { u32x4 w; w.x = cvt_pk_bf16(a[0], a[1]); w.y = cvt_pk_bf16(a[2], a[3]); w.z = cvt_pk_bf16(b[0], b[1]); w.w = cvt_pk_bf16(b[2], b[3]); return w; }
;     __device__ __forceinline__ void operator()(const f32x4 (&acc)[2][2][4][2], const Unit& u, int wr, int wc, int fr, int fq) const {
;     ...
;                 const int row = u.pm * BM + ai * HALF + wr * 64 + m * 16 + fr;
;                 const float rstd = rs[ai][m];
;                 f32x4 v[2][2];
; #pragma unroll
;                 for (int bj = 0; bj < 2; ++bj)
; #pragma unroll
;                     for (int n = 0; n < 2; ++n) v[bj][n] = acc[ai][bj][m][n] * rstd;
;                 if (mode == 2) {
;                     float q = (sq4(v[0][0]) + sq4(v[0][1])) + (sq4(v[1][0]) + sq4(v[1][1]));
;                     q += shx(q, 16); q += shx(q, 32);
;                     const float r2 = __builtin_amdgcn_rsqf(q * (1.0f / 64.0f) + RMS_EPS);
; #pragma unroll
;                     for (int bj = 0; bj < 2; ++bj)
; #pragma unroll
;                         for (int n = 0; n < 2; ++n) v[bj][n] = v[bj][n] * r2 * wv[bj][n];
;                 } else if (mode == 1) {
; #pragma unroll
;                     for (int bj = 0; bj < 2; ++bj)
; #pragma unroll
;                         for (int n = 0; n < 2; ++n) v[bj][n] = silu4(v[bj][n]);
;                 } else {
; #pragma unroll
;                     for (int bj = 0; bj < 2; ++bj)
; #pragma unroll
;                         for (int n = 0; n < 2; ++n) v[bj][n] = v[bj][n] * sc;
;                 }
;                 bf16_t* rowp = U + (size_t)row * 2560 + lcol;
; #pragma unroll
;                 for (int bj = 0; bj < 2; ++bj) *(u32x4*)(rowp + 32 * bj) = pack8(v[bj][0], v[bj][1]);
.LBB0_1198:
	v_add_f32_e32 v170, v212, v213
	v_fmamk_f32 v170, v170, 0x3a800000, v202
	v_rsq_f32_e32 v178, v170
	v_lshl_or_b32 v170, s50, 8, v197
	v_mov_b64_e32 v[180:181], s[18:19]
	v_ashrrev_i32_e32 v171, 31, v170
	v_mad_i64_i32 v[180:181], s[50:51], v176, s12, v[180:181]
	v_lshl_add_u64 v[180:181], v[170:171], 1, v[180:181]
	v_cvt_pk_bf16_f32 v112, v112, v113
	v_cvt_pk_bf16_f32 v113, v114, v115
	v_cvt_pk_bf16_f32 v114, v116, v117
	v_cvt_pk_bf16_f32 v115, v118, v119
	global_store_dwordx4 v[180:181], v[112:115], off
	v_pk_mul_f32 v[116:117], v[102:103], v[178:179] op_sel_hi:[1,0]
	v_pk_mul_f32 v[118:119], v[100:101], v[178:179] op_sel_hi:[1,0]
	v_cvt_pk_bf16_f32 v112, v120, v121
	v_cvt_pk_bf16_f32 v113, v122, v123
	v_cvt_pk_bf16_f32 v114, v124, v125
	v_cvt_pk_bf16_f32 v115, v126, v127
	global_store_dwordx4 v[180:181], v[112:115], off offset:64
	v_pk_mul_f32 v[124:125], v[110:111], v[178:179] op_sel_hi:[1,0]
	v_pk_mul_f32 v[126:127], v[108:109], v[178:179] op_sel_hi:[1,0]
	v_pk_mul_f32 v[120:121], v[106:107], v[178:179] op_sel_hi:[1,0]
	v_pk_mul_f32 v[122:123], v[104:105], v[178:179] op_sel_hi:[1,0]
	v_pk_mul_f32 v[114:115], v[98:99], v[178:179] op_sel_hi:[1,0]
	v_pk_mul_f32 v[112:113], v[96:97], v[178:179] op_sel_hi:[1,0]
	s_mov_b64 s[50:51], -1
	s_and_b64 vcc, exec, s[48:49]
	s_cbranch_vccz .LBB0_1200
	v_mov_b32_e32 v98, v127
	v_mov_b32_e32 v99, v119
	v_mov_b32_e32 v96, v126
	v_mov_b32_e32 v97, v118
	v_pk_mul_f32 v[98:99], v[98:99], v[98:99]
	v_mov_b32_e32 v100, v125
	v_mov_b32_e32 v101, v117
	v_pk_fma_f32 v[96:97], v[96:97], v[96:97], v[98:99]
	v_mov_b32_e32 v98, v124
	v_mov_b32_e32 v99, v116
	v_pk_mul_f32 v[100:101], v[100:101], v[100:101]
	v_mov_b32_e32 v102, v121
	v_pk_fma_f32 v[98:99], v[98:99], v[98:99], v[100:101]
	v_mov_b32_e32 v100, v123
	v_mov_b32_e32 v101, v113
	v_pk_add_f32 v[96:97], v[96:97], v[98:99]
	v_mov_b32_e32 v98, v122
	v_mov_b32_e32 v99, v112
	v_pk_mul_f32 v[100:101], v[100:101], v[100:101]
	v_mov_b32_e32 v103, v115
	v_pk_fma_f32 v[98:99], v[98:99], v[98:99], v[100:101]
	v_mov_b32_e32 v100, v120
	v_mov_b32_e32 v101, v114
	v_pk_mul_f32 v[102:103], v[102:103], v[102:103]
	s_mov_b64 s[50:51], 0
	v_pk_fma_f32 v[100:101], v[100:101], v[100:101], v[102:103]
	s_nop 0
	v_pk_add_f32 v[98:99], v[98:99], v[100:101]
	s_nop 0
	v_pk_add_f32 v[96:97], v[96:97], v[98:99]
	s_nop 0
	v_add_f32_e32 v96, v96, v97
	v_mov_b32_e32 v97, v201
	s_nop 0
	v_lshlrev_b32_e32 v97, 2, v97
	v_xor_b32_e32 v97, 64, v97
	v_mov_b32_e32 v97, v96
	s_nop 1
	v_permlane16_swap_b32_e32 v97, v96
	s_waitcnt lgkmcnt(0)
	v_add_f32_e32 v96, v96, v97
	v_mov_b32_e32 v97, v201
	s_nop 0
	v_lshlrev_b32_e32 v97, 2, v97
	v_xor_b32_e32 v97, 0x80, v97
	v_mov_b32_e32 v97, v96
	s_nop 1
	v_permlane32_swap_b32_e32 v97, v96
	s_waitcnt lgkmcnt(0)
	v_add_f32_e32 v96, v96, v97
	v_fmamk_f32 v96, v96, 0x3c800000, v202
	v_rsq_f32_e32 v108, v96
	s_nop 0
	v_pk_mul_f32 v[96:97], v[126:127], v[108:109] op_sel_hi:[1,0]
	v_pk_mul_f32 v[98:99], v[124:125], v[108:109] op_sel_hi:[1,0]
	v_pk_mul_f32 v[100:101], v[122:123], v[108:109] op_sel_hi:[1,0]
	v_pk_mul_f32 v[102:103], v[120:121], v[108:109] op_sel_hi:[1,0]
	v_pk_mul_f32 v[104:105], v[118:119], v[108:109] op_sel_hi:[1,0]
	v_pk_mul_f32 v[106:107], v[116:117], v[108:109] op_sel_hi:[1,0]
	v_pk_mul_f32 v[178:179], v[112:113], v[108:109] op_sel_hi:[1,0]
	v_pk_mul_f32 v[108:109], v[114:115], v[108:109] op_sel_hi:[1,0]
	v_pk_mul_f32 v[98:99], v[156:157], v[98:99]
	v_pk_mul_f32 v[96:97], v[160:161], v[96:97]
	v_pk_mul_f32 v[102:103], v[150:151], v[102:103]
	v_pk_mul_f32 v[100:101], v[152:153], v[100:101]
	v_pk_mul_f32 v[106:107], v[162:163], v[106:107]
	v_pk_mul_f32 v[104:105], v[164:165], v[104:105]
	v_pk_mul_f32 v[110:111], v[154:155], v[108:109]
	v_pk_mul_f32 v[108:109], v[158:159], v[178:179]

; __device__ __forceinline__ f32x4 silu4(f32x4 v) { return (f32x4){silu_f(v[0]), silu_f(v[1]), silu_f(v[2]), silu_f(v[3])}; }
; __device__ __forceinline__ float sq4(f32x4 v) { return (v[0] * v[0] + v[1] * v[1]) + (v[2] * v[2] + v[3] * v[3]); }
; __device__ __forceinline__ u32x4 pack8(f32x4 a, f32x4 b) { u32x4 w; w.x = cvt_pk_bf16(a[0], a[1]); w.y = cvt_pk_bf16(a[2], a[3]); w.z = cvt_pk_bf16(b[0], b[1]); w.w = cvt_pk_bf16(b[2], b[3]); return w; }
;     __device__ __forceinline__ void operator()(const f32x4 (&acc)[2][2][4][2], const Unit& u, int wr, int wc, int fr, int fq) const {
;     ...
;                 const int row = u.pm * BM + ai * HALF + wr * 64 + m * 16 + fr;
;                 const float rstd = rs[ai][m];
;                 f32x4 v[2][2];
; #pragma unroll
;                 for (int bj = 0; bj < 2; ++bj)
; #pragma unroll
;                     for (int n = 0; n < 2; ++n) v[bj][n] = acc[ai][bj][m][n] * rstd;
;                 if (mode == 2) {
;                     float q = (sq4(v[0][0]) + sq4(v[0][1])) + (sq4(v[1][0]) + sq4(v[1][1]));
;                     q += shx(q, 16); q += shx(q, 32);
;                     const float r2 = __builtin_amdgcn_rsqf(q * (1.0f / 64.0f) + RMS_EPS);
; #pragma unroll
;                     for (int bj = 0; bj < 2; ++bj)
; #pragma unroll
;                         for (int n = 0; n < 2; ++n) v[bj][n] = v[bj][n] * r2 * wv[bj][n];
;                 } else if (mode == 1) {
; #pragma unroll
;                     for (int bj = 0; bj < 2; ++bj)
; #pragma unroll
;                         for (int n = 0; n < 2; ++n) v[bj][n] = silu4(v[bj][n]);
;                 } else {
; #pragma unroll
;                     for (int bj = 0; bj < 2; ++bj)
; #pragma unroll
;                         for (int n = 0; n < 2; ++n) v[bj][n] = v[bj][n] * sc;
;                 }
;                 bf16_t* rowp = U + (size_t)row * 2560 + lcol;
; #pragma unroll
;                 for (int bj = 0; bj < 2; ++bj) *(u32x4*)(rowp + 32 * bj) = pack8(v[bj][0], v[bj][1]);
.LBB0_1205:
	v_add_f32_e32 v112, v210, v211
	v_fmamk_f32 v112, v112, 0x3a800000, v202
	v_add_u32_e32 v113, s0, v194
	v_rsq_f32_e32 v112, v112
	v_mov_b64_e32 v[114:115], s[18:19]
	v_mad_i64_i32 v[114:115], s[50:51], v113, s12, v[114:115]
	v_lshl_add_u64 v[114:115], v[170:171], 1, v[114:115]
	v_cvt_pk_bf16_f32 v96, v96, v97
	v_cvt_pk_bf16_f32 v97, v98, v99
	v_cvt_pk_bf16_f32 v98, v100, v101
	v_cvt_pk_bf16_f32 v99, v102, v103
	global_store_dwordx4 v[114:115], v[96:99], off
	v_pk_mul_f32 v[100:101], v[86:87], v[112:113] op_sel_hi:[1,0]
	v_pk_mul_f32 v[102:103], v[84:85], v[112:113] op_sel_hi:[1,0]
	v_cvt_pk_bf16_f32 v96, v104, v105
	v_cvt_pk_bf16_f32 v97, v106, v107
	v_cvt_pk_bf16_f32 v98, v108, v109
	v_cvt_pk_bf16_f32 v99, v110, v111
	global_store_dwordx4 v[114:115], v[96:99], off offset:64
	v_pk_mul_f32 v[108:109], v[94:95], v[112:113] op_sel_hi:[1,0]
	v_pk_mul_f32 v[110:111], v[92:93], v[112:113] op_sel_hi:[1,0]
	v_pk_mul_f32 v[104:105], v[90:91], v[112:113] op_sel_hi:[1,0]
	v_pk_mul_f32 v[106:107], v[88:89], v[112:113] op_sel_hi:[1,0]
	v_pk_mul_f32 v[98:99], v[82:83], v[112:113] op_sel_hi:[1,0]
	v_pk_mul_f32 v[96:97], v[80:81], v[112:113] op_sel_hi:[1,0]
	s_mov_b64 s[50:51], -1
	s_and_b64 vcc, exec, s[48:49]
	s_cbranch_vccz .LBB0_1207
	v_mov_b32_e32 v82, v111
	v_mov_b32_e32 v83, v103
	v_mov_b32_e32 v80, v110
	v_mov_b32_e32 v81, v102
	v_pk_mul_f32 v[82:83], v[82:83], v[82:83]
	v_mov_b32_e32 v84, v109
	v_mov_b32_e32 v85, v101
	v_pk_fma_f32 v[80:81], v[80:81], v[80:81], v[82:83]
	v_mov_b32_e32 v82, v108
	v_mov_b32_e32 v83, v100
	v_pk_mul_f32 v[84:85], v[84:85], v[84:85]
	v_mov_b32_e32 v86, v105
	v_pk_fma_f32 v[82:83], v[82:83], v[82:83], v[84:85]
	v_mov_b32_e32 v84, v107
	v_mov_b32_e32 v85, v97
	v_pk_add_f32 v[80:81], v[80:81], v[82:83]
	v_mov_b32_e32 v82, v106
	v_mov_b32_e32 v83, v96
	v_pk_mul_f32 v[84:85], v[84:85], v[84:85]
	v_mov_b32_e32 v87, v99
	v_pk_fma_f32 v[82:83], v[82:83], v[82:83], v[84:85]
	v_mov_b32_e32 v84, v104
	v_mov_b32_e32 v85, v98
	v_pk_mul_f32 v[86:87], v[86:87], v[86:87]
	s_mov_b64 s[50:51], 0
	v_pk_fma_f32 v[84:85], v[84:85], v[84:85], v[86:87]
	s_nop 0
	v_pk_add_f32 v[82:83], v[82:83], v[84:85]
	s_nop 0
	v_pk_add_f32 v[80:81], v[80:81], v[82:83]
	s_nop 0
	v_add_f32_e32 v80, v80, v81
	v_mov_b32_e32 v81, v201
	s_nop 0
	v_lshlrev_b32_e32 v81, 2, v81
	v_xor_b32_e32 v81, 64, v81
	v_mov_b32_e32 v81, v80
	s_nop 1
	v_permlane16_swap_b32_e32 v81, v80
	s_waitcnt lgkmcnt(0)
	v_add_f32_e32 v80, v80, v81
	v_mov_b32_e32 v81, v201
	s_nop 0
	v_lshlrev_b32_e32 v81, 2, v81
	v_xor_b32_e32 v81, 0x80, v81
	v_mov_b32_e32 v81, v80
	s_nop 1
	v_permlane32_swap_b32_e32 v81, v80
	s_waitcnt lgkmcnt(0)
	v_add_f32_e32 v80, v80, v81
	v_fmamk_f32 v80, v80, 0x3c800000, v202
	v_rsq_f32_e32 v92, v80
	s_nop 0
	v_pk_mul_f32 v[80:81], v[110:111], v[92:93] op_sel_hi:[1,0]
	v_pk_mul_f32 v[82:83], v[108:109], v[92:93] op_sel_hi:[1,0]
	v_pk_mul_f32 v[84:85], v[106:107], v[92:93] op_sel_hi:[1,0]
	v_pk_mul_f32 v[86:87], v[104:105], v[92:93] op_sel_hi:[1,0]
	v_pk_mul_f32 v[88:89], v[102:103], v[92:93] op_sel_hi:[1,0]
	v_pk_mul_f32 v[90:91], v[100:101], v[92:93] op_sel_hi:[1,0]
	v_pk_mul_f32 v[112:113], v[96:97], v[92:93] op_sel_hi:[1,0]
	v_pk_mul_f32 v[92:93], v[98:99], v[92:93] op_sel_hi:[1,0]
	v_pk_mul_f32 v[82:83], v[156:157], v[82:83]
	v_pk_mul_f32 v[80:81], v[160:161], v[80:81]
	v_pk_mul_f32 v[86:87], v[150:151], v[86:87]
	v_pk_mul_f32 v[84:85], v[152:153], v[84:85]
	v_pk_mul_f32 v[90:91], v[162:163], v[90:91]
	v_pk_mul_f32 v[88:89], v[164:165], v[88:89]
	v_pk_mul_f32 v[94:95], v[154:155], v[92:93]
	v_pk_mul_f32 v[92:93], v[158:159], v[112:113]

; __device__ __forceinline__ f32x4 silu4(f32x4 v) { return (f32x4){silu_f(v[0]), silu_f(v[1]), silu_f(v[2]), silu_f(v[3])}; }
; __device__ __forceinline__ float sq4(f32x4 v) { return (v[0] * v[0] + v[1] * v[1]) + (v[2] * v[2] + v[3] * v[3]); }
; __device__ __forceinline__ u32x4 pack8(f32x4 a, f32x4 b) { u32x4 w; w.x = cvt_pk_bf16(a[0], a[1]); w.y = cvt_pk_bf16(a[2], a[3]); w.z = cvt_pk_bf16(b[0], b[1]); w.w = cvt_pk_bf16(b[2], b[3]); return w; }
;     __device__ __forceinline__ void operator()(const f32x4 (&acc)[2][2][4][2], const Unit& u, int wr, int wc, int fr, int fq) const {
;     ...
;                 const int row = u.pm * BM + ai * HALF + wr * 64 + m * 16 + fr;
;                 const float rstd = rs[ai][m];
;                 f32x4 v[2][2];
; #pragma unroll
;                 for (int bj = 0; bj < 2; ++bj)
; #pragma unroll
;                     for (int n = 0; n < 2; ++n) v[bj][n] = acc[ai][bj][m][n] * rstd;
;                 if (mode == 2) {
;                     float q = (sq4(v[0][0]) + sq4(v[0][1])) + (sq4(v[1][0]) + sq4(v[1][1]));
;                     q += shx(q, 16); q += shx(q, 32);
;                     const float r2 = __builtin_amdgcn_rsqf(q * (1.0f / 64.0f) + RMS_EPS);
; #pragma unroll
;                     for (int bj = 0; bj < 2; ++bj)
; #pragma unroll
;                         for (int n = 0; n < 2; ++n) v[bj][n] = v[bj][n] * r2 * wv[bj][n];
;                 } else if (mode == 1) {
; #pragma unroll
;                     for (int bj = 0; bj < 2; ++bj)
; #pragma unroll
;                         for (int n = 0; n < 2; ++n) v[bj][n] = silu4(v[bj][n]);
;                 } else {
; #pragma unroll
;                     for (int bj = 0; bj < 2; ++bj)
; #pragma unroll
;                         for (int n = 0; n < 2; ++n) v[bj][n] = v[bj][n] * sc;
;                 }
;                 bf16_t* rowp = U + (size_t)row * 2560 + lcol;
; #pragma unroll
;                 for (int bj = 0; bj < 2; ++bj) *(u32x4*)(rowp + 32 * bj) = pack8(v[bj][0], v[bj][1]);
.LBB0_1212:
	v_add_f32_e32 v96, v208, v209
	v_fmamk_f32 v96, v96, 0x3a800000, v202
	v_add_u32_e32 v97, s0, v195
	v_rsq_f32_e32 v96, v96
	v_mov_b64_e32 v[98:99], s[18:19]
	v_mad_i64_i32 v[98:99], s[50:51], v97, s12, v[98:99]
	v_lshl_add_u64 v[98:99], v[170:171], 1, v[98:99]
	v_cvt_pk_bf16_f32 v80, v80, v81
	v_cvt_pk_bf16_f32 v81, v82, v83
	v_cvt_pk_bf16_f32 v82, v84, v85
	v_cvt_pk_bf16_f32 v83, v86, v87
	global_store_dwordx4 v[98:99], v[80:83], off
	v_pk_mul_f32 v[84:85], v[70:71], v[96:97] op_sel_hi:[1,0]
	v_pk_mul_f32 v[86:87], v[68:69], v[96:97] op_sel_hi:[1,0]
	v_cvt_pk_bf16_f32 v80, v88, v89
	v_cvt_pk_bf16_f32 v81, v90, v91
	v_cvt_pk_bf16_f32 v82, v92, v93
	v_cvt_pk_bf16_f32 v83, v94, v95
	global_store_dwordx4 v[98:99], v[80:83], off offset:64
	v_pk_mul_f32 v[92:93], v[78:79], v[96:97] op_sel_hi:[1,0]
	v_pk_mul_f32 v[94:95], v[76:77], v[96:97] op_sel_hi:[1,0]
	v_pk_mul_f32 v[88:89], v[74:75], v[96:97] op_sel_hi:[1,0]
	v_pk_mul_f32 v[90:91], v[72:73], v[96:97] op_sel_hi:[1,0]
	v_pk_mul_f32 v[82:83], v[66:67], v[96:97] op_sel_hi:[1,0]
	v_pk_mul_f32 v[80:81], v[64:65], v[96:97] op_sel_hi:[1,0]
	s_mov_b64 s[50:51], -1
	s_and_b64 vcc, exec, s[48:49]
	s_cbranch_vccz .LBB0_1214
	v_mov_b32_e32 v66, v95
	v_mov_b32_e32 v67, v87
	v_mov_b32_e32 v64, v94
	v_mov_b32_e32 v65, v86
	v_pk_mul_f32 v[66:67], v[66:67], v[66:67]
	v_mov_b32_e32 v68, v93
	v_mov_b32_e32 v69, v85
	v_pk_fma_f32 v[64:65], v[64:65], v[64:65], v[66:67]
	v_mov_b32_e32 v66, v92
	v_mov_b32_e32 v67, v84
	v_pk_mul_f32 v[68:69], v[68:69], v[68:69]
	v_mov_b32_e32 v70, v89
	v_pk_fma_f32 v[66:67], v[66:67], v[66:67], v[68:69]
	v_mov_b32_e32 v68, v91
	v_mov_b32_e32 v69, v81
	v_pk_add_f32 v[64:65], v[64:65], v[66:67]
	v_mov_b32_e32 v66, v90
	v_mov_b32_e32 v67, v80
	v_pk_mul_f32 v[68:69], v[68:69], v[68:69]
	v_mov_b32_e32 v71, v83
	v_pk_fma_f32 v[66:67], v[66:67], v[66:67], v[68:69]
	v_mov_b32_e32 v68, v88
	v_mov_b32_e32 v69, v82
	v_pk_mul_f32 v[70:71], v[70:71], v[70:71]
	s_mov_b64 s[50:51], 0
	v_pk_fma_f32 v[68:69], v[68:69], v[68:69], v[70:71]
	s_nop 0
	v_pk_add_f32 v[66:67], v[66:67], v[68:69]
	s_nop 0
	v_pk_add_f32 v[64:65], v[64:65], v[66:67]
	s_nop 0
	v_add_f32_e32 v64, v64, v65
	v_mov_b32_e32 v65, v201
	s_nop 0
	v_lshlrev_b32_e32 v65, 2, v65
	v_xor_b32_e32 v65, 64, v65
	v_mov_b32_e32 v65, v64
	s_nop 1
	v_permlane16_swap_b32_e32 v65, v64
	s_waitcnt lgkmcnt(0)
	v_add_f32_e32 v64, v64, v65
	v_mov_b32_e32 v65, v201
	s_nop 0
	v_lshlrev_b32_e32 v65, 2, v65
	v_xor_b32_e32 v65, 0x80, v65
	v_mov_b32_e32 v65, v64
	s_nop 1
	v_permlane32_swap_b32_e32 v65, v64
	s_waitcnt lgkmcnt(0)
	v_add_f32_e32 v64, v64, v65
	v_fmamk_f32 v64, v64, 0x3c800000, v202
	v_rsq_f32_e32 v76, v64
	s_nop 0
	v_pk_mul_f32 v[64:65], v[94:95], v[76:77] op_sel_hi:[1,0]
	v_pk_mul_f32 v[66:67], v[92:93], v[76:77] op_sel_hi:[1,0]
	v_pk_mul_f32 v[68:69], v[90:91], v[76:77] op_sel_hi:[1,0]
	v_pk_mul_f32 v[70:71], v[88:89], v[76:77] op_sel_hi:[1,0]
	v_pk_mul_f32 v[72:73], v[86:87], v[76:77] op_sel_hi:[1,0]
	v_pk_mul_f32 v[74:75], v[84:85], v[76:77] op_sel_hi:[1,0]
	v_pk_mul_f32 v[96:97], v[80:81], v[76:77] op_sel_hi:[1,0]
	v_pk_mul_f32 v[76:77], v[82:83], v[76:77] op_sel_hi:[1,0]
	v_pk_mul_f32 v[66:67], v[156:157], v[66:67]
	v_pk_mul_f32 v[64:65], v[160:161], v[64:65]
	v_pk_mul_f32 v[70:71], v[150:151], v[70:71]
	v_pk_mul_f32 v[68:69], v[152:153], v[68:69]
	v_pk_mul_f32 v[74:75], v[162:163], v[74:75]
	v_pk_mul_f32 v[72:73], v[164:165], v[72:73]
	v_pk_mul_f32 v[78:79], v[154:155], v[76:77]
	v_pk_mul_f32 v[76:77], v[158:159], v[96:97]

; __device__ __forceinline__ f32x4 silu4(f32x4 v) { return (f32x4){silu_f(v[0]), silu_f(v[1]), silu_f(v[2]), silu_f(v[3])}; }
; __device__ __forceinline__ float sq4(f32x4 v) { return (v[0] * v[0] + v[1] * v[1]) + (v[2] * v[2] + v[3] * v[3]); }
; __device__ __forceinline__ u32x4 pack8(f32x4 a, f32x4 b) { u32x4 w; w.x = cvt_pk_bf16(a[0], a[1]); w.y = cvt_pk_bf16(a[2], a[3]); w.z = cvt_pk_bf16(b[0], b[1]); w.w = cvt_pk_bf16(b[2], b[3]); return w; }
;     __device__ __forceinline__ void operator()(const f32x4 (&acc)[2][2][4][2], const Unit& u, int wr, int wc, int fr, int fq) const {
;     ...
;                 const int row = u.pm * BM + ai * HALF + wr * 64 + m * 16 + fr;
;                 const float rstd = rs[ai][m];
;                 f32x4 v[2][2];
; #pragma unroll
;                 for (int bj = 0; bj < 2; ++bj)
; #pragma unroll
;                     for (int n = 0; n < 2; ++n) v[bj][n] = acc[ai][bj][m][n] * rstd;
;                 if (mode == 2) {
;                     float q = (sq4(v[0][0]) + sq4(v[0][1])) + (sq4(v[1][0]) + sq4(v[1][1]));
;                     q += shx(q, 16); q += shx(q, 32);
;                     const float r2 = __builtin_amdgcn_rsqf(q * (1.0f / 64.0f) + RMS_EPS);
; #pragma unroll
;                     for (int bj = 0; bj < 2; ++bj)
; #pragma unroll
;                         for (int n = 0; n < 2; ++n) v[bj][n] = v[bj][n] * r2 * wv[bj][n];
;                 } else if (mode == 1) {
; #pragma unroll
;                     for (int bj = 0; bj < 2; ++bj)
; #pragma unroll
;                         for (int n = 0; n < 2; ++n) v[bj][n] = silu4(v[bj][n]);
;                 } else {
; #pragma unroll
;                     for (int bj = 0; bj < 2; ++bj)
; #pragma unroll
;                         for (int n = 0; n < 2; ++n) v[bj][n] = v[bj][n] * sc;
;                 }
;                 bf16_t* rowp = U + (size_t)row * 2560 + lcol;
; #pragma unroll
;                 for (int bj = 0; bj < 2; ++bj) *(u32x4*)(rowp + 32 * bj) = pack8(v[bj][0], v[bj][1]);
.LBB0_1219:
	v_add_f32_e32 v80, v206, v207
	v_fmamk_f32 v80, v80, 0x3a800000, v202
	v_add_u32_e32 v81, s0, v196
	v_rsq_f32_e32 v80, v80
	v_mov_b64_e32 v[82:83], s[18:19]
	v_mad_i64_i32 v[82:83], s[50:51], v81, s12, v[82:83]
	v_lshl_add_u64 v[82:83], v[170:171], 1, v[82:83]
	v_cvt_pk_bf16_f32 v64, v64, v65
	v_cvt_pk_bf16_f32 v65, v66, v67
	v_cvt_pk_bf16_f32 v66, v68, v69
	v_cvt_pk_bf16_f32 v67, v70, v71
	global_store_dwordx4 v[82:83], v[64:67], off
	v_pk_mul_f32 v[68:69], v[54:55], v[80:81] op_sel_hi:[1,0]
	v_pk_mul_f32 v[70:71], v[52:53], v[80:81] op_sel_hi:[1,0]
	v_cvt_pk_bf16_f32 v64, v72, v73
	v_cvt_pk_bf16_f32 v65, v74, v75
	v_cvt_pk_bf16_f32 v66, v76, v77
	v_cvt_pk_bf16_f32 v67, v78, v79
	global_store_dwordx4 v[82:83], v[64:67], off offset:64
	v_pk_mul_f32 v[76:77], v[62:63], v[80:81] op_sel_hi:[1,0]
	v_pk_mul_f32 v[78:79], v[60:61], v[80:81] op_sel_hi:[1,0]
	v_pk_mul_f32 v[72:73], v[58:59], v[80:81] op_sel_hi:[1,0]
	v_pk_mul_f32 v[74:75], v[56:57], v[80:81] op_sel_hi:[1,0]
	v_pk_mul_f32 v[66:67], v[50:51], v[80:81] op_sel_hi:[1,0]
	v_pk_mul_f32 v[64:65], v[48:49], v[80:81] op_sel_hi:[1,0]
	s_mov_b64 s[50:51], -1
	s_and_b64 vcc, exec, s[48:49]
	s_cbranch_vccz .LBB0_1221
	v_mov_b32_e32 v50, v79
	v_mov_b32_e32 v51, v71
	v_mov_b32_e32 v48, v78
	v_mov_b32_e32 v49, v70
	v_pk_mul_f32 v[50:51], v[50:51], v[50:51]
	v_mov_b32_e32 v52, v77
	v_mov_b32_e32 v53, v69
	v_pk_fma_f32 v[48:49], v[48:49], v[48:49], v[50:51]
	v_mov_b32_e32 v50, v76
	v_mov_b32_e32 v51, v68
	v_pk_mul_f32 v[52:53], v[52:53], v[52:53]
	v_mov_b32_e32 v54, v73
	v_pk_fma_f32 v[50:51], v[50:51], v[50:51], v[52:53]
	v_mov_b32_e32 v52, v75
	v_mov_b32_e32 v53, v65
	v_pk_add_f32 v[48:49], v[48:49], v[50:51]
	v_mov_b32_e32 v50, v74
	v_mov_b32_e32 v51, v64
	v_pk_mul_f32 v[52:53], v[52:53], v[52:53]
	v_mov_b32_e32 v55, v67
	v_pk_fma_f32 v[50:51], v[50:51], v[50:51], v[52:53]
	v_mov_b32_e32 v52, v72
	v_mov_b32_e32 v53, v66
	v_pk_mul_f32 v[54:55], v[54:55], v[54:55]
	s_mov_b64 s[50:51], 0
	v_pk_fma_f32 v[52:53], v[52:53], v[52:53], v[54:55]
	s_nop 0
	v_pk_add_f32 v[50:51], v[50:51], v[52:53]
	s_nop 0
	v_pk_add_f32 v[48:49], v[48:49], v[50:51]
	s_nop 0
	v_add_f32_e32 v48, v48, v49
	v_mov_b32_e32 v49, v201
	s_nop 0
	v_lshlrev_b32_e32 v49, 2, v49
	v_xor_b32_e32 v49, 64, v49
	v_mov_b32_e32 v49, v48
	s_nop 1
	v_permlane16_swap_b32_e32 v49, v48
	s_waitcnt lgkmcnt(0)
	v_add_f32_e32 v48, v48, v49
	v_mov_b32_e32 v49, v201
	s_nop 0
	v_lshlrev_b32_e32 v49, 2, v49
	v_xor_b32_e32 v49, 0x80, v49
	v_mov_b32_e32 v49, v48
	s_nop 1
	v_permlane32_swap_b32_e32 v49, v48
	s_waitcnt lgkmcnt(0)
	v_add_f32_e32 v48, v48, v49
	v_fmamk_f32 v48, v48, 0x3c800000, v202
	v_rsq_f32_e32 v60, v48
	s_nop 0
	v_pk_mul_f32 v[48:49], v[78:79], v[60:61] op_sel_hi:[1,0]
	v_pk_mul_f32 v[50:51], v[76:77], v[60:61] op_sel_hi:[1,0]
	v_pk_mul_f32 v[52:53], v[74:75], v[60:61] op_sel_hi:[1,0]
	v_pk_mul_f32 v[54:55], v[72:73], v[60:61] op_sel_hi:[1,0]
	v_pk_mul_f32 v[56:57], v[70:71], v[60:61] op_sel_hi:[1,0]
	v_pk_mul_f32 v[58:59], v[68:69], v[60:61] op_sel_hi:[1,0]
	v_pk_mul_f32 v[80:81], v[64:65], v[60:61] op_sel_hi:[1,0]
	v_pk_mul_f32 v[60:61], v[66:67], v[60:61] op_sel_hi:[1,0]
	v_pk_mul_f32 v[50:51], v[156:157], v[50:51]
	v_pk_mul_f32 v[48:49], v[160:161], v[48:49]
	v_pk_mul_f32 v[54:55], v[150:151], v[54:55]
	v_pk_mul_f32 v[52:53], v[152:153], v[52:53]
	v_pk_mul_f32 v[58:59], v[162:163], v[58:59]
	v_pk_mul_f32 v[56:57], v[164:165], v[56:57]
	v_pk_mul_f32 v[62:63], v[154:155], v[60:61]
	v_pk_mul_f32 v[60:61], v[158:159], v[80:81]

; __device__ __forceinline__ f32x4 silu4(f32x4 v) { return (f32x4){silu_f(v[0]), silu_f(v[1]), silu_f(v[2]), silu_f(v[3])}; }
; __device__ __forceinline__ float sq4(f32x4 v) { return (v[0] * v[0] + v[1] * v[1]) + (v[2] * v[2] + v[3] * v[3]); }
; __device__ __forceinline__ u32x4 pack8(f32x4 a, f32x4 b) { u32x4 w; w.x = cvt_pk_bf16(a[0], a[1]); w.y = cvt_pk_bf16(a[2], a[3]); w.z = cvt_pk_bf16(b[0], b[1]); w.w = cvt_pk_bf16(b[2], b[3]); return w; }
;     __device__ __forceinline__ void operator()(const f32x4 (&acc)[2][2][4][2], const Unit& u, int wr, int wc, int fr, int fq) const {
;     ...
;                 const int row = u.pm * BM + ai * HALF + wr * 64 + m * 16 + fr;
;                 const float rstd = rs[ai][m];
;                 f32x4 v[2][2];
; #pragma unroll
;                 for (int bj = 0; bj < 2; ++bj)
; #pragma unroll
;                     for (int n = 0; n < 2; ++n) v[bj][n] = acc[ai][bj][m][n] * rstd;
;                 if (mode == 2) {
;                     float q = (sq4(v[0][0]) + sq4(v[0][1])) + (sq4(v[1][0]) + sq4(v[1][1]));
;                     q += shx(q, 16); q += shx(q, 32);
;                     const float r2 = __builtin_amdgcn_rsqf(q * (1.0f / 64.0f) + RMS_EPS);
; #pragma unroll
;                     for (int bj = 0; bj < 2; ++bj)
; #pragma unroll
;                         for (int n = 0; n < 2; ++n) v[bj][n] = v[bj][n] * r2 * wv[bj][n];
;                 } else if (mode == 1) {
; #pragma unroll
;                     for (int bj = 0; bj < 2; ++bj)
; #pragma unroll
;                         for (int n = 0; n < 2; ++n) v[bj][n] = silu4(v[bj][n]);
;                 } else {
; #pragma unroll
;                     for (int bj = 0; bj < 2; ++bj)
; #pragma unroll
;                         for (int n = 0; n < 2; ++n) v[bj][n] = v[bj][n] * sc;
;                 }
;                 bf16_t* rowp = U + (size_t)row * 2560 + lcol;
; #pragma unroll
;                 for (int bj = 0; bj < 2; ++bj) *(u32x4*)(rowp + 32 * bj) = pack8(v[bj][0], v[bj][1]);
.LBB0_1226:
	v_add_f32_e32 v64, v177, v205
	v_fmamk_f32 v64, v64, 0x3a800000, v202
	v_rsq_f32_e32 v64, v64
	v_mov_b64_e32 v[66:67], s[18:19]
	v_mad_i64_i32 v[66:67], s[50:51], v174, s12, v[66:67]
	v_lshl_add_u64 v[66:67], v[170:171], 1, v[66:67]
	v_cvt_pk_bf16_f32 v48, v48, v49
	v_cvt_pk_bf16_f32 v49, v50, v51
	v_cvt_pk_bf16_f32 v50, v52, v53
	v_cvt_pk_bf16_f32 v51, v54, v55
	global_store_dwordx4 v[66:67], v[48:51], off
	v_pk_mul_f32 v[52:53], v[38:39], v[64:65] op_sel_hi:[1,0]
	v_pk_mul_f32 v[54:55], v[36:37], v[64:65] op_sel_hi:[1,0]
	v_cvt_pk_bf16_f32 v48, v56, v57
	v_cvt_pk_bf16_f32 v49, v58, v59
	v_cvt_pk_bf16_f32 v50, v60, v61
	v_cvt_pk_bf16_f32 v51, v62, v63
	global_store_dwordx4 v[66:67], v[48:51], off offset:64
	v_pk_mul_f32 v[60:61], v[46:47], v[64:65] op_sel_hi:[1,0]
	v_pk_mul_f32 v[62:63], v[44:45], v[64:65] op_sel_hi:[1,0]
	v_pk_mul_f32 v[56:57], v[42:43], v[64:65] op_sel_hi:[1,0]
	v_pk_mul_f32 v[58:59], v[40:41], v[64:65] op_sel_hi:[1,0]
	v_pk_mul_f32 v[50:51], v[34:35], v[64:65] op_sel_hi:[1,0]
	v_pk_mul_f32 v[48:49], v[32:33], v[64:65] op_sel_hi:[1,0]
	s_mov_b64 s[50:51], -1
	s_and_b64 vcc, exec, s[48:49]
	s_cbranch_vccz .LBB0_1228
	v_mov_b32_e32 v34, v63
	v_mov_b32_e32 v35, v55
	v_mov_b32_e32 v32, v62
	v_mov_b32_e32 v33, v54
	v_pk_mul_f32 v[34:35], v[34:35], v[34:35]
	v_mov_b32_e32 v36, v61
	v_mov_b32_e32 v37, v53
	v_pk_fma_f32 v[32:33], v[32:33], v[32:33], v[34:35]
	v_mov_b32_e32 v34, v60
	v_mov_b32_e32 v35, v52
	v_pk_mul_f32 v[36:37], v[36:37], v[36:37]
	v_mov_b32_e32 v38, v57
	v_pk_fma_f32 v[34:35], v[34:35], v[34:35], v[36:37]
	v_mov_b32_e32 v36, v59
	v_mov_b32_e32 v37, v49
	v_pk_add_f32 v[32:33], v[32:33], v[34:35]
	v_mov_b32_e32 v34, v58
	v_mov_b32_e32 v35, v48
	v_pk_mul_f32 v[36:37], v[36:37], v[36:37]
	v_mov_b32_e32 v39, v51
	v_pk_fma_f32 v[34:35], v[34:35], v[34:35], v[36:37]
	v_mov_b32_e32 v36, v56
	v_mov_b32_e32 v37, v50
	v_pk_mul_f32 v[38:39], v[38:39], v[38:39]
	s_mov_b64 s[50:51], 0
	v_pk_fma_f32 v[36:37], v[36:37], v[36:37], v[38:39]
	s_nop 0
	v_pk_add_f32 v[34:35], v[34:35], v[36:37]
	s_nop 0
	v_pk_add_f32 v[32:33], v[32:33], v[34:35]
	s_nop 0
	v_add_f32_e32 v32, v32, v33
	v_mov_b32_e32 v33, v201
	s_nop 0
	v_lshlrev_b32_e32 v33, 2, v33
	v_xor_b32_e32 v33, 64, v33
	v_mov_b32_e32 v33, v32
	s_nop 1
	v_permlane16_swap_b32_e32 v33, v32
	s_waitcnt lgkmcnt(0)
	v_add_f32_e32 v32, v32, v33
	v_mov_b32_e32 v33, v201
	s_nop 0
	v_lshlrev_b32_e32 v33, 2, v33
	v_xor_b32_e32 v33, 0x80, v33
	v_mov_b32_e32 v33, v32
	s_nop 1
	v_permlane32_swap_b32_e32 v33, v32
	s_waitcnt lgkmcnt(0)
	v_add_f32_e32 v32, v32, v33
	v_fmamk_f32 v32, v32, 0x3c800000, v202
	v_rsq_f32_e32 v44, v32
	s_nop 0
	v_pk_mul_f32 v[32:33], v[62:63], v[44:45] op_sel_hi:[1,0]
	v_pk_mul_f32 v[34:35], v[60:61], v[44:45] op_sel_hi:[1,0]
	v_pk_mul_f32 v[36:37], v[58:59], v[44:45] op_sel_hi:[1,0]
	v_pk_mul_f32 v[38:39], v[56:57], v[44:45] op_sel_hi:[1,0]
	v_pk_mul_f32 v[40:41], v[54:55], v[44:45] op_sel_hi:[1,0]
	v_pk_mul_f32 v[42:43], v[52:53], v[44:45] op_sel_hi:[1,0]
	v_pk_mul_f32 v[64:65], v[48:49], v[44:45] op_sel_hi:[1,0]
	v_pk_mul_f32 v[44:45], v[50:51], v[44:45] op_sel_hi:[1,0]
	v_pk_mul_f32 v[34:35], v[156:157], v[34:35]
	v_pk_mul_f32 v[32:33], v[160:161], v[32:33]
	v_pk_mul_f32 v[38:39], v[150:151], v[38:39]
	v_pk_mul_f32 v[36:37], v[152:153], v[36:37]
	v_pk_mul_f32 v[42:43], v[162:163], v[42:43]
	v_pk_mul_f32 v[40:41], v[164:165], v[40:41]
	v_pk_mul_f32 v[46:47], v[154:155], v[44:45]
	v_pk_mul_f32 v[44:45], v[158:159], v[64:65]

; __device__ __forceinline__ f32x4 silu4(f32x4 v) { return (f32x4){silu_f(v[0]), silu_f(v[1]), silu_f(v[2]), silu_f(v[3])}; }
; __device__ __forceinline__ float sq4(f32x4 v) { return (v[0] * v[0] + v[1] * v[1]) + (v[2] * v[2] + v[3] * v[3]); }
; __device__ __forceinline__ u32x4 pack8(f32x4 a, f32x4 b) { u32x4 w; w.x = cvt_pk_bf16(a[0], a[1]); w.y = cvt_pk_bf16(a[2], a[3]); w.z = cvt_pk_bf16(b[0], b[1]); w.w = cvt_pk_bf16(b[2], b[3]); return w; }
;     __device__ __forceinline__ void operator()(const f32x4 (&acc)[2][2][4][2], const Unit& u, int wr, int wc, int fr, int fq) const {
;     ...
;                 const int row = u.pm * BM + ai * HALF + wr * 64 + m * 16 + fr;
;                 const float rstd = rs[ai][m];
;                 f32x4 v[2][2];
; #pragma unroll
;                 for (int bj = 0; bj < 2; ++bj)
; #pragma unroll
;                     for (int n = 0; n < 2; ++n) v[bj][n] = acc[ai][bj][m][n] * rstd;
;                 if (mode == 2) {
;                     float q = (sq4(v[0][0]) + sq4(v[0][1])) + (sq4(v[1][0]) + sq4(v[1][1]));
;                     q += shx(q, 16); q += shx(q, 32);
;                     const float r2 = __builtin_amdgcn_rsqf(q * (1.0f / 64.0f) + RMS_EPS);
; #pragma unroll
;                     for (int bj = 0; bj < 2; ++bj)
; #pragma unroll
;                         for (int n = 0; n < 2; ++n) v[bj][n] = v[bj][n] * r2 * wv[bj][n];
;                 } else if (mode == 1) {
; #pragma unroll
;                     for (int bj = 0; bj < 2; ++bj)
; #pragma unroll
;                         for (int n = 0; n < 2; ++n) v[bj][n] = silu4(v[bj][n]);
;                 } else {
; #pragma unroll
;                     for (int bj = 0; bj < 2; ++bj)
; #pragma unroll
;                         for (int n = 0; n < 2; ++n) v[bj][n] = v[bj][n] * sc;
;                 }
;                 bf16_t* rowp = U + (size_t)row * 2560 + lcol;
; #pragma unroll
;                 for (int bj = 0; bj < 2; ++bj) *(u32x4*)(rowp + 32 * bj) = pack8(v[bj][0], v[bj][1]);
.LBB0_1233:
	v_add_f32_e32 v48, v173, v175
	v_fmamk_f32 v48, v48, 0x3a800000, v202
	v_rsq_f32_e32 v48, v48
	v_mov_b64_e32 v[50:51], s[18:19]
	v_mad_i64_i32 v[50:51], s[50:51], v172, s12, v[50:51]
	v_lshl_add_u64 v[50:51], v[170:171], 1, v[50:51]
	v_cvt_pk_bf16_f32 v32, v32, v33
	v_cvt_pk_bf16_f32 v33, v34, v35
	v_cvt_pk_bf16_f32 v34, v36, v37
	v_cvt_pk_bf16_f32 v35, v38, v39
	global_store_dwordx4 v[50:51], v[32:35], off
	v_pk_mul_f32 v[36:37], v[22:23], v[48:49] op_sel_hi:[1,0]
	v_pk_mul_f32 v[38:39], v[20:21], v[48:49] op_sel_hi:[1,0]
	v_cvt_pk_bf16_f32 v32, v40, v41
	v_cvt_pk_bf16_f32 v33, v42, v43
	v_cvt_pk_bf16_f32 v34, v44, v45
	v_cvt_pk_bf16_f32 v35, v46, v47
	global_store_dwordx4 v[50:51], v[32:35], off offset:64
	v_pk_mul_f32 v[44:45], v[30:31], v[48:49] op_sel_hi:[1,0]
	v_pk_mul_f32 v[46:47], v[28:29], v[48:49] op_sel_hi:[1,0]
	v_pk_mul_f32 v[40:41], v[26:27], v[48:49] op_sel_hi:[1,0]
	v_pk_mul_f32 v[42:43], v[24:25], v[48:49] op_sel_hi:[1,0]
	v_pk_mul_f32 v[34:35], v[18:19], v[48:49] op_sel_hi:[1,0]
	v_pk_mul_f32 v[32:33], v[16:17], v[48:49] op_sel_hi:[1,0]
	s_mov_b64 s[50:51], -1
	s_and_b64 vcc, exec, s[48:49]
	s_cbranch_vccz .LBB0_1235
	v_mov_b32_e32 v18, v47
	v_mov_b32_e32 v19, v39
	v_mov_b32_e32 v16, v46
	v_mov_b32_e32 v17, v38
	v_pk_mul_f32 v[18:19], v[18:19], v[18:19]
	v_mov_b32_e32 v20, v45
	v_mov_b32_e32 v21, v37
	v_pk_fma_f32 v[16:17], v[16:17], v[16:17], v[18:19]
	v_mov_b32_e32 v18, v44
	v_mov_b32_e32 v19, v36
	v_pk_mul_f32 v[20:21], v[20:21], v[20:21]
	v_mov_b32_e32 v22, v41
	v_pk_fma_f32 v[18:19], v[18:19], v[18:19], v[20:21]
	v_mov_b32_e32 v20, v43
	v_mov_b32_e32 v21, v33
	v_pk_add_f32 v[16:17], v[16:17], v[18:19]
	v_mov_b32_e32 v18, v42
	v_mov_b32_e32 v19, v32
	v_pk_mul_f32 v[20:21], v[20:21], v[20:21]
	v_mov_b32_e32 v23, v35
	v_pk_fma_f32 v[18:19], v[18:19], v[18:19], v[20:21]
	v_mov_b32_e32 v20, v40
	v_mov_b32_e32 v21, v34
	v_pk_mul_f32 v[22:23], v[22:23], v[22:23]
	s_mov_b64 s[50:51], 0
	v_pk_fma_f32 v[20:21], v[20:21], v[20:21], v[22:23]
	s_nop 0
	v_pk_add_f32 v[18:19], v[18:19], v[20:21]
	s_nop 0
	v_pk_add_f32 v[16:17], v[16:17], v[18:19]
	s_nop 0
	v_add_f32_e32 v16, v16, v17
	v_mov_b32_e32 v17, v201
	s_nop 0
	v_lshlrev_b32_e32 v17, 2, v17
	v_xor_b32_e32 v17, 64, v17
	v_mov_b32_e32 v17, v16
	s_nop 1
	v_permlane16_swap_b32_e32 v17, v16
	s_waitcnt lgkmcnt(0)
	v_add_f32_e32 v16, v16, v17
	v_mov_b32_e32 v17, v201
	s_nop 0
	v_lshlrev_b32_e32 v17, 2, v17
	v_xor_b32_e32 v17, 0x80, v17
	v_mov_b32_e32 v17, v16
	s_nop 1
	v_permlane32_swap_b32_e32 v17, v16
	s_waitcnt lgkmcnt(0)
	v_add_f32_e32 v16, v16, v17
	v_fmamk_f32 v16, v16, 0x3c800000, v202
	v_rsq_f32_e32 v28, v16
	s_nop 0
	v_pk_mul_f32 v[16:17], v[46:47], v[28:29] op_sel_hi:[1,0]
	v_pk_mul_f32 v[18:19], v[44:45], v[28:29] op_sel_hi:[1,0]
	v_pk_mul_f32 v[20:21], v[42:43], v[28:29] op_sel_hi:[1,0]
	v_pk_mul_f32 v[22:23], v[40:41], v[28:29] op_sel_hi:[1,0]
	v_pk_mul_f32 v[24:25], v[38:39], v[28:29] op_sel_hi:[1,0]
	v_pk_mul_f32 v[26:27], v[36:37], v[28:29] op_sel_hi:[1,0]
	v_pk_mul_f32 v[48:49], v[32:33], v[28:29] op_sel_hi:[1,0]
	v_pk_mul_f32 v[28:29], v[34:35], v[28:29] op_sel_hi:[1,0]
	v_pk_mul_f32 v[18:19], v[156:157], v[18:19]
	v_pk_mul_f32 v[16:17], v[160:161], v[16:17]
	v_pk_mul_f32 v[22:23], v[150:151], v[22:23]
	v_pk_mul_f32 v[20:21], v[152:153], v[20:21]
	v_pk_mul_f32 v[26:27], v[162:163], v[26:27]
	v_pk_mul_f32 v[24:25], v[164:165], v[24:25]
	v_pk_mul_f32 v[30:31], v[154:155], v[28:29]
	v_pk_mul_f32 v[28:29], v[158:159], v[48:49]

; __device__ __forceinline__ f32x4 silu4(f32x4 v) { return (f32x4){silu_f(v[0]), silu_f(v[1]), silu_f(v[2]), silu_f(v[3])}; }
; __device__ __forceinline__ float sq4(f32x4 v) { return (v[0] * v[0] + v[1] * v[1]) + (v[2] * v[2] + v[3] * v[3]); }
; __device__ __forceinline__ u32x4 pack8(f32x4 a, f32x4 b) { u32x4 w; w.x = cvt_pk_bf16(a[0], a[1]); w.y = cvt_pk_bf16(a[2], a[3]); w.z = cvt_pk_bf16(b[0], b[1]); w.w = cvt_pk_bf16(b[2], b[3]); return w; }
;     __device__ __forceinline__ void operator()(const f32x4 (&acc)[2][2][4][2], const Unit& u, int wr, int wc, int fr, int fq) const {
;     ...
;                 const int row = u.pm * BM + ai * HALF + wr * 64 + m * 16 + fr;
;                 const float rstd = rs[ai][m];
;                 f32x4 v[2][2];
; #pragma unroll
;                 for (int bj = 0; bj < 2; ++bj)
; #pragma unroll
;                     for (int n = 0; n < 2; ++n) v[bj][n] = acc[ai][bj][m][n] * rstd;
;                 if (mode == 2) {
;                     float q = (sq4(v[0][0]) + sq4(v[0][1])) + (sq4(v[1][0]) + sq4(v[1][1]));
;                     q += shx(q, 16); q += shx(q, 32);
;                     const float r2 = __builtin_amdgcn_rsqf(q * (1.0f / 64.0f) + RMS_EPS);
; #pragma unroll
;                     for (int bj = 0; bj < 2; ++bj)
; #pragma unroll
;                         for (int n = 0; n < 2; ++n) v[bj][n] = v[bj][n] * r2 * wv[bj][n];
;                 } else if (mode == 1) {
; #pragma unroll
;                     for (int bj = 0; bj < 2; ++bj)
; #pragma unroll
;                         for (int n = 0; n < 2; ++n) v[bj][n] = silu4(v[bj][n]);
;                 } else {
; #pragma unroll
;                     for (int bj = 0; bj < 2; ++bj)
; #pragma unroll
;                         for (int n = 0; n < 2; ++n) v[bj][n] = v[bj][n] * sc;
;                 }
;                 bf16_t* rowp = U + (size_t)row * 2560 + lcol;
; #pragma unroll
;                 for (int bj = 0; bj < 2; ++bj) *(u32x4*)(rowp + 32 * bj) = pack8(v[bj][0], v[bj][1]);
.LBB0_1240:
	s_waitcnt lgkmcnt(0)
	v_add_f32_e32 v32, v149, v167
	v_fmamk_f32 v32, v32, 0x3a800000, v202
	v_rsq_f32_e32 v32, v32
	v_mov_b64_e32 v[34:35], s[18:19]
	v_mad_i64_i32 v[34:35], s[50:51], v166, s12, v[34:35]
	v_lshl_add_u64 v[34:35], v[170:171], 1, v[34:35]
	v_cvt_pk_bf16_f32 v16, v16, v17
	v_cvt_pk_bf16_f32 v17, v18, v19
	v_cvt_pk_bf16_f32 v18, v20, v21
	v_cvt_pk_bf16_f32 v19, v22, v23
	global_store_dwordx4 v[34:35], v[16:19], off
	v_pk_mul_f32 v[20:21], v[6:7], v[32:33] op_sel_hi:[1,0]
	v_pk_mul_f32 v[22:23], v[4:5], v[32:33] op_sel_hi:[1,0]
	v_cvt_pk_bf16_f32 v16, v24, v25
	v_cvt_pk_bf16_f32 v17, v26, v27
	v_cvt_pk_bf16_f32 v18, v28, v29
	v_cvt_pk_bf16_f32 v19, v30, v31
	global_store_dwordx4 v[34:35], v[16:19], off offset:64
	v_pk_mul_f32 v[28:29], v[14:15], v[32:33] op_sel_hi:[1,0]
	v_pk_mul_f32 v[30:31], v[12:13], v[32:33] op_sel_hi:[1,0]
	v_pk_mul_f32 v[24:25], v[10:11], v[32:33] op_sel_hi:[1,0]
	v_pk_mul_f32 v[26:27], v[8:9], v[32:33] op_sel_hi:[1,0]
	v_pk_mul_f32 v[18:19], v[2:3], v[32:33] op_sel_hi:[1,0]
	v_pk_mul_f32 v[16:17], v[0:1], v[32:33] op_sel_hi:[1,0]
	s_mov_b64 s[50:51], -1
	s_and_b64 vcc, exec, s[48:49]
	s_cbranch_vccz .LBB0_1242
	v_mov_b32_e32 v2, v31
	v_mov_b32_e32 v3, v23
	v_mov_b32_e32 v0, v30
	v_mov_b32_e32 v1, v22
	v_pk_mul_f32 v[2:3], v[2:3], v[2:3]
	v_mov_b32_e32 v4, v29
	v_mov_b32_e32 v5, v21
	v_pk_fma_f32 v[0:1], v[0:1], v[0:1], v[2:3]
	v_mov_b32_e32 v2, v28
	v_mov_b32_e32 v3, v20
	v_pk_mul_f32 v[4:5], v[4:5], v[4:5]
	v_mov_b32_e32 v6, v25
	v_pk_fma_f32 v[2:3], v[2:3], v[2:3], v[4:5]
	v_mov_b32_e32 v4, v27
	v_mov_b32_e32 v5, v17
	v_pk_add_f32 v[0:1], v[0:1], v[2:3]
	v_mov_b32_e32 v2, v26
	v_mov_b32_e32 v3, v16
	v_pk_mul_f32 v[4:5], v[4:5], v[4:5]
	v_mov_b32_e32 v7, v19
	v_pk_fma_f32 v[2:3], v[2:3], v[2:3], v[4:5]
	v_mov_b32_e32 v4, v24
	v_mov_b32_e32 v5, v18
	v_pk_mul_f32 v[6:7], v[6:7], v[6:7]
	s_mov_b64 s[50:51], 0
	v_pk_fma_f32 v[4:5], v[4:5], v[4:5], v[6:7]
	s_nop 0
	v_pk_add_f32 v[2:3], v[2:3], v[4:5]
	s_nop 0
	v_pk_add_f32 v[0:1], v[0:1], v[2:3]
	s_nop 0
	v_add_f32_e32 v0, v0, v1
	v_mov_b32_e32 v1, v201
	s_nop 0
	v_lshlrev_b32_e32 v1, 2, v1
	v_xor_b32_e32 v1, 64, v1
	v_mov_b32_e32 v1, v0
	s_nop 1
	v_permlane16_swap_b32_e32 v1, v0
	s_waitcnt lgkmcnt(0)
	v_add_f32_e32 v0, v0, v1
	v_mov_b32_e32 v1, v201
	s_nop 0
	v_lshlrev_b32_e32 v1, 2, v1
	v_xor_b32_e32 v1, 0x80, v1
	v_mov_b32_e32 v1, v0
	s_nop 1
	v_permlane32_swap_b32_e32 v1, v0
	s_waitcnt lgkmcnt(0)
	v_add_f32_e32 v0, v0, v1
	v_fmamk_f32 v0, v0, 0x3c800000, v202
	v_rsq_f32_e32 v12, v0
	s_nop 0
	v_pk_mul_f32 v[0:1], v[30:31], v[12:13] op_sel_hi:[1,0]
	v_pk_mul_f32 v[2:3], v[28:29], v[12:13] op_sel_hi:[1,0]
	v_pk_mul_f32 v[4:5], v[26:27], v[12:13] op_sel_hi:[1,0]
	v_pk_mul_f32 v[6:7], v[24:25], v[12:13] op_sel_hi:[1,0]
	v_pk_mul_f32 v[8:9], v[22:23], v[12:13] op_sel_hi:[1,0]
	v_pk_mul_f32 v[10:11], v[20:21], v[12:13] op_sel_hi:[1,0]
	v_pk_mul_f32 v[32:33], v[16:17], v[12:13] op_sel_hi:[1,0]
	v_pk_mul_f32 v[12:13], v[18:19], v[12:13] op_sel_hi:[1,0]
	v_pk_mul_f32 v[2:3], v[156:157], v[2:3]
	v_pk_mul_f32 v[0:1], v[160:161], v[0:1]
	v_pk_mul_f32 v[6:7], v[150:151], v[6:7]
	v_pk_mul_f32 v[4:5], v[152:153], v[4:5]
	v_pk_mul_f32 v[10:11], v[162:163], v[10:11]
	v_pk_mul_f32 v[8:9], v[164:165], v[8:9]
	v_pk_mul_f32 v[14:15], v[154:155], v[12:13]
	v_pk_mul_f32 v[12:13], v[158:159], v[32:33]

; __device__ __forceinline__ float sq4(f32x4 v) { return (v[0] * v[0] + v[1] * v[1]) + (v[2] * v[2] + v[3] * v[3]); }
; __device__ __forceinline__ u32x4 pack8(f32x4 a, f32x4 b) { u32x4 w; w.x = cvt_pk_bf16(a[0], a[1]); w.y = cvt_pk_bf16(a[2], a[3]); w.z = cvt_pk_bf16(b[0], b[1]); w.w = cvt_pk_bf16(b[2], b[3]); return w; }
;     __device__ __forceinline__ void operator()(const f32x4 (&acc)[2][2][4][2], const Unit& u, int wr, int wc, int fr, int fq) const {
;         const int col0 = u.pn * 256 + 32 * wc + 8 * fq;
; #pragma unroll
;         for (int ai = 0; ai < 2; ++ai) {
;             u32x4 bs[4][2];
; #pragma unroll
;             for (int m = 0; m < 4; ++m)
; #pragma unroll
;                 for (int bj = 0; bj < 2; ++bj) bs[m][bj] = *(const u32x4*)(xb + (size_t)(u.pm * BM + ai * HALF + wr * 64 + m * 16 + fr) * 1024 + col0 + 128 * bj);
; #pragma unroll
;             for (int m = 0; m < 4; ++m) {
;                 const int row = u.pm * BM + ai * HALF + wr * 64 + m * 16 + fr;
;                 float q = 0.f;
; #pragma unroll
;                 for (int bj = 0; bj < 2; ++bj) {
;                     const size_t off = (size_t)row * 1024 + col0 + 128 * bj; const u32x4 w = bs[m][bj];
;                     const f32x4 b0 = (f32x4){__builtin_bit_cast(float, w.x << 16), __builtin_bit_cast(float, w.x & 0xffff0000u), __builtin_bit_cast(float, w.y << 16), __builtin_bit_cast(float, w.y & 0xffff0000u)};
;                     const f32x4 b1 = (f32x4){__builtin_bit_cast(float, w.z << 16), __builtin_bit_cast(float, w.z & 0xffff0000u), __builtin_bit_cast(float, w.w << 16), __builtin_bit_cast(float, w.w & 0xffff0000u)};
;                     const f32x4 v0 = acc[ai][bj][m][0] + b0, v1 = acc[ai][bj][m][1] + b1;
;                     if (last) { __builtin_nontemporal_store(v0, (f32x4*)(out + off)); __builtin_nontemporal_store(v1, (f32x4*)(out + off + 4)); }
;                     else { q += sq4(v0) + sq4(v1); *(u32x4*)(xb + off) = pack8(v0, v1); }
;                 }
;                 if (!last) { q += shx(q, 16); q += shx(q, 32); if (fq == 0) ss[(size_t)row * 16 + u.pn * 4 + wc] = q; }
;             }
.LBB0_1507:
	v_lshl_or_b32 v168, s16, 8, v188
	v_lshl_add_u32 v172, s50, 8, v186
	v_ashrrev_i32_e32 v169, 31, v168
	v_lshlrev_b64 v[202:203], 1, v[168:169]
	v_ashrrev_i32_e32 v173, 31, v172
	v_lshl_add_u64 v[170:171], s[20:21], 0, v[202:203]
	v_lshlrev_b64 v[204:205], 11, v[172:173]
	v_lshl_add_u64 v[120:121], v[170:171], 0, v[204:205]
	global_load_dwordx4 v[192:195], v[120:121], off
	global_load_dwordx4 v[196:199], v[120:121], off offset:256
	v_or_b32_e32 v182, 16, v172
	v_ashrrev_i32_e32 v183, 31, v182
	v_or_b32_e32 v178, 32, v172
	v_lshlrev_b64 v[184:185], 11, v[182:183]
	v_ashrrev_i32_e32 v179, 31, v178
	v_or_b32_e32 v174, 48, v172
	v_lshl_add_u64 v[120:121], v[170:171], 0, v[184:185]
	v_lshlrev_b64 v[180:181], 11, v[178:179]
	v_ashrrev_i32_e32 v175, 31, v174
	global_load_dwordx4 v[148:151], v[120:121], off
	global_load_dwordx4 v[144:147], v[120:121], off offset:256
	v_lshl_add_u64 v[120:121], v[170:171], 0, v[180:181]
	v_lshlrev_b64 v[176:177], 11, v[174:175]
	global_load_dwordx4 v[140:143], v[120:121], off
	global_load_dwordx4 v[136:139], v[120:121], off offset:256
	v_lshl_add_u64 v[120:121], v[170:171], 0, v[176:177]
	global_load_dwordx4 v[132:135], v[120:121], off
	s_nop 0
	global_load_dwordx4 v[120:123], v[120:121], off offset:256
	s_lshl_b32 s50, s16, 2
	s_ashr_i32 s51, s50, 31
	s_waitcnt vmcnt(0)
	v_lshlrev_b32_e32 v206, 16, v192
	v_and_b32_e32 v207, 0xffff0000, v192
	v_lshlrev_b32_e32 v192, 16, v193
	v_and_b32_e32 v193, 0xffff0000, v193
	v_lshlrev_b32_e32 v208, 16, v194
	v_and_b32_e32 v209, 0xffff0000, v194
	v_lshlrev_b32_e32 v194, 16, v195
	v_and_b32_e32 v195, 0xffff0000, v195
	v_pk_add_f32 v[130:131], v[130:131], v[192:193]
	v_pk_add_f32 v[128:129], v[128:129], v[206:207]
	v_pk_add_f32 v[192:193], v[126:127], v[194:195]
	v_pk_add_f32 v[126:127], v[124:125], v[208:209]
	v_mul_f32_e32 v124, v129, v129
	v_mul_f32_e32 v125, v131, v131
	v_fmac_f32_e32 v124, v128, v128
	v_fmac_f32_e32 v125, v130, v130
	v_add_f32_e32 v124, v124, v125
	v_mul_f32_e32 v125, v127, v127
	v_mul_f32_e32 v194, v193, v193
	v_fmac_f32_e32 v125, v126, v126
	v_fmac_f32_e32 v194, v192, v192
	v_add_f32_e32 v125, v125, v194
	v_add_f32_e32 v194, v124, v125
	v_cvt_pk_bf16_f32 v124, v128, v129
	v_lshl_add_u64 v[128:129], s[20:21], 0, v[204:205]
	v_cvt_pk_bf16_f32 v125, v130, v131
	v_cvt_pk_bf16_f32 v126, v126, v127
	v_cvt_pk_bf16_f32 v127, v192, v193
	v_lshl_add_u64 v[128:129], v[128:129], 0, v[202:203]
	global_store_dwordx4 v[128:129], v[124:127], off
	v_lshlrev_b32_e32 v130, 16, v198
	v_and_b32_e32 v131, 0xffff0000, v198
	v_lshlrev_b32_e32 v124, 16, v196
	v_and_b32_e32 v125, 0xffff0000, v196
	v_lshlrev_b32_e32 v126, 16, v197
	v_and_b32_e32 v127, 0xffff0000, v197
	v_lshlrev_b32_e32 v192, 16, v199
	v_and_b32_e32 v193, 0xffff0000, v199
	v_pk_add_f32 v[118:119], v[118:119], v[126:127]
	v_pk_add_f32 v[116:117], v[116:117], v[124:125]
	v_pk_add_f32 v[124:125], v[114:115], v[192:193]
	v_pk_add_f32 v[114:115], v[112:113], v[130:131]
	v_mul_f32_e32 v112, v117, v117
	v_mul_f32_e32 v113, v119, v119
	v_fmac_f32_e32 v112, v116, v116
	v_fmac_f32_e32 v113, v118, v118
	v_add_f32_e32 v112, v112, v113
	v_mul_f32_e32 v113, v115, v115
	v_mul_f32_e32 v126, v125, v125
	v_fmac_f32_e32 v113, v114, v114
	v_fmac_f32_e32 v126, v124, v124
	v_add_f32_e32 v113, v113, v126
	v_add_f32_e32 v112, v112, v113
	v_add_f32_e32 v126, v194, v112
	v_cvt_pk_bf16_f32 v112, v116, v117
	v_cvt_pk_bf16_f32 v113, v118, v119
	v_cvt_pk_bf16_f32 v114, v114, v115
	v_cvt_pk_bf16_f32 v115, v124, v125
	global_store_dwordx4 v[128:129], v[112:115], off offset:256
	s_nop 1
	v_mov_b32_e32 v112, v201
	v_mov_b32_e32 v113, v201
	v_lshlrev_b32_e32 v112, 2, v112
	v_xor_b32_e32 v112, 64, v112
	v_mov_b32_e32 v112, v126
	s_nop 1
	v_permlane16_swap_b32_e32 v112, v126
	s_waitcnt lgkmcnt(0)
	v_add_f32_e32 v112, v126, v112
	v_lshlrev_b32_e32 v113, 2, v113
	v_xor_b32_e32 v113, 0x80, v113
	v_mov_b32_e32 v113, v112
	s_nop 1
	v_permlane32_swap_b32_e32 v113, v112
	s_and_saveexec_b64 s[52:53], s[8:9]
	s_cbranch_execz .LBB0_1509
	s_waitcnt lgkmcnt(0)
	v_add_f32_e32 v114, v112, v113
	v_lshlrev_b64 v[112:113], 6, v[172:173]
	v_lshl_add_u64 v[112:113], s[22:23], 0, v[112:113]
	v_lshl_add_u64 v[112:113], s[50:51], 2, v[112:113]
	s_lshl_b32 s16, s58, 2
	v_lshl_add_u64 v[112:113], v[112:113], 0, s[16:17]
	global_store_dword v[112:113], v114, off
; __device__ __forceinline__ float sq4(f32x4 v) { return (v[0] * v[0] + v[1] * v[1]) + (v[2] * v[2] + v[3] * v[3]); }
; __device__ __forceinline__ u32x4 pack8(f32x4 a, f32x4 b) { u32x4 w; w.x = cvt_pk_bf16(a[0], a[1]); w.y = cvt_pk_bf16(a[2], a[3]); w.z = cvt_pk_bf16(b[0], b[1]); w.w = cvt_pk_bf16(b[2], b[3]); return w; }
;     __device__ __forceinline__ void operator()(const f32x4 (&acc)[2][2][4][2], const Unit& u, int wr, int wc, int fr, int fq) const {
;         const int col0 = u.pn * 256 + 32 * wc + 8 * fq;
; #pragma unroll
;         for (int ai = 0; ai < 2; ++ai) {
;             u32x4 bs[4][2];
; #pragma unroll
;             for (int m = 0; m < 4; ++m)
; #pragma unroll
;                 for (int bj = 0; bj < 2; ++bj) bs[m][bj] = *(const u32x4*)(xb + (size_t)(u.pm * BM + ai * HALF + wr * 64 + m * 16 + fr) * 1024 + col0 + 128 * bj);
; #pragma unroll
;             for (int m = 0; m < 4; ++m) {
;                 const int row = u.pm * BM + ai * HALF + wr * 64 + m * 16 + fr;
;                 float q = 0.f;
; #pragma unroll
;                 for (int bj = 0; bj < 2; ++bj) {
;                     const size_t off = (size_t)row * 1024 + col0 + 128 * bj; const u32x4 w = bs[m][bj];
;                     const f32x4 b0 = (f32x4){__builtin_bit_cast(float, w.x << 16), __builtin_bit_cast(float, w.x & 0xffff0000u), __builtin_bit_cast(float, w.y << 16), __builtin_bit_cast(float, w.y & 0xffff0000u)};
;                     const f32x4 b1 = (f32x4){__builtin_bit_cast(float, w.z << 16), __builtin_bit_cast(float, w.z & 0xffff0000u), __builtin_bit_cast(float, w.w << 16), __builtin_bit_cast(float, w.w & 0xffff0000u)};
;                     const f32x4 v0 = acc[ai][bj][m][0] + b0, v1 = acc[ai][bj][m][1] + b1;
;                     if (last) { __builtin_nontemporal_store(v0, (f32x4*)(out + off)); __builtin_nontemporal_store(v1, (f32x4*)(out + off + 4)); }
;                     else { q += sq4(v0) + sq4(v1); *(u32x4*)(xb + off) = pack8(v0, v1); }
;                 }
;                 if (!last) { q += shx(q, 16); q += shx(q, 32); if (fq == 0) ss[(size_t)row * 16 + u.pn * 4 + wc] = q; }
;             }
.LBB0_1509:
	s_or_b64 exec, exec, s[52:53]
	v_lshlrev_b32_e32 v112, 16, v148
	s_waitcnt lgkmcnt(0)
	v_and_b32_e32 v113, 0xffff0000, v148
	v_lshlrev_b32_e32 v114, 16, v149
	v_and_b32_e32 v115, 0xffff0000, v149
	v_lshlrev_b32_e32 v116, 16, v150
	v_and_b32_e32 v117, 0xffff0000, v150
	v_lshlrev_b32_e32 v118, 16, v151
	v_and_b32_e32 v119, 0xffff0000, v151
	v_pk_add_f32 v[110:111], v[110:111], v[114:115]
	v_pk_add_f32 v[108:109], v[108:109], v[112:113]
	v_pk_add_f32 v[112:113], v[106:107], v[118:119]
	v_pk_add_f32 v[106:107], v[104:105], v[116:117]
	v_mul_f32_e32 v104, v109, v109
	v_mul_f32_e32 v105, v111, v111
	v_fmac_f32_e32 v104, v108, v108
	v_fmac_f32_e32 v105, v110, v110
	v_add_f32_e32 v104, v104, v105
	v_mul_f32_e32 v105, v107, v107
	v_mul_f32_e32 v114, v113, v113
	v_fmac_f32_e32 v105, v106, v106
	v_fmac_f32_e32 v114, v112, v112
	v_add_f32_e32 v105, v105, v114
	v_add_f32_e32 v114, v104, v105
	v_cvt_pk_bf16_f32 v104, v108, v109
	v_lshl_add_u64 v[108:109], s[20:21], 0, v[184:185]
	v_cvt_pk_bf16_f32 v105, v110, v111
	v_cvt_pk_bf16_f32 v106, v106, v107
	v_cvt_pk_bf16_f32 v107, v112, v113
	v_lshl_add_u64 v[108:109], v[168:169], 1, v[108:109]
	global_store_dwordx4 v[108:109], v[104:107], off
	v_lshlrev_b32_e32 v110, 16, v146
	v_and_b32_e32 v111, 0xffff0000, v146
	v_lshlrev_b32_e32 v104, 16, v144
	v_and_b32_e32 v105, 0xffff0000, v144
	v_lshlrev_b32_e32 v106, 16, v145
	v_and_b32_e32 v107, 0xffff0000, v145
	v_lshlrev_b32_e32 v112, 16, v147
	v_and_b32_e32 v113, 0xffff0000, v147
	v_pk_add_f32 v[102:103], v[102:103], v[106:107]
	v_pk_add_f32 v[100:101], v[100:101], v[104:105]
	v_pk_add_f32 v[104:105], v[98:99], v[112:113]
	v_pk_add_f32 v[98:99], v[96:97], v[110:111]
	v_mul_f32_e32 v96, v101, v101
	v_mul_f32_e32 v97, v103, v103
	v_fmac_f32_e32 v96, v100, v100
	v_fmac_f32_e32 v97, v102, v102
	v_add_f32_e32 v96, v96, v97
	v_mul_f32_e32 v97, v99, v99
	v_mul_f32_e32 v106, v105, v105
	v_fmac_f32_e32 v97, v98, v98
	v_fmac_f32_e32 v106, v104, v104
	v_add_f32_e32 v97, v97, v106
	v_add_f32_e32 v96, v96, v97
	v_add_f32_e32 v106, v114, v96
	v_cvt_pk_bf16_f32 v96, v100, v101
	v_cvt_pk_bf16_f32 v97, v102, v103
	v_cvt_pk_bf16_f32 v98, v98, v99
	v_cvt_pk_bf16_f32 v99, v104, v105
	global_store_dwordx4 v[108:109], v[96:99], off offset:256
	s_nop 1
	v_mov_b32_e32 v96, v201
	v_mov_b32_e32 v97, v201
	v_lshlrev_b32_e32 v96, 2, v96
	v_xor_b32_e32 v96, 64, v96
	v_mov_b32_e32 v96, v106
	s_nop 1
	v_permlane16_swap_b32_e32 v96, v106
	s_waitcnt lgkmcnt(0)
	v_add_f32_e32 v96, v106, v96
	v_lshlrev_b32_e32 v97, 2, v97
	v_xor_b32_e32 v97, 0x80, v97
	v_mov_b32_e32 v97, v96
	s_nop 1
	v_permlane32_swap_b32_e32 v97, v96
	s_and_saveexec_b64 s[52:53], s[8:9]
	s_cbranch_execz .LBB0_1511
	s_waitcnt lgkmcnt(0)
	v_add_f32_e32 v98, v96, v97
	v_lshlrev_b64 v[96:97], 6, v[182:183]
	v_lshl_add_u64 v[96:97], s[22:23], 0, v[96:97]
	v_lshl_add_u64 v[96:97], s[50:51], 2, v[96:97]
	s_lshl_b32 s16, s58, 2
	v_lshl_add_u64 v[96:97], v[96:97], 0, s[16:17]
	global_store_dword v[96:97], v98, off
.LBB0_1511:
	s_or_b64 exec, exec, s[52:53]
	v_lshlrev_b32_e32 v96, 16, v140
	s_waitcnt lgkmcnt(0)
	v_and_b32_e32 v97, 0xffff0000, v140
	v_lshlrev_b32_e32 v98, 16, v141
	v_and_b32_e32 v99, 0xffff0000, v141
	v_lshlrev_b32_e32 v100, 16, v142
	v_and_b32_e32 v101, 0xffff0000, v142
	v_lshlrev_b32_e32 v102, 16, v143
	v_and_b32_e32 v103, 0xffff0000, v143
	v_pk_add_f32 v[94:95], v[94:95], v[98:99]
	v_pk_add_f32 v[92:93], v[92:93], v[96:97]
	v_pk_add_f32 v[96:97], v[90:91], v[102:103]
	v_pk_add_f32 v[90:91], v[88:89], v[100:101]
	v_mul_f32_e32 v88, v93, v93
	v_mul_f32_e32 v89, v95, v95
	v_fmac_f32_e32 v88, v92, v92
	v_fmac_f32_e32 v89, v94, v94
	v_add_f32_e32 v88, v88, v89
	v_mul_f32_e32 v89, v91, v91
	v_mul_f32_e32 v98, v97, v97
	v_fmac_f32_e32 v89, v90, v90
	v_fmac_f32_e32 v98, v96, v96
	v_add_f32_e32 v89, v89, v98
	v_add_f32_e32 v98, v88, v89
	v_cvt_pk_bf16_f32 v88, v92, v93
	v_lshl_add_u64 v[92:93], s[20:21], 0, v[180:181]
	v_cvt_pk_bf16_f32 v89, v94, v95
	v_cvt_pk_bf16_f32 v90, v90, v91
	v_cvt_pk_bf16_f32 v91, v96, v97
	v_lshl_add_u64 v[92:93], v[168:169], 1, v[92:93]
	global_store_dwordx4 v[92:93], v[88:91], off
	v_lshlrev_b32_e32 v94, 16, v138
	v_and_b32_e32 v95, 0xffff0000, v138
	v_lshlrev_b32_e32 v88, 16, v136
	v_and_b32_e32 v89, 0xffff0000, v136
	v_lshlrev_b32_e32 v90, 16, v137
	v_and_b32_e32 v91, 0xffff0000, v137
	v_lshlrev_b32_e32 v96, 16, v139
	v_and_b32_e32 v97, 0xffff0000, v139
	v_pk_add_f32 v[86:87], v[86:87], v[90:91]
	v_pk_add_f32 v[84:85], v[84:85], v[88:89]
	v_pk_add_f32 v[88:89], v[82:83], v[96:97]
	v_pk_add_f32 v[82:83], v[80:81], v[94:95]
	v_mul_f32_e32 v80, v85, v85
	v_mul_f32_e32 v81, v87, v87
	v_fmac_f32_e32 v80, v84, v84
	v_fmac_f32_e32 v81, v86, v86
	v_add_f32_e32 v80, v80, v81
	v_mul_f32_e32 v81, v83, v83
	v_mul_f32_e32 v90, v89, v89
	v_fmac_f32_e32 v81, v82, v82
	v_fmac_f32_e32 v90, v88, v88
	v_add_f32_e32 v81, v81, v90
	v_add_f32_e32 v80, v80, v81
	v_add_f32_e32 v90, v98, v80
	v_cvt_pk_bf16_f32 v80, v84, v85
	v_cvt_pk_bf16_f32 v81, v86, v87
	v_cvt_pk_bf16_f32 v82, v82, v83
	v_cvt_pk_bf16_f32 v83, v88, v89
	global_store_dwordx4 v[92:93], v[80:83], off offset:256
	s_nop 1
	v_mov_b32_e32 v80, v201
	v_mov_b32_e32 v81, v201
	v_lshlrev_b32_e32 v80, 2, v80
	v_xor_b32_e32 v80, 64, v80
	v_mov_b32_e32 v80, v90
	s_nop 1
	v_permlane16_swap_b32_e32 v80, v90
	s_waitcnt lgkmcnt(0)
	v_add_f32_e32 v80, v90, v80
	v_lshlrev_b32_e32 v81, 2, v81
	v_xor_b32_e32 v81, 0x80, v81
	v_mov_b32_e32 v81, v80
	s_nop 1
	v_permlane32_swap_b32_e32 v81, v80
	s_and_saveexec_b64 s[52:53], s[8:9]
	s_cbranch_execz .LBB0_1513
	s_waitcnt lgkmcnt(0)
	v_add_f32_e32 v82, v80, v81
	v_lshlrev_b64 v[80:81], 6, v[178:179]
	v_lshl_add_u64 v[80:81], s[22:23], 0, v[80:81]
	v_lshl_add_u64 v[80:81], s[50:51], 2, v[80:81]
	s_lshl_b32 s16, s58, 2
	v_lshl_add_u64 v[80:81], v[80:81], 0, s[16:17]
	global_store_dword v[80:81], v82, off
; __device__ __forceinline__ float sq4(f32x4 v) { return (v[0] * v[0] + v[1] * v[1]) + (v[2] * v[2] + v[3] * v[3]); }
; __device__ __forceinline__ u32x4 pack8(f32x4 a, f32x4 b) { u32x4 w; w.x = cvt_pk_bf16(a[0], a[1]); w.y = cvt_pk_bf16(a[2], a[3]); w.z = cvt_pk_bf16(b[0], b[1]); w.w = cvt_pk_bf16(b[2], b[3]); return w; }
;     __device__ __forceinline__ void operator()(const f32x4 (&acc)[2][2][4][2], const Unit& u, int wr, int wc, int fr, int fq) const {
;         const int col0 = u.pn * 256 + 32 * wc + 8 * fq;
; #pragma unroll
;         for (int ai = 0; ai < 2; ++ai) {
;             u32x4 bs[4][2];
; #pragma unroll
;             for (int m = 0; m < 4; ++m)
; #pragma unroll
;                 for (int bj = 0; bj < 2; ++bj) bs[m][bj] = *(const u32x4*)(xb + (size_t)(u.pm * BM + ai * HALF + wr * 64 + m * 16 + fr) * 1024 + col0 + 128 * bj);
; #pragma unroll
;             for (int m = 0; m < 4; ++m) {
;                 const int row = u.pm * BM + ai * HALF + wr * 64 + m * 16 + fr;
;                 float q = 0.f;
; #pragma unroll
;                 for (int bj = 0; bj < 2; ++bj) {
;                     const size_t off = (size_t)row * 1024 + col0 + 128 * bj; const u32x4 w = bs[m][bj];
;                     const f32x4 b0 = (f32x4){__builtin_bit_cast(float, w.x << 16), __builtin_bit_cast(float, w.x & 0xffff0000u), __builtin_bit_cast(float, w.y << 16), __builtin_bit_cast(float, w.y & 0xffff0000u)};
;                     const f32x4 b1 = (f32x4){__builtin_bit_cast(float, w.z << 16), __builtin_bit_cast(float, w.z & 0xffff0000u), __builtin_bit_cast(float, w.w << 16), __builtin_bit_cast(float, w.w & 0xffff0000u)};
;                     const f32x4 v0 = acc[ai][bj][m][0] + b0, v1 = acc[ai][bj][m][1] + b1;
;                     if (last) { __builtin_nontemporal_store(v0, (f32x4*)(out + off)); __builtin_nontemporal_store(v1, (f32x4*)(out + off + 4)); }
;                     else { q += sq4(v0) + sq4(v1); *(u32x4*)(xb + off) = pack8(v0, v1); }
;                 }
;                 if (!last) { q += shx(q, 16); q += shx(q, 32); if (fq == 0) ss[(size_t)row * 16 + u.pn * 4 + wc] = q; }
;             }
.LBB0_1513:
	s_or_b64 exec, exec, s[52:53]
	v_lshlrev_b32_e32 v80, 16, v132
	s_waitcnt lgkmcnt(0)
	v_and_b32_e32 v81, 0xffff0000, v132
	v_lshlrev_b32_e32 v82, 16, v133
	v_and_b32_e32 v83, 0xffff0000, v133
	v_lshlrev_b32_e32 v84, 16, v134
	v_and_b32_e32 v85, 0xffff0000, v134
	v_lshlrev_b32_e32 v86, 16, v135
	v_and_b32_e32 v87, 0xffff0000, v135
	v_pk_add_f32 v[78:79], v[78:79], v[82:83]
	v_pk_add_f32 v[76:77], v[76:77], v[80:81]
	v_pk_add_f32 v[80:81], v[74:75], v[86:87]
	v_pk_add_f32 v[74:75], v[72:73], v[84:85]
	v_mul_f32_e32 v72, v77, v77
	v_mul_f32_e32 v73, v79, v79
	v_fmac_f32_e32 v72, v76, v76
	v_fmac_f32_e32 v73, v78, v78
	v_add_f32_e32 v72, v72, v73
	v_mul_f32_e32 v73, v75, v75
	v_mul_f32_e32 v82, v81, v81
	v_fmac_f32_e32 v73, v74, v74
	v_fmac_f32_e32 v82, v80, v80
	v_add_f32_e32 v73, v73, v82
	v_add_f32_e32 v82, v72, v73
	v_cvt_pk_bf16_f32 v72, v76, v77
	v_lshl_add_u64 v[76:77], s[20:21], 0, v[176:177]
	v_cvt_pk_bf16_f32 v73, v78, v79
	v_cvt_pk_bf16_f32 v74, v74, v75
	v_cvt_pk_bf16_f32 v75, v80, v81
	v_lshl_add_u64 v[76:77], v[168:169], 1, v[76:77]
	global_store_dwordx4 v[76:77], v[72:75], off
	v_lshlrev_b32_e32 v78, 16, v122
	v_and_b32_e32 v79, 0xffff0000, v122
	v_lshlrev_b32_e32 v72, 16, v120
	v_and_b32_e32 v73, 0xffff0000, v120
	v_lshlrev_b32_e32 v74, 16, v121
	v_and_b32_e32 v75, 0xffff0000, v121
	v_lshlrev_b32_e32 v80, 16, v123
	v_and_b32_e32 v81, 0xffff0000, v123
	v_pk_add_f32 v[70:71], v[70:71], v[74:75]
	v_pk_add_f32 v[68:69], v[68:69], v[72:73]
	v_pk_add_f32 v[72:73], v[66:67], v[80:81]
	v_pk_add_f32 v[66:67], v[64:65], v[78:79]
	v_mul_f32_e32 v64, v69, v69
	v_mul_f32_e32 v65, v71, v71
	v_fmac_f32_e32 v64, v68, v68
	v_fmac_f32_e32 v65, v70, v70
	v_add_f32_e32 v64, v64, v65
	v_mul_f32_e32 v65, v67, v67
	v_mul_f32_e32 v74, v73, v73
	v_fmac_f32_e32 v65, v66, v66
	v_fmac_f32_e32 v74, v72, v72
	v_add_f32_e32 v65, v65, v74
	v_add_f32_e32 v64, v64, v65
	v_add_f32_e32 v74, v82, v64
	v_cvt_pk_bf16_f32 v64, v68, v69
	v_cvt_pk_bf16_f32 v65, v70, v71
	v_cvt_pk_bf16_f32 v66, v66, v67
	v_cvt_pk_bf16_f32 v67, v72, v73
	global_store_dwordx4 v[76:77], v[64:67], off offset:256
	s_nop 1
	v_mov_b32_e32 v64, v201
	v_mov_b32_e32 v65, v201
	v_lshlrev_b32_e32 v64, 2, v64
	v_xor_b32_e32 v64, 64, v64
	v_mov_b32_e32 v64, v74
	s_nop 1
	v_permlane16_swap_b32_e32 v64, v74
	s_waitcnt lgkmcnt(0)
	v_add_f32_e32 v64, v74, v64
	v_lshlrev_b32_e32 v65, 2, v65
	v_xor_b32_e32 v65, 0x80, v65
	v_mov_b32_e32 v65, v64
	s_nop 1
	v_permlane32_swap_b32_e32 v65, v64
	s_and_saveexec_b64 s[52:53], s[8:9]
	s_cbranch_execz .LBB0_1515
	s_waitcnt lgkmcnt(0)
	v_add_f32_e32 v66, v64, v65
	v_lshlrev_b64 v[64:65], 6, v[174:175]
	v_lshl_add_u64 v[64:65], s[22:23], 0, v[64:65]
	v_lshl_add_u64 v[64:65], s[50:51], 2, v[64:65]
	s_lshl_b32 s16, s58, 2
	v_lshl_add_u64 v[64:65], v[64:65], 0, s[16:17]
	global_store_dword v[64:65], v66, off
.LBB0_1515:
	s_or_b64 exec, exec, s[52:53]
	v_add_u32_e32 v100, 0x80, v172
	v_ashrrev_i32_e32 v101, 31, v100
	v_lshlrev_b64 v[110:111], 11, v[100:101]
	s_waitcnt lgkmcnt(0)
	v_lshl_add_u64 v[64:65], v[170:171], 0, v[110:111]
	global_load_dwordx4 v[102:105], v[64:65], off
	global_load_dwordx4 v[106:109], v[64:65], off offset:256
	v_add_u32_e32 v96, 0x90, v172
	v_ashrrev_i32_e32 v97, 31, v96
	v_add_u32_e32 v92, 0xa0, v172
	v_lshlrev_b64 v[98:99], 11, v[96:97]
	v_ashrrev_i32_e32 v93, 31, v92
	v_add_u32_e32 v88, 0xb0, v172
	v_lshl_add_u64 v[64:65], v[170:171], 0, v[98:99]
	v_lshlrev_b64 v[94:95], 11, v[92:93]
	v_ashrrev_i32_e32 v89, 31, v88
	global_load_dwordx4 v[84:87], v[64:65], off
	global_load_dwordx4 v[80:83], v[64:65], off offset:256
	v_lshl_add_u64 v[64:65], v[170:171], 0, v[94:95]
	v_lshlrev_b64 v[90:91], 11, v[88:89]
	global_load_dwordx4 v[76:79], v[64:65], off
	global_load_dwordx4 v[72:75], v[64:65], off offset:256
	v_lshl_add_u64 v[64:65], v[170:171], 0, v[90:91]
	global_load_dwordx4 v[68:71], v[64:65], off
	s_nop 0
	global_load_dwordx4 v[64:67], v[64:65], off offset:256
	s_waitcnt vmcnt(7)
	v_lshlrev_b32_e32 v112, 16, v102
	v_and_b32_e32 v113, 0xffff0000, v102
	v_lshlrev_b32_e32 v102, 16, v103
	v_and_b32_e32 v103, 0xffff0000, v103
	v_lshlrev_b32_e32 v114, 16, v104
	v_and_b32_e32 v115, 0xffff0000, v104
	v_lshlrev_b32_e32 v104, 16, v105
	v_and_b32_e32 v105, 0xffff0000, v105
	v_pk_add_f32 v[62:63], v[62:63], v[102:103]
	v_pk_add_f32 v[60:61], v[60:61], v[112:113]
	v_pk_add_f32 v[102:103], v[58:59], v[104:105]
	v_pk_add_f32 v[58:59], v[56:57], v[114:115]
	v_mul_f32_e32 v56, v61, v61
	v_mul_f32_e32 v57, v63, v63
	v_fmac_f32_e32 v56, v60, v60
	v_fmac_f32_e32 v57, v62, v62
	v_add_f32_e32 v56, v56, v57
	v_mul_f32_e32 v57, v59, v59
	v_mul_f32_e32 v104, v103, v103
	v_fmac_f32_e32 v57, v58, v58
	v_fmac_f32_e32 v104, v102, v102
	v_add_f32_e32 v57, v57, v104
	v_add_f32_e32 v104, v56, v57
	v_cvt_pk_bf16_f32 v56, v60, v61
	v_lshl_add_u64 v[60:61], s[20:21], 0, v[110:111]
	v_cvt_pk_bf16_f32 v57, v62, v63
	v_cvt_pk_bf16_f32 v58, v58, v59
	v_cvt_pk_bf16_f32 v59, v102, v103
	v_lshl_add_u64 v[60:61], v[168:169], 1, v[60:61]
	global_store_dwordx4 v[60:61], v[56:59], off
	s_waitcnt vmcnt(7)
	v_lshlrev_b32_e32 v62, 16, v108
	v_and_b32_e32 v63, 0xffff0000, v108
	v_lshlrev_b32_e32 v56, 16, v106
	v_and_b32_e32 v57, 0xffff0000, v106
	v_lshlrev_b32_e32 v58, 16, v107
	v_and_b32_e32 v59, 0xffff0000, v107
	v_lshlrev_b32_e32 v102, 16, v109
	v_and_b32_e32 v103, 0xffff0000, v109
	v_pk_add_f32 v[54:55], v[54:55], v[58:59]
	v_pk_add_f32 v[52:53], v[52:53], v[56:57]
	v_pk_add_f32 v[56:57], v[50:51], v[102:103]
	v_pk_add_f32 v[50:51], v[48:49], v[62:63]
	v_mul_f32_e32 v48, v53, v53
	v_mul_f32_e32 v49, v55, v55
	v_fmac_f32_e32 v48, v52, v52
	v_fmac_f32_e32 v49, v54, v54
	v_add_f32_e32 v48, v48, v49
	v_mul_f32_e32 v49, v51, v51
	v_mul_f32_e32 v58, v57, v57
	v_fmac_f32_e32 v49, v50, v50
	v_fmac_f32_e32 v58, v56, v56
	v_add_f32_e32 v49, v49, v58
	v_add_f32_e32 v48, v48, v49
	v_add_f32_e32 v58, v104, v48
	v_cvt_pk_bf16_f32 v48, v52, v53
	v_cvt_pk_bf16_f32 v49, v54, v55
	v_cvt_pk_bf16_f32 v50, v50, v51
	v_cvt_pk_bf16_f32 v51, v56, v57
	global_store_dwordx4 v[60:61], v[48:51], off offset:256
	s_nop 1
	v_mov_b32_e32 v48, v201
	v_mov_b32_e32 v49, v201
	v_lshlrev_b32_e32 v48, 2, v48
	v_xor_b32_e32 v48, 64, v48
	v_mov_b32_e32 v48, v58
	s_nop 1
	v_permlane16_swap_b32_e32 v48, v58
	s_waitcnt lgkmcnt(0)
	v_add_f32_e32 v48, v58, v48
	v_lshlrev_b32_e32 v49, 2, v49
	v_xor_b32_e32 v49, 0x80, v49
	v_mov_b32_e32 v49, v48
	s_nop 1
	v_permlane32_swap_b32_e32 v49, v48
	s_and_saveexec_b64 s[52:53], s[8:9]
	s_cbranch_execz .LBB0_1517
	s_waitcnt lgkmcnt(0)
	v_add_f32_e32 v50, v48, v49
	v_lshlrev_b64 v[48:49], 6, v[100:101]
	v_lshl_add_u64 v[48:49], s[22:23], 0, v[48:49]
	v_lshl_add_u64 v[48:49], s[50:51], 2, v[48:49]
	s_lshl_b32 s16, s58, 2
	v_lshl_add_u64 v[48:49], v[48:49], 0, s[16:17]
	global_store_dword v[48:49], v50, off
; __device__ __forceinline__ float sq4(f32x4 v) { return (v[0] * v[0] + v[1] * v[1]) + (v[2] * v[2] + v[3] * v[3]); }
; __device__ __forceinline__ u32x4 pack8(f32x4 a, f32x4 b) { u32x4 w; w.x = cvt_pk_bf16(a[0], a[1]); w.y = cvt_pk_bf16(a[2], a[3]); w.z = cvt_pk_bf16(b[0], b[1]); w.w = cvt_pk_bf16(b[2], b[3]); return w; }
;     __device__ __forceinline__ void operator()(const f32x4 (&acc)[2][2][4][2], const Unit& u, int wr, int wc, int fr, int fq) const {
;         const int col0 = u.pn * 256 + 32 * wc + 8 * fq;
; #pragma unroll
;         for (int ai = 0; ai < 2; ++ai) {
;             u32x4 bs[4][2];
; #pragma unroll
;             for (int m = 0; m < 4; ++m)
; #pragma unroll
;                 for (int bj = 0; bj < 2; ++bj) bs[m][bj] = *(const u32x4*)(xb + (size_t)(u.pm * BM + ai * HALF + wr * 64 + m * 16 + fr) * 1024 + col0 + 128 * bj);
; #pragma unroll
;             for (int m = 0; m < 4; ++m) {
;                 const int row = u.pm * BM + ai * HALF + wr * 64 + m * 16 + fr;
;                 float q = 0.f;
; #pragma unroll
;                 for (int bj = 0; bj < 2; ++bj) {
;                     const size_t off = (size_t)row * 1024 + col0 + 128 * bj; const u32x4 w = bs[m][bj];
;                     const f32x4 b0 = (f32x4){__builtin_bit_cast(float, w.x << 16), __builtin_bit_cast(float, w.x & 0xffff0000u), __builtin_bit_cast(float, w.y << 16), __builtin_bit_cast(float, w.y & 0xffff0000u)};
;                     const f32x4 b1 = (f32x4){__builtin_bit_cast(float, w.z << 16), __builtin_bit_cast(float, w.z & 0xffff0000u), __builtin_bit_cast(float, w.w << 16), __builtin_bit_cast(float, w.w & 0xffff0000u)};
;                     const f32x4 v0 = acc[ai][bj][m][0] + b0, v1 = acc[ai][bj][m][1] + b1;
;                     if (last) { __builtin_nontemporal_store(v0, (f32x4*)(out + off)); __builtin_nontemporal_store(v1, (f32x4*)(out + off + 4)); }
;                     else { q += sq4(v0) + sq4(v1); *(u32x4*)(xb + off) = pack8(v0, v1); }
;                 }
;                 if (!last) { q += shx(q, 16); q += shx(q, 32); if (fq == 0) ss[(size_t)row * 16 + u.pn * 4 + wc] = q; }
;             }
.LBB0_1517:
	s_or_b64 exec, exec, s[52:53]
	s_waitcnt vmcnt(7)
	v_lshlrev_b32_e32 v48, 16, v84
	s_waitcnt lgkmcnt(0)
	v_and_b32_e32 v49, 0xffff0000, v84
	v_lshlrev_b32_e32 v50, 16, v85
	v_and_b32_e32 v51, 0xffff0000, v85
	v_lshlrev_b32_e32 v52, 16, v86
	v_and_b32_e32 v53, 0xffff0000, v86
	v_lshlrev_b32_e32 v54, 16, v87
	v_and_b32_e32 v55, 0xffff0000, v87
	v_pk_add_f32 v[46:47], v[46:47], v[50:51]
	v_pk_add_f32 v[44:45], v[44:45], v[48:49]
	v_pk_add_f32 v[48:49], v[42:43], v[54:55]
	v_pk_add_f32 v[42:43], v[40:41], v[52:53]
	v_mul_f32_e32 v40, v45, v45
	v_mul_f32_e32 v41, v47, v47
	v_fmac_f32_e32 v40, v44, v44
	v_fmac_f32_e32 v41, v46, v46
	v_add_f32_e32 v40, v40, v41
	v_mul_f32_e32 v41, v43, v43
	v_mul_f32_e32 v50, v49, v49
	v_fmac_f32_e32 v41, v42, v42
	v_fmac_f32_e32 v50, v48, v48
	v_add_f32_e32 v41, v41, v50
	v_add_f32_e32 v50, v40, v41
	v_cvt_pk_bf16_f32 v40, v44, v45
	v_lshl_add_u64 v[44:45], s[20:21], 0, v[98:99]
	v_cvt_pk_bf16_f32 v41, v46, v47
	v_cvt_pk_bf16_f32 v42, v42, v43
	v_cvt_pk_bf16_f32 v43, v48, v49
	v_lshl_add_u64 v[44:45], v[168:169], 1, v[44:45]
	global_store_dwordx4 v[44:45], v[40:43], off
	s_waitcnt vmcnt(7)
	v_lshlrev_b32_e32 v46, 16, v82
	v_and_b32_e32 v47, 0xffff0000, v82
	v_lshlrev_b32_e32 v40, 16, v80
	v_and_b32_e32 v41, 0xffff0000, v80
	v_lshlrev_b32_e32 v42, 16, v81
	v_and_b32_e32 v43, 0xffff0000, v81
	v_lshlrev_b32_e32 v48, 16, v83
	v_and_b32_e32 v49, 0xffff0000, v83
	v_pk_add_f32 v[38:39], v[38:39], v[42:43]
	v_pk_add_f32 v[36:37], v[36:37], v[40:41]
	v_pk_add_f32 v[40:41], v[34:35], v[48:49]
	v_pk_add_f32 v[34:35], v[32:33], v[46:47]
	v_mul_f32_e32 v32, v37, v37
	v_mul_f32_e32 v33, v39, v39
	v_fmac_f32_e32 v32, v36, v36
	v_fmac_f32_e32 v33, v38, v38
	v_add_f32_e32 v32, v32, v33
	v_mul_f32_e32 v33, v35, v35
	v_mul_f32_e32 v42, v41, v41
	v_fmac_f32_e32 v33, v34, v34
	v_fmac_f32_e32 v42, v40, v40
	v_add_f32_e32 v33, v33, v42
	v_add_f32_e32 v32, v32, v33
	v_add_f32_e32 v42, v50, v32
	v_cvt_pk_bf16_f32 v32, v36, v37
	v_cvt_pk_bf16_f32 v33, v38, v39
	v_cvt_pk_bf16_f32 v34, v34, v35
	v_cvt_pk_bf16_f32 v35, v40, v41
	global_store_dwordx4 v[44:45], v[32:35], off offset:256
	s_nop 1
	v_mov_b32_e32 v32, v201
	v_mov_b32_e32 v33, v201
	v_lshlrev_b32_e32 v32, 2, v32
	v_xor_b32_e32 v32, 64, v32
	v_mov_b32_e32 v32, v42
	s_nop 1
	v_permlane16_swap_b32_e32 v32, v42
	s_waitcnt lgkmcnt(0)
	v_add_f32_e32 v32, v42, v32
	v_lshlrev_b32_e32 v33, 2, v33
	v_xor_b32_e32 v33, 0x80, v33
	v_mov_b32_e32 v33, v32
	s_nop 1
	v_permlane32_swap_b32_e32 v33, v32
	s_and_saveexec_b64 s[52:53], s[8:9]
	s_cbranch_execz .LBB0_1519
	s_waitcnt lgkmcnt(0)
	v_add_f32_e32 v34, v32, v33
	v_lshlrev_b64 v[32:33], 6, v[96:97]
	v_lshl_add_u64 v[32:33], s[22:23], 0, v[32:33]
	v_lshl_add_u64 v[32:33], s[50:51], 2, v[32:33]
	s_lshl_b32 s16, s58, 2
	v_lshl_add_u64 v[32:33], v[32:33], 0, s[16:17]
	global_store_dword v[32:33], v34, off
; __device__ __forceinline__ float sq4(f32x4 v) { return (v[0] * v[0] + v[1] * v[1]) + (v[2] * v[2] + v[3] * v[3]); }
; __device__ __forceinline__ u32x4 pack8(f32x4 a, f32x4 b) { u32x4 w; w.x = cvt_pk_bf16(a[0], a[1]); w.y = cvt_pk_bf16(a[2], a[3]); w.z = cvt_pk_bf16(b[0], b[1]); w.w = cvt_pk_bf16(b[2], b[3]); return w; }
;     __device__ __forceinline__ void operator()(const f32x4 (&acc)[2][2][4][2], const Unit& u, int wr, int wc, int fr, int fq) const {
;         const int col0 = u.pn * 256 + 32 * wc + 8 * fq;
; #pragma unroll
;         for (int ai = 0; ai < 2; ++ai) {
;             u32x4 bs[4][2];
; #pragma unroll
;             for (int m = 0; m < 4; ++m)
; #pragma unroll
;                 for (int bj = 0; bj < 2; ++bj) bs[m][bj] = *(const u32x4*)(xb + (size_t)(u.pm * BM + ai * HALF + wr * 64 + m * 16 + fr) * 1024 + col0 + 128 * bj);
; #pragma unroll
;             for (int m = 0; m < 4; ++m) {
;                 const int row = u.pm * BM + ai * HALF + wr * 64 + m * 16 + fr;
;                 float q = 0.f;
; #pragma unroll
;                 for (int bj = 0; bj < 2; ++bj) {
;                     const size_t off = (size_t)row * 1024 + col0 + 128 * bj; const u32x4 w = bs[m][bj];
;                     const f32x4 b0 = (f32x4){__builtin_bit_cast(float, w.x << 16), __builtin_bit_cast(float, w.x & 0xffff0000u), __builtin_bit_cast(float, w.y << 16), __builtin_bit_cast(float, w.y & 0xffff0000u)};
;                     const f32x4 b1 = (f32x4){__builtin_bit_cast(float, w.z << 16), __builtin_bit_cast(float, w.z & 0xffff0000u), __builtin_bit_cast(float, w.w << 16), __builtin_bit_cast(float, w.w & 0xffff0000u)};
;                     const f32x4 v0 = acc[ai][bj][m][0] + b0, v1 = acc[ai][bj][m][1] + b1;
;                     if (last) { __builtin_nontemporal_store(v0, (f32x4*)(out + off)); __builtin_nontemporal_store(v1, (f32x4*)(out + off + 4)); }
;                     else { q += sq4(v0) + sq4(v1); *(u32x4*)(xb + off) = pack8(v0, v1); }
;                 }
;                 if (!last) { q += shx(q, 16); q += shx(q, 32); if (fq == 0) ss[(size_t)row * 16 + u.pn * 4 + wc] = q; }
;             }
.LBB0_1519:
	s_or_b64 exec, exec, s[52:53]
	s_waitcnt vmcnt(7)
	v_lshlrev_b32_e32 v32, 16, v76
	s_waitcnt lgkmcnt(0)
	v_and_b32_e32 v33, 0xffff0000, v76
	v_lshlrev_b32_e32 v34, 16, v77
	v_and_b32_e32 v35, 0xffff0000, v77
	v_lshlrev_b32_e32 v36, 16, v78
	v_and_b32_e32 v37, 0xffff0000, v78
	v_lshlrev_b32_e32 v38, 16, v79
	v_and_b32_e32 v39, 0xffff0000, v79
	v_pk_add_f32 v[30:31], v[30:31], v[34:35]
	v_pk_add_f32 v[28:29], v[28:29], v[32:33]
	v_pk_add_f32 v[32:33], v[26:27], v[38:39]
	v_pk_add_f32 v[26:27], v[24:25], v[36:37]
	v_mul_f32_e32 v24, v29, v29
	v_mul_f32_e32 v25, v31, v31
	v_fmac_f32_e32 v24, v28, v28
	v_fmac_f32_e32 v25, v30, v30
	v_add_f32_e32 v24, v24, v25
	v_mul_f32_e32 v25, v27, v27
	v_mul_f32_e32 v34, v33, v33
	v_fmac_f32_e32 v25, v26, v26
	v_fmac_f32_e32 v34, v32, v32
	v_add_f32_e32 v25, v25, v34
	v_add_f32_e32 v34, v24, v25
	v_cvt_pk_bf16_f32 v24, v28, v29
	v_lshl_add_u64 v[28:29], s[20:21], 0, v[94:95]
	v_cvt_pk_bf16_f32 v25, v30, v31
	v_cvt_pk_bf16_f32 v26, v26, v27
	v_cvt_pk_bf16_f32 v27, v32, v33
	v_lshl_add_u64 v[28:29], v[168:169], 1, v[28:29]
	global_store_dwordx4 v[28:29], v[24:27], off
	s_waitcnt vmcnt(7)
	v_lshlrev_b32_e32 v30, 16, v74
	v_and_b32_e32 v31, 0xffff0000, v74
	v_lshlrev_b32_e32 v24, 16, v72
	v_and_b32_e32 v25, 0xffff0000, v72
	v_lshlrev_b32_e32 v26, 16, v73
	v_and_b32_e32 v27, 0xffff0000, v73
	v_lshlrev_b32_e32 v32, 16, v75
	v_and_b32_e32 v33, 0xffff0000, v75
	v_pk_add_f32 v[22:23], v[22:23], v[26:27]
	v_pk_add_f32 v[20:21], v[20:21], v[24:25]
	v_pk_add_f32 v[24:25], v[18:19], v[32:33]
	v_pk_add_f32 v[18:19], v[16:17], v[30:31]
	v_mul_f32_e32 v16, v21, v21
	v_mul_f32_e32 v17, v23, v23
	v_fmac_f32_e32 v16, v20, v20
	v_fmac_f32_e32 v17, v22, v22
	v_add_f32_e32 v16, v16, v17
	v_mul_f32_e32 v17, v19, v19
	v_mul_f32_e32 v26, v25, v25
	v_fmac_f32_e32 v17, v18, v18
	v_fmac_f32_e32 v26, v24, v24
	v_add_f32_e32 v17, v17, v26
	v_add_f32_e32 v16, v16, v17
	v_add_f32_e32 v26, v34, v16
	v_cvt_pk_bf16_f32 v16, v20, v21
	v_cvt_pk_bf16_f32 v17, v22, v23
	v_cvt_pk_bf16_f32 v18, v18, v19
	v_cvt_pk_bf16_f32 v19, v24, v25
	global_store_dwordx4 v[28:29], v[16:19], off offset:256
	s_nop 1
	v_mov_b32_e32 v16, v201
	v_mov_b32_e32 v17, v201
	v_lshlrev_b32_e32 v16, 2, v16
	v_xor_b32_e32 v16, 64, v16
	v_mov_b32_e32 v16, v26
	s_nop 1
	v_permlane16_swap_b32_e32 v16, v26
	s_waitcnt lgkmcnt(0)
	v_add_f32_e32 v16, v26, v16
	v_lshlrev_b32_e32 v17, 2, v17
	v_xor_b32_e32 v17, 0x80, v17
	v_mov_b32_e32 v17, v16
	s_nop 1
	v_permlane32_swap_b32_e32 v17, v16
	s_and_saveexec_b64 s[52:53], s[8:9]
	s_cbranch_execz .LBB0_1521
	s_waitcnt lgkmcnt(0)
	v_add_f32_e32 v18, v16, v17
	v_lshlrev_b64 v[16:17], 6, v[92:93]
	v_lshl_add_u64 v[16:17], s[22:23], 0, v[16:17]
	v_lshl_add_u64 v[16:17], s[50:51], 2, v[16:17]
	s_lshl_b32 s16, s58, 2
	v_lshl_add_u64 v[16:17], v[16:17], 0, s[16:17]
	global_store_dword v[16:17], v18, off
.LBB0_1521:
	s_or_b64 exec, exec, s[52:53]
	s_waitcnt vmcnt(7)
	v_lshlrev_b32_e32 v16, 16, v68
	s_waitcnt lgkmcnt(0)
	v_and_b32_e32 v17, 0xffff0000, v68
	v_lshlrev_b32_e32 v18, 16, v69
	v_and_b32_e32 v19, 0xffff0000, v69
	v_lshlrev_b32_e32 v20, 16, v70
	v_and_b32_e32 v21, 0xffff0000, v70
	v_lshlrev_b32_e32 v22, 16, v71
	v_and_b32_e32 v23, 0xffff0000, v71
	v_pk_add_f32 v[14:15], v[14:15], v[18:19]
	v_pk_add_f32 v[12:13], v[12:13], v[16:17]
	v_pk_add_f32 v[16:17], v[10:11], v[22:23]
	v_pk_add_f32 v[10:11], v[8:9], v[20:21]
	v_mul_f32_e32 v8, v13, v13
	v_mul_f32_e32 v9, v15, v15
	v_fmac_f32_e32 v8, v12, v12
	v_fmac_f32_e32 v9, v14, v14
	v_add_f32_e32 v8, v8, v9
	v_mul_f32_e32 v9, v11, v11
	v_mul_f32_e32 v18, v17, v17
	v_fmac_f32_e32 v9, v10, v10
	v_fmac_f32_e32 v18, v16, v16
	v_add_f32_e32 v9, v9, v18
	v_add_f32_e32 v18, v8, v9
	v_cvt_pk_bf16_f32 v8, v12, v13
	v_lshl_add_u64 v[12:13], s[20:21], 0, v[90:91]
	v_cvt_pk_bf16_f32 v9, v14, v15
	v_cvt_pk_bf16_f32 v10, v10, v11
	v_cvt_pk_bf16_f32 v11, v16, v17
	v_lshl_add_u64 v[12:13], v[168:169], 1, v[12:13]
	global_store_dwordx4 v[12:13], v[8:11], off
	s_waitcnt vmcnt(7)
	v_lshlrev_b32_e32 v14, 16, v66
	v_and_b32_e32 v15, 0xffff0000, v66
	v_lshlrev_b32_e32 v8, 16, v64
	v_and_b32_e32 v9, 0xffff0000, v64
	v_lshlrev_b32_e32 v10, 16, v65
	v_and_b32_e32 v11, 0xffff0000, v65
	v_lshlrev_b32_e32 v16, 16, v67
	v_and_b32_e32 v17, 0xffff0000, v67
	v_pk_add_f32 v[6:7], v[6:7], v[10:11]
	v_pk_add_f32 v[4:5], v[4:5], v[8:9]
	v_pk_add_f32 v[8:9], v[2:3], v[16:17]
	v_pk_add_f32 v[2:3], v[0:1], v[14:15]
	v_mul_f32_e32 v0, v5, v5
	v_mul_f32_e32 v1, v7, v7
	v_fmac_f32_e32 v0, v4, v4
	v_fmac_f32_e32 v1, v6, v6
	v_add_f32_e32 v0, v0, v1
	v_mul_f32_e32 v1, v3, v3
	v_mul_f32_e32 v10, v9, v9
	v_fmac_f32_e32 v1, v2, v2
	v_fmac_f32_e32 v10, v8, v8
	v_add_f32_e32 v1, v1, v10
	v_add_f32_e32 v0, v0, v1
	v_add_f32_e32 v10, v18, v0
	v_cvt_pk_bf16_f32 v0, v4, v5
	v_cvt_pk_bf16_f32 v1, v6, v7
	v_cvt_pk_bf16_f32 v2, v2, v3
	v_cvt_pk_bf16_f32 v3, v8, v9
	global_store_dwordx4 v[12:13], v[0:3], off offset:256
	s_nop 1
	v_mov_b32_e32 v0, v201
	v_mov_b32_e32 v1, v201
	v_lshlrev_b32_e32 v0, 2, v0
	v_xor_b32_e32 v0, 64, v0
	v_mov_b32_e32 v0, v10
	s_nop 1
	v_permlane16_swap_b32_e32 v0, v10
	s_waitcnt lgkmcnt(0)
	v_add_f32_e32 v0, v10, v0
	v_lshlrev_b32_e32 v1, 2, v1
	v_xor_b32_e32 v1, 0x80, v1
	v_mov_b32_e32 v1, v0
	s_nop 1
	v_permlane32_swap_b32_e32 v1, v0
	s_and_saveexec_b64 s[52:53], s[8:9]
	s_cbranch_execz .LBB0_1523
	s_waitcnt lgkmcnt(0)
	v_add_f32_e32 v2, v0, v1
	v_lshlrev_b64 v[0:1], 6, v[88:89]
	v_lshl_add_u64 v[0:1], s[22:23], 0, v[0:1]
	v_lshl_add_u64 v[0:1], s[50:51], 2, v[0:1]
	s_lshl_b32 s16, s58, 2
	v_lshl_add_u64 v[0:1], v[0:1], 0, s[16:17]
	global_store_dword v[0:1], v2, off

; __device__ __forceinline__ float row_part(const float* ss, int row, int fq) { const f32x4 a = ((const f32x4*)(ss + (size_t)row * 16))[fq]; return (a[0] + a[1]) + (a[2] + a[3]); }
; __device__ __forceinline__ float row_finish(float t) { t += shx(t, 16); t += shx(t, 32); return __builtin_amdgcn_rsqf(t * (1.0f / 1024.0f) + RMS_EPS); }
;     __device__ __forceinline__ void operator()(const f32x4 (&acc)[2][2][4][2], const Unit& u, int wr, int wc, int fr, int fq) const {
;         const int col0 = u.pn * 128 + 32 * wc + 8 * fq;
;         float rs[2][4];
; #pragma unroll
;         for (int ai = 0; ai < 2; ++ai)
; #pragma unroll
;             for (int m = 0; m < 4; ++m) rs[ai][m] = row_part(ss, u.pm * BM + ai * HALF + wr * 64 + m * 16 + fr, fq);
; #pragma unroll
;         for (int ai = 0; ai < 2; ++ai)
; #pragma unroll
;             for (int m = 0; m < 4; ++m) rs[ai][m] = row_finish(rs[ai][m]);
.LBB0_1591:
	v_lshl_add_u32 v170, s44, 8, v153
	v_ashrrev_i32_e32 v171, 31, v170
	v_or_b32_e32 v166, 16, v170
	v_lshlrev_b64 v[146:147], 6, v[170:171]
	v_ashrrev_i32_e32 v167, 31, v166
	v_lshl_add_u64 v[146:147], v[136:137], 0, v[146:147]
	v_lshlrev_b64 v[148:149], 6, v[166:167]
	v_lshl_add_u64 v[148:149], v[136:137], 0, v[148:149]
	ds_read_b128 v[176:179], v239
	ds_read_b128 v[180:183], v239 offset:1024
	v_or_b32_e32 v162, 32, v170
	v_ashrrev_i32_e32 v163, 31, v162
	v_or_b32_e32 v158, 48, v170
	v_lshlrev_b64 v[146:147], 6, v[162:163]
	v_ashrrev_i32_e32 v159, 31, v158
	v_lshl_add_u64 v[146:147], v[136:137], 0, v[146:147]
	v_lshlrev_b64 v[148:149], 6, v[158:159]
	v_lshl_add_u64 v[148:149], v[136:137], 0, v[148:149]
	ds_read_b128 v[184:187], v239 offset:2048
	ds_read_b128 v[188:191], v239 offset:3072
	v_add_u32_e32 v154, 0x80, v170
	v_ashrrev_i32_e32 v155, 31, v154
	v_add_u32_e32 v150, 0x90, v170
	v_lshlrev_b64 v[146:147], 6, v[154:155]
	v_ashrrev_i32_e32 v151, 31, v150
	v_lshl_add_u64 v[146:147], v[136:137], 0, v[146:147]
	v_lshlrev_b64 v[148:149], 6, v[150:151]
	v_lshl_add_u64 v[148:149], v[136:137], 0, v[148:149]
	ds_read_b128 v[192:195], v239 offset:8192
	ds_read_b128 v[196:199], v239 offset:9216
	v_add_u32_e32 v148, 0xa0, v170
	v_ashrrev_i32_e32 v149, 31, v148
	v_lshlrev_b64 v[146:147], 6, v[148:149]
	v_lshl_add_u64 v[146:147], v[136:137], 0, v[146:147]
	ds_read_b128 v[202:205], v239 offset:10240
	v_add_u32_e32 v146, 0xb0, v170
	v_ashrrev_i32_e32 v147, 31, v146
	v_lshlrev_b64 v[206:207], 6, v[146:147]
	v_lshl_add_u64 v[206:207], v[136:137], 0, v[206:207]
	ds_read_b128 v[206:209], v239 offset:11264
	v_mov_b32_e32 v147, v201
	v_mov_b32_e32 v149, v201
	v_lshlrev_b32_e32 v147, 2, v147
	v_mov_b32_e32 v151, v201
	v_xor_b32_e32 v147, 64, v147
	s_andn2_b64 vcc, exec, s[8:9]
	v_lshlrev_b32_e32 v151, 2, v151
	v_xor_b32_e32 v151, 64, v151
	v_lshlrev_b32_e32 v149, 2, v149
	v_xor_b32_e32 v149, 0x80, v149
	s_mov_b64 s[8:9], -1
	s_waitcnt lgkmcnt(0)
	v_mov_b32_e32 v210, v177
	v_mov_b32_e32 v211, v178
	v_mov_b32_e32 v177, v179
	v_pk_add_f32 v[176:177], v[210:211], v[176:177]
	v_mov_b32_e32 v178, v181
	v_add_f32_e32 v152, v176, v177
	v_mov_b32_e32 v179, v182
	v_mov_b32_e32 v181, v183
	v_mov_b32_e32 v147, v152
	s_nop 1
	v_permlane16_swap_b32_e32 v147, v152
	v_pk_add_f32 v[176:177], v[178:179], v[180:181]
	v_mov_b32_e32 v182, v185
	v_add_f32_e32 v155, v176, v177
	v_mov_b32_e32 v151, v155
	s_nop 1
	v_permlane16_swap_b32_e32 v151, v155
	s_waitcnt lgkmcnt(0)
	v_add_f32_e32 v147, v152, v147
	v_mov_b32_e32 v152, v201
	v_mov_b32_e32 v149, v147
	s_nop 1
	v_permlane32_swap_b32_e32 v149, v147
	s_waitcnt lgkmcnt(0)
	v_add_f32_e32 v151, v155, v151
	v_lshlrev_b32_e32 v152, 2, v152
	v_xor_b32_e32 v152, 0x80, v152
	v_mov_b32_e32 v152, v151
	s_nop 1
	v_permlane32_swap_b32_e32 v152, v151
	s_waitcnt lgkmcnt(0)
	v_add_f32_e32 v147, v147, v149
	v_mov_b32_e32 v149, v201
	v_mov_b32_e32 v183, v186
	v_mov_b32_e32 v185, v187
	v_pk_add_f32 v[178:179], v[182:183], v[184:185]
	v_fmamk_f32 v147, v147, 0x3a800000, v175
	v_lshlrev_b32_e32 v149, 2, v149
	v_add_f32_e32 v156, v178, v179
	v_rsq_f32_e32 v176, v147
	s_waitcnt lgkmcnt(0)
	v_add_f32_e32 v147, v151, v152
	v_xor_b32_e32 v149, 64, v149
	v_mov_b32_e32 v151, v201
	v_mov_b32_e32 v152, v201
	v_mov_b32_e32 v186, v189
	v_mov_b32_e32 v187, v190
	v_mov_b32_e32 v189, v191
	v_mov_b32_e32 v149, v156
	s_nop 1
	v_permlane16_swap_b32_e32 v149, v156
	v_pk_add_f32 v[180:181], v[186:187], v[188:189]
	v_lshlrev_b32_e32 v152, 2, v152
	v_add_f32_e32 v159, v180, v181
	v_xor_b32_e32 v152, 64, v152
	v_mov_b32_e32 v152, v159
	s_nop 1
	v_permlane16_swap_b32_e32 v152, v159
	s_waitcnt lgkmcnt(0)
	v_add_f32_e32 v149, v156, v149
	v_lshlrev_b32_e32 v151, 2, v151
	v_mov_b32_e32 v156, v201
	v_xor_b32_e32 v151, 0x80, v151
	v_mov_b32_e32 v151, v149
	s_nop 1
	v_permlane32_swap_b32_e32 v151, v149
	v_lshlrev_b32_e32 v156, 2, v156
	s_waitcnt lgkmcnt(0)
	v_add_f32_e32 v152, v159, v152
	v_xor_b32_e32 v156, 0x80, v156
	v_mov_b32_e32 v156, v152
	s_nop 1
	v_permlane32_swap_b32_e32 v156, v152
	v_fmamk_f32 v147, v147, 0x3a800000, v175
	v_rsq_f32_e32 v174, v147
	s_waitcnt lgkmcnt(0)
	v_add_f32_e32 v147, v149, v151
	v_mov_b32_e32 v149, v201
	v_mov_b32_e32 v190, v193
	v_mov_b32_e32 v191, v194
	v_mov_b32_e32 v193, v195
	v_fmamk_f32 v147, v147, 0x3a800000, v175
	v_pk_add_f32 v[182:183], v[190:191], v[192:193]
	v_rsq_f32_e32 v172, v147
	s_waitcnt lgkmcnt(0)
	v_add_f32_e32 v147, v152, v156
	v_lshlrev_b32_e32 v149, 2, v149
	v_mov_b32_e32 v151, v201
	v_mov_b32_e32 v152, v201
	v_mov_b32_e32 v194, v197
	v_mov_b32_e32 v195, v198
	v_mov_b32_e32 v197, v199
	v_add_f32_e32 v160, v182, v183
	v_xor_b32_e32 v149, 64, v149
	v_pk_add_f32 v[184:185], v[194:195], v[196:197]
	v_mov_b32_e32 v149, v160
	s_nop 1
	v_permlane16_swap_b32_e32 v149, v160
	v_lshlrev_b32_e32 v152, 2, v152
	v_add_f32_e32 v163, v184, v185
	v_xor_b32_e32 v152, 64, v152
	v_mov_b32_e32 v152, v163
	s_nop 1
	v_permlane16_swap_b32_e32 v152, v163
	v_lshlrev_b32_e32 v151, 2, v151
	v_mov_b32_e32 v156, v201
	s_waitcnt lgkmcnt(0)
	v_add_f32_e32 v149, v160, v149
	v_xor_b32_e32 v151, 0x80, v151
	v_mov_b32_e32 v151, v149
	s_nop 1
	v_permlane32_swap_b32_e32 v151, v149
	v_lshlrev_b32_e32 v156, 2, v156
	s_waitcnt lgkmcnt(0)
	v_add_f32_e32 v152, v163, v152
	v_xor_b32_e32 v156, 0x80, v156
	v_mov_b32_e32 v156, v152
	s_nop 1
	v_permlane32_swap_b32_e32 v156, v152
	v_fmamk_f32 v147, v147, 0x3a800000, v175
	v_rsq_f32_e32 v168, v147
	s_waitcnt lgkmcnt(0)
	v_add_f32_e32 v147, v149, v151
	v_fmamk_f32 v147, v147, 0x3a800000, v175
	v_rsq_f32_e32 v164, v147
	s_waitcnt lgkmcnt(0)
; __device__ __forceinline__ u32x4 pack8(f32x4 a, f32x4 b) { u32x4 w; w.x = cvt_pk_bf16(a[0], a[1]); w.y = cvt_pk_bf16(a[2], a[3]); w.z = cvt_pk_bf16(b[0], b[1]); w.w = cvt_pk_bf16(b[2], b[3]); return w; }
; __device__ __forceinline__ float row_finish(float t) { t += shx(t, 16); t += shx(t, 32); return __builtin_amdgcn_rsqf(t * (1.0f / 1024.0f) + RMS_EPS); }
; __device__ __forceinline__ float silu_f(float v) { return v * __builtin_amdgcn_rcpf(1.0f + __builtin_amdgcn_exp2f(v * -1.4426950408889634f)); }
; __device__ __forceinline__ f32x4 silu4(f32x4 v) { return (f32x4){silu_f(v[0]), silu_f(v[1]), silu_f(v[2]), silu_f(v[3])}; }
;     __device__ __forceinline__ void operator()(const f32x4 (&acc)[2][2][4][2], const Unit& u, int wr, int wc, int fr, int fq) const {
;     ...
;         for (int ai = 0; ai < 2; ++ai)
; #pragma unroll
;             for (int m = 0; m < 4; ++m) rs[ai][m] = row_finish(rs[ai][m]);
; #pragma unroll
;         for (int ai = 0; ai < 2; ++ai)
; #pragma unroll
;             for (int m = 0; m < 4; ++m) {
;                 const int row = u.pm * BM + ai * HALF + wr * 64 + m * 16 + fr;
;                 const float rstd = rs[ai][m];
;                 const f32x4 a0 = silu4(acc[ai][0][m][0] * rstd) * (acc[ai][1][m][0] * rstd);
;                 const f32x4 a1 = silu4(acc[ai][0][m][1] * rstd) * (acc[ai][1][m][1] * rstd);
;                 *(u32x4*)(ACT + (size_t)row * 2816 + col0) = pack8(a0, a1);
;             }
	v_add_f32_e32 v147, v152, v156
	v_mov_b32_e32 v149, v201
	v_mov_b32_e32 v151, v201
	v_mov_b32_e32 v152, v201
	v_mov_b32_e32 v198, v203
	v_mov_b32_e32 v199, v204
	v_mov_b32_e32 v203, v205
	v_mov_b32_e32 v204, v207
	v_mov_b32_e32 v205, v208
	v_mov_b32_e32 v207, v209
	v_pk_add_f32 v[188:189], v[204:205], v[206:207]
	v_lshlrev_b32_e32 v152, 2, v152
	v_pk_add_f32 v[186:187], v[198:199], v[202:203]
	v_add_f32_e32 v155, v188, v189
	v_lshlrev_b32_e32 v149, 2, v149
	v_xor_b32_e32 v152, 64, v152
	v_add_f32_e32 v167, v186, v187
	v_xor_b32_e32 v149, 64, v149
	v_mov_b32_e32 v152, v155
	s_nop 1
	v_permlane16_swap_b32_e32 v152, v155
	v_mov_b32_e32 v149, v167
	s_nop 1
	v_permlane16_swap_b32_e32 v149, v167
	v_lshlrev_b32_e32 v151, 2, v151
	v_xor_b32_e32 v151, 0x80, v151
	v_fmamk_f32 v147, v147, 0x3a800000, v175
	s_waitcnt lgkmcnt(0)
	v_add_f32_e32 v152, v155, v152
	v_mov_b32_e32 v155, v201
	s_waitcnt lgkmcnt(0)
	v_add_f32_e32 v149, v167, v149
	v_mov_b32_e32 v151, v149
	s_nop 1
	v_permlane32_swap_b32_e32 v151, v149
	v_lshlrev_b32_e32 v155, 2, v155
	v_xor_b32_e32 v155, 0x80, v155
	v_mov_b32_e32 v155, v152
	s_nop 1
	v_permlane32_swap_b32_e32 v155, v152
	v_rsq_f32_e32 v160, v147
	s_waitcnt lgkmcnt(0)
	v_add_f32_e32 v147, v149, v151
	v_fmamk_f32 v147, v147, 0x3a800000, v175
	v_rsq_f32_e32 v156, v147
	s_waitcnt lgkmcnt(0)
	v_add_f32_e32 v147, v152, v155
	v_fmamk_f32 v147, v147, 0x3a800000, v175
	v_pk_mul_f32 v[124:125], v[124:125], v[176:177] op_sel_hi:[1,0]
	v_rsq_f32_e32 v152, v147
	v_mul_f32_e32 v147, 0xbfb8aa3b, v124
	v_exp_f32_e32 v147, v147
	v_mul_f32_e32 v149, 0xbfb8aa3b, v125
	v_exp_f32_e32 v149, v149
	v_pk_mul_f32 v[126:127], v[126:127], v[176:177] op_sel_hi:[1,0]
	v_add_f32_e32 v147, 1.0, v147
	v_rcp_f32_e32 v178, v147
	v_add_f32_e32 v147, 1.0, v149
	v_mul_f32_e32 v149, 0xbfb8aa3b, v126
	v_exp_f32_e32 v149, v149
	v_mul_f32_e32 v151, 0xbfb8aa3b, v127
	v_exp_f32_e32 v151, v151
	v_rcp_f32_e32 v179, v147
	v_add_f32_e32 v147, 1.0, v149
	v_rcp_f32_e32 v180, v147
	v_add_f32_e32 v147, 1.0, v151
	v_pk_mul_f32 v[120:121], v[120:121], v[176:177] op_sel_hi:[1,0]
	v_rcp_f32_e32 v181, v147
	v_mul_f32_e32 v147, 0xbfb8aa3b, v120
	v_exp_f32_e32 v147, v147
	v_mul_f32_e32 v149, 0xbfb8aa3b, v121
	v_exp_f32_e32 v149, v149
	v_pk_mul_f32 v[122:123], v[122:123], v[176:177] op_sel_hi:[1,0]
	v_add_f32_e32 v147, 1.0, v147
	v_pk_mul_f32 v[124:125], v[124:125], v[178:179]
	v_rcp_f32_e32 v178, v147
	v_add_f32_e32 v147, 1.0, v149
	v_mul_f32_e32 v149, 0xbfb8aa3b, v122
	v_exp_f32_e32 v149, v149
	v_mul_f32_e32 v151, 0xbfb8aa3b, v123
	v_exp_f32_e32 v151, v151
	v_rcp_f32_e32 v179, v147
	v_add_f32_e32 v147, 1.0, v149
	v_pk_mul_f32 v[126:127], v[126:127], v[180:181]
	v_rcp_f32_e32 v180, v147
	v_add_f32_e32 v147, 1.0, v151
	v_rcp_f32_e32 v181, v147
	v_pk_mul_f32 v[116:117], v[116:117], v[176:177] op_sel_hi:[1,0]
	v_pk_mul_f32 v[118:119], v[118:119], v[176:177] op_sel_hi:[1,0]
	v_pk_mul_f32 v[120:121], v[120:121], v[178:179]
	v_pk_mul_f32 v[112:113], v[112:113], v[176:177] op_sel_hi:[1,0]
	v_lshl_or_b32 v182, s61, 7, v161
	v_pk_mul_f32 v[118:119], v[118:119], v[126:127]
	v_pk_mul_f32 v[116:117], v[116:117], v[124:125]
	v_pk_mul_f32 v[122:123], v[122:123], v[180:181]
	v_pk_mul_f32 v[114:115], v[114:115], v[176:177] op_sel_hi:[1,0]
	v_pk_mul_f32 v[112:113], v[112:113], v[120:121]
	v_ashrrev_i32_e32 v183, 31, v182
	v_pk_mul_f32 v[114:115], v[114:115], v[122:123]
	v_cvt_pk_bf16_f32 v116, v116, v117
	v_cvt_pk_bf16_f32 v117, v118, v119
	v_cvt_pk_bf16_f32 v118, v112, v113
	v_mov_b64_e32 v[112:113], s[16:17]
	v_cvt_pk_bf16_f32 v119, v114, v115
	v_mad_i64_i32 v[120:121], s[46:47], v170, s60, v[112:113]
	v_lshlrev_b64 v[114:115], 1, v[182:183]
	v_pk_mul_f32 v[108:109], v[108:109], v[174:175] op_sel_hi:[1,0]
	v_pk_mul_f32 v[110:111], v[110:111], v[174:175] op_sel_hi:[1,0]
	v_mul_f32_e32 v122, 0xbfb8aa3b, v108
	v_mul_f32_e32 v123, 0xbfb8aa3b, v109
	v_lshl_add_u64 v[120:121], v[120:121], 0, v[114:115]
	v_pk_mul_f32 v[104:105], v[104:105], v[174:175] op_sel_hi:[1,0]
	v_pk_mul_f32 v[106:107], v[106:107], v[174:175] op_sel_hi:[1,0]
	v_exp_f32_e32 v122, v122
	v_exp_f32_e32 v123, v123
	v_mul_f32_e32 v124, 0xbfb8aa3b, v110
	v_mul_f32_e32 v125, 0xbfb8aa3b, v111
	global_store_dwordx4 v[120:121], v[116:119], off
	v_exp_f32_e32 v124, v124
	v_exp_f32_e32 v125, v125
	v_mul_f32_e32 v116, 0xbfb8aa3b, v104
	v_mul_f32_e32 v117, 0xbfb8aa3b, v105
	v_mul_f32_e32 v118, 0xbfb8aa3b, v106
	v_mul_f32_e32 v119, 0xbfb8aa3b, v107
	v_exp_f32_e32 v116, v116
	v_exp_f32_e32 v117, v117
	v_exp_f32_e32 v118, v118
	v_exp_f32_e32 v119, v119
	v_add_f32_e32 v122, 1.0, v122
	v_add_f32_e32 v123, 1.0, v123
	v_rcp_f32_e32 v122, v122
	v_rcp_f32_e32 v123, v123
	v_add_f32_e32 v124, 1.0, v124
	v_add_f32_e32 v125, 1.0, v125
	v_add_f32_e32 v116, 1.0, v116
	v_add_f32_e32 v117, 1.0, v117
	v_add_f32_e32 v118, 1.0, v118
	v_add_f32_e32 v119, 1.0, v119
	v_rcp_f32_e32 v124, v124
	v_rcp_f32_e32 v125, v125
	v_rcp_f32_e32 v116, v116
	v_rcp_f32_e32 v117, v117
	v_rcp_f32_e32 v118, v118
	v_rcp_f32_e32 v119, v119
	v_pk_mul_f32 v[108:109], v[108:109], v[122:123]
	v_pk_mul_f32 v[100:101], v[100:101], v[174:175] op_sel_hi:[1,0]
	v_pk_mul_f32 v[110:111], v[110:111], v[124:125]
	v_pk_mul_f32 v[102:103], v[102:103], v[174:175] op_sel_hi:[1,0]
	v_pk_mul_f32 v[100:101], v[100:101], v[108:109]
	v_pk_mul_f32 v[104:105], v[104:105], v[116:117]
	v_pk_mul_f32 v[106:107], v[106:107], v[118:119]
	v_pk_mul_f32 v[96:97], v[96:97], v[174:175] op_sel_hi:[1,0]
	v_pk_mul_f32 v[98:99], v[98:99], v[174:175] op_sel_hi:[1,0]
	v_pk_mul_f32 v[102:103], v[102:103], v[110:111]
	v_pk_mul_f32 v[106:107], v[98:99], v[106:107]
	v_pk_mul_f32 v[98:99], v[96:97], v[104:105]
	v_cvt_pk_bf16_f32 v96, v100, v101
; __device__ __forceinline__ u32x4 pack8(f32x4 a, f32x4 b) { u32x4 w; w.x = cvt_pk_bf16(a[0], a[1]); w.y = cvt_pk_bf16(a[2], a[3]); w.z = cvt_pk_bf16(b[0], b[1]); w.w = cvt_pk_bf16(b[2], b[3]); return w; }
; __device__ __forceinline__ float silu_f(float v) { return v * __builtin_amdgcn_rcpf(1.0f + __builtin_amdgcn_exp2f(v * -1.4426950408889634f)); }
; __device__ __forceinline__ f32x4 silu4(f32x4 v) { return (f32x4){silu_f(v[0]), silu_f(v[1]), silu_f(v[2]), silu_f(v[3])}; }
;     __device__ __forceinline__ void operator()(const f32x4 (&acc)[2][2][4][2], const Unit& u, int wr, int wc, int fr, int fq) const {
;     ...
;         for (int ai = 0; ai < 2; ++ai)
; #pragma unroll
;             for (int m = 0; m < 4; ++m) {
;                 const int row = u.pm * BM + ai * HALF + wr * 64 + m * 16 + fr;
;                 const float rstd = rs[ai][m];
;                 const f32x4 a0 = silu4(acc[ai][0][m][0] * rstd) * (acc[ai][1][m][0] * rstd);
;                 const f32x4 a1 = silu4(acc[ai][0][m][1] * rstd) * (acc[ai][1][m][1] * rstd);
;                 *(u32x4*)(ACT + (size_t)row * 2816 + col0) = pack8(a0, a1);
;             }
	v_mad_i64_i32 v[100:101], s[46:47], v166, s60, v[112:113]
	v_pk_mul_f32 v[92:93], v[92:93], v[172:173] op_sel_hi:[1,0]
	v_cvt_pk_bf16_f32 v97, v102, v103
	v_cvt_pk_bf16_f32 v98, v98, v99
	v_cvt_pk_bf16_f32 v99, v106, v107
	v_pk_mul_f32 v[94:95], v[94:95], v[172:173] op_sel_hi:[1,0]
	v_mul_f32_e32 v102, 0xbfb8aa3b, v92
	v_mul_f32_e32 v103, 0xbfb8aa3b, v93
	v_lshl_add_u64 v[100:101], v[100:101], 0, v[114:115]
	v_pk_mul_f32 v[88:89], v[88:89], v[172:173] op_sel_hi:[1,0]
	v_pk_mul_f32 v[90:91], v[90:91], v[172:173] op_sel_hi:[1,0]
	v_exp_f32_e32 v102, v102
	v_exp_f32_e32 v103, v103
	v_mul_f32_e32 v104, 0xbfb8aa3b, v94
	v_mul_f32_e32 v105, 0xbfb8aa3b, v95
	global_store_dwordx4 v[100:101], v[96:99], off
	v_exp_f32_e32 v104, v104
	v_exp_f32_e32 v105, v105
	v_mul_f32_e32 v96, 0xbfb8aa3b, v88
	v_mul_f32_e32 v97, 0xbfb8aa3b, v89
	v_mul_f32_e32 v98, 0xbfb8aa3b, v90
	v_mul_f32_e32 v99, 0xbfb8aa3b, v91
	v_exp_f32_e32 v96, v96
	v_exp_f32_e32 v97, v97
	v_exp_f32_e32 v98, v98
	v_exp_f32_e32 v99, v99
	v_add_f32_e32 v102, 1.0, v102
	v_add_f32_e32 v103, 1.0, v103
	v_rcp_f32_e32 v102, v102
	v_rcp_f32_e32 v103, v103
	v_add_f32_e32 v104, 1.0, v104
	v_add_f32_e32 v105, 1.0, v105
	v_add_f32_e32 v96, 1.0, v96
	v_add_f32_e32 v97, 1.0, v97
	v_add_f32_e32 v98, 1.0, v98
	v_add_f32_e32 v99, 1.0, v99
	v_rcp_f32_e32 v104, v104
	v_rcp_f32_e32 v105, v105
	v_rcp_f32_e32 v96, v96
	v_rcp_f32_e32 v97, v97
	v_rcp_f32_e32 v98, v98
	v_rcp_f32_e32 v99, v99
	v_pk_mul_f32 v[92:93], v[92:93], v[102:103]
	v_pk_mul_f32 v[84:85], v[84:85], v[172:173] op_sel_hi:[1,0]
	v_pk_mul_f32 v[94:95], v[94:95], v[104:105]
	v_pk_mul_f32 v[86:87], v[86:87], v[172:173] op_sel_hi:[1,0]
	v_pk_mul_f32 v[84:85], v[84:85], v[92:93]
	v_pk_mul_f32 v[88:89], v[88:89], v[96:97]
	v_pk_mul_f32 v[90:91], v[90:91], v[98:99]
	v_pk_mul_f32 v[80:81], v[80:81], v[172:173] op_sel_hi:[1,0]
	v_pk_mul_f32 v[82:83], v[82:83], v[172:173] op_sel_hi:[1,0]
	v_pk_mul_f32 v[86:87], v[86:87], v[94:95]
	v_pk_mul_f32 v[90:91], v[82:83], v[90:91]
	v_pk_mul_f32 v[82:83], v[80:81], v[88:89]
	v_cvt_pk_bf16_f32 v80, v84, v85
	v_mad_i64_i32 v[84:85], s[46:47], v162, s60, v[112:113]
	v_pk_mul_f32 v[76:77], v[76:77], v[168:169] op_sel_hi:[1,0]
	v_cvt_pk_bf16_f32 v81, v86, v87
	v_cvt_pk_bf16_f32 v82, v82, v83
	v_cvt_pk_bf16_f32 v83, v90, v91
	v_pk_mul_f32 v[78:79], v[78:79], v[168:169] op_sel_hi:[1,0]
	v_mul_f32_e32 v86, 0xbfb8aa3b, v76
	v_mul_f32_e32 v87, 0xbfb8aa3b, v77
	v_lshl_add_u64 v[84:85], v[84:85], 0, v[114:115]
	v_pk_mul_f32 v[72:73], v[72:73], v[168:169] op_sel_hi:[1,0]
	v_pk_mul_f32 v[74:75], v[74:75], v[168:169] op_sel_hi:[1,0]
	v_exp_f32_e32 v86, v86
	v_exp_f32_e32 v87, v87
	v_mul_f32_e32 v88, 0xbfb8aa3b, v78
	v_mul_f32_e32 v89, 0xbfb8aa3b, v79
	global_store_dwordx4 v[84:85], v[80:83], off
	v_exp_f32_e32 v88, v88
	v_exp_f32_e32 v89, v89
	v_mul_f32_e32 v80, 0xbfb8aa3b, v72
	v_mul_f32_e32 v81, 0xbfb8aa3b, v73
	v_mul_f32_e32 v82, 0xbfb8aa3b, v74
	v_mul_f32_e32 v83, 0xbfb8aa3b, v75
	v_exp_f32_e32 v80, v80
	v_exp_f32_e32 v81, v81
	v_exp_f32_e32 v82, v82
	v_exp_f32_e32 v83, v83
	v_add_f32_e32 v86, 1.0, v86
	v_add_f32_e32 v87, 1.0, v87
	v_rcp_f32_e32 v86, v86
	v_rcp_f32_e32 v87, v87
	v_add_f32_e32 v88, 1.0, v88
	v_add_f32_e32 v89, 1.0, v89
	v_add_f32_e32 v80, 1.0, v80
	v_add_f32_e32 v81, 1.0, v81
	v_add_f32_e32 v82, 1.0, v82
	v_add_f32_e32 v83, 1.0, v83
	v_rcp_f32_e32 v88, v88
	v_rcp_f32_e32 v89, v89
	v_rcp_f32_e32 v80, v80
	v_rcp_f32_e32 v81, v81
	v_rcp_f32_e32 v82, v82
	v_rcp_f32_e32 v83, v83
	v_pk_mul_f32 v[76:77], v[76:77], v[86:87]
	v_pk_mul_f32 v[68:69], v[68:69], v[168:169] op_sel_hi:[1,0]
	v_pk_mul_f32 v[78:79], v[78:79], v[88:89]
	v_pk_mul_f32 v[70:71], v[70:71], v[168:169] op_sel_hi:[1,0]
	v_pk_mul_f32 v[68:69], v[68:69], v[76:77]
	v_pk_mul_f32 v[72:73], v[72:73], v[80:81]
	v_pk_mul_f32 v[74:75], v[74:75], v[82:83]
	v_pk_mul_f32 v[64:65], v[64:65], v[168:169] op_sel_hi:[1,0]
	v_pk_mul_f32 v[66:67], v[66:67], v[168:169] op_sel_hi:[1,0]
	v_pk_mul_f32 v[70:71], v[70:71], v[78:79]
	v_pk_mul_f32 v[74:75], v[66:67], v[74:75]
	v_pk_mul_f32 v[66:67], v[64:65], v[72:73]
	v_cvt_pk_bf16_f32 v64, v68, v69
	v_mad_i64_i32 v[68:69], s[46:47], v158, s60, v[112:113]
	v_pk_mul_f32 v[60:61], v[60:61], v[164:165] op_sel_hi:[1,0]
	v_cvt_pk_bf16_f32 v65, v70, v71
	v_cvt_pk_bf16_f32 v66, v66, v67
	v_cvt_pk_bf16_f32 v67, v74, v75
	v_pk_mul_f32 v[62:63], v[62:63], v[164:165] op_sel_hi:[1,0]
	v_mul_f32_e32 v70, 0xbfb8aa3b, v60
	v_mul_f32_e32 v71, 0xbfb8aa3b, v61
	v_lshl_add_u64 v[68:69], v[68:69], 0, v[114:115]
	v_pk_mul_f32 v[56:57], v[56:57], v[164:165] op_sel_hi:[1,0]
	v_pk_mul_f32 v[58:59], v[58:59], v[164:165] op_sel_hi:[1,0]
	v_exp_f32_e32 v70, v70
	v_exp_f32_e32 v71, v71
	v_mul_f32_e32 v72, 0xbfb8aa3b, v62
	v_mul_f32_e32 v73, 0xbfb8aa3b, v63
	global_store_dwordx4 v[68:69], v[64:67], off
	v_exp_f32_e32 v72, v72
	v_exp_f32_e32 v73, v73
	v_mul_f32_e32 v64, 0xbfb8aa3b, v56
	v_mul_f32_e32 v65, 0xbfb8aa3b, v57
	v_mul_f32_e32 v66, 0xbfb8aa3b, v58
	v_mul_f32_e32 v67, 0xbfb8aa3b, v59
	v_exp_f32_e32 v64, v64
	v_exp_f32_e32 v65, v65
	v_exp_f32_e32 v66, v66
	v_exp_f32_e32 v67, v67
	v_add_f32_e32 v70, 1.0, v70
	v_add_f32_e32 v71, 1.0, v71
	v_rcp_f32_e32 v70, v70
	v_rcp_f32_e32 v71, v71
	v_add_f32_e32 v72, 1.0, v72
	v_add_f32_e32 v73, 1.0, v73
	v_add_f32_e32 v64, 1.0, v64
	v_add_f32_e32 v65, 1.0, v65
	v_add_f32_e32 v66, 1.0, v66
	v_add_f32_e32 v67, 1.0, v67
	v_rcp_f32_e32 v72, v72
	v_rcp_f32_e32 v73, v73
	v_rcp_f32_e32 v64, v64
	v_rcp_f32_e32 v65, v65
	v_rcp_f32_e32 v66, v66
	v_rcp_f32_e32 v67, v67
	v_pk_mul_f32 v[60:61], v[60:61], v[70:71]
	v_pk_mul_f32 v[52:53], v[52:53], v[164:165] op_sel_hi:[1,0]
	v_pk_mul_f32 v[62:63], v[62:63], v[72:73]
; __device__ __forceinline__ f32x4 silu4(f32x4 v) { return (f32x4){silu_f(v[0]), silu_f(v[1]), silu_f(v[2]), silu_f(v[3])}; }
; __device__ __forceinline__ u32x4 pack8(f32x4 a, f32x4 b) { u32x4 w; w.x = cvt_pk_bf16(a[0], a[1]); w.y = cvt_pk_bf16(a[2], a[3]); w.z = cvt_pk_bf16(b[0], b[1]); w.w = cvt_pk_bf16(b[2], b[3]); return w; }
; #define PG8_BAR __builtin_amdgcn_s_barrier()
;     __device__ __forceinline__ void operator()(const f32x4 (&acc)[2][2][4][2], const Unit& u, int wr, int wc, int fr, int fq) const {
;     ...
;         for (int ai = 0; ai < 2; ++ai)
; #pragma unroll
;             for (int m = 0; m < 4; ++m) {
;                 const int row = u.pm * BM + ai * HALF + wr * 64 + m * 16 + fr;
;                 const float rstd = rs[ai][m];
;                 const f32x4 a0 = silu4(acc[ai][0][m][0] * rstd) * (acc[ai][1][m][0] * rstd);
;                 const f32x4 a1 = silu4(acc[ai][0][m][1] * rstd) * (acc[ai][1][m][1] * rstd);
;                 *(u32x4*)(ACT + (size_t)row * 2816 + col0) = pack8(a0, a1);
;             }
; template <class Epi, class Sched, bool ALIGN_EPI = false, bool SP2 = false>
; __device__ __forceinline__ void gemm_phase(PG8_LAS unsigned char* lds, const Gemm g, const Sched& S, const Epi& E, int tid_in) {
;     ...
;         if (!has_next) break;
; #pragma unroll
;         for (int a = 0; a < 2; ++a)
; #pragma unroll
;             for (int b = 0; b < 2; ++b)
; #pragma unroll
;                 for (int m = 0; m < 4; ++m)
; #pragma unroll
;                     for (int n = 0; n < 2; ++n) acc[a][b][m][n] = (f32x4){0.f, 0.f, 0.f, 0.f};
;         cur = nxt; cA = nA; cB = nB; ++ui;
;         if constexpr (ALIGN_EPI) { if (wr == 1) PG8_BAR; }
;     }
	v_pk_mul_f32 v[54:55], v[54:55], v[164:165] op_sel_hi:[1,0]
	v_pk_mul_f32 v[52:53], v[52:53], v[60:61]
	v_pk_mul_f32 v[56:57], v[56:57], v[64:65]
	v_pk_mul_f32 v[58:59], v[58:59], v[66:67]
	v_pk_mul_f32 v[48:49], v[48:49], v[164:165] op_sel_hi:[1,0]
	v_pk_mul_f32 v[50:51], v[50:51], v[164:165] op_sel_hi:[1,0]
	v_pk_mul_f32 v[54:55], v[54:55], v[62:63]
	v_pk_mul_f32 v[58:59], v[50:51], v[58:59]
	v_pk_mul_f32 v[50:51], v[48:49], v[56:57]
	v_cvt_pk_bf16_f32 v48, v52, v53
	v_mad_i64_i32 v[52:53], s[46:47], v154, s60, v[112:113]
	v_pk_mul_f32 v[44:45], v[44:45], v[160:161] op_sel_hi:[1,0]
	v_cvt_pk_bf16_f32 v49, v54, v55
	v_cvt_pk_bf16_f32 v50, v50, v51
	v_cvt_pk_bf16_f32 v51, v58, v59
	v_pk_mul_f32 v[46:47], v[46:47], v[160:161] op_sel_hi:[1,0]
	v_mul_f32_e32 v54, 0xbfb8aa3b, v44
	v_mul_f32_e32 v55, 0xbfb8aa3b, v45
	v_lshl_add_u64 v[52:53], v[52:53], 0, v[114:115]
	v_pk_mul_f32 v[40:41], v[40:41], v[160:161] op_sel_hi:[1,0]
	v_pk_mul_f32 v[42:43], v[42:43], v[160:161] op_sel_hi:[1,0]
	v_exp_f32_e32 v54, v54
	v_exp_f32_e32 v55, v55
	v_mul_f32_e32 v56, 0xbfb8aa3b, v46
	v_mul_f32_e32 v57, 0xbfb8aa3b, v47
	global_store_dwordx4 v[52:53], v[48:51], off
	v_exp_f32_e32 v56, v56
	v_exp_f32_e32 v57, v57
	v_mul_f32_e32 v48, 0xbfb8aa3b, v40
	v_mul_f32_e32 v49, 0xbfb8aa3b, v41
	v_mul_f32_e32 v50, 0xbfb8aa3b, v42
	v_mul_f32_e32 v51, 0xbfb8aa3b, v43
	v_exp_f32_e32 v48, v48
	v_exp_f32_e32 v49, v49
	v_exp_f32_e32 v50, v50
	v_exp_f32_e32 v51, v51
	v_add_f32_e32 v54, 1.0, v54
	v_add_f32_e32 v55, 1.0, v55
	v_rcp_f32_e32 v54, v54
	v_rcp_f32_e32 v55, v55
	v_add_f32_e32 v56, 1.0, v56
	v_add_f32_e32 v57, 1.0, v57
	v_add_f32_e32 v48, 1.0, v48
	v_add_f32_e32 v49, 1.0, v49
	v_add_f32_e32 v50, 1.0, v50
	v_add_f32_e32 v51, 1.0, v51
	v_rcp_f32_e32 v56, v56
	v_rcp_f32_e32 v57, v57
	v_rcp_f32_e32 v48, v48
	v_rcp_f32_e32 v49, v49
	v_rcp_f32_e32 v50, v50
	v_rcp_f32_e32 v51, v51
	v_pk_mul_f32 v[44:45], v[44:45], v[54:55]
	v_pk_mul_f32 v[36:37], v[36:37], v[160:161] op_sel_hi:[1,0]
	v_pk_mul_f32 v[46:47], v[46:47], v[56:57]
	v_pk_mul_f32 v[38:39], v[38:39], v[160:161] op_sel_hi:[1,0]
	v_pk_mul_f32 v[36:37], v[36:37], v[44:45]
	v_pk_mul_f32 v[40:41], v[40:41], v[48:49]
	v_pk_mul_f32 v[42:43], v[42:43], v[50:51]
	v_pk_mul_f32 v[32:33], v[32:33], v[160:161] op_sel_hi:[1,0]
	v_pk_mul_f32 v[34:35], v[34:35], v[160:161] op_sel_hi:[1,0]
	v_pk_mul_f32 v[38:39], v[38:39], v[46:47]
	v_pk_mul_f32 v[42:43], v[34:35], v[42:43]
	v_pk_mul_f32 v[34:35], v[32:33], v[40:41]
	v_cvt_pk_bf16_f32 v32, v36, v37
	v_mad_i64_i32 v[36:37], s[46:47], v150, s60, v[112:113]
	v_pk_mul_f32 v[28:29], v[28:29], v[156:157] op_sel_hi:[1,0]
	v_cvt_pk_bf16_f32 v33, v38, v39
	v_cvt_pk_bf16_f32 v34, v34, v35
	v_cvt_pk_bf16_f32 v35, v42, v43
	v_pk_mul_f32 v[30:31], v[30:31], v[156:157] op_sel_hi:[1,0]
	v_mul_f32_e32 v38, 0xbfb8aa3b, v28
	v_mul_f32_e32 v39, 0xbfb8aa3b, v29
	v_lshl_add_u64 v[36:37], v[36:37], 0, v[114:115]
	v_pk_mul_f32 v[24:25], v[24:25], v[156:157] op_sel_hi:[1,0]
	v_pk_mul_f32 v[26:27], v[26:27], v[156:157] op_sel_hi:[1,0]
	v_exp_f32_e32 v38, v38
	v_exp_f32_e32 v39, v39
	v_mul_f32_e32 v40, 0xbfb8aa3b, v30
	v_mul_f32_e32 v41, 0xbfb8aa3b, v31
	global_store_dwordx4 v[36:37], v[32:35], off
	v_exp_f32_e32 v40, v40
	v_exp_f32_e32 v41, v41
	v_mul_f32_e32 v32, 0xbfb8aa3b, v24
	v_mul_f32_e32 v33, 0xbfb8aa3b, v25
	v_mul_f32_e32 v34, 0xbfb8aa3b, v26
	v_mul_f32_e32 v35, 0xbfb8aa3b, v27
	v_exp_f32_e32 v32, v32
	v_exp_f32_e32 v33, v33
	v_exp_f32_e32 v34, v34
	v_exp_f32_e32 v35, v35
	v_add_f32_e32 v38, 1.0, v38
	v_add_f32_e32 v39, 1.0, v39
	v_rcp_f32_e32 v38, v38
	v_rcp_f32_e32 v39, v39
	v_add_f32_e32 v40, 1.0, v40
	v_add_f32_e32 v41, 1.0, v41
	v_add_f32_e32 v32, 1.0, v32
	v_add_f32_e32 v33, 1.0, v33
	v_add_f32_e32 v34, 1.0, v34
	v_add_f32_e32 v35, 1.0, v35
	v_rcp_f32_e32 v40, v40
	v_rcp_f32_e32 v41, v41
	v_rcp_f32_e32 v32, v32
	v_rcp_f32_e32 v33, v33
	v_rcp_f32_e32 v34, v34
	v_rcp_f32_e32 v35, v35
	v_pk_mul_f32 v[28:29], v[28:29], v[38:39]
	v_pk_mul_f32 v[20:21], v[20:21], v[156:157] op_sel_hi:[1,0]
	v_pk_mul_f32 v[30:31], v[30:31], v[40:41]
	v_pk_mul_f32 v[22:23], v[22:23], v[156:157] op_sel_hi:[1,0]
	v_pk_mul_f32 v[20:21], v[20:21], v[28:29]
	v_pk_mul_f32 v[24:25], v[24:25], v[32:33]
	v_pk_mul_f32 v[26:27], v[26:27], v[34:35]
	v_pk_mul_f32 v[16:17], v[16:17], v[156:157] op_sel_hi:[1,0]
	v_pk_mul_f32 v[18:19], v[18:19], v[156:157] op_sel_hi:[1,0]
	v_pk_mul_f32 v[22:23], v[22:23], v[30:31]
	v_pk_mul_f32 v[26:27], v[18:19], v[26:27]
	v_pk_mul_f32 v[18:19], v[16:17], v[24:25]
	v_cvt_pk_bf16_f32 v16, v20, v21
	v_mad_i64_i32 v[20:21], s[46:47], v148, s60, v[112:113]
	v_pk_mul_f32 v[12:13], v[12:13], v[152:153] op_sel_hi:[1,0]
	v_cvt_pk_bf16_f32 v17, v22, v23
	v_cvt_pk_bf16_f32 v18, v18, v19
	v_cvt_pk_bf16_f32 v19, v26, v27
	v_lshl_add_u64 v[20:21], v[20:21], 0, v[114:115]
	v_mul_f32_e32 v22, 0xbfb8aa3b, v12
	v_mul_f32_e32 v23, 0xbfb8aa3b, v13
	v_pk_mul_f32 v[8:9], v[8:9], v[152:153] op_sel_hi:[1,0]
	v_pk_mul_f32 v[10:11], v[10:11], v[152:153] op_sel_hi:[1,0]
	v_exp_f32_e32 v22, v22
	v_exp_f32_e32 v23, v23
	global_store_dwordx4 v[20:21], v[16:19], off
	v_pk_mul_f32 v[14:15], v[14:15], v[152:153] op_sel_hi:[1,0]
	v_add_f32_e32 v22, 1.0, v22
	v_mul_f32_e32 v16, 0xbfb8aa3b, v8
	v_mul_f32_e32 v17, 0xbfb8aa3b, v9
	v_mul_f32_e32 v18, 0xbfb8aa3b, v10
	v_mul_f32_e32 v19, 0xbfb8aa3b, v11
	v_exp_f32_e32 v16, v16
	v_exp_f32_e32 v17, v17
	v_exp_f32_e32 v18, v18
	v_exp_f32_e32 v19, v19
	v_mul_f32_e32 v24, 0xbfb8aa3b, v14
	v_mul_f32_e32 v25, 0xbfb8aa3b, v15
	v_exp_f32_e32 v24, v24
	v_exp_f32_e32 v25, v25
	v_add_f32_e32 v23, 1.0, v23
	v_rcp_f32_e32 v22, v22
	v_rcp_f32_e32 v23, v23
	v_add_f32_e32 v16, 1.0, v16
	v_add_f32_e32 v17, 1.0, v17
	v_add_f32_e32 v18, 1.0, v18
	v_add_f32_e32 v19, 1.0, v19
	v_rcp_f32_e32 v16, v16
	v_rcp_f32_e32 v17, v17
	v_rcp_f32_e32 v18, v18
	v_rcp_f32_e32 v19, v19
	v_add_f32_e32 v24, 1.0, v24
	v_add_f32_e32 v25, 1.0, v25
	v_rcp_f32_e32 v24, v24
	v_rcp_f32_e32 v25, v25
	v_pk_mul_f32 v[12:13], v[12:13], v[22:23]
	v_pk_mul_f32 v[4:5], v[4:5], v[152:153] op_sel_hi:[1,0]
	v_pk_mul_f32 v[8:9], v[8:9], v[16:17]
	v_pk_mul_f32 v[4:5], v[4:5], v[12:13]
	v_pk_mul_f32 v[10:11], v[10:11], v[18:19]
	v_pk_mul_f32 v[0:1], v[0:1], v[152:153] op_sel_hi:[1,0]
	v_pk_mul_f32 v[2:3], v[2:3], v[152:153] op_sel_hi:[1,0]
	v_pk_mul_f32 v[14:15], v[14:15], v[24:25]
	v_pk_mul_f32 v[10:11], v[2:3], v[10:11]
	v_pk_mul_f32 v[2:3], v[0:1], v[8:9]
	v_cvt_pk_bf16_f32 v0, v4, v5
	v_mad_i64_i32 v[4:5], s[46:47], v146, s60, v[112:113]
	v_pk_mul_f32 v[6:7], v[6:7], v[152:153] op_sel_hi:[1,0]
	v_lshl_add_u64 v[4:5], v[4:5], 0, v[114:115]
	v_pk_mul_f32 v[6:7], v[6:7], v[14:15]
	s_nop 0
	v_cvt_pk_bf16_f32 v1, v6, v7
	v_cvt_pk_bf16_f32 v2, v2, v3
	v_cvt_pk_bf16_f32 v3, v10, v11
	global_store_dwordx4 v[4:5], v[0:3], off
	s_cbranch_vccnz .LBB0_1584
	s_andn2_b64 vcc, exec, s[14:15]
	s_cbranch_vccnz .LBB0_1583
	s_barrier
	s_branch .LBB0_1583

; __device__ __forceinline__ float sq4(f32x4 v) { return (v[0] * v[0] + v[1] * v[1]) + (v[2] * v[2] + v[3] * v[3]); }
; __device__ __forceinline__ u32x4 pack8(f32x4 a, f32x4 b) { u32x4 w; w.x = cvt_pk_bf16(a[0], a[1]); w.y = cvt_pk_bf16(a[2], a[3]); w.z = cvt_pk_bf16(b[0], b[1]); w.w = cvt_pk_bf16(b[2], b[3]); return w; }
;     __device__ __forceinline__ void operator()(const f32x4 (&acc)[2][2][4][2], const Unit& u, int wr, int wc, int fr, int fq) const {
;         const int col0 = u.pn * 256 + 32 * wc + 8 * fq;
; #pragma unroll
;         for (int ai = 0; ai < 2; ++ai) {
;             u32x4 bs[4][2];
; #pragma unroll
;             for (int m = 0; m < 4; ++m)
; #pragma unroll
;                 for (int bj = 0; bj < 2; ++bj) bs[m][bj] = *(const u32x4*)(xb + (size_t)(u.pm * BM + ai * HALF + wr * 64 + m * 16 + fr) * 1024 + col0 + 128 * bj);
; #pragma unroll
;             for (int m = 0; m < 4; ++m) {
;                 const int row = u.pm * BM + ai * HALF + wr * 64 + m * 16 + fr;
;                 float q = 0.f;
; #pragma unroll
;                 for (int bj = 0; bj < 2; ++bj) {
;                     const size_t off = (size_t)row * 1024 + col0 + 128 * bj; const u32x4 w = bs[m][bj];
;                     const f32x4 b0 = (f32x4){__builtin_bit_cast(float, w.x << 16), __builtin_bit_cast(float, w.x & 0xffff0000u), __builtin_bit_cast(float, w.y << 16), __builtin_bit_cast(float, w.y & 0xffff0000u)};
;                     const f32x4 b1 = (f32x4){__builtin_bit_cast(float, w.z << 16), __builtin_bit_cast(float, w.z & 0xffff0000u), __builtin_bit_cast(float, w.w << 16), __builtin_bit_cast(float, w.w & 0xffff0000u)};
;                     const f32x4 v0 = acc[ai][bj][m][0] + b0, v1 = acc[ai][bj][m][1] + b1;
;                     if (last) { __builtin_nontemporal_store(v0, (f32x4*)(out + off)); __builtin_nontemporal_store(v1, (f32x4*)(out + off + 4)); }
;                     else { q += sq4(v0) + sq4(v1); *(u32x4*)(xb + off) = pack8(v0, v1); }
;                 }
;                 if (!last) { q += shx(q, 16); q += shx(q, 32); if (fq == 0) ss[(size_t)row * 16 + u.pn * 4 + wc] = q; }
;             }
.LBB0_1673:
	v_lshl_or_b32 v168, s18, 8, v188
	v_lshl_add_u32 v172, s65, 8, v186
	v_ashrrev_i32_e32 v169, 31, v168
	v_lshlrev_b64 v[202:203], 1, v[168:169]
	v_ashrrev_i32_e32 v173, 31, v172
	v_lshl_add_u64 v[170:171], s[22:23], 0, v[202:203]
	v_lshlrev_b64 v[204:205], 11, v[172:173]
	v_lshl_add_u64 v[120:121], v[170:171], 0, v[204:205]
	global_load_dwordx4 v[192:195], v[120:121], off
	global_load_dwordx4 v[196:199], v[120:121], off offset:256
	v_or_b32_e32 v182, 16, v172
	v_ashrrev_i32_e32 v183, 31, v182
	v_or_b32_e32 v178, 32, v172
	v_lshlrev_b64 v[184:185], 11, v[182:183]
	v_ashrrev_i32_e32 v179, 31, v178
	v_or_b32_e32 v174, 48, v172
	v_lshl_add_u64 v[120:121], v[170:171], 0, v[184:185]
	v_lshlrev_b64 v[180:181], 11, v[178:179]
	v_ashrrev_i32_e32 v175, 31, v174
	global_load_dwordx4 v[148:151], v[120:121], off
	global_load_dwordx4 v[144:147], v[120:121], off offset:256
	v_lshl_add_u64 v[120:121], v[170:171], 0, v[180:181]
	v_lshlrev_b64 v[176:177], 11, v[174:175]
	global_load_dwordx4 v[140:143], v[120:121], off
	global_load_dwordx4 v[136:139], v[120:121], off offset:256
	v_lshl_add_u64 v[120:121], v[170:171], 0, v[176:177]
	global_load_dwordx4 v[132:135], v[120:121], off
	s_nop 0
	global_load_dwordx4 v[120:123], v[120:121], off offset:256
	s_lshl_b32 s46, s18, 2
	s_ashr_i32 s47, s46, 31
	s_waitcnt vmcnt(0)
	v_lshlrev_b32_e32 v206, 16, v192
	v_and_b32_e32 v207, 0xffff0000, v192
	v_lshlrev_b32_e32 v192, 16, v193
	v_and_b32_e32 v193, 0xffff0000, v193
	v_lshlrev_b32_e32 v208, 16, v194
	v_and_b32_e32 v209, 0xffff0000, v194
	v_lshlrev_b32_e32 v194, 16, v195
	v_and_b32_e32 v195, 0xffff0000, v195
	v_pk_add_f32 v[130:131], v[130:131], v[192:193]
	v_pk_add_f32 v[128:129], v[128:129], v[206:207]
	v_pk_add_f32 v[192:193], v[126:127], v[194:195]
	v_pk_add_f32 v[126:127], v[124:125], v[208:209]
	v_mul_f32_e32 v124, v129, v129
	v_mul_f32_e32 v125, v131, v131
	v_fmac_f32_e32 v124, v128, v128
	v_fmac_f32_e32 v125, v130, v130
	v_add_f32_e32 v124, v124, v125
	v_mul_f32_e32 v125, v127, v127
	v_mul_f32_e32 v194, v193, v193
	v_fmac_f32_e32 v125, v126, v126
	v_fmac_f32_e32 v194, v192, v192
	v_add_f32_e32 v125, v125, v194
	v_add_f32_e32 v194, v124, v125
	v_cvt_pk_bf16_f32 v124, v128, v129
	v_lshl_add_u64 v[128:129], s[22:23], 0, v[204:205]
	v_cvt_pk_bf16_f32 v125, v130, v131
	v_cvt_pk_bf16_f32 v126, v126, v127
	v_cvt_pk_bf16_f32 v127, v192, v193
	v_lshl_add_u64 v[128:129], v[128:129], 0, v[202:203]
	global_store_dwordx4 v[128:129], v[124:127], off
	v_lshlrev_b32_e32 v130, 16, v198
	v_and_b32_e32 v131, 0xffff0000, v198
	v_lshlrev_b32_e32 v124, 16, v196
	v_and_b32_e32 v125, 0xffff0000, v196
	v_lshlrev_b32_e32 v126, 16, v197
	v_and_b32_e32 v127, 0xffff0000, v197
	v_lshlrev_b32_e32 v192, 16, v199
	v_and_b32_e32 v193, 0xffff0000, v199
	v_pk_add_f32 v[118:119], v[118:119], v[126:127]
	v_pk_add_f32 v[116:117], v[116:117], v[124:125]
	v_pk_add_f32 v[124:125], v[114:115], v[192:193]
	v_pk_add_f32 v[114:115], v[112:113], v[130:131]
	v_mul_f32_e32 v112, v117, v117
	v_mul_f32_e32 v113, v119, v119
	v_fmac_f32_e32 v112, v116, v116
	v_fmac_f32_e32 v113, v118, v118
	v_add_f32_e32 v112, v112, v113
	v_mul_f32_e32 v113, v115, v115
	v_mul_f32_e32 v126, v125, v125
	v_fmac_f32_e32 v113, v114, v114
	v_fmac_f32_e32 v126, v124, v124
	v_add_f32_e32 v113, v113, v126
	v_add_f32_e32 v112, v112, v113
	v_add_f32_e32 v126, v194, v112
	v_cvt_pk_bf16_f32 v112, v116, v117
	v_cvt_pk_bf16_f32 v113, v118, v119
	v_cvt_pk_bf16_f32 v114, v114, v115
	v_cvt_pk_bf16_f32 v115, v124, v125
	global_store_dwordx4 v[128:129], v[112:115], off offset:256
	s_nop 1
	v_mov_b32_e32 v112, v201
	v_mov_b32_e32 v113, v201
	v_lshlrev_b32_e32 v112, 2, v112
	v_xor_b32_e32 v112, 64, v112
	v_mov_b32_e32 v112, v126
	s_nop 1
	v_permlane16_swap_b32_e32 v112, v126
	s_waitcnt lgkmcnt(0)
	v_add_f32_e32 v112, v126, v112
	v_lshlrev_b32_e32 v113, 2, v113
	v_xor_b32_e32 v113, 0x80, v113
	v_mov_b32_e32 v113, v112
	s_nop 1
	v_permlane32_swap_b32_e32 v113, v112
	s_and_saveexec_b64 s[48:49], s[8:9]
	s_cbranch_execz .LBB0_1675
	s_waitcnt lgkmcnt(0)
	v_add_f32_e32 v114, v112, v113
	v_lshlrev_b64 v[112:113], 6, v[172:173]
	v_lshl_add_u64 v[112:113], s[24:25], 0, v[112:113]
	v_lshl_add_u64 v[112:113], s[46:47], 2, v[112:113]
	s_lshl_b32 s18, s54, 2
	v_lshl_add_u64 v[112:113], v[112:113], 0, s[18:19]
	global_store_dword v[112:113], v114, off
; __device__ __forceinline__ float sq4(f32x4 v) { return (v[0] * v[0] + v[1] * v[1]) + (v[2] * v[2] + v[3] * v[3]); }
; __device__ __forceinline__ u32x4 pack8(f32x4 a, f32x4 b) { u32x4 w; w.x = cvt_pk_bf16(a[0], a[1]); w.y = cvt_pk_bf16(a[2], a[3]); w.z = cvt_pk_bf16(b[0], b[1]); w.w = cvt_pk_bf16(b[2], b[3]); return w; }
;     __device__ __forceinline__ void operator()(const f32x4 (&acc)[2][2][4][2], const Unit& u, int wr, int wc, int fr, int fq) const {
;         const int col0 = u.pn * 256 + 32 * wc + 8 * fq;
; #pragma unroll
;         for (int ai = 0; ai < 2; ++ai) {
;             u32x4 bs[4][2];
; #pragma unroll
;             for (int m = 0; m < 4; ++m)
; #pragma unroll
;                 for (int bj = 0; bj < 2; ++bj) bs[m][bj] = *(const u32x4*)(xb + (size_t)(u.pm * BM + ai * HALF + wr * 64 + m * 16 + fr) * 1024 + col0 + 128 * bj);
; #pragma unroll
;             for (int m = 0; m < 4; ++m) {
;                 const int row = u.pm * BM + ai * HALF + wr * 64 + m * 16 + fr;
;                 float q = 0.f;
; #pragma unroll
;                 for (int bj = 0; bj < 2; ++bj) {
;                     const size_t off = (size_t)row * 1024 + col0 + 128 * bj; const u32x4 w = bs[m][bj];
;                     const f32x4 b0 = (f32x4){__builtin_bit_cast(float, w.x << 16), __builtin_bit_cast(float, w.x & 0xffff0000u), __builtin_bit_cast(float, w.y << 16), __builtin_bit_cast(float, w.y & 0xffff0000u)};
;                     const f32x4 b1 = (f32x4){__builtin_bit_cast(float, w.z << 16), __builtin_bit_cast(float, w.z & 0xffff0000u), __builtin_bit_cast(float, w.w << 16), __builtin_bit_cast(float, w.w & 0xffff0000u)};
;                     const f32x4 v0 = acc[ai][bj][m][0] + b0, v1 = acc[ai][bj][m][1] + b1;
;                     if (last) { __builtin_nontemporal_store(v0, (f32x4*)(out + off)); __builtin_nontemporal_store(v1, (f32x4*)(out + off + 4)); }
;                     else { q += sq4(v0) + sq4(v1); *(u32x4*)(xb + off) = pack8(v0, v1); }
;                 }
;                 if (!last) { q += shx(q, 16); q += shx(q, 32); if (fq == 0) ss[(size_t)row * 16 + u.pn * 4 + wc] = q; }
;             }
.LBB0_1675:
	s_or_b64 exec, exec, s[48:49]
	v_lshlrev_b32_e32 v112, 16, v148
	s_waitcnt lgkmcnt(0)
	v_and_b32_e32 v113, 0xffff0000, v148
	v_lshlrev_b32_e32 v114, 16, v149
	v_and_b32_e32 v115, 0xffff0000, v149
	v_lshlrev_b32_e32 v116, 16, v150
	v_and_b32_e32 v117, 0xffff0000, v150
	v_lshlrev_b32_e32 v118, 16, v151
	v_and_b32_e32 v119, 0xffff0000, v151
	v_pk_add_f32 v[110:111], v[110:111], v[114:115]
	v_pk_add_f32 v[108:109], v[108:109], v[112:113]
	v_pk_add_f32 v[112:113], v[106:107], v[118:119]
	v_pk_add_f32 v[106:107], v[104:105], v[116:117]
	v_mul_f32_e32 v104, v109, v109
	v_mul_f32_e32 v105, v111, v111
	v_fmac_f32_e32 v104, v108, v108
	v_fmac_f32_e32 v105, v110, v110
	v_add_f32_e32 v104, v104, v105
	v_mul_f32_e32 v105, v107, v107
	v_mul_f32_e32 v114, v113, v113
	v_fmac_f32_e32 v105, v106, v106
	v_fmac_f32_e32 v114, v112, v112
	v_add_f32_e32 v105, v105, v114
	v_add_f32_e32 v114, v104, v105
	v_cvt_pk_bf16_f32 v104, v108, v109
	v_lshl_add_u64 v[108:109], s[22:23], 0, v[184:185]
	v_cvt_pk_bf16_f32 v105, v110, v111
	v_cvt_pk_bf16_f32 v106, v106, v107
	v_cvt_pk_bf16_f32 v107, v112, v113
	v_lshl_add_u64 v[108:109], v[168:169], 1, v[108:109]
	global_store_dwordx4 v[108:109], v[104:107], off
	v_lshlrev_b32_e32 v110, 16, v146
	v_and_b32_e32 v111, 0xffff0000, v146
	v_lshlrev_b32_e32 v104, 16, v144
	v_and_b32_e32 v105, 0xffff0000, v144
	v_lshlrev_b32_e32 v106, 16, v145
	v_and_b32_e32 v107, 0xffff0000, v145
	v_lshlrev_b32_e32 v112, 16, v147
	v_and_b32_e32 v113, 0xffff0000, v147
	v_pk_add_f32 v[102:103], v[102:103], v[106:107]
	v_pk_add_f32 v[100:101], v[100:101], v[104:105]
	v_pk_add_f32 v[104:105], v[98:99], v[112:113]
	v_pk_add_f32 v[98:99], v[96:97], v[110:111]
	v_mul_f32_e32 v96, v101, v101
	v_mul_f32_e32 v97, v103, v103
	v_fmac_f32_e32 v96, v100, v100
	v_fmac_f32_e32 v97, v102, v102
	v_add_f32_e32 v96, v96, v97
	v_mul_f32_e32 v97, v99, v99
	v_mul_f32_e32 v106, v105, v105
	v_fmac_f32_e32 v97, v98, v98
	v_fmac_f32_e32 v106, v104, v104
	v_add_f32_e32 v97, v97, v106
	v_add_f32_e32 v96, v96, v97
	v_add_f32_e32 v106, v114, v96
	v_cvt_pk_bf16_f32 v96, v100, v101
	v_cvt_pk_bf16_f32 v97, v102, v103
	v_cvt_pk_bf16_f32 v98, v98, v99
	v_cvt_pk_bf16_f32 v99, v104, v105
	global_store_dwordx4 v[108:109], v[96:99], off offset:256
	s_nop 1
	v_mov_b32_e32 v96, v201
	v_mov_b32_e32 v97, v201
	v_lshlrev_b32_e32 v96, 2, v96
	v_xor_b32_e32 v96, 64, v96
	v_mov_b32_e32 v96, v106
	s_nop 1
	v_permlane16_swap_b32_e32 v96, v106
	s_waitcnt lgkmcnt(0)
	v_add_f32_e32 v96, v106, v96
	v_lshlrev_b32_e32 v97, 2, v97
	v_xor_b32_e32 v97, 0x80, v97
	v_mov_b32_e32 v97, v96
	s_nop 1
	v_permlane32_swap_b32_e32 v97, v96
	s_and_saveexec_b64 s[48:49], s[8:9]
	s_cbranch_execz .LBB0_1677
	s_waitcnt lgkmcnt(0)
	v_add_f32_e32 v98, v96, v97
	v_lshlrev_b64 v[96:97], 6, v[182:183]
	v_lshl_add_u64 v[96:97], s[24:25], 0, v[96:97]
	v_lshl_add_u64 v[96:97], s[46:47], 2, v[96:97]
	s_lshl_b32 s18, s54, 2
	v_lshl_add_u64 v[96:97], v[96:97], 0, s[18:19]
	global_store_dword v[96:97], v98, off
.LBB0_1677:
	s_or_b64 exec, exec, s[48:49]
	v_lshlrev_b32_e32 v96, 16, v140
	s_waitcnt lgkmcnt(0)
	v_and_b32_e32 v97, 0xffff0000, v140
	v_lshlrev_b32_e32 v98, 16, v141
	v_and_b32_e32 v99, 0xffff0000, v141
	v_lshlrev_b32_e32 v100, 16, v142
	v_and_b32_e32 v101, 0xffff0000, v142
	v_lshlrev_b32_e32 v102, 16, v143
	v_and_b32_e32 v103, 0xffff0000, v143
	v_pk_add_f32 v[94:95], v[94:95], v[98:99]
	v_pk_add_f32 v[92:93], v[92:93], v[96:97]
	v_pk_add_f32 v[96:97], v[90:91], v[102:103]
	v_pk_add_f32 v[90:91], v[88:89], v[100:101]
	v_mul_f32_e32 v88, v93, v93
	v_mul_f32_e32 v89, v95, v95
	v_fmac_f32_e32 v88, v92, v92
	v_fmac_f32_e32 v89, v94, v94
	v_add_f32_e32 v88, v88, v89
	v_mul_f32_e32 v89, v91, v91
	v_mul_f32_e32 v98, v97, v97
	v_fmac_f32_e32 v89, v90, v90
	v_fmac_f32_e32 v98, v96, v96
	v_add_f32_e32 v89, v89, v98
	v_add_f32_e32 v98, v88, v89
	v_cvt_pk_bf16_f32 v88, v92, v93
	v_lshl_add_u64 v[92:93], s[22:23], 0, v[180:181]
	v_cvt_pk_bf16_f32 v89, v94, v95
	v_cvt_pk_bf16_f32 v90, v90, v91
	v_cvt_pk_bf16_f32 v91, v96, v97
	v_lshl_add_u64 v[92:93], v[168:169], 1, v[92:93]
	global_store_dwordx4 v[92:93], v[88:91], off
	v_lshlrev_b32_e32 v94, 16, v138
	v_and_b32_e32 v95, 0xffff0000, v138
	v_lshlrev_b32_e32 v88, 16, v136
	v_and_b32_e32 v89, 0xffff0000, v136
	v_lshlrev_b32_e32 v90, 16, v137
	v_and_b32_e32 v91, 0xffff0000, v137
	v_lshlrev_b32_e32 v96, 16, v139
	v_and_b32_e32 v97, 0xffff0000, v139
	v_pk_add_f32 v[86:87], v[86:87], v[90:91]
	v_pk_add_f32 v[84:85], v[84:85], v[88:89]
	v_pk_add_f32 v[88:89], v[82:83], v[96:97]
	v_pk_add_f32 v[82:83], v[80:81], v[94:95]
	v_mul_f32_e32 v80, v85, v85
	v_mul_f32_e32 v81, v87, v87
	v_fmac_f32_e32 v80, v84, v84
	v_fmac_f32_e32 v81, v86, v86
	v_add_f32_e32 v80, v80, v81
	v_mul_f32_e32 v81, v83, v83
	v_mul_f32_e32 v90, v89, v89
	v_fmac_f32_e32 v81, v82, v82
	v_fmac_f32_e32 v90, v88, v88
	v_add_f32_e32 v81, v81, v90
	v_add_f32_e32 v80, v80, v81
	v_add_f32_e32 v90, v98, v80
	v_cvt_pk_bf16_f32 v80, v84, v85
	v_cvt_pk_bf16_f32 v81, v86, v87
	v_cvt_pk_bf16_f32 v82, v82, v83
	v_cvt_pk_bf16_f32 v83, v88, v89
	global_store_dwordx4 v[92:93], v[80:83], off offset:256
	s_nop 1
	v_mov_b32_e32 v80, v201
	v_mov_b32_e32 v81, v201
	v_lshlrev_b32_e32 v80, 2, v80
	v_xor_b32_e32 v80, 64, v80
	v_mov_b32_e32 v80, v90
	s_nop 1
	v_permlane16_swap_b32_e32 v80, v90
	s_waitcnt lgkmcnt(0)
	v_add_f32_e32 v80, v90, v80
	v_lshlrev_b32_e32 v81, 2, v81
	v_xor_b32_e32 v81, 0x80, v81
	v_mov_b32_e32 v81, v80
	s_nop 1
	v_permlane32_swap_b32_e32 v81, v80
	s_and_saveexec_b64 s[48:49], s[8:9]
	s_cbranch_execz .LBB0_1679
	s_waitcnt lgkmcnt(0)
	v_add_f32_e32 v82, v80, v81
	v_lshlrev_b64 v[80:81], 6, v[178:179]
	v_lshl_add_u64 v[80:81], s[24:25], 0, v[80:81]
	v_lshl_add_u64 v[80:81], s[46:47], 2, v[80:81]
	s_lshl_b32 s18, s54, 2
	v_lshl_add_u64 v[80:81], v[80:81], 0, s[18:19]
	global_store_dword v[80:81], v82, off
; __device__ __forceinline__ float sq4(f32x4 v) { return (v[0] * v[0] + v[1] * v[1]) + (v[2] * v[2] + v[3] * v[3]); }
; __device__ __forceinline__ u32x4 pack8(f32x4 a, f32x4 b) { u32x4 w; w.x = cvt_pk_bf16(a[0], a[1]); w.y = cvt_pk_bf16(a[2], a[3]); w.z = cvt_pk_bf16(b[0], b[1]); w.w = cvt_pk_bf16(b[2], b[3]); return w; }
;     __device__ __forceinline__ void operator()(const f32x4 (&acc)[2][2][4][2], const Unit& u, int wr, int wc, int fr, int fq) const {
;         const int col0 = u.pn * 256 + 32 * wc + 8 * fq;
; #pragma unroll
;         for (int ai = 0; ai < 2; ++ai) {
;             u32x4 bs[4][2];
; #pragma unroll
;             for (int m = 0; m < 4; ++m)
; #pragma unroll
;                 for (int bj = 0; bj < 2; ++bj) bs[m][bj] = *(const u32x4*)(xb + (size_t)(u.pm * BM + ai * HALF + wr * 64 + m * 16 + fr) * 1024 + col0 + 128 * bj);
; #pragma unroll
;             for (int m = 0; m < 4; ++m) {
;                 const int row = u.pm * BM + ai * HALF + wr * 64 + m * 16 + fr;
;                 float q = 0.f;
; #pragma unroll
;                 for (int bj = 0; bj < 2; ++bj) {
;                     const size_t off = (size_t)row * 1024 + col0 + 128 * bj; const u32x4 w = bs[m][bj];
;                     const f32x4 b0 = (f32x4){__builtin_bit_cast(float, w.x << 16), __builtin_bit_cast(float, w.x & 0xffff0000u), __builtin_bit_cast(float, w.y << 16), __builtin_bit_cast(float, w.y & 0xffff0000u)};
;                     const f32x4 b1 = (f32x4){__builtin_bit_cast(float, w.z << 16), __builtin_bit_cast(float, w.z & 0xffff0000u), __builtin_bit_cast(float, w.w << 16), __builtin_bit_cast(float, w.w & 0xffff0000u)};
;                     const f32x4 v0 = acc[ai][bj][m][0] + b0, v1 = acc[ai][bj][m][1] + b1;
;                     if (last) { __builtin_nontemporal_store(v0, (f32x4*)(out + off)); __builtin_nontemporal_store(v1, (f32x4*)(out + off + 4)); }
;                     else { q += sq4(v0) + sq4(v1); *(u32x4*)(xb + off) = pack8(v0, v1); }
;                 }
;                 if (!last) { q += shx(q, 16); q += shx(q, 32); if (fq == 0) ss[(size_t)row * 16 + u.pn * 4 + wc] = q; }
;             }
.LBB0_1679:
	s_or_b64 exec, exec, s[48:49]
	v_lshlrev_b32_e32 v80, 16, v132
	s_waitcnt lgkmcnt(0)
	v_and_b32_e32 v81, 0xffff0000, v132
	v_lshlrev_b32_e32 v82, 16, v133
	v_and_b32_e32 v83, 0xffff0000, v133
	v_lshlrev_b32_e32 v84, 16, v134
	v_and_b32_e32 v85, 0xffff0000, v134
	v_lshlrev_b32_e32 v86, 16, v135
	v_and_b32_e32 v87, 0xffff0000, v135
	v_pk_add_f32 v[78:79], v[78:79], v[82:83]
	v_pk_add_f32 v[76:77], v[76:77], v[80:81]
	v_pk_add_f32 v[80:81], v[74:75], v[86:87]
	v_pk_add_f32 v[74:75], v[72:73], v[84:85]
	v_mul_f32_e32 v72, v77, v77
	v_mul_f32_e32 v73, v79, v79
	v_fmac_f32_e32 v72, v76, v76
	v_fmac_f32_e32 v73, v78, v78
	v_add_f32_e32 v72, v72, v73
	v_mul_f32_e32 v73, v75, v75
	v_mul_f32_e32 v82, v81, v81
	v_fmac_f32_e32 v73, v74, v74
	v_fmac_f32_e32 v82, v80, v80
	v_add_f32_e32 v73, v73, v82
	v_add_f32_e32 v82, v72, v73
	v_cvt_pk_bf16_f32 v72, v76, v77
	v_lshl_add_u64 v[76:77], s[22:23], 0, v[176:177]
	v_cvt_pk_bf16_f32 v73, v78, v79
	v_cvt_pk_bf16_f32 v74, v74, v75
	v_cvt_pk_bf16_f32 v75, v80, v81
	v_lshl_add_u64 v[76:77], v[168:169], 1, v[76:77]
	global_store_dwordx4 v[76:77], v[72:75], off
	v_lshlrev_b32_e32 v78, 16, v122
	v_and_b32_e32 v79, 0xffff0000, v122
	v_lshlrev_b32_e32 v72, 16, v120
	v_and_b32_e32 v73, 0xffff0000, v120
	v_lshlrev_b32_e32 v74, 16, v121
	v_and_b32_e32 v75, 0xffff0000, v121
	v_lshlrev_b32_e32 v80, 16, v123
	v_and_b32_e32 v81, 0xffff0000, v123
	v_pk_add_f32 v[70:71], v[70:71], v[74:75]
	v_pk_add_f32 v[68:69], v[68:69], v[72:73]
	v_pk_add_f32 v[72:73], v[66:67], v[80:81]
	v_pk_add_f32 v[66:67], v[64:65], v[78:79]
	v_mul_f32_e32 v64, v69, v69
	v_mul_f32_e32 v65, v71, v71
	v_fmac_f32_e32 v64, v68, v68
	v_fmac_f32_e32 v65, v70, v70
	v_add_f32_e32 v64, v64, v65
	v_mul_f32_e32 v65, v67, v67
	v_mul_f32_e32 v74, v73, v73
	v_fmac_f32_e32 v65, v66, v66
	v_fmac_f32_e32 v74, v72, v72
	v_add_f32_e32 v65, v65, v74
	v_add_f32_e32 v64, v64, v65
	v_add_f32_e32 v74, v82, v64
	v_cvt_pk_bf16_f32 v64, v68, v69
	v_cvt_pk_bf16_f32 v65, v70, v71
	v_cvt_pk_bf16_f32 v66, v66, v67
	v_cvt_pk_bf16_f32 v67, v72, v73
	global_store_dwordx4 v[76:77], v[64:67], off offset:256
	s_nop 1
	v_mov_b32_e32 v64, v201
	v_mov_b32_e32 v65, v201
	v_lshlrev_b32_e32 v64, 2, v64
	v_xor_b32_e32 v64, 64, v64
	v_mov_b32_e32 v64, v74
	s_nop 1
	v_permlane16_swap_b32_e32 v64, v74
	s_waitcnt lgkmcnt(0)
	v_add_f32_e32 v64, v74, v64
	v_lshlrev_b32_e32 v65, 2, v65
	v_xor_b32_e32 v65, 0x80, v65
	v_mov_b32_e32 v65, v64
	s_nop 1
	v_permlane32_swap_b32_e32 v65, v64
	s_and_saveexec_b64 s[48:49], s[8:9]
	s_cbranch_execz .LBB0_1681
	s_waitcnt lgkmcnt(0)
	v_add_f32_e32 v66, v64, v65
	v_lshlrev_b64 v[64:65], 6, v[174:175]
	v_lshl_add_u64 v[64:65], s[24:25], 0, v[64:65]
	v_lshl_add_u64 v[64:65], s[46:47], 2, v[64:65]
	s_lshl_b32 s18, s54, 2
	v_lshl_add_u64 v[64:65], v[64:65], 0, s[18:19]
	global_store_dword v[64:65], v66, off
.LBB0_1681:
	s_or_b64 exec, exec, s[48:49]
	v_add_u32_e32 v100, 0x80, v172
	v_ashrrev_i32_e32 v101, 31, v100
	v_lshlrev_b64 v[110:111], 11, v[100:101]
	s_waitcnt lgkmcnt(0)
	v_lshl_add_u64 v[64:65], v[170:171], 0, v[110:111]
	global_load_dwordx4 v[102:105], v[64:65], off
	global_load_dwordx4 v[106:109], v[64:65], off offset:256
	v_add_u32_e32 v96, 0x90, v172
	v_ashrrev_i32_e32 v97, 31, v96
	v_add_u32_e32 v92, 0xa0, v172
	v_lshlrev_b64 v[98:99], 11, v[96:97]
	v_ashrrev_i32_e32 v93, 31, v92
	v_add_u32_e32 v88, 0xb0, v172
	v_lshl_add_u64 v[64:65], v[170:171], 0, v[98:99]
	v_lshlrev_b64 v[94:95], 11, v[92:93]
	v_ashrrev_i32_e32 v89, 31, v88
	global_load_dwordx4 v[84:87], v[64:65], off
	global_load_dwordx4 v[80:83], v[64:65], off offset:256
	v_lshl_add_u64 v[64:65], v[170:171], 0, v[94:95]
	v_lshlrev_b64 v[90:91], 11, v[88:89]
	global_load_dwordx4 v[76:79], v[64:65], off
	global_load_dwordx4 v[72:75], v[64:65], off offset:256
	v_lshl_add_u64 v[64:65], v[170:171], 0, v[90:91]
	global_load_dwordx4 v[68:71], v[64:65], off
	s_nop 0
	global_load_dwordx4 v[64:67], v[64:65], off offset:256
	s_waitcnt vmcnt(7)
	v_lshlrev_b32_e32 v112, 16, v102
	v_and_b32_e32 v113, 0xffff0000, v102
	v_lshlrev_b32_e32 v102, 16, v103
	v_and_b32_e32 v103, 0xffff0000, v103
	v_lshlrev_b32_e32 v114, 16, v104
	v_and_b32_e32 v115, 0xffff0000, v104
	v_lshlrev_b32_e32 v104, 16, v105
	v_and_b32_e32 v105, 0xffff0000, v105
	v_pk_add_f32 v[62:63], v[62:63], v[102:103]
	v_pk_add_f32 v[60:61], v[60:61], v[112:113]
	v_pk_add_f32 v[102:103], v[58:59], v[104:105]
	v_pk_add_f32 v[58:59], v[56:57], v[114:115]
	v_mul_f32_e32 v56, v61, v61
	v_mul_f32_e32 v57, v63, v63
	v_fmac_f32_e32 v56, v60, v60
	v_fmac_f32_e32 v57, v62, v62
	v_add_f32_e32 v56, v56, v57
	v_mul_f32_e32 v57, v59, v59
	v_mul_f32_e32 v104, v103, v103
	v_fmac_f32_e32 v57, v58, v58
	v_fmac_f32_e32 v104, v102, v102
	v_add_f32_e32 v57, v57, v104
	v_add_f32_e32 v104, v56, v57
	v_cvt_pk_bf16_f32 v56, v60, v61
	v_lshl_add_u64 v[60:61], s[22:23], 0, v[110:111]
	v_cvt_pk_bf16_f32 v57, v62, v63
	v_cvt_pk_bf16_f32 v58, v58, v59
	v_cvt_pk_bf16_f32 v59, v102, v103
	v_lshl_add_u64 v[60:61], v[168:169], 1, v[60:61]
	global_store_dwordx4 v[60:61], v[56:59], off
	s_waitcnt vmcnt(7)
	v_lshlrev_b32_e32 v62, 16, v108
	v_and_b32_e32 v63, 0xffff0000, v108
	v_lshlrev_b32_e32 v56, 16, v106
	v_and_b32_e32 v57, 0xffff0000, v106
	v_lshlrev_b32_e32 v58, 16, v107
	v_and_b32_e32 v59, 0xffff0000, v107
	v_lshlrev_b32_e32 v102, 16, v109
	v_and_b32_e32 v103, 0xffff0000, v109
	v_pk_add_f32 v[54:55], v[54:55], v[58:59]
	v_pk_add_f32 v[52:53], v[52:53], v[56:57]
	v_pk_add_f32 v[56:57], v[50:51], v[102:103]
	v_pk_add_f32 v[50:51], v[48:49], v[62:63]
	v_mul_f32_e32 v48, v53, v53
	v_mul_f32_e32 v49, v55, v55
	v_fmac_f32_e32 v48, v52, v52
	v_fmac_f32_e32 v49, v54, v54
	v_add_f32_e32 v48, v48, v49
	v_mul_f32_e32 v49, v51, v51
	v_mul_f32_e32 v58, v57, v57
	v_fmac_f32_e32 v49, v50, v50
	v_fmac_f32_e32 v58, v56, v56
	v_add_f32_e32 v49, v49, v58
	v_add_f32_e32 v48, v48, v49
	v_add_f32_e32 v58, v104, v48
	v_cvt_pk_bf16_f32 v48, v52, v53
	v_cvt_pk_bf16_f32 v49, v54, v55
	v_cvt_pk_bf16_f32 v50, v50, v51
	v_cvt_pk_bf16_f32 v51, v56, v57
	global_store_dwordx4 v[60:61], v[48:51], off offset:256
	s_nop 1
	v_mov_b32_e32 v48, v201
	v_mov_b32_e32 v49, v201
	v_lshlrev_b32_e32 v48, 2, v48
	v_xor_b32_e32 v48, 64, v48
	v_mov_b32_e32 v48, v58
	s_nop 1
	v_permlane16_swap_b32_e32 v48, v58
	s_waitcnt lgkmcnt(0)
	v_add_f32_e32 v48, v58, v48
	v_lshlrev_b32_e32 v49, 2, v49
	v_xor_b32_e32 v49, 0x80, v49
	v_mov_b32_e32 v49, v48
	s_nop 1
	v_permlane32_swap_b32_e32 v49, v48
	s_and_saveexec_b64 s[48:49], s[8:9]
	s_cbranch_execz .LBB0_1683
	s_waitcnt lgkmcnt(0)
	v_add_f32_e32 v50, v48, v49
	v_lshlrev_b64 v[48:49], 6, v[100:101]
	v_lshl_add_u64 v[48:49], s[24:25], 0, v[48:49]
	v_lshl_add_u64 v[48:49], s[46:47], 2, v[48:49]
	s_lshl_b32 s18, s54, 2
	v_lshl_add_u64 v[48:49], v[48:49], 0, s[18:19]
	global_store_dword v[48:49], v50, off
; __device__ __forceinline__ float sq4(f32x4 v) { return (v[0] * v[0] + v[1] * v[1]) + (v[2] * v[2] + v[3] * v[3]); }
; __device__ __forceinline__ u32x4 pack8(f32x4 a, f32x4 b) { u32x4 w; w.x = cvt_pk_bf16(a[0], a[1]); w.y = cvt_pk_bf16(a[2], a[3]); w.z = cvt_pk_bf16(b[0], b[1]); w.w = cvt_pk_bf16(b[2], b[3]); return w; }
;     __device__ __forceinline__ void operator()(const f32x4 (&acc)[2][2][4][2], const Unit& u, int wr, int wc, int fr, int fq) const {
;         const int col0 = u.pn * 256 + 32 * wc + 8 * fq;
; #pragma unroll
;         for (int ai = 0; ai < 2; ++ai) {
;             u32x4 bs[4][2];
; #pragma unroll
;             for (int m = 0; m < 4; ++m)
; #pragma unroll
;                 for (int bj = 0; bj < 2; ++bj) bs[m][bj] = *(const u32x4*)(xb + (size_t)(u.pm * BM + ai * HALF + wr * 64 + m * 16 + fr) * 1024 + col0 + 128 * bj);
; #pragma unroll
;             for (int m = 0; m < 4; ++m) {
;                 const int row = u.pm * BM + ai * HALF + wr * 64 + m * 16 + fr;
;                 float q = 0.f;
; #pragma unroll
;                 for (int bj = 0; bj < 2; ++bj) {
;                     const size_t off = (size_t)row * 1024 + col0 + 128 * bj; const u32x4 w = bs[m][bj];
;                     const f32x4 b0 = (f32x4){__builtin_bit_cast(float, w.x << 16), __builtin_bit_cast(float, w.x & 0xffff0000u), __builtin_bit_cast(float, w.y << 16), __builtin_bit_cast(float, w.y & 0xffff0000u)};
;                     const f32x4 b1 = (f32x4){__builtin_bit_cast(float, w.z << 16), __builtin_bit_cast(float, w.z & 0xffff0000u), __builtin_bit_cast(float, w.w << 16), __builtin_bit_cast(float, w.w & 0xffff0000u)};
;                     const f32x4 v0 = acc[ai][bj][m][0] + b0, v1 = acc[ai][bj][m][1] + b1;
;                     if (last) { __builtin_nontemporal_store(v0, (f32x4*)(out + off)); __builtin_nontemporal_store(v1, (f32x4*)(out + off + 4)); }
;                     else { q += sq4(v0) + sq4(v1); *(u32x4*)(xb + off) = pack8(v0, v1); }
;                 }
;                 if (!last) { q += shx(q, 16); q += shx(q, 32); if (fq == 0) ss[(size_t)row * 16 + u.pn * 4 + wc] = q; }
;             }
.LBB0_1683:
	s_or_b64 exec, exec, s[48:49]
	s_waitcnt vmcnt(7)
	v_lshlrev_b32_e32 v48, 16, v84
	s_waitcnt lgkmcnt(0)
	v_and_b32_e32 v49, 0xffff0000, v84
	v_lshlrev_b32_e32 v50, 16, v85
	v_and_b32_e32 v51, 0xffff0000, v85
	v_lshlrev_b32_e32 v52, 16, v86
	v_and_b32_e32 v53, 0xffff0000, v86
	v_lshlrev_b32_e32 v54, 16, v87
	v_and_b32_e32 v55, 0xffff0000, v87
	v_pk_add_f32 v[46:47], v[46:47], v[50:51]
	v_pk_add_f32 v[44:45], v[44:45], v[48:49]
	v_pk_add_f32 v[48:49], v[42:43], v[54:55]
	v_pk_add_f32 v[42:43], v[40:41], v[52:53]
	v_mul_f32_e32 v40, v45, v45
	v_mul_f32_e32 v41, v47, v47
	v_fmac_f32_e32 v40, v44, v44
	v_fmac_f32_e32 v41, v46, v46
	v_add_f32_e32 v40, v40, v41
	v_mul_f32_e32 v41, v43, v43
	v_mul_f32_e32 v50, v49, v49
	v_fmac_f32_e32 v41, v42, v42
	v_fmac_f32_e32 v50, v48, v48
	v_add_f32_e32 v41, v41, v50
	v_add_f32_e32 v50, v40, v41
	v_cvt_pk_bf16_f32 v40, v44, v45
	v_lshl_add_u64 v[44:45], s[22:23], 0, v[98:99]
	v_cvt_pk_bf16_f32 v41, v46, v47
	v_cvt_pk_bf16_f32 v42, v42, v43
	v_cvt_pk_bf16_f32 v43, v48, v49
	v_lshl_add_u64 v[44:45], v[168:169], 1, v[44:45]
	global_store_dwordx4 v[44:45], v[40:43], off
	s_waitcnt vmcnt(7)
	v_lshlrev_b32_e32 v46, 16, v82
	v_and_b32_e32 v47, 0xffff0000, v82
	v_lshlrev_b32_e32 v40, 16, v80
	v_and_b32_e32 v41, 0xffff0000, v80
	v_lshlrev_b32_e32 v42, 16, v81
	v_and_b32_e32 v43, 0xffff0000, v81
	v_lshlrev_b32_e32 v48, 16, v83
	v_and_b32_e32 v49, 0xffff0000, v83
	v_pk_add_f32 v[38:39], v[38:39], v[42:43]
	v_pk_add_f32 v[36:37], v[36:37], v[40:41]
	v_pk_add_f32 v[40:41], v[34:35], v[48:49]
	v_pk_add_f32 v[34:35], v[32:33], v[46:47]
	v_mul_f32_e32 v32, v37, v37
	v_mul_f32_e32 v33, v39, v39
	v_fmac_f32_e32 v32, v36, v36
	v_fmac_f32_e32 v33, v38, v38
	v_add_f32_e32 v32, v32, v33
	v_mul_f32_e32 v33, v35, v35
	v_mul_f32_e32 v42, v41, v41
	v_fmac_f32_e32 v33, v34, v34
	v_fmac_f32_e32 v42, v40, v40
	v_add_f32_e32 v33, v33, v42
	v_add_f32_e32 v32, v32, v33
	v_add_f32_e32 v42, v50, v32
	v_cvt_pk_bf16_f32 v32, v36, v37
	v_cvt_pk_bf16_f32 v33, v38, v39
	v_cvt_pk_bf16_f32 v34, v34, v35
	v_cvt_pk_bf16_f32 v35, v40, v41
	global_store_dwordx4 v[44:45], v[32:35], off offset:256
	s_nop 1
	v_mov_b32_e32 v32, v201
	v_mov_b32_e32 v33, v201
	v_lshlrev_b32_e32 v32, 2, v32
	v_xor_b32_e32 v32, 64, v32
	v_mov_b32_e32 v32, v42
	s_nop 1
	v_permlane16_swap_b32_e32 v32, v42
	s_waitcnt lgkmcnt(0)
	v_add_f32_e32 v32, v42, v32
	v_lshlrev_b32_e32 v33, 2, v33
	v_xor_b32_e32 v33, 0x80, v33
	v_mov_b32_e32 v33, v32
	s_nop 1
	v_permlane32_swap_b32_e32 v33, v32
	s_and_saveexec_b64 s[48:49], s[8:9]
	s_cbranch_execz .LBB0_1685
	s_waitcnt lgkmcnt(0)
	v_add_f32_e32 v34, v32, v33
	v_lshlrev_b64 v[32:33], 6, v[96:97]
	v_lshl_add_u64 v[32:33], s[24:25], 0, v[32:33]
	v_lshl_add_u64 v[32:33], s[46:47], 2, v[32:33]
	s_lshl_b32 s18, s54, 2
	v_lshl_add_u64 v[32:33], v[32:33], 0, s[18:19]
	global_store_dword v[32:33], v34, off
; __device__ __forceinline__ float sq4(f32x4 v) { return (v[0] * v[0] + v[1] * v[1]) + (v[2] * v[2] + v[3] * v[3]); }
; __device__ __forceinline__ u32x4 pack8(f32x4 a, f32x4 b) { u32x4 w; w.x = cvt_pk_bf16(a[0], a[1]); w.y = cvt_pk_bf16(a[2], a[3]); w.z = cvt_pk_bf16(b[0], b[1]); w.w = cvt_pk_bf16(b[2], b[3]); return w; }
;     __device__ __forceinline__ void operator()(const f32x4 (&acc)[2][2][4][2], const Unit& u, int wr, int wc, int fr, int fq) const {
;         const int col0 = u.pn * 256 + 32 * wc + 8 * fq;
; #pragma unroll
;         for (int ai = 0; ai < 2; ++ai) {
;             u32x4 bs[4][2];
; #pragma unroll
;             for (int m = 0; m < 4; ++m)
; #pragma unroll
;                 for (int bj = 0; bj < 2; ++bj) bs[m][bj] = *(const u32x4*)(xb + (size_t)(u.pm * BM + ai * HALF + wr * 64 + m * 16 + fr) * 1024 + col0 + 128 * bj);
; #pragma unroll
;             for (int m = 0; m < 4; ++m) {
;                 const int row = u.pm * BM + ai * HALF + wr * 64 + m * 16 + fr;
;                 float q = 0.f;
; #pragma unroll
;                 for (int bj = 0; bj < 2; ++bj) {
;                     const size_t off = (size_t)row * 1024 + col0 + 128 * bj; const u32x4 w = bs[m][bj];
;                     const f32x4 b0 = (f32x4){__builtin_bit_cast(float, w.x << 16), __builtin_bit_cast(float, w.x & 0xffff0000u), __builtin_bit_cast(float, w.y << 16), __builtin_bit_cast(float, w.y & 0xffff0000u)};
;                     const f32x4 b1 = (f32x4){__builtin_bit_cast(float, w.z << 16), __builtin_bit_cast(float, w.z & 0xffff0000u), __builtin_bit_cast(float, w.w << 16), __builtin_bit_cast(float, w.w & 0xffff0000u)};
;                     const f32x4 v0 = acc[ai][bj][m][0] + b0, v1 = acc[ai][bj][m][1] + b1;
;                     if (last) { __builtin_nontemporal_store(v0, (f32x4*)(out + off)); __builtin_nontemporal_store(v1, (f32x4*)(out + off + 4)); }
;                     else { q += sq4(v0) + sq4(v1); *(u32x4*)(xb + off) = pack8(v0, v1); }
;                 }
;                 if (!last) { q += shx(q, 16); q += shx(q, 32); if (fq == 0) ss[(size_t)row * 16 + u.pn * 4 + wc] = q; }
;             }
.LBB0_1685:
	s_or_b64 exec, exec, s[48:49]
	s_waitcnt vmcnt(7)
	v_lshlrev_b32_e32 v32, 16, v76
	s_waitcnt lgkmcnt(0)
	v_and_b32_e32 v33, 0xffff0000, v76
	v_lshlrev_b32_e32 v34, 16, v77
	v_and_b32_e32 v35, 0xffff0000, v77
	v_lshlrev_b32_e32 v36, 16, v78
	v_and_b32_e32 v37, 0xffff0000, v78
	v_lshlrev_b32_e32 v38, 16, v79
	v_and_b32_e32 v39, 0xffff0000, v79
	v_pk_add_f32 v[30:31], v[30:31], v[34:35]
	v_pk_add_f32 v[28:29], v[28:29], v[32:33]
	v_pk_add_f32 v[32:33], v[26:27], v[38:39]
	v_pk_add_f32 v[26:27], v[24:25], v[36:37]
	v_mul_f32_e32 v24, v29, v29
	v_mul_f32_e32 v25, v31, v31
	v_fmac_f32_e32 v24, v28, v28
	v_fmac_f32_e32 v25, v30, v30
	v_add_f32_e32 v24, v24, v25
	v_mul_f32_e32 v25, v27, v27
	v_mul_f32_e32 v34, v33, v33
	v_fmac_f32_e32 v25, v26, v26
	v_fmac_f32_e32 v34, v32, v32
	v_add_f32_e32 v25, v25, v34
	v_add_f32_e32 v34, v24, v25
	v_cvt_pk_bf16_f32 v24, v28, v29
	v_lshl_add_u64 v[28:29], s[22:23], 0, v[94:95]
	v_cvt_pk_bf16_f32 v25, v30, v31
	v_cvt_pk_bf16_f32 v26, v26, v27
	v_cvt_pk_bf16_f32 v27, v32, v33
	v_lshl_add_u64 v[28:29], v[168:169], 1, v[28:29]
	global_store_dwordx4 v[28:29], v[24:27], off
	s_waitcnt vmcnt(7)
	v_lshlrev_b32_e32 v30, 16, v74
	v_and_b32_e32 v31, 0xffff0000, v74
	v_lshlrev_b32_e32 v24, 16, v72
	v_and_b32_e32 v25, 0xffff0000, v72
	v_lshlrev_b32_e32 v26, 16, v73
	v_and_b32_e32 v27, 0xffff0000, v73
	v_lshlrev_b32_e32 v32, 16, v75
	v_and_b32_e32 v33, 0xffff0000, v75
	v_pk_add_f32 v[22:23], v[22:23], v[26:27]
	v_pk_add_f32 v[20:21], v[20:21], v[24:25]
	v_pk_add_f32 v[24:25], v[18:19], v[32:33]
	v_pk_add_f32 v[18:19], v[16:17], v[30:31]
	v_mul_f32_e32 v16, v21, v21
	v_mul_f32_e32 v17, v23, v23
	v_fmac_f32_e32 v16, v20, v20
	v_fmac_f32_e32 v17, v22, v22
	v_add_f32_e32 v16, v16, v17
	v_mul_f32_e32 v17, v19, v19
	v_mul_f32_e32 v26, v25, v25
	v_fmac_f32_e32 v17, v18, v18
	v_fmac_f32_e32 v26, v24, v24
	v_add_f32_e32 v17, v17, v26
	v_add_f32_e32 v16, v16, v17
	v_add_f32_e32 v26, v34, v16
	v_cvt_pk_bf16_f32 v16, v20, v21
	v_cvt_pk_bf16_f32 v17, v22, v23
	v_cvt_pk_bf16_f32 v18, v18, v19
	v_cvt_pk_bf16_f32 v19, v24, v25
	global_store_dwordx4 v[28:29], v[16:19], off offset:256
	s_nop 1
	v_mov_b32_e32 v16, v201
	v_mov_b32_e32 v17, v201
	v_lshlrev_b32_e32 v16, 2, v16
	v_xor_b32_e32 v16, 64, v16
	v_mov_b32_e32 v16, v26
	s_nop 1
	v_permlane16_swap_b32_e32 v16, v26
	s_waitcnt lgkmcnt(0)
	v_add_f32_e32 v16, v26, v16
	v_lshlrev_b32_e32 v17, 2, v17
	v_xor_b32_e32 v17, 0x80, v17
	v_mov_b32_e32 v17, v16
	s_nop 1
	v_permlane32_swap_b32_e32 v17, v16
	s_and_saveexec_b64 s[48:49], s[8:9]
	s_cbranch_execz .LBB0_1687
	s_waitcnt lgkmcnt(0)
	v_add_f32_e32 v18, v16, v17
	v_lshlrev_b64 v[16:17], 6, v[92:93]
	v_lshl_add_u64 v[16:17], s[24:25], 0, v[16:17]
	v_lshl_add_u64 v[16:17], s[46:47], 2, v[16:17]
	s_lshl_b32 s18, s54, 2
	v_lshl_add_u64 v[16:17], v[16:17], 0, s[18:19]
	global_store_dword v[16:17], v18, off
.LBB0_1687:
	s_or_b64 exec, exec, s[48:49]
	s_waitcnt vmcnt(7)
	v_lshlrev_b32_e32 v16, 16, v68
	s_waitcnt lgkmcnt(0)
	v_and_b32_e32 v17, 0xffff0000, v68
	v_lshlrev_b32_e32 v18, 16, v69
	v_and_b32_e32 v19, 0xffff0000, v69
	v_lshlrev_b32_e32 v20, 16, v70
	v_and_b32_e32 v21, 0xffff0000, v70
	v_lshlrev_b32_e32 v22, 16, v71
	v_and_b32_e32 v23, 0xffff0000, v71
	v_pk_add_f32 v[14:15], v[14:15], v[18:19]
	v_pk_add_f32 v[12:13], v[12:13], v[16:17]
	v_pk_add_f32 v[16:17], v[10:11], v[22:23]
	v_pk_add_f32 v[10:11], v[8:9], v[20:21]
	v_mul_f32_e32 v8, v13, v13
	v_mul_f32_e32 v9, v15, v15
	v_fmac_f32_e32 v8, v12, v12
	v_fmac_f32_e32 v9, v14, v14
	v_add_f32_e32 v8, v8, v9
	v_mul_f32_e32 v9, v11, v11
	v_mul_f32_e32 v18, v17, v17
	v_fmac_f32_e32 v9, v10, v10
	v_fmac_f32_e32 v18, v16, v16
	v_add_f32_e32 v9, v9, v18
	v_add_f32_e32 v18, v8, v9
	v_cvt_pk_bf16_f32 v8, v12, v13
	v_lshl_add_u64 v[12:13], s[22:23], 0, v[90:91]
	v_cvt_pk_bf16_f32 v9, v14, v15
	v_cvt_pk_bf16_f32 v10, v10, v11
	v_cvt_pk_bf16_f32 v11, v16, v17
	v_lshl_add_u64 v[12:13], v[168:169], 1, v[12:13]
	global_store_dwordx4 v[12:13], v[8:11], off
	s_waitcnt vmcnt(7)
	v_lshlrev_b32_e32 v14, 16, v66
	v_and_b32_e32 v15, 0xffff0000, v66
	v_lshlrev_b32_e32 v8, 16, v64
	v_and_b32_e32 v9, 0xffff0000, v64
	v_lshlrev_b32_e32 v10, 16, v65
	v_and_b32_e32 v11, 0xffff0000, v65
	v_lshlrev_b32_e32 v16, 16, v67
	v_and_b32_e32 v17, 0xffff0000, v67
	v_pk_add_f32 v[6:7], v[6:7], v[10:11]
	v_pk_add_f32 v[4:5], v[4:5], v[8:9]
	v_pk_add_f32 v[8:9], v[2:3], v[16:17]
	v_pk_add_f32 v[2:3], v[0:1], v[14:15]
	v_mul_f32_e32 v0, v5, v5
	v_mul_f32_e32 v1, v7, v7
	v_fmac_f32_e32 v0, v4, v4
	v_fmac_f32_e32 v1, v6, v6
	v_add_f32_e32 v0, v0, v1
	v_mul_f32_e32 v1, v3, v3
	v_mul_f32_e32 v10, v9, v9
	v_fmac_f32_e32 v1, v2, v2
	v_fmac_f32_e32 v10, v8, v8
	v_add_f32_e32 v1, v1, v10
	v_add_f32_e32 v0, v0, v1
	v_add_f32_e32 v10, v18, v0
	v_cvt_pk_bf16_f32 v0, v4, v5
	v_cvt_pk_bf16_f32 v1, v6, v7
	v_cvt_pk_bf16_f32 v2, v2, v3
	v_cvt_pk_bf16_f32 v3, v8, v9
	global_store_dwordx4 v[12:13], v[0:3], off offset:256
	s_nop 1
	v_mov_b32_e32 v0, v201
	v_mov_b32_e32 v1, v201
	v_lshlrev_b32_e32 v0, 2, v0
	v_xor_b32_e32 v0, 64, v0
	v_mov_b32_e32 v0, v10
	s_nop 1
	v_permlane16_swap_b32_e32 v0, v10
	s_waitcnt lgkmcnt(0)
	v_add_f32_e32 v0, v10, v0
	v_lshlrev_b32_e32 v1, 2, v1
	v_xor_b32_e32 v1, 0x80, v1
	v_mov_b32_e32 v1, v0
	s_nop 1
	v_permlane32_swap_b32_e32 v1, v0
	s_and_saveexec_b64 s[48:49], s[8:9]
	s_cbranch_execz .LBB0_1689
	s_waitcnt lgkmcnt(0)
	v_add_f32_e32 v2, v0, v1
	v_lshlrev_b64 v[0:1], 6, v[88:89]
	v_lshl_add_u64 v[0:1], s[24:25], 0, v[0:1]
	v_lshl_add_u64 v[0:1], s[46:47], 2, v[0:1]
	s_lshl_b32 s18, s54, 2
	v_lshl_add_u64 v[0:1], v[0:1], 0, s[18:19]
	global_store_dword v[0:1], v2, off

; __device__ __forceinline__ float row_part(const float* ss, int row, int fq) { const f32x4 a = ((const f32x4*)(ss + (size_t)row * 16))[fq]; return (a[0] + a[1]) + (a[2] + a[3]); }
; __device__ __forceinline__ float row_finish(float t) { t += shx(t, 16); t += shx(t, 32); return __builtin_amdgcn_rsqf(t * (1.0f / 1024.0f) + RMS_EPS); }
;     __device__ __forceinline__ void operator()(const f32x4 (&acc)[2][2][4][2], const Unit& u, int wr, int wc, int fr, int fq) const {
;         const int g = u.pn * 4 + wc;
;         int mode = 0; const float* w = mqw; float sc = 1.f, nsc = 1.f;
;         if (g >= 36) { mode = 2; w = mqw; nsc = qscale; }
;         else if (diff) { if (g < 12) { mode = 2; w = qw; nsc = qscale; } else if (g < 24) { mode = 2; w = kw; } }
;         else { if (g >= 6 && g < 12) sc = 0.125f; else if (g >= 24) mode = 1; }
;         f32x4 wv[2][2];
; #pragma unroll
;         for (int bj = 0; bj < 2; ++bj)
; #pragma unroll
;             for (int n = 0; n < 2; ++n) wv[bj][n] = *(const f32x4*)(w + 32 * bj + 8 * fq + 4 * n) * nsc;
;         const int lcol = u.pn * 256 + 64 * wc + 8 * fq;
;         float rs[2][4];
; #pragma unroll
;         for (int ai = 0; ai < 2; ++ai)
; #pragma unroll
;             for (int m = 0; m < 4; ++m) rs[ai][m] = row_part(ss, u.pm * BM + ai * HALF + wr * 64 + m * 16 + fr, fq);
; #pragma unroll
;         for (int ai = 0; ai < 2; ++ai)
; #pragma unroll
;             for (int m = 0; m < 4; ++m) rs[ai][m] = row_finish(rs[ai][m]);
.LBB0_1759:
	s_lshl_b32 s4, s8, 2
	s_or_b32 s5, s4, s60
	s_cmp_lt_u32 s4, 24
	s_cselect_b32 s9, s57, s59
	s_cselect_b32 s23, s56, s58
	s_cmp_lt_i32 s5, 12
	s_cselect_b32 s23, s54, s23
	s_cselect_b32 s9, s55, s9
	s_sub_i32 s4, s4, 36
	s_cmp_lt_u32 s4, 0xffffffe8
	s_cselect_b64 vcc, -1, 0
	s_cmp_gt_i32 s5, 35
	s_cselect_b32 s49, s59, s9
	s_cselect_b32 s48, s58, s23
	global_load_dwordx4 v[148:151], v183, s[48:49] offset:16
	global_load_dwordx4 v[154:157], v183, s[48:49]
	global_load_dwordx4 v[162:165], v183, s[48:49] offset:144
	global_load_dwordx4 v[166:169], v183, s[48:49] offset:128
	s_cmp_lt_u32 s4, -12
	v_cndmask_b32_e32 v170, 1.0, v185, vcc
	s_cselect_b64 s[46:47], -1, 0
	s_lshl_b32 s23, s44, 8
	s_cmp_gt_u32 s4, -13
	s_waitcnt vmcnt(0)
	v_pk_mul_f32 v[146:147], v[170:171], v[150:151] op_sel_hi:[0,1]
	v_pk_mul_f32 v[152:153], v[170:171], v[156:157] op_sel_hi:[0,1]
	v_pk_mul_f32 v[156:157], v[170:171], v[154:155] op_sel_hi:[0,1]
	v_pk_mul_f32 v[148:149], v[170:171], v[148:149] op_sel_hi:[0,1]
	v_pk_mul_f32 v[158:159], v[170:171], v[168:169] op_sel_hi:[0,1]
	v_pk_mul_f32 v[160:161], v[170:171], v[166:167] op_sel_hi:[0,1]
	v_pk_mul_f32 v[150:151], v[170:171], v[164:165] op_sel_hi:[0,1]
	v_pk_mul_f32 v[154:155], v[170:171], v[162:163] op_sel_hi:[0,1]
	v_add_u32_e32 v170, s23, v174
	v_ashrrev_i32_e32 v171, 31, v170
	v_lshlrev_b64 v[162:163], 6, v[170:171]
	v_lshl_add_u64 v[162:163], v[136:137], 0, v[162:163]
	ds_read_b128 v[162:165], v239
	v_add_u32_e32 v168, 0x80, v170
	v_ashrrev_i32_e32 v169, 31, v168
	s_waitcnt lgkmcnt(0)
	v_mov_b32_e32 v166, v163
	v_mov_b32_e32 v167, v164
	v_mov_b32_e32 v163, v165
	v_pk_add_f32 v[162:163], v[166:167], v[162:163]
	v_add_u32_e32 v166, 0x90, v170
	v_add_f32_e32 v171, v162, v163
	v_or_b32_e32 v162, 16, v170
	v_ashrrev_i32_e32 v163, 31, v162
	v_lshlrev_b64 v[162:163], 6, v[162:163]
	v_lshl_add_u64 v[162:163], v[136:137], 0, v[162:163]
	ds_read_b128 v[162:165], v239 offset:1024
	v_ashrrev_i32_e32 v167, 31, v166
	s_waitcnt lgkmcnt(0)
	v_add_f32_e32 v162, v162, v163
	v_add_f32_e32 v163, v164, v165
	v_add_f32_e32 v190, v162, v163
	v_or_b32_e32 v162, 32, v170
	v_ashrrev_i32_e32 v163, 31, v162
	v_lshlrev_b64 v[162:163], 6, v[162:163]
	v_lshl_add_u64 v[162:163], v[136:137], 0, v[162:163]
	ds_read_b128 v[162:165], v239 offset:2048
	s_waitcnt lgkmcnt(0)
	v_add_f32_e32 v162, v162, v163
	v_add_f32_e32 v163, v164, v165
	v_add_f32_e32 v191, v162, v163
	v_or_b32_e32 v162, 48, v170
	v_ashrrev_i32_e32 v163, 31, v162
	v_lshlrev_b64 v[162:163], 6, v[162:163]
	v_lshl_add_u64 v[162:163], v[136:137], 0, v[162:163]
	ds_read_b128 v[162:165], v239 offset:3072
	s_waitcnt lgkmcnt(0)
	v_add_f32_e32 v162, v162, v163
	v_add_f32_e32 v163, v164, v165
	v_add_f32_e32 v195, v162, v163
	v_lshlrev_b64 v[162:163], 6, v[168:169]
	v_lshl_add_u64 v[162:163], v[136:137], 0, v[162:163]
	ds_read_b128 v[162:165], v239 offset:8192
	s_waitcnt lgkmcnt(0)
	v_add_f32_e32 v162, v162, v163
	v_add_f32_e32 v163, v164, v165
	v_add_f32_e32 v169, v162, v163
	v_lshlrev_b64 v[162:163], 6, v[166:167]
	v_lshl_add_u64 v[162:163], v[136:137], 0, v[162:163]
	ds_read_b128 v[162:165], v239 offset:9216
	s_waitcnt lgkmcnt(0)
	v_add_f32_e32 v162, v162, v163
	v_add_f32_e32 v163, v164, v165
	v_add_u32_e32 v164, 0xa0, v170
	v_ashrrev_i32_e32 v165, 31, v164
	v_add_f32_e32 v167, v162, v163
	v_lshlrev_b64 v[162:163], 6, v[164:165]
	v_lshl_add_u64 v[162:163], v[136:137], 0, v[162:163]
	ds_read_b128 v[186:189], v239 offset:10240
	s_waitcnt lgkmcnt(0)
	v_add_f32_e32 v162, v186, v187
	v_add_f32_e32 v163, v188, v189
	v_add_f32_e32 v165, v162, v163
	v_add_u32_e32 v162, 0xb0, v170
	v_ashrrev_i32_e32 v163, 31, v162
	v_lshlrev_b64 v[172:173], 6, v[162:163]
	v_lshl_add_u64 v[172:173], v[136:137], 0, v[172:173]
	ds_read_b128 v[186:189], v239 offset:11264
	s_waitcnt lgkmcnt(0)
	v_add_f32_e32 v163, v186, v187
	v_add_f32_e32 v172, v188, v189
	v_add_f32_e32 v163, v163, v172
	v_mov_b32_e32 v172, v201
	s_nop 0
	v_lshlrev_b32_e32 v172, 2, v172
	v_xor_b32_e32 v172, 64, v172
	v_mov_b32_e32 v172, v171
	s_nop 1
	v_permlane16_swap_b32_e32 v172, v171
	s_waitcnt lgkmcnt(0)
	v_add_f32_e32 v171, v171, v172
	v_mov_b32_e32 v172, v201
	s_nop 0
	v_lshlrev_b32_e32 v172, 2, v172
	v_xor_b32_e32 v172, 0x80, v172
	v_mov_b32_e32 v172, v171
	s_nop 1
	v_permlane32_swap_b32_e32 v172, v171
	s_waitcnt lgkmcnt(0)
	v_add_f32_e32 v171, v171, v172
	v_fmamk_f32 v171, v171, 0x3a800000, v184
	v_rsq_f32_e32 v196, v171
	v_mov_b32_e32 v171, v201
	v_pk_mul_f32 v[126:127], v[126:127], v[196:197] op_sel_hi:[1,0]
	v_lshlrev_b32_e32 v171, 2, v171
	v_xor_b32_e32 v171, 64, v171
	v_mov_b32_e32 v171, v190
	s_nop 1
	v_permlane16_swap_b32_e32 v171, v190
	v_pk_mul_f32 v[124:125], v[124:125], v[196:197] op_sel_hi:[1,0]
	v_pk_mul_f32 v[122:123], v[122:123], v[196:197] op_sel_hi:[1,0]
	v_pk_mul_f32 v[172:173], v[120:121], v[196:197] op_sel_hi:[1,0]
	v_pk_mul_f32 v[118:119], v[118:119], v[196:197] op_sel_hi:[1,0]
	s_waitcnt lgkmcnt(0)
	v_add_f32_e32 v193, v190, v171
	v_mov_b32_e32 v171, v201
	v_pk_mul_f32 v[116:117], v[116:117], v[196:197] op_sel_hi:[1,0]
	v_lshlrev_b32_e32 v171, 2, v171
	v_xor_b32_e32 v171, 0x80, v171
	v_mov_b32_e32 v194, v193
	s_nop 1
	v_permlane32_swap_b32_e32 v194, v193
	v_mov_b32_e32 v171, v201
	v_pk_mul_f32 v[114:115], v[114:115], v[196:197] op_sel_hi:[1,0]
	v_lshlrev_b32_e32 v171, 2, v171
	v_xor_b32_e32 v171, 64, v171
	v_mov_b32_e32 v171, v191
	s_nop 1
	v_permlane16_swap_b32_e32 v171, v191
	v_pk_mul_f32 v[120:121], v[112:113], v[196:197] op_sel_hi:[1,0]
	s_waitcnt lgkmcnt(0)
; __device__ __forceinline__ float row_finish(float t) { t += shx(t, 16); t += shx(t, 32); return __builtin_amdgcn_rsqf(t * (1.0f / 1024.0f) + RMS_EPS); }
; __device__ __forceinline__ float sq4(f32x4 v) { return (v[0] * v[0] + v[1] * v[1]) + (v[2] * v[2] + v[3] * v[3]); }
;     __device__ __forceinline__ void operator()(const f32x4 (&acc)[2][2][4][2], const Unit& u, int wr, int wc, int fr, int fq) const {
;     ...
;             for (int m = 0; m < 4; ++m) rs[ai][m] = row_finish(rs[ai][m]);
; #pragma unroll
;         for (int ai = 0; ai < 2; ++ai)
; #pragma unroll
;             for (int m = 0; m < 4; ++m) {
;                 const int row = u.pm * BM + ai * HALF + wr * 64 + m * 16 + fr;
;                 const float rstd = rs[ai][m];
;                 f32x4 v[2][2];
; #pragma unroll
;                 for (int bj = 0; bj < 2; ++bj)
; #pragma unroll
;                     for (int n = 0; n < 2; ++n) v[bj][n] = acc[ai][bj][m][n] * rstd;
;                 if (mode == 2) {
;                     float q = (sq4(v[0][0]) + sq4(v[0][1])) + (sq4(v[1][0]) + sq4(v[1][1]));
;                     q += shx(q, 16); q += shx(q, 32);
;                     const float r2 = __builtin_amdgcn_rsqf(q * (1.0f / 64.0f) + RMS_EPS);
; #pragma unroll
;                     for (int bj = 0; bj < 2; ++bj)
; #pragma unroll
;                         for (int n = 0; n < 2; ++n) v[bj][n] = v[bj][n] * r2 * wv[bj][n];
	v_add_f32_e32 v191, v191, v171
	v_mov_b32_e32 v171, v201
	s_nop 0
	v_lshlrev_b32_e32 v171, 2, v171
	v_xor_b32_e32 v171, 0x80, v171
	v_mov_b32_e32 v192, v191
	s_nop 1
	v_permlane32_swap_b32_e32 v192, v191
	v_mov_b32_e32 v171, v201
	s_nop 0
	v_lshlrev_b32_e32 v171, 2, v171
	v_xor_b32_e32 v171, 64, v171
	v_mov_b32_e32 v171, v195
	s_nop 1
	v_permlane16_swap_b32_e32 v171, v195
	s_waitcnt lgkmcnt(0)
	v_add_f32_e32 v189, v195, v171
	v_mov_b32_e32 v171, v201
	s_nop 0
	v_lshlrev_b32_e32 v171, 2, v171
	v_xor_b32_e32 v171, 0x80, v171
	v_mov_b32_e32 v190, v189
	s_nop 1
	v_permlane32_swap_b32_e32 v190, v189
	v_mov_b32_e32 v171, v201
	s_nop 0
	v_lshlrev_b32_e32 v171, 2, v171
	v_xor_b32_e32 v171, 64, v171
	v_mov_b32_e32 v171, v169
	s_nop 1
	v_permlane16_swap_b32_e32 v171, v169
	s_waitcnt lgkmcnt(0)
	v_add_f32_e32 v187, v169, v171
	v_mov_b32_e32 v169, v201
	s_nop 0
	v_lshlrev_b32_e32 v169, 2, v169
	v_xor_b32_e32 v169, 0x80, v169
	v_mov_b32_e32 v188, v187
	s_nop 1
	v_permlane32_swap_b32_e32 v188, v187
	v_mov_b32_e32 v169, v201
	s_nop 0
	v_lshlrev_b32_e32 v169, 2, v169
	v_xor_b32_e32 v169, 64, v169
	v_mov_b32_e32 v169, v167
	s_nop 1
	v_permlane16_swap_b32_e32 v169, v167
	s_waitcnt lgkmcnt(0)
	v_add_f32_e32 v171, v167, v169
	v_mov_b32_e32 v167, v201
	s_nop 0
	v_lshlrev_b32_e32 v167, 2, v167
	v_xor_b32_e32 v167, 0x80, v167
	v_mov_b32_e32 v186, v171
	s_nop 1
	v_permlane32_swap_b32_e32 v186, v171
	v_mov_b32_e32 v167, v201
	s_nop 0
	v_lshlrev_b32_e32 v167, 2, v167
	v_xor_b32_e32 v167, 64, v167
	v_mov_b32_e32 v167, v165
	s_nop 1
	v_permlane16_swap_b32_e32 v167, v165
	s_waitcnt lgkmcnt(0)
	v_add_f32_e32 v167, v165, v167
	v_mov_b32_e32 v165, v201
	s_nop 0
	v_lshlrev_b32_e32 v165, 2, v165
	v_xor_b32_e32 v165, 0x80, v165
	v_mov_b32_e32 v169, v167
	s_nop 1
	v_permlane32_swap_b32_e32 v169, v167
	v_mov_b32_e32 v165, v201
	s_nop 0
	v_lshlrev_b32_e32 v165, 2, v165
	v_xor_b32_e32 v165, 64, v165
	v_mov_b32_e32 v165, v163
	s_nop 1
	v_permlane16_swap_b32_e32 v165, v163
	s_waitcnt lgkmcnt(0)
	v_add_f32_e32 v163, v163, v165
	v_mov_b32_e32 v165, v201
	s_nop 0
	v_lshlrev_b32_e32 v165, 2, v165
	v_xor_b32_e32 v165, 0x80, v165
	v_mov_b32_e32 v165, v163
	s_nop 1
	v_permlane32_swap_b32_e32 v165, v163
	s_cbranch_scc1 .LBB0_1761
	v_mov_b32_e32 v196, v125
	v_mov_b32_e32 v197, v117
	v_mov_b32_e32 v112, v124
	v_mov_b32_e32 v113, v116
	v_pk_mul_f32 v[196:197], v[196:197], v[196:197]
	v_mov_b32_e32 v198, v127
	v_mov_b32_e32 v199, v119
	v_pk_fma_f32 v[112:113], v[112:113], v[112:113], v[196:197]
	v_mov_b32_e32 v196, v126
	v_mov_b32_e32 v197, v118
	v_pk_mul_f32 v[198:199], v[198:199], v[198:199]
	v_mov_b32_e32 v202, v123
	v_pk_fma_f32 v[196:197], v[196:197], v[196:197], v[198:199]
	v_mov_b32_e32 v198, v173
	v_mov_b32_e32 v199, v121
	v_pk_add_f32 v[112:113], v[112:113], v[196:197]
	v_mov_b32_e32 v196, v172
	v_mov_b32_e32 v197, v120
	v_pk_mul_f32 v[198:199], v[198:199], v[198:199]
	v_mov_b32_e32 v203, v115
	v_pk_fma_f32 v[196:197], v[196:197], v[196:197], v[198:199]
	v_mov_b32_e32 v198, v122
	v_mov_b32_e32 v199, v114
	v_pk_mul_f32 v[202:203], v[202:203], v[202:203]
	s_nop 0
	v_pk_fma_f32 v[198:199], v[198:199], v[198:199], v[202:203]
	s_nop 0
	v_pk_add_f32 v[196:197], v[196:197], v[198:199]
	s_nop 0
	v_pk_add_f32 v[112:113], v[112:113], v[196:197]
	s_nop 0
	v_add_f32_e32 v112, v112, v113
	v_mov_b32_e32 v113, v201
	s_nop 0
	v_lshlrev_b32_e32 v113, 2, v113
	v_xor_b32_e32 v113, 64, v113
	v_mov_b32_e32 v113, v112
	s_nop 1
	v_permlane16_swap_b32_e32 v113, v112
	s_waitcnt lgkmcnt(0)
	v_add_f32_e32 v112, v112, v113
	v_mov_b32_e32 v113, v201
	s_nop 0
	v_lshlrev_b32_e32 v113, 2, v113
	v_xor_b32_e32 v113, 0x80, v113
	v_mov_b32_e32 v113, v112
	s_nop 1
	v_permlane32_swap_b32_e32 v113, v112
	s_waitcnt lgkmcnt(0)
	v_add_f32_e32 v112, v112, v113
	v_fmamk_f32 v112, v112, 0x3c800000, v184
	v_rsq_f32_e32 v112, v112
	s_nop 0
	v_pk_mul_f32 v[124:125], v[124:125], v[112:113] op_sel_hi:[1,0]
	v_pk_mul_f32 v[126:127], v[126:127], v[112:113] op_sel_hi:[1,0]
	v_pk_mul_f32 v[172:173], v[172:173], v[112:113] op_sel_hi:[1,0]
	v_pk_mul_f32 v[122:123], v[122:123], v[112:113] op_sel_hi:[1,0]
	v_pk_mul_f32 v[116:117], v[116:117], v[112:113] op_sel_hi:[1,0]
	v_pk_mul_f32 v[118:119], v[118:119], v[112:113] op_sel_hi:[1,0]
	v_pk_mul_f32 v[120:121], v[120:121], v[112:113] op_sel_hi:[1,0]
	v_pk_mul_f32 v[112:113], v[114:115], v[112:113] op_sel_hi:[1,0]
	v_pk_mul_f32 v[126:127], v[152:153], v[126:127]
	v_pk_mul_f32 v[124:125], v[156:157], v[124:125]
	v_pk_mul_f32 v[122:123], v[146:147], v[122:123]
	v_pk_mul_f32 v[172:173], v[148:149], v[172:173]
	v_pk_mul_f32 v[118:119], v[158:159], v[118:119]
	v_pk_mul_f32 v[116:117], v[160:161], v[116:117]
	v_pk_mul_f32 v[114:115], v[150:151], v[112:113]
	v_pk_mul_f32 v[120:121], v[154:155], v[120:121]
; __device__ __forceinline__ f32x4 silu4(f32x4 v) { return (f32x4){silu_f(v[0]), silu_f(v[1]), silu_f(v[2]), silu_f(v[3])}; }
; __device__ __forceinline__ float sq4(f32x4 v) { return (v[0] * v[0] + v[1] * v[1]) + (v[2] * v[2] + v[3] * v[3]); }
; __device__ __forceinline__ u32x4 pack8(f32x4 a, f32x4 b) { u32x4 w; w.x = cvt_pk_bf16(a[0], a[1]); w.y = cvt_pk_bf16(a[2], a[3]); w.z = cvt_pk_bf16(b[0], b[1]); w.w = cvt_pk_bf16(b[2], b[3]); return w; }
;     __device__ __forceinline__ void operator()(const f32x4 (&acc)[2][2][4][2], const Unit& u, int wr, int wc, int fr, int fq) const {
;     ...
;         for (int ai = 0; ai < 2; ++ai)
; #pragma unroll
;             for (int m = 0; m < 4; ++m) {
;                 const int row = u.pm * BM + ai * HALF + wr * 64 + m * 16 + fr;
;                 const float rstd = rs[ai][m];
;                 f32x4 v[2][2];
; #pragma unroll
;                 for (int bj = 0; bj < 2; ++bj)
; #pragma unroll
;                     for (int n = 0; n < 2; ++n) v[bj][n] = acc[ai][bj][m][n] * rstd;
;                 if (mode == 2) {
;                     float q = (sq4(v[0][0]) + sq4(v[0][1])) + (sq4(v[1][0]) + sq4(v[1][1]));
;                     q += shx(q, 16); q += shx(q, 32);
;                     const float r2 = __builtin_amdgcn_rsqf(q * (1.0f / 64.0f) + RMS_EPS);
; #pragma unroll
;                     for (int bj = 0; bj < 2; ++bj)
; #pragma unroll
;                         for (int n = 0; n < 2; ++n) v[bj][n] = v[bj][n] * r2 * wv[bj][n];
;                 } else if (mode == 1) {
; #pragma unroll
;                     for (int bj = 0; bj < 2; ++bj)
; #pragma unroll
;                         for (int n = 0; n < 2; ++n) v[bj][n] = silu4(v[bj][n]);
;                 } else {
; #pragma unroll
;                     for (int bj = 0; bj < 2; ++bj)
; #pragma unroll
;                         for (int n = 0; n < 2; ++n) v[bj][n] = v[bj][n] * sc;
;                 }
;                 bf16_t* rowp = U + (size_t)row * 2560 + lcol;
; #pragma unroll
;                 for (int bj = 0; bj < 2; ++bj) *(u32x4*)(rowp + 32 * bj) = pack8(v[bj][0], v[bj][1]);
.LBB0_1761:
	v_add_f32_e32 v112, v193, v194
	v_fmamk_f32 v112, v112, 0x3a800000, v184
	v_rsq_f32_e32 v194, v112
	v_lshl_or_b32 v112, s8, 8, v179
	v_mov_b64_e32 v[196:197], s[20:21]
	v_ashrrev_i32_e32 v113, 31, v112
	v_mad_i64_i32 v[196:197], s[8:9], v170, s68, v[196:197]
	v_lshl_add_u64 v[196:197], v[112:113], 1, v[196:197]
	v_cvt_pk_bf16_f32 v124, v124, v125
	v_cvt_pk_bf16_f32 v125, v126, v127
	v_cvt_pk_bf16_f32 v126, v172, v173
	v_cvt_pk_bf16_f32 v127, v122, v123
	global_store_dwordx4 v[196:197], v[124:127], off
	v_cvt_pk_bf16_f32 v116, v116, v117
	v_cvt_pk_bf16_f32 v117, v118, v119
	v_cvt_pk_bf16_f32 v118, v120, v121
	v_cvt_pk_bf16_f32 v119, v114, v115
	v_cndmask_b32_e64 v114, 0, 1, s[46:47]
	v_pk_mul_f32 v[110:111], v[110:111], v[194:195] op_sel_hi:[1,0]
	v_pk_mul_f32 v[108:109], v[108:109], v[194:195] op_sel_hi:[1,0]
	v_pk_mul_f32 v[106:107], v[106:107], v[194:195] op_sel_hi:[1,0]
	v_pk_mul_f32 v[104:105], v[104:105], v[194:195] op_sel_hi:[1,0]
	v_pk_mul_f32 v[102:103], v[102:103], v[194:195] op_sel_hi:[1,0]
	v_pk_mul_f32 v[100:101], v[100:101], v[194:195] op_sel_hi:[1,0]
	v_pk_mul_f32 v[98:99], v[98:99], v[194:195] op_sel_hi:[1,0]
	v_cmp_ne_u32_e64 s[8:9], 1, v114
	s_andn2_b64 vcc, exec, s[46:47]
	v_pk_mul_f32 v[96:97], v[96:97], v[194:195] op_sel_hi:[1,0]
	global_store_dwordx4 v[196:197], v[116:119], off offset:64
	s_cbranch_vccnz .LBB0_1763
	s_nop 0
	v_mov_b32_e32 v116, v109
	v_mov_b32_e32 v117, v101
	v_mov_b32_e32 v114, v108
	v_mov_b32_e32 v115, v100
	v_pk_mul_f32 v[116:117], v[116:117], v[116:117]
	v_mov_b32_e32 v118, v111
	v_mov_b32_e32 v119, v103
	v_pk_fma_f32 v[114:115], v[114:115], v[114:115], v[116:117]
	v_mov_b32_e32 v116, v110
	v_mov_b32_e32 v117, v102
	v_pk_mul_f32 v[118:119], v[118:119], v[118:119]
	v_mov_b32_e32 v120, v107
	v_pk_fma_f32 v[116:117], v[116:117], v[116:117], v[118:119]
	v_mov_b32_e32 v118, v105
	v_mov_b32_e32 v119, v97
	v_pk_add_f32 v[114:115], v[114:115], v[116:117]
	v_mov_b32_e32 v116, v104
	v_mov_b32_e32 v117, v96
	v_pk_mul_f32 v[118:119], v[118:119], v[118:119]
	v_mov_b32_e32 v121, v99
	v_pk_fma_f32 v[116:117], v[116:117], v[116:117], v[118:119]
	v_mov_b32_e32 v118, v106
	v_mov_b32_e32 v119, v98
	v_pk_mul_f32 v[120:121], v[120:121], v[120:121]
	s_nop 0
	v_pk_fma_f32 v[118:119], v[118:119], v[118:119], v[120:121]
	s_nop 0
	v_pk_add_f32 v[116:117], v[116:117], v[118:119]
	s_nop 0
	v_pk_add_f32 v[114:115], v[114:115], v[116:117]
	s_nop 0
	v_add_f32_e32 v114, v114, v115
	v_mov_b32_e32 v115, v201
	s_nop 0
	v_lshlrev_b32_e32 v115, 2, v115
	v_xor_b32_e32 v115, 64, v115
	v_mov_b32_e32 v115, v114
	s_nop 1
	v_permlane16_swap_b32_e32 v115, v114
	s_waitcnt lgkmcnt(0)
	v_add_f32_e32 v114, v114, v115
	v_mov_b32_e32 v115, v201
	s_nop 0
	v_lshlrev_b32_e32 v115, 2, v115
	v_xor_b32_e32 v115, 0x80, v115
	v_mov_b32_e32 v115, v114
	s_nop 1
	v_permlane32_swap_b32_e32 v115, v114
	s_waitcnt lgkmcnt(0)
	v_add_f32_e32 v114, v114, v115
	v_fmamk_f32 v114, v114, 0x3c800000, v184
	v_rsq_f32_e32 v114, v114
	s_nop 0
	v_pk_mul_f32 v[108:109], v[108:109], v[114:115] op_sel_hi:[1,0]
	v_pk_mul_f32 v[110:111], v[110:111], v[114:115] op_sel_hi:[1,0]
	v_pk_mul_f32 v[104:105], v[104:105], v[114:115] op_sel_hi:[1,0]
	v_pk_mul_f32 v[106:107], v[106:107], v[114:115] op_sel_hi:[1,0]
	v_pk_mul_f32 v[100:101], v[100:101], v[114:115] op_sel_hi:[1,0]
	v_pk_mul_f32 v[102:103], v[102:103], v[114:115] op_sel_hi:[1,0]
	v_pk_mul_f32 v[96:97], v[96:97], v[114:115] op_sel_hi:[1,0]
	v_pk_mul_f32 v[98:99], v[98:99], v[114:115] op_sel_hi:[1,0]
	v_pk_mul_f32 v[110:111], v[152:153], v[110:111]
	v_pk_mul_f32 v[108:109], v[156:157], v[108:109]
	v_pk_mul_f32 v[106:107], v[146:147], v[106:107]
	v_pk_mul_f32 v[104:105], v[148:149], v[104:105]
	v_pk_mul_f32 v[102:103], v[158:159], v[102:103]
	v_pk_mul_f32 v[100:101], v[160:161], v[100:101]
	v_pk_mul_f32 v[98:99], v[150:151], v[98:99]
	v_pk_mul_f32 v[96:97], v[154:155], v[96:97]
.LBB0_1763:
	v_add_f32_e32 v114, v191, v192
	v_fmamk_f32 v114, v114, 0x3a800000, v184
	v_rsq_f32_e32 v114, v114
	v_add_u32_e32 v115, s23, v176
	v_mov_b64_e32 v[116:117], s[20:21]
	v_mad_i64_i32 v[116:117], s[46:47], v115, s68, v[116:117]
	v_lshl_add_u64 v[116:117], v[112:113], 1, v[116:117]
	v_pk_mul_f32 v[94:95], v[94:95], v[114:115] op_sel_hi:[1,0]
	v_pk_mul_f32 v[92:93], v[92:93], v[114:115] op_sel_hi:[1,0]
	v_pk_mul_f32 v[90:91], v[90:91], v[114:115] op_sel_hi:[1,0]
	v_pk_mul_f32 v[88:89], v[88:89], v[114:115] op_sel_hi:[1,0]
	v_pk_mul_f32 v[86:87], v[86:87], v[114:115] op_sel_hi:[1,0]
	v_pk_mul_f32 v[84:85], v[84:85], v[114:115] op_sel_hi:[1,0]
	v_pk_mul_f32 v[82:83], v[82:83], v[114:115] op_sel_hi:[1,0]
	s_and_b64 vcc, exec, s[8:9]
	v_pk_mul_f32 v[80:81], v[80:81], v[114:115] op_sel_hi:[1,0]
	v_cvt_pk_bf16_f32 v108, v108, v109
	v_cvt_pk_bf16_f32 v109, v110, v111
	v_cvt_pk_bf16_f32 v110, v104, v105
	v_cvt_pk_bf16_f32 v111, v106, v107
	global_store_dwordx4 v[116:117], v[108:111], off
	v_cvt_pk_bf16_f32 v100, v100, v101
	v_cvt_pk_bf16_f32 v101, v102, v103
	v_cvt_pk_bf16_f32 v102, v96, v97
	v_cvt_pk_bf16_f32 v103, v98, v99
	global_store_dwordx4 v[116:117], v[100:103], off offset:64
	s_cbranch_vccnz .LBB0_1765
; __device__ __forceinline__ f32x4 silu4(f32x4 v) { return (f32x4){silu_f(v[0]), silu_f(v[1]), silu_f(v[2]), silu_f(v[3])}; }
; __device__ __forceinline__ float sq4(f32x4 v) { return (v[0] * v[0] + v[1] * v[1]) + (v[2] * v[2] + v[3] * v[3]); }
; __device__ __forceinline__ u32x4 pack8(f32x4 a, f32x4 b) { u32x4 w; w.x = cvt_pk_bf16(a[0], a[1]); w.y = cvt_pk_bf16(a[2], a[3]); w.z = cvt_pk_bf16(b[0], b[1]); w.w = cvt_pk_bf16(b[2], b[3]); return w; }
;     __device__ __forceinline__ void operator()(const f32x4 (&acc)[2][2][4][2], const Unit& u, int wr, int wc, int fr, int fq) const {
;     ...
;         for (int ai = 0; ai < 2; ++ai)
; #pragma unroll
;             for (int m = 0; m < 4; ++m) {
;                 const int row = u.pm * BM + ai * HALF + wr * 64 + m * 16 + fr;
;                 const float rstd = rs[ai][m];
;                 f32x4 v[2][2];
; #pragma unroll
;                 for (int bj = 0; bj < 2; ++bj)
; #pragma unroll
;                     for (int n = 0; n < 2; ++n) v[bj][n] = acc[ai][bj][m][n] * rstd;
;                 if (mode == 2) {
;                     float q = (sq4(v[0][0]) + sq4(v[0][1])) + (sq4(v[1][0]) + sq4(v[1][1]));
;                     q += shx(q, 16); q += shx(q, 32);
;                     const float r2 = __builtin_amdgcn_rsqf(q * (1.0f / 64.0f) + RMS_EPS);
; #pragma unroll
;                     for (int bj = 0; bj < 2; ++bj)
; #pragma unroll
;                         for (int n = 0; n < 2; ++n) v[bj][n] = v[bj][n] * r2 * wv[bj][n];
;                 } else if (mode == 1) {
; #pragma unroll
;                     for (int bj = 0; bj < 2; ++bj)
; #pragma unroll
;                         for (int n = 0; n < 2; ++n) v[bj][n] = silu4(v[bj][n]);
;                 } else {
; #pragma unroll
;                     for (int bj = 0; bj < 2; ++bj)
; #pragma unroll
;                         for (int n = 0; n < 2; ++n) v[bj][n] = v[bj][n] * sc;
;                 }
;                 bf16_t* rowp = U + (size_t)row * 2560 + lcol;
; #pragma unroll
;                 for (int bj = 0; bj < 2; ++bj) *(u32x4*)(rowp + 32 * bj) = pack8(v[bj][0], v[bj][1]);
	v_mov_b32_e32 v98, v93
	v_mov_b32_e32 v99, v85
	v_mov_b32_e32 v96, v92
	v_mov_b32_e32 v97, v84
	v_pk_mul_f32 v[98:99], v[98:99], v[98:99]
	v_mov_b32_e32 v100, v95
	v_mov_b32_e32 v101, v87
	v_pk_fma_f32 v[96:97], v[96:97], v[96:97], v[98:99]
	v_mov_b32_e32 v98, v94
	v_mov_b32_e32 v99, v86
	v_pk_mul_f32 v[100:101], v[100:101], v[100:101]
	v_mov_b32_e32 v102, v91
	v_pk_fma_f32 v[98:99], v[98:99], v[98:99], v[100:101]
	v_mov_b32_e32 v100, v89
	v_mov_b32_e32 v101, v81
	v_pk_add_f32 v[96:97], v[96:97], v[98:99]
	v_mov_b32_e32 v98, v88
	v_mov_b32_e32 v99, v80
	v_pk_mul_f32 v[100:101], v[100:101], v[100:101]
	v_mov_b32_e32 v103, v83
	v_pk_fma_f32 v[98:99], v[98:99], v[98:99], v[100:101]
	v_mov_b32_e32 v100, v90
	v_mov_b32_e32 v101, v82
	v_pk_mul_f32 v[102:103], v[102:103], v[102:103]
	s_nop 0
	v_pk_fma_f32 v[100:101], v[100:101], v[100:101], v[102:103]
	s_nop 0
	v_pk_add_f32 v[98:99], v[98:99], v[100:101]
	s_nop 0
	v_pk_add_f32 v[96:97], v[96:97], v[98:99]
	s_nop 0
	v_add_f32_e32 v96, v96, v97
	v_mov_b32_e32 v97, v201
	s_nop 0
	v_lshlrev_b32_e32 v97, 2, v97
	v_xor_b32_e32 v97, 64, v97
	v_mov_b32_e32 v97, v96
	s_nop 1
	v_permlane16_swap_b32_e32 v97, v96
	s_waitcnt lgkmcnt(0)
	v_add_f32_e32 v96, v96, v97
	v_mov_b32_e32 v97, v201
	s_nop 0
	v_lshlrev_b32_e32 v97, 2, v97
	v_xor_b32_e32 v97, 0x80, v97
	v_mov_b32_e32 v97, v96
	s_nop 1
	v_permlane32_swap_b32_e32 v97, v96
	s_waitcnt lgkmcnt(0)
	v_add_f32_e32 v96, v96, v97
	v_fmamk_f32 v96, v96, 0x3c800000, v184
	v_rsq_f32_e32 v96, v96
	s_nop 0
	v_pk_mul_f32 v[92:93], v[92:93], v[96:97] op_sel_hi:[1,0]
	v_pk_mul_f32 v[94:95], v[94:95], v[96:97] op_sel_hi:[1,0]
	v_pk_mul_f32 v[88:89], v[88:89], v[96:97] op_sel_hi:[1,0]
	v_pk_mul_f32 v[90:91], v[90:91], v[96:97] op_sel_hi:[1,0]
	v_pk_mul_f32 v[84:85], v[84:85], v[96:97] op_sel_hi:[1,0]
	v_pk_mul_f32 v[86:87], v[86:87], v[96:97] op_sel_hi:[1,0]
	v_pk_mul_f32 v[80:81], v[80:81], v[96:97] op_sel_hi:[1,0]
	v_pk_mul_f32 v[82:83], v[82:83], v[96:97] op_sel_hi:[1,0]
	v_pk_mul_f32 v[94:95], v[152:153], v[94:95]
	v_pk_mul_f32 v[92:93], v[156:157], v[92:93]
	v_pk_mul_f32 v[90:91], v[146:147], v[90:91]
	v_pk_mul_f32 v[88:89], v[148:149], v[88:89]
	v_pk_mul_f32 v[86:87], v[158:159], v[86:87]
	v_pk_mul_f32 v[84:85], v[160:161], v[84:85]
	v_pk_mul_f32 v[82:83], v[150:151], v[82:83]
	v_pk_mul_f32 v[80:81], v[154:155], v[80:81]
.LBB0_1765:
	v_add_f32_e32 v96, v189, v190
	v_fmamk_f32 v96, v96, 0x3a800000, v184
	v_rsq_f32_e32 v96, v96
	v_add_u32_e32 v97, s23, v177
	v_mov_b64_e32 v[98:99], s[20:21]
	v_mad_i64_i32 v[98:99], s[46:47], v97, s68, v[98:99]
	v_lshl_add_u64 v[98:99], v[112:113], 1, v[98:99]
	v_pk_mul_f32 v[78:79], v[78:79], v[96:97] op_sel_hi:[1,0]
	v_pk_mul_f32 v[76:77], v[76:77], v[96:97] op_sel_hi:[1,0]
	v_pk_mul_f32 v[74:75], v[74:75], v[96:97] op_sel_hi:[1,0]
	v_pk_mul_f32 v[72:73], v[72:73], v[96:97] op_sel_hi:[1,0]
	v_pk_mul_f32 v[70:71], v[70:71], v[96:97] op_sel_hi:[1,0]
	v_pk_mul_f32 v[68:69], v[68:69], v[96:97] op_sel_hi:[1,0]
	v_pk_mul_f32 v[66:67], v[66:67], v[96:97] op_sel_hi:[1,0]
	s_and_b64 vcc, exec, s[8:9]
	v_pk_mul_f32 v[64:65], v[64:65], v[96:97] op_sel_hi:[1,0]
	v_cvt_pk_bf16_f32 v92, v92, v93
	v_cvt_pk_bf16_f32 v93, v94, v95
	v_cvt_pk_bf16_f32 v94, v88, v89
	v_cvt_pk_bf16_f32 v95, v90, v91
	global_store_dwordx4 v[98:99], v[92:95], off
	v_cvt_pk_bf16_f32 v84, v84, v85
	v_cvt_pk_bf16_f32 v85, v86, v87
	v_cvt_pk_bf16_f32 v86, v80, v81
	v_cvt_pk_bf16_f32 v87, v82, v83
	global_store_dwordx4 v[98:99], v[84:87], off offset:64
	s_cbranch_vccnz .LBB0_1767
	v_mov_b32_e32 v82, v77
	v_mov_b32_e32 v83, v69
	v_mov_b32_e32 v80, v76
	v_mov_b32_e32 v81, v68
	v_pk_mul_f32 v[82:83], v[82:83], v[82:83]
	v_mov_b32_e32 v84, v79
	v_mov_b32_e32 v85, v71
	v_pk_fma_f32 v[80:81], v[80:81], v[80:81], v[82:83]
	v_mov_b32_e32 v82, v78
	v_mov_b32_e32 v83, v70
	v_pk_mul_f32 v[84:85], v[84:85], v[84:85]
	v_mov_b32_e32 v86, v75
	v_pk_fma_f32 v[82:83], v[82:83], v[82:83], v[84:85]
	v_mov_b32_e32 v84, v73
	v_mov_b32_e32 v85, v65
	v_pk_add_f32 v[80:81], v[80:81], v[82:83]
	v_mov_b32_e32 v82, v72
	v_mov_b32_e32 v83, v64
	v_pk_mul_f32 v[84:85], v[84:85], v[84:85]
	v_mov_b32_e32 v87, v67
	v_pk_fma_f32 v[82:83], v[82:83], v[82:83], v[84:85]
	v_mov_b32_e32 v84, v74
	v_mov_b32_e32 v85, v66
	v_pk_mul_f32 v[86:87], v[86:87], v[86:87]
	s_nop 0
	v_pk_fma_f32 v[84:85], v[84:85], v[84:85], v[86:87]
	s_nop 0
	v_pk_add_f32 v[82:83], v[82:83], v[84:85]
	s_nop 0
	v_pk_add_f32 v[80:81], v[80:81], v[82:83]
	s_nop 0
	v_add_f32_e32 v80, v80, v81
	v_mov_b32_e32 v81, v201
	s_nop 0
	v_lshlrev_b32_e32 v81, 2, v81
	v_xor_b32_e32 v81, 64, v81
	v_mov_b32_e32 v81, v80
	s_nop 1
	v_permlane16_swap_b32_e32 v81, v80
	s_waitcnt lgkmcnt(0)
	v_add_f32_e32 v80, v80, v81
	v_mov_b32_e32 v81, v201
	s_nop 0
	v_lshlrev_b32_e32 v81, 2, v81
	v_xor_b32_e32 v81, 0x80, v81
	v_mov_b32_e32 v81, v80
	s_nop 1
	v_permlane32_swap_b32_e32 v81, v80
	s_waitcnt lgkmcnt(0)
	v_add_f32_e32 v80, v80, v81
	v_fmamk_f32 v80, v80, 0x3c800000, v184
	v_rsq_f32_e32 v80, v80
	s_nop 0
	v_pk_mul_f32 v[76:77], v[76:77], v[80:81] op_sel_hi:[1,0]
	v_pk_mul_f32 v[78:79], v[78:79], v[80:81] op_sel_hi:[1,0]
	v_pk_mul_f32 v[72:73], v[72:73], v[80:81] op_sel_hi:[1,0]
	v_pk_mul_f32 v[74:75], v[74:75], v[80:81] op_sel_hi:[1,0]
	v_pk_mul_f32 v[68:69], v[68:69], v[80:81] op_sel_hi:[1,0]
	v_pk_mul_f32 v[70:71], v[70:71], v[80:81] op_sel_hi:[1,0]
	v_pk_mul_f32 v[64:65], v[64:65], v[80:81] op_sel_hi:[1,0]
	v_pk_mul_f32 v[66:67], v[66:67], v[80:81] op_sel_hi:[1,0]
	v_pk_mul_f32 v[78:79], v[152:153], v[78:79]
	v_pk_mul_f32 v[76:77], v[156:157], v[76:77]
	v_pk_mul_f32 v[74:75], v[146:147], v[74:75]
	v_pk_mul_f32 v[72:73], v[148:149], v[72:73]
	v_pk_mul_f32 v[70:71], v[158:159], v[70:71]
	v_pk_mul_f32 v[68:69], v[160:161], v[68:69]
	v_pk_mul_f32 v[66:67], v[150:151], v[66:67]
	v_pk_mul_f32 v[64:65], v[154:155], v[64:65]
; __device__ __forceinline__ f32x4 silu4(f32x4 v) { return (f32x4){silu_f(v[0]), silu_f(v[1]), silu_f(v[2]), silu_f(v[3])}; }
; __device__ __forceinline__ float sq4(f32x4 v) { return (v[0] * v[0] + v[1] * v[1]) + (v[2] * v[2] + v[3] * v[3]); }
; __device__ __forceinline__ u32x4 pack8(f32x4 a, f32x4 b) { u32x4 w; w.x = cvt_pk_bf16(a[0], a[1]); w.y = cvt_pk_bf16(a[2], a[3]); w.z = cvt_pk_bf16(b[0], b[1]); w.w = cvt_pk_bf16(b[2], b[3]); return w; }
;     __device__ __forceinline__ void operator()(const f32x4 (&acc)[2][2][4][2], const Unit& u, int wr, int wc, int fr, int fq) const {
;     ...
;         for (int ai = 0; ai < 2; ++ai)
; #pragma unroll
;             for (int m = 0; m < 4; ++m) {
;                 const int row = u.pm * BM + ai * HALF + wr * 64 + m * 16 + fr;
;                 const float rstd = rs[ai][m];
;                 f32x4 v[2][2];
; #pragma unroll
;                 for (int bj = 0; bj < 2; ++bj)
; #pragma unroll
;                     for (int n = 0; n < 2; ++n) v[bj][n] = acc[ai][bj][m][n] * rstd;
;                 if (mode == 2) {
;                     float q = (sq4(v[0][0]) + sq4(v[0][1])) + (sq4(v[1][0]) + sq4(v[1][1]));
;                     q += shx(q, 16); q += shx(q, 32);
;                     const float r2 = __builtin_amdgcn_rsqf(q * (1.0f / 64.0f) + RMS_EPS);
; #pragma unroll
;                     for (int bj = 0; bj < 2; ++bj)
; #pragma unroll
;                         for (int n = 0; n < 2; ++n) v[bj][n] = v[bj][n] * r2 * wv[bj][n];
;                 } else if (mode == 1) {
; #pragma unroll
;                     for (int bj = 0; bj < 2; ++bj)
; #pragma unroll
;                         for (int n = 0; n < 2; ++n) v[bj][n] = silu4(v[bj][n]);
;                 } else {
; #pragma unroll
;                     for (int bj = 0; bj < 2; ++bj)
; #pragma unroll
;                         for (int n = 0; n < 2; ++n) v[bj][n] = v[bj][n] * sc;
;                 }
;                 bf16_t* rowp = U + (size_t)row * 2560 + lcol;
; #pragma unroll
;                 for (int bj = 0; bj < 2; ++bj) *(u32x4*)(rowp + 32 * bj) = pack8(v[bj][0], v[bj][1]);
.LBB0_1767:
	v_add_f32_e32 v80, v187, v188
	v_fmamk_f32 v80, v80, 0x3a800000, v184
	v_rsq_f32_e32 v80, v80
	v_add_u32_e32 v81, s23, v178
	v_mov_b64_e32 v[82:83], s[20:21]
	v_mad_i64_i32 v[82:83], s[46:47], v81, s68, v[82:83]
	v_lshl_add_u64 v[82:83], v[112:113], 1, v[82:83]
	v_pk_mul_f32 v[62:63], v[62:63], v[80:81] op_sel_hi:[1,0]
	v_pk_mul_f32 v[60:61], v[60:61], v[80:81] op_sel_hi:[1,0]
	v_pk_mul_f32 v[58:59], v[58:59], v[80:81] op_sel_hi:[1,0]
	v_pk_mul_f32 v[56:57], v[56:57], v[80:81] op_sel_hi:[1,0]
	v_pk_mul_f32 v[54:55], v[54:55], v[80:81] op_sel_hi:[1,0]
	v_pk_mul_f32 v[52:53], v[52:53], v[80:81] op_sel_hi:[1,0]
	v_pk_mul_f32 v[50:51], v[50:51], v[80:81] op_sel_hi:[1,0]
	s_and_b64 vcc, exec, s[8:9]
	v_pk_mul_f32 v[48:49], v[48:49], v[80:81] op_sel_hi:[1,0]
	v_cvt_pk_bf16_f32 v76, v76, v77
	v_cvt_pk_bf16_f32 v77, v78, v79
	v_cvt_pk_bf16_f32 v78, v72, v73
	v_cvt_pk_bf16_f32 v79, v74, v75
	global_store_dwordx4 v[82:83], v[76:79], off
	v_cvt_pk_bf16_f32 v68, v68, v69
	v_cvt_pk_bf16_f32 v69, v70, v71
	v_cvt_pk_bf16_f32 v70, v64, v65
	v_cvt_pk_bf16_f32 v71, v66, v67
	global_store_dwordx4 v[82:83], v[68:71], off offset:64
	s_cbranch_vccnz .LBB0_1769
	v_mov_b32_e32 v66, v61
	v_mov_b32_e32 v67, v53
	v_mov_b32_e32 v64, v60
	v_mov_b32_e32 v65, v52
	v_pk_mul_f32 v[66:67], v[66:67], v[66:67]
	v_mov_b32_e32 v68, v63
	v_mov_b32_e32 v69, v55
	v_pk_fma_f32 v[64:65], v[64:65], v[64:65], v[66:67]
	v_mov_b32_e32 v66, v62
	v_mov_b32_e32 v67, v54
	v_pk_mul_f32 v[68:69], v[68:69], v[68:69]
	v_mov_b32_e32 v70, v59
	v_pk_fma_f32 v[66:67], v[66:67], v[66:67], v[68:69]
	v_mov_b32_e32 v68, v57
	v_mov_b32_e32 v69, v49
	v_pk_add_f32 v[64:65], v[64:65], v[66:67]
	v_mov_b32_e32 v66, v56
	v_mov_b32_e32 v67, v48
	v_pk_mul_f32 v[68:69], v[68:69], v[68:69]
	v_mov_b32_e32 v71, v51
	v_pk_fma_f32 v[66:67], v[66:67], v[66:67], v[68:69]
	v_mov_b32_e32 v68, v58
	v_mov_b32_e32 v69, v50
	v_pk_mul_f32 v[70:71], v[70:71], v[70:71]
	s_nop 0
	v_pk_fma_f32 v[68:69], v[68:69], v[68:69], v[70:71]
	s_nop 0
	v_pk_add_f32 v[66:67], v[66:67], v[68:69]
	s_nop 0
	v_pk_add_f32 v[64:65], v[64:65], v[66:67]
	s_nop 0
	v_add_f32_e32 v64, v64, v65
	v_mov_b32_e32 v65, v201
	s_nop 0
	v_lshlrev_b32_e32 v65, 2, v65
	v_xor_b32_e32 v65, 64, v65
	v_mov_b32_e32 v65, v64
	s_nop 1
	v_permlane16_swap_b32_e32 v65, v64
	s_waitcnt lgkmcnt(0)
	v_add_f32_e32 v64, v64, v65
	v_mov_b32_e32 v65, v201
	s_nop 0
	v_lshlrev_b32_e32 v65, 2, v65
	v_xor_b32_e32 v65, 0x80, v65
	v_mov_b32_e32 v65, v64
	s_nop 1
	v_permlane32_swap_b32_e32 v65, v64
	s_waitcnt lgkmcnt(0)
	v_add_f32_e32 v64, v64, v65
	v_fmamk_f32 v64, v64, 0x3c800000, v184
	v_rsq_f32_e32 v64, v64
	s_nop 0
	v_pk_mul_f32 v[60:61], v[60:61], v[64:65] op_sel_hi:[1,0]
	v_pk_mul_f32 v[62:63], v[62:63], v[64:65] op_sel_hi:[1,0]
	v_pk_mul_f32 v[56:57], v[56:57], v[64:65] op_sel_hi:[1,0]
	v_pk_mul_f32 v[58:59], v[58:59], v[64:65] op_sel_hi:[1,0]
	v_pk_mul_f32 v[52:53], v[52:53], v[64:65] op_sel_hi:[1,0]
	v_pk_mul_f32 v[54:55], v[54:55], v[64:65] op_sel_hi:[1,0]
	v_pk_mul_f32 v[48:49], v[48:49], v[64:65] op_sel_hi:[1,0]
	v_pk_mul_f32 v[50:51], v[50:51], v[64:65] op_sel_hi:[1,0]
	v_pk_mul_f32 v[62:63], v[152:153], v[62:63]
	v_pk_mul_f32 v[60:61], v[156:157], v[60:61]
	v_pk_mul_f32 v[58:59], v[146:147], v[58:59]
	v_pk_mul_f32 v[56:57], v[148:149], v[56:57]
	v_pk_mul_f32 v[54:55], v[158:159], v[54:55]
	v_pk_mul_f32 v[52:53], v[160:161], v[52:53]
	v_pk_mul_f32 v[50:51], v[150:151], v[50:51]
	v_pk_mul_f32 v[48:49], v[154:155], v[48:49]
.LBB0_1769:
	v_add_f32_e32 v64, v171, v186
	v_fmamk_f32 v64, v64, 0x3a800000, v184
	v_rsq_f32_e32 v64, v64
	v_mov_b64_e32 v[66:67], s[20:21]
	v_mad_i64_i32 v[66:67], s[46:47], v168, s68, v[66:67]
	v_lshl_add_u64 v[66:67], v[112:113], 1, v[66:67]
	v_pk_mul_f32 v[46:47], v[46:47], v[64:65] op_sel_hi:[1,0]
	v_pk_mul_f32 v[44:45], v[44:45], v[64:65] op_sel_hi:[1,0]
	v_pk_mul_f32 v[42:43], v[42:43], v[64:65] op_sel_hi:[1,0]
	v_pk_mul_f32 v[40:41], v[40:41], v[64:65] op_sel_hi:[1,0]
	v_pk_mul_f32 v[38:39], v[38:39], v[64:65] op_sel_hi:[1,0]
	v_pk_mul_f32 v[36:37], v[36:37], v[64:65] op_sel_hi:[1,0]
	v_pk_mul_f32 v[34:35], v[34:35], v[64:65] op_sel_hi:[1,0]
	s_and_b64 vcc, exec, s[8:9]
	v_pk_mul_f32 v[32:33], v[32:33], v[64:65] op_sel_hi:[1,0]
	v_cvt_pk_bf16_f32 v60, v60, v61
	v_cvt_pk_bf16_f32 v61, v62, v63
	v_cvt_pk_bf16_f32 v62, v56, v57
	v_cvt_pk_bf16_f32 v63, v58, v59
	global_store_dwordx4 v[66:67], v[60:63], off
	v_cvt_pk_bf16_f32 v52, v52, v53
	v_cvt_pk_bf16_f32 v53, v54, v55
	v_cvt_pk_bf16_f32 v54, v48, v49
	v_cvt_pk_bf16_f32 v55, v50, v51
	global_store_dwordx4 v[66:67], v[52:55], off offset:64
	s_cbranch_vccnz .LBB0_1771
	v_mov_b32_e32 v50, v45
	v_mov_b32_e32 v51, v37
	v_mov_b32_e32 v48, v44
	v_mov_b32_e32 v49, v36
	v_pk_mul_f32 v[50:51], v[50:51], v[50:51]
	v_mov_b32_e32 v52, v47
	v_mov_b32_e32 v53, v39
	v_pk_fma_f32 v[48:49], v[48:49], v[48:49], v[50:51]
	v_mov_b32_e32 v50, v46
	v_mov_b32_e32 v51, v38
	v_pk_mul_f32 v[52:53], v[52:53], v[52:53]
	v_mov_b32_e32 v54, v43
	v_pk_fma_f32 v[50:51], v[50:51], v[50:51], v[52:53]
	v_mov_b32_e32 v52, v41
	v_mov_b32_e32 v53, v33
	v_pk_add_f32 v[48:49], v[48:49], v[50:51]
	v_mov_b32_e32 v50, v40
	v_mov_b32_e32 v51, v32
	v_pk_mul_f32 v[52:53], v[52:53], v[52:53]
	v_mov_b32_e32 v55, v35
	v_pk_fma_f32 v[50:51], v[50:51], v[50:51], v[52:53]
	v_mov_b32_e32 v52, v42
	v_mov_b32_e32 v53, v34
	v_pk_mul_f32 v[54:55], v[54:55], v[54:55]
	s_nop 0
	v_pk_fma_f32 v[52:53], v[52:53], v[52:53], v[54:55]
	s_nop 0
	v_pk_add_f32 v[50:51], v[50:51], v[52:53]
	s_nop 0
	v_pk_add_f32 v[48:49], v[48:49], v[50:51]
	s_nop 0
	v_add_f32_e32 v48, v48, v49
	v_mov_b32_e32 v49, v201
	s_nop 0
	v_lshlrev_b32_e32 v49, 2, v49
	v_xor_b32_e32 v49, 64, v49
	v_mov_b32_e32 v49, v48
	s_nop 1
	v_permlane16_swap_b32_e32 v49, v48
	s_waitcnt lgkmcnt(0)
	v_add_f32_e32 v48, v48, v49
	v_mov_b32_e32 v49, v201
	s_nop 0
	v_lshlrev_b32_e32 v49, 2, v49
	v_xor_b32_e32 v49, 0x80, v49
	v_mov_b32_e32 v49, v48
	s_nop 1
	v_permlane32_swap_b32_e32 v49, v48
	s_waitcnt lgkmcnt(0)
	v_add_f32_e32 v48, v48, v49
	v_fmamk_f32 v48, v48, 0x3c800000, v184
	v_rsq_f32_e32 v48, v48
	s_nop 0
	v_pk_mul_f32 v[44:45], v[44:45], v[48:49] op_sel_hi:[1,0]
	v_pk_mul_f32 v[46:47], v[46:47], v[48:49] op_sel_hi:[1,0]
	v_pk_mul_f32 v[40:41], v[40:41], v[48:49] op_sel_hi:[1,0]
	v_pk_mul_f32 v[42:43], v[42:43], v[48:49] op_sel_hi:[1,0]
	v_pk_mul_f32 v[36:37], v[36:37], v[48:49] op_sel_hi:[1,0]
	v_pk_mul_f32 v[38:39], v[38:39], v[48:49] op_sel_hi:[1,0]
	v_pk_mul_f32 v[32:33], v[32:33], v[48:49] op_sel_hi:[1,0]
	v_pk_mul_f32 v[34:35], v[34:35], v[48:49] op_sel_hi:[1,0]
	v_pk_mul_f32 v[46:47], v[152:153], v[46:47]
	v_pk_mul_f32 v[44:45], v[156:157], v[44:45]
	v_pk_mul_f32 v[42:43], v[146:147], v[42:43]
	v_pk_mul_f32 v[40:41], v[148:149], v[40:41]
	v_pk_mul_f32 v[38:39], v[158:159], v[38:39]
	v_pk_mul_f32 v[36:37], v[160:161], v[36:37]
	v_pk_mul_f32 v[34:35], v[150:151], v[34:35]
	v_pk_mul_f32 v[32:33], v[154:155], v[32:33]
; __device__ __forceinline__ float row_finish(float t) { t += shx(t, 16); t += shx(t, 32); return __builtin_amdgcn_rsqf(t * (1.0f / 1024.0f) + RMS_EPS); }
; __device__ __forceinline__ f32x4 silu4(f32x4 v) { return (f32x4){silu_f(v[0]), silu_f(v[1]), silu_f(v[2]), silu_f(v[3])}; }
; __device__ __forceinline__ float sq4(f32x4 v) { return (v[0] * v[0] + v[1] * v[1]) + (v[2] * v[2] + v[3] * v[3]); }
; __device__ __forceinline__ u32x4 pack8(f32x4 a, f32x4 b) { u32x4 w; w.x = cvt_pk_bf16(a[0], a[1]); w.y = cvt_pk_bf16(a[2], a[3]); w.z = cvt_pk_bf16(b[0], b[1]); w.w = cvt_pk_bf16(b[2], b[3]); return w; }
;     __device__ __forceinline__ void operator()(const f32x4 (&acc)[2][2][4][2], const Unit& u, int wr, int wc, int fr, int fq) const {
;     ...
;             for (int m = 0; m < 4; ++m) rs[ai][m] = row_finish(rs[ai][m]);
; #pragma unroll
;         for (int ai = 0; ai < 2; ++ai)
; #pragma unroll
;             for (int m = 0; m < 4; ++m) {
;                 const int row = u.pm * BM + ai * HALF + wr * 64 + m * 16 + fr;
;                 const float rstd = rs[ai][m];
;                 f32x4 v[2][2];
; #pragma unroll
;                 for (int bj = 0; bj < 2; ++bj)
; #pragma unroll
;                     for (int n = 0; n < 2; ++n) v[bj][n] = acc[ai][bj][m][n] * rstd;
;                 if (mode == 2) {
;                     float q = (sq4(v[0][0]) + sq4(v[0][1])) + (sq4(v[1][0]) + sq4(v[1][1]));
;                     q += shx(q, 16); q += shx(q, 32);
;                     const float r2 = __builtin_amdgcn_rsqf(q * (1.0f / 64.0f) + RMS_EPS);
; #pragma unroll
;                     for (int bj = 0; bj < 2; ++bj)
; #pragma unroll
;                         for (int n = 0; n < 2; ++n) v[bj][n] = v[bj][n] * r2 * wv[bj][n];
;                 } else if (mode == 1) {
; #pragma unroll
;                     for (int bj = 0; bj < 2; ++bj)
; #pragma unroll
;                         for (int n = 0; n < 2; ++n) v[bj][n] = silu4(v[bj][n]);
;                 } else {
; #pragma unroll
;                     for (int bj = 0; bj < 2; ++bj)
; #pragma unroll
;                         for (int n = 0; n < 2; ++n) v[bj][n] = v[bj][n] * sc;
;                 }
;                 bf16_t* rowp = U + (size_t)row * 2560 + lcol;
; #pragma unroll
;                 for (int bj = 0; bj < 2; ++bj) *(u32x4*)(rowp + 32 * bj) = pack8(v[bj][0], v[bj][1]);
.LBB0_1771:
	v_add_f32_e32 v48, v167, v169
	v_fmamk_f32 v48, v48, 0x3a800000, v184
	v_rsq_f32_e32 v48, v48
	v_mov_b64_e32 v[50:51], s[20:21]
	v_mad_i64_i32 v[50:51], s[46:47], v166, s68, v[50:51]
	v_lshl_add_u64 v[50:51], v[112:113], 1, v[50:51]
	v_pk_mul_f32 v[30:31], v[30:31], v[48:49] op_sel_hi:[1,0]
	v_pk_mul_f32 v[28:29], v[28:29], v[48:49] op_sel_hi:[1,0]
	v_pk_mul_f32 v[26:27], v[26:27], v[48:49] op_sel_hi:[1,0]
	v_pk_mul_f32 v[24:25], v[24:25], v[48:49] op_sel_hi:[1,0]
	v_pk_mul_f32 v[22:23], v[22:23], v[48:49] op_sel_hi:[1,0]
	v_pk_mul_f32 v[20:21], v[20:21], v[48:49] op_sel_hi:[1,0]
	v_pk_mul_f32 v[18:19], v[18:19], v[48:49] op_sel_hi:[1,0]
	s_and_b64 vcc, exec, s[8:9]
	v_pk_mul_f32 v[16:17], v[16:17], v[48:49] op_sel_hi:[1,0]
	v_cvt_pk_bf16_f32 v44, v44, v45
	v_cvt_pk_bf16_f32 v45, v46, v47
	v_cvt_pk_bf16_f32 v46, v40, v41
	v_cvt_pk_bf16_f32 v47, v42, v43
	global_store_dwordx4 v[50:51], v[44:47], off
	v_cvt_pk_bf16_f32 v36, v36, v37
	v_cvt_pk_bf16_f32 v37, v38, v39
	v_cvt_pk_bf16_f32 v38, v32, v33
	v_cvt_pk_bf16_f32 v39, v34, v35
	global_store_dwordx4 v[50:51], v[36:39], off offset:64
	s_cbranch_vccnz .LBB0_1773
	v_mov_b32_e32 v34, v29
	v_mov_b32_e32 v35, v21
	v_mov_b32_e32 v32, v28
	v_mov_b32_e32 v33, v20
	v_pk_mul_f32 v[34:35], v[34:35], v[34:35]
	v_mov_b32_e32 v36, v31
	v_mov_b32_e32 v37, v23
	v_pk_fma_f32 v[32:33], v[32:33], v[32:33], v[34:35]
	v_mov_b32_e32 v34, v30
	v_mov_b32_e32 v35, v22
	v_pk_mul_f32 v[36:37], v[36:37], v[36:37]
	v_mov_b32_e32 v38, v27
	v_pk_fma_f32 v[34:35], v[34:35], v[34:35], v[36:37]
	v_mov_b32_e32 v36, v25
	v_mov_b32_e32 v37, v17
	v_pk_add_f32 v[32:33], v[32:33], v[34:35]
	v_mov_b32_e32 v34, v24
	v_mov_b32_e32 v35, v16
	v_pk_mul_f32 v[36:37], v[36:37], v[36:37]
	v_mov_b32_e32 v39, v19
	v_pk_fma_f32 v[34:35], v[34:35], v[34:35], v[36:37]
	v_mov_b32_e32 v36, v26
	v_mov_b32_e32 v37, v18
	v_pk_mul_f32 v[38:39], v[38:39], v[38:39]
	s_nop 0
	v_pk_fma_f32 v[36:37], v[36:37], v[36:37], v[38:39]
	s_nop 0
	v_pk_add_f32 v[34:35], v[34:35], v[36:37]
	s_nop 0
	v_pk_add_f32 v[32:33], v[32:33], v[34:35]
	s_nop 0
	v_add_f32_e32 v32, v32, v33
	v_mov_b32_e32 v33, v201
	s_nop 0
	v_lshlrev_b32_e32 v33, 2, v33
	v_xor_b32_e32 v33, 64, v33
	v_mov_b32_e32 v33, v32
	s_nop 1
	v_permlane16_swap_b32_e32 v33, v32
	s_waitcnt lgkmcnt(0)
	v_add_f32_e32 v32, v32, v33
	v_mov_b32_e32 v33, v201
	s_nop 0
	v_lshlrev_b32_e32 v33, 2, v33
	v_xor_b32_e32 v33, 0x80, v33
	v_mov_b32_e32 v33, v32
	s_nop 1
	v_permlane32_swap_b32_e32 v33, v32
	s_waitcnt lgkmcnt(0)
	v_add_f32_e32 v32, v32, v33
	v_fmamk_f32 v32, v32, 0x3c800000, v184
	v_rsq_f32_e32 v32, v32
	s_nop 0
	v_pk_mul_f32 v[28:29], v[28:29], v[32:33] op_sel_hi:[1,0]
	v_pk_mul_f32 v[30:31], v[30:31], v[32:33] op_sel_hi:[1,0]
	v_pk_mul_f32 v[24:25], v[24:25], v[32:33] op_sel_hi:[1,0]
	v_pk_mul_f32 v[26:27], v[26:27], v[32:33] op_sel_hi:[1,0]
	v_pk_mul_f32 v[20:21], v[20:21], v[32:33] op_sel_hi:[1,0]
	v_pk_mul_f32 v[22:23], v[22:23], v[32:33] op_sel_hi:[1,0]
	v_pk_mul_f32 v[16:17], v[16:17], v[32:33] op_sel_hi:[1,0]
	v_pk_mul_f32 v[18:19], v[18:19], v[32:33] op_sel_hi:[1,0]
	v_pk_mul_f32 v[30:31], v[152:153], v[30:31]
	v_pk_mul_f32 v[28:29], v[156:157], v[28:29]
	v_pk_mul_f32 v[26:27], v[146:147], v[26:27]
	v_pk_mul_f32 v[24:25], v[148:149], v[24:25]
	v_pk_mul_f32 v[22:23], v[158:159], v[22:23]
	v_pk_mul_f32 v[20:21], v[160:161], v[20:21]
	v_pk_mul_f32 v[18:19], v[150:151], v[18:19]
	v_pk_mul_f32 v[16:17], v[154:155], v[16:17]
.LBB0_1773:
	s_waitcnt lgkmcnt(0)
	v_add_f32_e32 v32, v163, v165
	v_fmamk_f32 v32, v32, 0x3a800000, v184
	v_rsq_f32_e32 v32, v32
	v_mov_b64_e32 v[34:35], s[20:21]
	v_mad_i64_i32 v[34:35], s[46:47], v164, s68, v[34:35]
	v_lshl_add_u64 v[34:35], v[112:113], 1, v[34:35]
	v_pk_mul_f32 v[14:15], v[14:15], v[32:33] op_sel_hi:[1,0]
	v_pk_mul_f32 v[12:13], v[12:13], v[32:33] op_sel_hi:[1,0]
	v_pk_mul_f32 v[10:11], v[10:11], v[32:33] op_sel_hi:[1,0]
	v_pk_mul_f32 v[8:9], v[8:9], v[32:33] op_sel_hi:[1,0]
	v_pk_mul_f32 v[6:7], v[6:7], v[32:33] op_sel_hi:[1,0]
	v_pk_mul_f32 v[4:5], v[4:5], v[32:33] op_sel_hi:[1,0]
	v_pk_mul_f32 v[2:3], v[2:3], v[32:33] op_sel_hi:[1,0]
	s_and_b64 vcc, exec, s[8:9]
	v_pk_mul_f32 v[0:1], v[0:1], v[32:33] op_sel_hi:[1,0]
	v_cvt_pk_bf16_f32 v28, v28, v29
	v_cvt_pk_bf16_f32 v29, v30, v31
	v_cvt_pk_bf16_f32 v30, v24, v25
	v_cvt_pk_bf16_f32 v31, v26, v27
	global_store_dwordx4 v[34:35], v[28:31], off
	v_cvt_pk_bf16_f32 v20, v20, v21
	v_cvt_pk_bf16_f32 v21, v22, v23
	v_cvt_pk_bf16_f32 v22, v16, v17
	v_cvt_pk_bf16_f32 v23, v18, v19
	global_store_dwordx4 v[34:35], v[20:23], off offset:64
	s_cbranch_vccnz .LBB0_1775
	v_mov_b32_e32 v18, v13
	v_mov_b32_e32 v19, v5
	v_mov_b32_e32 v16, v12
	v_mov_b32_e32 v17, v4
	v_pk_mul_f32 v[18:19], v[18:19], v[18:19]
	v_mov_b32_e32 v20, v15
	v_mov_b32_e32 v21, v7
	v_pk_fma_f32 v[16:17], v[16:17], v[16:17], v[18:19]
	v_mov_b32_e32 v18, v14
	v_mov_b32_e32 v19, v6
	v_pk_mul_f32 v[20:21], v[20:21], v[20:21]
	v_mov_b32_e32 v22, v11
	v_pk_fma_f32 v[18:19], v[18:19], v[18:19], v[20:21]
	v_mov_b32_e32 v20, v9
	v_mov_b32_e32 v21, v1
	v_pk_add_f32 v[16:17], v[16:17], v[18:19]
	v_mov_b32_e32 v18, v8
	v_mov_b32_e32 v19, v0
	v_pk_mul_f32 v[20:21], v[20:21], v[20:21]
	v_mov_b32_e32 v23, v3
	v_pk_fma_f32 v[18:19], v[18:19], v[18:19], v[20:21]
	v_mov_b32_e32 v20, v10
	v_mov_b32_e32 v21, v2
	v_pk_mul_f32 v[22:23], v[22:23], v[22:23]
	s_nop 0
	v_pk_fma_f32 v[20:21], v[20:21], v[20:21], v[22:23]
	s_nop 0
	v_pk_add_f32 v[18:19], v[18:19], v[20:21]
	s_nop 0
	v_pk_add_f32 v[16:17], v[16:17], v[18:19]
	s_nop 0
	v_add_f32_e32 v16, v16, v17
	v_mov_b32_e32 v17, v201
	s_nop 0
	v_lshlrev_b32_e32 v17, 2, v17
	v_xor_b32_e32 v17, 64, v17
	v_mov_b32_e32 v17, v16
	s_nop 1
	v_permlane16_swap_b32_e32 v17, v16
	s_waitcnt lgkmcnt(0)
	v_add_f32_e32 v16, v16, v17
	v_mov_b32_e32 v17, v201
	s_nop 0
	v_lshlrev_b32_e32 v17, 2, v17
	v_xor_b32_e32 v17, 0x80, v17
	v_mov_b32_e32 v17, v16
	s_nop 1
	v_permlane32_swap_b32_e32 v17, v16
	s_waitcnt lgkmcnt(0)
	v_add_f32_e32 v16, v16, v17
	v_fmamk_f32 v16, v16, 0x3c800000, v184
	v_rsq_f32_e32 v16, v16
	s_nop 0
	v_pk_mul_f32 v[12:13], v[12:13], v[16:17] op_sel_hi:[1,0]
	v_pk_mul_f32 v[14:15], v[14:15], v[16:17] op_sel_hi:[1,0]
	v_pk_mul_f32 v[8:9], v[8:9], v[16:17] op_sel_hi:[1,0]
	v_pk_mul_f32 v[10:11], v[10:11], v[16:17] op_sel_hi:[1,0]
	v_pk_mul_f32 v[4:5], v[4:5], v[16:17] op_sel_hi:[1,0]
	v_pk_mul_f32 v[6:7], v[6:7], v[16:17] op_sel_hi:[1,0]
	v_pk_mul_f32 v[0:1], v[0:1], v[16:17] op_sel_hi:[1,0]
	v_pk_mul_f32 v[2:3], v[2:3], v[16:17] op_sel_hi:[1,0]
	v_pk_mul_f32 v[14:15], v[152:153], v[14:15]
	v_pk_mul_f32 v[12:13], v[156:157], v[12:13]
	v_pk_mul_f32 v[10:11], v[146:147], v[10:11]
	v_pk_mul_f32 v[8:9], v[148:149], v[8:9]
	v_pk_mul_f32 v[6:7], v[158:159], v[6:7]
	v_pk_mul_f32 v[4:5], v[160:161], v[4:5]
	v_pk_mul_f32 v[2:3], v[150:151], v[2:3]
	v_pk_mul_f32 v[0:1], v[154:155], v[0:1]

; __device__ __forceinline__ float sq4(f32x4 v) { return (v[0] * v[0] + v[1] * v[1]) + (v[2] * v[2] + v[3] * v[3]); }
; __device__ __forceinline__ u32x4 pack8(f32x4 a, f32x4 b) { u32x4 w; w.x = cvt_pk_bf16(a[0], a[1]); w.y = cvt_pk_bf16(a[2], a[3]); w.z = cvt_pk_bf16(b[0], b[1]); w.w = cvt_pk_bf16(b[2], b[3]); return w; }
;     __device__ __forceinline__ void operator()(const f32x4 (&acc)[2][2][4][2], const Unit& u, int wr, int wc, int fr, int fq) const {
;     ...
;         for (int ai = 0; ai < 2; ++ai) {
;             u32x4 bs[4][2];
; #pragma unroll
;             for (int m = 0; m < 4; ++m)
; #pragma unroll
;                 for (int bj = 0; bj < 2; ++bj) bs[m][bj] = *(const u32x4*)(xb + (size_t)(u.pm * BM + ai * HALF + wr * 64 + m * 16 + fr) * 1024 + col0 + 128 * bj);
; #pragma unroll
;             for (int m = 0; m < 4; ++m) {
;                 const int row = u.pm * BM + ai * HALF + wr * 64 + m * 16 + fr;
;                 float q = 0.f;
; #pragma unroll
;                 for (int bj = 0; bj < 2; ++bj) {
;                     const size_t off = (size_t)row * 1024 + col0 + 128 * bj; const u32x4 w = bs[m][bj];
;                     const f32x4 b0 = (f32x4){__builtin_bit_cast(float, w.x << 16), __builtin_bit_cast(float, w.x & 0xffff0000u), __builtin_bit_cast(float, w.y << 16), __builtin_bit_cast(float, w.y & 0xffff0000u)};
;                     const f32x4 b1 = (f32x4){__builtin_bit_cast(float, w.z << 16), __builtin_bit_cast(float, w.z & 0xffff0000u), __builtin_bit_cast(float, w.w << 16), __builtin_bit_cast(float, w.w & 0xffff0000u)};
;                     const f32x4 v0 = acc[ai][bj][m][0] + b0, v1 = acc[ai][bj][m][1] + b1;
;                     if (last) { __builtin_nontemporal_store(v0, (f32x4*)(out + off)); __builtin_nontemporal_store(v1, (f32x4*)(out + off + 4)); }
;                     else { q += sq4(v0) + sq4(v1); *(u32x4*)(xb + off) = pack8(v0, v1); }
;                 }
;                 if (!last) { q += shx(q, 16); q += shx(q, 32); if (fq == 0) ss[(size_t)row * 16 + u.pn * 4 + wc] = q; }
.LBB0_1959:
	v_lshl_or_b32 v168, s10, 8, v188
	v_lshl_add_u32 v172, s38, 8, v186
	v_ashrrev_i32_e32 v169, 31, v168
	v_lshlrev_b64 v[202:203], 1, v[168:169]
	v_ashrrev_i32_e32 v173, 31, v172
	v_lshl_add_u64 v[170:171], s[16:17], 0, v[202:203]
	v_lshlrev_b64 v[204:205], 11, v[172:173]
	v_lshl_add_u64 v[128:129], v[170:171], 0, v[204:205]
	global_load_dwordx4 v[192:195], v[128:129], off
	global_load_dwordx4 v[196:199], v[128:129], off offset:256
	v_or_b32_e32 v182, 16, v172
	v_or_b32_e32 v178, 32, v172
	v_or_b32_e32 v174, 48, v172
	v_ashrrev_i32_e32 v183, 31, v182
	v_ashrrev_i32_e32 v179, 31, v178
	v_ashrrev_i32_e32 v175, 31, v174
	v_lshlrev_b64 v[184:185], 11, v[182:183]
	v_lshlrev_b64 v[180:181], 11, v[178:179]
	v_lshlrev_b64 v[176:177], 11, v[174:175]
	v_lshl_add_u64 v[128:129], v[170:171], 0, v[184:185]
	v_lshl_add_u64 v[130:131], v[170:171], 0, v[180:181]
	v_lshl_add_u64 v[206:207], v[170:171], 0, v[176:177]
	global_load_dwordx4 v[148:151], v[128:129], off
	global_load_dwordx4 v[144:147], v[128:129], off offset:256
	global_load_dwordx4 v[140:143], v[130:131], off
	global_load_dwordx4 v[136:139], v[130:131], off offset:256
	global_load_dwordx4 v[132:135], v[206:207], off
	s_nop 0
	global_load_dwordx4 v[128:131], v[206:207], off offset:256
	v_lshl_add_u64 v[204:205], s[16:17], 0, v[204:205]
	v_lshl_add_u64 v[202:203], v[204:205], 0, v[202:203]
	v_mov_b32_e32 v200, v201
	s_lshl_b32 s38, s10, 2
	s_ashr_i32 s39, s38, 31
	s_waitcnt vmcnt(0)
	v_lshlrev_b32_e32 v204, 16, v192
	v_and_b32_e32 v205, 0xffff0000, v192
	v_lshlrev_b32_e32 v192, 16, v193
	v_and_b32_e32 v193, 0xffff0000, v193
	v_lshlrev_b32_e32 v206, 16, v194
	v_and_b32_e32 v207, 0xffff0000, v194
	v_lshlrev_b32_e32 v194, 16, v195
	v_and_b32_e32 v195, 0xffff0000, v195
	v_lshlrev_b32_e32 v208, 16, v196
	v_and_b32_e32 v209, 0xffff0000, v196
	v_lshlrev_b32_e32 v196, 16, v197
	v_and_b32_e32 v197, 0xffff0000, v197
	v_lshlrev_b32_e32 v210, 16, v198
	v_and_b32_e32 v211, 0xffff0000, v198
	v_lshlrev_b32_e32 v198, 16, v199
	v_and_b32_e32 v199, 0xffff0000, v199
	v_pk_add_f32 v[126:127], v[126:127], v[192:193]
	v_pk_add_f32 v[124:125], v[124:125], v[204:205]
	v_pk_add_f32 v[122:123], v[122:123], v[194:195]
	v_pk_add_f32 v[120:121], v[120:121], v[206:207]
	v_pk_add_f32 v[118:119], v[118:119], v[196:197]
	v_pk_add_f32 v[116:117], v[116:117], v[208:209]
	v_pk_add_f32 v[192:193], v[114:115], v[198:199]
	v_pk_add_f32 v[194:195], v[112:113], v[210:211]
	v_mul_f32_e32 v196, v125, v125
	v_mul_f32_e32 v197, v127, v127
	v_mul_f32_e32 v198, v121, v121
	v_mul_f32_e32 v199, v123, v123
	v_cvt_pk_bf16_f32 v112, v124, v125
	v_cvt_pk_bf16_f32 v113, v126, v127
	v_cvt_pk_bf16_f32 v114, v120, v121
	v_cvt_pk_bf16_f32 v115, v122, v123
	v_mul_f32_e32 v121, v117, v117
	v_mul_f32_e32 v123, v119, v119
	v_mul_f32_e32 v125, v195, v195
	v_mul_f32_e32 v127, v193, v193
	v_fmac_f32_e32 v196, v124, v124
	v_fmac_f32_e32 v197, v126, v126
	v_fmac_f32_e32 v198, v120, v120
	v_fmac_f32_e32 v199, v122, v122
	v_fmac_f32_e32 v121, v116, v116
	v_fmac_f32_e32 v123, v118, v118
	v_fmac_f32_e32 v125, v194, v194
	v_fmac_f32_e32 v127, v192, v192
	global_store_dwordx4 v[202:203], v[112:115], off
	s_nop 1
	v_cvt_pk_bf16_f32 v112, v116, v117
	v_cvt_pk_bf16_f32 v113, v118, v119
	v_cvt_pk_bf16_f32 v114, v194, v195
	v_add_f32_e32 v116, v196, v197
	v_add_f32_e32 v117, v198, v199
	v_add_f32_e32 v118, v121, v123
	v_add_f32_e32 v119, v125, v127
	v_cvt_pk_bf16_f32 v115, v192, v193
	global_store_dwordx4 v[202:203], v[112:115], off offset:256
	s_nop 1
	v_add_f32_e32 v112, v116, v117
	v_add_f32_e32 v113, v118, v119
	v_lshlrev_b32_e32 v114, 2, v200
	v_add_f32_e32 v112, v112, v113
	v_xor_b32_e32 v113, 64, v114
	v_mov_b32_e32 v113, v112
	s_nop 1
	v_permlane16_swap_b32_e32 v113, v112
	v_mov_b32_e32 v114, v201
	s_waitcnt lgkmcnt(0)
	v_add_f32_e32 v112, v112, v113
	v_lshlrev_b32_e32 v114, 2, v114
	v_xor_b32_e32 v113, 0x80, v114
	v_mov_b32_e32 v113, v112
	s_nop 1
	v_permlane32_swap_b32_e32 v113, v112
	s_and_saveexec_b64 s[40:41], s[6:7]
	s_cbranch_execz .LBB0_1961
	s_waitcnt lgkmcnt(0)
	v_add_f32_e32 v114, v112, v113
	v_lshlrev_b64 v[112:113], 6, v[172:173]
	v_lshl_add_u64 v[112:113], s[18:19], 0, v[112:113]
	v_lshl_add_u64 v[112:113], s[38:39], 2, v[112:113]
	s_lshl_b32 s10, s33, 2
	v_lshl_add_u64 v[112:113], v[112:113], 0, s[10:11]
	global_store_dword v[112:113], v114, off
; __device__ __forceinline__ float sq4(f32x4 v) { return (v[0] * v[0] + v[1] * v[1]) + (v[2] * v[2] + v[3] * v[3]); }
; __device__ __forceinline__ u32x4 pack8(f32x4 a, f32x4 b) { u32x4 w; w.x = cvt_pk_bf16(a[0], a[1]); w.y = cvt_pk_bf16(a[2], a[3]); w.z = cvt_pk_bf16(b[0], b[1]); w.w = cvt_pk_bf16(b[2], b[3]); return w; }
;     __device__ __forceinline__ void operator()(const f32x4 (&acc)[2][2][4][2], const Unit& u, int wr, int wc, int fr, int fq) const {
;     ...
;         for (int ai = 0; ai < 2; ++ai) {
;             u32x4 bs[4][2];
; #pragma unroll
;             for (int m = 0; m < 4; ++m)
; #pragma unroll
;                 for (int bj = 0; bj < 2; ++bj) bs[m][bj] = *(const u32x4*)(xb + (size_t)(u.pm * BM + ai * HALF + wr * 64 + m * 16 + fr) * 1024 + col0 + 128 * bj);
; #pragma unroll
;             for (int m = 0; m < 4; ++m) {
;                 const int row = u.pm * BM + ai * HALF + wr * 64 + m * 16 + fr;
;                 float q = 0.f;
; #pragma unroll
;                 for (int bj = 0; bj < 2; ++bj) {
;                     const size_t off = (size_t)row * 1024 + col0 + 128 * bj; const u32x4 w = bs[m][bj];
;                     const f32x4 b0 = (f32x4){__builtin_bit_cast(float, w.x << 16), __builtin_bit_cast(float, w.x & 0xffff0000u), __builtin_bit_cast(float, w.y << 16), __builtin_bit_cast(float, w.y & 0xffff0000u)};
;                     const f32x4 b1 = (f32x4){__builtin_bit_cast(float, w.z << 16), __builtin_bit_cast(float, w.z & 0xffff0000u), __builtin_bit_cast(float, w.w << 16), __builtin_bit_cast(float, w.w & 0xffff0000u)};
;                     const f32x4 v0 = acc[ai][bj][m][0] + b0, v1 = acc[ai][bj][m][1] + b1;
;                     if (last) { __builtin_nontemporal_store(v0, (f32x4*)(out + off)); __builtin_nontemporal_store(v1, (f32x4*)(out + off + 4)); }
;                     else { q += sq4(v0) + sq4(v1); *(u32x4*)(xb + off) = pack8(v0, v1); }
;                 }
;                 if (!last) { q += shx(q, 16); q += shx(q, 32); if (fq == 0) ss[(size_t)row * 16 + u.pn * 4 + wc] = q; }
.LBB0_1961:
	s_or_b64 exec, exec, s[40:41]
	v_lshlrev_b32_e32 v112, 16, v148
	s_waitcnt lgkmcnt(0)
	v_and_b32_e32 v113, 0xffff0000, v148
	v_lshlrev_b32_e32 v114, 16, v149
	v_and_b32_e32 v115, 0xffff0000, v149
	v_lshlrev_b32_e32 v116, 16, v150
	v_and_b32_e32 v117, 0xffff0000, v150
	v_lshlrev_b32_e32 v118, 16, v151
	v_and_b32_e32 v119, 0xffff0000, v151
	v_pk_add_f32 v[110:111], v[110:111], v[114:115]
	v_pk_add_f32 v[108:109], v[108:109], v[112:113]
	v_pk_add_f32 v[112:113], v[106:107], v[118:119]
	v_pk_add_f32 v[106:107], v[104:105], v[116:117]
	v_mul_f32_e32 v104, v109, v109
	v_mul_f32_e32 v105, v111, v111
	v_fmac_f32_e32 v104, v108, v108
	v_fmac_f32_e32 v105, v110, v110
	v_add_f32_e32 v104, v104, v105
	v_mul_f32_e32 v105, v107, v107
	v_mul_f32_e32 v114, v113, v113
	v_fmac_f32_e32 v105, v106, v106
	v_fmac_f32_e32 v114, v112, v112
	v_add_f32_e32 v105, v105, v114
	v_add_f32_e32 v114, v104, v105
	v_cvt_pk_bf16_f32 v104, v108, v109
	v_lshl_add_u64 v[108:109], s[16:17], 0, v[184:185]
	v_cvt_pk_bf16_f32 v105, v110, v111
	v_cvt_pk_bf16_f32 v106, v106, v107
	v_cvt_pk_bf16_f32 v107, v112, v113
	v_lshl_add_u64 v[108:109], v[168:169], 1, v[108:109]
	global_store_dwordx4 v[108:109], v[104:107], off
	v_lshlrev_b32_e32 v110, 16, v146
	v_and_b32_e32 v111, 0xffff0000, v146
	v_lshlrev_b32_e32 v104, 16, v144
	v_and_b32_e32 v105, 0xffff0000, v144
	v_lshlrev_b32_e32 v106, 16, v145
	v_and_b32_e32 v107, 0xffff0000, v145
	v_lshlrev_b32_e32 v112, 16, v147
	v_and_b32_e32 v113, 0xffff0000, v147
	v_pk_add_f32 v[102:103], v[102:103], v[106:107]
	v_pk_add_f32 v[100:101], v[100:101], v[104:105]
	v_pk_add_f32 v[104:105], v[98:99], v[112:113]
	v_pk_add_f32 v[98:99], v[96:97], v[110:111]
	v_mul_f32_e32 v96, v101, v101
	v_mul_f32_e32 v97, v103, v103
	v_fmac_f32_e32 v96, v100, v100
	v_fmac_f32_e32 v97, v102, v102
	v_add_f32_e32 v96, v96, v97
	v_mul_f32_e32 v97, v99, v99
	v_mul_f32_e32 v106, v105, v105
	v_fmac_f32_e32 v97, v98, v98
	v_fmac_f32_e32 v106, v104, v104
	v_add_f32_e32 v97, v97, v106
	v_add_f32_e32 v96, v96, v97
	v_add_f32_e32 v106, v114, v96
	v_cvt_pk_bf16_f32 v96, v100, v101
	v_cvt_pk_bf16_f32 v97, v102, v103
	v_cvt_pk_bf16_f32 v98, v98, v99
	v_cvt_pk_bf16_f32 v99, v104, v105
	global_store_dwordx4 v[108:109], v[96:99], off offset:256
	s_nop 1
	v_mov_b32_e32 v96, v201
	v_mov_b32_e32 v97, v201
	v_lshlrev_b32_e32 v96, 2, v96
	v_xor_b32_e32 v96, 64, v96
	v_mov_b32_e32 v96, v106
	s_nop 1
	v_permlane16_swap_b32_e32 v96, v106
	s_waitcnt lgkmcnt(0)
	v_add_f32_e32 v96, v106, v96
	v_lshlrev_b32_e32 v97, 2, v97
	v_xor_b32_e32 v97, 0x80, v97
	v_mov_b32_e32 v97, v96
	s_nop 1
	v_permlane32_swap_b32_e32 v97, v96
	s_and_saveexec_b64 s[40:41], s[6:7]
	s_cbranch_execz .LBB0_1963
	s_waitcnt lgkmcnt(0)
	v_add_f32_e32 v98, v96, v97
	v_lshlrev_b64 v[96:97], 6, v[182:183]
	v_lshl_add_u64 v[96:97], s[18:19], 0, v[96:97]
	v_lshl_add_u64 v[96:97], s[38:39], 2, v[96:97]
	s_lshl_b32 s10, s33, 2
	v_lshl_add_u64 v[96:97], v[96:97], 0, s[10:11]
	global_store_dword v[96:97], v98, off
.LBB0_1963:
	s_or_b64 exec, exec, s[40:41]
	v_lshlrev_b32_e32 v96, 16, v140
	s_waitcnt lgkmcnt(0)
	v_and_b32_e32 v97, 0xffff0000, v140
	v_lshlrev_b32_e32 v98, 16, v141
	v_and_b32_e32 v99, 0xffff0000, v141
	v_lshlrev_b32_e32 v100, 16, v142
	v_and_b32_e32 v101, 0xffff0000, v142
	v_lshlrev_b32_e32 v102, 16, v143
	v_and_b32_e32 v103, 0xffff0000, v143
	v_pk_add_f32 v[94:95], v[94:95], v[98:99]
	v_pk_add_f32 v[92:93], v[92:93], v[96:97]
	v_pk_add_f32 v[96:97], v[90:91], v[102:103]
	v_pk_add_f32 v[90:91], v[88:89], v[100:101]
	v_mul_f32_e32 v88, v93, v93
	v_mul_f32_e32 v89, v95, v95
	v_fmac_f32_e32 v88, v92, v92
	v_fmac_f32_e32 v89, v94, v94
	v_add_f32_e32 v88, v88, v89
	v_mul_f32_e32 v89, v91, v91
	v_mul_f32_e32 v98, v97, v97
	v_fmac_f32_e32 v89, v90, v90
	v_fmac_f32_e32 v98, v96, v96
	v_add_f32_e32 v89, v89, v98
	v_add_f32_e32 v98, v88, v89
	v_cvt_pk_bf16_f32 v88, v92, v93
	v_lshl_add_u64 v[92:93], s[16:17], 0, v[180:181]
	v_cvt_pk_bf16_f32 v89, v94, v95
	v_cvt_pk_bf16_f32 v90, v90, v91
	v_cvt_pk_bf16_f32 v91, v96, v97
	v_lshl_add_u64 v[92:93], v[168:169], 1, v[92:93]
	global_store_dwordx4 v[92:93], v[88:91], off
	v_lshlrev_b32_e32 v94, 16, v138
	v_and_b32_e32 v95, 0xffff0000, v138
	v_lshlrev_b32_e32 v88, 16, v136
	v_and_b32_e32 v89, 0xffff0000, v136
	v_lshlrev_b32_e32 v90, 16, v137
	v_and_b32_e32 v91, 0xffff0000, v137
	v_lshlrev_b32_e32 v96, 16, v139
	v_and_b32_e32 v97, 0xffff0000, v139
	v_pk_add_f32 v[86:87], v[86:87], v[90:91]
	v_pk_add_f32 v[84:85], v[84:85], v[88:89]
	v_pk_add_f32 v[88:89], v[82:83], v[96:97]
	v_pk_add_f32 v[82:83], v[80:81], v[94:95]
	v_mul_f32_e32 v80, v85, v85
	v_mul_f32_e32 v81, v87, v87
	v_fmac_f32_e32 v80, v84, v84
	v_fmac_f32_e32 v81, v86, v86
	v_add_f32_e32 v80, v80, v81
	v_mul_f32_e32 v81, v83, v83
	v_mul_f32_e32 v90, v89, v89
	v_fmac_f32_e32 v81, v82, v82
	v_fmac_f32_e32 v90, v88, v88
	v_add_f32_e32 v81, v81, v90
	v_add_f32_e32 v80, v80, v81
	v_add_f32_e32 v90, v98, v80
	v_cvt_pk_bf16_f32 v80, v84, v85
	v_cvt_pk_bf16_f32 v81, v86, v87
	v_cvt_pk_bf16_f32 v82, v82, v83
	v_cvt_pk_bf16_f32 v83, v88, v89
	global_store_dwordx4 v[92:93], v[80:83], off offset:256
	s_nop 1
	v_mov_b32_e32 v80, v201
	v_mov_b32_e32 v81, v201
	v_lshlrev_b32_e32 v80, 2, v80
	v_xor_b32_e32 v80, 64, v80
	v_mov_b32_e32 v80, v90
	s_nop 1
	v_permlane16_swap_b32_e32 v80, v90
	s_waitcnt lgkmcnt(0)
	v_add_f32_e32 v80, v90, v80
	v_lshlrev_b32_e32 v81, 2, v81
	v_xor_b32_e32 v81, 0x80, v81
	v_mov_b32_e32 v81, v80
	s_nop 1
	v_permlane32_swap_b32_e32 v81, v80
	s_and_saveexec_b64 s[40:41], s[6:7]
	s_cbranch_execz .LBB0_1965
	s_waitcnt lgkmcnt(0)
	v_add_f32_e32 v82, v80, v81
	v_lshlrev_b64 v[80:81], 6, v[178:179]
	v_lshl_add_u64 v[80:81], s[18:19], 0, v[80:81]
	v_lshl_add_u64 v[80:81], s[38:39], 2, v[80:81]
	s_lshl_b32 s10, s33, 2
	v_lshl_add_u64 v[80:81], v[80:81], 0, s[10:11]
	global_store_dword v[80:81], v82, off
; __device__ __forceinline__ float sq4(f32x4 v) { return (v[0] * v[0] + v[1] * v[1]) + (v[2] * v[2] + v[3] * v[3]); }
; __device__ __forceinline__ u32x4 pack8(f32x4 a, f32x4 b) { u32x4 w; w.x = cvt_pk_bf16(a[0], a[1]); w.y = cvt_pk_bf16(a[2], a[3]); w.z = cvt_pk_bf16(b[0], b[1]); w.w = cvt_pk_bf16(b[2], b[3]); return w; }
;     __device__ __forceinline__ void operator()(const f32x4 (&acc)[2][2][4][2], const Unit& u, int wr, int wc, int fr, int fq) const {
;     ...
;         for (int ai = 0; ai < 2; ++ai) {
;             u32x4 bs[4][2];
; #pragma unroll
;             for (int m = 0; m < 4; ++m)
; #pragma unroll
;                 for (int bj = 0; bj < 2; ++bj) bs[m][bj] = *(const u32x4*)(xb + (size_t)(u.pm * BM + ai * HALF + wr * 64 + m * 16 + fr) * 1024 + col0 + 128 * bj);
; #pragma unroll
;             for (int m = 0; m < 4; ++m) {
;                 const int row = u.pm * BM + ai * HALF + wr * 64 + m * 16 + fr;
;                 float q = 0.f;
; #pragma unroll
;                 for (int bj = 0; bj < 2; ++bj) {
;                     const size_t off = (size_t)row * 1024 + col0 + 128 * bj; const u32x4 w = bs[m][bj];
;                     const f32x4 b0 = (f32x4){__builtin_bit_cast(float, w.x << 16), __builtin_bit_cast(float, w.x & 0xffff0000u), __builtin_bit_cast(float, w.y << 16), __builtin_bit_cast(float, w.y & 0xffff0000u)};
;                     const f32x4 b1 = (f32x4){__builtin_bit_cast(float, w.z << 16), __builtin_bit_cast(float, w.z & 0xffff0000u), __builtin_bit_cast(float, w.w << 16), __builtin_bit_cast(float, w.w & 0xffff0000u)};
;                     const f32x4 v0 = acc[ai][bj][m][0] + b0, v1 = acc[ai][bj][m][1] + b1;
;                     if (last) { __builtin_nontemporal_store(v0, (f32x4*)(out + off)); __builtin_nontemporal_store(v1, (f32x4*)(out + off + 4)); }
;                     else { q += sq4(v0) + sq4(v1); *(u32x4*)(xb + off) = pack8(v0, v1); }
;                 }
;                 if (!last) { q += shx(q, 16); q += shx(q, 32); if (fq == 0) ss[(size_t)row * 16 + u.pn * 4 + wc] = q; }
.LBB0_1965:
	s_or_b64 exec, exec, s[40:41]
	v_lshlrev_b32_e32 v80, 16, v132
	s_waitcnt lgkmcnt(0)
	v_and_b32_e32 v81, 0xffff0000, v132
	v_lshlrev_b32_e32 v82, 16, v133
	v_and_b32_e32 v83, 0xffff0000, v133
	v_lshlrev_b32_e32 v84, 16, v134
	v_and_b32_e32 v85, 0xffff0000, v134
	v_lshlrev_b32_e32 v86, 16, v135
	v_and_b32_e32 v87, 0xffff0000, v135
	v_pk_add_f32 v[78:79], v[78:79], v[82:83]
	v_pk_add_f32 v[76:77], v[76:77], v[80:81]
	v_pk_add_f32 v[80:81], v[74:75], v[86:87]
	v_pk_add_f32 v[74:75], v[72:73], v[84:85]
	v_mul_f32_e32 v72, v77, v77
	v_mul_f32_e32 v73, v79, v79
	v_fmac_f32_e32 v72, v76, v76
	v_fmac_f32_e32 v73, v78, v78
	v_add_f32_e32 v72, v72, v73
	v_mul_f32_e32 v73, v75, v75
	v_mul_f32_e32 v82, v81, v81
	v_fmac_f32_e32 v73, v74, v74
	v_fmac_f32_e32 v82, v80, v80
	v_add_f32_e32 v73, v73, v82
	v_add_f32_e32 v82, v72, v73
	v_cvt_pk_bf16_f32 v72, v76, v77
	v_lshl_add_u64 v[76:77], s[16:17], 0, v[176:177]
	v_cvt_pk_bf16_f32 v73, v78, v79
	v_cvt_pk_bf16_f32 v74, v74, v75
	v_cvt_pk_bf16_f32 v75, v80, v81
	v_lshl_add_u64 v[76:77], v[168:169], 1, v[76:77]
	global_store_dwordx4 v[76:77], v[72:75], off
	v_lshlrev_b32_e32 v78, 16, v130
	v_and_b32_e32 v79, 0xffff0000, v130
	v_lshlrev_b32_e32 v72, 16, v128
	v_and_b32_e32 v73, 0xffff0000, v128
	v_lshlrev_b32_e32 v74, 16, v129
	v_and_b32_e32 v75, 0xffff0000, v129
	v_lshlrev_b32_e32 v80, 16, v131
	v_and_b32_e32 v81, 0xffff0000, v131
	v_pk_add_f32 v[70:71], v[70:71], v[74:75]
	v_pk_add_f32 v[68:69], v[68:69], v[72:73]
	v_pk_add_f32 v[72:73], v[66:67], v[80:81]
	v_pk_add_f32 v[66:67], v[64:65], v[78:79]
	v_mul_f32_e32 v64, v69, v69
	v_mul_f32_e32 v65, v71, v71
	v_fmac_f32_e32 v64, v68, v68
	v_fmac_f32_e32 v65, v70, v70
	v_add_f32_e32 v64, v64, v65
	v_mul_f32_e32 v65, v67, v67
	v_mul_f32_e32 v74, v73, v73
	v_fmac_f32_e32 v65, v66, v66
	v_fmac_f32_e32 v74, v72, v72
	v_add_f32_e32 v65, v65, v74
	v_add_f32_e32 v64, v64, v65
	v_add_f32_e32 v74, v82, v64
	v_cvt_pk_bf16_f32 v64, v68, v69
	v_cvt_pk_bf16_f32 v65, v70, v71
	v_cvt_pk_bf16_f32 v66, v66, v67
	v_cvt_pk_bf16_f32 v67, v72, v73
	global_store_dwordx4 v[76:77], v[64:67], off offset:256
	s_nop 1
	v_mov_b32_e32 v64, v201
	v_mov_b32_e32 v65, v201
	v_lshlrev_b32_e32 v64, 2, v64
	v_xor_b32_e32 v64, 64, v64
	v_mov_b32_e32 v64, v74
	s_nop 1
	v_permlane16_swap_b32_e32 v64, v74
	s_waitcnt lgkmcnt(0)
	v_add_f32_e32 v64, v74, v64
	v_lshlrev_b32_e32 v65, 2, v65
	v_xor_b32_e32 v65, 0x80, v65
	v_mov_b32_e32 v65, v64
	s_nop 1
	v_permlane32_swap_b32_e32 v65, v64
	s_and_saveexec_b64 s[40:41], s[6:7]
	s_cbranch_execz .LBB0_1967
	s_waitcnt lgkmcnt(0)
	v_add_f32_e32 v66, v64, v65
	v_lshlrev_b64 v[64:65], 6, v[174:175]
	v_lshl_add_u64 v[64:65], s[18:19], 0, v[64:65]
	v_lshl_add_u64 v[64:65], s[38:39], 2, v[64:65]
	s_lshl_b32 s10, s33, 2
	v_lshl_add_u64 v[64:65], v[64:65], 0, s[10:11]
	global_store_dword v[64:65], v66, off
.LBB0_1967:
	s_or_b64 exec, exec, s[40:41]
	v_add_u32_e32 v100, 0x80, v172
	v_ashrrev_i32_e32 v101, 31, v100
	v_lshlrev_b64 v[110:111], 11, v[100:101]
	s_waitcnt lgkmcnt(0)
	v_lshl_add_u64 v[64:65], v[170:171], 0, v[110:111]
	global_load_dwordx4 v[102:105], v[64:65], off
	global_load_dwordx4 v[106:109], v[64:65], off offset:256
	v_add_u32_e32 v96, 0x90, v172
	v_add_u32_e32 v92, 0xa0, v172
	v_add_u32_e32 v88, 0xb0, v172
	v_ashrrev_i32_e32 v97, 31, v96
	v_ashrrev_i32_e32 v93, 31, v92
	v_ashrrev_i32_e32 v89, 31, v88
	v_lshlrev_b64 v[98:99], 11, v[96:97]
	v_lshlrev_b64 v[94:95], 11, v[92:93]
	v_lshlrev_b64 v[90:91], 11, v[88:89]
	v_lshl_add_u64 v[64:65], v[170:171], 0, v[98:99]
	v_lshl_add_u64 v[66:67], v[170:171], 0, v[94:95]
	v_lshl_add_u64 v[112:113], v[170:171], 0, v[90:91]
	global_load_dwordx4 v[84:87], v[64:65], off
	global_load_dwordx4 v[80:83], v[64:65], off offset:256
	global_load_dwordx4 v[76:79], v[66:67], off
	global_load_dwordx4 v[72:75], v[66:67], off offset:256
	global_load_dwordx4 v[68:71], v[112:113], off
	s_nop 0
	global_load_dwordx4 v[64:67], v[112:113], off offset:256
	v_lshl_add_u64 v[110:111], s[16:17], 0, v[110:111]
	v_lshl_add_u64 v[110:111], v[168:169], 1, v[110:111]
	v_mov_b32_e32 v120, v201
	s_waitcnt vmcnt(7)
	v_lshlrev_b32_e32 v112, 16, v102
	v_and_b32_e32 v113, 0xffff0000, v102
	v_lshlrev_b32_e32 v102, 16, v103
	v_and_b32_e32 v103, 0xffff0000, v103
	v_lshlrev_b32_e32 v114, 16, v104
	v_and_b32_e32 v115, 0xffff0000, v104
	v_lshlrev_b32_e32 v104, 16, v105
	v_and_b32_e32 v105, 0xffff0000, v105
	s_waitcnt vmcnt(6)
	v_lshlrev_b32_e32 v116, 16, v106
	v_and_b32_e32 v117, 0xffff0000, v106
	v_lshlrev_b32_e32 v106, 16, v107
	v_and_b32_e32 v107, 0xffff0000, v107
	v_lshlrev_b32_e32 v118, 16, v108
	v_and_b32_e32 v119, 0xffff0000, v108
	v_lshlrev_b32_e32 v108, 16, v109
	v_and_b32_e32 v109, 0xffff0000, v109
	v_pk_add_f32 v[62:63], v[62:63], v[102:103]
	v_pk_add_f32 v[60:61], v[60:61], v[112:113]
	v_pk_add_f32 v[58:59], v[58:59], v[104:105]
	v_pk_add_f32 v[56:57], v[56:57], v[114:115]
	v_pk_add_f32 v[54:55], v[54:55], v[106:107]
	v_pk_add_f32 v[52:53], v[52:53], v[116:117]
	v_pk_add_f32 v[102:103], v[50:51], v[108:109]
	v_pk_add_f32 v[104:105], v[48:49], v[118:119]
	v_mul_f32_e32 v106, v61, v61
	v_mul_f32_e32 v107, v63, v63
	v_mul_f32_e32 v108, v57, v57
	v_mul_f32_e32 v109, v59, v59
	v_cvt_pk_bf16_f32 v48, v60, v61
	v_cvt_pk_bf16_f32 v49, v62, v63
	v_cvt_pk_bf16_f32 v50, v56, v57
	v_cvt_pk_bf16_f32 v51, v58, v59
	v_mul_f32_e32 v57, v53, v53
	v_mul_f32_e32 v59, v55, v55
	v_mul_f32_e32 v61, v105, v105
	v_mul_f32_e32 v63, v103, v103
	v_fmac_f32_e32 v106, v60, v60
	v_fmac_f32_e32 v107, v62, v62
	v_fmac_f32_e32 v108, v56, v56
	v_fmac_f32_e32 v109, v58, v58
	v_fmac_f32_e32 v57, v52, v52
	v_fmac_f32_e32 v59, v54, v54
	v_fmac_f32_e32 v61, v104, v104
	v_fmac_f32_e32 v63, v102, v102
	global_store_dwordx4 v[110:111], v[48:51], off
	s_nop 1
	v_cvt_pk_bf16_f32 v48, v52, v53
	v_cvt_pk_bf16_f32 v49, v54, v55
	v_cvt_pk_bf16_f32 v50, v104, v105
	v_add_f32_e32 v52, v106, v107
	v_add_f32_e32 v53, v108, v109
	v_add_f32_e32 v54, v57, v59
	v_add_f32_e32 v55, v61, v63
	v_cvt_pk_bf16_f32 v51, v102, v103
	global_store_dwordx4 v[110:111], v[48:51], off offset:256
	s_nop 1
	v_add_f32_e32 v48, v52, v53
	v_add_f32_e32 v49, v54, v55
	v_lshlrev_b32_e32 v50, 2, v120
	v_add_f32_e32 v48, v48, v49
	v_xor_b32_e32 v49, 64, v50
	v_mov_b32_e32 v49, v48
	s_nop 1
	v_permlane16_swap_b32_e32 v49, v48
	v_mov_b32_e32 v50, v201
	s_waitcnt lgkmcnt(0)
	v_add_f32_e32 v48, v48, v49
	v_lshlrev_b32_e32 v50, 2, v50
	v_xor_b32_e32 v49, 0x80, v50
	v_mov_b32_e32 v49, v48
	s_nop 1
	v_permlane32_swap_b32_e32 v49, v48
	s_and_saveexec_b64 s[40:41], s[6:7]
	s_cbranch_execz .LBB0_1969
	s_waitcnt lgkmcnt(0)
	v_add_f32_e32 v50, v48, v49
	v_lshlrev_b64 v[48:49], 6, v[100:101]
	v_lshl_add_u64 v[48:49], s[18:19], 0, v[48:49]
	v_lshl_add_u64 v[48:49], s[38:39], 2, v[48:49]
	s_lshl_b32 s10, s33, 2
	v_lshl_add_u64 v[48:49], v[48:49], 0, s[10:11]
	global_store_dword v[48:49], v50, off
; __device__ __forceinline__ float sq4(f32x4 v) { return (v[0] * v[0] + v[1] * v[1]) + (v[2] * v[2] + v[3] * v[3]); }
; __device__ __forceinline__ u32x4 pack8(f32x4 a, f32x4 b) { u32x4 w; w.x = cvt_pk_bf16(a[0], a[1]); w.y = cvt_pk_bf16(a[2], a[3]); w.z = cvt_pk_bf16(b[0], b[1]); w.w = cvt_pk_bf16(b[2], b[3]); return w; }
;     __device__ __forceinline__ void operator()(const f32x4 (&acc)[2][2][4][2], const Unit& u, int wr, int wc, int fr, int fq) const {
;     ...
;         for (int ai = 0; ai < 2; ++ai) {
;             u32x4 bs[4][2];
; #pragma unroll
;             for (int m = 0; m < 4; ++m)
; #pragma unroll
;                 for (int bj = 0; bj < 2; ++bj) bs[m][bj] = *(const u32x4*)(xb + (size_t)(u.pm * BM + ai * HALF + wr * 64 + m * 16 + fr) * 1024 + col0 + 128 * bj);
; #pragma unroll
;             for (int m = 0; m < 4; ++m) {
;                 const int row = u.pm * BM + ai * HALF + wr * 64 + m * 16 + fr;
;                 float q = 0.f;
; #pragma unroll
;                 for (int bj = 0; bj < 2; ++bj) {
;                     const size_t off = (size_t)row * 1024 + col0 + 128 * bj; const u32x4 w = bs[m][bj];
;                     const f32x4 b0 = (f32x4){__builtin_bit_cast(float, w.x << 16), __builtin_bit_cast(float, w.x & 0xffff0000u), __builtin_bit_cast(float, w.y << 16), __builtin_bit_cast(float, w.y & 0xffff0000u)};
;                     const f32x4 b1 = (f32x4){__builtin_bit_cast(float, w.z << 16), __builtin_bit_cast(float, w.z & 0xffff0000u), __builtin_bit_cast(float, w.w << 16), __builtin_bit_cast(float, w.w & 0xffff0000u)};
;                     const f32x4 v0 = acc[ai][bj][m][0] + b0, v1 = acc[ai][bj][m][1] + b1;
;                     if (last) { __builtin_nontemporal_store(v0, (f32x4*)(out + off)); __builtin_nontemporal_store(v1, (f32x4*)(out + off + 4)); }
;                     else { q += sq4(v0) + sq4(v1); *(u32x4*)(xb + off) = pack8(v0, v1); }
;                 }
;                 if (!last) { q += shx(q, 16); q += shx(q, 32); if (fq == 0) ss[(size_t)row * 16 + u.pn * 4 + wc] = q; }
.LBB0_1969:
	s_or_b64 exec, exec, s[40:41]
	s_waitcnt vmcnt(7)
	v_lshlrev_b32_e32 v48, 16, v84
	s_waitcnt lgkmcnt(0)
	v_and_b32_e32 v49, 0xffff0000, v84
	v_lshlrev_b32_e32 v50, 16, v85
	v_and_b32_e32 v51, 0xffff0000, v85
	v_lshlrev_b32_e32 v52, 16, v86
	v_and_b32_e32 v53, 0xffff0000, v86
	v_lshlrev_b32_e32 v54, 16, v87
	v_and_b32_e32 v55, 0xffff0000, v87
	v_pk_add_f32 v[46:47], v[46:47], v[50:51]
	v_pk_add_f32 v[44:45], v[44:45], v[48:49]
	v_pk_add_f32 v[48:49], v[42:43], v[54:55]
	v_pk_add_f32 v[42:43], v[40:41], v[52:53]
	v_mul_f32_e32 v40, v45, v45
	v_mul_f32_e32 v41, v47, v47
	v_fmac_f32_e32 v40, v44, v44
	v_fmac_f32_e32 v41, v46, v46
	v_add_f32_e32 v40, v40, v41
	v_mul_f32_e32 v41, v43, v43
	v_mul_f32_e32 v50, v49, v49
	v_fmac_f32_e32 v41, v42, v42
	v_fmac_f32_e32 v50, v48, v48
	v_add_f32_e32 v41, v41, v50
	v_add_f32_e32 v50, v40, v41
	v_cvt_pk_bf16_f32 v40, v44, v45
	v_lshl_add_u64 v[44:45], s[16:17], 0, v[98:99]
	v_cvt_pk_bf16_f32 v41, v46, v47
	v_cvt_pk_bf16_f32 v42, v42, v43
	v_cvt_pk_bf16_f32 v43, v48, v49
	v_lshl_add_u64 v[44:45], v[168:169], 1, v[44:45]
	global_store_dwordx4 v[44:45], v[40:43], off
	s_waitcnt vmcnt(7)
	v_lshlrev_b32_e32 v46, 16, v82
	v_and_b32_e32 v47, 0xffff0000, v82
	v_lshlrev_b32_e32 v40, 16, v80
	v_and_b32_e32 v41, 0xffff0000, v80
	v_lshlrev_b32_e32 v42, 16, v81
	v_and_b32_e32 v43, 0xffff0000, v81
	v_lshlrev_b32_e32 v48, 16, v83
	v_and_b32_e32 v49, 0xffff0000, v83
	v_pk_add_f32 v[38:39], v[38:39], v[42:43]
	v_pk_add_f32 v[36:37], v[36:37], v[40:41]
	v_pk_add_f32 v[40:41], v[34:35], v[48:49]
	v_pk_add_f32 v[34:35], v[32:33], v[46:47]
	v_mul_f32_e32 v32, v37, v37
	v_mul_f32_e32 v33, v39, v39
	v_fmac_f32_e32 v32, v36, v36
	v_fmac_f32_e32 v33, v38, v38
	v_add_f32_e32 v32, v32, v33
	v_mul_f32_e32 v33, v35, v35
	v_mul_f32_e32 v42, v41, v41
	v_fmac_f32_e32 v33, v34, v34
	v_fmac_f32_e32 v42, v40, v40
	v_add_f32_e32 v33, v33, v42
	v_add_f32_e32 v32, v32, v33
	v_add_f32_e32 v42, v50, v32
	v_cvt_pk_bf16_f32 v32, v36, v37
	v_cvt_pk_bf16_f32 v33, v38, v39
	v_cvt_pk_bf16_f32 v34, v34, v35
	v_cvt_pk_bf16_f32 v35, v40, v41
	global_store_dwordx4 v[44:45], v[32:35], off offset:256
	s_nop 1
	v_mov_b32_e32 v32, v201
	v_mov_b32_e32 v33, v201
	v_lshlrev_b32_e32 v32, 2, v32
	v_xor_b32_e32 v32, 64, v32
	v_mov_b32_e32 v32, v42
	s_nop 1
	v_permlane16_swap_b32_e32 v32, v42
	s_waitcnt lgkmcnt(0)
	v_add_f32_e32 v32, v42, v32
	v_lshlrev_b32_e32 v33, 2, v33
	v_xor_b32_e32 v33, 0x80, v33
	v_mov_b32_e32 v33, v32
	s_nop 1
	v_permlane32_swap_b32_e32 v33, v32
	s_and_saveexec_b64 s[40:41], s[6:7]
	s_cbranch_execz .LBB0_1971
	s_waitcnt lgkmcnt(0)
	v_add_f32_e32 v34, v32, v33
	v_lshlrev_b64 v[32:33], 6, v[96:97]
	v_lshl_add_u64 v[32:33], s[18:19], 0, v[32:33]
	v_lshl_add_u64 v[32:33], s[38:39], 2, v[32:33]
	s_lshl_b32 s10, s33, 2
	v_lshl_add_u64 v[32:33], v[32:33], 0, s[10:11]
	global_store_dword v[32:33], v34, off
; __device__ __forceinline__ float sq4(f32x4 v) { return (v[0] * v[0] + v[1] * v[1]) + (v[2] * v[2] + v[3] * v[3]); }
; __device__ __forceinline__ u32x4 pack8(f32x4 a, f32x4 b) { u32x4 w; w.x = cvt_pk_bf16(a[0], a[1]); w.y = cvt_pk_bf16(a[2], a[3]); w.z = cvt_pk_bf16(b[0], b[1]); w.w = cvt_pk_bf16(b[2], b[3]); return w; }
;     __device__ __forceinline__ void operator()(const f32x4 (&acc)[2][2][4][2], const Unit& u, int wr, int wc, int fr, int fq) const {
;     ...
;         for (int ai = 0; ai < 2; ++ai) {
;             u32x4 bs[4][2];
; #pragma unroll
;             for (int m = 0; m < 4; ++m)
; #pragma unroll
;                 for (int bj = 0; bj < 2; ++bj) bs[m][bj] = *(const u32x4*)(xb + (size_t)(u.pm * BM + ai * HALF + wr * 64 + m * 16 + fr) * 1024 + col0 + 128 * bj);
; #pragma unroll
;             for (int m = 0; m < 4; ++m) {
;                 const int row = u.pm * BM + ai * HALF + wr * 64 + m * 16 + fr;
;                 float q = 0.f;
; #pragma unroll
;                 for (int bj = 0; bj < 2; ++bj) {
;                     const size_t off = (size_t)row * 1024 + col0 + 128 * bj; const u32x4 w = bs[m][bj];
;                     const f32x4 b0 = (f32x4){__builtin_bit_cast(float, w.x << 16), __builtin_bit_cast(float, w.x & 0xffff0000u), __builtin_bit_cast(float, w.y << 16), __builtin_bit_cast(float, w.y & 0xffff0000u)};
;                     const f32x4 b1 = (f32x4){__builtin_bit_cast(float, w.z << 16), __builtin_bit_cast(float, w.z & 0xffff0000u), __builtin_bit_cast(float, w.w << 16), __builtin_bit_cast(float, w.w & 0xffff0000u)};
;                     const f32x4 v0 = acc[ai][bj][m][0] + b0, v1 = acc[ai][bj][m][1] + b1;
;                     if (last) { __builtin_nontemporal_store(v0, (f32x4*)(out + off)); __builtin_nontemporal_store(v1, (f32x4*)(out + off + 4)); }
;                     else { q += sq4(v0) + sq4(v1); *(u32x4*)(xb + off) = pack8(v0, v1); }
;                 }
;                 if (!last) { q += shx(q, 16); q += shx(q, 32); if (fq == 0) ss[(size_t)row * 16 + u.pn * 4 + wc] = q; }
.LBB0_1971:
	s_or_b64 exec, exec, s[40:41]
	s_waitcnt vmcnt(7)
	v_lshlrev_b32_e32 v32, 16, v76
	s_waitcnt lgkmcnt(0)
	v_and_b32_e32 v33, 0xffff0000, v76
	v_lshlrev_b32_e32 v34, 16, v77
	v_and_b32_e32 v35, 0xffff0000, v77
	v_lshlrev_b32_e32 v36, 16, v78
	v_and_b32_e32 v37, 0xffff0000, v78
	v_lshlrev_b32_e32 v38, 16, v79
	v_and_b32_e32 v39, 0xffff0000, v79
	v_pk_add_f32 v[30:31], v[30:31], v[34:35]
	v_pk_add_f32 v[28:29], v[28:29], v[32:33]
	v_pk_add_f32 v[32:33], v[26:27], v[38:39]
	v_pk_add_f32 v[26:27], v[24:25], v[36:37]
	v_mul_f32_e32 v24, v29, v29
	v_mul_f32_e32 v25, v31, v31
	v_fmac_f32_e32 v24, v28, v28
	v_fmac_f32_e32 v25, v30, v30
	v_add_f32_e32 v24, v24, v25
	v_mul_f32_e32 v25, v27, v27
	v_mul_f32_e32 v34, v33, v33
	v_fmac_f32_e32 v25, v26, v26
	v_fmac_f32_e32 v34, v32, v32
	v_add_f32_e32 v25, v25, v34
	v_add_f32_e32 v34, v24, v25
	v_cvt_pk_bf16_f32 v24, v28, v29
	v_lshl_add_u64 v[28:29], s[16:17], 0, v[94:95]
	v_cvt_pk_bf16_f32 v25, v30, v31
	v_cvt_pk_bf16_f32 v26, v26, v27
	v_cvt_pk_bf16_f32 v27, v32, v33
	v_lshl_add_u64 v[28:29], v[168:169], 1, v[28:29]
	global_store_dwordx4 v[28:29], v[24:27], off
	s_waitcnt vmcnt(7)
	v_lshlrev_b32_e32 v30, 16, v74
	v_and_b32_e32 v31, 0xffff0000, v74
	v_lshlrev_b32_e32 v24, 16, v72
	v_and_b32_e32 v25, 0xffff0000, v72
	v_lshlrev_b32_e32 v26, 16, v73
	v_and_b32_e32 v27, 0xffff0000, v73
	v_lshlrev_b32_e32 v32, 16, v75
	v_and_b32_e32 v33, 0xffff0000, v75
	v_pk_add_f32 v[22:23], v[22:23], v[26:27]
	v_pk_add_f32 v[20:21], v[20:21], v[24:25]
	v_pk_add_f32 v[24:25], v[18:19], v[32:33]
	v_pk_add_f32 v[18:19], v[16:17], v[30:31]
	v_mul_f32_e32 v16, v21, v21
	v_mul_f32_e32 v17, v23, v23
	v_fmac_f32_e32 v16, v20, v20
	v_fmac_f32_e32 v17, v22, v22
	v_add_f32_e32 v16, v16, v17
	v_mul_f32_e32 v17, v19, v19
	v_mul_f32_e32 v26, v25, v25
	v_fmac_f32_e32 v17, v18, v18
	v_fmac_f32_e32 v26, v24, v24
	v_add_f32_e32 v17, v17, v26
	v_add_f32_e32 v16, v16, v17
	v_add_f32_e32 v26, v34, v16
	v_cvt_pk_bf16_f32 v16, v20, v21
	v_cvt_pk_bf16_f32 v17, v22, v23
	v_cvt_pk_bf16_f32 v18, v18, v19
	v_cvt_pk_bf16_f32 v19, v24, v25
	global_store_dwordx4 v[28:29], v[16:19], off offset:256
	s_nop 1
	v_mov_b32_e32 v16, v201
	v_mov_b32_e32 v17, v201
	v_lshlrev_b32_e32 v16, 2, v16
	v_xor_b32_e32 v16, 64, v16
	v_mov_b32_e32 v16, v26
	s_nop 1
	v_permlane16_swap_b32_e32 v16, v26
	s_waitcnt lgkmcnt(0)
	v_add_f32_e32 v16, v26, v16
	v_lshlrev_b32_e32 v17, 2, v17
	v_xor_b32_e32 v17, 0x80, v17
	v_mov_b32_e32 v17, v16
	s_nop 1
	v_permlane32_swap_b32_e32 v17, v16
	s_and_saveexec_b64 s[40:41], s[6:7]
	s_cbranch_execz .LBB0_1973
	s_waitcnt lgkmcnt(0)
	v_add_f32_e32 v18, v16, v17
	v_lshlrev_b64 v[16:17], 6, v[92:93]
	v_lshl_add_u64 v[16:17], s[18:19], 0, v[16:17]
	v_lshl_add_u64 v[16:17], s[38:39], 2, v[16:17]
	s_lshl_b32 s10, s33, 2
	v_lshl_add_u64 v[16:17], v[16:17], 0, s[10:11]
	global_store_dword v[16:17], v18, off
.LBB0_1973:
	s_or_b64 exec, exec, s[40:41]
	s_waitcnt vmcnt(7)
	v_lshlrev_b32_e32 v16, 16, v68
	s_waitcnt lgkmcnt(0)
	v_and_b32_e32 v17, 0xffff0000, v68
	v_lshlrev_b32_e32 v18, 16, v69
	v_and_b32_e32 v19, 0xffff0000, v69
	v_lshlrev_b32_e32 v20, 16, v70
	v_and_b32_e32 v21, 0xffff0000, v70
	v_lshlrev_b32_e32 v22, 16, v71
	v_and_b32_e32 v23, 0xffff0000, v71
	v_pk_add_f32 v[14:15], v[14:15], v[18:19]
	v_pk_add_f32 v[12:13], v[12:13], v[16:17]
	v_pk_add_f32 v[16:17], v[10:11], v[22:23]
	v_pk_add_f32 v[10:11], v[8:9], v[20:21]
	v_mul_f32_e32 v8, v13, v13
	v_mul_f32_e32 v9, v15, v15
	v_fmac_f32_e32 v8, v12, v12
	v_fmac_f32_e32 v9, v14, v14
	v_add_f32_e32 v8, v8, v9
	v_mul_f32_e32 v9, v11, v11
	v_mul_f32_e32 v18, v17, v17
	v_fmac_f32_e32 v9, v10, v10
	v_fmac_f32_e32 v18, v16, v16
	v_add_f32_e32 v9, v9, v18
	v_add_f32_e32 v18, v8, v9
	v_cvt_pk_bf16_f32 v8, v12, v13
	v_lshl_add_u64 v[12:13], s[16:17], 0, v[90:91]
	v_cvt_pk_bf16_f32 v9, v14, v15
	v_cvt_pk_bf16_f32 v10, v10, v11
	v_cvt_pk_bf16_f32 v11, v16, v17
	v_lshl_add_u64 v[12:13], v[168:169], 1, v[12:13]
	global_store_dwordx4 v[12:13], v[8:11], off
	s_waitcnt vmcnt(7)
	v_lshlrev_b32_e32 v14, 16, v66
	v_and_b32_e32 v15, 0xffff0000, v66
	v_lshlrev_b32_e32 v8, 16, v64
	v_and_b32_e32 v9, 0xffff0000, v64
	v_lshlrev_b32_e32 v10, 16, v65
	v_and_b32_e32 v11, 0xffff0000, v65
	v_lshlrev_b32_e32 v16, 16, v67
	v_and_b32_e32 v17, 0xffff0000, v67
	v_pk_add_f32 v[6:7], v[6:7], v[10:11]
	v_pk_add_f32 v[4:5], v[4:5], v[8:9]
	v_pk_add_f32 v[8:9], v[2:3], v[16:17]
	v_pk_add_f32 v[2:3], v[0:1], v[14:15]
	v_mul_f32_e32 v0, v5, v5
	v_mul_f32_e32 v1, v7, v7
	v_fmac_f32_e32 v0, v4, v4
	v_fmac_f32_e32 v1, v6, v6
	v_add_f32_e32 v0, v0, v1
	v_mul_f32_e32 v1, v3, v3
	v_mul_f32_e32 v10, v9, v9
	v_fmac_f32_e32 v1, v2, v2
	v_fmac_f32_e32 v10, v8, v8
	v_add_f32_e32 v1, v1, v10
	v_add_f32_e32 v0, v0, v1
	v_add_f32_e32 v10, v18, v0
	v_cvt_pk_bf16_f32 v0, v4, v5
	v_cvt_pk_bf16_f32 v1, v6, v7
	v_cvt_pk_bf16_f32 v2, v2, v3
	v_cvt_pk_bf16_f32 v3, v8, v9
	global_store_dwordx4 v[12:13], v[0:3], off offset:256
	s_nop 1
	v_mov_b32_e32 v0, v201
	v_mov_b32_e32 v1, v201
	v_lshlrev_b32_e32 v0, 2, v0
	v_xor_b32_e32 v0, 64, v0
	v_mov_b32_e32 v0, v10
	s_nop 1
	v_permlane16_swap_b32_e32 v0, v10
	s_waitcnt lgkmcnt(0)
	v_add_f32_e32 v0, v10, v0
	v_lshlrev_b32_e32 v1, 2, v1
	v_xor_b32_e32 v1, 0x80, v1
	v_mov_b32_e32 v1, v0
	s_nop 1
	v_permlane32_swap_b32_e32 v1, v0
	s_and_saveexec_b64 s[40:41], s[6:7]
	s_cbranch_execz .LBB0_1975
	s_waitcnt lgkmcnt(0)
	v_add_f32_e32 v2, v0, v1
	v_lshlrev_b64 v[0:1], 6, v[88:89]
	v_lshl_add_u64 v[0:1], s[18:19], 0, v[0:1]
	v_lshl_add_u64 v[0:1], s[38:39], 2, v[0:1]
	s_lshl_b32 s10, s33, 2
	v_lshl_add_u64 v[0:1], v[0:1], 0, s[10:11]
	global_store_dword v[0:1], v2, off

; __device__ __forceinline__ float row_part(const float* ss, int row, int fq) { const f32x4 a = ((const f32x4*)(ss + (size_t)row * 16))[fq]; return (a[0] + a[1]) + (a[2] + a[3]); }
; __device__ __forceinline__ float row_finish(float t) { t += shx(t, 16); t += shx(t, 32); return __builtin_amdgcn_rsqf(t * (1.0f / 1024.0f) + RMS_EPS); }
;     __device__ __forceinline__ void operator()(const f32x4 (&acc)[2][2][4][2], const Unit& u, int wr, int wc, int fr, int fq) const {
;     ...
;         float rs[2][4];
; #pragma unroll
;         for (int ai = 0; ai < 2; ++ai)
; #pragma unroll
;             for (int m = 0; m < 4; ++m) rs[ai][m] = row_part(ss, u.pm * BM + ai * HALF + wr * 64 + m * 16 + fr, fq);
; #pragma unroll
;         for (int ai = 0; ai < 2; ++ai)
; #pragma unroll
;             for (int m = 0; m < 4; ++m) rs[ai][m] = row_finish(rs[ai][m]);
.LBB0_2043:
	v_lshl_add_u32 v170, s24, 8, v153
	v_ashrrev_i32_e32 v171, 31, v170
	v_or_b32_e32 v166, 16, v170
	v_lshlrev_b64 v[146:147], 6, v[170:171]
	v_ashrrev_i32_e32 v167, 31, v166
	v_lshl_add_u64 v[146:147], v[136:137], 0, v[146:147]
	v_lshlrev_b64 v[148:149], 6, v[166:167]
	v_lshl_add_u64 v[148:149], v[136:137], 0, v[148:149]
	ds_read_b128 v[176:179], v239
	ds_read_b128 v[180:183], v239 offset:1024
	v_or_b32_e32 v162, 32, v170
	v_ashrrev_i32_e32 v163, 31, v162
	v_or_b32_e32 v158, 48, v170
	v_lshlrev_b64 v[146:147], 6, v[162:163]
	v_ashrrev_i32_e32 v159, 31, v158
	v_lshl_add_u64 v[146:147], v[136:137], 0, v[146:147]
	v_lshlrev_b64 v[148:149], 6, v[158:159]
	v_lshl_add_u64 v[148:149], v[136:137], 0, v[148:149]
	ds_read_b128 v[184:187], v239 offset:2048
	ds_read_b128 v[188:191], v239 offset:3072
	v_add_u32_e32 v154, 0x80, v170
	v_ashrrev_i32_e32 v155, 31, v154
	v_add_u32_e32 v150, 0x90, v170
	v_lshlrev_b64 v[146:147], 6, v[154:155]
	v_ashrrev_i32_e32 v151, 31, v150
	v_lshl_add_u64 v[146:147], v[136:137], 0, v[146:147]
	v_lshlrev_b64 v[148:149], 6, v[150:151]
	v_lshl_add_u64 v[148:149], v[136:137], 0, v[148:149]
	ds_read_b128 v[192:195], v239 offset:8192
	ds_read_b128 v[196:199], v239 offset:9216
	v_add_u32_e32 v148, 0xa0, v170
	v_ashrrev_i32_e32 v149, 31, v148
	v_lshlrev_b64 v[146:147], 6, v[148:149]
	v_lshl_add_u64 v[146:147], v[136:137], 0, v[146:147]
	ds_read_b128 v[202:205], v239 offset:10240
	v_add_u32_e32 v146, 0xb0, v170
	v_ashrrev_i32_e32 v147, 31, v146
	v_lshlrev_b64 v[206:207], 6, v[146:147]
	v_lshl_add_u64 v[206:207], v[136:137], 0, v[206:207]
	ds_read_b128 v[206:209], v239 offset:11264
	v_mov_b32_e32 v147, v201
	v_mov_b32_e32 v149, v201
	v_lshlrev_b32_e32 v147, 2, v147
	v_mov_b32_e32 v151, v201
	v_xor_b32_e32 v147, 64, v147
	s_andn2_b64 vcc, exec, s[6:7]
	v_lshlrev_b32_e32 v151, 2, v151
	v_xor_b32_e32 v151, 64, v151
	v_lshlrev_b32_e32 v149, 2, v149
	v_xor_b32_e32 v149, 0x80, v149
	s_mov_b64 s[6:7], -1
	s_waitcnt lgkmcnt(0)
	v_mov_b32_e32 v210, v177
	v_mov_b32_e32 v211, v178
	v_mov_b32_e32 v177, v179
	v_pk_add_f32 v[176:177], v[210:211], v[176:177]
	v_mov_b32_e32 v178, v181
	v_add_f32_e32 v152, v176, v177
	v_mov_b32_e32 v179, v182
	v_mov_b32_e32 v181, v183
	v_mov_b32_e32 v147, v152
	s_nop 1
	v_permlane16_swap_b32_e32 v147, v152
	v_pk_add_f32 v[176:177], v[178:179], v[180:181]
	v_mov_b32_e32 v182, v185
	v_add_f32_e32 v155, v176, v177
	v_mov_b32_e32 v151, v155
	s_nop 1
	v_permlane16_swap_b32_e32 v151, v155
	s_waitcnt lgkmcnt(0)
	v_add_f32_e32 v147, v152, v147
	v_mov_b32_e32 v152, v201
	v_mov_b32_e32 v149, v147
	s_nop 1
	v_permlane32_swap_b32_e32 v149, v147
	s_waitcnt lgkmcnt(0)
	v_add_f32_e32 v151, v155, v151
	v_lshlrev_b32_e32 v152, 2, v152
	v_xor_b32_e32 v152, 0x80, v152
	v_mov_b32_e32 v152, v151
	s_nop 1
	v_permlane32_swap_b32_e32 v152, v151
	s_waitcnt lgkmcnt(0)
	v_add_f32_e32 v147, v147, v149
	v_mov_b32_e32 v149, v201
	v_mov_b32_e32 v183, v186
	v_mov_b32_e32 v185, v187
	v_pk_add_f32 v[178:179], v[182:183], v[184:185]
	v_fmamk_f32 v147, v147, 0x3a800000, v175
	v_lshlrev_b32_e32 v149, 2, v149
	v_add_f32_e32 v156, v178, v179
	v_rsq_f32_e32 v176, v147
	s_waitcnt lgkmcnt(0)
	v_add_f32_e32 v147, v151, v152
	v_xor_b32_e32 v149, 64, v149
	v_mov_b32_e32 v151, v201
	v_mov_b32_e32 v152, v201
	v_mov_b32_e32 v186, v189
	v_mov_b32_e32 v187, v190
	v_mov_b32_e32 v189, v191
	v_mov_b32_e32 v149, v156
	s_nop 1
	v_permlane16_swap_b32_e32 v149, v156
	v_pk_add_f32 v[180:181], v[186:187], v[188:189]
	v_lshlrev_b32_e32 v152, 2, v152
	v_add_f32_e32 v159, v180, v181
	v_xor_b32_e32 v152, 64, v152
	v_mov_b32_e32 v152, v159
	s_nop 1
	v_permlane16_swap_b32_e32 v152, v159
	s_waitcnt lgkmcnt(0)
	v_add_f32_e32 v149, v156, v149
	v_lshlrev_b32_e32 v151, 2, v151
	v_mov_b32_e32 v156, v201
	v_xor_b32_e32 v151, 0x80, v151
	v_mov_b32_e32 v151, v149
	s_nop 1
	v_permlane32_swap_b32_e32 v151, v149
	v_lshlrev_b32_e32 v156, 2, v156
	s_waitcnt lgkmcnt(0)
	v_add_f32_e32 v152, v159, v152
	v_xor_b32_e32 v156, 0x80, v156
	v_mov_b32_e32 v156, v152
	s_nop 1
	v_permlane32_swap_b32_e32 v156, v152
	v_fmamk_f32 v147, v147, 0x3a800000, v175
	v_rsq_f32_e32 v174, v147
	s_waitcnt lgkmcnt(0)
	v_add_f32_e32 v147, v149, v151
	v_mov_b32_e32 v149, v201
	v_mov_b32_e32 v190, v193
	v_mov_b32_e32 v191, v194
	v_mov_b32_e32 v193, v195
	v_fmamk_f32 v147, v147, 0x3a800000, v175
	v_pk_add_f32 v[182:183], v[190:191], v[192:193]
	v_rsq_f32_e32 v172, v147
	s_waitcnt lgkmcnt(0)
	v_add_f32_e32 v147, v152, v156
	v_lshlrev_b32_e32 v149, 2, v149
	v_mov_b32_e32 v151, v201
	v_mov_b32_e32 v152, v201
	v_mov_b32_e32 v194, v197
	v_mov_b32_e32 v195, v198
	v_mov_b32_e32 v197, v199
	v_add_f32_e32 v160, v182, v183
	v_xor_b32_e32 v149, 64, v149
	v_pk_add_f32 v[184:185], v[194:195], v[196:197]
	v_mov_b32_e32 v149, v160
	s_nop 1
	v_permlane16_swap_b32_e32 v149, v160
	v_lshlrev_b32_e32 v152, 2, v152
	v_add_f32_e32 v163, v184, v185
	v_xor_b32_e32 v152, 64, v152
	v_mov_b32_e32 v152, v163
	s_nop 1
	v_permlane16_swap_b32_e32 v152, v163
	v_lshlrev_b32_e32 v151, 2, v151
	v_mov_b32_e32 v156, v201
	s_waitcnt lgkmcnt(0)
	v_add_f32_e32 v149, v160, v149
	v_xor_b32_e32 v151, 0x80, v151
	v_mov_b32_e32 v151, v149
	s_nop 1
	v_permlane32_swap_b32_e32 v151, v149
	v_lshlrev_b32_e32 v156, 2, v156
	s_waitcnt lgkmcnt(0)
	v_add_f32_e32 v152, v163, v152
	v_xor_b32_e32 v156, 0x80, v156
	v_mov_b32_e32 v156, v152
	s_nop 1
	v_permlane32_swap_b32_e32 v156, v152
	v_fmamk_f32 v147, v147, 0x3a800000, v175
	v_rsq_f32_e32 v168, v147
	s_waitcnt lgkmcnt(0)
	v_add_f32_e32 v147, v149, v151
	v_fmamk_f32 v147, v147, 0x3a800000, v175
	v_rsq_f32_e32 v164, v147
	s_waitcnt lgkmcnt(0)
; __device__ __forceinline__ float row_finish(float t) { t += shx(t, 16); t += shx(t, 32); return __builtin_amdgcn_rsqf(t * (1.0f / 1024.0f) + RMS_EPS); }
; __device__ __forceinline__ f32x4 silu4(f32x4 v) { return (f32x4){silu_f(v[0]), silu_f(v[1]), silu_f(v[2]), silu_f(v[3])}; }
; __device__ __forceinline__ u32x4 pack8(f32x4 a, f32x4 b) { u32x4 w; w.x = cvt_pk_bf16(a[0], a[1]); w.y = cvt_pk_bf16(a[2], a[3]); w.z = cvt_pk_bf16(b[0], b[1]); w.w = cvt_pk_bf16(b[2], b[3]); return w; }
;     __device__ __forceinline__ void operator()(const f32x4 (&acc)[2][2][4][2], const Unit& u, int wr, int wc, int fr, int fq) const {
;     ...
;         for (int ai = 0; ai < 2; ++ai)
; #pragma unroll
;             for (int m = 0; m < 4; ++m) rs[ai][m] = row_finish(rs[ai][m]);
; #pragma unroll
;         for (int ai = 0; ai < 2; ++ai)
; #pragma unroll
;             for (int m = 0; m < 4; ++m) {
;                 const int row = u.pm * BM + ai * HALF + wr * 64 + m * 16 + fr;
;                 const float rstd = rs[ai][m];
;                 const f32x4 a0 = silu4(acc[ai][0][m][0] * rstd) * (acc[ai][1][m][0] * rstd);
;                 const f32x4 a1 = silu4(acc[ai][0][m][1] * rstd) * (acc[ai][1][m][1] * rstd);
;                 *(u32x4*)(ACT + (size_t)row * 2816 + col0) = pack8(a0, a1);
	v_add_f32_e32 v147, v152, v156
	v_mov_b32_e32 v149, v201
	v_mov_b32_e32 v151, v201
	v_mov_b32_e32 v152, v201
	v_mov_b32_e32 v198, v203
	v_mov_b32_e32 v199, v204
	v_mov_b32_e32 v203, v205
	v_mov_b32_e32 v204, v207
	v_mov_b32_e32 v205, v208
	v_mov_b32_e32 v207, v209
	v_pk_add_f32 v[188:189], v[204:205], v[206:207]
	v_lshlrev_b32_e32 v152, 2, v152
	v_pk_add_f32 v[186:187], v[198:199], v[202:203]
	v_add_f32_e32 v155, v188, v189
	v_lshlrev_b32_e32 v149, 2, v149
	v_xor_b32_e32 v152, 64, v152
	v_add_f32_e32 v167, v186, v187
	v_xor_b32_e32 v149, 64, v149
	v_mov_b32_e32 v152, v155
	s_nop 1
	v_permlane16_swap_b32_e32 v152, v155
	v_mov_b32_e32 v149, v167
	s_nop 1
	v_permlane16_swap_b32_e32 v149, v167
	v_lshlrev_b32_e32 v151, 2, v151
	v_xor_b32_e32 v151, 0x80, v151
	v_fmamk_f32 v147, v147, 0x3a800000, v175
	s_waitcnt lgkmcnt(0)
	v_add_f32_e32 v152, v155, v152
	v_mov_b32_e32 v155, v201
	s_waitcnt lgkmcnt(0)
	v_add_f32_e32 v149, v167, v149
	v_mov_b32_e32 v151, v149
	s_nop 1
	v_permlane32_swap_b32_e32 v151, v149
	v_lshlrev_b32_e32 v155, 2, v155
	v_xor_b32_e32 v155, 0x80, v155
	v_mov_b32_e32 v155, v152
	s_nop 1
	v_permlane32_swap_b32_e32 v155, v152
	v_rsq_f32_e32 v160, v147
	s_waitcnt lgkmcnt(0)
	v_add_f32_e32 v147, v149, v151
	v_fmamk_f32 v147, v147, 0x3a800000, v175
	v_rsq_f32_e32 v156, v147
	s_waitcnt lgkmcnt(0)
	v_add_f32_e32 v147, v152, v155
	v_fmamk_f32 v147, v147, 0x3a800000, v175
	v_pk_mul_f32 v[124:125], v[124:125], v[176:177] op_sel_hi:[1,0]
	v_rsq_f32_e32 v152, v147
	v_mul_f32_e32 v147, 0xbfb8aa3b, v124
	v_exp_f32_e32 v147, v147
	v_mul_f32_e32 v149, 0xbfb8aa3b, v125
	v_exp_f32_e32 v149, v149
	v_pk_mul_f32 v[126:127], v[126:127], v[176:177] op_sel_hi:[1,0]
	v_add_f32_e32 v147, 1.0, v147
	v_rcp_f32_e32 v178, v147
	v_add_f32_e32 v147, 1.0, v149
	v_mul_f32_e32 v149, 0xbfb8aa3b, v126
	v_exp_f32_e32 v149, v149
	v_mul_f32_e32 v151, 0xbfb8aa3b, v127
	v_exp_f32_e32 v151, v151
	v_rcp_f32_e32 v179, v147
	v_add_f32_e32 v147, 1.0, v149
	v_rcp_f32_e32 v180, v147
	v_add_f32_e32 v147, 1.0, v151
	v_pk_mul_f32 v[120:121], v[120:121], v[176:177] op_sel_hi:[1,0]
	v_rcp_f32_e32 v181, v147
	v_mul_f32_e32 v147, 0xbfb8aa3b, v120
	v_exp_f32_e32 v147, v147
	v_mul_f32_e32 v149, 0xbfb8aa3b, v121
	v_exp_f32_e32 v149, v149
	v_pk_mul_f32 v[122:123], v[122:123], v[176:177] op_sel_hi:[1,0]
	v_add_f32_e32 v147, 1.0, v147
	v_pk_mul_f32 v[124:125], v[124:125], v[178:179]
	v_rcp_f32_e32 v178, v147
	v_add_f32_e32 v147, 1.0, v149
	v_mul_f32_e32 v149, 0xbfb8aa3b, v122
	v_exp_f32_e32 v149, v149
	v_mul_f32_e32 v151, 0xbfb8aa3b, v123
	v_exp_f32_e32 v151, v151
	v_rcp_f32_e32 v179, v147
	v_add_f32_e32 v147, 1.0, v149
	v_pk_mul_f32 v[126:127], v[126:127], v[180:181]
	v_rcp_f32_e32 v180, v147
	v_add_f32_e32 v147, 1.0, v151
	v_rcp_f32_e32 v181, v147
	v_pk_mul_f32 v[116:117], v[116:117], v[176:177] op_sel_hi:[1,0]
	v_pk_mul_f32 v[118:119], v[118:119], v[176:177] op_sel_hi:[1,0]
	v_pk_mul_f32 v[120:121], v[120:121], v[178:179]
	v_pk_mul_f32 v[112:113], v[112:113], v[176:177] op_sel_hi:[1,0]
	v_lshl_or_b32 v182, s48, 7, v161
	v_pk_mul_f32 v[118:119], v[118:119], v[126:127]
	v_pk_mul_f32 v[116:117], v[116:117], v[124:125]
	v_pk_mul_f32 v[122:123], v[122:123], v[180:181]
	v_pk_mul_f32 v[114:115], v[114:115], v[176:177] op_sel_hi:[1,0]
	v_pk_mul_f32 v[112:113], v[112:113], v[120:121]
	v_ashrrev_i32_e32 v183, 31, v182
	v_pk_mul_f32 v[114:115], v[114:115], v[122:123]
	v_cvt_pk_bf16_f32 v116, v116, v117
	v_cvt_pk_bf16_f32 v117, v118, v119
	v_cvt_pk_bf16_f32 v118, v112, v113
	v_mov_b64_e32 v[112:113], s[10:11]
	v_cvt_pk_bf16_f32 v119, v114, v115
	v_mad_i64_i32 v[120:121], s[26:27], v170, s47, v[112:113]
	v_lshlrev_b64 v[114:115], 1, v[182:183]
	v_pk_mul_f32 v[108:109], v[108:109], v[174:175] op_sel_hi:[1,0]
	v_pk_mul_f32 v[110:111], v[110:111], v[174:175] op_sel_hi:[1,0]
	v_mul_f32_e32 v122, 0xbfb8aa3b, v108
	v_mul_f32_e32 v123, 0xbfb8aa3b, v109
	v_lshl_add_u64 v[120:121], v[120:121], 0, v[114:115]
	v_pk_mul_f32 v[104:105], v[104:105], v[174:175] op_sel_hi:[1,0]
	v_pk_mul_f32 v[106:107], v[106:107], v[174:175] op_sel_hi:[1,0]
	v_exp_f32_e32 v122, v122
	v_exp_f32_e32 v123, v123
	v_mul_f32_e32 v124, 0xbfb8aa3b, v110
	v_mul_f32_e32 v125, 0xbfb8aa3b, v111
	global_store_dwordx4 v[120:121], v[116:119], off
	v_exp_f32_e32 v124, v124
	v_exp_f32_e32 v125, v125
	v_mul_f32_e32 v116, 0xbfb8aa3b, v104
	v_mul_f32_e32 v117, 0xbfb8aa3b, v105
	v_mul_f32_e32 v118, 0xbfb8aa3b, v106
	v_mul_f32_e32 v119, 0xbfb8aa3b, v107
	v_exp_f32_e32 v116, v116
	v_exp_f32_e32 v117, v117
	v_exp_f32_e32 v118, v118
	v_exp_f32_e32 v119, v119
	v_add_f32_e32 v122, 1.0, v122
	v_add_f32_e32 v123, 1.0, v123
	v_rcp_f32_e32 v122, v122
	v_rcp_f32_e32 v123, v123
	v_add_f32_e32 v124, 1.0, v124
	v_add_f32_e32 v125, 1.0, v125
	v_add_f32_e32 v116, 1.0, v116
	v_add_f32_e32 v117, 1.0, v117
	v_add_f32_e32 v118, 1.0, v118
	v_add_f32_e32 v119, 1.0, v119
	v_rcp_f32_e32 v124, v124
	v_rcp_f32_e32 v125, v125
	v_rcp_f32_e32 v116, v116
	v_rcp_f32_e32 v117, v117
	v_rcp_f32_e32 v118, v118
	v_rcp_f32_e32 v119, v119
	v_pk_mul_f32 v[108:109], v[108:109], v[122:123]
	v_pk_mul_f32 v[100:101], v[100:101], v[174:175] op_sel_hi:[1,0]
	v_pk_mul_f32 v[110:111], v[110:111], v[124:125]
	v_pk_mul_f32 v[102:103], v[102:103], v[174:175] op_sel_hi:[1,0]
	v_pk_mul_f32 v[100:101], v[100:101], v[108:109]
	v_pk_mul_f32 v[104:105], v[104:105], v[116:117]
	v_pk_mul_f32 v[106:107], v[106:107], v[118:119]
	v_pk_mul_f32 v[96:97], v[96:97], v[174:175] op_sel_hi:[1,0]
	v_pk_mul_f32 v[98:99], v[98:99], v[174:175] op_sel_hi:[1,0]
	v_pk_mul_f32 v[102:103], v[102:103], v[110:111]
	v_pk_mul_f32 v[106:107], v[98:99], v[106:107]
	v_pk_mul_f32 v[98:99], v[96:97], v[104:105]
	v_cvt_pk_bf16_f32 v96, v100, v101
; __device__ __forceinline__ f32x4 silu4(f32x4 v) { return (f32x4){silu_f(v[0]), silu_f(v[1]), silu_f(v[2]), silu_f(v[3])}; }
; __device__ __forceinline__ u32x4 pack8(f32x4 a, f32x4 b) { u32x4 w; w.x = cvt_pk_bf16(a[0], a[1]); w.y = cvt_pk_bf16(a[2], a[3]); w.z = cvt_pk_bf16(b[0], b[1]); w.w = cvt_pk_bf16(b[2], b[3]); return w; }
;     __device__ __forceinline__ void operator()(const f32x4 (&acc)[2][2][4][2], const Unit& u, int wr, int wc, int fr, int fq) const {
;     ...
;         for (int ai = 0; ai < 2; ++ai)
; #pragma unroll
;             for (int m = 0; m < 4; ++m) {
;                 const int row = u.pm * BM + ai * HALF + wr * 64 + m * 16 + fr;
;                 const float rstd = rs[ai][m];
;                 const f32x4 a0 = silu4(acc[ai][0][m][0] * rstd) * (acc[ai][1][m][0] * rstd);
;                 const f32x4 a1 = silu4(acc[ai][0][m][1] * rstd) * (acc[ai][1][m][1] * rstd);
;                 *(u32x4*)(ACT + (size_t)row * 2816 + col0) = pack8(a0, a1);
;             }
	v_mad_i64_i32 v[100:101], s[26:27], v166, s47, v[112:113]
	v_pk_mul_f32 v[92:93], v[92:93], v[172:173] op_sel_hi:[1,0]
	v_cvt_pk_bf16_f32 v97, v102, v103
	v_cvt_pk_bf16_f32 v98, v98, v99
	v_cvt_pk_bf16_f32 v99, v106, v107
	v_pk_mul_f32 v[94:95], v[94:95], v[172:173] op_sel_hi:[1,0]
	v_mul_f32_e32 v102, 0xbfb8aa3b, v92
	v_mul_f32_e32 v103, 0xbfb8aa3b, v93
	v_lshl_add_u64 v[100:101], v[100:101], 0, v[114:115]
	v_pk_mul_f32 v[88:89], v[88:89], v[172:173] op_sel_hi:[1,0]
	v_pk_mul_f32 v[90:91], v[90:91], v[172:173] op_sel_hi:[1,0]
	v_exp_f32_e32 v102, v102
	v_exp_f32_e32 v103, v103
	v_mul_f32_e32 v104, 0xbfb8aa3b, v94
	v_mul_f32_e32 v105, 0xbfb8aa3b, v95
	global_store_dwordx4 v[100:101], v[96:99], off
	v_exp_f32_e32 v104, v104
	v_exp_f32_e32 v105, v105
	v_mul_f32_e32 v96, 0xbfb8aa3b, v88
	v_mul_f32_e32 v97, 0xbfb8aa3b, v89
	v_mul_f32_e32 v98, 0xbfb8aa3b, v90
	v_mul_f32_e32 v99, 0xbfb8aa3b, v91
	v_exp_f32_e32 v96, v96
	v_exp_f32_e32 v97, v97
	v_exp_f32_e32 v98, v98
	v_exp_f32_e32 v99, v99
	v_add_f32_e32 v102, 1.0, v102
	v_add_f32_e32 v103, 1.0, v103
	v_rcp_f32_e32 v102, v102
	v_rcp_f32_e32 v103, v103
	v_add_f32_e32 v104, 1.0, v104
	v_add_f32_e32 v105, 1.0, v105
	v_add_f32_e32 v96, 1.0, v96
	v_add_f32_e32 v97, 1.0, v97
	v_add_f32_e32 v98, 1.0, v98
	v_add_f32_e32 v99, 1.0, v99
	v_rcp_f32_e32 v104, v104
	v_rcp_f32_e32 v105, v105
	v_rcp_f32_e32 v96, v96
	v_rcp_f32_e32 v97, v97
	v_rcp_f32_e32 v98, v98
	v_rcp_f32_e32 v99, v99
	v_pk_mul_f32 v[92:93], v[92:93], v[102:103]
	v_pk_mul_f32 v[84:85], v[84:85], v[172:173] op_sel_hi:[1,0]
	v_pk_mul_f32 v[94:95], v[94:95], v[104:105]
	v_pk_mul_f32 v[86:87], v[86:87], v[172:173] op_sel_hi:[1,0]
	v_pk_mul_f32 v[84:85], v[84:85], v[92:93]
	v_pk_mul_f32 v[88:89], v[88:89], v[96:97]
	v_pk_mul_f32 v[90:91], v[90:91], v[98:99]
	v_pk_mul_f32 v[80:81], v[80:81], v[172:173] op_sel_hi:[1,0]
	v_pk_mul_f32 v[82:83], v[82:83], v[172:173] op_sel_hi:[1,0]
	v_pk_mul_f32 v[86:87], v[86:87], v[94:95]
	v_pk_mul_f32 v[90:91], v[82:83], v[90:91]
	v_pk_mul_f32 v[82:83], v[80:81], v[88:89]
	v_cvt_pk_bf16_f32 v80, v84, v85
	v_mad_i64_i32 v[84:85], s[26:27], v162, s47, v[112:113]
	v_pk_mul_f32 v[76:77], v[76:77], v[168:169] op_sel_hi:[1,0]
	v_cvt_pk_bf16_f32 v81, v86, v87
	v_cvt_pk_bf16_f32 v82, v82, v83
	v_cvt_pk_bf16_f32 v83, v90, v91
	v_pk_mul_f32 v[78:79], v[78:79], v[168:169] op_sel_hi:[1,0]
	v_mul_f32_e32 v86, 0xbfb8aa3b, v76
	v_mul_f32_e32 v87, 0xbfb8aa3b, v77
	v_lshl_add_u64 v[84:85], v[84:85], 0, v[114:115]
	v_pk_mul_f32 v[72:73], v[72:73], v[168:169] op_sel_hi:[1,0]
	v_pk_mul_f32 v[74:75], v[74:75], v[168:169] op_sel_hi:[1,0]
	v_exp_f32_e32 v86, v86
	v_exp_f32_e32 v87, v87
	v_mul_f32_e32 v88, 0xbfb8aa3b, v78
	v_mul_f32_e32 v89, 0xbfb8aa3b, v79
	global_store_dwordx4 v[84:85], v[80:83], off
	v_exp_f32_e32 v88, v88
	v_exp_f32_e32 v89, v89
	v_mul_f32_e32 v80, 0xbfb8aa3b, v72
	v_mul_f32_e32 v81, 0xbfb8aa3b, v73
	v_mul_f32_e32 v82, 0xbfb8aa3b, v74
	v_mul_f32_e32 v83, 0xbfb8aa3b, v75
	v_exp_f32_e32 v80, v80
	v_exp_f32_e32 v81, v81
	v_exp_f32_e32 v82, v82
	v_exp_f32_e32 v83, v83
	v_add_f32_e32 v86, 1.0, v86
	v_add_f32_e32 v87, 1.0, v87
	v_rcp_f32_e32 v86, v86
	v_rcp_f32_e32 v87, v87
	v_add_f32_e32 v88, 1.0, v88
	v_add_f32_e32 v89, 1.0, v89
	v_add_f32_e32 v80, 1.0, v80
	v_add_f32_e32 v81, 1.0, v81
	v_add_f32_e32 v82, 1.0, v82
	v_add_f32_e32 v83, 1.0, v83
	v_rcp_f32_e32 v88, v88
	v_rcp_f32_e32 v89, v89
	v_rcp_f32_e32 v80, v80
	v_rcp_f32_e32 v81, v81
	v_rcp_f32_e32 v82, v82
	v_rcp_f32_e32 v83, v83
	v_pk_mul_f32 v[76:77], v[76:77], v[86:87]
	v_pk_mul_f32 v[68:69], v[68:69], v[168:169] op_sel_hi:[1,0]
	v_pk_mul_f32 v[78:79], v[78:79], v[88:89]
	v_pk_mul_f32 v[70:71], v[70:71], v[168:169] op_sel_hi:[1,0]
	v_pk_mul_f32 v[68:69], v[68:69], v[76:77]
	v_pk_mul_f32 v[72:73], v[72:73], v[80:81]
	v_pk_mul_f32 v[74:75], v[74:75], v[82:83]
	v_pk_mul_f32 v[64:65], v[64:65], v[168:169] op_sel_hi:[1,0]
	v_pk_mul_f32 v[66:67], v[66:67], v[168:169] op_sel_hi:[1,0]
	v_pk_mul_f32 v[70:71], v[70:71], v[78:79]
	v_pk_mul_f32 v[74:75], v[66:67], v[74:75]
	v_pk_mul_f32 v[66:67], v[64:65], v[72:73]
	v_cvt_pk_bf16_f32 v64, v68, v69
	v_mad_i64_i32 v[68:69], s[26:27], v158, s47, v[112:113]
	v_pk_mul_f32 v[60:61], v[60:61], v[164:165] op_sel_hi:[1,0]
	v_cvt_pk_bf16_f32 v65, v70, v71
	v_cvt_pk_bf16_f32 v66, v66, v67
	v_cvt_pk_bf16_f32 v67, v74, v75
	v_pk_mul_f32 v[62:63], v[62:63], v[164:165] op_sel_hi:[1,0]
	v_mul_f32_e32 v70, 0xbfb8aa3b, v60
	v_mul_f32_e32 v71, 0xbfb8aa3b, v61
	v_lshl_add_u64 v[68:69], v[68:69], 0, v[114:115]
	v_pk_mul_f32 v[56:57], v[56:57], v[164:165] op_sel_hi:[1,0]
	v_pk_mul_f32 v[58:59], v[58:59], v[164:165] op_sel_hi:[1,0]
	v_exp_f32_e32 v70, v70
	v_exp_f32_e32 v71, v71
	v_mul_f32_e32 v72, 0xbfb8aa3b, v62
	v_mul_f32_e32 v73, 0xbfb8aa3b, v63
	global_store_dwordx4 v[68:69], v[64:67], off
	v_exp_f32_e32 v72, v72
	v_exp_f32_e32 v73, v73
	v_mul_f32_e32 v64, 0xbfb8aa3b, v56
	v_mul_f32_e32 v65, 0xbfb8aa3b, v57
	v_mul_f32_e32 v66, 0xbfb8aa3b, v58
	v_mul_f32_e32 v67, 0xbfb8aa3b, v59
	v_exp_f32_e32 v64, v64
	v_exp_f32_e32 v65, v65
	v_exp_f32_e32 v66, v66
	v_exp_f32_e32 v67, v67
	v_add_f32_e32 v70, 1.0, v70
	v_add_f32_e32 v71, 1.0, v71
	v_rcp_f32_e32 v70, v70
	v_rcp_f32_e32 v71, v71
	v_add_f32_e32 v72, 1.0, v72
	v_add_f32_e32 v73, 1.0, v73
	v_add_f32_e32 v64, 1.0, v64
	v_add_f32_e32 v65, 1.0, v65
	v_add_f32_e32 v66, 1.0, v66
	v_add_f32_e32 v67, 1.0, v67
	v_rcp_f32_e32 v72, v72
	v_rcp_f32_e32 v73, v73
	v_rcp_f32_e32 v64, v64
	v_rcp_f32_e32 v65, v65
	v_rcp_f32_e32 v66, v66
	v_rcp_f32_e32 v67, v67
	v_pk_mul_f32 v[60:61], v[60:61], v[70:71]
	v_pk_mul_f32 v[52:53], v[52:53], v[164:165] op_sel_hi:[1,0]
	v_pk_mul_f32 v[62:63], v[62:63], v[72:73]
; #define PG8_WAIT_V(n) asm volatile("s_waitcnt vmcnt(" #n ")" ::: "memory")
;     __device__ __forceinline__ void operator()(const f32x4 (&acc)[2][2][4][2], const Unit& u, int wr, int wc, int fr, int fq) const {
;     ...
;         for (int ai = 0; ai < 2; ++ai)
; #pragma unroll
;             for (int m = 0; m < 4; ++m) {
;                 const int row = u.pm * BM + ai * HALF + wr * 64 + m * 16 + fr;
;                 const float rstd = rs[ai][m];
;                 const f32x4 a0 = silu4(acc[ai][0][m][0] * rstd) * (acc[ai][1][m][0] * rstd);
;                 const f32x4 a1 = silu4(acc[ai][0][m][1] * rstd) * (acc[ai][1][m][1] * rstd);
;                 *(u32x4*)(ACT + (size_t)row * 2816 + col0) = pack8(a0, a1);
;             }
; template <class Epi, class Sched, bool ALIGN_EPI = false, bool SP2 = false>
; __device__ __forceinline__ void gemm_phase(PG8_LAS unsigned char* lds, const Gemm g, const Sched& S, const Epi& E, int tid_in) {
;     ...
;     for (;;) {
;         const bool has_next = S.next(ui + 1, nxt);
;         const char* nA = has_next ? (const char*)g.A + (size_t)nxt.pm * tstep : cA; const char* nB = has_next ? (const char*)g.Bt + (size_t)nxt.pn * tstep : cB;
;         for (int t = 0; t < nt; t += 2) {
;             const bool last = (t == nt - 2);
;             const char* a1 = cA + (size_t)(t + 1) * kstep;
;             const char* a2 = last ? nA : cA + (size_t)(t + 2) * kstep; const char* b2 = last ? nB : cB + (size_t)(t + 2) * kstep;
;             const char* a3 = a2 + kstep; const char* b3 = b2 + kstep;
;             if (last && has_next) S.a_ready(nxt);
;             if constexpr (SP2) {
;             PG8_LDB(B0, 0, 0); PG8_LDB(B1, 0, 1); PG8_SCHED; PG8_LDA(At, 0, 0); PG8_STAGE(PG8_SA(1, 1), a1 + hstep, voffA);
;             PG8_WAIT_V(8); PG8_WAIT_L(0); PG8_BAR; PG8_MMA(0, 0, At, B0); PG8_MMA(0, 1, At, B1); PG8_BAR; PG8_SCHED;
;             PG8_LDA(At, 0, 1); PG8_STAGE(PG8_SB(0, 0), b2, voffB); PG8_STAGE(PG8_SB(0, 1), b2 + hstep, voffB); PG8_STAGE(PG8_SA(0, 0), a2, voffA);
;             PG8_WAIT_V(8); PG8_WAIT_L(0); PG8_BAR; PG8_MMA(1, 0, At, B0); PG8_MMA(1, 1, At, B1); PG8_BAR; PG8_SCHED;
;             PG8_LDB(B0, 1, 0); PG8_LDB(B1, 1, 1); PG8_SCHED; PG8_LDA(At, 1, 0); PG8_STAGE(PG8_SA(0, 1), a2 + hstep, voffA);
;             PG8_WAIT_V(8); PG8_WAIT_L(0); PG8_BAR; PG8_MMA(0, 0, At, B0); PG8_MMA(0, 1, At, B1); PG8_BAR; PG8_SCHED;
	v_pk_mul_f32 v[54:55], v[54:55], v[164:165] op_sel_hi:[1,0]
	v_pk_mul_f32 v[52:53], v[52:53], v[60:61]
	v_pk_mul_f32 v[56:57], v[56:57], v[64:65]
	v_pk_mul_f32 v[58:59], v[58:59], v[66:67]
	v_pk_mul_f32 v[48:49], v[48:49], v[164:165] op_sel_hi:[1,0]
	v_pk_mul_f32 v[50:51], v[50:51], v[164:165] op_sel_hi:[1,0]
	v_pk_mul_f32 v[54:55], v[54:55], v[62:63]
	v_pk_mul_f32 v[58:59], v[50:51], v[58:59]
	v_pk_mul_f32 v[50:51], v[48:49], v[56:57]
	v_cvt_pk_bf16_f32 v48, v52, v53
	v_mad_i64_i32 v[52:53], s[26:27], v154, s47, v[112:113]
	v_pk_mul_f32 v[44:45], v[44:45], v[160:161] op_sel_hi:[1,0]
	v_cvt_pk_bf16_f32 v49, v54, v55
	v_cvt_pk_bf16_f32 v50, v50, v51
	v_cvt_pk_bf16_f32 v51, v58, v59
	v_pk_mul_f32 v[46:47], v[46:47], v[160:161] op_sel_hi:[1,0]
	v_mul_f32_e32 v54, 0xbfb8aa3b, v44
	v_mul_f32_e32 v55, 0xbfb8aa3b, v45
	v_lshl_add_u64 v[52:53], v[52:53], 0, v[114:115]
	v_pk_mul_f32 v[40:41], v[40:41], v[160:161] op_sel_hi:[1,0]
	v_pk_mul_f32 v[42:43], v[42:43], v[160:161] op_sel_hi:[1,0]
	v_exp_f32_e32 v54, v54
	v_exp_f32_e32 v55, v55
	v_mul_f32_e32 v56, 0xbfb8aa3b, v46
	v_mul_f32_e32 v57, 0xbfb8aa3b, v47
	global_store_dwordx4 v[52:53], v[48:51], off
	v_exp_f32_e32 v56, v56
	v_exp_f32_e32 v57, v57
	v_mul_f32_e32 v48, 0xbfb8aa3b, v40
	v_mul_f32_e32 v49, 0xbfb8aa3b, v41
	v_mul_f32_e32 v50, 0xbfb8aa3b, v42
	v_mul_f32_e32 v51, 0xbfb8aa3b, v43
	v_exp_f32_e32 v48, v48
	v_exp_f32_e32 v49, v49
	v_exp_f32_e32 v50, v50
	v_exp_f32_e32 v51, v51
	v_add_f32_e32 v54, 1.0, v54
	v_add_f32_e32 v55, 1.0, v55
	v_rcp_f32_e32 v54, v54
	v_rcp_f32_e32 v55, v55
	v_add_f32_e32 v56, 1.0, v56
	v_add_f32_e32 v57, 1.0, v57
	v_add_f32_e32 v48, 1.0, v48
	v_add_f32_e32 v49, 1.0, v49
	v_add_f32_e32 v50, 1.0, v50
	v_add_f32_e32 v51, 1.0, v51
	v_rcp_f32_e32 v56, v56
	v_rcp_f32_e32 v57, v57
	v_rcp_f32_e32 v48, v48
	v_rcp_f32_e32 v49, v49
	v_rcp_f32_e32 v50, v50
	v_rcp_f32_e32 v51, v51
	v_pk_mul_f32 v[44:45], v[44:45], v[54:55]
	v_pk_mul_f32 v[36:37], v[36:37], v[160:161] op_sel_hi:[1,0]
	v_pk_mul_f32 v[46:47], v[46:47], v[56:57]
	v_pk_mul_f32 v[38:39], v[38:39], v[160:161] op_sel_hi:[1,0]
	v_pk_mul_f32 v[36:37], v[36:37], v[44:45]
	v_pk_mul_f32 v[40:41], v[40:41], v[48:49]
	v_pk_mul_f32 v[42:43], v[42:43], v[50:51]
	v_pk_mul_f32 v[32:33], v[32:33], v[160:161] op_sel_hi:[1,0]
	v_pk_mul_f32 v[34:35], v[34:35], v[160:161] op_sel_hi:[1,0]
	v_pk_mul_f32 v[38:39], v[38:39], v[46:47]
	v_pk_mul_f32 v[42:43], v[34:35], v[42:43]
	v_pk_mul_f32 v[34:35], v[32:33], v[40:41]
	v_cvt_pk_bf16_f32 v32, v36, v37
	v_mad_i64_i32 v[36:37], s[26:27], v150, s47, v[112:113]
	v_pk_mul_f32 v[28:29], v[28:29], v[156:157] op_sel_hi:[1,0]
	v_cvt_pk_bf16_f32 v33, v38, v39
	v_cvt_pk_bf16_f32 v34, v34, v35
	v_cvt_pk_bf16_f32 v35, v42, v43
	v_pk_mul_f32 v[30:31], v[30:31], v[156:157] op_sel_hi:[1,0]
	v_mul_f32_e32 v38, 0xbfb8aa3b, v28
	v_mul_f32_e32 v39, 0xbfb8aa3b, v29
	v_lshl_add_u64 v[36:37], v[36:37], 0, v[114:115]
	v_pk_mul_f32 v[24:25], v[24:25], v[156:157] op_sel_hi:[1,0]
	v_pk_mul_f32 v[26:27], v[26:27], v[156:157] op_sel_hi:[1,0]
	v_exp_f32_e32 v38, v38
	v_exp_f32_e32 v39, v39
	v_mul_f32_e32 v40, 0xbfb8aa3b, v30
	v_mul_f32_e32 v41, 0xbfb8aa3b, v31
	global_store_dwordx4 v[36:37], v[32:35], off
	v_exp_f32_e32 v40, v40
	v_exp_f32_e32 v41, v41
	v_mul_f32_e32 v32, 0xbfb8aa3b, v24
	v_mul_f32_e32 v33, 0xbfb8aa3b, v25
	v_mul_f32_e32 v34, 0xbfb8aa3b, v26
	v_mul_f32_e32 v35, 0xbfb8aa3b, v27
	v_exp_f32_e32 v32, v32
	v_exp_f32_e32 v33, v33
	v_exp_f32_e32 v34, v34
	v_exp_f32_e32 v35, v35
	v_add_f32_e32 v38, 1.0, v38
	v_add_f32_e32 v39, 1.0, v39
	v_rcp_f32_e32 v38, v38
	v_rcp_f32_e32 v39, v39
	v_add_f32_e32 v40, 1.0, v40
	v_add_f32_e32 v41, 1.0, v41
	v_add_f32_e32 v32, 1.0, v32
	v_add_f32_e32 v33, 1.0, v33
	v_add_f32_e32 v34, 1.0, v34
	v_add_f32_e32 v35, 1.0, v35
	v_rcp_f32_e32 v40, v40
	v_rcp_f32_e32 v41, v41
	v_rcp_f32_e32 v32, v32
	v_rcp_f32_e32 v33, v33
	v_rcp_f32_e32 v34, v34
	v_rcp_f32_e32 v35, v35
	v_pk_mul_f32 v[28:29], v[28:29], v[38:39]
	v_pk_mul_f32 v[20:21], v[20:21], v[156:157] op_sel_hi:[1,0]
	v_pk_mul_f32 v[30:31], v[30:31], v[40:41]
	v_pk_mul_f32 v[22:23], v[22:23], v[156:157] op_sel_hi:[1,0]
	v_pk_mul_f32 v[20:21], v[20:21], v[28:29]
	v_pk_mul_f32 v[24:25], v[24:25], v[32:33]
	v_pk_mul_f32 v[26:27], v[26:27], v[34:35]
	v_pk_mul_f32 v[16:17], v[16:17], v[156:157] op_sel_hi:[1,0]
	v_pk_mul_f32 v[18:19], v[18:19], v[156:157] op_sel_hi:[1,0]
	v_pk_mul_f32 v[22:23], v[22:23], v[30:31]
	v_pk_mul_f32 v[26:27], v[18:19], v[26:27]
	v_pk_mul_f32 v[18:19], v[16:17], v[24:25]
	v_cvt_pk_bf16_f32 v16, v20, v21
	v_mad_i64_i32 v[20:21], s[26:27], v148, s47, v[112:113]
	v_pk_mul_f32 v[12:13], v[12:13], v[152:153] op_sel_hi:[1,0]
	v_cvt_pk_bf16_f32 v17, v22, v23
	v_cvt_pk_bf16_f32 v18, v18, v19
	v_cvt_pk_bf16_f32 v19, v26, v27
	v_lshl_add_u64 v[20:21], v[20:21], 0, v[114:115]
	v_mul_f32_e32 v22, 0xbfb8aa3b, v12
	v_mul_f32_e32 v23, 0xbfb8aa3b, v13
	v_pk_mul_f32 v[8:9], v[8:9], v[152:153] op_sel_hi:[1,0]
	v_pk_mul_f32 v[10:11], v[10:11], v[152:153] op_sel_hi:[1,0]
	v_exp_f32_e32 v22, v22
	v_exp_f32_e32 v23, v23
	global_store_dwordx4 v[20:21], v[16:19], off
	v_pk_mul_f32 v[14:15], v[14:15], v[152:153] op_sel_hi:[1,0]
	v_add_f32_e32 v22, 1.0, v22
	v_mul_f32_e32 v16, 0xbfb8aa3b, v8
	v_mul_f32_e32 v17, 0xbfb8aa3b, v9
	v_mul_f32_e32 v18, 0xbfb8aa3b, v10
	v_mul_f32_e32 v19, 0xbfb8aa3b, v11
	v_exp_f32_e32 v16, v16
	v_exp_f32_e32 v17, v17
	v_exp_f32_e32 v18, v18
	v_exp_f32_e32 v19, v19
	v_mul_f32_e32 v24, 0xbfb8aa3b, v14
	v_mul_f32_e32 v25, 0xbfb8aa3b, v15
	v_exp_f32_e32 v24, v24
	v_exp_f32_e32 v25, v25
	v_add_f32_e32 v23, 1.0, v23
	v_rcp_f32_e32 v22, v22
	v_rcp_f32_e32 v23, v23
	v_add_f32_e32 v16, 1.0, v16
	v_add_f32_e32 v17, 1.0, v17
	v_add_f32_e32 v18, 1.0, v18
	v_add_f32_e32 v19, 1.0, v19
	v_rcp_f32_e32 v16, v16
	v_rcp_f32_e32 v17, v17
	v_rcp_f32_e32 v18, v18
	v_rcp_f32_e32 v19, v19
	v_add_f32_e32 v24, 1.0, v24
	v_add_f32_e32 v25, 1.0, v25
	v_rcp_f32_e32 v24, v24
	v_rcp_f32_e32 v25, v25
	v_pk_mul_f32 v[12:13], v[12:13], v[22:23]
	v_pk_mul_f32 v[4:5], v[4:5], v[152:153] op_sel_hi:[1,0]
	v_pk_mul_f32 v[8:9], v[8:9], v[16:17]
	v_pk_mul_f32 v[4:5], v[4:5], v[12:13]
	v_pk_mul_f32 v[10:11], v[10:11], v[18:19]
	v_pk_mul_f32 v[0:1], v[0:1], v[152:153] op_sel_hi:[1,0]
	v_pk_mul_f32 v[2:3], v[2:3], v[152:153] op_sel_hi:[1,0]
	v_pk_mul_f32 v[14:15], v[14:15], v[24:25]
	v_pk_mul_f32 v[10:11], v[2:3], v[10:11]
	v_pk_mul_f32 v[2:3], v[0:1], v[8:9]
	v_cvt_pk_bf16_f32 v0, v4, v5
	v_mad_i64_i32 v[4:5], s[26:27], v146, s47, v[112:113]
	v_pk_mul_f32 v[6:7], v[6:7], v[152:153] op_sel_hi:[1,0]
	v_lshl_add_u64 v[4:5], v[4:5], 0, v[114:115]
	v_pk_mul_f32 v[6:7], v[6:7], v[14:15]
	s_nop 0
	v_cvt_pk_bf16_f32 v1, v6, v7
	v_cvt_pk_bf16_f32 v2, v2, v3
	v_cvt_pk_bf16_f32 v3, v10, v11
	global_store_dwordx4 v[4:5], v[0:3], off
	s_cbranch_vccnz .LBB0_2036
	s_andn2_b64 vcc, exec, s[8:9]
	s_cbranch_vccnz .LBB0_2035
	s_barrier
	s_branch .LBB0_2035
